# v20 + nt hint on streaming global loads of the memory-bound phases (P0,P1,P3 conv,P9,P11 pre,P12) and on the final output stores
# baseline (speedup 1.0000x reference)
; __device__ __forceinline__ float siluf_(float x) { return x * sigmoidf_(x); }
; __global__ void __launch_bounds__(NWAVES * 64, 2) fwd_kernel(Args args) {
;     ...
;             for (int i = tid; i < BATCH * D; i += NWAVES * 64) { const float v = cvec[i]; cact[i] = pg8::siluf_(v); }
;             __syncthreads();
;             const int cg = tid % 24, kg = tid / 24;
;             for (int g = vcu; g < NMOD / 96; g += G) {
;                 if (kg < 21) {
;                     f32x4 a0 = {0.f, 0.f, 0.f, 0.f}, a1 = {0.f, 0.f, 0.f, 0.f};
;                     const float* wp = w_ada + (size_t)g * 96 + cg * 4;
; #pragma unroll 8
;                     for (int k = kg; k < D; k += 21) { const f32x4 w = *(const f32x4*)(wp + (size_t)k * NMOD); const float c0 = cact[k], c1 = cact[D + k]; a0 += w * c0; a1 += w * c1; }
.LBB0_15:
	global_load_dword v5, v[2:3], off nt
	v_add_u32_e32 v1, 0x200, v1
	v_cmp_lt_u32_e32 vcc, s4, v1
	v_lshl_add_u64 v[2:3], v[2:3], 0, s[2:3]
	s_or_b64 s[0:1], vcc, s[0:1]
	s_waitcnt vmcnt(0)
	v_mul_f32_e32 v6, 0xbfb8aa3b, v5
	v_exp_f32_e32 v6, v6
	s_nop 0
	v_add_f32_e32 v6, 1.0, v6
	v_rcp_f32_e32 v6, v6
	s_nop 0
	v_mul_f32_e32 v5, v5, v6
	ds_write_b32 v4, v5
	v_add_u32_e32 v4, 0x800, v4
	s_andn2_b64 exec, exec, s[0:1]
	s_cbranch_execnz .LBB0_15
	s_or_b64 exec, exec, s[0:1]
	s_cmpk_gt_i32 s34, 0xff
	s_waitcnt lgkmcnt(0)
	s_barrier
	s_cbranch_scc1 .LBB0_29
	v_mul_u32_u24_e32 v2, 0xaab, v0
	v_lshrrev_b32_e32 v20, 16, v2
	s_movk_i32 s0, 0x1f8
	v_mul_lo_u16_e32 v2, 24, v20
	v_cmp_gt_u32_e32 vcc, s0, v0
	s_movk_i32 s0, 0xc0
	v_sub_u16_e32 v6, v0, v2
	v_lshrrev_b32_e32 v4, 3, v0
	v_and_b32_e32 v2, 3, v0
	v_cmp_gt_u32_e64 s[2:3], s0, v0
	v_lshl_or_b32 v21, v4, 2, v2
	v_lshlrev_b32_e32 v9, 5, v4
	v_sub_u32_e32 v4, 0xfea, v20
	s_mov_b32 s0, 0xc30c30d
	v_mul_hi_u32 v4, v4, s0
	s_mov_b32 s0, 0xaaaaaab
	v_add_u32_e32 v5, 2, v4
	v_and_b32_e32 v4, 7, v4
	v_mul_hi_u32 v7, v0, s0
	s_mul_hi_i32 s1, s34, 0x180
	s_mul_i32 s0, s34, 0x180
	v_and_b32_e32 v22, 7, v5
	v_cmp_ne_u32_e64 s[4:5], 6, v4
	s_mov_b32 s7, 0x18000
	v_mov_b64_e32 v[4:5], s[0:1]
	v_mad_u64_u32 v[4:5], s[12:13], v7, s7, v[4:5]
	v_readlane_b32 s12, v249, 9
	v_mov_b32_e32 v2, 0
	v_lshlrev_b16_e32 v6, 2, v6
	v_readlane_b32 s16, v249, 13
	v_and_b32_e32 v3, 7, v0
	v_lshlrev_b32_e32 v6, 2, v6
	v_mov_b32_e32 v7, v2
	v_readlane_b32 s17, v249, 14
	s_add_u32 s0, s16, s0
	v_bfe_u32 v1, v0, 2, 1
	v_lshlrev_b32_e32 v8, 5, v0
	v_lshl_add_u32 v3, v3, 2, 0
	v_lshlrev_b32_e32 v23, 2, v20
	v_lshl_add_u64 v[4:5], v[4:5], 0, v[6:7]
	s_addc_u32 s1, s17, s1
	v_mul_u32_u24_e32 v1, 0x6000, v1
	v_add_u32_e32 v24, 0, v23
	v_lshl_add_u64 v[12:13], s[16:17], 0, v[4:5]
	s_mul_hi_i32 s39, s10, 0x180
	s_mul_i32 s38, s10, 0x180
	v_lshl_add_u64 v[14:15], s[0:1], 0, v[6:7]
	s_mov_b64 s[40:41], 0xfc0000
	s_movk_i32 s8, 0xf57
	v_add_u32_e32 v25, 0, v8
	v_add_u32_e32 v26, v3, v9
	s_mov_b32 s11, s34
	v_readlane_b32 s13, v249, 10
	v_readlane_b32 s14, v249, 11
	v_readlane_b32 s15, v249, 12
	v_readlane_b32 s18, v249, 15
	v_readlane_b32 s19, v249, 16
	v_readlane_b32 s20, v249, 17
	v_readlane_b32 s21, v249, 18
	v_readlane_b32 s22, v249, 19
	v_readlane_b32 s23, v249, 20
	v_readlane_b32 s24, v249, 21
	v_readlane_b32 s25, v249, 22
	v_readlane_b32 s26, v249, 23
	v_readlane_b32 s27, v249, 24
	s_branch .LBB0_19

; __global__ void __launch_bounds__(NWAVES * 64, 2) fwd_kernel(Args args) {
;     ...
; #pragma unroll 8
;                     for (int k = kg; k < D; k += 21) { const f32x4 w = *(const f32x4*)(wp + (size_t)k * NMOD); const float c0 = cact[k], c1 = cact[D + k]; a0 += w * c0; a1 += w * c1; }
.LBB0_22:
	global_load_dwordx4 v[28:31], v[16:17], off nt
	ds_read2st64_b32 v[32:33], v19 offset1:64
	s_mov_b64 s[0:1], 0x1f8000
	v_add_u32_e32 v3, -1, v3
	v_lshl_add_u64 v[16:17], v[16:17], 0, s[0:1]
	v_cmp_eq_u32_e64 s[0:1], 0, v3
	s_waitcnt lgkmcnt(0)
	v_mov_b32_e32 v34, v33
	v_add_u32_e32 v18, 21, v18
	v_add_u32_e32 v19, 0x54, v19
	s_or_b64 s[96:97], s[0:1], s[96:97]
	s_waitcnt vmcnt(0)
	v_pk_fma_f32 v[6:7], v[30:31], v[32:33], v[6:7] op_sel_hi:[1,0,1]
	v_pk_fma_f32 v[4:5], v[28:29], v[32:33], v[4:5] op_sel_hi:[1,0,1]
	v_pk_fma_f32 v[10:11], v[30:31], v[34:35], v[10:11] op_sel_hi:[1,0,1]
	v_pk_fma_f32 v[8:9], v[28:29], v[34:35], v[8:9] op_sel_hi:[1,0,1]
	s_andn2_b64 exec, exec, s[96:97]
	s_cbranch_execnz .LBB0_22
	s_or_b64 exec, exec, s[96:97]
	v_lshlrev_b32_e32 v19, 2, v18

; #define LAS __attribute__((address_space(3)))
; __global__ void __launch_bounds__(NWAVES * 64, 2) fwd_kernel(Args args) {
;     ...
; #pragma unroll 8
;                     for (int k = kg; k < D; k += 21) { const f32x4 w = *(const f32x4*)(wp + (size_t)k * NMOD); const float c0 = cact[k], c1 = cact[D + k]; a0 += w * c0; a1 += w * c1; }
;                     LAS float* rp = red + (kg * 24 + cg) * 8;
;                     rp[0] = a0.x; rp[1] = a0.y; rp[2] = a0.z; rp[3] = a0.w; rp[4] = a1.x; rp[5] = a1.y; rp[6] = a1.z; rp[7] = a1.w;
.LBB0_25:
	v_lshl_add_u64 v[32:33], v[18:19], 0, v[16:17]
	s_mov_b32 s0, 0x1f8000
	v_add_co_u32_e64 v34, s[0:1], s0, v32
	s_mov_b32 s12, 0x3f0000
	s_nop 0
	v_addc_co_u32_e64 v35, s[0:1], 0, v33, s[0:1]
	v_add_co_u32_e64 v36, s[0:1], s12, v32
	s_mov_b32 s13, 0x5e8000
	s_nop 0
	v_addc_co_u32_e64 v37, s[0:1], 0, v33, s[0:1]
	v_add_co_u32_e64 v40, s[0:1], s13, v32
	s_mov_b32 s14, 0x7e0000
	s_nop 0
	v_addc_co_u32_e64 v41, s[0:1], 0, v33, s[0:1]
	v_add_co_u32_e64 v44, s[0:1], s14, v32
	s_mov_b32 s15, 0x9d8000
	global_load_dwordx4 v[28:31], v[32:33], off nt
	v_addc_co_u32_e64 v45, s[0:1], 0, v33, s[0:1]
	v_add_co_u32_e64 v48, s[0:1], s15, v32
	s_mov_b32 s16, 0xbd0000
	s_nop 0
	v_addc_co_u32_e64 v49, s[0:1], 0, v33, s[0:1]
	v_add_co_u32_e64 v52, s[0:1], s16, v32
	s_mov_b32 s17, 0xdc8000
	s_nop 0
	v_addc_co_u32_e64 v53, s[0:1], 0, v33, s[0:1]
	v_add_co_u32_e64 v56, s[0:1], s17, v32
	v_add_u32_e32 v74, 0x4000, v27
	s_nop 0
	v_addc_co_u32_e64 v57, s[0:1], 0, v33, s[0:1]
	global_load_dwordx4 v[32:35], v[34:35], off nt
	s_nop 0
	global_load_dwordx4 v[36:39], v[36:37], off nt
	s_nop 0
	global_load_dwordx4 v[40:43], v[40:41], off nt
	s_nop 0
	global_load_dwordx4 v[44:47], v[44:45], off nt
	s_nop 0
	global_load_dwordx4 v[48:51], v[48:49], off nt
	s_nop 0
	global_load_dwordx4 v[52:55], v[52:53], off nt
	s_nop 0
	global_load_dwordx4 v[56:59], v[56:57], off nt
	ds_read2_b32 v[60:61], v27 offset1:21
	ds_read2_b32 v[62:63], v27 offset0:42 offset1:63
	ds_read2_b32 v[64:65], v27 offset0:84 offset1:105
	ds_read2_b32 v[66:67], v27 offset0:126 offset1:147
	ds_read2_b32 v[68:69], v74 offset1:21
	ds_read2_b32 v[70:71], v74 offset0:42 offset1:63
	ds_read2_b32 v[72:73], v74 offset0:84 offset1:105
	ds_read2_b32 v[74:75], v74 offset0:126 offset1:147
	v_add_u32_e32 v3, 0xa8, v3
	s_waitcnt lgkmcnt(3)
	v_mov_b32_e32 v84, v69
	v_mov_b32_e32 v76, v61
	v_mov_b32_e32 v78, v63
	s_waitcnt lgkmcnt(2)
	v_mov_b32_e32 v86, v71
	v_mov_b32_e32 v80, v65
	s_waitcnt lgkmcnt(1)
	v_mov_b32_e32 v88, v73
	v_cmp_lt_u32_e64 s[0:1], s8, v3
	v_mov_b32_e32 v82, v67
	s_waitcnt lgkmcnt(0)
	v_mov_b32_e32 v90, v75
	v_lshl_add_u64 v[18:19], v[18:19], 0, s[40:41]
	v_add_u32_e32 v27, 0x2a0, v27
	s_or_b64 s[94:95], s[0:1], s[94:95]
	s_waitcnt vmcnt(7)
	v_pk_fma_f32 v[6:7], v[30:31], v[60:61], v[6:7] op_sel_hi:[1,0,1]
	v_pk_fma_f32 v[4:5], v[28:29], v[60:61], v[4:5] op_sel_hi:[1,0,1]
	v_pk_fma_f32 v[10:11], v[30:31], v[68:69], v[10:11] op_sel_hi:[1,0,1]
	v_pk_fma_f32 v[8:9], v[28:29], v[68:69], v[8:9] op_sel_hi:[1,0,1]
	s_waitcnt vmcnt(6)
	v_pk_fma_f32 v[4:5], v[32:33], v[76:77], v[4:5] op_sel_hi:[1,0,1]
	v_pk_fma_f32 v[6:7], v[34:35], v[76:77], v[6:7] op_sel_hi:[1,0,1]
	v_pk_fma_f32 v[8:9], v[32:33], v[84:85], v[8:9] op_sel_hi:[1,0,1]
	v_pk_fma_f32 v[10:11], v[34:35], v[84:85], v[10:11] op_sel_hi:[1,0,1]
	s_waitcnt vmcnt(5)
	v_pk_fma_f32 v[6:7], v[38:39], v[62:63], v[6:7] op_sel_hi:[1,0,1]
	v_pk_fma_f32 v[4:5], v[36:37], v[62:63], v[4:5] op_sel_hi:[1,0,1]
	v_pk_fma_f32 v[10:11], v[38:39], v[70:71], v[10:11] op_sel_hi:[1,0,1]
	v_pk_fma_f32 v[8:9], v[36:37], v[70:71], v[8:9] op_sel_hi:[1,0,1]
	s_waitcnt vmcnt(4)
	v_pk_fma_f32 v[6:7], v[42:43], v[78:79], v[6:7] op_sel_hi:[1,0,1]
	v_pk_fma_f32 v[4:5], v[40:41], v[78:79], v[4:5] op_sel_hi:[1,0,1]
	v_pk_fma_f32 v[10:11], v[42:43], v[86:87], v[10:11] op_sel_hi:[1,0,1]
	v_pk_fma_f32 v[8:9], v[40:41], v[86:87], v[8:9] op_sel_hi:[1,0,1]
	s_waitcnt vmcnt(3)
	v_pk_fma_f32 v[6:7], v[46:47], v[64:65], v[6:7] op_sel_hi:[1,0,1]
	v_pk_fma_f32 v[4:5], v[44:45], v[64:65], v[4:5] op_sel_hi:[1,0,1]
	v_pk_fma_f32 v[10:11], v[46:47], v[72:73], v[10:11] op_sel_hi:[1,0,1]
	v_pk_fma_f32 v[8:9], v[44:45], v[72:73], v[8:9] op_sel_hi:[1,0,1]
	s_waitcnt vmcnt(2)
	v_pk_fma_f32 v[6:7], v[50:51], v[80:81], v[6:7] op_sel_hi:[1,0,1]
	v_pk_fma_f32 v[4:5], v[48:49], v[80:81], v[4:5] op_sel_hi:[1,0,1]
	v_pk_fma_f32 v[10:11], v[50:51], v[88:89], v[10:11] op_sel_hi:[1,0,1]
	v_pk_fma_f32 v[8:9], v[48:49], v[88:89], v[8:9] op_sel_hi:[1,0,1]
	s_waitcnt vmcnt(1)
	v_pk_fma_f32 v[6:7], v[54:55], v[66:67], v[6:7] op_sel_hi:[1,0,1]
	v_pk_fma_f32 v[4:5], v[52:53], v[66:67], v[4:5] op_sel_hi:[1,0,1]
	v_pk_fma_f32 v[10:11], v[54:55], v[74:75], v[10:11] op_sel_hi:[1,0,1]
	v_pk_fma_f32 v[8:9], v[52:53], v[74:75], v[8:9] op_sel_hi:[1,0,1]
	s_waitcnt vmcnt(0)
	v_pk_fma_f32 v[6:7], v[58:59], v[82:83], v[6:7] op_sel_hi:[1,0,1]
	v_pk_fma_f32 v[4:5], v[56:57], v[82:83], v[4:5] op_sel_hi:[1,0,1]
	v_pk_fma_f32 v[10:11], v[58:59], v[90:91], v[10:11] op_sel_hi:[1,0,1]
	v_pk_fma_f32 v[8:9], v[56:57], v[90:91], v[8:9] op_sel_hi:[1,0,1]
	s_andn2_b64 exec, exec, s[94:95]
	s_cbranch_execnz .LBB0_25
	s_or_b64 exec, exec, s[94:95]
	ds_write_b128 v25, v[4:7] offset:32768
	ds_write_b128 v25, v[8:11] offset:32784
; __global__ void __launch_bounds__(NWAVES * 64, 2) fwd_kernel(Args args) {
;     ...
;                 __syncthreads();
;                 if (tid < 192) { const int cgo = tid >> 3, r = tid & 7, b = r >> 2, j = r & 3; float s = 0.f;
; #pragma unroll
;                     for (int q = 0; q < 21; ++q) s += red[(q * 24 + cgo) * 8 + r];
;                     const int n = g * 96 + cgo * 4 + j; mod[b * NMOD + n] = s + b_ada[n]; }
.LBB0_27:
	s_or_b64 exec, exec, s[92:93]
	s_waitcnt lgkmcnt(0)
	s_barrier
	s_and_saveexec_b64 s[0:1], s[2:3]
	s_cbranch_execz .LBB0_18
	s_mul_i32 s12, s11, 0x60
	v_add_u32_e32 v4, s12, v21
	v_readlane_b32 s12, v249, 9
	v_ashrrev_i32_e32 v5, 31, v4
	v_readlane_b32 s18, v249, 15
	v_readlane_b32 s19, v249, 16
	v_readlane_b32 s13, v249, 10
	v_readlane_b32 s14, v249, 11
	v_lshl_add_u64 v[6:7], v[4:5], 2, s[18:19]
	global_load_dword v3, v[6:7], off nt
	ds_read2st64_b32 v[6:7], v26 offset0:128 offset1:131
	ds_read2st64_b32 v[8:9], v26 offset0:134 offset1:137
	ds_read2st64_b32 v[10:11], v26 offset0:140 offset1:143
	ds_read2st64_b32 v[16:17], v26 offset0:146 offset1:149
	ds_read2st64_b32 v[18:19], v26 offset0:152 offset1:155
	ds_read2st64_b32 v[28:29], v26 offset0:158 offset1:161
	ds_read2st64_b32 v[30:31], v26 offset0:164 offset1:167
	ds_read2st64_b32 v[32:33], v26 offset0:170 offset1:173
	ds_read2st64_b32 v[34:35], v26 offset0:176 offset1:179
	ds_read2st64_b32 v[36:37], v26 offset0:182 offset1:185
	ds_read_b32 v27, v26 offset:48128
	s_waitcnt lgkmcnt(10)
	v_add_f32_e32 v6, 0, v6
	v_add_f32_e32 v6, v6, v7
	s_waitcnt lgkmcnt(9)
	v_add_f32_e32 v6, v6, v8
	v_add_f32_e32 v6, v6, v9
	s_waitcnt lgkmcnt(8)
	v_add_f32_e32 v6, v6, v10
	v_add_f32_e32 v6, v6, v11
	s_waitcnt lgkmcnt(7)
	v_add_f32_e32 v6, v6, v16
	v_add_f32_e32 v6, v6, v17
	s_waitcnt lgkmcnt(6)
	v_add_f32_e32 v6, v6, v18
	v_add_f32_e32 v6, v6, v19
	s_waitcnt lgkmcnt(5)
	v_add_f32_e32 v6, v6, v28
	v_add_f32_e32 v6, v6, v29
	s_waitcnt lgkmcnt(4)
	v_add_f32_e32 v6, v6, v30
	v_add_f32_e32 v6, v6, v31
	s_waitcnt lgkmcnt(3)
	v_add_f32_e32 v6, v6, v32
	v_add_f32_e32 v6, v6, v33
	s_waitcnt lgkmcnt(2)
	v_add_f32_e32 v6, v6, v34
	v_add_f32_e32 v6, v6, v35
	s_waitcnt lgkmcnt(1)
	v_add_f32_e32 v6, v6, v36
	v_add_u32_e32 v4, v4, v1
	v_add_f32_e32 v6, v6, v37
	v_ashrrev_i32_e32 v5, 31, v4
	s_waitcnt lgkmcnt(0)
	v_add_f32_e32 v6, v6, v27
	v_lshl_add_u64 v[4:5], v[4:5], 2, s[30:31]
	v_readlane_b32 s15, v249, 12
	v_readlane_b32 s16, v249, 13
	v_readlane_b32 s17, v249, 14
	v_readlane_b32 s20, v249, 17
	v_readlane_b32 s21, v249, 18
	v_readlane_b32 s22, v249, 19
	v_readlane_b32 s23, v249, 20
	v_readlane_b32 s24, v249, 21
	v_readlane_b32 s25, v249, 22
	v_readlane_b32 s26, v249, 23
	v_readlane_b32 s27, v249, 24
	s_waitcnt vmcnt(0)
	v_add_f32_e32 v3, v6, v3
	global_store_dword v[4:5], v3, off
	s_branch .LBB0_18

; __global__ void __launch_bounds__(NWAVES * 64, 2) fwd_kernel(Args args) {
;     ...
;         for (int i = bx * NWAVES * 64 + tid; i < D; i += G * NWAVES * 64) { const float l = lam[i]; sp8[i] = -8.0f * log1pf(expf(-l)); }
.LBB0_31:
	v_lshl_add_u64 v[8:9], s[62:63], 0, v[2:3]
	global_load_dword v5, v[8:9], off nt
	v_add_u32_e32 v7, s2, v7
	v_cmp_lt_i32_e32 vcc, s15, v7
	s_or_b64 s[38:39], vcc, s[38:39]
	v_lshl_add_u64 v[8:9], s[16:17], 0, v[2:3]
	v_lshl_add_u64 v[2:3], v[2:3], 0, s[4:5]
	s_waitcnt vmcnt(0)
	v_mul_f32_e32 v10, 0xbfb8aa3b, v5
	v_fma_f32 v11, v5, s3, -v10
	v_rndne_f32_e32 v12, v10
	v_fmac_f32_e32 v11, 0xb2a5705f, v5
	v_sub_f32_e32 v10, v10, v12
	v_add_f32_e32 v10, v10, v11
	v_cvt_i32_f32_e32 v12, v12
	v_exp_f32_e32 v10, v10
	v_cmp_nlt_f32_e32 vcc, s7, v5
	v_ldexp_f32 v10, v10, v12
	s_nop 0
	v_cndmask_b32_e32 v10, 0, v10, vcc
	v_cmp_ngt_f32_e32 vcc, s8, v5
	s_nop 1
	v_cndmask_b32_e32 v24, v1, v10, vcc
	v_add_f32_e32 v5, 1.0, v24
	v_add_f32_e32 v12, -1.0, v5
	v_frexp_mant_f32_e32 v13, v5
	v_cvt_f64_f32_e32 v[10:11], v5
	v_sub_f32_e32 v14, v12, v5
	v_frexp_exp_i32_f64_e32 v10, v[10:11]
	v_cmp_gt_f32_e32 vcc, s12, v13
	v_sub_f32_e32 v12, v24, v12
	v_add_f32_e32 v11, 1.0, v14
	v_subbrev_co_u32_e32 v10, vcc, 0, v10, vcc
	v_add_f32_e32 v11, v12, v11
	v_sub_u32_e32 v12, 0, v10
	v_ldexp_f32 v5, v5, v12
	v_ldexp_f32 v11, v11, v12
	v_add_f32_e32 v12, -1.0, v5
	v_add_f32_e32 v14, 1.0, v5
	v_add_f32_e32 v13, 1.0, v12
	v_add_f32_e32 v15, -1.0, v14
	v_sub_f32_e32 v13, v5, v13
	v_sub_f32_e32 v5, v5, v15
	v_add_f32_e32 v5, v11, v5
	v_add_f32_e32 v15, v11, v13
	v_add_f32_e32 v11, v14, v5
	v_rcp_f32_e32 v18, v11
	v_add_f32_e32 v13, v12, v15
	v_sub_f32_e32 v14, v14, v11
	v_add_f32_e32 v5, v5, v14
	v_mul_f32_e32 v20, v13, v18
	v_mul_f32_e32 v14, v11, v20
	v_fma_f32 v16, v20, v11, -v14
	v_sub_f32_e32 v12, v12, v13
	v_fmac_f32_e32 v16, v20, v5
	v_add_f32_e32 v19, v15, v12
	v_add_f32_e32 v12, v14, v16
	v_sub_f32_e32 v15, v13, v12
	v_mov_b32_e32 v17, v12
	v_pk_add_f32 v[12:13], v[12:13], v[14:15] neg_lo:[0,1] neg_hi:[0,1]
	v_cvt_f32_i32_e32 v10, v10
	v_pk_add_f32 v[12:13], v[12:13], v[16:17] neg_lo:[0,1] neg_hi:[0,1]
	v_cmp_neq_f32_e32 vcc, s11, v24
	v_add_f32_e32 v13, v19, v13
	v_add_f32_e32 v12, v12, v13
	v_add_f32_e32 v13, v15, v12
	v_mul_f32_e32 v17, v18, v13
	v_mul_f32_e32 v14, v11, v17
	v_fma_f32 v16, v17, v11, -v14
	v_sub_f32_e32 v15, v15, v13
	v_fmac_f32_e32 v16, v17, v5
	v_add_f32_e32 v19, v12, v15
	v_add_f32_e32 v21, v20, v17
	v_add_f32_e32 v12, v14, v16
	v_sub_f32_e32 v11, v21, v20
	v_sub_f32_e32 v15, v13, v12
	v_sub_f32_e32 v5, v17, v11
	v_mov_b32_e32 v17, v12
	v_pk_add_f32 v[12:13], v[12:13], v[14:15] neg_lo:[0,1] neg_hi:[0,1]
	s_nop 0
	v_pk_add_f32 v[12:13], v[12:13], v[16:17] neg_lo:[0,1] neg_hi:[0,1]
	s_nop 0
	v_add_f32_e32 v11, v19, v13
	v_add_f32_e32 v11, v12, v11
	v_add_f32_e32 v11, v15, v11
	v_mul_f32_e32 v11, v18, v11
	v_add_f32_e32 v5, v5, v11
	v_add_f32_e32 v11, v21, v5
	v_mul_f32_e32 v12, v11, v11
	v_sub_f32_e32 v14, v11, v21
	v_fmamk_f32 v15, v12, 0x3e9b6dac, v6
	v_ldexp_f32 v13, v11, 1
	v_sub_f32_e32 v14, v5, v14
	v_mul_f32_e32 v11, v11, v12
	v_fmaak_f32 v5, v12, v15, 0x3f2aaada
	v_ldexp_f32 v17, v14, 1
	v_pk_mul_f32 v[14:15], v[10:11], v[4:5]
	s_nop 0
	v_fma_f32 v12, v10, s13, -v14
	v_fmac_f32_e32 v12, 0xb102e308, v10
	v_pk_add_f32 v[10:11], v[14:15], v[12:13]
	v_mov_b32_e32 v16, v14
	v_sub_f32_e32 v5, v11, v13
	v_sub_f32_e32 v5, v15, v5
	v_add_f32_e32 v17, v17, v5
	v_pk_add_f32 v[18:19], v[10:11], v[14:15] neg_lo:[0,1] neg_hi:[0,1]
	v_pk_add_f32 v[14:15], v[10:11], v[16:17]
	v_mov_b32_e32 v13, v10
	v_mov_b32_e32 v19, v15
	v_pk_add_f32 v[22:23], v[12:13], v[18:19] neg_lo:[0,1] neg_hi:[0,1]
	v_pk_add_f32 v[12:13], v[12:13], v[18:19]
	v_mov_b32_e32 v21, v10
	v_pk_add_f32 v[18:19], v[12:13], v[10:11] op_sel:[1,0] op_sel_hi:[0,1] neg_lo:[0,1] neg_hi:[0,1]
	v_mov_b32_e32 v20, v17
	v_mov_b32_e32 v16, v15
	v_mov_b32_e32 v17, v13
	v_pk_mov_b32 v[10:11], v[10:11], v[18:19] op_sel:[1,0]
	v_pk_add_f32 v[14:15], v[14:15], v[18:19] op_sel_hi:[1,0] neg_lo:[0,1] neg_hi:[0,1]
	v_pk_add_f32 v[10:11], v[16:17], v[10:11] neg_lo:[0,1] neg_hi:[0,1]
	v_mov_b32_e32 v14, v22
	v_pk_add_f32 v[10:11], v[20:21], v[10:11] neg_lo:[0,1] neg_hi:[0,1]
	v_mov_b32_e32 v23, v13
	v_pk_add_f32 v[14:15], v[14:15], v[10:11]
	s_nop 0
	v_pk_add_f32 v[16:17], v[14:15], v[14:15] op_sel:[0,1] op_sel_hi:[1,0]
	s_nop 0
	v_pk_add_f32 v[12:13], v[12:13], v[16:17] op_sel:[1,0] op_sel_hi:[0,1]
	v_mov_b32_e32 v15, v12
	v_mov_b32_e32 v11, v16
	v_pk_add_f32 v[16:17], v[14:15], v[22:23] neg_lo:[0,1] neg_hi:[0,1]
	s_nop 0
	v_sub_f32_e32 v5, v14, v16
	v_pk_add_f32 v[10:11], v[10:11], v[16:17] neg_lo:[0,1] neg_hi:[0,1]
	v_sub_f32_e32 v5, v22, v5
	v_add_f32_e32 v5, v10, v5
	v_add_f32_e32 v5, v5, v11
	v_add_f32_e32 v5, v12, v5
	v_cndmask_b32_e32 v5, v1, v5, vcc
	v_cmp_lt_f32_e64 vcc, |v24|, s14
	s_nop 1
	v_cndmask_b32_e32 v5, v5, v24, vcc
	v_mul_f32_e32 v5, 0xc1000000, v5
	global_store_dword v[8:9], v5, off
	s_andn2_b64 exec, exec, s[38:39]
	s_cbranch_execnz .LBB0_31
; #define TR_MAP(it_, k0_, n0_, dr_) do { const int kb_ = (it_) / nblk, nb_ = (it_) % nblk; k0_ = 64 * kb_; n0_ = 32 * nb_; \
;         if (DMAP == 1) { const int isup_ = n0_ >= DFF ? 1 : 0, j_ = n0_ - isup_ * DFF; dr_ = drow_off + (j_ >> 7) * 256 + isup_ * 128 + (j_ & 127); } else dr_ = drow_off + n0_; } while (0)
; __device__ __forceinline__ void tr_load(float (&v)[32], const float* W, int N, int k0, int n0, int lane) {
;     const float* wp = W + (size_t)(k0 + (lane >> 5)) * N + n0 + (lane & 31);
; #pragma unroll
;     for (int i = 0; i < 32; ++i) v[i] = wp[(size_t)(2 * i) * N];
; }
;     const int nblk = (ncols ? ncols : N) / 32, nitems = (K / 64) * nblk;
;     int it = gw - (itbase % NGW); if (it < 0) it += NGW;
;     itbase += nitems;
;     if (it >= nitems) return;
;     ...
;     float va[32], vb[32]; int ka, na, da, kb2 = 0, nb2 = 0, db = 0;
;     TR_MAP(it, ka, na, da); tr_load(va, W, N, ka, na, lane);
.LBB0_32:
	s_or_b64 exec, exec, s[0:1]
	v_readlane_b32 s1, v249, 40
	s_ashr_i32 s0, s1, 31
	s_and_b32 s0, s0, s9
	s_add_i32 s39, s0, s1
	v_readlane_b32 s0, v249, 38
	v_lshlrev_b32_e32 v2, 3, v0
	s_lshl_b32 s7, s0, 14
	v_and_b32_e32 v1, 31, v0
	v_and_b32_e32 v2, 56, v2
	s_add_i32 s0, s7, 0
	v_lshrrev_b32_e32 v35, 3, v178
	v_lshrrev_b32_e32 v34, 5, v178
	v_readlane_b32 s1, v249, 39
	v_lshl_add_u32 v42, v1, 2, s0
	s_movk_i32 s13, 0x84
	v_mul_u32_u24_e32 v3, 0x84, v2
	v_lshlrev_b32_e32 v4, 2, v35
	v_mov_b32_e32 v37, 0
	s_mov_b32 s1, 0
	s_movk_i32 s12, 0x2000
	s_cmpk_lt_i32 s39, 0x2000
	v_mad_u32_u24 v33, v34, s13, v42
	v_add3_u32 v43, s0, v3, v4
	v_or_b32_e32 v46, 8, v35
	v_or_b32_e32 v47, 16, v35
	v_or_b32_e32 v48, 24, v35
	v_lshlrev_b32_e32 v36, 2, v1
	v_lshlrev_b32_e32 v38, 1, v2
	s_cbranch_scc0 .LBB0_41
	v_readlane_b32 s80, v249, 9
	v_readlane_b32 s88, v249, 17
	v_readlane_b32 s89, v249, 18
	v_readlane_b32 s90, v249, 19
	v_readlane_b32 s91, v249, 20
	v_readlane_b32 s92, v249, 21
	v_readlane_b32 s93, v249, 22
	v_readlane_b32 s94, v249, 23
	v_readlane_b32 s95, v249, 24
	s_mov_b64 s[44:45], s[88:89]
	s_mov_b64 s[48:49], s[92:93]
	s_add_u32 s2, s48, 0x4000
	s_addc_u32 s3, s49, 0
	s_ashr_i32 s0, s39, 31
	s_lshr_b32 s0, s0, 25
	s_add_i32 s0, s39, s0
	s_ashr_i32 s4, s0, 7
	s_and_b32 s0, s0, 0x7ffff80
	s_sub_i32 s0, s39, s0
	s_lshl_b32 s4, s4, 6
	s_lshl_b32 s14, s0, 5
	v_or_b32_e32 v1, s4, v34
	s_mov_b32 s0, 0x14000
	v_mov_b64_e32 v[2:3], s[2:3]
	v_mad_i64_i32 v[2:3], s[16:17], v1, s0, v[2:3]
	s_ashr_i32 s15, s14, 31
	v_lshl_add_u64 v[2:3], s[14:15], 2, v[2:3]
	v_lshl_add_u64 v[2:3], v[2:3], 0, v[36:37]
	s_mov_b32 s8, 0x28000
	v_add_co_u32_e32 v4, vcc, s8, v2
	s_add_i32 s11, s14, 0x1000
	s_nop 0
	v_addc_co_u32_e32 v5, vcc, 0, v3, vcc
	s_mov_b32 s14, 0x50000
	v_add_co_u32_e32 v6, vcc, s14, v2
	s_mov_b32 s15, 0x78000
	s_nop 0
	v_addc_co_u32_e32 v7, vcc, 0, v3, vcc
	v_add_co_u32_e32 v8, vcc, s15, v2
	s_mov_b32 s16, 0xa0000
	s_nop 0
	v_addc_co_u32_e32 v9, vcc, 0, v3, vcc
	v_add_co_u32_e32 v10, vcc, s16, v2
	s_mov_b32 s17, 0xc8000
	s_nop 0
	v_addc_co_u32_e32 v11, vcc, 0, v3, vcc
	v_add_co_u32_e32 v12, vcc, s17, v2
	s_mov_b32 s18, 0xf0000
	s_nop 0
	v_addc_co_u32_e32 v13, vcc, 0, v3, vcc
	v_add_co_u32_e32 v14, vcc, s18, v2
	s_mov_b32 s19, 0x118000
	s_nop 0
	v_addc_co_u32_e32 v15, vcc, 0, v3, vcc
	v_add_co_u32_e32 v16, vcc, s19, v2
	s_mov_b32 s20, 0x140000
	s_nop 0
	v_addc_co_u32_e32 v17, vcc, 0, v3, vcc
	v_add_co_u32_e32 v18, vcc, s20, v2
	s_mov_b32 s21, 0x168000
	s_nop 0
	v_addc_co_u32_e32 v19, vcc, 0, v3, vcc
	v_add_co_u32_e32 v20, vcc, s21, v2
	s_mov_b32 s22, 0x190000
	s_nop 0
	v_addc_co_u32_e32 v21, vcc, 0, v3, vcc
	v_add_co_u32_e32 v22, vcc, s22, v2
	s_mov_b32 s23, 0x1b8000
	s_nop 0
	v_addc_co_u32_e32 v23, vcc, 0, v3, vcc
	v_add_co_u32_e32 v24, vcc, s23, v2
	s_mov_b32 s24, 0x1e0000
	s_nop 0
	v_addc_co_u32_e32 v25, vcc, 0, v3, vcc
	v_add_co_u32_e32 v26, vcc, s24, v2
	s_mov_b32 s25, 0x208000
	s_nop 0
	v_addc_co_u32_e32 v27, vcc, 0, v3, vcc
	v_add_co_u32_e32 v28, vcc, s25, v2
	s_mov_b32 s26, 0x230000
	s_nop 0
	v_addc_co_u32_e32 v29, vcc, 0, v3, vcc
	v_add_co_u32_e32 v30, vcc, s26, v2
	s_mov_b32 s27, 0x258000
	s_nop 0
	v_addc_co_u32_e32 v31, vcc, 0, v3, vcc
	v_add_co_u32_e32 v80, vcc, s27, v2
	s_mov_b32 s28, 0x280000
	s_nop 0
	v_addc_co_u32_e32 v81, vcc, 0, v3, vcc
	v_add_co_u32_e32 v82, vcc, s28, v2
	s_mov_b32 s29, 0x2a8000
	s_nop 0
	v_addc_co_u32_e32 v83, vcc, 0, v3, vcc
	v_add_co_u32_e32 v84, vcc, s29, v2
	s_mov_b32 s33, 0x2d0000
	s_nop 0
	v_addc_co_u32_e32 v85, vcc, 0, v3, vcc
	v_add_co_u32_e32 v86, vcc, s33, v2
	s_mov_b32 s35, 0x2f8000
	s_nop 0
	v_addc_co_u32_e32 v87, vcc, 0, v3, vcc
	v_add_co_u32_e32 v88, vcc, s35, v2
	s_mov_b32 s36, 0x320000
	s_nop 0
	v_addc_co_u32_e32 v89, vcc, 0, v3, vcc
	v_add_co_u32_e32 v90, vcc, s36, v2
	s_mov_b32 s37, 0x348000
	s_nop 0
	v_addc_co_u32_e32 v91, vcc, 0, v3, vcc
	v_add_co_u32_e32 v92, vcc, s37, v2
	s_mov_b32 s44, 0x370000
	s_nop 0
	v_addc_co_u32_e32 v93, vcc, 0, v3, vcc
	v_add_co_u32_e32 v94, vcc, s44, v2
	s_mov_b32 s45, 0x398000
	s_nop 0
	v_addc_co_u32_e32 v95, vcc, 0, v3, vcc
	s_mov_b64 s[46:47], s[90:91]
	v_add_co_u32_e32 v96, vcc, s45, v2
	s_mov_b32 s46, 0x3c0000
	s_nop 0
	v_addc_co_u32_e32 v97, vcc, 0, v3, vcc
	v_add_co_u32_e32 v98, vcc, s46, v2
	s_mov_b32 s47, 0x3e8000
	s_nop 0
	v_addc_co_u32_e32 v99, vcc, 0, v3, vcc
	v_add_co_u32_e32 v100, vcc, s47, v2
	s_mov_b32 s48, 0x410000
	s_nop 0
	v_addc_co_u32_e32 v101, vcc, 0, v3, vcc
	v_add_co_u32_e32 v102, vcc, s48, v2
	s_mov_b32 s49, 0x438000
	s_nop 0
	v_addc_co_u32_e32 v103, vcc, 0, v3, vcc
	s_mov_b64 s[50:51], s[94:95]
	v_add_co_u32_e32 v104, vcc, s49, v2
	s_mov_b32 s50, 0x460000
	s_nop 0
	v_addc_co_u32_e32 v105, vcc, 0, v3, vcc
	v_add_co_u32_e32 v106, vcc, s50, v2
	s_mov_b32 s5, 0x488000
	s_nop 0
	v_addc_co_u32_e32 v107, vcc, 0, v3, vcc
	v_add_co_u32_e32 v108, vcc, s5, v2
	s_mov_b32 s5, 0x4b0000
	s_nop 0
	v_addc_co_u32_e32 v109, vcc, 0, v3, vcc
	v_add_co_u32_e32 v110, vcc, s5, v2
	v_readlane_b32 s40, v249, 35
	s_nop 0
	v_addc_co_u32_e32 v111, vcc, 0, v3, vcc
	v_add_co_u32_e32 v112, vcc, 0x4d8000, v2
	v_mov_b32_e32 v39, v37
	s_nop 0
	v_addc_co_u32_e32 v113, vcc, 0, v3, vcc
	global_load_dword v2, v[2:3], off nt
	s_nop 0
	global_load_dword v1, v[4:5], off nt
	s_nop 0
	global_load_dword v4, v[6:7], off nt
	global_load_dword v3, v[8:9], off nt
	s_nop 0
	global_load_dword v6, v[10:11], off nt
	global_load_dword v5, v[12:13], off nt
	global_load_dword v8, v[14:15], off nt
	global_load_dword v7, v[16:17], off nt
	s_nop 0
	global_load_dword v10, v[18:19], off nt
	global_load_dword v9, v[20:21], off nt
	global_load_dword v12, v[22:23], off nt
	global_load_dword v11, v[24:25], off nt
	global_load_dword v14, v[26:27], off nt
	global_load_dword v13, v[28:29], off nt
	global_load_dword v16, v[30:31], off nt
	global_load_dword v15, v[80:81], off nt
	global_load_dword v18, v[82:83], off nt
	global_load_dword v17, v[84:85], off nt
	global_load_dword v20, v[86:87], off nt
	global_load_dword v19, v[88:89], off nt
	global_load_dword v22, v[90:91], off nt
	global_load_dword v21, v[92:93], off nt
	global_load_dword v24, v[94:95], off nt
	global_load_dword v23, v[96:97], off nt
	global_load_dword v26, v[98:99], off nt
	global_load_dword v25, v[100:101], off nt
	global_load_dword v28, v[102:103], off nt
	global_load_dword v27, v[104:105], off nt
	global_load_dword v30, v[106:107], off nt
	global_load_dword v29, v[108:109], off nt
	global_load_dword v32, v[110:111], off nt
	global_load_dword v31, v[112:113], off nt
	v_readlane_b32 s41, v249, 36
	s_mov_b32 s42, 0
	s_lshl_b32 s51, s10, 4
	s_mov_b32 s38, 0
	v_lshl_add_u64 v[44:45], s[40:41], 0, v[38:39]
	v_readlane_b32 s81, v249, 10
	v_readlane_b32 s82, v249, 11
	v_readlane_b32 s83, v249, 12
	v_readlane_b32 s84, v249, 13
	v_readlane_b32 s85, v249, 14
	v_readlane_b32 s86, v249, 15
	v_readlane_b32 s87, v249, 16
	s_branch .LBB0_36

; #define TR_MAP(it_, k0_, n0_, dr_) do { const int kb_ = (it_) / nblk, nb_ = (it_) % nblk; k0_ = 64 * kb_; n0_ = 32 * nb_; \
;         if (DMAP == 1) { const int isup_ = n0_ >= DFF ? 1 : 0, j_ = n0_ - isup_ * DFF; dr_ = drow_off + (j_ >> 7) * 256 + isup_ * 128 + (j_ & 127); } else dr_ = drow_off + n0_; } while (0)
; __device__ __forceinline__ void tr_load(float (&v)[32], const float* W, int N, int k0, int n0, int lane) {
;     const float* wp = W + (size_t)(k0 + (lane >> 5)) * N + n0 + (lane & 31);
; #pragma unroll
;     for (int i = 0; i < 32; ++i) v[i] = wp[(size_t)(2 * i) * N];
; }
;     ...
;     while (true) {
;         const int itb = it + NGW; const bool hb = itb < nitems;
;         if (hb) { TR_MAP(itb, kb2, nb2, db); tr_load(vb, W, N, kb2, nb2, lane); }
;         tr_finish(va, WT, ldk, ka, da, scr, lane);
.LBB0_36:
	s_add_i32 s62, s39, s9
	s_cmpk_lt_i32 s62, 0x2000
	s_cselect_b64 s[40:41], -1, 0
	s_cmpk_gt_i32 s62, 0x1fff
	s_cbranch_scc1 .LBB0_38
	s_ashr_i32 s5, s62, 31
	s_lshr_b32 s5, s5, 25
	s_add_i32 s5, s62, s5
	s_ashr_i32 s38, s5, 7
	s_and_b32 s5, s5, 0x7ffff80
	s_sub_i32 s5, s62, s5
	s_lshl_b32 s38, s38, 6
	s_lshl_b32 s42, s5, 5
	v_or_b32_e32 v39, s38, v34
	v_mov_b64_e32 v[50:51], s[2:3]
	v_mad_i64_i32 v[50:51], s[68:69], v39, s0, v[50:51]
	s_ashr_i32 s43, s42, 31
	v_lshl_add_u64 v[50:51], s[42:43], 2, v[50:51]
	v_lshl_add_u64 v[72:73], v[50:51], 0, v[36:37]
	v_add_co_u32_e32 v50, vcc, s8, v72
	s_addk_i32 s42, 0x1000
	s_nop 0
	v_addc_co_u32_e32 v51, vcc, 0, v73, vcc
	v_add_co_u32_e32 v56, vcc, s14, v72
	s_nop 1
	v_addc_co_u32_e32 v57, vcc, 0, v73, vcc
	v_add_co_u32_e32 v58, vcc, s15, v72
	s_nop 1
	v_addc_co_u32_e32 v59, vcc, 0, v73, vcc
	v_add_co_u32_e32 v60, vcc, s16, v72
	s_nop 1
	v_addc_co_u32_e32 v61, vcc, 0, v73, vcc
	v_add_co_u32_e32 v62, vcc, s17, v72
	s_nop 1
	v_addc_co_u32_e32 v63, vcc, 0, v73, vcc
	v_add_co_u32_e32 v64, vcc, s18, v72
	s_nop 1
	v_addc_co_u32_e32 v65, vcc, 0, v73, vcc
	v_add_co_u32_e32 v66, vcc, s19, v72
	s_nop 1
	v_addc_co_u32_e32 v67, vcc, 0, v73, vcc
	global_load_dword v54, v[72:73], off nt
	global_load_dword v53, v[50:51], off nt
	global_load_dword v52, v[56:57], off nt
	s_nop 0
	global_load_dword v51, v[58:59], off nt
	global_load_dword v50, v[60:61], off nt
	global_load_dword v49, v[62:63], off nt
	global_load_dword v41, v[64:65], off nt
	global_load_dword v55, v[66:67], off nt
	v_add_co_u32_e32 v56, vcc, s20, v72
	s_nop 1
	v_addc_co_u32_e32 v57, vcc, 0, v73, vcc
	v_add_co_u32_e32 v58, vcc, s21, v72
	s_nop 1
	v_addc_co_u32_e32 v59, vcc, 0, v73, vcc
	v_add_co_u32_e32 v60, vcc, s22, v72
	s_nop 1
	v_addc_co_u32_e32 v61, vcc, 0, v73, vcc
	v_add_co_u32_e32 v64, vcc, s23, v72
	s_nop 1
	v_addc_co_u32_e32 v65, vcc, 0, v73, vcc
	v_add_co_u32_e32 v66, vcc, s24, v72
	s_nop 1
	v_addc_co_u32_e32 v67, vcc, 0, v73, vcc
	v_add_co_u32_e32 v68, vcc, s25, v72
	s_nop 1
	v_addc_co_u32_e32 v69, vcc, 0, v73, vcc
	v_add_co_u32_e32 v70, vcc, s26, v72
	s_nop 1
	v_addc_co_u32_e32 v71, vcc, 0, v73, vcc
	v_add_co_u32_e32 v74, vcc, s27, v72
	s_nop 1
	v_addc_co_u32_e32 v75, vcc, 0, v73, vcc
	global_load_dword v63, v[56:57], off nt
	global_load_dword v62, v[58:59], off nt
	s_nop 0
	global_load_dword v60, v[60:61], off nt
	s_nop 0
	global_load_dword v59, v[64:65], off nt
	global_load_dword v58, v[66:67], off nt
	global_load_dword v57, v[68:69], off nt
	global_load_dword v56, v[70:71], off nt
	global_load_dword v61, v[74:75], off nt
	v_add_co_u32_e32 v64, vcc, s28, v72
	s_nop 1
	v_addc_co_u32_e32 v65, vcc, 0, v73, vcc
	v_add_co_u32_e32 v66, vcc, s29, v72
	s_nop 1
	v_addc_co_u32_e32 v67, vcc, 0, v73, vcc
	v_add_co_u32_e32 v74, vcc, s33, v72
	s_nop 1
	v_addc_co_u32_e32 v75, vcc, 0, v73, vcc
	v_add_co_u32_e32 v76, vcc, s35, v72
	s_nop 1
	v_addc_co_u32_e32 v77, vcc, 0, v73, vcc
	v_add_co_u32_e32 v78, vcc, s36, v72
	s_nop 1
	v_addc_co_u32_e32 v79, vcc, 0, v73, vcc
	v_add_co_u32_e32 v80, vcc, s37, v72
	s_nop 1
	v_addc_co_u32_e32 v81, vcc, 0, v73, vcc
	v_add_co_u32_e32 v82, vcc, s44, v72
	s_nop 1
	v_addc_co_u32_e32 v83, vcc, 0, v73, vcc
	v_add_co_u32_e32 v84, vcc, s45, v72
	s_nop 1
	v_addc_co_u32_e32 v85, vcc, 0, v73, vcc
	global_load_dword v70, v[64:65], off nt
	global_load_dword v69, v[66:67], off nt
	global_load_dword v68, v[74:75], off nt
	s_nop 0
	global_load_dword v67, v[76:77], off nt
	global_load_dword v66, v[78:79], off nt
	global_load_dword v65, v[80:81], off nt
	global_load_dword v64, v[82:83], off nt
	global_load_dword v71, v[84:85], off nt
	v_add_co_u32_e32 v74, vcc, s46, v72
	s_nop 1
	v_addc_co_u32_e32 v75, vcc, 0, v73, vcc
	v_add_co_u32_e32 v76, vcc, s47, v72
	s_nop 1
	v_addc_co_u32_e32 v77, vcc, 0, v73, vcc
	v_add_co_u32_e32 v80, vcc, s48, v72
	s_nop 1
	v_addc_co_u32_e32 v81, vcc, 0, v73, vcc
	v_add_co_u32_e32 v82, vcc, s49, v72
	s_nop 1
	v_addc_co_u32_e32 v83, vcc, 0, v73, vcc
	v_add_co_u32_e32 v84, vcc, 0x460000, v72
	s_nop 1
	v_addc_co_u32_e32 v85, vcc, 0, v73, vcc
	v_add_co_u32_e32 v86, vcc, 0x488000, v72
	s_nop 1
	v_addc_co_u32_e32 v87, vcc, 0, v73, vcc
	v_add_co_u32_e32 v88, vcc, 0x4b0000, v72
	s_nop 1
	v_addc_co_u32_e32 v89, vcc, 0, v73, vcc
	v_add_co_u32_e32 v90, vcc, 0x4d8000, v72
	s_nop 1
	v_addc_co_u32_e32 v91, vcc, 0, v73, vcc
	global_load_dword v78, v[74:75], off nt
	s_nop 0
	global_load_dword v77, v[76:77], off nt
	s_nop 0
	global_load_dword v76, v[80:81], off nt
	global_load_dword v75, v[82:83], off nt
	global_load_dword v74, v[84:85], off nt
	global_load_dword v73, v[86:87], off nt
	global_load_dword v72, v[88:89], off nt
	global_load_dword v79, v[90:91], off nt
; __device__ __forceinline__ unsigned cvt_pk_bf16(float lo, float hi) { unsigned r; asm volatile("v_cvt_pk_bf16_f32 %0, %1, %2" : "=v"(r) : "v"(lo), "v"(hi)); return r; }
; #define LAS __attribute__((address_space(3)))
; #define LDS_WAIT() asm volatile("s_waitcnt lgkmcnt(0)" ::: "memory")
; __device__ __forceinline__ void tr_finish(const float (&v)[32], bf16* WT, int ldk, int k0, int drow0, LAS float* scr, int lane) {
; #pragma unroll
;     for (int i = 0; i < 32; ++i) scr[(2 * i + (lane >> 5)) * 33 + (lane & 31)] = v[i];
;     LDS_WAIT(); asm volatile("" ::: "memory");
;     const int c = lane & 7;
; #pragma unroll
;     for (int j = 0; j < 4; ++j) { const int n = (lane >> 3) + 8 * j; const LAS float* s = scr + (8 * c) * 33 + n;
;         v4u o;
;         { o.x = cvt_pk_bf16(s[0 * 33], s[1 * 33]); o.y = cvt_pk_bf16(s[2 * 33], s[3 * 33]); o.z = cvt_pk_bf16(s[4 * 33], s[5 * 33]); o.w = cvt_pk_bf16(s[6 * 33], s[7 * 33]); }
;         *(v4u*)(WT + (size_t)(drow0 + n) * ldk + k0 + 8 * c) = o; }
;     LDS_WAIT(); asm volatile("" ::: "memory");
.LBB0_38:
	v_add_u32_e32 v39, 0x400, v33
	v_add_u32_e32 v80, 0x800, v33
	v_add_u32_e32 v81, 0xc00, v33
	v_add_u32_e32 v82, 0x1000, v33
	v_add_u32_e32 v83, 0x1400, v33
	v_add_u32_e32 v84, 0x1800, v33
	v_add_u32_e32 v85, 0x1c00, v33
	s_waitcnt vmcnt(30)
	ds_write2_b32 v33, v2, v1 offset1:66
	s_waitcnt vmcnt(28)
	ds_write2_b32 v33, v4, v3 offset0:132 offset1:198
	s_waitcnt vmcnt(26)
	ds_write2_b32 v39, v6, v5 offset0:8 offset1:74
	s_waitcnt vmcnt(24)
	ds_write2_b32 v39, v8, v7 offset0:140 offset1:206
	s_waitcnt vmcnt(22)
	ds_write2_b32 v80, v10, v9 offset0:16 offset1:82
	s_waitcnt vmcnt(20)
	ds_write2_b32 v80, v12, v11 offset0:148 offset1:214
	s_waitcnt vmcnt(18)
	ds_write2_b32 v81, v14, v13 offset0:24 offset1:90
	s_waitcnt vmcnt(16)
	ds_write2_b32 v81, v16, v15 offset0:156 offset1:222
	s_waitcnt vmcnt(14)
	ds_write2_b32 v82, v18, v17 offset0:32 offset1:98
	s_waitcnt vmcnt(12)
	ds_write2_b32 v82, v20, v19 offset0:164 offset1:230
	s_waitcnt vmcnt(10)
	ds_write2_b32 v83, v22, v21 offset0:40 offset1:106
	s_waitcnt vmcnt(8)
	ds_write2_b32 v83, v24, v23 offset0:172 offset1:238
	s_waitcnt vmcnt(6)
	ds_write2_b32 v84, v26, v25 offset0:48 offset1:114
	s_waitcnt vmcnt(4)
	ds_write2_b32 v84, v28, v27 offset0:180 offset1:246
	s_waitcnt vmcnt(2)
	ds_write2_b32 v85, v30, v29 offset0:56 offset1:122
	s_waitcnt vmcnt(0)
	ds_write2_b32 v85, v32, v31 offset0:188 offset1:254
	s_waitcnt lgkmcnt(0)
	ds_read2_b32 v[86:87], v43 offset1:33
	s_waitcnt lgkmcnt(0)
	v_cvt_pk_bf16_f32 v86, v86, v87
	ds_read2_b32 v[88:89], v43 offset0:66 offset1:99
	s_waitcnt lgkmcnt(0)
	v_cvt_pk_bf16_f32 v87, v88, v89
	ds_read2_b32 v[88:89], v43 offset0:132 offset1:165
	s_waitcnt lgkmcnt(0)
	v_cvt_pk_bf16_f32 v88, v88, v89
	ds_read2_b32 v[90:91], v43 offset0:198 offset1:231
	s_waitcnt lgkmcnt(0)
	v_cvt_pk_bf16_f32 v89, v90, v91
	s_ashr_i32 s5, s4, 31
	v_add_u32_e32 v90, s11, v35
	v_mov_b32_e32 v91, v37
	v_lshlrev_b64 v[90:91], 13, v[90:91]
	v_lshl_add_u64 v[92:93], s[4:5], 1, v[44:45]
	v_lshl_add_u64 v[90:91], v[92:93], 0, v[90:91]
	global_store_dwordx4 v[90:91], v[86:89], off
	ds_read2_b32 v[86:87], v43 offset0:8 offset1:41
	s_andn2_b64 vcc, exec, s[40:41]
	s_waitcnt lgkmcnt(0)
	v_cvt_pk_bf16_f32 v86, v86, v87
	ds_read2_b32 v[88:89], v43 offset0:74 offset1:107
	s_waitcnt lgkmcnt(0)
	v_cvt_pk_bf16_f32 v87, v88, v89
	ds_read2_b32 v[88:89], v43 offset0:140 offset1:173
	s_waitcnt lgkmcnt(0)
	v_cvt_pk_bf16_f32 v88, v88, v89
	ds_read2_b32 v[90:91], v43 offset0:206 offset1:239
	s_waitcnt lgkmcnt(0)
	v_cvt_pk_bf16_f32 v89, v90, v91
	v_add_u32_e32 v90, s11, v46
	v_mov_b32_e32 v91, v37
	v_lshlrev_b64 v[90:91], 13, v[90:91]
	v_lshl_add_u64 v[90:91], v[92:93], 0, v[90:91]
	global_store_dwordx4 v[90:91], v[86:89], off
	ds_read2_b32 v[86:87], v43 offset0:16 offset1:49
	s_mov_b64 s[40:41], -1
	s_waitcnt lgkmcnt(0)
	v_cvt_pk_bf16_f32 v86, v86, v87
	ds_read2_b32 v[88:89], v43 offset0:82 offset1:115
	s_waitcnt lgkmcnt(0)
	v_cvt_pk_bf16_f32 v87, v88, v89
	ds_read2_b32 v[88:89], v43 offset0:148 offset1:181
	s_waitcnt lgkmcnt(0)
	v_cvt_pk_bf16_f32 v88, v88, v89
	ds_read2_b32 v[90:91], v43 offset0:214 offset1:247
	s_waitcnt lgkmcnt(0)
	v_cvt_pk_bf16_f32 v89, v90, v91
	v_add_u32_e32 v90, s11, v47
	v_mov_b32_e32 v91, v37
	v_lshlrev_b64 v[90:91], 13, v[90:91]
	v_lshl_add_u64 v[90:91], v[92:93], 0, v[90:91]
	global_store_dwordx4 v[90:91], v[86:89], off
	s_nop 1
	v_add_u32_e32 v86, s11, v48
	v_mov_b32_e32 v87, v37
	v_lshlrev_b64 v[86:87], 13, v[86:87]
	v_lshl_add_u64 v[90:91], v[92:93], 0, v[86:87]
	ds_read2_b32 v[86:87], v43 offset0:24 offset1:57
	s_waitcnt lgkmcnt(0)
	v_cvt_pk_bf16_f32 v86, v86, v87
	ds_read2_b32 v[88:89], v43 offset0:90 offset1:123
	s_waitcnt lgkmcnt(0)
	v_cvt_pk_bf16_f32 v87, v88, v89
	ds_read2_b32 v[88:89], v43 offset0:156 offset1:189
	s_waitcnt lgkmcnt(0)
	v_cvt_pk_bf16_f32 v88, v88, v89
	ds_read2_b32 v[92:93], v43 offset0:222 offset1:255
	s_waitcnt lgkmcnt(0)
	v_cvt_pk_bf16_f32 v89, v92, v93
	global_store_dwordx4 v[90:91], v[86:89], off
	s_waitcnt lgkmcnt(0)
	s_cbranch_vccnz .LBB0_35
	s_add_i32 s5, s51, s39
	s_cmpk_gt_i32 s5, 0x1fff
	s_cbranch_scc1 .LBB0_34
; #define TR_MAP(it_, k0_, n0_, dr_) do { const int kb_ = (it_) / nblk, nb_ = (it_) % nblk; k0_ = 64 * kb_; n0_ = 32 * nb_; \
;         if (DMAP == 1) { const int isup_ = n0_ >= DFF ? 1 : 0, j_ = n0_ - isup_ * DFF; dr_ = drow_off + (j_ >> 7) * 256 + isup_ * 128 + (j_ & 127); } else dr_ = drow_off + n0_; } while (0)
; __device__ __forceinline__ void tr_load(float (&v)[32], const float* W, int N, int k0, int n0, int lane) {
;     const float* wp = W + (size_t)(k0 + (lane >> 5)) * N + n0 + (lane & 31);
; #pragma unroll
;     for (int i = 0; i < 32; ++i) v[i] = wp[(size_t)(2 * i) * N];
; }
;     ...
;         if (!hb) break;
;         it = itb + NGW; const bool ha = it < nitems;
;         if (ha) { TR_MAP(it, ka, na, da); tr_load(va, W, N, ka, na, lane); }
;         tr_finish(vb, WT, ldk, kb2, db, scr, lane);
	s_ashr_i32 s4, s5, 31
	s_lshr_b32 s4, s4, 25
	s_add_i32 s4, s5, s4
	s_ashr_i32 s11, s4, 7
	s_and_b32 s4, s4, 0x7ffff80
	s_sub_i32 s5, s5, s4
	s_lshl_b32 s4, s11, 6
	s_lshl_b32 s40, s5, 5
	v_or_b32_e32 v1, s4, v34
	v_mov_b64_e32 v[2:3], s[2:3]
	v_mad_i64_i32 v[2:3], s[68:69], v1, s0, v[2:3]
	s_ashr_i32 s41, s40, 31
	v_lshl_add_u64 v[2:3], s[40:41], 2, v[2:3]
	v_lshl_add_u64 v[2:3], v[2:3], 0, v[36:37]
	v_add_co_u32_e32 v4, vcc, s8, v2
	s_add_i32 s11, s40, 0x1000
	s_nop 0
	v_addc_co_u32_e32 v5, vcc, 0, v3, vcc
	v_add_co_u32_e32 v6, vcc, s14, v2
	s_nop 1
	v_addc_co_u32_e32 v7, vcc, 0, v3, vcc
	v_add_co_u32_e32 v8, vcc, s15, v2
	s_nop 1
	v_addc_co_u32_e32 v9, vcc, 0, v3, vcc
	v_add_co_u32_e32 v10, vcc, s16, v2
	s_nop 1
	v_addc_co_u32_e32 v11, vcc, 0, v3, vcc
	v_add_co_u32_e32 v12, vcc, s17, v2
	s_nop 1
	v_addc_co_u32_e32 v13, vcc, 0, v3, vcc
	v_add_co_u32_e32 v14, vcc, s18, v2
	s_nop 1
	v_addc_co_u32_e32 v15, vcc, 0, v3, vcc
	v_add_co_u32_e32 v16, vcc, s19, v2
	s_nop 1
	v_addc_co_u32_e32 v17, vcc, 0, v3, vcc
	v_add_co_u32_e32 v18, vcc, s20, v2
	s_nop 1
	v_addc_co_u32_e32 v19, vcc, 0, v3, vcc
	v_add_co_u32_e32 v20, vcc, s21, v2
	s_nop 1
	v_addc_co_u32_e32 v21, vcc, 0, v3, vcc
	v_add_co_u32_e32 v22, vcc, s22, v2
	s_nop 1
	v_addc_co_u32_e32 v23, vcc, 0, v3, vcc
	v_add_co_u32_e32 v24, vcc, s23, v2
	s_nop 1
	v_addc_co_u32_e32 v25, vcc, 0, v3, vcc
	v_add_co_u32_e32 v26, vcc, s24, v2
	s_nop 1
	v_addc_co_u32_e32 v27, vcc, 0, v3, vcc
	v_add_co_u32_e32 v28, vcc, s25, v2
	s_nop 1
	v_addc_co_u32_e32 v29, vcc, 0, v3, vcc
	v_add_co_u32_e32 v30, vcc, s26, v2
	s_nop 1
	v_addc_co_u32_e32 v31, vcc, 0, v3, vcc
	v_add_co_u32_e32 v86, vcc, s27, v2
	s_nop 1
	v_addc_co_u32_e32 v87, vcc, 0, v3, vcc
	v_add_co_u32_e32 v88, vcc, s28, v2
	s_nop 1
	v_addc_co_u32_e32 v89, vcc, 0, v3, vcc
	v_add_co_u32_e32 v90, vcc, s29, v2
	s_nop 1
	v_addc_co_u32_e32 v91, vcc, 0, v3, vcc
	v_add_co_u32_e32 v92, vcc, s33, v2
	s_nop 1
	v_addc_co_u32_e32 v93, vcc, 0, v3, vcc
	v_add_co_u32_e32 v94, vcc, s35, v2
	s_nop 1
	v_addc_co_u32_e32 v95, vcc, 0, v3, vcc
	v_add_co_u32_e32 v96, vcc, s36, v2
	s_nop 1
	v_addc_co_u32_e32 v97, vcc, 0, v3, vcc
	v_add_co_u32_e32 v98, vcc, s37, v2
	s_nop 1
	v_addc_co_u32_e32 v99, vcc, 0, v3, vcc
	v_add_co_u32_e32 v100, vcc, s44, v2
	s_nop 1
	v_addc_co_u32_e32 v101, vcc, 0, v3, vcc
	v_add_co_u32_e32 v102, vcc, s45, v2
	s_nop 1
	v_addc_co_u32_e32 v103, vcc, 0, v3, vcc
	v_add_co_u32_e32 v104, vcc, s46, v2
	s_nop 1
	v_addc_co_u32_e32 v105, vcc, 0, v3, vcc
	v_add_co_u32_e32 v106, vcc, s47, v2
	s_nop 1
	v_addc_co_u32_e32 v107, vcc, 0, v3, vcc
	v_add_co_u32_e32 v108, vcc, s48, v2
	s_nop 1
	v_addc_co_u32_e32 v109, vcc, 0, v3, vcc
	v_add_co_u32_e32 v110, vcc, s49, v2
	s_nop 1
	v_addc_co_u32_e32 v111, vcc, 0, v3, vcc
	v_add_co_u32_e32 v112, vcc, s50, v2
	s_nop 1
	v_addc_co_u32_e32 v113, vcc, 0, v3, vcc
	v_add_co_u32_e32 v114, vcc, 0x488000, v2
	s_nop 1
	v_addc_co_u32_e32 v115, vcc, 0, v3, vcc
	v_add_co_u32_e32 v116, vcc, 0x4b0000, v2
	s_nop 1
	v_addc_co_u32_e32 v117, vcc, 0, v3, vcc
	v_add_co_u32_e32 v118, vcc, 0x4d8000, v2
	s_nop 1
	v_addc_co_u32_e32 v119, vcc, 0, v3, vcc
	global_load_dword v2, v[2:3], off nt
	s_nop 0
	global_load_dword v1, v[4:5], off nt
	s_nop 0
	global_load_dword v4, v[6:7], off nt
	global_load_dword v3, v[8:9], off nt
	s_nop 0
	global_load_dword v6, v[10:11], off nt
	global_load_dword v5, v[12:13], off nt
	global_load_dword v8, v[14:15], off nt
	global_load_dword v7, v[16:17], off nt
	s_nop 0
	global_load_dword v10, v[18:19], off nt
	global_load_dword v9, v[20:21], off nt
	global_load_dword v12, v[22:23], off nt
	global_load_dword v11, v[24:25], off nt
	global_load_dword v14, v[26:27], off nt
	global_load_dword v13, v[28:29], off nt
	global_load_dword v16, v[30:31], off nt
	global_load_dword v15, v[86:87], off nt
	global_load_dword v18, v[88:89], off nt
	global_load_dword v17, v[90:91], off nt
	global_load_dword v20, v[92:93], off nt
	global_load_dword v19, v[94:95], off nt
	global_load_dword v22, v[96:97], off nt
	global_load_dword v21, v[98:99], off nt
	global_load_dword v24, v[100:101], off nt
	global_load_dword v23, v[102:103], off nt
	global_load_dword v26, v[104:105], off nt
	global_load_dword v25, v[106:107], off nt
	global_load_dword v28, v[108:109], off nt
	global_load_dword v27, v[110:111], off nt
	global_load_dword v30, v[112:113], off nt
	global_load_dword v29, v[114:115], off nt
	global_load_dword v32, v[116:117], off nt
	global_load_dword v31, v[118:119], off nt
	s_branch .LBB0_34

; #define LAS __attribute__((address_space(3)))
; #define LDS_WAIT() asm volatile("s_waitcnt lgkmcnt(0)" ::: "memory")
; __device__ __forceinline__ void transpose_item(const float* W, int N, bf16* WT, int ldk, int k0, int n0, int drow0, LAS float* scr, int lane) {
; #pragma unroll 8
;     for (int i = 0; i < 32; ++i) { const int kk = 2 * i + (lane >> 5); scr[kk * 33 + (lane & 31)] = W[(size_t)(k0 + kk) * N + n0 + (lane & 31)]; }
;     LDS_WAIT(); asm volatile("" ::: "memory");
; __global__ void __launch_bounds__(NWAVES * 64, 2) fwd_kernel(Args args) {
;     ...
;             for (int h = 0; h < HEADS; ++h) {
;                 const int nblk = HD / 32, nitems = (HD / 64) * nblk * 2;
;                 int it = gw - (itbase % NGW); if (it < 0) it += NGW;
;                 for (; it < nitems; it += NGW) { const int which = it / ((HD / 64) * nblk), r = it % ((HD / 64) * nblk), kb = r / nblk, nb = r % nblk, n0 = 32 * nb;
;                     const float* W = (which ? w_rg_x : w_rg_a) + (size_t)h * HD * HD;
;                     transpose_item(W, HD, Wrg_t, HD, 64 * kb, n0, h * 512 + (n0 >> 7) * 256 + which * 128 + (n0 & 127), scr, lane); }
.LBB0_46:
	s_lshl_b32 s21, s18, 1
	s_lshl_b32 s22, s19, 1
	s_waitcnt vmcnt(5)
	v_or_b32_e32 v32, s21, v1
	v_or_b32_e32 v39, s22, v34
	s_add_i32 s23, s21, 4
	s_add_i32 s24, s22, 4
	s_add_i32 s25, s21, 8
	s_add_i32 s26, s22, 8
	s_add_i32 s27, s21, 12
	s_add_i32 s28, s22, 12
	s_add_i32 s29, s21, 16
	s_add_i32 s33, s22, 16
	s_add_i32 s35, s21, 20
	s_add_i32 s36, s22, 20
	s_add_i32 s37, s21, 24
	s_add_i32 s39, s22, 24
	s_add_i32 s21, s21, 28
	s_add_i32 s22, s22, 28
	v_add_u32_e32 v8, s38, v39
	v_or_b32_e32 v41, s23, v1
	v_or_b32_e32 v49, s24, v34
	v_or_b32_e32 v54, s25, v1
	v_or_b32_e32 v55, s26, v34
	v_or_b32_e32 v56, s27, v1
	v_or_b32_e32 v57, s28, v34
	v_or_b32_e32 v58, s29, v1
	v_or_b32_e32 v59, s33, v34
	v_or_b32_e32 v60, s35, v1
	v_or_b32_e32 v61, s36, v34
	v_or_b32_e32 v62, s37, v1
	v_or_b32_e32 v63, s39, v34
	v_or_b32_e32 v64, s21, v1
	v_or_b32_e32 v65, s22, v34
	v_add_u32_e32 v6, s5, v32
	v_ashrrev_i32_e32 v9, 31, v8
	v_add_u32_e32 v10, s5, v41
	v_add_u32_e32 v12, s38, v49
	v_add_u32_e32 v14, s5, v54
	v_add_u32_e32 v16, s38, v55
	v_add_u32_e32 v18, s5, v56
	v_add_u32_e32 v20, s38, v57
	v_add_u32_e32 v22, s5, v58
	v_add_u32_e32 v24, s38, v59
	v_add_u32_e32 v26, s5, v60
	v_add_u32_e32 v28, s38, v61
	v_add_u32_e32 v30, s5, v62
	v_add_u32_e32 v44, s38, v63
	v_add_u32_e32 v50, s5, v64
	v_add_u32_e32 v52, s38, v65
	v_ashrrev_i32_e32 v7, 31, v6
	v_lshlrev_b64 v[8:9], 10, v[8:9]
	v_ashrrev_i32_e32 v13, 31, v12
	v_ashrrev_i32_e32 v11, 31, v10
	v_ashrrev_i32_e32 v17, 31, v16
	v_ashrrev_i32_e32 v15, 31, v14
	v_ashrrev_i32_e32 v21, 31, v20
	v_ashrrev_i32_e32 v19, 31, v18
	v_ashrrev_i32_e32 v25, 31, v24
	v_ashrrev_i32_e32 v23, 31, v22
	v_ashrrev_i32_e32 v29, 31, v28
	v_ashrrev_i32_e32 v27, 31, v26
	v_ashrrev_i32_e32 v45, 31, v44
	s_waitcnt vmcnt(4)
	v_ashrrev_i32_e32 v31, 31, v30
	v_ashrrev_i32_e32 v53, 31, v52
	v_ashrrev_i32_e32 v51, 31, v50
	v_lshlrev_b64 v[6:7], 10, v[6:7]
	v_lshl_add_u64 v[8:9], v[4:5], 0, v[8:9]
	v_lshlrev_b64 v[10:11], 10, v[10:11]
	v_lshlrev_b64 v[12:13], 10, v[12:13]
	v_lshlrev_b64 v[14:15], 10, v[14:15]
	v_lshlrev_b64 v[16:17], 10, v[16:17]
	v_lshlrev_b64 v[18:19], 10, v[18:19]
	v_lshlrev_b64 v[20:21], 10, v[20:21]
	v_lshlrev_b64 v[22:23], 10, v[22:23]
	v_lshlrev_b64 v[24:25], 10, v[24:25]
	v_lshlrev_b64 v[26:27], 10, v[26:27]
	v_lshlrev_b64 v[28:29], 10, v[28:29]
	v_lshlrev_b64 v[30:31], 10, v[30:31]
	v_lshlrev_b64 v[44:45], 10, v[44:45]
	v_lshlrev_b64 v[50:51], 10, v[50:51]
	v_lshlrev_b64 v[52:53], 10, v[52:53]
	v_lshl_add_u64 v[6:7], v[4:5], 0, v[6:7]
	v_lshl_add_u64 v[12:13], v[4:5], 0, v[12:13]
	v_lshl_add_u64 v[10:11], v[4:5], 0, v[10:11]
	v_lshl_add_u64 v[16:17], v[4:5], 0, v[16:17]
	v_lshl_add_u64 v[14:15], v[4:5], 0, v[14:15]
	v_lshl_add_u64 v[20:21], v[4:5], 0, v[20:21]
	v_lshl_add_u64 v[18:19], v[4:5], 0, v[18:19]
	v_lshl_add_u64 v[24:25], v[4:5], 0, v[24:25]
	v_lshl_add_u64 v[22:23], v[4:5], 0, v[22:23]
	v_lshl_add_u64 v[28:29], v[4:5], 0, v[28:29]
	v_lshl_add_u64 v[26:27], v[4:5], 0, v[26:27]
	v_lshl_add_u64 v[44:45], v[4:5], 0, v[44:45]
	v_lshl_add_u64 v[30:31], v[4:5], 0, v[30:31]
	v_lshl_add_u64 v[52:53], v[4:5], 0, v[52:53]
	v_lshl_add_u64 v[50:51], v[4:5], 0, v[50:51]
	global_load_dword v66, v[8:9], off nt
	global_load_dword v67, v[6:7], off nt
	global_load_dword v68, v[12:13], off nt
	global_load_dword v69, v[10:11], off nt
	global_load_dword v70, v[16:17], off nt
	global_load_dword v71, v[14:15], off nt
	global_load_dword v72, v[20:21], off nt
	global_load_dword v73, v[18:19], off nt
	global_load_dword v74, v[24:25], off nt
	global_load_dword v75, v[22:23], off nt
	global_load_dword v76, v[28:29], off nt
	global_load_dword v77, v[26:27], off nt
	global_load_dword v78, v[44:45], off nt
	global_load_dword v79, v[30:31], off nt
	global_load_dword v80, v[52:53], off nt
	global_load_dword v81, v[50:51], off nt
	s_add_i32 s19, s19, 16
	s_add_i32 s18, s18, 16
	s_add_i32 s20, s20, -16
	v_mad_u64_u32 v[6:7], s[22:23], v39, s13, v[42:43]
	s_cmp_lg_u32 s20, 0
	v_mad_u64_u32 v[8:9], s[22:23], v32, s13, v[42:43]
	v_mad_u64_u32 v[10:11], s[22:23], v49, s13, v[42:43]
	v_mad_u64_u32 v[12:13], s[22:23], v41, s13, v[42:43]
	v_mad_u64_u32 v[14:15], s[22:23], v55, s13, v[42:43]
	v_mad_u64_u32 v[16:17], s[22:23], v54, s13, v[42:43]
	v_mad_u64_u32 v[18:19], s[22:23], v57, s13, v[42:43]
	v_mad_u64_u32 v[20:21], s[22:23], v56, s13, v[42:43]
	v_mad_u64_u32 v[22:23], s[22:23], v59, s13, v[42:43]
	v_mad_u64_u32 v[24:25], s[22:23], v58, s13, v[42:43]
	v_mad_u64_u32 v[26:27], s[22:23], v61, s13, v[42:43]
	v_mad_u64_u32 v[28:29], s[22:23], v60, s13, v[42:43]
	v_mad_u64_u32 v[30:31], s[22:23], v63, s13, v[42:43]
	v_mad_u64_u32 v[44:45], s[22:23], v62, s13, v[42:43]
	v_mad_u64_u32 v[50:51], s[22:23], v65, s13, v[42:43]
	v_mad_u64_u32 v[52:53], s[22:23], v64, s13, v[42:43]
	s_waitcnt vmcnt(15)
	ds_write_b32 v6, v66
	s_waitcnt vmcnt(14)
	ds_write_b32 v8, v67
	s_waitcnt vmcnt(13)
	ds_write_b32 v10, v68
	s_waitcnt vmcnt(12)
	ds_write_b32 v12, v69
	s_waitcnt vmcnt(11)
	ds_write_b32 v14, v70
	s_waitcnt vmcnt(10)
	ds_write_b32 v16, v71
	s_waitcnt vmcnt(9)
	ds_write_b32 v18, v72
	s_waitcnt vmcnt(8)
	ds_write_b32 v20, v73
	s_waitcnt vmcnt(7)
	ds_write_b32 v22, v74
	s_waitcnt vmcnt(6)
	ds_write_b32 v24, v75
	s_waitcnt vmcnt(5)
	ds_write_b32 v26, v76
	s_waitcnt vmcnt(4)
	ds_write_b32 v28, v77
	s_waitcnt vmcnt(3)
	ds_write_b32 v30, v78
	s_waitcnt vmcnt(2)
	ds_write_b32 v44, v79
	s_waitcnt vmcnt(1)
	ds_write_b32 v50, v80
	s_waitcnt vmcnt(0)
	ds_write_b32 v52, v81
	s_cbranch_scc1 .LBB0_46
; __device__ __forceinline__ unsigned cvt_pk_bf16(float lo, float hi) { unsigned r; asm volatile("v_cvt_pk_bf16_f32 %0, %1, %2" : "=v"(r) : "v"(lo), "v"(hi)); return r; }
; #define LAS __attribute__((address_space(3)))
; #define LDS_WAIT() asm volatile("s_waitcnt lgkmcnt(0)" ::: "memory")
; __device__ __forceinline__ void transpose_item(const float* W, int N, bf16* WT, int ldk, int k0, int n0, int drow0, LAS float* scr, int lane) {
;     ...
;     LDS_WAIT(); asm volatile("" ::: "memory");
;     const int c = lane & 7;
; #pragma unroll
;     for (int j = 0; j < 4; ++j) { const int n = (lane >> 3) + 8 * j; const LAS float* s = scr + (8 * c) * 33 + n;
;         v4u o;
;         { o.x = cvt_pk_bf16(s[0 * 33], s[1 * 33]); o.y = cvt_pk_bf16(s[2 * 33], s[3 * 33]); o.z = cvt_pk_bf16(s[4 * 33], s[5 * 33]); o.w = cvt_pk_bf16(s[6 * 33], s[7 * 33]); }
;         *(v4u*)(WT + (size_t)(drow0 + n) * ldk + k0 + 8 * c) = o; }
;     LDS_WAIT(); asm volatile("" ::: "memory");
; __global__ void __launch_bounds__(NWAVES * 64, 2) fwd_kernel(Args args) {
;     ...
;                 for (; it < nitems; it += NGW) { const int which = it / ((HD / 64) * nblk), r = it % ((HD / 64) * nblk), kb = r / nblk, nb = r % nblk, n0 = 32 * nb;
;                     const float* W = (which ? w_rg_x : w_rg_a) + (size_t)h * HD * HD;
;                     transpose_item(W, HD, Wrg_t, HD, 64 * kb, n0, h * 512 + (n0 >> 7) * 256 + which * 128 + (n0 & 127), scr, lane); }
;                 itbase += nitems;
	s_lshl_b32 s5, s17, 6
	s_lshl_b32 s0, s0, 7
	s_add_i32 s0, s0, s16
	s_and_b32 s5, s5, 0xffffff00
	s_and_b32 s4, s4, 0x60
	s_add_i32 s0, s0, s5
	s_waitcnt lgkmcnt(0)
	s_or_b32 s0, s0, s4
	v_or_b32_e32 v12, s0, v35
	ds_read2_b32 v[4:5], v43 offset1:33
	s_ashr_i32 s39, s38, 31
	v_ashrrev_i32_e32 v13, 31, v12
	s_waitcnt lgkmcnt(0)
	v_cvt_pk_bf16_f32 v4, v4, v5
	ds_read2_b32 v[6:7], v43 offset0:66 offset1:99
	v_lshl_add_u64 v[10:11], s[38:39], 1, v[2:3]
	v_lshlrev_b64 v[12:13], 9, v[12:13]
	s_waitcnt lgkmcnt(0)
	v_cvt_pk_bf16_f32 v5, v6, v7
	ds_read2_b32 v[6:7], v43 offset0:132 offset1:165
	v_lshl_add_u64 v[12:13], v[10:11], 0, v[12:13]
	s_waitcnt lgkmcnt(0)
	v_cvt_pk_bf16_f32 v6, v6, v7
	ds_read2_b32 v[8:9], v43 offset0:198 offset1:231
	s_waitcnt lgkmcnt(0)
	v_cvt_pk_bf16_f32 v7, v8, v9
	global_store_dwordx4 v[12:13], v[4:7], off
	v_or_b32_e32 v12, s0, v46
	v_ashrrev_i32_e32 v13, 31, v12
	ds_read2_b32 v[8:9], v43 offset0:8 offset1:41
	s_waitcnt lgkmcnt(0)
	v_cvt_pk_bf16_f32 v4, v8, v9
	ds_read2_b32 v[6:7], v43 offset0:74 offset1:107
	v_lshlrev_b64 v[12:13], 9, v[12:13]
	s_waitcnt lgkmcnt(0)
	v_cvt_pk_bf16_f32 v5, v6, v7
	ds_read2_b32 v[6:7], v43 offset0:140 offset1:173
	v_lshl_add_u64 v[12:13], v[10:11], 0, v[12:13]
	s_waitcnt lgkmcnt(0)
	v_cvt_pk_bf16_f32 v6, v6, v7
	ds_read2_b32 v[8:9], v43 offset0:206 offset1:239
	s_waitcnt lgkmcnt(0)
	v_cvt_pk_bf16_f32 v7, v8, v9
	global_store_dwordx4 v[12:13], v[4:7], off
	v_or_b32_e32 v12, s0, v47
	v_ashrrev_i32_e32 v13, 31, v12
	ds_read2_b32 v[8:9], v43 offset0:16 offset1:49
	s_waitcnt lgkmcnt(0)
	v_cvt_pk_bf16_f32 v4, v8, v9
	ds_read2_b32 v[6:7], v43 offset0:82 offset1:115
	v_lshlrev_b64 v[12:13], 9, v[12:13]
	s_waitcnt lgkmcnt(0)
	v_cvt_pk_bf16_f32 v5, v6, v7
	ds_read2_b32 v[6:7], v43 offset0:148 offset1:181
	v_lshl_add_u64 v[12:13], v[10:11], 0, v[12:13]
	s_waitcnt lgkmcnt(0)
	v_cvt_pk_bf16_f32 v6, v6, v7
	ds_read2_b32 v[8:9], v43 offset0:214 offset1:247
	s_waitcnt lgkmcnt(0)
	v_cvt_pk_bf16_f32 v7, v8, v9
	global_store_dwordx4 v[12:13], v[4:7], off
	v_or_b32_e32 v12, s0, v48
	v_ashrrev_i32_e32 v13, 31, v12
	ds_read2_b32 v[8:9], v43 offset0:24 offset1:57
	s_waitcnt lgkmcnt(0)
	v_cvt_pk_bf16_f32 v4, v8, v9
	ds_read2_b32 v[6:7], v43 offset0:90 offset1:123
	v_lshlrev_b64 v[12:13], 9, v[12:13]
	s_waitcnt lgkmcnt(0)
	v_cvt_pk_bf16_f32 v5, v6, v7
	ds_read2_b32 v[6:7], v43 offset0:156 offset1:189
	v_lshl_add_u64 v[10:11], v[10:11], 0, v[12:13]
	s_waitcnt lgkmcnt(0)
	v_cvt_pk_bf16_f32 v6, v6, v7
	ds_read2_b32 v[8:9], v43 offset0:222 offset1:255
	s_waitcnt lgkmcnt(0)
	v_cvt_pk_bf16_f32 v7, v8, v9
	global_store_dwordx4 v[10:11], v[4:7], off
	s_waitcnt lgkmcnt(0)
	s_add_i32 s15, s15, s9
	s_cmp_lt_i32 s15, 64
	s_cbranch_scc1 .LBB0_45
	s_branch .LBB0_42

; __device__ __forceinline__ unsigned cvt_pk_bf16(float lo, float hi) { unsigned r; asm volatile("v_cvt_pk_bf16_f32 %0, %1, %2" : "=v"(r) : "v"(lo), "v"(hi)); return r; }
; __global__ void __launch_bounds__(NWAVES * 64, 2) fwd_kernel(Args args) {
;     ...
;             for (int e = (bx * NWAVES * 64 + tid) * 4; e < PGRP * PGD * PGD; e += G * NWAVES * 64 * 4) {
;                 const int j = e % PGD, gi = e / (PGD * PGD); const f32x4 w = *(const f32x4*)(pool_w + e), sc = *(const f32x4*)(pool_scale + gi * PGD + j);
;                 v2u o; o.x = cvt_pk_bf16(w.x * sc.x, w.y * sc.y); o.y = cvt_pk_bf16(w.z * sc.z, w.w * sc.w); *(v2u*)(Wpool_t + e) = o; }
.LBB0_50:
	v_ashrrev_i32_e32 v1, 31, v2
	v_lshrrev_b32_e32 v3, 22, v1
	v_lshrrev_b32_e32 v1, 12, v1
	v_add_u32_e32 v1, v2, v1
	v_add_u32_e32 v3, v2, v3
	v_ashrrev_i32_e32 v1, 20, v1
	v_and_b32_e32 v3, 0xfffffc00, v3
	s_waitcnt vmcnt(23)
	v_lshlrev_b32_e32 v14, 10, v1
	v_sub_u32_e32 v12, v2, v3
	s_waitcnt vmcnt(20)
	v_ashrrev_i32_e32 v15, 31, v14
	v_ashrrev_i32_e32 v13, 31, v12
	v_lshl_add_u64 v[14:15], v[14:15], 2, s[66:67]
	v_lshl_add_u64 v[12:13], v[12:13], 2, v[14:15]
	global_load_dwordx4 v[8:11], v[4:5], off nt
	v_add_u32_e32 v2, s2, v2
	global_load_dwordx4 v[12:15], v[12:13], off nt
	v_cmp_lt_i32_e32 vcc, s3, v2
	v_lshl_add_u64 v[4:5], v[4:5], 0, s[4:5]
	s_or_b64 s[40:41], vcc, s[40:41]
	s_waitcnt vmcnt(0)
	v_mul_f32_e32 v3, v9, v13
	v_mul_f32_e32 v9, v10, v14
	v_mul_f32_e32 v1, v8, v12
	v_mul_f32_e32 v10, v11, v15
	v_cvt_pk_bf16_f32 v8, v1, v3
	v_cvt_pk_bf16_f32 v9, v9, v10
	global_store_dwordx2 v[6:7], v[8:9], off
	v_lshl_add_u64 v[6:7], v[6:7], 0, s[38:39]
	s_andn2_b64 exec, exec, s[40:41]
	s_cbranch_execnz .LBB0_50
; #define TR_MAP(it_, k0_, n0_, dr_) do { const int kb_ = (it_) / nblk, nb_ = (it_) % nblk; k0_ = 64 * kb_; n0_ = 32 * nb_; \
;         if (DMAP == 1) { const int isup_ = n0_ >= DFF ? 1 : 0, j_ = n0_ - isup_ * DFF; dr_ = drow_off + (j_ >> 7) * 256 + isup_ * 128 + (j_ & 127); } else dr_ = drow_off + n0_; } while (0)
; __device__ __forceinline__ void tr_load(float (&v)[32], const float* W, int N, int k0, int n0, int lane) {
;     const float* wp = W + (size_t)(k0 + (lane >> 5)) * N + n0 + (lane & 31);
; #pragma unroll
;     for (int i = 0; i < 32; ++i) v[i] = wp[(size_t)(2 * i) * N];
; }
;     const int nblk = (ncols ? ncols : N) / 32, nitems = (K / 64) * nblk;
;     int it = gw - (itbase % NGW); if (it < 0) it += NGW;
;     itbase += nitems;
;     if (it >= nitems) return;
;     ...
;     float va[32], vb[32]; int ka, na, da, kb2 = 0, nb2 = 0, db = 0;
;     TR_MAP(it, ka, na, da); tr_load(va, W, N, ka, na, lane);
.LBB0_51:
	s_or_b64 exec, exec, s[0:1]
	s_mul_hi_u32 s0, s11, 0x2400
	s_mul_i32 s0, s0, s8
	s_sub_i32 s0, 0x2400, s0
	s_sub_i32 s1, s0, s8
	s_cmp_ge_u32 s0, s8
	s_cselect_b32 s0, s1, s0
	s_sub_i32 s1, s0, s8
	s_cmp_ge_u32 s0, s8
	s_cselect_b32 s0, s1, s0
	v_readlane_b32 s1, v249, 40
	s_sub_i32 s0, s1, s0
	s_ashr_i32 s1, s0, 31
	s_and_b32 s1, s1, s9
	s_add_i32 s39, s1, s0
	v_readlane_b32 s50, v249, 33
	s_cmpk_gt_i32 s39, 0x1fff
	v_readlane_b32 s51, v249, 34
	s_cbranch_scc1 .LBB0_60
	s_ashr_i32 s0, s39, 31
	s_lshr_b32 s0, s0, 25
	s_add_i32 s0, s39, s0
	s_ashr_i32 s1, s0, 7
	s_and_b32 s0, s0, 0x7ffff80
	s_sub_i32 s2, s39, s0
	s_lshl_b32 s0, s1, 6
	v_or_b32_e32 v2, s0, v34
	v_ashrrev_i32_e32 v3, 31, v2
	v_readlane_b32 s12, v249, 43
	s_lshl_b32 s2, s2, 5
	v_lshlrev_b64 v[2:3], 14, v[2:3]
	v_readlane_b32 s13, v249, 44
	s_ashr_i32 s3, s2, 31
	v_mov_b32_e32 v37, 0
	v_lshl_add_u64 v[2:3], s[12:13], 0, v[2:3]
	v_lshl_add_u64 v[2:3], s[2:3], 2, v[2:3]
	v_lshl_add_u64 v[2:3], v[2:3], 0, v[36:37]
	s_mov_b32 s12, 0x8000
	v_add_co_u32_e32 v4, vcc, s12, v2
	s_mov_b32 s13, 0x10000
	s_waitcnt vmcnt(30)
	v_addc_co_u32_e32 v5, vcc, 0, v3, vcc
	v_readlane_b32 s14, v249, 45
	v_add_co_u32_e32 v6, vcc, s13, v2
	s_mov_b32 s14, 0x18000
	s_waitcnt vmcnt(28)
	v_addc_co_u32_e32 v7, vcc, 0, v3, vcc
	v_readlane_b32 s15, v249, 46
	v_add_co_u32_e32 v8, vcc, s14, v2
	s_mov_b32 s15, 0x20000
	s_waitcnt vmcnt(26)
	v_addc_co_u32_e32 v9, vcc, 0, v3, vcc
	v_readlane_b32 s16, v249, 47
	v_add_co_u32_e32 v10, vcc, s15, v2
	s_mov_b32 s16, 0x28000
	s_waitcnt vmcnt(24)
	v_addc_co_u32_e32 v11, vcc, 0, v3, vcc
	v_readlane_b32 s17, v249, 48
	v_add_co_u32_e32 v12, vcc, s16, v2
	s_mov_b32 s17, 0x30000
	s_waitcnt vmcnt(22)
	v_addc_co_u32_e32 v13, vcc, 0, v3, vcc
	v_readlane_b32 s18, v249, 49
	v_add_co_u32_e32 v14, vcc, s17, v2
	s_mov_b32 s18, 0x38000
	s_waitcnt vmcnt(20)
	v_addc_co_u32_e32 v15, vcc, 0, v3, vcc
	v_readlane_b32 s19, v249, 50
	v_add_co_u32_e32 v16, vcc, s18, v2
	s_mov_b32 s19, 0x40000
	s_waitcnt vmcnt(18)
	v_addc_co_u32_e32 v17, vcc, 0, v3, vcc
	v_readlane_b32 s20, v249, 51
	v_add_co_u32_e32 v18, vcc, s19, v2
	s_mov_b32 s20, 0x48000
	s_waitcnt vmcnt(16)
	v_addc_co_u32_e32 v19, vcc, 0, v3, vcc
	v_readlane_b32 s21, v249, 52
	v_add_co_u32_e32 v20, vcc, s20, v2
	s_mov_b32 s21, 0x50000
	s_waitcnt vmcnt(14)
	v_addc_co_u32_e32 v21, vcc, 0, v3, vcc
	v_readlane_b32 s22, v249, 53
	v_add_co_u32_e32 v22, vcc, s21, v2
	s_mov_b32 s22, 0x58000
	s_waitcnt vmcnt(12)
	v_addc_co_u32_e32 v23, vcc, 0, v3, vcc
	v_readlane_b32 s23, v249, 54
	v_add_co_u32_e32 v24, vcc, s22, v2
	s_mov_b32 s23, 0x60000
	s_waitcnt vmcnt(10)
	v_addc_co_u32_e32 v25, vcc, 0, v3, vcc
	v_readlane_b32 s24, v249, 55
	v_add_co_u32_e32 v26, vcc, s23, v2
	s_mov_b32 s24, 0x68000
	s_waitcnt vmcnt(8)
	v_addc_co_u32_e32 v27, vcc, 0, v3, vcc
	v_readlane_b32 s25, v249, 56
	v_add_co_u32_e32 v28, vcc, s24, v2
	s_mov_b32 s25, 0x70000
	s_waitcnt vmcnt(6)
	v_addc_co_u32_e32 v29, vcc, 0, v3, vcc
	v_readlane_b32 s26, v249, 57
	v_add_co_u32_e32 v30, vcc, s25, v2
	s_mov_b32 s26, 0x78000
	s_waitcnt vmcnt(4)
	v_addc_co_u32_e32 v31, vcc, 0, v3, vcc
	v_readlane_b32 s27, v249, 58
	v_add_co_u32_e32 v78, vcc, s26, v2
	s_mov_b32 s27, 0x80000
	s_nop 0
	v_addc_co_u32_e32 v79, vcc, 0, v3, vcc
	v_add_co_u32_e32 v80, vcc, s27, v2
	s_mov_b32 s28, 0x88000
	s_nop 0
	v_addc_co_u32_e32 v81, vcc, 0, v3, vcc
	v_add_co_u32_e32 v82, vcc, s28, v2
	s_mov_b32 s29, 0x90000
	s_nop 0
	v_addc_co_u32_e32 v83, vcc, 0, v3, vcc
	v_add_co_u32_e32 v84, vcc, s29, v2
	s_mov_b32 s33, 0x98000
	s_nop 0
	v_addc_co_u32_e32 v85, vcc, 0, v3, vcc
	v_add_co_u32_e32 v86, vcc, s33, v2
	s_mov_b32 s35, 0xa0000
	s_nop 0
	v_addc_co_u32_e32 v87, vcc, 0, v3, vcc
	v_add_co_u32_e32 v88, vcc, s35, v2
	s_mov_b32 s36, 0xa8000
	s_nop 0
	v_addc_co_u32_e32 v89, vcc, 0, v3, vcc
	v_add_co_u32_e32 v90, vcc, s36, v2
	s_mov_b32 s37, 0xb0000
	s_nop 0
	v_addc_co_u32_e32 v91, vcc, 0, v3, vcc
	v_mov_b32_e32 v39, v37
	v_add_co_u32_e32 v92, vcc, s37, v2
	v_lshl_add_u64 v[40:41], s[42:43], 0, v[38:39]
	s_nop 0
	v_addc_co_u32_e32 v93, vcc, 0, v3, vcc
	s_mov_b32 s42, 0xb8000
	v_add_co_u32_e32 v94, vcc, s42, v2
	s_mov_b32 s43, 0xc0000
	s_nop 0
	v_addc_co_u32_e32 v95, vcc, 0, v3, vcc
	v_add_co_u32_e32 v96, vcc, s43, v2
	s_mov_b32 s44, 0xc8000
	s_nop 0
	v_addc_co_u32_e32 v97, vcc, 0, v3, vcc
	v_add_co_u32_e32 v98, vcc, s44, v2
	s_mov_b32 s45, 0xd0000
	s_nop 0
	v_addc_co_u32_e32 v99, vcc, 0, v3, vcc
	v_add_co_u32_e32 v100, vcc, s45, v2
	s_mov_b32 s46, 0xd8000
	s_nop 0
	v_addc_co_u32_e32 v101, vcc, 0, v3, vcc
	v_add_co_u32_e32 v102, vcc, s46, v2
	s_mov_b32 s47, 0xe0000
	s_nop 0
	v_addc_co_u32_e32 v103, vcc, 0, v3, vcc
	v_add_co_u32_e32 v104, vcc, s47, v2
	s_mov_b32 s1, 0xe8000
	s_nop 0
	v_addc_co_u32_e32 v105, vcc, 0, v3, vcc
	v_add_co_u32_e32 v106, vcc, s1, v2
	s_mov_b32 s1, 0xf0000
	s_nop 0
	v_addc_co_u32_e32 v107, vcc, 0, v3, vcc
	v_add_co_u32_e32 v108, vcc, s1, v2
	s_mov_b32 s4, 0
	s_nop 0
	v_addc_co_u32_e32 v109, vcc, 0, v3, vcc
	v_add_co_u32_e32 v110, vcc, 0xf8000, v2
	s_lshl_b32 s48, s10, 4
	s_nop 0
	v_addc_co_u32_e32 v111, vcc, 0, v3, vcc
	global_load_dword v2, v[2:3], off nt
	s_nop 0
	global_load_dword v1, v[4:5], off nt
	s_nop 0
	global_load_dword v4, v[6:7], off nt
	global_load_dword v3, v[8:9], off nt
	s_nop 0
	global_load_dword v6, v[10:11], off nt
	global_load_dword v5, v[12:13], off nt
	global_load_dword v8, v[14:15], off nt
	global_load_dword v7, v[16:17], off nt
	s_nop 0
	global_load_dword v10, v[18:19], off nt
	global_load_dword v9, v[20:21], off nt
	global_load_dword v12, v[22:23], off nt
	global_load_dword v11, v[24:25], off nt
	global_load_dword v14, v[26:27], off nt
	global_load_dword v13, v[28:29], off nt
	global_load_dword v16, v[30:31], off nt
	global_load_dword v15, v[78:79], off nt
	global_load_dword v18, v[80:81], off nt
	global_load_dword v17, v[82:83], off nt
	global_load_dword v20, v[84:85], off nt
	global_load_dword v19, v[86:87], off nt
	global_load_dword v22, v[88:89], off nt
	global_load_dword v21, v[90:91], off nt
	global_load_dword v24, v[92:93], off nt
	global_load_dword v23, v[94:95], off nt
	global_load_dword v26, v[96:97], off nt
	global_load_dword v25, v[98:99], off nt
	global_load_dword v28, v[100:101], off nt
	global_load_dword v27, v[102:103], off nt
	global_load_dword v30, v[104:105], off nt
	global_load_dword v29, v[106:107], off nt
	global_load_dword v32, v[108:109], off nt
	global_load_dword v31, v[110:111], off nt
	s_mov_b32 s38, 0
	s_branch .LBB0_55

; #define TR_MAP(it_, k0_, n0_, dr_) do { const int kb_ = (it_) / nblk, nb_ = (it_) % nblk; k0_ = 64 * kb_; n0_ = 32 * nb_; \
;         if (DMAP == 1) { const int isup_ = n0_ >= DFF ? 1 : 0, j_ = n0_ - isup_ * DFF; dr_ = drow_off + (j_ >> 7) * 256 + isup_ * 128 + (j_ & 127); } else dr_ = drow_off + n0_; } while (0)
; __device__ __forceinline__ void tr_load(float (&v)[32], const float* W, int N, int k0, int n0, int lane) {
;     const float* wp = W + (size_t)(k0 + (lane >> 5)) * N + n0 + (lane & 31);
; #pragma unroll
;     for (int i = 0; i < 32; ++i) v[i] = wp[(size_t)(2 * i) * N];
; }
;     ...
;     while (true) {
;         const int itb = it + NGW; const bool hb = itb < nitems;
;         if (hb) { TR_MAP(itb, kb2, nb2, db); tr_load(vb, W, N, kb2, nb2, lane); }
;         tr_finish(va, WT, ldk, ka, da, scr, lane);
.LBB0_55:
	s_add_i32 s49, s39, s9
	s_cmpk_lt_i32 s49, 0x2000
	s_cselect_b64 s[40:41], -1, 0
	s_cmpk_gt_i32 s49, 0x1fff
	s_cbranch_scc1 .LBB0_57
	s_ashr_i32 s1, s49, 31
	s_lshr_b32 s1, s1, 25
	s_add_i32 s1, s49, s1
	s_ashr_i32 s3, s1, 7
	s_lshl_b32 s38, s3, 6
	s_and_b32 s1, s1, 0x7ffff80
	v_or_b32_e32 v44, s38, v34
	s_sub_i32 s1, s49, s1
	v_ashrrev_i32_e32 v45, 31, v44
	v_readlane_b32 s76, v249, 43
	s_lshl_b32 s4, s1, 5
	v_lshlrev_b64 v[44:45], 14, v[44:45]
	v_readlane_b32 s77, v249, 44
	s_ashr_i32 s5, s4, 31
	v_readlane_b32 s78, v249, 45
	v_lshl_add_u64 v[44:45], s[76:77], 0, v[44:45]
	v_lshl_add_u64 v[44:45], s[4:5], 2, v[44:45]
	v_lshl_add_u64 v[70:71], v[44:45], 0, v[36:37]
	v_add_co_u32_e32 v44, vcc, s12, v70
	v_readlane_b32 s76, v249, 59
	s_nop 0
	v_addc_co_u32_e32 v45, vcc, 0, v71, vcc
	v_add_co_u32_e32 v52, vcc, s13, v70
	v_readlane_b32 s79, v249, 46
	s_nop 0
	v_addc_co_u32_e32 v53, vcc, 0, v71, vcc
	v_add_co_u32_e32 v54, vcc, s14, v70
	v_readlane_b32 s80, v249, 47
	s_nop 0
	v_addc_co_u32_e32 v55, vcc, 0, v71, vcc
	v_add_co_u32_e32 v56, vcc, s15, v70
	v_readlane_b32 s81, v249, 48
	s_nop 0
	v_addc_co_u32_e32 v57, vcc, 0, v71, vcc
	v_add_co_u32_e32 v58, vcc, s16, v70
	v_readlane_b32 s82, v249, 49
	s_nop 0
	v_addc_co_u32_e32 v59, vcc, 0, v71, vcc
	v_add_co_u32_e32 v60, vcc, s17, v70
	v_readlane_b32 s83, v249, 50
	s_nop 0
	v_addc_co_u32_e32 v61, vcc, 0, v71, vcc
	v_add_co_u32_e32 v62, vcc, s18, v70
	v_readlane_b32 s84, v249, 51
	s_nop 0
	v_addc_co_u32_e32 v63, vcc, 0, v71, vcc
	global_load_dword v51, v[70:71], off nt
	global_load_dword v50, v[44:45], off nt
	global_load_dword v49, v[52:53], off nt
	s_nop 0
	global_load_dword v45, v[54:55], off nt
	global_load_dword v44, v[56:57], off nt
	global_load_dword v42, v[58:59], off nt
	global_load_dword v39, v[60:61], off nt
	global_load_dword v52, v[62:63], off nt
	v_add_co_u32_e32 v54, vcc, s19, v70
	v_readlane_b32 s85, v249, 52
	s_nop 0
	v_addc_co_u32_e32 v55, vcc, 0, v71, vcc
	v_add_co_u32_e32 v56, vcc, s20, v70
	v_readlane_b32 s86, v249, 53
	s_nop 0
	v_addc_co_u32_e32 v57, vcc, 0, v71, vcc
	v_add_co_u32_e32 v60, vcc, s21, v70
	v_readlane_b32 s87, v249, 54
	s_nop 0
	v_addc_co_u32_e32 v61, vcc, 0, v71, vcc
	v_add_co_u32_e32 v62, vcc, s22, v70
	v_readlane_b32 s88, v249, 55
	s_nop 0
	v_addc_co_u32_e32 v63, vcc, 0, v71, vcc
	v_add_co_u32_e32 v64, vcc, s23, v70
	v_readlane_b32 s89, v249, 56
	s_nop 0
	v_addc_co_u32_e32 v65, vcc, 0, v71, vcc
	v_add_co_u32_e32 v66, vcc, s24, v70
	v_readlane_b32 s90, v249, 57
	s_nop 0
	v_addc_co_u32_e32 v67, vcc, 0, v71, vcc
	v_add_co_u32_e32 v68, vcc, s25, v70
	v_readlane_b32 s91, v249, 58
	s_nop 0
	v_addc_co_u32_e32 v69, vcc, 0, v71, vcc
	v_add_co_u32_e32 v72, vcc, s26, v70
	s_nop 1
	v_addc_co_u32_e32 v73, vcc, 0, v71, vcc
	global_load_dword v59, v[54:55], off nt
	global_load_dword v58, v[56:57], off nt
	s_nop 0
	global_load_dword v57, v[60:61], off nt
	global_load_dword v56, v[62:63], off nt
	global_load_dword v55, v[64:65], off nt
	global_load_dword v54, v[66:67], off nt
	global_load_dword v53, v[68:69], off nt
	s_nop 0
	global_load_dword v60, v[72:73], off nt
	v_add_co_u32_e32 v62, vcc, s27, v70
	s_nop 1
	v_addc_co_u32_e32 v63, vcc, 0, v71, vcc
	v_add_co_u32_e32 v64, vcc, s28, v70
	s_nop 1
	v_addc_co_u32_e32 v65, vcc, 0, v71, vcc
	v_add_co_u32_e32 v68, vcc, s29, v70
	s_nop 1
	v_addc_co_u32_e32 v69, vcc, 0, v71, vcc
	v_add_co_u32_e32 v72, vcc, s33, v70
	s_nop 1
	v_addc_co_u32_e32 v73, vcc, 0, v71, vcc
	v_add_co_u32_e32 v74, vcc, s35, v70
	s_nop 1
	v_addc_co_u32_e32 v75, vcc, 0, v71, vcc
	v_add_co_u32_e32 v76, vcc, s36, v70
	s_nop 1
	v_addc_co_u32_e32 v77, vcc, 0, v71, vcc
	v_add_co_u32_e32 v78, vcc, s37, v70
	s_nop 1
	v_addc_co_u32_e32 v79, vcc, 0, v71, vcc
	v_add_co_u32_e32 v80, vcc, s42, v70
	s_nop 1
	v_addc_co_u32_e32 v81, vcc, 0, v71, vcc
	global_load_dword v67, v[62:63], off nt
	global_load_dword v66, v[64:65], off nt
	s_nop 0
	global_load_dword v65, v[68:69], off nt
	global_load_dword v64, v[72:73], off nt
	global_load_dword v63, v[74:75], off nt
	global_load_dword v62, v[76:77], off nt
	global_load_dword v61, v[78:79], off nt
	s_nop 0
	global_load_dword v68, v[80:81], off nt
	v_add_co_u32_e32 v72, vcc, s43, v70
	s_nop 1
	v_addc_co_u32_e32 v73, vcc, 0, v71, vcc
	v_add_co_u32_e32 v76, vcc, s44, v70
	s_nop 1
	v_addc_co_u32_e32 v77, vcc, 0, v71, vcc
	v_add_co_u32_e32 v78, vcc, s45, v70
	s_nop 1
	v_addc_co_u32_e32 v79, vcc, 0, v71, vcc
	v_add_co_u32_e32 v80, vcc, s46, v70
	s_nop 1
	v_addc_co_u32_e32 v81, vcc, 0, v71, vcc
	v_add_co_u32_e32 v82, vcc, 0xe0000, v70
	s_nop 1
	v_addc_co_u32_e32 v83, vcc, 0, v71, vcc
	v_add_co_u32_e32 v84, vcc, 0xe8000, v70
	s_nop 1
	v_addc_co_u32_e32 v85, vcc, 0, v71, vcc
	v_add_co_u32_e32 v86, vcc, 0xf0000, v70
	s_nop 1
	v_addc_co_u32_e32 v87, vcc, 0, v71, vcc
	v_add_co_u32_e32 v88, vcc, 0xf8000, v70
	s_nop 1
	v_addc_co_u32_e32 v89, vcc, 0, v71, vcc
	global_load_dword v75, v[72:73], off nt
	global_load_dword v74, v[76:77], off nt
	s_nop 0
	global_load_dword v73, v[78:79], off nt
	global_load_dword v72, v[80:81], off nt
	global_load_dword v71, v[82:83], off nt
	global_load_dword v70, v[84:85], off nt
	global_load_dword v69, v[86:87], off nt
	global_load_dword v76, v[88:89], off nt
; __device__ __forceinline__ unsigned cvt_pk_bf16(float lo, float hi) { unsigned r; asm volatile("v_cvt_pk_bf16_f32 %0, %1, %2" : "=v"(r) : "v"(lo), "v"(hi)); return r; }
; #define LAS __attribute__((address_space(3)))
; #define LDS_WAIT() asm volatile("s_waitcnt lgkmcnt(0)" ::: "memory")
; #define TR_MAP(it_, k0_, n0_, dr_) do { const int kb_ = (it_) / nblk, nb_ = (it_) % nblk; k0_ = 64 * kb_; n0_ = 32 * nb_; \
;         if (DMAP == 1) { const int isup_ = n0_ >= DFF ? 1 : 0, j_ = n0_ - isup_ * DFF; dr_ = drow_off + (j_ >> 7) * 256 + isup_ * 128 + (j_ & 127); } else dr_ = drow_off + n0_; } while (0)
; __device__ __forceinline__ void tr_finish(const float (&v)[32], bf16* WT, int ldk, int k0, int drow0, LAS float* scr, int lane) {
; #pragma unroll
;     for (int i = 0; i < 32; ++i) scr[(2 * i + (lane >> 5)) * 33 + (lane & 31)] = v[i];
;     LDS_WAIT(); asm volatile("" ::: "memory");
;     const int c = lane & 7;
; #pragma unroll
;     for (int j = 0; j < 4; ++j) { const int n = (lane >> 3) + 8 * j; const LAS float* s = scr + (8 * c) * 33 + n;
;         v4u o;
;         { o.x = cvt_pk_bf16(s[0 * 33], s[1 * 33]); o.y = cvt_pk_bf16(s[2 * 33], s[3 * 33]); o.z = cvt_pk_bf16(s[4 * 33], s[5 * 33]); o.w = cvt_pk_bf16(s[6 * 33], s[7 * 33]); }
;         *(v4u*)(WT + (size_t)(drow0 + n) * ldk + k0 + 8 * c) = o; }
;     LDS_WAIT(); asm volatile("" ::: "memory");
;     ...
;         it = itb + NGW; const bool ha = it < nitems;
;         if (ha) { TR_MAP(it, ka, na, da); tr_load(va, W, N, ka, na, lane); }
.LBB0_57:
	v_add_u32_e32 v77, 0x400, v33
	v_add_u32_e32 v78, 0x800, v33
	v_add_u32_e32 v79, 0xc00, v33
	v_add_u32_e32 v80, 0x1000, v33
	v_add_u32_e32 v81, 0x1400, v33
	v_add_u32_e32 v82, 0x1800, v33
	v_add_u32_e32 v83, 0x1c00, v33
	s_waitcnt vmcnt(30)
	ds_write2_b32 v33, v2, v1 offset1:66
	s_waitcnt vmcnt(28)
	ds_write2_b32 v33, v4, v3 offset0:132 offset1:198
	s_waitcnt vmcnt(26)
	ds_write2_b32 v77, v6, v5 offset0:8 offset1:74
	s_waitcnt vmcnt(24)
	ds_write2_b32 v77, v8, v7 offset0:140 offset1:206
	s_waitcnt vmcnt(22)
	ds_write2_b32 v78, v10, v9 offset0:16 offset1:82
	s_waitcnt vmcnt(20)
	ds_write2_b32 v78, v12, v11 offset0:148 offset1:214
	s_waitcnt vmcnt(18)
	ds_write2_b32 v79, v14, v13 offset0:24 offset1:90
	s_waitcnt vmcnt(16)
	ds_write2_b32 v79, v16, v15 offset0:156 offset1:222
	s_waitcnt vmcnt(14)
	ds_write2_b32 v80, v18, v17 offset0:32 offset1:98
	s_waitcnt vmcnt(12)
	ds_write2_b32 v80, v20, v19 offset0:164 offset1:230
	s_waitcnt vmcnt(10)
	ds_write2_b32 v81, v22, v21 offset0:40 offset1:106
	s_waitcnt vmcnt(8)
	ds_write2_b32 v81, v24, v23 offset0:172 offset1:238
	s_waitcnt vmcnt(6)
	ds_write2_b32 v82, v26, v25 offset0:48 offset1:114
	s_waitcnt vmcnt(4)
	ds_write2_b32 v82, v28, v27 offset0:180 offset1:246
	s_waitcnt vmcnt(2)
	ds_write2_b32 v83, v30, v29 offset0:56 offset1:122
	s_waitcnt vmcnt(0)
	ds_write2_b32 v83, v32, v31 offset0:188 offset1:254
	s_waitcnt lgkmcnt(0)
	ds_read2_b32 v[84:85], v43 offset1:33
	s_waitcnt lgkmcnt(0)
	v_cvt_pk_bf16_f32 v84, v84, v85
	ds_read2_b32 v[86:87], v43 offset0:66 offset1:99
	s_waitcnt lgkmcnt(0)
	v_cvt_pk_bf16_f32 v85, v86, v87
	ds_read2_b32 v[86:87], v43 offset0:132 offset1:165
	s_waitcnt lgkmcnt(0)
	v_cvt_pk_bf16_f32 v86, v86, v87
	ds_read2_b32 v[88:89], v43 offset0:198 offset1:231
	s_waitcnt lgkmcnt(0)
	v_cvt_pk_bf16_f32 v87, v88, v89
	v_or_b32_e32 v88, s2, v35
	s_ashr_i32 s1, s0, 31
	v_ashrrev_i32_e32 v89, 31, v88
	v_lshlrev_b64 v[88:89], 13, v[88:89]
	v_lshl_add_u64 v[90:91], s[0:1], 1, v[40:41]
	v_lshl_add_u64 v[88:89], v[90:91], 0, v[88:89]
	global_store_dwordx4 v[88:89], v[84:87], off
	ds_read2_b32 v[84:85], v43 offset0:8 offset1:41
	s_andn2_b64 vcc, exec, s[40:41]
	s_waitcnt lgkmcnt(0)
	v_cvt_pk_bf16_f32 v84, v84, v85
	ds_read2_b32 v[86:87], v43 offset0:74 offset1:107
	s_waitcnt lgkmcnt(0)
	v_cvt_pk_bf16_f32 v85, v86, v87
	ds_read2_b32 v[86:87], v43 offset0:140 offset1:173
	s_waitcnt lgkmcnt(0)
	v_cvt_pk_bf16_f32 v86, v86, v87
	ds_read2_b32 v[88:89], v43 offset0:206 offset1:239
	s_waitcnt lgkmcnt(0)
	v_cvt_pk_bf16_f32 v87, v88, v89
	v_or_b32_e32 v88, s2, v46
	v_ashrrev_i32_e32 v89, 31, v88
	v_lshlrev_b64 v[88:89], 13, v[88:89]
	v_lshl_add_u64 v[88:89], v[90:91], 0, v[88:89]
	global_store_dwordx4 v[88:89], v[84:87], off
	ds_read2_b32 v[84:85], v43 offset0:16 offset1:49
	s_mov_b64 s[40:41], -1
	s_waitcnt lgkmcnt(0)
	v_cvt_pk_bf16_f32 v84, v84, v85
	ds_read2_b32 v[86:87], v43 offset0:82 offset1:115
	s_waitcnt lgkmcnt(0)
	v_cvt_pk_bf16_f32 v85, v86, v87
	ds_read2_b32 v[86:87], v43 offset0:148 offset1:181
	s_waitcnt lgkmcnt(0)
	v_cvt_pk_bf16_f32 v86, v86, v87
	ds_read2_b32 v[88:89], v43 offset0:214 offset1:247
	s_waitcnt lgkmcnt(0)
	v_cvt_pk_bf16_f32 v87, v88, v89
	v_or_b32_e32 v88, s2, v47
	v_ashrrev_i32_e32 v89, 31, v88
	v_lshlrev_b64 v[88:89], 13, v[88:89]
	v_lshl_add_u64 v[88:89], v[90:91], 0, v[88:89]
	global_store_dwordx4 v[88:89], v[84:87], off
	s_nop 1
	v_or_b32_e32 v84, s2, v48
	v_ashrrev_i32_e32 v85, 31, v84
	v_lshlrev_b64 v[84:85], 13, v[84:85]
	v_lshl_add_u64 v[88:89], v[90:91], 0, v[84:85]
	ds_read2_b32 v[84:85], v43 offset0:24 offset1:57
	s_waitcnt lgkmcnt(0)
	v_cvt_pk_bf16_f32 v84, v84, v85
	ds_read2_b32 v[86:87], v43 offset0:90 offset1:123
	s_waitcnt lgkmcnt(0)
	v_cvt_pk_bf16_f32 v85, v86, v87
	ds_read2_b32 v[86:87], v43 offset0:156 offset1:189
	s_waitcnt lgkmcnt(0)
	v_cvt_pk_bf16_f32 v86, v86, v87
	ds_read2_b32 v[90:91], v43 offset0:222 offset1:255
	s_waitcnt lgkmcnt(0)
	v_cvt_pk_bf16_f32 v87, v90, v91
	global_store_dwordx4 v[88:89], v[84:87], off
	s_waitcnt lgkmcnt(0)
	s_cbranch_vccnz .LBB0_54
	s_add_i32 s1, s48, s39
	s_cmpk_gt_i32 s1, 0x1fff
	s_cbranch_scc1 .LBB0_53
	s_ashr_i32 s0, s1, 31
	s_lshr_b32 s0, s0, 25
	s_add_i32 s0, s1, s0
	s_ashr_i32 s2, s0, 7
	s_and_b32 s0, s0, 0x7ffff80
	s_sub_i32 s1, s1, s0
	s_lshl_b32 s0, s2, 6
	v_or_b32_e32 v2, s0, v34
	v_ashrrev_i32_e32 v3, 31, v2
	v_readlane_b32 s76, v249, 43
	s_lshl_b32 s2, s1, 5
	v_lshlrev_b64 v[2:3], 14, v[2:3]
	v_readlane_b32 s77, v249, 44
	s_ashr_i32 s3, s2, 31
	v_readlane_b32 s78, v249, 45
	v_lshl_add_u64 v[2:3], s[76:77], 0, v[2:3]
	v_lshl_add_u64 v[2:3], s[2:3], 2, v[2:3]
	v_lshl_add_u64 v[2:3], v[2:3], 0, v[36:37]
	v_add_co_u32_e32 v4, vcc, s12, v2
	v_readlane_b32 s76, v249, 59
	s_nop 0
	v_addc_co_u32_e32 v5, vcc, 0, v3, vcc
	v_add_co_u32_e32 v6, vcc, s13, v2
	v_readlane_b32 s79, v249, 46
	s_nop 0
	v_addc_co_u32_e32 v7, vcc, 0, v3, vcc
	v_add_co_u32_e32 v8, vcc, s14, v2
	v_readlane_b32 s80, v249, 47
	s_nop 0
	v_addc_co_u32_e32 v9, vcc, 0, v3, vcc
	v_add_co_u32_e32 v10, vcc, s15, v2
	v_readlane_b32 s81, v249, 48
	s_nop 0
	v_addc_co_u32_e32 v11, vcc, 0, v3, vcc
	v_add_co_u32_e32 v12, vcc, s16, v2
	v_readlane_b32 s82, v249, 49
	s_nop 0
	v_addc_co_u32_e32 v13, vcc, 0, v3, vcc
	v_add_co_u32_e32 v14, vcc, s17, v2
	v_readlane_b32 s83, v249, 50
	s_nop 0
	v_addc_co_u32_e32 v15, vcc, 0, v3, vcc
	v_add_co_u32_e32 v16, vcc, s18, v2
	v_readlane_b32 s84, v249, 51
	s_nop 0
	v_addc_co_u32_e32 v17, vcc, 0, v3, vcc
	v_add_co_u32_e32 v18, vcc, s19, v2
	v_readlane_b32 s85, v249, 52
	s_nop 0
	v_addc_co_u32_e32 v19, vcc, 0, v3, vcc
	v_add_co_u32_e32 v20, vcc, s20, v2
	v_readlane_b32 s86, v249, 53
	s_nop 0
	v_addc_co_u32_e32 v21, vcc, 0, v3, vcc
; #define TR_MAP(it_, k0_, n0_, dr_) do { const int kb_ = (it_) / nblk, nb_ = (it_) % nblk; k0_ = 64 * kb_; n0_ = 32 * nb_; \
;         if (DMAP == 1) { const int isup_ = n0_ >= DFF ? 1 : 0, j_ = n0_ - isup_ * DFF; dr_ = drow_off + (j_ >> 7) * 256 + isup_ * 128 + (j_ & 127); } else dr_ = drow_off + n0_; } while (0)
; __device__ __forceinline__ void tr_load(float (&v)[32], const float* W, int N, int k0, int n0, int lane) {
;     const float* wp = W + (size_t)(k0 + (lane >> 5)) * N + n0 + (lane & 31);
; #pragma unroll
;     for (int i = 0; i < 32; ++i) v[i] = wp[(size_t)(2 * i) * N];
; }
;     ...
;         it = itb + NGW; const bool ha = it < nitems;
;         if (ha) { TR_MAP(it, ka, na, da); tr_load(va, W, N, ka, na, lane); }
	v_add_co_u32_e32 v22, vcc, s21, v2
	v_readlane_b32 s87, v249, 54
	s_nop 0
	v_addc_co_u32_e32 v23, vcc, 0, v3, vcc
	v_add_co_u32_e32 v24, vcc, s22, v2
	v_readlane_b32 s88, v249, 55
	s_nop 0
	v_addc_co_u32_e32 v25, vcc, 0, v3, vcc
	v_add_co_u32_e32 v26, vcc, s23, v2
	v_readlane_b32 s89, v249, 56
	s_nop 0
	v_addc_co_u32_e32 v27, vcc, 0, v3, vcc
	v_add_co_u32_e32 v28, vcc, s24, v2
	v_readlane_b32 s90, v249, 57
	s_nop 0
	v_addc_co_u32_e32 v29, vcc, 0, v3, vcc
	v_add_co_u32_e32 v30, vcc, s25, v2
	v_readlane_b32 s91, v249, 58
	s_nop 0
	v_addc_co_u32_e32 v31, vcc, 0, v3, vcc
	v_add_co_u32_e32 v84, vcc, s26, v2
	s_nop 1
	v_addc_co_u32_e32 v85, vcc, 0, v3, vcc
	v_add_co_u32_e32 v86, vcc, s27, v2
	s_nop 1
	v_addc_co_u32_e32 v87, vcc, 0, v3, vcc
	v_add_co_u32_e32 v88, vcc, s28, v2
	s_nop 1
	v_addc_co_u32_e32 v89, vcc, 0, v3, vcc
	v_add_co_u32_e32 v90, vcc, s29, v2
	s_nop 1
	v_addc_co_u32_e32 v91, vcc, 0, v3, vcc
	v_add_co_u32_e32 v92, vcc, s33, v2
	s_nop 1
	v_addc_co_u32_e32 v93, vcc, 0, v3, vcc
	v_add_co_u32_e32 v94, vcc, s35, v2
	s_nop 1
	v_addc_co_u32_e32 v95, vcc, 0, v3, vcc
	v_add_co_u32_e32 v96, vcc, s36, v2
	s_nop 1
	v_addc_co_u32_e32 v97, vcc, 0, v3, vcc
	v_add_co_u32_e32 v98, vcc, s37, v2
	s_nop 1
	v_addc_co_u32_e32 v99, vcc, 0, v3, vcc
	v_add_co_u32_e32 v100, vcc, s42, v2
	s_nop 1
	v_addc_co_u32_e32 v101, vcc, 0, v3, vcc
	v_add_co_u32_e32 v102, vcc, s43, v2
	s_nop 1
	v_addc_co_u32_e32 v103, vcc, 0, v3, vcc
	v_add_co_u32_e32 v104, vcc, s44, v2
	s_nop 1
	v_addc_co_u32_e32 v105, vcc, 0, v3, vcc
	v_add_co_u32_e32 v106, vcc, s45, v2
	s_nop 1
	v_addc_co_u32_e32 v107, vcc, 0, v3, vcc
	v_add_co_u32_e32 v108, vcc, s46, v2
	s_nop 1
	v_addc_co_u32_e32 v109, vcc, 0, v3, vcc
	v_add_co_u32_e32 v110, vcc, s47, v2
	s_nop 1
	v_addc_co_u32_e32 v111, vcc, 0, v3, vcc
	v_add_co_u32_e32 v112, vcc, 0xe8000, v2
	s_nop 1
	v_addc_co_u32_e32 v113, vcc, 0, v3, vcc
	v_add_co_u32_e32 v114, vcc, 0xf0000, v2
	s_nop 1
	v_addc_co_u32_e32 v115, vcc, 0, v3, vcc
	v_add_co_u32_e32 v116, vcc, 0xf8000, v2
	s_nop 1
	v_addc_co_u32_e32 v117, vcc, 0, v3, vcc
	global_load_dword v2, v[2:3], off nt
	s_nop 0
	global_load_dword v1, v[4:5], off nt
	s_nop 0
	global_load_dword v4, v[6:7], off nt
	global_load_dword v3, v[8:9], off nt
	s_nop 0
	global_load_dword v6, v[10:11], off nt
	global_load_dword v5, v[12:13], off nt
	global_load_dword v8, v[14:15], off nt
	global_load_dword v7, v[16:17], off nt
	s_nop 0
	global_load_dword v10, v[18:19], off nt
	global_load_dword v9, v[20:21], off nt
	global_load_dword v12, v[22:23], off nt
	global_load_dword v11, v[24:25], off nt
	global_load_dword v14, v[26:27], off nt
	global_load_dword v13, v[28:29], off nt
	global_load_dword v16, v[30:31], off nt
	global_load_dword v15, v[84:85], off nt
	global_load_dword v18, v[86:87], off nt
	global_load_dword v17, v[88:89], off nt
	global_load_dword v20, v[90:91], off nt
	global_load_dword v19, v[92:93], off nt
	global_load_dword v22, v[94:95], off nt
	global_load_dword v21, v[96:97], off nt
	global_load_dword v24, v[98:99], off nt
	global_load_dword v23, v[100:101], off nt
	global_load_dword v26, v[102:103], off nt
	global_load_dword v25, v[104:105], off nt
	global_load_dword v28, v[106:107], off nt
	global_load_dword v27, v[108:109], off nt
	global_load_dword v30, v[110:111], off nt
	global_load_dword v29, v[112:113], off nt
	global_load_dword v32, v[114:115], off nt
	global_load_dword v31, v[116:117], off nt
	s_branch .LBB0_53
; #define TR_MAP(it_, k0_, n0_, dr_) do { const int kb_ = (it_) / nblk, nb_ = (it_) % nblk; k0_ = 64 * kb_; n0_ = 32 * nb_; \
;         if (DMAP == 1) { const int isup_ = n0_ >= DFF ? 1 : 0, j_ = n0_ - isup_ * DFF; dr_ = drow_off + (j_ >> 7) * 256 + isup_ * 128 + (j_ & 127); } else dr_ = drow_off + n0_; } while (0)
; __device__ __forceinline__ void tr_load(float (&v)[32], const float* W, int N, int k0, int n0, int lane) {
;     const float* wp = W + (size_t)(k0 + (lane >> 5)) * N + n0 + (lane & 31);
; #pragma unroll
;     for (int i = 0; i < 32; ++i) v[i] = wp[(size_t)(2 * i) * N];
; }
;     const int nblk = (ncols ? ncols : N) / 32, nitems = (K / 64) * nblk;
;     int it = gw - (itbase % NGW); if (it < 0) it += NGW;
;     itbase += nitems;
;     if (it >= nitems) return;
;     ...
;     float va[32], vb[32]; int ka, na, da, kb2 = 0, nb2 = 0, db = 0;
;     TR_MAP(it, ka, na, da); tr_load(va, W, N, ka, na, lane);
.LBB0_60:
	s_mul_hi_u32 s0, s11, 0x4400
	s_mul_i32 s0, s0, s8
	s_sub_i32 s0, 0x4400, s0
	s_sub_i32 s1, s0, s8
	s_cmp_ge_u32 s0, s8
	s_cselect_b32 s0, s1, s0
	s_sub_i32 s1, s0, s8
	s_cmp_ge_u32 s0, s8
	s_cselect_b32 s0, s1, s0
	v_readlane_b32 s1, v249, 40
	s_sub_i32 s0, s1, s0
	s_ashr_i32 s1, s0, 31
	s_and_b32 s1, s1, s9
	s_add_i32 s13, s1, s0
	s_cmpk_gt_i32 s13, 0x1fff
	s_cbranch_scc1 .LBB0_69
	s_ashr_i32 s0, s13, 31
	s_lshr_b32 s0, s0, 25
	s_add_i32 s0, s13, s0
	s_ashr_i32 s1, s0, 7
	s_and_b32 s0, s0, 0x7ffff80
	v_mov_b32_e32 v37, 0
	s_sub_i32 s2, s13, s0
	s_lshl_b32 s0, s1, 6
	v_mov_b32_e32 v39, v37
	s_waitcnt vmcnt(35)
	v_or_b32_e32 v2, s0, v34
	v_lshl_add_u64 v[40:41], s[50:51], 0, v[38:39]
	s_waitcnt vmcnt(32)
	v_ashrrev_i32_e32 v3, 31, v2
	v_readlane_b32 s36, v249, 43
	s_lshl_b32 s2, s2, 5
	v_lshlrev_b64 v[2:3], 14, v[2:3]
	v_readlane_b32 s38, v249, 45
	v_readlane_b32 s39, v249, 46
	s_ashr_i32 s3, s2, 31
	s_mov_b32 s14, 0x8000
	v_lshl_add_u64 v[2:3], s[38:39], 0, v[2:3]
	v_lshl_add_u64 v[2:3], s[2:3], 2, v[2:3]
	v_lshl_add_u64 v[2:3], v[2:3], 0, v[36:37]
	v_add_co_u32_e32 v4, vcc, s14, v2
	s_mov_b32 s15, 0x10000
	s_waitcnt vmcnt(30)
	v_addc_co_u32_e32 v5, vcc, 0, v3, vcc
	v_add_co_u32_e32 v6, vcc, s15, v2
	s_mov_b32 s16, 0x18000
	s_waitcnt vmcnt(28)
	v_addc_co_u32_e32 v7, vcc, 0, v3, vcc
	v_add_co_u32_e32 v8, vcc, s16, v2
	s_mov_b32 s17, 0x20000
	s_waitcnt vmcnt(26)
	v_addc_co_u32_e32 v9, vcc, 0, v3, vcc
	v_add_co_u32_e32 v10, vcc, s17, v2
	s_mov_b32 s18, 0x28000
	s_waitcnt vmcnt(24)
	v_addc_co_u32_e32 v11, vcc, 0, v3, vcc
	v_add_co_u32_e32 v12, vcc, s18, v2
	s_mov_b32 s19, 0x30000
	s_waitcnt vmcnt(22)
	v_addc_co_u32_e32 v13, vcc, 0, v3, vcc
	v_add_co_u32_e32 v14, vcc, s19, v2
	s_mov_b32 s20, 0x38000
	s_waitcnt vmcnt(20)
	v_addc_co_u32_e32 v15, vcc, 0, v3, vcc
	v_add_co_u32_e32 v16, vcc, s20, v2
	s_mov_b32 s21, 0x40000
	s_waitcnt vmcnt(18)
	v_addc_co_u32_e32 v17, vcc, 0, v3, vcc
	v_add_co_u32_e32 v18, vcc, s21, v2
	s_mov_b32 s22, 0x48000
	s_waitcnt vmcnt(16)
	v_addc_co_u32_e32 v19, vcc, 0, v3, vcc
	v_add_co_u32_e32 v20, vcc, s22, v2
	s_mov_b32 s23, 0x50000
	s_waitcnt vmcnt(14)
	v_addc_co_u32_e32 v21, vcc, 0, v3, vcc
	v_add_co_u32_e32 v22, vcc, s23, v2
	s_mov_b32 s24, 0x58000
	s_waitcnt vmcnt(12)
	v_addc_co_u32_e32 v23, vcc, 0, v3, vcc
	v_add_co_u32_e32 v24, vcc, s24, v2
	s_mov_b32 s25, 0x60000
	s_waitcnt vmcnt(10)
	v_addc_co_u32_e32 v25, vcc, 0, v3, vcc
	v_add_co_u32_e32 v26, vcc, s25, v2
	s_mov_b32 s26, 0x68000
	s_waitcnt vmcnt(8)
	v_addc_co_u32_e32 v27, vcc, 0, v3, vcc
	v_add_co_u32_e32 v28, vcc, s26, v2
	s_mov_b32 s27, 0x70000
	s_waitcnt vmcnt(6)
	v_addc_co_u32_e32 v29, vcc, 0, v3, vcc
	v_add_co_u32_e32 v30, vcc, s27, v2
	s_mov_b32 s28, 0x78000
	s_waitcnt vmcnt(4)
	v_addc_co_u32_e32 v31, vcc, 0, v3, vcc
	v_add_co_u32_e32 v78, vcc, s28, v2
	s_mov_b32 s29, 0x80000
	s_nop 0
	v_addc_co_u32_e32 v79, vcc, 0, v3, vcc
	v_add_co_u32_e32 v80, vcc, s29, v2
	s_mov_b32 s33, 0x88000
	s_nop 0
	v_addc_co_u32_e32 v81, vcc, 0, v3, vcc
	v_add_co_u32_e32 v82, vcc, s33, v2
	s_mov_b32 s35, 0x90000
	s_nop 0
	v_addc_co_u32_e32 v83, vcc, 0, v3, vcc
	v_add_co_u32_e32 v84, vcc, s35, v2
	s_mov_b32 s36, 0x98000
	s_nop 0
	v_addc_co_u32_e32 v85, vcc, 0, v3, vcc
	v_readlane_b32 s37, v249, 44
	v_add_co_u32_e32 v86, vcc, s36, v2
	s_mov_b32 s37, 0xa0000
	s_nop 0
	v_addc_co_u32_e32 v87, vcc, 0, v3, vcc
	v_readlane_b32 s40, v249, 47
	v_add_co_u32_e32 v88, vcc, s37, v2
	s_mov_b32 s40, 0xa8000
	s_nop 0
	v_addc_co_u32_e32 v89, vcc, 0, v3, vcc
	v_readlane_b32 s41, v249, 48
	v_add_co_u32_e32 v90, vcc, s40, v2
	s_mov_b32 s41, 0xb0000
	s_nop 0
	v_addc_co_u32_e32 v91, vcc, 0, v3, vcc
	v_readlane_b32 s42, v249, 49
	v_add_co_u32_e32 v92, vcc, s41, v2
	s_mov_b32 s42, 0xb8000
	s_nop 0
	v_addc_co_u32_e32 v93, vcc, 0, v3, vcc
	v_readlane_b32 s43, v249, 50
	v_add_co_u32_e32 v94, vcc, s42, v2
	s_mov_b32 s43, 0xc0000
	s_nop 0
	v_addc_co_u32_e32 v95, vcc, 0, v3, vcc
	v_readlane_b32 s44, v249, 51
	v_add_co_u32_e32 v96, vcc, s43, v2
	s_mov_b32 s44, 0xc8000
	s_nop 0
	v_addc_co_u32_e32 v97, vcc, 0, v3, vcc
	v_readlane_b32 s45, v249, 52
	v_add_co_u32_e32 v98, vcc, s44, v2
	s_mov_b32 s45, 0xd0000
	s_nop 0
	v_addc_co_u32_e32 v99, vcc, 0, v3, vcc
	v_readlane_b32 s46, v249, 53
	v_add_co_u32_e32 v100, vcc, s45, v2
	s_mov_b32 s46, 0xd8000
	s_nop 0
	v_addc_co_u32_e32 v101, vcc, 0, v3, vcc
	v_readlane_b32 s47, v249, 54
	v_add_co_u32_e32 v102, vcc, s46, v2
	s_mov_b32 s47, 0xe0000
	s_nop 0
	v_addc_co_u32_e32 v103, vcc, 0, v3, vcc
	v_add_co_u32_e32 v104, vcc, s47, v2
	s_mov_b32 s1, 0xe8000
	s_nop 0
	v_addc_co_u32_e32 v105, vcc, 0, v3, vcc
	v_add_co_u32_e32 v106, vcc, s1, v2
	s_mov_b32 s1, 0xf0000
	s_nop 0
	v_addc_co_u32_e32 v107, vcc, 0, v3, vcc
	v_add_co_u32_e32 v108, vcc, s1, v2
	v_readlane_b32 s48, v249, 55
	s_nop 0
	v_addc_co_u32_e32 v109, vcc, 0, v3, vcc
	v_add_co_u32_e32 v110, vcc, 0xf8000, v2
	s_mov_b32 s4, 0
	s_nop 0
	v_addc_co_u32_e32 v111, vcc, 0, v3, vcc
	global_load_dword v2, v[2:3], off nt
	s_nop 0
	global_load_dword v1, v[4:5], off nt
	s_nop 0
	global_load_dword v4, v[6:7], off nt
	global_load_dword v3, v[8:9], off nt
	s_nop 0
	global_load_dword v6, v[10:11], off nt
	global_load_dword v5, v[12:13], off nt
	global_load_dword v8, v[14:15], off nt
	global_load_dword v7, v[16:17], off nt
	s_nop 0
	global_load_dword v10, v[18:19], off nt
	global_load_dword v9, v[20:21], off nt
	global_load_dword v12, v[22:23], off nt
	global_load_dword v11, v[24:25], off nt
	global_load_dword v14, v[26:27], off nt
	global_load_dword v13, v[28:29], off nt
	global_load_dword v16, v[30:31], off nt
	global_load_dword v15, v[78:79], off nt
	global_load_dword v18, v[80:81], off nt
	global_load_dword v17, v[82:83], off nt
	global_load_dword v20, v[84:85], off nt
	global_load_dword v19, v[86:87], off nt
	global_load_dword v22, v[88:89], off nt
	global_load_dword v21, v[90:91], off nt
	global_load_dword v24, v[92:93], off nt
	global_load_dword v23, v[94:95], off nt
	global_load_dword v26, v[96:97], off nt
	global_load_dword v25, v[98:99], off nt
	global_load_dword v28, v[100:101], off nt
	global_load_dword v27, v[102:103], off nt
	global_load_dword v30, v[104:105], off nt
	global_load_dword v29, v[106:107], off nt
	global_load_dword v32, v[108:109], off nt
	global_load_dword v31, v[110:111], off nt
	s_lshl_b32 s48, s10, 4
	s_mov_b32 s12, 0
	v_readlane_b32 s49, v249, 56
	v_readlane_b32 s50, v249, 57
	v_readlane_b32 s51, v249, 58
	s_branch .LBB0_64

; #define TR_MAP(it_, k0_, n0_, dr_) do { const int kb_ = (it_) / nblk, nb_ = (it_) % nblk; k0_ = 64 * kb_; n0_ = 32 * nb_; \
;         if (DMAP == 1) { const int isup_ = n0_ >= DFF ? 1 : 0, j_ = n0_ - isup_ * DFF; dr_ = drow_off + (j_ >> 7) * 256 + isup_ * 128 + (j_ & 127); } else dr_ = drow_off + n0_; } while (0)
; __device__ __forceinline__ void tr_load(float (&v)[32], const float* W, int N, int k0, int n0, int lane) {
;     const float* wp = W + (size_t)(k0 + (lane >> 5)) * N + n0 + (lane & 31);
; #pragma unroll
;     for (int i = 0; i < 32; ++i) v[i] = wp[(size_t)(2 * i) * N];
; }
;     ...
;     while (true) {
;         const int itb = it + NGW; const bool hb = itb < nitems;
;         if (hb) { TR_MAP(itb, kb2, nb2, db); tr_load(vb, W, N, kb2, nb2, lane); }
;         tr_finish(va, WT, ldk, ka, da, scr, lane);
.LBB0_64:
	s_add_i32 s49, s13, s9
	s_cmpk_lt_i32 s49, 0x2000
	s_cselect_b64 s[38:39], -1, 0
	s_cmpk_gt_i32 s49, 0x1fff
	s_cbranch_scc1 .LBB0_66
	s_ashr_i32 s1, s49, 31
	s_lshr_b32 s1, s1, 25
	s_add_i32 s1, s49, s1
	s_ashr_i32 s3, s1, 7
	s_lshl_b32 s12, s3, 6
	s_and_b32 s1, s1, 0x7ffff80
	v_or_b32_e32 v44, s12, v34
	s_sub_i32 s1, s49, s1
	v_ashrrev_i32_e32 v45, 31, v44
	v_readlane_b32 s76, v249, 43
	s_lshl_b32 s4, s1, 5
	v_lshlrev_b64 v[44:45], 14, v[44:45]
	v_readlane_b32 s78, v249, 45
	v_readlane_b32 s79, v249, 46
	s_ashr_i32 s5, s4, 31
	v_readlane_b32 s76, v249, 59
	v_lshl_add_u64 v[44:45], s[78:79], 0, v[44:45]
	v_lshl_add_u64 v[44:45], s[4:5], 2, v[44:45]
	v_lshl_add_u64 v[70:71], v[44:45], 0, v[36:37]
	v_add_co_u32_e32 v44, vcc, s14, v70
	v_readlane_b32 s77, v249, 44
	s_nop 0
	v_addc_co_u32_e32 v45, vcc, 0, v71, vcc
	v_add_co_u32_e32 v52, vcc, s15, v70
	v_readlane_b32 s80, v249, 47
	s_nop 0
	v_addc_co_u32_e32 v53, vcc, 0, v71, vcc
	v_add_co_u32_e32 v54, vcc, s16, v70
	v_readlane_b32 s81, v249, 48
	s_nop 0
	v_addc_co_u32_e32 v55, vcc, 0, v71, vcc
	v_add_co_u32_e32 v56, vcc, s17, v70
	v_readlane_b32 s82, v249, 49
	s_nop 0
	v_addc_co_u32_e32 v57, vcc, 0, v71, vcc
	v_add_co_u32_e32 v58, vcc, s18, v70
	v_readlane_b32 s83, v249, 50
	s_nop 0
	v_addc_co_u32_e32 v59, vcc, 0, v71, vcc
	v_add_co_u32_e32 v60, vcc, s19, v70
	v_readlane_b32 s84, v249, 51
	s_nop 0
	v_addc_co_u32_e32 v61, vcc, 0, v71, vcc
	v_add_co_u32_e32 v62, vcc, s20, v70
	v_readlane_b32 s85, v249, 52
	s_nop 0
	v_addc_co_u32_e32 v63, vcc, 0, v71, vcc
	global_load_dword v51, v[70:71], off nt
	global_load_dword v50, v[44:45], off nt
	global_load_dword v49, v[52:53], off nt
	s_nop 0
	global_load_dword v45, v[54:55], off nt
	global_load_dword v44, v[56:57], off nt
	global_load_dword v42, v[58:59], off nt
	global_load_dword v39, v[60:61], off nt
	global_load_dword v52, v[62:63], off nt
	v_add_co_u32_e32 v54, vcc, s21, v70
	v_readlane_b32 s86, v249, 53
	s_nop 0
	v_addc_co_u32_e32 v55, vcc, 0, v71, vcc
	v_add_co_u32_e32 v56, vcc, s22, v70
	v_readlane_b32 s87, v249, 54
	s_nop 0
	v_addc_co_u32_e32 v57, vcc, 0, v71, vcc
	v_add_co_u32_e32 v60, vcc, s23, v70
	v_readlane_b32 s88, v249, 55
	s_nop 0
	v_addc_co_u32_e32 v61, vcc, 0, v71, vcc
	v_add_co_u32_e32 v62, vcc, s24, v70
	v_readlane_b32 s89, v249, 56
	s_nop 0
	v_addc_co_u32_e32 v63, vcc, 0, v71, vcc
	v_add_co_u32_e32 v64, vcc, s25, v70
	v_readlane_b32 s90, v249, 57
	s_nop 0
	v_addc_co_u32_e32 v65, vcc, 0, v71, vcc
	v_add_co_u32_e32 v66, vcc, s26, v70
	v_readlane_b32 s91, v249, 58
	s_nop 0
	v_addc_co_u32_e32 v67, vcc, 0, v71, vcc
	v_add_co_u32_e32 v68, vcc, s27, v70
	s_nop 1
	v_addc_co_u32_e32 v69, vcc, 0, v71, vcc
	v_add_co_u32_e32 v72, vcc, s28, v70
	s_nop 1
	v_addc_co_u32_e32 v73, vcc, 0, v71, vcc
	global_load_dword v59, v[54:55], off nt
	global_load_dword v58, v[56:57], off nt
	s_nop 0
	global_load_dword v57, v[60:61], off nt
	global_load_dword v56, v[62:63], off nt
	global_load_dword v55, v[64:65], off nt
	global_load_dword v54, v[66:67], off nt
	global_load_dword v53, v[68:69], off nt
	s_nop 0
	global_load_dword v60, v[72:73], off nt
	v_add_co_u32_e32 v62, vcc, s29, v70
	s_nop 1
	v_addc_co_u32_e32 v63, vcc, 0, v71, vcc
	v_add_co_u32_e32 v64, vcc, s33, v70
	s_nop 1
	v_addc_co_u32_e32 v65, vcc, 0, v71, vcc
	v_add_co_u32_e32 v68, vcc, s35, v70
	s_nop 1
	v_addc_co_u32_e32 v69, vcc, 0, v71, vcc
	v_add_co_u32_e32 v72, vcc, s36, v70
	s_nop 1
	v_addc_co_u32_e32 v73, vcc, 0, v71, vcc
	v_add_co_u32_e32 v74, vcc, s37, v70
	s_nop 1
	v_addc_co_u32_e32 v75, vcc, 0, v71, vcc
	v_add_co_u32_e32 v76, vcc, s40, v70
	s_nop 1
	v_addc_co_u32_e32 v77, vcc, 0, v71, vcc
	v_add_co_u32_e32 v78, vcc, s41, v70
	s_nop 1
	v_addc_co_u32_e32 v79, vcc, 0, v71, vcc
	v_add_co_u32_e32 v80, vcc, s42, v70
	s_nop 1
	v_addc_co_u32_e32 v81, vcc, 0, v71, vcc
	global_load_dword v67, v[62:63], off nt
	global_load_dword v66, v[64:65], off nt
	s_nop 0
	global_load_dword v65, v[68:69], off nt
	global_load_dword v64, v[72:73], off nt
	global_load_dword v63, v[74:75], off nt
	global_load_dword v62, v[76:77], off nt
	global_load_dword v61, v[78:79], off nt
	s_nop 0
	global_load_dword v68, v[80:81], off nt
	v_add_co_u32_e32 v72, vcc, s43, v70
	s_nop 1
	v_addc_co_u32_e32 v73, vcc, 0, v71, vcc
	v_add_co_u32_e32 v76, vcc, s44, v70
	s_nop 1
	v_addc_co_u32_e32 v77, vcc, 0, v71, vcc
	v_add_co_u32_e32 v78, vcc, s45, v70
	s_nop 1
	v_addc_co_u32_e32 v79, vcc, 0, v71, vcc
	v_add_co_u32_e32 v80, vcc, s46, v70
	s_nop 1
	v_addc_co_u32_e32 v81, vcc, 0, v71, vcc
	v_add_co_u32_e32 v82, vcc, 0xe0000, v70
	s_nop 1
	v_addc_co_u32_e32 v83, vcc, 0, v71, vcc
	v_add_co_u32_e32 v84, vcc, 0xe8000, v70
	s_nop 1
	v_addc_co_u32_e32 v85, vcc, 0, v71, vcc
	v_add_co_u32_e32 v86, vcc, 0xf0000, v70
	s_nop 1
	v_addc_co_u32_e32 v87, vcc, 0, v71, vcc
	v_add_co_u32_e32 v88, vcc, 0xf8000, v70
	s_nop 1
	v_addc_co_u32_e32 v89, vcc, 0, v71, vcc
	global_load_dword v75, v[72:73], off nt
	global_load_dword v74, v[76:77], off nt
	s_nop 0
	global_load_dword v73, v[78:79], off nt
	global_load_dword v72, v[80:81], off nt
	global_load_dword v71, v[82:83], off nt
	global_load_dword v70, v[84:85], off nt
	global_load_dword v69, v[86:87], off nt
	global_load_dword v76, v[88:89], off nt
; __device__ __forceinline__ unsigned cvt_pk_bf16(float lo, float hi) { unsigned r; asm volatile("v_cvt_pk_bf16_f32 %0, %1, %2" : "=v"(r) : "v"(lo), "v"(hi)); return r; }
; #define LAS __attribute__((address_space(3)))
; #define LDS_WAIT() asm volatile("s_waitcnt lgkmcnt(0)" ::: "memory")
; #define TR_MAP(it_, k0_, n0_, dr_) do { const int kb_ = (it_) / nblk, nb_ = (it_) % nblk; k0_ = 64 * kb_; n0_ = 32 * nb_; \
;         if (DMAP == 1) { const int isup_ = n0_ >= DFF ? 1 : 0, j_ = n0_ - isup_ * DFF; dr_ = drow_off + (j_ >> 7) * 256 + isup_ * 128 + (j_ & 127); } else dr_ = drow_off + n0_; } while (0)
; __device__ __forceinline__ void tr_finish(const float (&v)[32], bf16* WT, int ldk, int k0, int drow0, LAS float* scr, int lane) {
; #pragma unroll
;     for (int i = 0; i < 32; ++i) scr[(2 * i + (lane >> 5)) * 33 + (lane & 31)] = v[i];
;     LDS_WAIT(); asm volatile("" ::: "memory");
;     const int c = lane & 7;
; #pragma unroll
;     for (int j = 0; j < 4; ++j) { const int n = (lane >> 3) + 8 * j; const LAS float* s = scr + (8 * c) * 33 + n;
;         v4u o;
;         { o.x = cvt_pk_bf16(s[0 * 33], s[1 * 33]); o.y = cvt_pk_bf16(s[2 * 33], s[3 * 33]); o.z = cvt_pk_bf16(s[4 * 33], s[5 * 33]); o.w = cvt_pk_bf16(s[6 * 33], s[7 * 33]); }
;         *(v4u*)(WT + (size_t)(drow0 + n) * ldk + k0 + 8 * c) = o; }
;     LDS_WAIT(); asm volatile("" ::: "memory");
;     ...
;         it = itb + NGW; const bool ha = it < nitems;
;         if (ha) { TR_MAP(it, ka, na, da); tr_load(va, W, N, ka, na, lane); }
.LBB0_66:
	v_add_u32_e32 v77, 0x400, v33
	v_add_u32_e32 v78, 0x800, v33
	v_add_u32_e32 v79, 0xc00, v33
	v_add_u32_e32 v80, 0x1000, v33
	v_add_u32_e32 v81, 0x1400, v33
	v_add_u32_e32 v82, 0x1800, v33
	v_add_u32_e32 v83, 0x1c00, v33
	s_waitcnt vmcnt(30)
	ds_write2_b32 v33, v2, v1 offset1:66
	s_waitcnt vmcnt(28)
	ds_write2_b32 v33, v4, v3 offset0:132 offset1:198
	s_waitcnt vmcnt(26)
	ds_write2_b32 v77, v6, v5 offset0:8 offset1:74
	s_waitcnt vmcnt(24)
	ds_write2_b32 v77, v8, v7 offset0:140 offset1:206
	s_waitcnt vmcnt(22)
	ds_write2_b32 v78, v10, v9 offset0:16 offset1:82
	s_waitcnt vmcnt(20)
	ds_write2_b32 v78, v12, v11 offset0:148 offset1:214
	s_waitcnt vmcnt(18)
	ds_write2_b32 v79, v14, v13 offset0:24 offset1:90
	s_waitcnt vmcnt(16)
	ds_write2_b32 v79, v16, v15 offset0:156 offset1:222
	s_waitcnt vmcnt(14)
	ds_write2_b32 v80, v18, v17 offset0:32 offset1:98
	s_waitcnt vmcnt(12)
	ds_write2_b32 v80, v20, v19 offset0:164 offset1:230
	s_waitcnt vmcnt(10)
	ds_write2_b32 v81, v22, v21 offset0:40 offset1:106
	s_waitcnt vmcnt(8)
	ds_write2_b32 v81, v24, v23 offset0:172 offset1:238
	s_waitcnt vmcnt(6)
	ds_write2_b32 v82, v26, v25 offset0:48 offset1:114
	s_waitcnt vmcnt(4)
	ds_write2_b32 v82, v28, v27 offset0:180 offset1:246
	s_waitcnt vmcnt(2)
	ds_write2_b32 v83, v30, v29 offset0:56 offset1:122
	s_waitcnt vmcnt(0)
	ds_write2_b32 v83, v32, v31 offset0:188 offset1:254
	s_waitcnt lgkmcnt(0)
	ds_read2_b32 v[84:85], v43 offset1:33
	s_waitcnt lgkmcnt(0)
	v_cvt_pk_bf16_f32 v84, v84, v85
	ds_read2_b32 v[86:87], v43 offset0:66 offset1:99
	s_waitcnt lgkmcnt(0)
	v_cvt_pk_bf16_f32 v85, v86, v87
	ds_read2_b32 v[86:87], v43 offset0:132 offset1:165
	s_waitcnt lgkmcnt(0)
	v_cvt_pk_bf16_f32 v86, v86, v87
	ds_read2_b32 v[88:89], v43 offset0:198 offset1:231
	s_waitcnt lgkmcnt(0)
	v_cvt_pk_bf16_f32 v87, v88, v89
	v_or_b32_e32 v88, s2, v35
	s_ashr_i32 s1, s0, 31
	v_ashrrev_i32_e32 v89, 31, v88
	v_lshlrev_b64 v[88:89], 13, v[88:89]
	v_lshl_add_u64 v[90:91], s[0:1], 1, v[40:41]
	v_lshl_add_u64 v[88:89], v[90:91], 0, v[88:89]
	global_store_dwordx4 v[88:89], v[84:87], off
	ds_read2_b32 v[84:85], v43 offset0:8 offset1:41
	s_andn2_b64 vcc, exec, s[38:39]
	s_waitcnt lgkmcnt(0)
	v_cvt_pk_bf16_f32 v84, v84, v85
	ds_read2_b32 v[86:87], v43 offset0:74 offset1:107
	s_waitcnt lgkmcnt(0)
	v_cvt_pk_bf16_f32 v85, v86, v87
	ds_read2_b32 v[86:87], v43 offset0:140 offset1:173
	s_waitcnt lgkmcnt(0)
	v_cvt_pk_bf16_f32 v86, v86, v87
	ds_read2_b32 v[88:89], v43 offset0:206 offset1:239
	s_waitcnt lgkmcnt(0)
	v_cvt_pk_bf16_f32 v87, v88, v89
	v_or_b32_e32 v88, s2, v46
	v_ashrrev_i32_e32 v89, 31, v88
	v_lshlrev_b64 v[88:89], 13, v[88:89]
	v_lshl_add_u64 v[88:89], v[90:91], 0, v[88:89]
	global_store_dwordx4 v[88:89], v[84:87], off
	ds_read2_b32 v[84:85], v43 offset0:16 offset1:49
	s_mov_b64 s[38:39], -1
	s_waitcnt lgkmcnt(0)
	v_cvt_pk_bf16_f32 v84, v84, v85
	ds_read2_b32 v[86:87], v43 offset0:82 offset1:115
	s_waitcnt lgkmcnt(0)
	v_cvt_pk_bf16_f32 v85, v86, v87
	ds_read2_b32 v[86:87], v43 offset0:148 offset1:181
	s_waitcnt lgkmcnt(0)
	v_cvt_pk_bf16_f32 v86, v86, v87
	ds_read2_b32 v[88:89], v43 offset0:214 offset1:247
	s_waitcnt lgkmcnt(0)
	v_cvt_pk_bf16_f32 v87, v88, v89
	v_or_b32_e32 v88, s2, v47
	v_ashrrev_i32_e32 v89, 31, v88
	v_lshlrev_b64 v[88:89], 13, v[88:89]
	v_lshl_add_u64 v[88:89], v[90:91], 0, v[88:89]
	global_store_dwordx4 v[88:89], v[84:87], off
	s_nop 1
	v_or_b32_e32 v84, s2, v48
	v_ashrrev_i32_e32 v85, 31, v84
	v_lshlrev_b64 v[84:85], 13, v[84:85]
	v_lshl_add_u64 v[88:89], v[90:91], 0, v[84:85]
	ds_read2_b32 v[84:85], v43 offset0:24 offset1:57
	s_waitcnt lgkmcnt(0)
	v_cvt_pk_bf16_f32 v84, v84, v85
	ds_read2_b32 v[86:87], v43 offset0:90 offset1:123
	s_waitcnt lgkmcnt(0)
	v_cvt_pk_bf16_f32 v85, v86, v87
	ds_read2_b32 v[86:87], v43 offset0:156 offset1:189
	s_waitcnt lgkmcnt(0)
	v_cvt_pk_bf16_f32 v86, v86, v87
	ds_read2_b32 v[90:91], v43 offset0:222 offset1:255
	s_waitcnt lgkmcnt(0)
	v_cvt_pk_bf16_f32 v87, v90, v91
	global_store_dwordx4 v[88:89], v[84:87], off
	s_waitcnt lgkmcnt(0)
	s_cbranch_vccnz .LBB0_63
	s_add_i32 s1, s48, s13
	s_cmpk_gt_i32 s1, 0x1fff
	s_cbranch_scc1 .LBB0_62
	s_ashr_i32 s0, s1, 31
	s_lshr_b32 s0, s0, 25
	s_add_i32 s0, s1, s0
	s_ashr_i32 s2, s0, 7
	s_and_b32 s0, s0, 0x7ffff80
	s_sub_i32 s1, s1, s0
	s_lshl_b32 s0, s2, 6
	v_or_b32_e32 v2, s0, v34
	v_ashrrev_i32_e32 v3, 31, v2
	v_readlane_b32 s76, v249, 43
	s_lshl_b32 s2, s1, 5
	v_lshlrev_b64 v[2:3], 14, v[2:3]
	v_readlane_b32 s78, v249, 45
	v_readlane_b32 s79, v249, 46
	s_ashr_i32 s3, s2, 31
	v_readlane_b32 s76, v249, 59
	v_lshl_add_u64 v[2:3], s[78:79], 0, v[2:3]
	v_lshl_add_u64 v[2:3], s[2:3], 2, v[2:3]
	v_lshl_add_u64 v[2:3], v[2:3], 0, v[36:37]
	v_add_co_u32_e32 v4, vcc, s14, v2
	v_readlane_b32 s77, v249, 44
	s_nop 0
	v_addc_co_u32_e32 v5, vcc, 0, v3, vcc
	v_add_co_u32_e32 v6, vcc, s15, v2
	v_readlane_b32 s80, v249, 47
	s_nop 0
	v_addc_co_u32_e32 v7, vcc, 0, v3, vcc
	v_add_co_u32_e32 v8, vcc, s16, v2
	v_readlane_b32 s81, v249, 48
	s_nop 0
	v_addc_co_u32_e32 v9, vcc, 0, v3, vcc
	v_add_co_u32_e32 v10, vcc, s17, v2
	v_readlane_b32 s82, v249, 49
	s_nop 0
	v_addc_co_u32_e32 v11, vcc, 0, v3, vcc
	v_add_co_u32_e32 v12, vcc, s18, v2
	v_readlane_b32 s83, v249, 50
	s_nop 0
	v_addc_co_u32_e32 v13, vcc, 0, v3, vcc
	v_add_co_u32_e32 v14, vcc, s19, v2
	v_readlane_b32 s84, v249, 51
	s_nop 0
	v_addc_co_u32_e32 v15, vcc, 0, v3, vcc
	v_add_co_u32_e32 v16, vcc, s20, v2
	v_readlane_b32 s85, v249, 52
	s_nop 0
	v_addc_co_u32_e32 v17, vcc, 0, v3, vcc
	v_add_co_u32_e32 v18, vcc, s21, v2
	v_readlane_b32 s86, v249, 53
	s_nop 0
	v_addc_co_u32_e32 v19, vcc, 0, v3, vcc
	v_add_co_u32_e32 v20, vcc, s22, v2
	v_readlane_b32 s87, v249, 54
	s_nop 0
; #define TR_MAP(it_, k0_, n0_, dr_) do { const int kb_ = (it_) / nblk, nb_ = (it_) % nblk; k0_ = 64 * kb_; n0_ = 32 * nb_; \
;         if (DMAP == 1) { const int isup_ = n0_ >= DFF ? 1 : 0, j_ = n0_ - isup_ * DFF; dr_ = drow_off + (j_ >> 7) * 256 + isup_ * 128 + (j_ & 127); } else dr_ = drow_off + n0_; } while (0)
; __device__ __forceinline__ void tr_load(float (&v)[32], const float* W, int N, int k0, int n0, int lane) {
;     const float* wp = W + (size_t)(k0 + (lane >> 5)) * N + n0 + (lane & 31);
; #pragma unroll
;     for (int i = 0; i < 32; ++i) v[i] = wp[(size_t)(2 * i) * N];
; }
;     ...
;         it = itb + NGW; const bool ha = it < nitems;
;         if (ha) { TR_MAP(it, ka, na, da); tr_load(va, W, N, ka, na, lane); }
	v_addc_co_u32_e32 v21, vcc, 0, v3, vcc
	v_add_co_u32_e32 v22, vcc, s23, v2
	v_readlane_b32 s88, v249, 55
	s_nop 0
	v_addc_co_u32_e32 v23, vcc, 0, v3, vcc
	v_add_co_u32_e32 v24, vcc, s24, v2
	v_readlane_b32 s89, v249, 56
	s_nop 0
	v_addc_co_u32_e32 v25, vcc, 0, v3, vcc
	v_add_co_u32_e32 v26, vcc, s25, v2
	v_readlane_b32 s90, v249, 57
	s_nop 0
	v_addc_co_u32_e32 v27, vcc, 0, v3, vcc
	v_add_co_u32_e32 v28, vcc, s26, v2
	v_readlane_b32 s91, v249, 58
	s_nop 0
	v_addc_co_u32_e32 v29, vcc, 0, v3, vcc
	v_add_co_u32_e32 v30, vcc, s27, v2
	s_nop 1
	v_addc_co_u32_e32 v31, vcc, 0, v3, vcc
	v_add_co_u32_e32 v84, vcc, s28, v2
	s_nop 1
	v_addc_co_u32_e32 v85, vcc, 0, v3, vcc
	v_add_co_u32_e32 v86, vcc, s29, v2
	s_nop 1
	v_addc_co_u32_e32 v87, vcc, 0, v3, vcc
	v_add_co_u32_e32 v88, vcc, s33, v2
	s_nop 1
	v_addc_co_u32_e32 v89, vcc, 0, v3, vcc
	v_add_co_u32_e32 v90, vcc, s35, v2
	s_nop 1
	v_addc_co_u32_e32 v91, vcc, 0, v3, vcc
	v_add_co_u32_e32 v92, vcc, s36, v2
	s_nop 1
	v_addc_co_u32_e32 v93, vcc, 0, v3, vcc
	v_add_co_u32_e32 v94, vcc, s37, v2
	s_nop 1
	v_addc_co_u32_e32 v95, vcc, 0, v3, vcc
	v_add_co_u32_e32 v96, vcc, s40, v2
	s_nop 1
	v_addc_co_u32_e32 v97, vcc, 0, v3, vcc
	v_add_co_u32_e32 v98, vcc, s41, v2
	s_nop 1
	v_addc_co_u32_e32 v99, vcc, 0, v3, vcc
	v_add_co_u32_e32 v100, vcc, s42, v2
	s_nop 1
	v_addc_co_u32_e32 v101, vcc, 0, v3, vcc
	v_add_co_u32_e32 v102, vcc, s43, v2
	s_nop 1
	v_addc_co_u32_e32 v103, vcc, 0, v3, vcc
	v_add_co_u32_e32 v104, vcc, s44, v2
	s_nop 1
	v_addc_co_u32_e32 v105, vcc, 0, v3, vcc
	v_add_co_u32_e32 v106, vcc, s45, v2
	s_nop 1
	v_addc_co_u32_e32 v107, vcc, 0, v3, vcc
	v_add_co_u32_e32 v108, vcc, s46, v2
	s_nop 1
	v_addc_co_u32_e32 v109, vcc, 0, v3, vcc
	v_add_co_u32_e32 v110, vcc, s47, v2
	s_nop 1
	v_addc_co_u32_e32 v111, vcc, 0, v3, vcc
	v_add_co_u32_e32 v112, vcc, 0xe8000, v2
	s_nop 1
	v_addc_co_u32_e32 v113, vcc, 0, v3, vcc
	v_add_co_u32_e32 v114, vcc, 0xf0000, v2
	s_nop 1
	v_addc_co_u32_e32 v115, vcc, 0, v3, vcc
	v_add_co_u32_e32 v116, vcc, 0xf8000, v2
	s_nop 1
	v_addc_co_u32_e32 v117, vcc, 0, v3, vcc
	global_load_dword v2, v[2:3], off nt
	s_nop 0
	global_load_dword v1, v[4:5], off nt
	s_nop 0
	global_load_dword v4, v[6:7], off nt
	global_load_dword v3, v[8:9], off nt
	s_nop 0
	global_load_dword v6, v[10:11], off nt
	global_load_dword v5, v[12:13], off nt
	global_load_dword v8, v[14:15], off nt
	global_load_dword v7, v[16:17], off nt
	s_nop 0
	global_load_dword v10, v[18:19], off nt
	global_load_dword v9, v[20:21], off nt
	global_load_dword v12, v[22:23], off nt
	global_load_dword v11, v[24:25], off nt
	global_load_dword v14, v[26:27], off nt
	global_load_dword v13, v[28:29], off nt
	global_load_dword v16, v[30:31], off nt
	global_load_dword v15, v[84:85], off nt
	global_load_dword v18, v[86:87], off nt
	global_load_dword v17, v[88:89], off nt
	global_load_dword v20, v[90:91], off nt
	global_load_dword v19, v[92:93], off nt
	global_load_dword v22, v[94:95], off nt
	global_load_dword v21, v[96:97], off nt
	global_load_dword v24, v[98:99], off nt
	global_load_dword v23, v[100:101], off nt
	global_load_dword v26, v[102:103], off nt
	global_load_dword v25, v[104:105], off nt
	global_load_dword v28, v[106:107], off nt
	global_load_dword v27, v[108:109], off nt
	global_load_dword v30, v[110:111], off nt
	global_load_dword v29, v[112:113], off nt
	global_load_dword v32, v[114:115], off nt
	global_load_dword v31, v[116:117], off nt
	s_branch .LBB0_62
; #define TR_MAP(it_, k0_, n0_, dr_) do { const int kb_ = (it_) / nblk, nb_ = (it_) % nblk; k0_ = 64 * kb_; n0_ = 32 * nb_; \
;         if (DMAP == 1) { const int isup_ = n0_ >= DFF ? 1 : 0, j_ = n0_ - isup_ * DFF; dr_ = drow_off + (j_ >> 7) * 256 + isup_ * 128 + (j_ & 127); } else dr_ = drow_off + n0_; } while (0)
; __device__ __forceinline__ void tr_load(float (&v)[32], const float* W, int N, int k0, int n0, int lane) {
;     const float* wp = W + (size_t)(k0 + (lane >> 5)) * N + n0 + (lane & 31);
; #pragma unroll
;     for (int i = 0; i < 32; ++i) v[i] = wp[(size_t)(2 * i) * N];
; }
;     const int nblk = (ncols ? ncols : N) / 32, nitems = (K / 64) * nblk;
;     int it = gw - (itbase % NGW); if (it < 0) it += NGW;
;     itbase += nitems;
;     if (it >= nitems) return;
;     ...
;     float va[32], vb[32]; int ka, na, da, kb2 = 0, nb2 = 0, db = 0;
;     TR_MAP(it, ka, na, da); tr_load(va, W, N, ka, na, lane);
.LBB0_69:
	s_mul_hi_u32 s0, s11, 0x6400
	s_mul_i32 s0, s0, s8
	s_sub_i32 s0, 0x6400, s0
	s_sub_i32 s1, s0, s8
	s_cmp_ge_u32 s0, s8
	s_cselect_b32 s0, s1, s0
	s_sub_i32 s1, s0, s8
	s_cmp_ge_u32 s0, s8
	s_cselect_b32 s0, s1, s0
	v_readlane_b32 s1, v249, 40
	s_sub_i32 s0, s1, s0
	s_ashr_i32 s1, s0, 31
	s_and_b32 s1, s1, s9
	s_add_i32 s13, s1, s0
	s_cmpk_gt_i32 s13, 0x1fff
	s_cbranch_scc1 .LBB0_78
	v_mov_b32_e32 v37, 0
	v_readlane_b32 s0, v249, 29
	v_mov_b32_e32 v39, v37
	v_readlane_b32 s1, v249, 30
	v_readlane_b32 s36, v249, 43
	v_readlane_b32 s40, v249, 47
	v_lshl_add_u64 v[38:39], s[0:1], 0, v[38:39]
	s_ashr_i32 s0, s13, 31
	s_lshr_b32 s0, s0, 25
	s_add_i32 s0, s13, s0
	s_ashr_i32 s1, s0, 7
	s_and_b32 s0, s0, 0x7ffff80
	s_sub_i32 s2, s13, s0
	s_lshl_b32 s0, s1, 6
	s_waitcnt vmcnt(35)
	v_or_b32_e32 v2, s0, v34
	s_waitcnt vmcnt(32)
	v_ashrrev_i32_e32 v3, 31, v2
	s_lshl_b32 s2, s2, 5
	v_lshlrev_b64 v[2:3], 14, v[2:3]
	v_readlane_b32 s41, v249, 48
	s_ashr_i32 s3, s2, 31
	s_mov_b32 s8, 0x8000
	v_lshl_add_u64 v[2:3], s[40:41], 0, v[2:3]
	v_lshl_add_u64 v[2:3], s[2:3], 2, v[2:3]
	v_lshl_add_u64 v[2:3], v[2:3], 0, v[36:37]
	v_add_co_u32_e32 v4, vcc, s8, v2
	s_mov_b32 s11, 0x10000
	s_waitcnt vmcnt(30)
	v_addc_co_u32_e32 v5, vcc, 0, v3, vcc
	v_add_co_u32_e32 v6, vcc, s11, v2
	s_mov_b32 s16, 0x18000
	s_waitcnt vmcnt(28)
	v_addc_co_u32_e32 v7, vcc, 0, v3, vcc
	v_add_co_u32_e32 v8, vcc, s16, v2
	s_mov_b32 s17, 0x20000
	s_waitcnt vmcnt(26)
	v_addc_co_u32_e32 v9, vcc, 0, v3, vcc
	v_add_co_u32_e32 v10, vcc, s17, v2
	s_mov_b32 s18, 0x28000
	s_waitcnt vmcnt(24)
	v_addc_co_u32_e32 v11, vcc, 0, v3, vcc
	v_add_co_u32_e32 v12, vcc, s18, v2
	s_mov_b32 s19, 0x30000
	s_waitcnt vmcnt(22)
	v_addc_co_u32_e32 v13, vcc, 0, v3, vcc
	v_add_co_u32_e32 v14, vcc, s19, v2
	s_mov_b32 s20, 0x38000
	s_waitcnt vmcnt(20)
	v_addc_co_u32_e32 v15, vcc, 0, v3, vcc
	v_add_co_u32_e32 v16, vcc, s20, v2
	s_mov_b32 s21, 0x40000
	s_waitcnt vmcnt(18)
	v_addc_co_u32_e32 v17, vcc, 0, v3, vcc
	v_add_co_u32_e32 v18, vcc, s21, v2
	s_mov_b32 s22, 0x48000
	s_waitcnt vmcnt(16)
	v_addc_co_u32_e32 v19, vcc, 0, v3, vcc
	v_add_co_u32_e32 v20, vcc, s22, v2
	s_mov_b32 s23, 0x50000
	s_waitcnt vmcnt(14)
	v_addc_co_u32_e32 v21, vcc, 0, v3, vcc
	v_add_co_u32_e32 v22, vcc, s23, v2
	s_mov_b32 s24, 0x58000
	s_waitcnt vmcnt(12)
	v_addc_co_u32_e32 v23, vcc, 0, v3, vcc
	v_add_co_u32_e32 v24, vcc, s24, v2
	s_mov_b32 s25, 0x60000
	s_waitcnt vmcnt(10)
	v_addc_co_u32_e32 v25, vcc, 0, v3, vcc
	v_add_co_u32_e32 v26, vcc, s25, v2
	s_mov_b32 s26, 0x68000
	s_waitcnt vmcnt(8)
	v_addc_co_u32_e32 v27, vcc, 0, v3, vcc
	v_add_co_u32_e32 v28, vcc, s26, v2
	s_mov_b32 s27, 0x70000
	s_waitcnt vmcnt(6)
	v_addc_co_u32_e32 v29, vcc, 0, v3, vcc
	v_add_co_u32_e32 v30, vcc, s27, v2
	s_mov_b32 s28, 0x78000
	s_waitcnt vmcnt(4)
	v_addc_co_u32_e32 v31, vcc, 0, v3, vcc
	v_add_co_u32_e32 v76, vcc, s28, v2
	s_mov_b32 s29, 0x80000
	s_nop 0
	v_addc_co_u32_e32 v77, vcc, 0, v3, vcc
	v_add_co_u32_e32 v78, vcc, s29, v2
	s_mov_b32 s33, 0x88000
	s_nop 0
	v_addc_co_u32_e32 v79, vcc, 0, v3, vcc
	v_add_co_u32_e32 v80, vcc, s33, v2
	s_mov_b32 s35, 0x90000
	s_nop 0
	v_addc_co_u32_e32 v81, vcc, 0, v3, vcc
	v_add_co_u32_e32 v82, vcc, s35, v2
	s_mov_b32 s36, 0x98000
	s_nop 0
	v_addc_co_u32_e32 v83, vcc, 0, v3, vcc
	v_readlane_b32 s37, v249, 44
	v_add_co_u32_e32 v84, vcc, s36, v2
	s_mov_b32 s37, 0xa0000
	s_nop 0
	v_addc_co_u32_e32 v85, vcc, 0, v3, vcc
	v_readlane_b32 s38, v249, 45
	v_add_co_u32_e32 v86, vcc, s37, v2
	s_mov_b32 s38, 0xa8000
	s_nop 0
	v_addc_co_u32_e32 v87, vcc, 0, v3, vcc
	v_readlane_b32 s39, v249, 46
	v_add_co_u32_e32 v88, vcc, s38, v2
	s_mov_b32 s39, 0xb0000
	s_nop 0
	v_addc_co_u32_e32 v89, vcc, 0, v3, vcc
	v_add_co_u32_e32 v90, vcc, s39, v2
	s_mov_b32 s40, 0xb8000
	s_nop 0
	v_addc_co_u32_e32 v91, vcc, 0, v3, vcc
	v_add_co_u32_e32 v92, vcc, s40, v2
	s_mov_b32 s41, 0xc0000
	s_nop 0
	v_addc_co_u32_e32 v93, vcc, 0, v3, vcc
	v_readlane_b32 s42, v249, 49
	v_add_co_u32_e32 v94, vcc, s41, v2
	s_mov_b32 s42, 0xc8000
	s_nop 0
	v_addc_co_u32_e32 v95, vcc, 0, v3, vcc
	v_readlane_b32 s43, v249, 50
	v_add_co_u32_e32 v96, vcc, s42, v2
	s_mov_b32 s43, 0xd0000
	s_nop 0
	v_addc_co_u32_e32 v97, vcc, 0, v3, vcc
	v_readlane_b32 s44, v249, 51
	v_add_co_u32_e32 v98, vcc, s43, v2
	s_mov_b32 s44, 0xd8000
	s_nop 0
	v_addc_co_u32_e32 v99, vcc, 0, v3, vcc
	v_readlane_b32 s45, v249, 52
	v_add_co_u32_e32 v100, vcc, s44, v2
	s_mov_b32 s45, 0xe0000
	s_nop 0
	v_addc_co_u32_e32 v101, vcc, 0, v3, vcc
	v_add_co_u32_e32 v102, vcc, s45, v2
	s_mov_b32 s1, 0xe8000
	s_nop 0
	v_addc_co_u32_e32 v103, vcc, 0, v3, vcc
	v_add_co_u32_e32 v104, vcc, s1, v2
	s_mov_b32 s1, 0xf0000
	s_nop 0
	v_addc_co_u32_e32 v105, vcc, 0, v3, vcc
	v_add_co_u32_e32 v106, vcc, s1, v2
	v_readlane_b32 s46, v249, 53
	s_nop 0
	v_addc_co_u32_e32 v107, vcc, 0, v3, vcc
	v_add_co_u32_e32 v108, vcc, 0xf8000, v2
	s_mov_b32 s4, 0
	s_nop 0
	v_addc_co_u32_e32 v109, vcc, 0, v3, vcc
	global_load_dword v2, v[2:3], off nt
	s_nop 0
	global_load_dword v1, v[4:5], off nt
	s_nop 0
	global_load_dword v4, v[6:7], off nt
	global_load_dword v3, v[8:9], off nt
	s_nop 0
	global_load_dword v6, v[10:11], off nt
	global_load_dword v5, v[12:13], off nt
	global_load_dword v8, v[14:15], off nt
	global_load_dword v7, v[16:17], off nt
	s_nop 0
	global_load_dword v10, v[18:19], off nt
	global_load_dword v9, v[20:21], off nt
	global_load_dword v12, v[22:23], off nt
	global_load_dword v11, v[24:25], off nt
	global_load_dword v14, v[26:27], off nt
	global_load_dword v13, v[28:29], off nt
	global_load_dword v16, v[30:31], off nt
	global_load_dword v15, v[76:77], off nt
	global_load_dword v18, v[78:79], off nt
	global_load_dword v17, v[80:81], off nt
	global_load_dword v20, v[82:83], off nt
	global_load_dword v19, v[84:85], off nt
	global_load_dword v22, v[86:87], off nt
	global_load_dword v21, v[88:89], off nt
	global_load_dword v24, v[90:91], off nt
	global_load_dword v23, v[92:93], off nt
	global_load_dword v26, v[94:95], off nt
	global_load_dword v25, v[96:97], off nt
	global_load_dword v28, v[98:99], off nt
	global_load_dword v27, v[100:101], off nt
	global_load_dword v30, v[102:103], off nt
	global_load_dword v29, v[104:105], off nt
	global_load_dword v32, v[106:107], off nt
	global_load_dword v31, v[108:109], off nt
	s_lshl_b32 s46, s10, 4
	s_mov_b32 s12, 0
	v_readlane_b32 s47, v249, 54
	v_readlane_b32 s48, v249, 55
	v_readlane_b32 s49, v249, 56
	v_readlane_b32 s50, v249, 57
	v_readlane_b32 s51, v249, 58
	s_branch .LBB0_73

; #define TR_MAP(it_, k0_, n0_, dr_) do { const int kb_ = (it_) / nblk, nb_ = (it_) % nblk; k0_ = 64 * kb_; n0_ = 32 * nb_; \
;         if (DMAP == 1) { const int isup_ = n0_ >= DFF ? 1 : 0, j_ = n0_ - isup_ * DFF; dr_ = drow_off + (j_ >> 7) * 256 + isup_ * 128 + (j_ & 127); } else dr_ = drow_off + n0_; } while (0)
; __device__ __forceinline__ void tr_load(float (&v)[32], const float* W, int N, int k0, int n0, int lane) {
;     const float* wp = W + (size_t)(k0 + (lane >> 5)) * N + n0 + (lane & 31);
; #pragma unroll
;     for (int i = 0; i < 32; ++i) v[i] = wp[(size_t)(2 * i) * N];
; }
;     ...
;     float va[32], vb[32]; int ka, na, da, kb2 = 0, nb2 = 0, db = 0;
;     TR_MAP(it, ka, na, da); tr_load(va, W, N, ka, na, lane);
; #pragma unroll 1
;     while (true) {
;         const int itb = it + NGW; const bool hb = itb < nitems;
;         if (hb) { TR_MAP(itb, kb2, nb2, db); tr_load(vb, W, N, kb2, nb2, lane); }
;         tr_finish(va, WT, ldk, ka, da, scr, lane);
;         if (!hb) break;
;         it = itb + NGW; const bool ha = it < nitems;
;         if (ha) { TR_MAP(it, ka, na, da); tr_load(va, W, N, ka, na, lane); }
.LBB0_73:
	s_add_i32 s47, s13, s9
	s_cmpk_lt_i32 s47, 0x2000
	s_cselect_b64 s[14:15], -1, 0
	s_cmpk_gt_i32 s47, 0x1fff
	s_cbranch_scc1 .LBB0_75
	s_ashr_i32 s1, s47, 31
	s_lshr_b32 s1, s1, 25
	s_add_i32 s1, s47, s1
	s_ashr_i32 s3, s1, 7
	s_lshl_b32 s12, s3, 6
	s_and_b32 s1, s1, 0x7ffff80
	v_or_b32_e32 v40, s12, v34
	s_sub_i32 s1, s47, s1
	v_ashrrev_i32_e32 v41, 31, v40
	v_readlane_b32 s76, v249, 43
	s_lshl_b32 s4, s1, 5
	v_lshlrev_b64 v[40:41], 14, v[40:41]
	v_readlane_b32 s80, v249, 47
	v_readlane_b32 s81, v249, 48
	s_ashr_i32 s5, s4, 31
	v_readlane_b32 s76, v249, 59
	v_lshl_add_u64 v[40:41], s[80:81], 0, v[40:41]
	v_lshl_add_u64 v[40:41], s[4:5], 2, v[40:41]
	v_lshl_add_u64 v[68:69], v[40:41], 0, v[36:37]
	v_add_co_u32_e32 v40, vcc, s8, v68
	v_readlane_b32 s77, v249, 44
	s_nop 0
	v_addc_co_u32_e32 v41, vcc, 0, v69, vcc
	v_add_co_u32_e32 v44, vcc, s11, v68
	v_readlane_b32 s78, v249, 45
	s_nop 0
	v_addc_co_u32_e32 v45, vcc, 0, v69, vcc
	v_add_co_u32_e32 v52, vcc, s16, v68
	v_readlane_b32 s79, v249, 46
	s_nop 0
	v_addc_co_u32_e32 v53, vcc, 0, v69, vcc
	v_add_co_u32_e32 v54, vcc, s17, v68
	v_readlane_b32 s82, v249, 49
	s_nop 0
	v_addc_co_u32_e32 v55, vcc, 0, v69, vcc
	v_add_co_u32_e32 v56, vcc, s18, v68
	v_readlane_b32 s83, v249, 50
	s_nop 0
	v_addc_co_u32_e32 v57, vcc, 0, v69, vcc
	v_add_co_u32_e32 v58, vcc, s19, v68
	v_readlane_b32 s84, v249, 51
	s_nop 0
	v_addc_co_u32_e32 v59, vcc, 0, v69, vcc
	v_add_co_u32_e32 v60, vcc, s20, v68
	v_readlane_b32 s85, v249, 52
	s_nop 0
	v_addc_co_u32_e32 v61, vcc, 0, v69, vcc
	global_load_dword v50, v[68:69], off nt
	global_load_dword v49, v[40:41], off nt
	s_nop 0
	global_load_dword v45, v[44:45], off nt
	s_nop 0
	global_load_dword v44, v[52:53], off nt
	global_load_dword v42, v[54:55], off nt
	global_load_dword v41, v[56:57], off nt
	global_load_dword v40, v[58:59], off nt
	global_load_dword v51, v[60:61], off nt
	v_add_co_u32_e32 v52, vcc, s21, v68
	v_readlane_b32 s86, v249, 53
	s_nop 0
	v_addc_co_u32_e32 v53, vcc, 0, v69, vcc
	v_add_co_u32_e32 v54, vcc, s22, v68
	v_readlane_b32 s87, v249, 54
	s_nop 0
	v_addc_co_u32_e32 v55, vcc, 0, v69, vcc
	v_add_co_u32_e32 v60, vcc, s23, v68
	v_readlane_b32 s88, v249, 55
	s_nop 0
	v_addc_co_u32_e32 v61, vcc, 0, v69, vcc
	v_add_co_u32_e32 v62, vcc, s24, v68
	v_readlane_b32 s89, v249, 56
	s_nop 0
	v_addc_co_u32_e32 v63, vcc, 0, v69, vcc
	v_add_co_u32_e32 v64, vcc, s25, v68
	v_readlane_b32 s90, v249, 57
	s_nop 0
	v_addc_co_u32_e32 v65, vcc, 0, v69, vcc
	v_add_co_u32_e32 v66, vcc, s26, v68
	v_readlane_b32 s91, v249, 58
	s_nop 0
	v_addc_co_u32_e32 v67, vcc, 0, v69, vcc
	v_add_co_u32_e32 v70, vcc, s27, v68
	s_nop 1
	v_addc_co_u32_e32 v71, vcc, 0, v69, vcc
	v_add_co_u32_e32 v72, vcc, s28, v68
	s_nop 1
	v_addc_co_u32_e32 v73, vcc, 0, v69, vcc
	global_load_dword v58, v[52:53], off nt
	global_load_dword v57, v[54:55], off nt
	global_load_dword v56, v[60:61], off nt
	s_nop 0
	global_load_dword v55, v[62:63], off nt
	global_load_dword v54, v[64:65], off nt
	global_load_dword v53, v[66:67], off nt
	global_load_dword v52, v[70:71], off nt
	global_load_dword v59, v[72:73], off nt
	v_add_co_u32_e32 v60, vcc, s29, v68
	s_nop 1
	v_addc_co_u32_e32 v61, vcc, 0, v69, vcc
	v_add_co_u32_e32 v62, vcc, s33, v68
	s_nop 1
	v_addc_co_u32_e32 v63, vcc, 0, v69, vcc
	v_add_co_u32_e32 v70, vcc, s35, v68
	s_nop 1
	v_addc_co_u32_e32 v71, vcc, 0, v69, vcc
	v_add_co_u32_e32 v72, vcc, s36, v68
	s_nop 1
	v_addc_co_u32_e32 v73, vcc, 0, v69, vcc
	v_add_co_u32_e32 v74, vcc, s37, v68
	s_nop 1
	v_addc_co_u32_e32 v75, vcc, 0, v69, vcc
	v_add_co_u32_e32 v76, vcc, s38, v68
	s_nop 1
	v_addc_co_u32_e32 v77, vcc, 0, v69, vcc
	v_add_co_u32_e32 v78, vcc, s39, v68
	s_nop 1
	v_addc_co_u32_e32 v79, vcc, 0, v69, vcc
	v_add_co_u32_e32 v80, vcc, s40, v68
	s_nop 1
	v_addc_co_u32_e32 v81, vcc, 0, v69, vcc
	global_load_dword v66, v[60:61], off nt
	global_load_dword v65, v[62:63], off nt
	global_load_dword v64, v[70:71], off nt
	s_nop 0
	global_load_dword v63, v[72:73], off nt
	global_load_dword v62, v[74:75], off nt
	global_load_dword v61, v[76:77], off nt
	global_load_dword v60, v[78:79], off nt
	global_load_dword v67, v[80:81], off nt
	v_add_co_u32_e32 v70, vcc, s41, v68
	s_nop 1
	v_addc_co_u32_e32 v71, vcc, 0, v69, vcc
	v_add_co_u32_e32 v72, vcc, s42, v68
	s_nop 1
	v_addc_co_u32_e32 v73, vcc, 0, v69, vcc
	v_add_co_u32_e32 v76, vcc, s43, v68
	s_nop 1
	v_addc_co_u32_e32 v77, vcc, 0, v69, vcc
	v_add_co_u32_e32 v78, vcc, s44, v68
	s_nop 1
	v_addc_co_u32_e32 v79, vcc, 0, v69, vcc
	v_add_co_u32_e32 v80, vcc, 0xe0000, v68
	s_nop 1
	v_addc_co_u32_e32 v81, vcc, 0, v69, vcc
	v_add_co_u32_e32 v82, vcc, 0xe8000, v68
	s_nop 1
	v_addc_co_u32_e32 v83, vcc, 0, v69, vcc
	v_add_co_u32_e32 v84, vcc, 0xf0000, v68
	s_nop 1
	v_addc_co_u32_e32 v85, vcc, 0, v69, vcc
	v_add_co_u32_e32 v86, vcc, 0xf8000, v68
	s_nop 1
	v_addc_co_u32_e32 v87, vcc, 0, v69, vcc
	global_load_dword v74, v[70:71], off nt
	s_nop 0
	global_load_dword v73, v[72:73], off nt
	s_nop 0
	global_load_dword v72, v[76:77], off nt
	global_load_dword v71, v[78:79], off nt
	global_load_dword v70, v[80:81], off nt
	global_load_dword v69, v[82:83], off nt
	global_load_dword v68, v[84:85], off nt
	global_load_dword v75, v[86:87], off nt
; __device__ __forceinline__ unsigned cvt_pk_bf16(float lo, float hi) { unsigned r; asm volatile("v_cvt_pk_bf16_f32 %0, %1, %2" : "=v"(r) : "v"(lo), "v"(hi)); return r; }
; #define LAS __attribute__((address_space(3)))
; #define LDS_WAIT() asm volatile("s_waitcnt lgkmcnt(0)" ::: "memory")
; #define TR_MAP(it_, k0_, n0_, dr_) do { const int kb_ = (it_) / nblk, nb_ = (it_) % nblk; k0_ = 64 * kb_; n0_ = 32 * nb_; \
;         if (DMAP == 1) { const int isup_ = n0_ >= DFF ? 1 : 0, j_ = n0_ - isup_ * DFF; dr_ = drow_off + (j_ >> 7) * 256 + isup_ * 128 + (j_ & 127); } else dr_ = drow_off + n0_; } while (0)
; __device__ __forceinline__ void tr_finish(const float (&v)[32], bf16* WT, int ldk, int k0, int drow0, LAS float* scr, int lane) {
; #pragma unroll
;     for (int i = 0; i < 32; ++i) scr[(2 * i + (lane >> 5)) * 33 + (lane & 31)] = v[i];
;     LDS_WAIT(); asm volatile("" ::: "memory");
;     const int c = lane & 7;
; #pragma unroll
;     for (int j = 0; j < 4; ++j) { const int n = (lane >> 3) + 8 * j; const LAS float* s = scr + (8 * c) * 33 + n;
;         v4u o;
;         { o.x = cvt_pk_bf16(s[0 * 33], s[1 * 33]); o.y = cvt_pk_bf16(s[2 * 33], s[3 * 33]); o.z = cvt_pk_bf16(s[4 * 33], s[5 * 33]); o.w = cvt_pk_bf16(s[6 * 33], s[7 * 33]); }
;         *(v4u*)(WT + (size_t)(drow0 + n) * ldk + k0 + 8 * c) = o; }
;     LDS_WAIT(); asm volatile("" ::: "memory");
; }
;     ...
;     while (true) {
;         const int itb = it + NGW; const bool hb = itb < nitems;
;         if (hb) { TR_MAP(itb, kb2, nb2, db); tr_load(vb, W, N, kb2, nb2, lane); }
;         tr_finish(va, WT, ldk, ka, da, scr, lane);
;         if (!hb) break;
;         it = itb + NGW; const bool ha = it < nitems;
;         if (ha) { TR_MAP(it, ka, na, da); tr_load(va, W, N, ka, na, lane); }
.LBB0_75:
	v_add_u32_e32 v76, 0x400, v33
	v_add_u32_e32 v77, 0x800, v33
	v_add_u32_e32 v78, 0xc00, v33
	v_add_u32_e32 v79, 0x1000, v33
	v_add_u32_e32 v80, 0x1400, v33
	v_add_u32_e32 v81, 0x1800, v33
	v_add_u32_e32 v82, 0x1c00, v33
	s_waitcnt vmcnt(30)
	ds_write2_b32 v33, v2, v1 offset1:66
	s_waitcnt vmcnt(28)
	ds_write2_b32 v33, v4, v3 offset0:132 offset1:198
	s_waitcnt vmcnt(26)
	ds_write2_b32 v76, v6, v5 offset0:8 offset1:74
	s_waitcnt vmcnt(24)
	ds_write2_b32 v76, v8, v7 offset0:140 offset1:206
	s_waitcnt vmcnt(22)
	ds_write2_b32 v77, v10, v9 offset0:16 offset1:82
	s_waitcnt vmcnt(20)
	ds_write2_b32 v77, v12, v11 offset0:148 offset1:214
	s_waitcnt vmcnt(18)
	ds_write2_b32 v78, v14, v13 offset0:24 offset1:90
	s_waitcnt vmcnt(16)
	ds_write2_b32 v78, v16, v15 offset0:156 offset1:222
	s_waitcnt vmcnt(14)
	ds_write2_b32 v79, v18, v17 offset0:32 offset1:98
	s_waitcnt vmcnt(12)
	ds_write2_b32 v79, v20, v19 offset0:164 offset1:230
	s_waitcnt vmcnt(10)
	ds_write2_b32 v80, v22, v21 offset0:40 offset1:106
	s_waitcnt vmcnt(8)
	ds_write2_b32 v80, v24, v23 offset0:172 offset1:238
	s_waitcnt vmcnt(6)
	ds_write2_b32 v81, v26, v25 offset0:48 offset1:114
	s_waitcnt vmcnt(4)
	ds_write2_b32 v81, v28, v27 offset0:180 offset1:246
	s_waitcnt vmcnt(2)
	ds_write2_b32 v82, v30, v29 offset0:56 offset1:122
	s_waitcnt vmcnt(0)
	ds_write2_b32 v82, v32, v31 offset0:188 offset1:254
	s_waitcnt lgkmcnt(0)
	ds_read2_b32 v[84:85], v43 offset1:33
	s_waitcnt lgkmcnt(0)
	v_cvt_pk_bf16_f32 v84, v84, v85
	ds_read2_b32 v[86:87], v43 offset0:66 offset1:99
	s_waitcnt lgkmcnt(0)
	v_cvt_pk_bf16_f32 v85, v86, v87
	ds_read2_b32 v[86:87], v43 offset0:132 offset1:165
	s_waitcnt lgkmcnt(0)
	v_cvt_pk_bf16_f32 v86, v86, v87
	ds_read2_b32 v[88:89], v43 offset0:198 offset1:231
	s_waitcnt lgkmcnt(0)
	v_cvt_pk_bf16_f32 v87, v88, v89
	v_or_b32_e32 v88, s2, v35
	s_ashr_i32 s1, s0, 31
	v_ashrrev_i32_e32 v89, 31, v88
	v_lshlrev_b64 v[88:89], 13, v[88:89]
	v_lshl_add_u64 v[90:91], s[0:1], 1, v[38:39]
	v_lshl_add_u64 v[88:89], v[90:91], 0, v[88:89]
	global_store_dwordx4 v[88:89], v[84:87], off
	ds_read2_b32 v[84:85], v43 offset0:8 offset1:41
	s_andn2_b64 vcc, exec, s[14:15]
	s_waitcnt lgkmcnt(0)
	v_cvt_pk_bf16_f32 v84, v84, v85
	ds_read2_b32 v[86:87], v43 offset0:74 offset1:107
	s_waitcnt lgkmcnt(0)
	v_cvt_pk_bf16_f32 v85, v86, v87
	ds_read2_b32 v[86:87], v43 offset0:140 offset1:173
	s_waitcnt lgkmcnt(0)
	v_cvt_pk_bf16_f32 v86, v86, v87
	ds_read2_b32 v[88:89], v43 offset0:206 offset1:239
	s_waitcnt lgkmcnt(0)
	v_cvt_pk_bf16_f32 v87, v88, v89
	v_or_b32_e32 v88, s2, v46
	v_ashrrev_i32_e32 v89, 31, v88
	v_lshlrev_b64 v[88:89], 13, v[88:89]
	v_lshl_add_u64 v[88:89], v[90:91], 0, v[88:89]
	global_store_dwordx4 v[88:89], v[84:87], off
	ds_read2_b32 v[84:85], v43 offset0:16 offset1:49
	s_mov_b64 s[14:15], -1
	s_waitcnt lgkmcnt(0)
	v_cvt_pk_bf16_f32 v84, v84, v85
	ds_read2_b32 v[86:87], v43 offset0:82 offset1:115
	s_waitcnt lgkmcnt(0)
	v_cvt_pk_bf16_f32 v85, v86, v87
	ds_read2_b32 v[86:87], v43 offset0:148 offset1:181
	s_waitcnt lgkmcnt(0)
	v_cvt_pk_bf16_f32 v86, v86, v87
	ds_read2_b32 v[88:89], v43 offset0:214 offset1:247
	s_waitcnt lgkmcnt(0)
	v_cvt_pk_bf16_f32 v87, v88, v89
	v_or_b32_e32 v88, s2, v47
	v_ashrrev_i32_e32 v89, 31, v88
	v_lshlrev_b64 v[88:89], 13, v[88:89]
	v_lshl_add_u64 v[88:89], v[90:91], 0, v[88:89]
	global_store_dwordx4 v[88:89], v[84:87], off
	s_nop 1
	v_or_b32_e32 v84, s2, v48
	v_ashrrev_i32_e32 v85, 31, v84
	v_lshlrev_b64 v[84:85], 13, v[84:85]
	v_lshl_add_u64 v[88:89], v[90:91], 0, v[84:85]
	ds_read2_b32 v[84:85], v43 offset0:24 offset1:57
	s_waitcnt lgkmcnt(0)
	v_cvt_pk_bf16_f32 v84, v84, v85
	ds_read2_b32 v[86:87], v43 offset0:90 offset1:123
	s_waitcnt lgkmcnt(0)
	v_cvt_pk_bf16_f32 v85, v86, v87
	ds_read2_b32 v[86:87], v43 offset0:156 offset1:189
	s_waitcnt lgkmcnt(0)
	v_cvt_pk_bf16_f32 v86, v86, v87
	ds_read2_b32 v[90:91], v43 offset0:222 offset1:255
	s_waitcnt lgkmcnt(0)
	v_cvt_pk_bf16_f32 v87, v90, v91
	global_store_dwordx4 v[88:89], v[84:87], off
	s_waitcnt lgkmcnt(0)
	s_cbranch_vccnz .LBB0_72
	s_add_i32 s1, s46, s13
	s_cmpk_gt_i32 s1, 0x1fff
	s_cbranch_scc1 .LBB0_71
	s_ashr_i32 s0, s1, 31
	s_lshr_b32 s0, s0, 25
	s_add_i32 s0, s1, s0
	s_ashr_i32 s2, s0, 7
	s_and_b32 s0, s0, 0x7ffff80
	s_sub_i32 s1, s1, s0
	s_lshl_b32 s0, s2, 6
	v_or_b32_e32 v2, s0, v34
	v_ashrrev_i32_e32 v3, 31, v2
	v_readlane_b32 s76, v249, 43
	s_lshl_b32 s2, s1, 5
	v_lshlrev_b64 v[2:3], 14, v[2:3]
	v_readlane_b32 s80, v249, 47
	v_readlane_b32 s81, v249, 48
	s_ashr_i32 s3, s2, 31
	v_readlane_b32 s76, v249, 59
	v_lshl_add_u64 v[2:3], s[80:81], 0, v[2:3]
	v_lshl_add_u64 v[2:3], s[2:3], 2, v[2:3]
	v_lshl_add_u64 v[2:3], v[2:3], 0, v[36:37]
	v_add_co_u32_e32 v4, vcc, s8, v2
	v_readlane_b32 s77, v249, 44
	s_nop 0
	v_addc_co_u32_e32 v5, vcc, 0, v3, vcc
	v_add_co_u32_e32 v6, vcc, s11, v2
	v_readlane_b32 s78, v249, 45
	s_nop 0
	v_addc_co_u32_e32 v7, vcc, 0, v3, vcc
	v_add_co_u32_e32 v8, vcc, s16, v2
	v_readlane_b32 s79, v249, 46
	s_nop 0
	v_addc_co_u32_e32 v9, vcc, 0, v3, vcc
	v_add_co_u32_e32 v10, vcc, s17, v2
	v_readlane_b32 s82, v249, 49
	s_nop 0
	v_addc_co_u32_e32 v11, vcc, 0, v3, vcc
	v_add_co_u32_e32 v12, vcc, s18, v2
	v_readlane_b32 s83, v249, 50
	s_nop 0
	v_addc_co_u32_e32 v13, vcc, 0, v3, vcc
	v_add_co_u32_e32 v14, vcc, s19, v2
	v_readlane_b32 s84, v249, 51
	s_nop 0
	v_addc_co_u32_e32 v15, vcc, 0, v3, vcc
	v_add_co_u32_e32 v16, vcc, s20, v2
	v_readlane_b32 s85, v249, 52
	s_nop 0
	v_addc_co_u32_e32 v17, vcc, 0, v3, vcc
	v_add_co_u32_e32 v18, vcc, s21, v2
	v_readlane_b32 s86, v249, 53
	s_nop 0
	v_addc_co_u32_e32 v19, vcc, 0, v3, vcc
	v_add_co_u32_e32 v20, vcc, s22, v2
	v_readlane_b32 s87, v249, 54
	s_nop 0
; #define LAS __attribute__((address_space(3)))
; __device__ __forceinline__ void tr_load(float (&v)[32], const float* W, int N, int k0, int n0, int lane) {
;     const float* wp = W + (size_t)(k0 + (lane >> 5)) * N + n0 + (lane & 31);
; #pragma unroll
;     for (int i = 0; i < 32; ++i) v[i] = wp[(size_t)(2 * i) * N];
; }
; template <class MapF>
; __device__ __forceinline__ void strip_quant(const float* W, int ldw, unsigned char* W8o, float* cso, int nstrips, int s0, int sstride, LAS unsigned char* lds, int lane, int wave, const MapF map) {
;     LAS unsigned char* sbuf = lds; LAS float* red = (LAS float*)(lds + RING_BYTES + 8192);
;     const int nn = lane & 15, kh = lane >> 4;
;     const float s16 = (kh & 1) ? -1.f : 1.f, s32 = (kh & 2) ? -0.125f : 0.125f;
;     float va[16], vb[16];
;     if (s0 >= nstrips) return;
;     int n0, drow0; map(s0, n0, drow0);
;     const float* wp = W + (size_t)(512 * wave + 16 * kh) * ldw + n0 + nn;
; #pragma unroll
;     for (int i = 0; i < 16; ++i) { va[i] = wp[(size_t)i * ldw]; vb[i] = wp[(size_t)(64 + i) * ldw]; }
	v_addc_co_u32_e32 v21, vcc, 0, v3, vcc
	v_add_co_u32_e32 v22, vcc, s23, v2
	v_readlane_b32 s88, v249, 55
	s_nop 0
	v_addc_co_u32_e32 v23, vcc, 0, v3, vcc
	v_add_co_u32_e32 v24, vcc, s24, v2
	v_readlane_b32 s89, v249, 56
	s_nop 0
	v_addc_co_u32_e32 v25, vcc, 0, v3, vcc
	v_add_co_u32_e32 v26, vcc, s25, v2
	v_readlane_b32 s90, v249, 57
	s_nop 0
	v_addc_co_u32_e32 v27, vcc, 0, v3, vcc
	v_add_co_u32_e32 v28, vcc, s26, v2
	v_readlane_b32 s91, v249, 58
	s_nop 0
	v_addc_co_u32_e32 v29, vcc, 0, v3, vcc
	v_add_co_u32_e32 v30, vcc, s27, v2
	s_nop 1
	v_addc_co_u32_e32 v31, vcc, 0, v3, vcc
	v_add_co_u32_e32 v84, vcc, s28, v2
	s_nop 1
	v_addc_co_u32_e32 v85, vcc, 0, v3, vcc
	v_add_co_u32_e32 v86, vcc, s29, v2
	s_nop 1
	v_addc_co_u32_e32 v87, vcc, 0, v3, vcc
	v_add_co_u32_e32 v88, vcc, s33, v2
	s_nop 1
	v_addc_co_u32_e32 v89, vcc, 0, v3, vcc
	v_add_co_u32_e32 v90, vcc, s35, v2
	s_nop 1
	v_addc_co_u32_e32 v91, vcc, 0, v3, vcc
	v_add_co_u32_e32 v92, vcc, s36, v2
	s_nop 1
	v_addc_co_u32_e32 v93, vcc, 0, v3, vcc
	v_add_co_u32_e32 v94, vcc, s37, v2
	s_nop 1
	v_addc_co_u32_e32 v95, vcc, 0, v3, vcc
	v_add_co_u32_e32 v96, vcc, s38, v2
	s_nop 1
	v_addc_co_u32_e32 v97, vcc, 0, v3, vcc
	v_add_co_u32_e32 v98, vcc, s39, v2
	s_nop 1
	v_addc_co_u32_e32 v99, vcc, 0, v3, vcc
	v_add_co_u32_e32 v100, vcc, s40, v2
	s_nop 1
	v_addc_co_u32_e32 v101, vcc, 0, v3, vcc
	v_add_co_u32_e32 v102, vcc, s41, v2
	s_nop 1
	v_addc_co_u32_e32 v103, vcc, 0, v3, vcc
	v_add_co_u32_e32 v104, vcc, s42, v2
	s_nop 1
	v_addc_co_u32_e32 v105, vcc, 0, v3, vcc
	v_add_co_u32_e32 v106, vcc, s43, v2
	s_nop 1
	v_addc_co_u32_e32 v107, vcc, 0, v3, vcc
	v_add_co_u32_e32 v108, vcc, s44, v2
	s_nop 1
	v_addc_co_u32_e32 v109, vcc, 0, v3, vcc
	v_add_co_u32_e32 v110, vcc, s45, v2
	s_nop 1
	v_addc_co_u32_e32 v111, vcc, 0, v3, vcc
	v_add_co_u32_e32 v112, vcc, 0xe8000, v2
	s_nop 1
	v_addc_co_u32_e32 v113, vcc, 0, v3, vcc
	v_add_co_u32_e32 v114, vcc, 0xf0000, v2
	s_nop 1
	v_addc_co_u32_e32 v115, vcc, 0, v3, vcc
	v_add_co_u32_e32 v116, vcc, 0xf8000, v2
	s_nop 1
	v_addc_co_u32_e32 v117, vcc, 0, v3, vcc
	global_load_dword v2, v[2:3], off nt
	s_nop 0
	global_load_dword v1, v[4:5], off nt
	s_nop 0
	global_load_dword v4, v[6:7], off nt
	global_load_dword v3, v[8:9], off nt
	s_nop 0
	global_load_dword v6, v[10:11], off nt
	global_load_dword v5, v[12:13], off nt
	global_load_dword v8, v[14:15], off nt
	global_load_dword v7, v[16:17], off nt
	s_nop 0
	global_load_dword v10, v[18:19], off nt
	global_load_dword v9, v[20:21], off nt
	global_load_dword v12, v[22:23], off nt
	global_load_dword v11, v[24:25], off nt
	global_load_dword v14, v[26:27], off nt
	global_load_dword v13, v[28:29], off nt
	global_load_dword v16, v[30:31], off nt
	global_load_dword v15, v[84:85], off nt
	global_load_dword v18, v[86:87], off nt
	global_load_dword v17, v[88:89], off nt
	global_load_dword v20, v[90:91], off nt
	global_load_dword v19, v[92:93], off nt
	global_load_dword v22, v[94:95], off nt
	global_load_dword v21, v[96:97], off nt
	global_load_dword v24, v[98:99], off nt
	global_load_dword v23, v[100:101], off nt
	global_load_dword v26, v[102:103], off nt
	global_load_dword v25, v[104:105], off nt
	global_load_dword v28, v[106:107], off nt
	global_load_dword v27, v[108:109], off nt
	global_load_dword v30, v[110:111], off nt
	global_load_dword v29, v[112:113], off nt
	global_load_dword v32, v[114:115], off nt
	global_load_dword v31, v[116:117], off nt
	s_branch .LBB0_71
.LBB0_78:
	s_cmpk_gt_i32 s34, 0x3ff
	s_barrier
	s_cbranch_scc1 .LBB0_93
	v_readlane_b32 s12, v249, 9
	s_waitcnt vmcnt(34)
	v_and_b32_e32 v1, 48, v0
	v_readlane_b32 s0, v249, 38
	v_readlane_b32 s24, v249, 21
	v_readlane_b32 s25, v249, 22
	v_readlane_b32 s1, v249, 39
	s_waitcnt vmcnt(19)
	v_lshl_or_b32 v18, s0, 9, v1
	s_mov_b32 s4, 0x14000
	v_mov_b64_e32 v[2:3], s[24:25]
	s_waitcnt vmcnt(12)
	v_mad_i64_i32 v[22:23], s[0:1], v18, s4, v[2:3]
	v_readlane_b32 s19, v249, 16
	s_cmpk_lt_i32 s34, 0x300
	s_movk_i32 s1, 0x2000
	s_cselect_b32 s0, s1, 0xffffd000
	s_lshl_b32 s19, s34, 4
	s_add_i32 s2, s0, s19
	v_and_b32_e32 v34, 15, v0
	s_ashr_i32 s3, s2, 31
	v_mov_b32_e32 v21, 0
	v_lshl_add_u64 v[2:3], s[2:3], 2, v[22:23]
	v_lshlrev_b32_e32 v20, 2, v34
	v_lshl_add_u64 v[36:37], v[2:3], 0, v[20:21]
	s_mov_b32 s0, 0x500000
	v_add_co_u32_e32 v2, vcc, s0, v36
	s_mov_b32 s0, 0x514000
	s_nop 0
	v_addc_co_u32_e32 v3, vcc, 0, v37, vcc
	v_add_co_u32_e32 v4, vcc, s0, v36
	s_mov_b32 s0, 0x528000
	s_nop 0
	v_addc_co_u32_e32 v5, vcc, 0, v37, vcc
	v_add_co_u32_e32 v6, vcc, s0, v36
	s_mov_b32 s0, 0x53c000
	s_nop 0
	v_addc_co_u32_e32 v7, vcc, 0, v37, vcc
	v_add_co_u32_e32 v8, vcc, s0, v36
	s_mov_b32 s0, 0x550000
	s_nop 0
	v_addc_co_u32_e32 v9, vcc, 0, v37, vcc
	v_add_co_u32_e32 v10, vcc, s0, v36
	s_mov_b32 s0, 0x564000
	s_nop 0
	v_addc_co_u32_e32 v11, vcc, 0, v37, vcc
	v_add_co_u32_e32 v12, vcc, s0, v36
	s_mov_b32 s0, 0x578000
	s_nop 0
	v_addc_co_u32_e32 v13, vcc, 0, v37, vcc
	v_add_co_u32_e32 v14, vcc, s0, v36
	s_mov_b32 s0, 0x58c000
	s_nop 0
	v_addc_co_u32_e32 v15, vcc, 0, v37, vcc
	v_add_co_u32_e32 v16, vcc, s0, v36
	s_mov_b32 s0, 0x5a0000
	s_nop 0
	v_addc_co_u32_e32 v17, vcc, 0, v37, vcc
	global_load_dword v44, v[2:3], off nt
	global_load_dword v45, v[4:5], off nt
	global_load_dword v48, v[6:7], off nt
	global_load_dword v49, v[8:9], off nt
	global_load_dword v50, v[10:11], off nt
	global_load_dword v51, v[12:13], off nt
	global_load_dword v52, v[14:15], off nt
	global_load_dword v53, v[16:17], off nt
	v_add_co_u32_e32 v2, vcc, s0, v36
	s_mov_b32 s0, 0x5b4000
	s_nop 0
	v_addc_co_u32_e32 v3, vcc, 0, v37, vcc
	v_add_co_u32_e32 v4, vcc, s0, v36
	s_mov_b32 s0, 0x5c8000
	s_nop 0
; #define LAS __attribute__((address_space(3)))
; template <class MapF>
; __device__ __forceinline__ void strip_quant(const float* W, int ldw, unsigned char* W8o, float* cso, int nstrips, int s0, int sstride, LAS unsigned char* lds, int lane, int wave, const MapF map) {
;     LAS unsigned char* sbuf = lds; LAS float* red = (LAS float*)(lds + RING_BYTES + 8192);
;     const int nn = lane & 15, kh = lane >> 4;
;     const float s16 = (kh & 1) ? -1.f : 1.f, s32 = (kh & 2) ? -0.125f : 0.125f;
;     float va[16], vb[16];
;     if (s0 >= nstrips) return;
;     int n0, drow0; map(s0, n0, drow0);
;     const float* wp = W + (size_t)(512 * wave + 16 * kh) * ldw + n0 + nn;
; #pragma unroll
;     for (int i = 0; i < 16; ++i) { va[i] = wp[(size_t)i * ldw]; vb[i] = wp[(size_t)(64 + i) * ldw]; }
;     for (int strip = s0; strip < nstrips; strip += sstride) {
;         float cm = 0.f;
	v_addc_co_u32_e32 v5, vcc, 0, v37, vcc
	v_add_co_u32_e32 v6, vcc, s0, v36
	s_mov_b32 s0, 0x5dc000
	s_nop 0
	v_addc_co_u32_e32 v7, vcc, 0, v37, vcc
	v_add_co_u32_e32 v8, vcc, s0, v36
	s_mov_b32 s0, 0x5f0000
	s_nop 0
	v_addc_co_u32_e32 v9, vcc, 0, v37, vcc
	v_add_co_u32_e32 v10, vcc, s0, v36
	s_mov_b32 s0, 0x604000
	s_nop 0
	v_addc_co_u32_e32 v11, vcc, 0, v37, vcc
	v_add_co_u32_e32 v12, vcc, s0, v36
	s_mov_b32 s0, 0x618000
	s_nop 0
	v_addc_co_u32_e32 v13, vcc, 0, v37, vcc
	v_add_co_u32_e32 v14, vcc, s0, v36
	s_mov_b32 s0, 0x62c000
	s_nop 0
	v_addc_co_u32_e32 v15, vcc, 0, v37, vcc
	v_add_co_u32_e32 v16, vcc, s0, v36
	s_mov_b32 s0, 0x28000
	s_nop 0
	v_addc_co_u32_e32 v17, vcc, 0, v37, vcc
	global_load_dword v54, v[2:3], off nt
	global_load_dword v55, v[4:5], off nt
	global_load_dword v56, v[6:7], off nt
	global_load_dword v57, v[8:9], off nt
	global_load_dword v58, v[10:11], off nt
	global_load_dword v59, v[12:13], off nt
	global_load_dword v60, v[14:15], off nt
	global_load_dword v61, v[16:17], off nt
	v_add_co_u32_e32 v2, vcc, s4, v36
	v_and_b32_e32 v1, 16, v0
	s_nop 0
	v_addc_co_u32_e32 v3, vcc, 0, v37, vcc
	v_add_co_u32_e32 v4, vcc, s0, v36
	s_mov_b32 s0, 0x3c000
	s_nop 0
	v_addc_co_u32_e32 v5, vcc, 0, v37, vcc
	v_add_co_u32_e32 v6, vcc, s0, v36
	s_mov_b32 s0, 0x50000
	s_nop 0
	v_addc_co_u32_e32 v7, vcc, 0, v37, vcc
	v_add_co_u32_e32 v8, vcc, s0, v36
	s_mov_b32 s0, 0x64000
	s_nop 0
	v_addc_co_u32_e32 v9, vcc, 0, v37, vcc
	v_add_co_u32_e32 v10, vcc, s0, v36
	s_mov_b32 s0, 0x78000
	s_nop 0
	v_addc_co_u32_e32 v11, vcc, 0, v37, vcc
	v_add_co_u32_e32 v12, vcc, s0, v36
	s_mov_b32 s0, 0x8c000
	s_nop 0
	v_addc_co_u32_e32 v13, vcc, 0, v37, vcc
	v_add_co_u32_e32 v14, vcc, s0, v36
	s_mov_b32 s0, 0xa0000
	s_nop 0
	v_addc_co_u32_e32 v15, vcc, 0, v37, vcc
	v_add_co_u32_e32 v16, vcc, s0, v36
	s_mov_b32 s0, 0xb4000
	s_nop 0
	v_addc_co_u32_e32 v17, vcc, 0, v37, vcc
	global_load_dword v3, v[2:3], off nt
	s_nop 0
	global_load_dword v4, v[4:5], off nt
	s_nop 0
	global_load_dword v5, v[6:7], off nt
	s_nop 0
	global_load_dword v6, v[8:9], off nt
	global_load_dword v7, v[10:11], off nt
	s_nop 0
	global_load_dword v8, v[12:13], off nt
	global_load_dword v9, v[14:15], off nt
	global_load_dword v10, v[16:17], off nt
	v_add_co_u32_e32 v12, vcc, s0, v36
	s_mov_b32 s0, 0xc8000
	s_nop 0
	v_addc_co_u32_e32 v13, vcc, 0, v37, vcc
	v_add_co_u32_e32 v14, vcc, s0, v36
	s_mov_b32 s0, 0xdc000
	s_nop 0
	v_addc_co_u32_e32 v15, vcc, 0, v37, vcc
	v_add_co_u32_e32 v16, vcc, s0, v36
	s_mov_b32 s0, 0xf0000
	s_nop 0
	v_addc_co_u32_e32 v17, vcc, 0, v37, vcc
	v_add_co_u32_e32 v24, vcc, s0, v36
	s_mov_b32 s0, 0x104000
	s_waitcnt vmcnt(34)
	v_addc_co_u32_e32 v25, vcc, 0, v37, vcc
	v_add_co_u32_e32 v26, vcc, s0, v36
	s_mov_b32 s0, 0x118000
	s_waitcnt vmcnt(32)
	v_addc_co_u32_e32 v27, vcc, 0, v37, vcc
	v_add_co_u32_e32 v28, vcc, s0, v36
	s_mov_b32 s0, 0x12c000
	s_waitcnt vmcnt(30)
	v_addc_co_u32_e32 v29, vcc, 0, v37, vcc
	v_add_co_u32_e32 v30, vcc, s0, v36
	v_lshl_add_u64 v[40:41], v[22:23], 0, v[20:21]
	s_waitcnt vmcnt(28)
	v_addc_co_u32_e32 v31, vcc, 0, v37, vcc
	global_load_dword v2, v[36:37], off nt
	global_load_dword v11, v[12:13], off nt
	s_nop 0
	global_load_dword v12, v[14:15], off nt
	global_load_dword v13, v[16:17], off nt
	s_nop 0
	global_load_dword v14, v[24:25], off nt
	global_load_dword v15, v[26:27], off nt
	global_load_dword v16, v[28:29], off nt
	global_load_dword v17, v[30:31], off nt
	v_mbcnt_lo_u32_b32 v29, -1, 0
	v_mbcnt_hi_u32_b32 v29, -1, v29
	v_cmp_eq_u32_e32 vcc, 0, v1
	v_and_b32_e32 v31, 64, v29
	v_mov_b32_e32 v1, 0xbe000000
	v_cndmask_b32_e64 v38, -1.0, 1.0, vcc
	v_mov_b32_e32 v22, 0x3e000000
	v_cmp_gt_u32_e32 vcc, 32, v178
	v_xor_b32_e32 v30, 16, v29
	v_add_u32_e32 v31, 64, v31
	v_cndmask_b32_e32 v42, v1, v22, vcc
	v_cmp_lt_i32_e32 vcc, v30, v31
	v_ashrrev_i32_e32 v19, 31, v18
	s_add_i32 s4, 0, 0x22000
	v_readlane_b32 s5, v249, 37
	v_cndmask_b32_e32 v30, v29, v30, vcc
	s_and_b32 s8, s5, 0xffffffc0
	v_add_u32_e32 v1, s4, v20
	v_or_b32_e32 v20, v18, v34
	v_lshlrev_b32_e32 v64, 2, v30
	v_xor_b32_e32 v30, 32, v29
	v_lshl_add_u64 v[46:47], s[74:75], 0, v[18:19]
	v_lshlrev_b32_e32 v18, 5, v178
	v_readlane_b32 s22, v249, 19
	v_readlane_b32 s23, v249, 20
	s_cmp_lt_u32 s5, 64
	v_lshlrev_b32_e32 v35, 5, v20
	v_cmp_lt_i32_e32 vcc, v30, v31
	v_and_b32_e32 v18, 0x600, v18
	v_readlane_b32 s16, v249, 13
	v_readlane_b32 s17, v249, 14
	v_lshl_add_u32 v21, v178, 2, s4
	v_lshlrev_b32_e32 v22, 5, v34
	v_cmp_gt_u32_e64 s[2:3], 16, v178
	s_cselect_b64 s[4:5], -1, 0
	v_or_b32_e32 v20, 0x800, v35
	v_or_b32_e32 v23, 0x1000, v35
	v_or_b32_e32 v24, 0x1800, v35
	v_or_b32_e32 v25, 0x2000, v35
	v_or_b32_e32 v26, 0x2800, v35
	v_or_b32_e32 v27, 0x3000, v35
	v_or_b32_e32 v28, 0x3800, v35
	v_cndmask_b32_e32 v29, v29, v30, vcc
	v_add_u32_e32 v18, s7, v18
	v_readlane_b32 s22, v249, 41
	s_mov_b32 s0, 0x3e000000
	s_and_b64 s[4:5], s[2:3], s[4:5]
	v_lshlrev_b32_e32 v65, 2, v29
	v_mov_b32_e32 v39, v38
	v_mov_b32_e32 v43, v42
	v_add3_u32 v66, v18, v22, 0
	v_add_u32_e32 v67, s8, v21
	s_mov_b32 s7, 0xda24260
	s_mov_b32 s8, 0x42fe0000
	s_mov_b32 s11, 0xc0c0400
	s_mov_b32 s16, 0x5040100
	v_add_u32_e32 v68, 0, v20
	v_add_u32_e32 v69, 0, v23
	v_add_u32_e32 v70, 0, v24
	v_add_u32_e32 v71, 0, v25
	v_add_u32_e32 v72, 0, v26
	v_add_u32_e32 v73, 0, v27
	v_add_u32_e32 v74, 0, v28
	s_mov_b32 s17, s34
	v_readlane_b32 s23, v249, 42
	v_readlane_b32 s13, v249, 10
	v_readlane_b32 s14, v249, 11
	v_readlane_b32 s15, v249, 12
	v_readlane_b32 s18, v249, 15
	v_readlane_b32 s20, v249, 17
	v_readlane_b32 s21, v249, 18
	v_readlane_b32 s26, v249, 23
	v_readlane_b32 s27, v249, 24
	s_branch .LBB0_81

; #define SQ_LOAD(v, blk) do { _Pragma("unroll") for (int i = 0; i < 16; ++i) v[i] = wp[(size_t)(64 * (blk) + i) * ldw]; } while (0)
; template <class MapF>
; __device__ __forceinline__ void strip_quant(const float* W, int ldw, unsigned char* W8o, float* cso, int nstrips, int s0, int sstride, LAS unsigned char* lds, int lane, int wave, const MapF map) {
;     ...
; #pragma unroll 1
;         for (int blk = 0; blk < 8; blk += 2) {
;             if (blk != 0) SQ_LOAD(vb, blk + 1);
;             SQ_FIN(va, blk);
;             if (blk + 2 < 8) SQ_LOAD(va, blk + 2);
;             SQ_FIN(vb, blk + 1);
.LBB0_83:
	s_cmp_eq_u32 s12, 0
	v_lshl_add_u64 v[62:63], v[36:37], 0, s[12:13]
	s_cbranch_scc1 .LBB0_85
	v_add_co_u32_e32 v18, vcc, 0x500000, v62
	s_nop 1
	v_addc_co_u32_e32 v19, vcc, 0, v63, vcc
	v_add_co_u32_e32 v20, vcc, 0x514000, v62
	s_nop 1
	v_addc_co_u32_e32 v21, vcc, 0, v63, vcc
	v_add_co_u32_e32 v22, vcc, 0x528000, v62
	s_nop 1
	v_addc_co_u32_e32 v23, vcc, 0, v63, vcc
	v_add_co_u32_e32 v24, vcc, 0x53c000, v62
	s_nop 1
	v_addc_co_u32_e32 v25, vcc, 0, v63, vcc
	v_add_co_u32_e32 v26, vcc, 0x550000, v62
	s_nop 1
	v_addc_co_u32_e32 v27, vcc, 0, v63, vcc
	v_add_co_u32_e32 v28, vcc, 0x564000, v62
	s_nop 1
	v_addc_co_u32_e32 v29, vcc, 0, v63, vcc
	v_add_co_u32_e32 v30, vcc, 0x578000, v62
	s_nop 1
	v_addc_co_u32_e32 v31, vcc, 0, v63, vcc
	v_add_co_u32_e32 v32, vcc, 0x58c000, v62
	s_nop 1
	v_addc_co_u32_e32 v33, vcc, 0, v63, vcc
	global_load_dword v44, v[18:19], off nt
	global_load_dword v45, v[20:21], off nt
	global_load_dword v48, v[22:23], off nt
	global_load_dword v49, v[24:25], off nt
	global_load_dword v50, v[26:27], off nt
	global_load_dword v51, v[28:29], off nt
	global_load_dword v52, v[30:31], off nt
	global_load_dword v53, v[32:33], off nt
	v_add_co_u32_e32 v18, vcc, 0x5a0000, v62
	s_nop 1
	v_addc_co_u32_e32 v19, vcc, 0, v63, vcc
	v_add_co_u32_e32 v20, vcc, 0x5b4000, v62
	s_nop 1
	v_addc_co_u32_e32 v21, vcc, 0, v63, vcc
	v_add_co_u32_e32 v22, vcc, 0x5c8000, v62
	s_nop 1
	v_addc_co_u32_e32 v23, vcc, 0, v63, vcc
	v_add_co_u32_e32 v24, vcc, 0x5dc000, v62
	s_nop 1
	v_addc_co_u32_e32 v25, vcc, 0, v63, vcc
	v_add_co_u32_e32 v26, vcc, 0x5f0000, v62
	s_nop 1
	v_addc_co_u32_e32 v27, vcc, 0, v63, vcc
	v_add_co_u32_e32 v28, vcc, 0x604000, v62
	s_nop 1
	v_addc_co_u32_e32 v29, vcc, 0, v63, vcc
	v_add_co_u32_e32 v30, vcc, 0x618000, v62
	s_nop 1
	v_addc_co_u32_e32 v31, vcc, 0, v63, vcc
	v_add_co_u32_e32 v32, vcc, 0x62c000, v62
	s_nop 1
	v_addc_co_u32_e32 v33, vcc, 0, v63, vcc
	global_load_dword v54, v[18:19], off nt
	global_load_dword v55, v[20:21], off nt
	global_load_dword v56, v[22:23], off nt
	global_load_dword v57, v[24:25], off nt
	global_load_dword v58, v[26:27], off nt
	global_load_dword v59, v[28:29], off nt
	global_load_dword v60, v[30:31], off nt
	global_load_dword v61, v[32:33], off nt
.LBB0_85:
	s_waitcnt vmcnt(7)
	v_mov_b32_e32 v24, v10
	s_waitcnt vmcnt(3)
	v_mov_b32_e32 v25, v14
	v_mov_b32_e32 v26, v11
	s_waitcnt vmcnt(2)
	v_mov_b32_e32 v27, v15
	v_pk_add_f32 v[24:25], v[24:25], v[26:27]
	v_mov_b32_e32 v26, v12
	s_waitcnt vmcnt(1)
	v_mov_b32_e32 v27, v16
	v_mov_b32_e32 v28, v13
	s_waitcnt vmcnt(0)
	v_mov_b32_e32 v29, v17
	v_pk_add_f32 v[26:27], v[26:27], v[28:29]
	v_mov_b32_e32 v28, v2
	v_mov_b32_e32 v29, v10
	v_mov_b32_e32 v10, v3
	v_mov_b32_e32 v18, v2
	v_mov_b32_e32 v19, v6
	v_mov_b32_e32 v20, v3
	v_mov_b32_e32 v21, v7
	v_pk_add_f32 v[2:3], v[28:29], v[10:11] neg_lo:[0,1] neg_hi:[0,1]
	v_mov_b32_e32 v10, v4
	v_mov_b32_e32 v11, v12
	v_mov_b32_e32 v12, v5
	v_pk_add_f32 v[18:19], v[18:19], v[20:21]
	v_mov_b32_e32 v20, v4
	v_mov_b32_e32 v21, v8
	v_mov_b32_e32 v22, v5
	v_mov_b32_e32 v23, v9
	v_pk_add_f32 v[4:5], v[10:11], v[12:13] neg_lo:[0,1] neg_hi:[0,1]
	v_mov_b32_e32 v10, v6
	v_mov_b32_e32 v11, v14
	v_mov_b32_e32 v14, v7
	v_pk_add_f32 v[20:21], v[20:21], v[22:23]
	v_pk_add_f32 v[6:7], v[10:11], v[14:15] neg_lo:[0,1] neg_hi:[0,1]
	v_mov_b32_e32 v10, v8
	v_mov_b32_e32 v11, v16
	v_mov_b32_e32 v16, v9
	v_pk_add_f32 v[8:9], v[10:11], v[16:17] neg_lo:[0,1] neg_hi:[0,1]
	v_mov_b32_e32 v14, v18
	v_mov_b32_e32 v15, v2
	v_mov_b32_e32 v16, v20
	v_mov_b32_e32 v17, v4
	v_pk_add_f32 v[22:23], v[18:19], v[20:21] neg_lo:[0,1] neg_hi:[0,1]
	v_pk_add_f32 v[10:11], v[2:3], v[4:5] neg_lo:[0,1] neg_hi:[0,1]
	v_pk_add_f32 v[12:13], v[6:7], v[8:9] neg_lo:[0,1] neg_hi:[0,1]
	v_pk_add_f32 v[14:15], v[14:15], v[16:17]
	v_pk_mov_b32 v[16:17], v[18:19], v[6:7] op_sel:[1,0]
	v_pk_mov_b32 v[18:19], v[20:21], v[8:9] op_sel:[1,0]
	v_mov_b32_e32 v2, v24
	v_mov_b32_e32 v4, v26
	v_mov_b32_e32 v6, v25
	v_mov_b32_e32 v8, v27
	v_pk_add_f32 v[16:17], v[16:17], v[18:19]
	v_pk_add_f32 v[2:3], v[2:3], v[4:5]
	v_pk_add_f32 v[4:5], v[6:7], v[8:9]
	v_pk_add_f32 v[24:25], v[24:25], v[26:27] neg_lo:[0,1] neg_hi:[0,1]
	v_pk_add_f32 v[6:7], v[14:15], v[16:17]
	v_pk_add_f32 v[8:9], v[2:3], v[4:5]
	v_pk_add_f32 v[28:29], v[22:23], v[22:23] op_sel:[0,1] op_sel_hi:[1,0] neg_lo:[0,1] neg_hi:[0,1]
	v_pk_add_f32 v[26:27], v[10:11], v[12:13] neg_lo:[0,1] neg_hi:[0,1]
	v_mov_b32_e32 v32, v22
	v_mov_b32_e32 v33, v10
	v_pk_mov_b32 v[22:23], v[22:23], v[12:13] op_sel:[1,0]
	v_mov_b32_e32 v10, v24
	v_mov_b32_e32 v12, v25
	v_pk_add_f32 v[18:19], v[6:7], v[8:9]
	v_pk_add_f32 v[32:33], v[32:33], v[22:23]
	v_pk_add_f32 v[10:11], v[10:11], v[12:13]
	ds_bpermute_b32 v20, v64, v18
	ds_bpermute_b32 v21, v64, v19
	v_pk_add_f32 v[12:13], v[32:33], v[10:11]
	v_pk_add_f32 v[14:15], v[14:15], v[16:17] neg_lo:[0,1] neg_hi:[0,1]
	v_pk_add_f32 v[2:3], v[2:3], v[4:5] neg_lo:[0,1] neg_hi:[0,1]
	ds_bpermute_b32 v22, v64, v12
	ds_bpermute_b32 v23, v64, v13
	v_pk_add_f32 v[4:5], v[14:15], v[2:3]
	ds_bpermute_b32 v16, v64, v4
	ds_bpermute_b32 v17, v64, v5
	s_waitcnt lgkmcnt(4)
	v_pk_fma_f32 v[18:19], v[18:19], v[38:39], v[20:21]
	ds_bpermute_b32 v20, v65, v18
	ds_bpermute_b32 v21, v65, v19
	s_waitcnt lgkmcnt(4)
	v_pk_fma_f32 v[12:13], v[12:13], v[38:39], v[22:23]
	ds_bpermute_b32 v22, v65, v12
	ds_bpermute_b32 v23, v65, v13
	s_waitcnt lgkmcnt(4)
; #define SQ_LOAD(v, blk) do { _Pragma("unroll") for (int i = 0; i < 16; ++i) v[i] = wp[(size_t)(64 * (blk) + i) * ldw]; } while (0)
; template <class MapF>
; __device__ __forceinline__ void strip_quant(const float* W, int ldw, unsigned char* W8o, float* cso, int nstrips, int s0, int sstride, LAS unsigned char* lds, int lane, int wave, const MapF map) {
;     ...
; #pragma unroll 1
;         for (int blk = 0; blk < 8; blk += 2) {
;             if (blk != 0) SQ_LOAD(vb, blk + 1);
;             SQ_FIN(va, blk);
;             if (blk + 2 < 8) SQ_LOAD(va, blk + 2);
;             SQ_FIN(vb, blk + 1);
	v_pk_fma_f32 v[4:5], v[4:5], v[38:39], v[16:17]
	ds_bpermute_b32 v16, v65, v4
	ds_bpermute_b32 v17, v65, v5
	v_pk_add_f32 v[30:31], v[24:25], v[24:25] op_sel:[0,1] op_sel_hi:[1,0] neg_lo:[0,1] neg_hi:[0,1]
	s_waitcnt lgkmcnt(4)
	v_pk_mul_f32 v[20:21], v[20:21], s[0:1] op_sel_hi:[1,0]
	v_mov_b32_e32 v29, v26
	v_pk_fma_f32 v[18:19], v[18:19], v[42:43], v[20:21]
	s_waitcnt lgkmcnt(2)
	v_pk_mul_f32 v[20:21], v[22:23], s[0:1] op_sel_hi:[1,0]
	v_mov_b32_e32 v31, v27
	v_pk_fma_f32 v[20:21], v[12:13], v[42:43], v[20:21]
	s_waitcnt lgkmcnt(0)
	v_pk_mul_f32 v[12:13], v[16:17], s[0:1] op_sel_hi:[1,0]
	v_pk_add_f32 v[16:17], v[28:29], v[30:31]
	ds_bpermute_b32 v24, v64, v16
	ds_bpermute_b32 v25, v64, v17
	v_pk_add_f32 v[6:7], v[6:7], v[8:9] neg_lo:[0,1] neg_hi:[0,1]
	ds_bpermute_b32 v8, v64, v6
	ds_bpermute_b32 v9, v64, v7
	v_pk_fma_f32 v[22:23], v[4:5], v[42:43], v[12:13]
	s_waitcnt lgkmcnt(2)
	v_pk_fma_f32 v[4:5], v[16:17], v[38:39], v[24:25]
	ds_bpermute_b32 v12, v65, v4
	ds_bpermute_b32 v13, v65, v5
	s_waitcnt lgkmcnt(2)
	v_pk_fma_f32 v[6:7], v[6:7], v[38:39], v[8:9]
	ds_bpermute_b32 v8, v65, v6
	ds_bpermute_b32 v9, v65, v7
	v_pk_add_f32 v[10:11], v[32:33], v[10:11] neg_lo:[0,1] neg_hi:[0,1]
	ds_bpermute_b32 v16, v64, v10
	ds_bpermute_b32 v17, v64, v11
	s_waitcnt lgkmcnt(4)
	v_pk_mul_f32 v[12:13], v[12:13], s[0:1] op_sel_hi:[1,0]
	v_pk_add_f32 v[2:3], v[14:15], v[2:3] neg_lo:[0,1] neg_hi:[0,1]
	v_pk_fma_f32 v[24:25], v[4:5], v[42:43], v[12:13]
	s_waitcnt lgkmcnt(2)
	v_pk_mul_f32 v[4:5], v[8:9], s[0:1] op_sel_hi:[1,0]
	ds_bpermute_b32 v8, v64, v2
	v_pk_fma_f32 v[26:27], v[6:7], v[42:43], v[4:5]
	s_waitcnt lgkmcnt(1)
	v_pk_fma_f32 v[4:5], v[10:11], v[38:39], v[16:17]
	ds_bpermute_b32 v9, v64, v3
	v_pk_add_f32 v[10:11], v[28:29], v[30:31] neg_lo:[0,1] neg_hi:[0,1]
	ds_bpermute_b32 v12, v64, v10
	ds_bpermute_b32 v13, v64, v11
	ds_bpermute_b32 v6, v65, v4
	ds_bpermute_b32 v7, v65, v5
	s_waitcnt lgkmcnt(4)
	v_pk_fma_f32 v[2:3], v[2:3], v[38:39], v[8:9]
	ds_bpermute_b32 v8, v65, v2
	ds_bpermute_b32 v9, v65, v3
	s_waitcnt lgkmcnt(4)
	v_pk_fma_f32 v[10:11], v[10:11], v[38:39], v[12:13]
	ds_bpermute_b32 v12, v65, v10
	ds_bpermute_b32 v13, v65, v11
	s_waitcnt lgkmcnt(4)
	v_pk_mul_f32 v[6:7], v[6:7], s[0:1] op_sel_hi:[1,0]
	s_cmp_gt_u32 s19, 5
	v_pk_fma_f32 v[28:29], v[4:5], v[42:43], v[6:7]
	s_waitcnt lgkmcnt(2)
	v_pk_mul_f32 v[4:5], v[8:9], s[0:1] op_sel_hi:[1,0]
	s_cselect_b64 s[14:15], -1, 0
	v_pk_fma_f32 v[30:31], v[2:3], v[42:43], v[4:5]
	s_waitcnt lgkmcnt(0)
	v_pk_mul_f32 v[2:3], v[12:13], s[0:1] op_sel_hi:[1,0]
	s_and_b64 vcc, exec, s[14:15]
	v_pk_fma_f32 v[32:33], v[10:11], v[42:43], v[2:3]
	v_cvt_pk_bf16_f32 v2, v18, v19
	v_cvt_pk_bf16_f32 v3, v20, v21
	v_cvt_pk_bf16_f32 v4, v22, v23
	v_cvt_pk_bf16_f32 v5, v24, v25
	v_cvt_pk_bf16_f32 v6, v26, v27
	v_cvt_pk_bf16_f32 v7, v28, v29
	v_cvt_pk_bf16_f32 v8, v30, v31
	s_nop 0
	v_cvt_pk_bf16_f32 v9, v32, v33
	ds_write_b128 v75, v[2:5]
	ds_write_b128 v75, v[6:9] offset:16
	v_mov_b64_e32 v[2:3], v[18:19]
	v_mov_b64_e32 v[4:5], v[20:21]
	v_mov_b64_e32 v[6:7], v[22:23]
	v_mov_b64_e32 v[8:9], v[24:25]
	v_mov_b64_e32 v[10:11], v[26:27]
	v_mov_b64_e32 v[12:13], v[28:29]
	v_mov_b64_e32 v[14:15], v[30:31]
	v_mov_b64_e32 v[16:17], v[32:33]
	s_cbranch_vccnz .LBB0_82
	v_add_co_u32_e32 v2, vcc, 0xa00000, v62
	s_nop 1
	v_addc_co_u32_e32 v3, vcc, 0, v63, vcc
	v_add_co_u32_e32 v4, vcc, 0xa14000, v62
	s_nop 1
	v_addc_co_u32_e32 v5, vcc, 0, v63, vcc
	v_add_co_u32_e32 v6, vcc, 0xa28000, v62
	s_nop 1
	v_addc_co_u32_e32 v7, vcc, 0, v63, vcc
	v_add_co_u32_e32 v8, vcc, 0xa3c000, v62
	s_nop 1
	v_addc_co_u32_e32 v9, vcc, 0, v63, vcc
	v_add_co_u32_e32 v10, vcc, 0xa50000, v62
	s_nop 1
	v_addc_co_u32_e32 v11, vcc, 0, v63, vcc
	v_add_co_u32_e32 v12, vcc, 0xa64000, v62
	s_nop 1
	v_addc_co_u32_e32 v13, vcc, 0, v63, vcc
	v_add_co_u32_e32 v14, vcc, 0xa78000, v62
	s_nop 1
	v_addc_co_u32_e32 v15, vcc, 0, v63, vcc
	v_add_co_u32_e32 v16, vcc, 0xa8c000, v62
	s_nop 1
	v_addc_co_u32_e32 v17, vcc, 0, v63, vcc
	global_load_dword v2, v[2:3], off nt
	s_nop 0
	global_load_dword v3, v[4:5], off nt
	s_nop 0
	global_load_dword v4, v[6:7], off nt
	global_load_dword v5, v[8:9], off nt
	s_nop 0
	global_load_dword v6, v[10:11], off nt
	global_load_dword v7, v[12:13], off nt
	global_load_dword v8, v[14:15], off nt
	global_load_dword v9, v[16:17], off nt
	v_add_co_u32_e32 v10, vcc, 0xaa0000, v62
	s_nop 1
	v_addc_co_u32_e32 v11, vcc, 0, v63, vcc
	v_add_co_u32_e32 v12, vcc, 0xab4000, v62
	s_nop 1
	v_addc_co_u32_e32 v13, vcc, 0, v63, vcc
	v_add_co_u32_e32 v14, vcc, 0xac8000, v62
	s_nop 1
	v_addc_co_u32_e32 v15, vcc, 0, v63, vcc
	v_add_co_u32_e32 v16, vcc, 0xadc000, v62
	s_nop 1
	v_addc_co_u32_e32 v17, vcc, 0, v63, vcc
	v_add_co_u32_e32 v78, vcc, 0xaf0000, v62
	s_nop 1
	v_addc_co_u32_e32 v79, vcc, 0, v63, vcc
	v_add_co_u32_e32 v80, vcc, 0xb04000, v62
	s_nop 1
	v_addc_co_u32_e32 v81, vcc, 0, v63, vcc
	v_add_co_u32_e32 v82, vcc, 0xb18000, v62
	s_nop 1
	v_addc_co_u32_e32 v83, vcc, 0, v63, vcc
	v_add_co_u32_e32 v62, vcc, 0xb2c000, v62
	s_nop 1
	v_addc_co_u32_e32 v63, vcc, 0, v63, vcc
	global_load_dword v10, v[10:11], off nt
	s_nop 0
	global_load_dword v11, v[12:13], off nt
	s_nop 0
	global_load_dword v12, v[14:15], off nt
	global_load_dword v13, v[16:17], off nt
	s_nop 0
	global_load_dword v14, v[78:79], off nt
	global_load_dword v15, v[80:81], off nt
	global_load_dword v16, v[82:83], off nt
	global_load_dword v17, v[62:63], off nt
	s_branch .LBB0_82

; template <class MapF>
; __device__ __forceinline__ void strip_quant(const float* W, int ldw, unsigned char* W8o, float* cso, int nstrips, int s0, int sstride, LAS unsigned char* lds, int lane, int wave, const MapF map) {
;     ...
;         cm = fmaxf(cm, __shfl_xor(cm, 16)); cm = fmaxf(cm, __shfl_xor(cm, 32));
;         if (kh == 0) red[wave * 16 + nn] = cm;
;         const int drow_cur = drow0;
;         if (strip + sstride < nstrips) { map(strip + sstride, n0, drow0); wp = W + (size_t)(512 * wave + 16 * kh) * ldw + n0 + nn;
; #pragma unroll
;             for (int i = 0; i < 16; ++i) { va[i] = wp[(size_t)i * ldw]; vb[i] = wp[(size_t)(64 + i) * ldw]; } }
.LBB0_89:
	s_or_b64 exec, exec, s[12:13]
	s_add_i32 s17, s17, s10
	s_cmpk_gt_i32 s17, 0x3ff
	s_cselect_b64 s[12:13], -1, 0
	s_and_b64 vcc, exec, s[12:13]
	s_mov_b32 s19, s18
	s_cbranch_vccnz .LBB0_91
	s_lshl_b32 s19, s17, 4
	s_cmpk_lt_i32 s17, 0x300
	s_cselect_b32 s14, s1, 0xffffd000
	s_add_i32 s14, s14, s19
	s_ashr_i32 s15, s14, 31
	v_lshl_add_u64 v[36:37], s[14:15], 2, v[40:41]
	s_waitcnt vmcnt(15)
	v_add_co_u32_e32 v2, vcc, 0x500000, v36
	s_waitcnt vmcnt(14)
	s_nop 0
	v_addc_co_u32_e32 v3, vcc, 0, v37, vcc
	s_waitcnt vmcnt(13)
	v_add_co_u32_e32 v4, vcc, 0x14000, v36
	s_waitcnt vmcnt(12)
	s_nop 0
	v_addc_co_u32_e32 v5, vcc, 0, v37, vcc
	s_waitcnt vmcnt(11)
	v_add_co_u32_e32 v6, vcc, 0x514000, v36
	s_waitcnt vmcnt(10)
	s_nop 0
	v_addc_co_u32_e32 v7, vcc, 0, v37, vcc
	s_waitcnt vmcnt(9)
	v_add_co_u32_e32 v8, vcc, 0x28000, v36
	s_waitcnt vmcnt(8)
	s_nop 0
	v_addc_co_u32_e32 v9, vcc, 0, v37, vcc
	s_waitcnt vmcnt(7)
	v_add_co_u32_e32 v10, vcc, 0x528000, v36
	s_waitcnt vmcnt(6)
	s_nop 0
	v_addc_co_u32_e32 v11, vcc, 0, v37, vcc
	s_waitcnt vmcnt(5)
	v_add_co_u32_e32 v12, vcc, 0x3c000, v36
	s_waitcnt vmcnt(4)
	s_nop 0
	v_addc_co_u32_e32 v13, vcc, 0, v37, vcc
	s_waitcnt vmcnt(3)
	v_add_co_u32_e32 v14, vcc, 0x53c000, v36
	s_waitcnt vmcnt(2)
	s_nop 0
	v_addc_co_u32_e32 v15, vcc, 0, v37, vcc
	s_waitcnt vmcnt(1)
	v_add_co_u32_e32 v16, vcc, 0x50000, v36
	s_waitcnt vmcnt(0)
	s_nop 0
	v_addc_co_u32_e32 v17, vcc, 0, v37, vcc
	global_load_dword v44, v[2:3], off nt
	s_nop 0
	global_load_dword v3, v[4:5], off nt
	global_load_dword v45, v[6:7], off nt
	s_nop 0
	global_load_dword v4, v[8:9], off nt
	global_load_dword v48, v[10:11], off nt
	global_load_dword v5, v[12:13], off nt
	global_load_dword v49, v[14:15], off nt
	global_load_dword v6, v[16:17], off nt
	v_add_co_u32_e32 v8, vcc, 0x550000, v36
	s_nop 1
	v_addc_co_u32_e32 v9, vcc, 0, v37, vcc
	v_add_co_u32_e32 v10, vcc, 0x64000, v36
	s_nop 1
	v_addc_co_u32_e32 v11, vcc, 0, v37, vcc
	v_add_co_u32_e32 v12, vcc, 0x564000, v36
	s_nop 1
	v_addc_co_u32_e32 v13, vcc, 0, v37, vcc
	v_add_co_u32_e32 v14, vcc, 0x78000, v36
	s_nop 1
	v_addc_co_u32_e32 v15, vcc, 0, v37, vcc
	v_add_co_u32_e32 v16, vcc, 0x578000, v36
	s_nop 1
	v_addc_co_u32_e32 v17, vcc, 0, v37, vcc
	v_add_co_u32_e32 v18, vcc, 0x8c000, v36
	s_waitcnt lgkmcnt(0)
	s_nop 0
	v_addc_co_u32_e32 v19, vcc, 0, v37, vcc
	v_add_co_u32_e32 v20, vcc, 0x58c000, v36
	s_nop 1
	v_addc_co_u32_e32 v21, vcc, 0, v37, vcc
	v_add_co_u32_e32 v22, vcc, 0xa0000, v36
	s_nop 1
	v_addc_co_u32_e32 v23, vcc, 0, v37, vcc
	global_load_dword v50, v[8:9], off nt
	global_load_dword v7, v[10:11], off nt
	global_load_dword v51, v[12:13], off nt
	s_nop 0
	global_load_dword v8, v[14:15], off nt
	global_load_dword v52, v[16:17], off nt
	global_load_dword v9, v[18:19], off nt
	global_load_dword v53, v[20:21], off nt
	global_load_dword v10, v[22:23], off nt
	v_add_co_u32_e32 v12, vcc, 0x5a0000, v36
	s_nop 1
	v_addc_co_u32_e32 v13, vcc, 0, v37, vcc
	v_add_co_u32_e32 v14, vcc, 0xb4000, v36
	s_nop 1
	v_addc_co_u32_e32 v15, vcc, 0, v37, vcc
	v_add_co_u32_e32 v16, vcc, 0x5b4000, v36
	s_nop 1
	v_addc_co_u32_e32 v17, vcc, 0, v37, vcc
	v_add_co_u32_e32 v18, vcc, 0xc8000, v36
	s_nop 1
	v_addc_co_u32_e32 v19, vcc, 0, v37, vcc
	v_add_co_u32_e32 v20, vcc, 0x5c8000, v36
	s_nop 1
	v_addc_co_u32_e32 v21, vcc, 0, v37, vcc
	v_add_co_u32_e32 v22, vcc, 0xdc000, v36
	s_nop 1
	v_addc_co_u32_e32 v23, vcc, 0, v37, vcc
	v_add_co_u32_e32 v24, vcc, 0x5dc000, v36
	s_nop 1
	v_addc_co_u32_e32 v25, vcc, 0, v37, vcc
	v_add_co_u32_e32 v26, vcc, 0xf0000, v36
	s_nop 1
	v_addc_co_u32_e32 v27, vcc, 0, v37, vcc
	global_load_dword v54, v[12:13], off nt
	global_load_dword v11, v[14:15], off nt
	global_load_dword v55, v[16:17], off nt
	s_nop 0
	global_load_dword v12, v[18:19], off nt
	global_load_dword v56, v[20:21], off nt
	global_load_dword v13, v[22:23], off nt
	global_load_dword v57, v[24:25], off nt
	global_load_dword v14, v[26:27], off nt
	v_add_co_u32_e32 v16, vcc, 0x5f0000, v36
	s_nop 1
	v_addc_co_u32_e32 v17, vcc, 0, v37, vcc
	v_add_co_u32_e32 v18, vcc, 0x104000, v36
	s_nop 1
	v_addc_co_u32_e32 v19, vcc, 0, v37, vcc
	v_add_co_u32_e32 v20, vcc, 0x604000, v36
	s_nop 1
	v_addc_co_u32_e32 v21, vcc, 0, v37, vcc
	v_add_co_u32_e32 v22, vcc, 0x118000, v36
	s_nop 1
	v_addc_co_u32_e32 v23, vcc, 0, v37, vcc
	v_add_co_u32_e32 v24, vcc, 0x618000, v36
	s_nop 1
	v_addc_co_u32_e32 v25, vcc, 0, v37, vcc
	v_add_co_u32_e32 v26, vcc, 0x12c000, v36
	s_nop 1
	v_addc_co_u32_e32 v27, vcc, 0, v37, vcc
	v_add_co_u32_e32 v28, vcc, 0x62c000, v36
	s_nop 1
	v_addc_co_u32_e32 v29, vcc, 0, v37, vcc
	global_load_dword v2, v[36:37], off nt
	global_load_dword v58, v[16:17], off nt
	global_load_dword v15, v[18:19], off nt
	global_load_dword v59, v[20:21], off nt
	s_nop 0
	global_load_dword v16, v[22:23], off nt
	global_load_dword v60, v[24:25], off nt
	global_load_dword v17, v[26:27], off nt
	global_load_dword v61, v[28:29], off nt

; #define LAS __attribute__((address_space(3)))
; __global__ void __launch_bounds__(NWAVES * 64, 2) fwd_kernel(Args args) {
;     ...
;         LAS float* cA = (LAS float*)lds; LAS float* cB = cA + D;
;         int cur_b = -1;
;         for (int slot = vcu; slot < M / 8; slot += G) {
;             const int b = slot / (SEQ / 8);
;             if (b != cur_b) { __syncthreads();
;                 for (int i = tid; i < D; i += NWAVES * 64) { cA[i] = g_mix_pre[i] * (1.0f + mod[b * NMOD + 1 * D + i]); cB[i] = mod[b * NMOD + 0 * D + i]; }
;                 __syncthreads(); cur_b = b; }
.LBB0_151:
	s_ashr_i32 s0, s27, 31
	s_lshr_b32 s0, s0, 22
	s_add_i32 s0, s27, s0
	s_ashr_i32 s29, s0, 10
	s_cmp_eq_u32 s29, s28
	s_cbranch_scc1 .LBB0_155
	s_mul_i32 s28, s29, 0x6000
	v_or_b32_e32 v2, s28, v0
	v_ashrrev_i32_e32 v3, 31, v2
	v_lshl_add_u64 v[2:3], v[2:3], 2, s[30:31]
	v_or_b32_e32 v6, s28, v129
	v_add_co_u32_e32 v4, vcc, 0x4000, v2
	v_ashrrev_i32_e32 v7, 31, v6
	s_nop 0
	v_addc_co_u32_e32 v5, vcc, 0, v3, vcc
	v_lshl_add_u64 v[6:7], v[6:7], 2, s[30:31]
	v_or_b32_e32 v10, s28, v179
	v_add_co_u32_e32 v8, vcc, s11, v6
	s_waitcnt vmcnt(14)
	v_ashrrev_i32_e32 v11, 31, v10
	v_addc_co_u32_e32 v9, vcc, 0, v7, vcc
	v_lshl_add_u64 v[10:11], v[10:11], 2, s[30:31]
	s_waitcnt vmcnt(11)
	v_or_b32_e32 v14, s28, v130
	v_add_co_u32_e32 v12, vcc, s11, v10
	s_waitcnt vmcnt(10)
	v_ashrrev_i32_e32 v15, 31, v14
	v_addc_co_u32_e32 v13, vcc, 0, v11, vcc
	v_lshl_add_u64 v[14:15], v[14:15], 2, s[30:31]
	s_waitcnt vmcnt(9)
	v_add_co_u32_e32 v16, vcc, s11, v14
	s_waitcnt vmcnt(8)
	s_nop 0
	v_addc_co_u32_e32 v17, vcc, 0, v15, vcc
	s_barrier
	global_load_dword v18, v[4:5], off nt
	global_load_dword v19, v[8:9], off nt
	global_load_dword v20, v[12:13], off nt
	s_nop 0
	global_load_dword v16, v[16:17], off nt
	s_nop 0
	global_load_dword v14, v[14:15], off nt
	s_nop 0
	global_load_dword v15, v[10:11], off nt
	global_load_dword v17, v[6:7], off nt
	global_load_dword v21, v[74:75], off nt
	global_load_dword v22, v[74:75], off offset:2048 nt
	global_load_dword v23, v[76:77], off nt
	v_or_b32_e32 v4, s28, v210
	v_ashrrev_i32_e32 v5, 31, v4
	v_lshl_add_u64 v[4:5], v[4:5], 2, s[30:31]
	v_or_b32_e32 v8, s28, v131
	v_add_co_u32_e32 v6, vcc, s11, v4
	v_ashrrev_i32_e32 v9, 31, v8
	s_nop 0
	v_addc_co_u32_e32 v7, vcc, 0, v5, vcc
	v_lshl_add_u64 v[8:9], v[8:9], 2, s[30:31]
	v_add_co_u32_e32 v10, vcc, s11, v8
	v_or_b32_e32 v12, s28, v211
	s_nop 0
	v_addc_co_u32_e32 v11, vcc, 0, v9, vcc
	v_ashrrev_i32_e32 v13, 31, v12
	v_lshl_add_u64 v[12:13], v[12:13], 2, s[30:31]
	global_load_dword v6, v[6:7], off nt
	s_nop 0
	global_load_dword v7, v[10:11], off nt
	s_nop 0
	global_load_dword v10, v[12:13], off nt
	s_nop 0
	global_load_dword v8, v[8:9], off nt
	s_nop 0
	global_load_dword v9, v[4:5], off nt
	global_load_dword v11, v[78:79], off nt
	global_load_dword v24, v[80:81], off nt
	global_load_dword v25, v[82:83], off nt
	v_add_co_u32_e32 v4, vcc, 0x4000, v12
	s_waitcnt vmcnt(16)
	v_add_f32_e32 v12, 1.0, v19
	v_addc_co_u32_e32 v5, vcc, 0, v13, vcc
	global_load_dword v4, v[4:5], off nt
	s_nop 0
	global_load_dword v5, v[84:85], off nt
	s_nop 0
	global_load_dword v2, v[2:3], off nt
	v_add_f32_e32 v3, 1.0, v18
	s_waitcnt vmcnt(18)
	v_add_f32_e32 v13, 1.0, v20
	s_waitcnt vmcnt(13)
	v_mul_f32_e32 v3, v21, v3
	s_waitcnt vmcnt(12)
	v_mul_f32_e32 v12, v22, v12
	ds_write2st64_b32 v128, v3, v12 offset1:8
	v_add_f32_e32 v12, 1.0, v16
	s_waitcnt vmcnt(11)
	v_mul_f32_e32 v3, v23, v13
	ds_write2st64_b32 v128, v17, v15 offset0:72 offset1:80
	s_waitcnt vmcnt(6)
	ds_write2st64_b32 v128, v14, v9 offset0:88 offset1:96
	s_waitcnt vmcnt(5)
	v_mul_f32_e32 v11, v11, v12
	ds_write2st64_b32 v128, v3, v11 offset0:16 offset1:24
	v_add_f32_e32 v3, 1.0, v6
	v_add_f32_e32 v6, 1.0, v7
	s_waitcnt vmcnt(4)
	v_mul_f32_e32 v3, v24, v3
	s_waitcnt vmcnt(3)
	v_mul_f32_e32 v6, v25, v6
	ds_write2st64_b32 v128, v3, v6 offset0:32 offset1:40
	s_waitcnt vmcnt(2)
	v_add_f32_e32 v3, 1.0, v4
	s_waitcnt vmcnt(1)
	v_mul_f32_e32 v3, v5, v3
	s_waitcnt vmcnt(0)
	ds_write2st64_b32 v128, v3, v2 offset0:48 offset1:64
	ds_write2st64_b32 v128, v8, v10 offset0:104 offset1:112
	s_and_saveexec_b64 s[0:1], s[4:5]
	s_cbranch_execz .LBB0_154
	v_or_b32_e32 v2, s28, v132
	v_ashrrev_i32_e32 v3, 31, v2
	v_lshl_add_u64 v[2:3], v[2:3], 2, s[30:31]
	v_add_co_u32_e32 v4, vcc, 0x4000, v2
	s_nop 1
	v_addc_co_u32_e32 v5, vcc, 0, v3, vcc
	global_load_dword v4, v[4:5], off nt
	s_nop 0
	global_load_dword v5, v[86:87], off nt
	s_nop 0
	global_load_dword v2, v[2:3], off nt
	s_waitcnt vmcnt(2)
	v_add_f32_e32 v3, 1.0, v4
	s_waitcnt vmcnt(1)
	v_mul_f32_e32 v3, v5, v3
	s_waitcnt vmcnt(0)
	ds_write2st64_b32 v128, v3, v2 offset0:56 offset1:120

; __device__ __forceinline__ float dot4(f32x4 a) { return (a.x * a.x + a.y * a.y) + (a.z * a.z + a.w * a.w); }
; __global__ void __launch_bounds__(NWAVES * 64, 2) fwd_kernel(Args args) {
;     ...
;             { const size_t row = (size_t)slot * 8 + wave;
;                 const f32x4* xr = (const f32x4*)(x + row * D) + lane;
;                 f32x4 v[16]; float s = 0.f;
; #pragma unroll
;                 for (int j = 0; j < 16; ++j) { v[j] = xr[64 * j]; s += dot4(v[j]); }
;                 const float rstd = 1.0f / sqrtf(wave_sum(s) * (1.0f / D) + RMS_EPS);
.LBB0_155:
	v_add_co_u32_e32 v2, vcc, s18, v90
	s_mov_b64 s[36:37], s[70:71]
	s_nop 0
	v_addc_co_u32_e32 v3, vcc, -1, v91, vcc
	global_load_dwordx4 v[46:49], v[2:3], off offset:-3072 nt
	global_load_dwordx4 v[30:33], v[2:3], off offset:-1024 nt
	global_load_dwordx4 v[42:45], v[2:3], off offset:-2048 nt
	global_load_dwordx4 v[34:37], v[2:3], off nt
	v_add_co_u32_e32 v2, vcc, s19, v90
	s_waitcnt vmcnt(3)
	v_pk_mul_f32 v[96:97], v[48:49], v[48:49]
	v_addc_co_u32_e32 v3, vcc, -1, v91, vcc
	v_add_co_u32_e32 v4, vcc, 0xffffd000, v90
	global_load_dwordx4 v[26:29], v[2:3], off offset:-3072 nt
	global_load_dwordx4 v[18:21], v[2:3], off offset:-2048 nt
	v_addc_co_u32_e32 v5, vcc, -1, v91, vcc
	global_load_dwordx4 v[62:65], v[4:5], off offset:-3072 nt
	global_load_dwordx4 v[58:61], v[4:5], off offset:-2048 nt
	global_load_dwordx4 v[50:53], v[4:5], off nt
	global_load_dwordx4 v[54:57], v[4:5], off offset:-1024 nt
	global_load_dwordx4 v[22:25], v[2:3], off offset:-1024 nt
	global_load_dwordx4 v[10:13], v[90:91], off offset:-3072 nt
	global_load_dwordx4 v[14:17], v[90:91], off offset:-2048 nt
	global_load_dwordx4 v[6:9], v[90:91], off offset:-1024 nt
	s_nop 0
	global_load_dwordx4 v[2:5], v[90:91], off nt
	global_load_dwordx4 v[38:41], v[90:91], off offset:-4096 nt
	s_waitcnt vmcnt(13)
	v_mul_f32_e32 v100, v43, v43
	v_mul_f32_e32 v102, v45, v45
	v_pk_mul_f32 v[98:99], v[46:47], v[46:47]
	v_mul_f32_e32 v140, v32, v32
	v_mul_f32_e32 v141, v33, v33
	s_waitcnt vmcnt(12)
	v_pk_mul_f32 v[104:105], v[36:37], v[36:37]
	v_pk_mul_f32 v[106:107], v[34:35], v[34:35]
	v_pk_fma_f32 v[100:101], v[42:43], v[42:43], v[100:101] op_sel_hi:[1,1,0]
	v_pk_fma_f32 v[102:103], v[44:45], v[44:45], v[102:103] op_sel_hi:[1,1,0]
	v_pk_mov_b32 v[136:137], v[98:99], v[96:97] op_sel:[1,0]
	v_mov_b32_e32 v99, v97
	v_pk_mov_b32 v[96:97], v[106:107], v[104:105] op_sel:[1,0]
	v_mov_b32_e32 v107, v105
	v_mov_b32_e32 v101, v140
	v_mov_b32_e32 v103, v141
	v_pk_add_f32 v[96:97], v[96:97], v[106:107]
	v_pk_add_f32 v[100:101], v[100:101], v[102:103]
	v_pk_add_f32 v[98:99], v[136:137], v[98:99]
	v_mul_f32_e32 v111, v30, v30
	v_mul_f32_e32 v135, v31, v31
	v_pk_add_f32 v[98:99], v[98:99], v[98:99] op_sel:[0,1] op_sel_hi:[1,0]
	v_pk_add_f32 v[96:97], v[96:97], v[96:97] op_sel:[0,1] op_sel_hi:[1,0]
	v_mov_b32_e32 v99, v135
	s_waitcnt vmcnt(9)
	v_pk_mul_f32 v[112:113], v[64:65], v[64:65]
	v_pk_mul_f32 v[114:115], v[62:63], v[62:63]
	s_waitcnt vmcnt(8)
	v_pk_mul_f32 v[116:117], v[60:61], v[60:61]
	v_pk_mul_f32 v[118:119], v[58:59], v[58:59]
	v_pk_mov_b32 v[138:139], v[114:115], v[112:113] op_sel:[1,0]
	v_mov_b32_e32 v115, v113
	v_pk_mov_b32 v[112:113], v[118:119], v[116:117] op_sel:[1,0]
	v_mov_b32_e32 v119, v117
	s_waitcnt vmcnt(6)
	v_mul_f32_e32 v104, v55, v55
	v_mul_f32_e32 v120, v57, v57
	v_pk_add_f32 v[114:115], v[138:139], v[114:115]
	v_pk_add_f32 v[112:113], v[112:113], v[118:119]
	v_mul_f32_e32 v146, v50, v50
	v_mul_f32_e32 v147, v51, v51
	v_mul_f32_e32 v148, v52, v52
	v_mul_f32_e32 v149, v53, v53
	v_pk_fma_f32 v[104:105], v[54:55], v[54:55], v[104:105] op_sel_hi:[1,1,0]
	v_pk_fma_f32 v[106:107], v[56:57], v[56:57], v[120:121] op_sel_hi:[1,1,0]
	v_pk_add_f32 v[102:103], v[114:115], v[114:115] op_sel:[0,1] op_sel_hi:[1,0]
	v_pk_add_f32 v[112:113], v[112:113], v[112:113] op_sel:[0,1] op_sel_hi:[1,0]
	v_mov_b32_e32 v105, v148
	v_mov_b32_e32 v107, v149
	v_mov_b32_e32 v103, v146
	v_mov_b32_e32 v113, v147
	v_pk_add_f32 v[104:105], v[104:105], v[106:107]
	v_pk_add_f32 v[102:103], v[102:103], v[112:113]
	v_mul_f32_e32 v142, v18, v18
	v_pk_add_f32 v[102:103], v[102:103], v[104:105]
	v_mul_f32_e32 v143, v19, v19
	v_pk_add_f32 v[102:103], v[102:103], v[102:103] op_sel:[0,1] op_sel_hi:[1,0]
	v_mul_f32_e32 v108, v27, v27
	v_mov_b32_e32 v103, v111
	v_pk_add_f32 v[98:99], v[102:103], v[98:99]
	v_mul_f32_e32 v110, v29, v29
	v_pk_add_f32 v[98:99], v[98:99], v[100:101]
	v_mov_b32_e32 v97, v143
	v_pk_add_f32 v[98:99], v[98:99], v[98:99] op_sel:[0,1] op_sel_hi:[1,0]
	v_mul_f32_e32 v144, v20, v20
	v_mov_b32_e32 v99, v142
	v_mul_f32_e32 v145, v21, v21
	v_pk_fma_f32 v[108:109], v[26:27], v[26:27], v[108:109] op_sel_hi:[1,1,0]
	v_pk_add_f32 v[96:97], v[98:99], v[96:97]
	v_pk_fma_f32 v[98:99], v[28:29], v[28:29], v[110:111] op_sel_hi:[1,1,0]
	v_mov_b32_e32 v109, v144
	v_mov_b32_e32 v99, v145
	v_pk_add_f32 v[98:99], v[108:109], v[98:99]
	s_waitcnt vmcnt(5)
	v_pk_mul_f32 v[100:101], v[22:23], v[22:23]
	v_pk_add_f32 v[96:97], v[96:97], v[98:99]
	v_pk_mul_f32 v[98:99], v[24:25], v[24:25]
	v_pk_add_f32 v[96:97], v[96:97], v[96:97] op_sel:[0,1] op_sel_hi:[1,0]
	v_pk_mov_b32 v[102:103], v[100:101], v[98:99] op_sel:[1,0]
	v_mov_b32_e32 v101, v99
	v_pk_add_f32 v[98:99], v[102:103], v[100:101]
	s_waitcnt vmcnt(4)
	v_mul_f32_e32 v100, v10, v10
	v_mul_f32_e32 v101, v11, v11
	v_pk_add_f32 v[98:99], v[98:99], v[98:99] op_sel:[0,1] op_sel_hi:[1,0]
	v_mov_b32_e32 v97, v100
	v_mov_b32_e32 v99, v101
	v_pk_add_f32 v[96:97], v[96:97], v[98:99]
	s_waitcnt vmcnt(0)
; __device__ __forceinline__ unsigned cvt_pk_bf16(float lo, float hi) { unsigned r; asm volatile("v_cvt_pk_bf16_f32 %0, %1, %2" : "=v"(r) : "v"(lo), "v"(hi)); return r; }
; #define LAS __attribute__((address_space(3)))
; __device__ __forceinline__ float dot4(f32x4 a) { return (a.x * a.x + a.y * a.y) + (a.z * a.z + a.w * a.w); }
; __device__ __forceinline__ float wave_sum(float v) {
; #pragma unroll
;     for (int o = 1; o < 64; o <<= 1) v += __shfl_xor(v, o);
;     return v;
; }
; __global__ void __launch_bounds__(NWAVES * 64, 2) fwd_kernel(Args args) {
;     ...
;                 f32x4 v[16]; float s = 0.f;
; #pragma unroll
;                 for (int j = 0; j < 16; ++j) { v[j] = xr[64 * j]; s += dot4(v[j]); }
;                 const float rstd = 1.0f / sqrtf(wave_sum(s) * (1.0f / D) + RMS_EPS);
;                 v2u* o8 = (v2u*)(U + row * D) + lane;
; #pragma unroll
;                 for (int j = 0; j < 16; ++j) { const f32x4 a = ((const LAS f32x4*)cA)[lane + 64 * j], bb = ((const LAS f32x4*)cB)[lane + 64 * j]; v[j] = v[j] * rstd * a + bb;
;                     v2u w; w.x = cvt_pk_bf16(v[j].x, v[j].y); w.y = cvt_pk_bf16(v[j].z, v[j].w); o8[64 * j] = w; }
	v_mul_f32_e32 v98, v39, v39
	v_mul_f32_e32 v100, v41, v41
	v_mul_f32_e32 v102, v12, v12
	v_mul_f32_e32 v103, v13, v13
	v_pk_fma_f32 v[98:99], v[38:39], v[38:39], v[98:99] op_sel_hi:[1,1,0]
	v_pk_fma_f32 v[100:101], v[40:41], v[40:41], v[100:101] op_sel_hi:[1,1,0]
	v_mov_b32_e32 v99, v102
	v_mov_b32_e32 v101, v103
	v_pk_add_f32 v[98:99], v[98:99], v[100:101]
	v_pk_mul_f32 v[100:101], v[14:15], v[14:15]
	v_pk_add_f32 v[96:97], v[96:97], v[98:99]
	v_pk_mul_f32 v[98:99], v[16:17], v[16:17]
	v_pk_add_f32 v[96:97], v[96:97], v[96:97] op_sel:[0,1] op_sel_hi:[1,0]
	v_pk_mov_b32 v[102:103], v[100:101], v[98:99] op_sel:[1,0]
	v_mov_b32_e32 v101, v99
	v_pk_add_f32 v[98:99], v[102:103], v[100:101]
	v_mul_f32_e32 v100, v2, v2
	v_mul_f32_e32 v101, v3, v3
	v_pk_add_f32 v[98:99], v[98:99], v[98:99] op_sel:[0,1] op_sel_hi:[1,0]
	v_mov_b32_e32 v97, v100
	v_mov_b32_e32 v99, v101
	v_pk_add_f32 v[96:97], v[96:97], v[98:99]
	v_mul_f32_e32 v98, v7, v7
	v_mul_f32_e32 v100, v9, v9
	v_mul_f32_e32 v102, v4, v4
	v_mul_f32_e32 v103, v5, v5
	v_pk_fma_f32 v[98:99], v[6:7], v[6:7], v[98:99] op_sel_hi:[1,1,0]
	v_pk_fma_f32 v[100:101], v[8:9], v[8:9], v[100:101] op_sel_hi:[1,1,0]
	v_mov_b32_e32 v99, v102
	v_mov_b32_e32 v101, v103
	v_pk_add_f32 v[98:99], v[98:99], v[100:101]
	s_nop 0
	v_pk_add_f32 v[96:97], v[96:97], v[98:99]
	s_nop 0
	v_add_f32_e32 v96, v96, v97
	ds_bpermute_b32 v97, v1, v96
	s_waitcnt lgkmcnt(0)
	v_add_f32_e32 v96, v96, v97
	ds_bpermute_b32 v97, v121, v96
	s_waitcnt lgkmcnt(0)
	v_add_f32_e32 v96, v96, v97
	ds_bpermute_b32 v97, v122, v96
	s_waitcnt lgkmcnt(0)
	v_add_f32_e32 v96, v96, v97
	ds_bpermute_b32 v97, v123, v96
	s_waitcnt lgkmcnt(0)
	v_add_f32_e32 v96, v96, v97
	ds_bpermute_b32 v97, v124, v96
	s_waitcnt lgkmcnt(0)
	v_add_f32_e32 v96, v96, v97
	ds_bpermute_b32 v97, v125, v96
	s_waitcnt lgkmcnt(0)
	v_add_f32_e32 v96, v96, v97
	v_fmamk_f32 v96, v96, 0x39800000, v133
	v_mul_f32_e32 v97, 0x4f800000, v96
	v_cmp_gt_f32_e32 vcc, s20, v96
	s_nop 1
	v_cndmask_b32_e32 v96, v96, v97, vcc
	v_sqrt_f32_e32 v97, v96
	s_nop 0
	v_add_u32_e32 v98, -1, v97
	v_fma_f32 v99, -v98, v97, v96
	v_cmp_ge_f32_e64 s[0:1], 0, v99
	v_add_u32_e32 v99, 1, v97
	s_nop 0
	v_cndmask_b32_e64 v98, v97, v98, s[0:1]
	v_fma_f32 v97, -v99, v97, v96
	v_cmp_lt_f32_e64 s[0:1], 0, v97
	s_nop 1
	v_cndmask_b32_e64 v97, v98, v99, s[0:1]
	v_mul_f32_e32 v98, 0x37800000, v97
	v_cndmask_b32_e32 v97, v97, v98, vcc
	v_cmp_class_f32_e32 vcc, v96, v134
	s_nop 1
	v_cndmask_b32_e32 v104, v97, v96, vcc
	v_div_scale_f32 v96, s[0:1], v104, v104, 1.0
	v_rcp_f32_e32 v97, v96
	s_nop 0
	v_fma_f32 v98, -v96, v97, 1.0
	v_fmac_f32_e32 v97, v98, v97
	v_div_scale_f32 v98, vcc, 1.0, v104, 1.0
	v_mul_f32_e32 v99, v98, v97
	v_fma_f32 v100, -v96, v99, v98
	v_fmac_f32_e32 v99, v100, v97
	v_fma_f32 v96, -v96, v99, v98
	v_div_fmas_f32 v105, v96, v97, v99
	ds_read_b128 v[96:99], v126
	ds_read_b128 v[100:103], v126 offset:16384
	v_div_fixup_f32 v120, v105, v104, 1.0
	v_pk_mul_f32 v[62:63], v[120:121], v[62:63] op_sel_hi:[0,1]
	v_pk_mul_f32 v[64:65], v[120:121], v[64:65] op_sel_hi:[0,1]
	v_lshl_add_u64 v[104:105], s[36:37], 0, v[94:95]
	s_waitcnt lgkmcnt(0)
	v_pk_fma_f32 v[118:119], v[98:99], v[64:65], v[102:103]
	v_pk_fma_f32 v[116:117], v[96:97], v[62:63], v[100:101]
	v_add_co_u32_e32 v62, vcc, s22, v104
	v_cvt_pk_bf16_f32 v64, v116, v117
	v_cvt_pk_bf16_f32 v65, v118, v119
	ds_read_b128 v[96:99], v126 offset:1024
	ds_read_b128 v[100:103], v126 offset:17408
	v_addc_co_u32_e32 v63, vcc, 0, v105, vcc
	v_pk_mul_f32 v[58:59], v[120:121], v[58:59] op_sel_hi:[0,1]
	v_pk_mul_f32 v[60:61], v[120:121], v[60:61] op_sel_hi:[0,1]
	global_store_dwordx2 v[62:63], v[64:65], off offset:-4096
	s_waitcnt lgkmcnt(0)
	v_pk_fma_f32 v[114:115], v[98:99], v[60:61], v[102:103]
	v_pk_fma_f32 v[112:113], v[96:97], v[58:59], v[100:101]
	v_add_co_u32_e32 v136, vcc, s21, v104
	v_cvt_pk_bf16_f32 v64, v112, v113
	v_cvt_pk_bf16_f32 v65, v114, v115
	ds_read_b128 v[58:61], v126 offset:2048
	ds_read_b128 v[96:99], v126 offset:18432
	v_addc_co_u32_e32 v137, vcc, 0, v105, vcc
	v_pk_mul_f32 v[54:55], v[120:121], v[54:55] op_sel_hi:[0,1]
	v_pk_mul_f32 v[56:57], v[120:121], v[56:57] op_sel_hi:[0,1]
	global_store_dwordx2 v[136:137], v[64:65], off offset:512
	s_waitcnt lgkmcnt(0)
	v_pk_fma_f32 v[110:111], v[60:61], v[56:57], v[98:99]
	v_pk_fma_f32 v[108:109], v[58:59], v[54:55], v[96:97]
	v_pk_mul_f32 v[50:51], v[120:121], v[50:51] op_sel_hi:[0,1]
	v_cvt_pk_bf16_f32 v64, v108, v109
	v_cvt_pk_bf16_f32 v65, v110, v111
	ds_read_b128 v[54:57], v126 offset:3072
	ds_read_b128 v[58:61], v126 offset:19456
	v_pk_mul_f32 v[52:53], v[120:121], v[52:53] op_sel_hi:[0,1]
	global_store_dwordx2 v[136:137], v[64:65], off offset:1024
	v_pk_mul_f32 v[46:47], v[120:121], v[46:47] op_sel_hi:[0,1]
	v_pk_mul_f32 v[48:49], v[120:121], v[48:49] op_sel_hi:[0,1]
	s_waitcnt lgkmcnt(0)
	v_pk_fma_f32 v[106:107], v[56:57], v[52:53], v[60:61]
	v_pk_fma_f32 v[104:105], v[54:55], v[50:51], v[58:59]
	v_pk_mul_f32 v[42:43], v[120:121], v[42:43] op_sel_hi:[0,1]
	v_cvt_pk_bf16_f32 v58, v104, v105
	v_cvt_pk_bf16_f32 v59, v106, v107
	ds_read_b128 v[50:53], v126 offset:4096
	ds_read_b128 v[54:57], v126 offset:20480
	global_store_dwordx2 v[136:137], v[58:59], off offset:1536
	v_pk_mul_f32 v[44:45], v[120:121], v[44:45] op_sel_hi:[0,1]
	v_pk_mul_f32 v[30:31], v[120:121], v[30:31] op_sel_hi:[0,1]
	v_pk_mul_f32 v[32:33], v[120:121], v[32:33] op_sel_hi:[0,1]
	s_waitcnt lgkmcnt(0)
; __device__ __forceinline__ unsigned cvt_pk_bf16(float lo, float hi) { unsigned r; asm volatile("v_cvt_pk_bf16_f32 %0, %1, %2" : "=v"(r) : "v"(lo), "v"(hi)); return r; }
; #define LAS __attribute__((address_space(3)))
; __global__ void __launch_bounds__(NWAVES * 64, 2) fwd_kernel(Args args) {
;     ...
;                 v2u* o8 = (v2u*)(U + row * D) + lane;
; #pragma unroll
;                 for (int j = 0; j < 16; ++j) { const f32x4 a = ((const LAS f32x4*)cA)[lane + 64 * j], bb = ((const LAS f32x4*)cB)[lane + 64 * j]; v[j] = v[j] * rstd * a + bb;
;                     v2u w; w.x = cvt_pk_bf16(v[j].x, v[j].y); w.y = cvt_pk_bf16(v[j].z, v[j].w); o8[64 * j] = w; }
	v_pk_fma_f32 v[102:103], v[52:53], v[48:49], v[56:57]
	v_pk_fma_f32 v[100:101], v[50:51], v[46:47], v[54:55]
	v_pk_mul_f32 v[34:35], v[120:121], v[34:35] op_sel_hi:[0,1]
	v_cvt_pk_bf16_f32 v50, v100, v101
	v_cvt_pk_bf16_f32 v51, v102, v103
	ds_read_b128 v[46:49], v126 offset:5120
	ds_read_b128 v[52:55], v126 offset:21504
	global_store_dwordx2 v[136:137], v[50:51], off offset:2048
	v_pk_mul_f32 v[36:37], v[120:121], v[36:37] op_sel_hi:[0,1]
	v_pk_mul_f32 v[26:27], v[120:121], v[26:27] op_sel_hi:[0,1]
	v_pk_mul_f32 v[28:29], v[120:121], v[28:29] op_sel_hi:[0,1]
	s_waitcnt lgkmcnt(0)
	v_pk_fma_f32 v[50:51], v[48:49], v[44:45], v[54:55]
	v_pk_fma_f32 v[48:49], v[46:47], v[42:43], v[52:53]
	v_pk_mul_f32 v[18:19], v[120:121], v[18:19] op_sel_hi:[0,1]
	v_cvt_pk_bf16_f32 v46, v48, v49
	v_cvt_pk_bf16_f32 v47, v50, v51
	ds_read_b128 v[42:45], v126 offset:6144
	ds_read_b128 v[52:55], v126 offset:22528
	global_store_dwordx2 v[136:137], v[46:47], off offset:2560
	v_pk_mul_f32 v[20:21], v[120:121], v[20:21] op_sel_hi:[0,1]
	v_pk_mul_f32 v[22:23], v[120:121], v[22:23] op_sel_hi:[0,1]
	v_pk_mul_f32 v[24:25], v[120:121], v[24:25] op_sel_hi:[0,1]
	s_waitcnt lgkmcnt(0)
	v_pk_fma_f32 v[64:65], v[44:45], v[32:33], v[54:55]
	v_pk_fma_f32 v[60:61], v[42:43], v[30:31], v[52:53]
	v_pk_mul_f32 v[10:11], v[120:121], v[10:11] op_sel_hi:[0,1]
	v_cvt_pk_bf16_f32 v46, v60, v61
	v_cvt_pk_bf16_f32 v47, v64, v65
	ds_read_b128 v[30:33], v126 offset:7168
	ds_read_b128 v[42:45], v126 offset:23552
	global_store_dwordx2 v[136:137], v[46:47], off offset:3072
	v_pk_mul_f32 v[12:13], v[120:121], v[12:13] op_sel_hi:[0,1]
	v_pk_mul_f32 v[14:15], v[120:121], v[14:15] op_sel_hi:[0,1]
	v_pk_mul_f32 v[16:17], v[120:121], v[16:17] op_sel_hi:[0,1]
	s_waitcnt lgkmcnt(0)
	v_pk_fma_f32 v[98:99], v[32:33], v[36:37], v[44:45]
	v_pk_fma_f32 v[96:97], v[30:31], v[34:35], v[42:43]
	v_pk_mul_f32 v[6:7], v[120:121], v[6:7] op_sel_hi:[0,1]
	v_cvt_pk_bf16_f32 v42, v96, v97
	v_cvt_pk_bf16_f32 v43, v98, v99
	ds_read_b128 v[30:33], v126 offset:8192
	ds_read_b128 v[34:37], v126 offset:24576
	global_store_dwordx2 v[136:137], v[42:43], off offset:3584
	v_pk_mul_f32 v[8:9], v[120:121], v[8:9] op_sel_hi:[0,1]
	s_waitcnt lgkmcnt(0)
	v_pk_fma_f32 v[58:59], v[32:33], v[28:29], v[36:37]
	v_pk_fma_f32 v[56:57], v[30:31], v[26:27], v[34:35]
	s_nop 0
	v_cvt_pk_bf16_f32 v34, v56, v57
	v_cvt_pk_bf16_f32 v35, v58, v59
	ds_read_b128 v[26:29], v126 offset:9216
	ds_read_b128 v[30:33], v126 offset:25600
	global_store_dwordx2 v[62:63], v[34:35], off
	s_waitcnt lgkmcnt(0)
	v_pk_fma_f32 v[54:55], v[28:29], v[20:21], v[32:33]
	v_pk_fma_f32 v[52:53], v[26:27], v[18:19], v[30:31]
	s_nop 0
	v_cvt_pk_bf16_f32 v30, v52, v53
	v_cvt_pk_bf16_f32 v31, v54, v55
	ds_read_b128 v[18:21], v126 offset:10240
	ds_read_b128 v[26:29], v126 offset:26624
	global_store_dwordx2 v[62:63], v[30:31], off offset:512
	s_waitcnt lgkmcnt(0)
	v_pk_fma_f32 v[46:47], v[20:21], v[24:25], v[28:29]
	v_pk_fma_f32 v[44:45], v[18:19], v[22:23], v[26:27]
	v_pk_mul_f32 v[28:29], v[120:121], v[40:41] op_sel_hi:[0,1]
	v_cvt_pk_bf16_f32 v26, v44, v45
	v_cvt_pk_bf16_f32 v27, v46, v47
	ds_read_b128 v[18:21], v126 offset:11264
	ds_read_b128 v[22:25], v126 offset:27648
	global_store_dwordx2 v[62:63], v[26:27], off offset:1024
	v_pk_mul_f32 v[26:27], v[120:121], v[38:39] op_sel_hi:[0,1]
	s_waitcnt lgkmcnt(0)
	v_pk_fma_f32 v[38:39], v[20:21], v[28:29], v[24:25]
	v_pk_fma_f32 v[36:37], v[18:19], v[26:27], v[22:23]
	s_nop 0
	v_cvt_pk_bf16_f32 v26, v36, v37
	v_cvt_pk_bf16_f32 v27, v38, v39
	ds_read_b128 v[18:21], v126 offset:12288
	ds_read_b128 v[22:25], v126 offset:28672
	global_store_dwordx2 v[62:63], v[26:27], off offset:1536
	s_waitcnt lgkmcnt(0)
	v_pk_fma_f32 v[30:31], v[20:21], v[12:13], v[24:25]
	v_pk_fma_f32 v[28:29], v[18:19], v[10:11], v[22:23]
	s_nop 0
	v_cvt_pk_bf16_f32 v22, v28, v29
	v_cvt_pk_bf16_f32 v23, v30, v31
	ds_read_b128 v[10:13], v126 offset:13312
	ds_read_b128 v[18:21], v126 offset:29696
	global_store_dwordx2 v[62:63], v[22:23], off offset:2048
	s_waitcnt lgkmcnt(0)
	v_pk_fma_f32 v[22:23], v[12:13], v[16:17], v[20:21]
	v_pk_fma_f32 v[20:21], v[10:11], v[14:15], v[18:19]
	s_nop 0
	v_cvt_pk_bf16_f32 v18, v20, v21
	v_cvt_pk_bf16_f32 v19, v22, v23
	ds_read_b128 v[10:13], v126 offset:14336
	ds_read_b128 v[14:17], v126 offset:30720
	global_store_dwordx2 v[62:63], v[18:19], off offset:2560
	s_waitcnt lgkmcnt(0)
	v_pk_fma_f32 v[18:19], v[12:13], v[8:9], v[16:17]
	v_pk_fma_f32 v[16:17], v[10:11], v[6:7], v[14:15]
	s_nop 0
	v_cvt_pk_bf16_f32 v14, v16, v17
	v_cvt_pk_bf16_f32 v15, v18, v19
	ds_read_b128 v[6:9], v127
	ds_read_b128 v[10:13], v127 offset:16384
	global_store_dwordx2 v[62:63], v[14:15], off offset:3072
	v_pk_mul_f32 v[14:15], v[120:121], v[2:3] op_sel_hi:[0,1]
	v_pk_mul_f32 v[2:3], v[120:121], v[4:5] op_sel_hi:[0,1]
	s_waitcnt lgkmcnt(0)
; __device__ __forceinline__ float xlane1(float t) { return dpp_mov<0xB1, 0xF, true>(0.f, t); }
; __device__ __forceinline__ float xlane2(float t) { return dpp_mov<0x4E, 0xF, true>(0.f, t); }
; __device__ __forceinline__ float xlane4(float t) { const float r = dpp_mov<0x104, 0x5, false>(t, t); return dpp_mov<0x114, 0xA, false>(r, t); }
; __device__ __forceinline__ float xlane8(float t) { return dpp_mov<0x128, 0xF, true>(0.f, t); }
; __device__ __forceinline__ f32x4 rot64(f32x4 t, const RotSigns sg) {
;     { const float p0 = t.x + t.y, p1 = t.x - t.y, p2 = t.z + t.w, p3 = t.z - t.w; t = (f32x4){p0 + p2, p1 + p3, p0 - p2, p1 - p3}; }
;     t = (f32x4){__builtin_fmaf(sg.s1, t.x, xlane1(t.x)), __builtin_fmaf(sg.s1, t.y, xlane1(t.y)), __builtin_fmaf(sg.s1, t.z, xlane1(t.z)), __builtin_fmaf(sg.s1, t.w, xlane1(t.w))};
;     t = (f32x4){__builtin_fmaf(sg.s2, t.x, xlane2(t.x)), __builtin_fmaf(sg.s2, t.y, xlane2(t.y)), __builtin_fmaf(sg.s2, t.z, xlane2(t.z)), __builtin_fmaf(sg.s2, t.w, xlane2(t.w))};
;     t = (f32x4){__builtin_fmaf(sg.s4, t.x, xlane4(t.x)), __builtin_fmaf(sg.s4, t.y, xlane4(t.y)), __builtin_fmaf(sg.s4, t.z, xlane4(t.z)), __builtin_fmaf(sg.s4, t.w, xlane4(t.w))};
;     t = (f32x4){__builtin_fmaf(sg.s8, t.x, xlane8(t.x)), __builtin_fmaf(sg.s8, t.y, xlane8(t.y)), __builtin_fmaf(sg.s8, t.z, xlane8(t.z)), __builtin_fmaf(sg.s8, t.w, xlane8(t.w))};
;     return t * 0.125f;
; }
; __device__ __forceinline__ unsigned pack_q8m(float a, float b, float c, float d, float inv) {
;     const unsigned ua = __float_as_uint(__builtin_fmaf(a, inv, 12582912.0f)), ub = __float_as_uint(__builtin_fmaf(b, inv, 12582912.0f));
;     const unsigned uc = __float_as_uint(__builtin_fmaf(c, inv, 12582912.0f)), ud = __float_as_uint(__builtin_fmaf(d, inv, 12582912.0f));
;     return __builtin_amdgcn_perm(__builtin_amdgcn_perm(ud, uc, 0x0c0c0400u), __builtin_amdgcn_perm(ub, ua, 0x0c0c0400u), 0x05040100u);
; }
; __device__ __forceinline__ void rotq_row(f32x4 (&v)[16], unsigned* q8row, float* rsp, int lane) {
;     float am = 0.f; const RotSigns sg = rot_signs(lane);
; #pragma unroll
;     for (int j = 0; j < 16; ++j) { v[j] = rot64(v[j], sg);
;         am = fmaxf(fmaxf(am, fmaxf(fabsf(v[j].x), fabsf(v[j].y))), fmaxf(fabsf(v[j].z), fabsf(v[j].w))); }
	v_pk_fma_f32 v[2:3], v[8:9], v[2:3], v[12:13]
	v_pk_fma_f32 v[10:11], v[6:7], v[14:15], v[10:11]
	v_mov_b32_e32 v6, v118
	v_mov_b32_e32 v7, v116
	v_mov_b32_e32 v8, v119
	v_mov_b32_e32 v9, v117
	v_pk_add_f32 v[12:13], v[6:7], v[8:9]
	v_pk_add_f32 v[6:7], v[6:7], v[8:9] neg_lo:[0,1] neg_hi:[0,1]
	v_pk_mov_b32 v[8:9], v[116:117], v[118:119] op_sel:[1,0]
	v_mov_b32_e32 v117, v119
	v_pk_add_f32 v[14:15], v[8:9], v[116:117]
	v_pk_add_f32 v[8:9], v[8:9], v[116:117] neg_lo:[0,1] neg_hi:[0,1]
	v_mov_b32_e32 v13, v7
	v_mov_b32_e32 v15, v9
	v_pk_add_f32 v[24:25], v[14:15], v[12:13]
	v_mov_b32_e32 v15, v7
	v_mov_b32_e32 v13, v9
	v_pk_add_f32 v[6:7], v[14:15], v[12:13] neg_lo:[0,1] neg_hi:[0,1]
	v_mov_b32_dpp v26, v24 quad_perm:[1,0,3,2] row_mask:0xf bank_mask:0xf bound_ctrl:1
	v_mov_b32_dpp v27, v25 quad_perm:[1,0,3,2] row_mask:0xf bank_mask:0xf bound_ctrl:1
	v_mov_b32_dpp v8, v6 quad_perm:[1,0,3,2] row_mask:0xf bank_mask:0xf bound_ctrl:1
	v_mov_b32_dpp v9, v7 quad_perm:[1,0,3,2] row_mask:0xf bank_mask:0xf bound_ctrl:1
	v_pk_fma_f32 v[24:25], v[72:73], v[24:25], v[26:27]
	v_pk_fma_f32 v[6:7], v[72:73], v[6:7], v[8:9]
	v_mov_b32_e32 v14, v115
	v_mov_b32_dpp v26, v24 quad_perm:[2,3,0,1] row_mask:0xf bank_mask:0xf bound_ctrl:1
	v_mov_b32_dpp v27, v25 quad_perm:[2,3,0,1] row_mask:0xf bank_mask:0xf bound_ctrl:1
	v_mov_b32_dpp v8, v6 quad_perm:[2,3,0,1] row_mask:0xf bank_mask:0xf bound_ctrl:1
	v_mov_b32_dpp v9, v7 quad_perm:[2,3,0,1] row_mask:0xf bank_mask:0xf bound_ctrl:1
	v_pk_fma_f32 v[24:25], v[70:71], v[24:25], v[26:27]
	v_pk_fma_f32 v[6:7], v[70:71], v[6:7], v[8:9]
	v_mov_b32_e32 v26, v24
	v_mov_b32_e32 v27, v25
	v_mov_b32_e32 v8, v6
	v_mov_b32_e32 v9, v7
	v_mov_b32_dpp v26, v26 row_shl:4 row_mask:0xf bank_mask:0x5
	v_mov_b32_dpp v27, v27 row_shl:4 row_mask:0xf bank_mask:0x5
	v_mov_b32_dpp v8, v8 row_shl:4 row_mask:0xf bank_mask:0x5
	v_mov_b32_dpp v9, v9 row_shl:4 row_mask:0xf bank_mask:0x5
	v_mov_b32_dpp v26, v24 row_shr:4 row_mask:0xf bank_mask:0xa
	v_mov_b32_dpp v27, v25 row_shr:4 row_mask:0xf bank_mask:0xa
	v_mov_b32_dpp v8, v6 row_shr:4 row_mask:0xf bank_mask:0xa
	v_mov_b32_dpp v9, v7 row_shr:4 row_mask:0xf bank_mask:0xa
	v_pk_fma_f32 v[24:25], v[68:69], v[24:25], v[26:27]
	v_pk_fma_f32 v[6:7], v[68:69], v[6:7], v[8:9]
	v_mov_b32_e32 v15, v113
	v_mov_b32_dpp v26, v24 row_ror:8 row_mask:0xf bank_mask:0xf bound_ctrl:1
	v_mov_b32_dpp v27, v25 row_ror:8 row_mask:0xf bank_mask:0xf bound_ctrl:1
	v_mov_b32_dpp v8, v6 row_ror:8 row_mask:0xf bank_mask:0xf bound_ctrl:1
	v_mov_b32_dpp v9, v7 row_ror:8 row_mask:0xf bank_mask:0xf bound_ctrl:1
	v_pk_fma_f32 v[12:13], v[66:67], v[24:25], v[26:27]
	v_pk_fma_f32 v[6:7], v[88:89], v[6:7], v[8:9]
	v_pk_mul_f32 v[8:9], v[12:13], s[40:41] op_sel_hi:[1,0]
	v_pk_mul_f32 v[6:7], v[6:7], s[40:41] op_sel_hi:[1,0]
	v_max_f32_e64 v5, |v8|, |v9|
	v_max_f32_e64 v12, |v6|, |v7|
	v_max3_f32 v5, v5, 0, v12
	v_mov_b32_e32 v12, v114
	v_mov_b32_e32 v13, v112
	v_pk_add_f32 v[24:25], v[12:13], v[14:15]
	v_pk_add_f32 v[12:13], v[12:13], v[14:15] neg_lo:[0,1] neg_hi:[0,1]
	v_pk_mov_b32 v[14:15], v[112:113], v[114:115] op_sel:[1,0]
	v_mov_b32_e32 v113, v115
	v_pk_add_f32 v[26:27], v[14:15], v[112:113]
	v_pk_add_f32 v[14:15], v[14:15], v[112:113] neg_lo:[0,1] neg_hi:[0,1]
	v_mov_b32_e32 v25, v13
	v_mov_b32_e32 v27, v15
	v_pk_add_f32 v[32:33], v[26:27], v[24:25]
	v_mov_b32_e32 v27, v13
	v_mov_b32_e32 v25, v15
	v_pk_add_f32 v[12:13], v[26:27], v[24:25] neg_lo:[0,1] neg_hi:[0,1]
	v_mov_b32_dpp v34, v32 quad_perm:[1,0,3,2] row_mask:0xf bank_mask:0xf bound_ctrl:1
	v_mov_b32_dpp v35, v33 quad_perm:[1,0,3,2] row_mask:0xf bank_mask:0xf bound_ctrl:1
	v_mov_b32_dpp v14, v12 quad_perm:[1,0,3,2] row_mask:0xf bank_mask:0xf bound_ctrl:1
	v_mov_b32_dpp v15, v13 quad_perm:[1,0,3,2] row_mask:0xf bank_mask:0xf bound_ctrl:1
	v_pk_fma_f32 v[32:33], v[72:73], v[32:33], v[34:35]
	v_pk_fma_f32 v[12:13], v[72:73], v[12:13], v[14:15]
	v_mov_b32_e32 v26, v111
	v_mov_b32_dpp v34, v32 quad_perm:[2,3,0,1] row_mask:0xf bank_mask:0xf bound_ctrl:1
	v_mov_b32_dpp v35, v33 quad_perm:[2,3,0,1] row_mask:0xf bank_mask:0xf bound_ctrl:1
	v_mov_b32_dpp v14, v12 quad_perm:[2,3,0,1] row_mask:0xf bank_mask:0xf bound_ctrl:1
	v_mov_b32_dpp v15, v13 quad_perm:[2,3,0,1] row_mask:0xf bank_mask:0xf bound_ctrl:1
	v_pk_fma_f32 v[32:33], v[70:71], v[32:33], v[34:35]
	v_pk_fma_f32 v[12:13], v[70:71], v[12:13], v[14:15]
	v_mov_b32_e32 v34, v32
	v_mov_b32_e32 v35, v33
	v_mov_b32_e32 v14, v12
	v_mov_b32_e32 v15, v13
	v_mov_b32_dpp v34, v34 row_shl:4 row_mask:0xf bank_mask:0x5
	v_mov_b32_dpp v35, v35 row_shl:4 row_mask:0xf bank_mask:0x5
	v_mov_b32_dpp v14, v14 row_shl:4 row_mask:0xf bank_mask:0x5
	v_mov_b32_dpp v15, v15 row_shl:4 row_mask:0xf bank_mask:0x5
	v_mov_b32_dpp v34, v32 row_shr:4 row_mask:0xf bank_mask:0xa
	v_mov_b32_dpp v35, v33 row_shr:4 row_mask:0xf bank_mask:0xa
	v_mov_b32_dpp v14, v12 row_shr:4 row_mask:0xf bank_mask:0xa
	v_mov_b32_dpp v15, v13 row_shr:4 row_mask:0xf bank_mask:0xa
	v_pk_fma_f32 v[32:33], v[68:69], v[32:33], v[34:35]
	v_pk_fma_f32 v[12:13], v[68:69], v[12:13], v[14:15]
	v_mov_b32_e32 v27, v109
	v_mov_b32_dpp v34, v32 row_ror:8 row_mask:0xf bank_mask:0xf bound_ctrl:1
	v_mov_b32_dpp v35, v33 row_ror:8 row_mask:0xf bank_mask:0xf bound_ctrl:1
	v_mov_b32_dpp v14, v12 row_ror:8 row_mask:0xf bank_mask:0xf bound_ctrl:1
	v_mov_b32_dpp v15, v13 row_ror:8 row_mask:0xf bank_mask:0xf bound_ctrl:1
	v_pk_fma_f32 v[24:25], v[66:67], v[32:33], v[34:35]
	v_pk_fma_f32 v[12:13], v[88:89], v[12:13], v[14:15]
	v_pk_mul_f32 v[14:15], v[24:25], s[40:41] op_sel_hi:[1,0]
	v_pk_mul_f32 v[12:13], v[12:13], s[40:41] op_sel_hi:[1,0]
	v_max_f32_e64 v24, |v14|, |v15|
	v_max_f32_e64 v25, |v12|, |v13|
; __device__ __forceinline__ float xlane1(float t) { return dpp_mov<0xB1, 0xF, true>(0.f, t); }
; __device__ __forceinline__ float xlane2(float t) { return dpp_mov<0x4E, 0xF, true>(0.f, t); }
; __device__ __forceinline__ float xlane4(float t) { const float r = dpp_mov<0x104, 0x5, false>(t, t); return dpp_mov<0x114, 0xA, false>(r, t); }
; __device__ __forceinline__ float xlane8(float t) { return dpp_mov<0x128, 0xF, true>(0.f, t); }
; __device__ __forceinline__ f32x4 rot64(f32x4 t, const RotSigns sg) {
;     { const float p0 = t.x + t.y, p1 = t.x - t.y, p2 = t.z + t.w, p3 = t.z - t.w; t = (f32x4){p0 + p2, p1 + p3, p0 - p2, p1 - p3}; }
;     t = (f32x4){__builtin_fmaf(sg.s1, t.x, xlane1(t.x)), __builtin_fmaf(sg.s1, t.y, xlane1(t.y)), __builtin_fmaf(sg.s1, t.z, xlane1(t.z)), __builtin_fmaf(sg.s1, t.w, xlane1(t.w))};
;     t = (f32x4){__builtin_fmaf(sg.s2, t.x, xlane2(t.x)), __builtin_fmaf(sg.s2, t.y, xlane2(t.y)), __builtin_fmaf(sg.s2, t.z, xlane2(t.z)), __builtin_fmaf(sg.s2, t.w, xlane2(t.w))};
;     t = (f32x4){__builtin_fmaf(sg.s4, t.x, xlane4(t.x)), __builtin_fmaf(sg.s4, t.y, xlane4(t.y)), __builtin_fmaf(sg.s4, t.z, xlane4(t.z)), __builtin_fmaf(sg.s4, t.w, xlane4(t.w))};
;     t = (f32x4){__builtin_fmaf(sg.s8, t.x, xlane8(t.x)), __builtin_fmaf(sg.s8, t.y, xlane8(t.y)), __builtin_fmaf(sg.s8, t.z, xlane8(t.z)), __builtin_fmaf(sg.s8, t.w, xlane8(t.w))};
;     return t * 0.125f;
; }
; __device__ __forceinline__ unsigned pack_q8m(float a, float b, float c, float d, float inv) {
;     const unsigned ua = __float_as_uint(__builtin_fmaf(a, inv, 12582912.0f)), ub = __float_as_uint(__builtin_fmaf(b, inv, 12582912.0f));
;     const unsigned uc = __float_as_uint(__builtin_fmaf(c, inv, 12582912.0f)), ud = __float_as_uint(__builtin_fmaf(d, inv, 12582912.0f));
;     return __builtin_amdgcn_perm(__builtin_amdgcn_perm(ud, uc, 0x0c0c0400u), __builtin_amdgcn_perm(ub, ua, 0x0c0c0400u), 0x05040100u);
; }
; __device__ __forceinline__ void rotq_row(f32x4 (&v)[16], unsigned* q8row, float* rsp, int lane) {
;     float am = 0.f; const RotSigns sg = rot_signs(lane);
; #pragma unroll
;     for (int j = 0; j < 16; ++j) { v[j] = rot64(v[j], sg);
;         am = fmaxf(fmaxf(am, fmaxf(fabsf(v[j].x), fabsf(v[j].y))), fmaxf(fabsf(v[j].z), fabsf(v[j].w))); }
	v_max3_f32 v5, v5, v24, v25
	v_mov_b32_e32 v24, v110
	v_mov_b32_e32 v25, v108
	v_pk_add_f32 v[32:33], v[24:25], v[26:27]
	v_pk_add_f32 v[24:25], v[24:25], v[26:27] neg_lo:[0,1] neg_hi:[0,1]
	v_pk_mov_b32 v[26:27], v[108:109], v[110:111] op_sel:[1,0]
	v_mov_b32_e32 v109, v111
	v_pk_add_f32 v[34:35], v[26:27], v[108:109]
	v_pk_add_f32 v[26:27], v[26:27], v[108:109] neg_lo:[0,1] neg_hi:[0,1]
	v_mov_b32_e32 v33, v25
	v_mov_b32_e32 v35, v27
	v_pk_add_f32 v[40:41], v[34:35], v[32:33]
	v_mov_b32_e32 v35, v25
	v_mov_b32_e32 v33, v27
	v_pk_add_f32 v[24:25], v[34:35], v[32:33] neg_lo:[0,1] neg_hi:[0,1]
	v_mov_b32_dpp v42, v40 quad_perm:[1,0,3,2] row_mask:0xf bank_mask:0xf bound_ctrl:1
	v_mov_b32_dpp v43, v41 quad_perm:[1,0,3,2] row_mask:0xf bank_mask:0xf bound_ctrl:1
	v_mov_b32_dpp v26, v24 quad_perm:[1,0,3,2] row_mask:0xf bank_mask:0xf bound_ctrl:1
	v_mov_b32_dpp v27, v25 quad_perm:[1,0,3,2] row_mask:0xf bank_mask:0xf bound_ctrl:1
	v_pk_fma_f32 v[40:41], v[72:73], v[40:41], v[42:43]
	v_pk_fma_f32 v[24:25], v[72:73], v[24:25], v[26:27]
	v_mov_b32_e32 v34, v107
	v_mov_b32_dpp v42, v40 quad_perm:[2,3,0,1] row_mask:0xf bank_mask:0xf bound_ctrl:1
	v_mov_b32_dpp v43, v41 quad_perm:[2,3,0,1] row_mask:0xf bank_mask:0xf bound_ctrl:1
	v_mov_b32_dpp v26, v24 quad_perm:[2,3,0,1] row_mask:0xf bank_mask:0xf bound_ctrl:1
	v_mov_b32_dpp v27, v25 quad_perm:[2,3,0,1] row_mask:0xf bank_mask:0xf bound_ctrl:1
	v_pk_fma_f32 v[40:41], v[70:71], v[40:41], v[42:43]
	v_pk_fma_f32 v[24:25], v[70:71], v[24:25], v[26:27]
	v_mov_b32_e32 v42, v40
	v_mov_b32_e32 v43, v41
	v_mov_b32_e32 v26, v24
	v_mov_b32_e32 v27, v25
	v_mov_b32_dpp v42, v42 row_shl:4 row_mask:0xf bank_mask:0x5
	v_mov_b32_dpp v43, v43 row_shl:4 row_mask:0xf bank_mask:0x5
	v_mov_b32_dpp v26, v26 row_shl:4 row_mask:0xf bank_mask:0x5
	v_mov_b32_dpp v27, v27 row_shl:4 row_mask:0xf bank_mask:0x5
	v_mov_b32_dpp v42, v40 row_shr:4 row_mask:0xf bank_mask:0xa
	v_mov_b32_dpp v43, v41 row_shr:4 row_mask:0xf bank_mask:0xa
	v_mov_b32_dpp v26, v24 row_shr:4 row_mask:0xf bank_mask:0xa
	v_mov_b32_dpp v27, v25 row_shr:4 row_mask:0xf bank_mask:0xa
	v_pk_fma_f32 v[40:41], v[68:69], v[40:41], v[42:43]
	v_pk_fma_f32 v[24:25], v[68:69], v[24:25], v[26:27]
	v_mov_b32_e32 v35, v105
	v_mov_b32_dpp v42, v40 row_ror:8 row_mask:0xf bank_mask:0xf bound_ctrl:1
	v_mov_b32_dpp v43, v41 row_ror:8 row_mask:0xf bank_mask:0xf bound_ctrl:1
	v_mov_b32_dpp v26, v24 row_ror:8 row_mask:0xf bank_mask:0xf bound_ctrl:1
	v_mov_b32_dpp v27, v25 row_ror:8 row_mask:0xf bank_mask:0xf bound_ctrl:1
	v_pk_fma_f32 v[32:33], v[66:67], v[40:41], v[42:43]
	v_pk_fma_f32 v[24:25], v[88:89], v[24:25], v[26:27]
	v_pk_mul_f32 v[26:27], v[32:33], s[40:41] op_sel_hi:[1,0]
	v_pk_mul_f32 v[24:25], v[24:25], s[40:41] op_sel_hi:[1,0]
	v_max_f32_e64 v32, |v26|, |v27|
	v_max_f32_e64 v33, |v24|, |v25|
	v_max3_f32 v5, v5, v32, v33
	v_mov_b32_e32 v32, v106
	v_mov_b32_e32 v33, v104
	v_pk_add_f32 v[40:41], v[32:33], v[34:35]
	v_pk_add_f32 v[32:33], v[32:33], v[34:35] neg_lo:[0,1] neg_hi:[0,1]
	v_pk_mov_b32 v[34:35], v[104:105], v[106:107] op_sel:[1,0]
	v_mov_b32_e32 v105, v107
	v_pk_add_f32 v[42:43], v[34:35], v[104:105]
	v_pk_add_f32 v[34:35], v[34:35], v[104:105] neg_lo:[0,1] neg_hi:[0,1]
	v_mov_b32_e32 v41, v33
	v_mov_b32_e32 v43, v35
	v_pk_add_f32 v[104:105], v[42:43], v[40:41]
	v_mov_b32_e32 v43, v33
	v_mov_b32_e32 v41, v35
	v_pk_add_f32 v[32:33], v[42:43], v[40:41] neg_lo:[0,1] neg_hi:[0,1]
	v_mov_b32_dpp v106, v104 quad_perm:[1,0,3,2] row_mask:0xf bank_mask:0xf bound_ctrl:1
	v_mov_b32_dpp v107, v105 quad_perm:[1,0,3,2] row_mask:0xf bank_mask:0xf bound_ctrl:1
	v_mov_b32_dpp v34, v32 quad_perm:[1,0,3,2] row_mask:0xf bank_mask:0xf bound_ctrl:1
	v_mov_b32_dpp v35, v33 quad_perm:[1,0,3,2] row_mask:0xf bank_mask:0xf bound_ctrl:1
	v_pk_fma_f32 v[104:105], v[72:73], v[104:105], v[106:107]
	v_pk_fma_f32 v[32:33], v[72:73], v[32:33], v[34:35]
	v_mov_b32_e32 v42, v103
	v_mov_b32_dpp v106, v104 quad_perm:[2,3,0,1] row_mask:0xf bank_mask:0xf bound_ctrl:1
	v_mov_b32_dpp v107, v105 quad_perm:[2,3,0,1] row_mask:0xf bank_mask:0xf bound_ctrl:1
	v_mov_b32_dpp v34, v32 quad_perm:[2,3,0,1] row_mask:0xf bank_mask:0xf bound_ctrl:1
	v_mov_b32_dpp v35, v33 quad_perm:[2,3,0,1] row_mask:0xf bank_mask:0xf bound_ctrl:1
	v_pk_fma_f32 v[104:105], v[70:71], v[104:105], v[106:107]
	v_pk_fma_f32 v[32:33], v[70:71], v[32:33], v[34:35]
	v_mov_b32_e32 v106, v104
	v_mov_b32_e32 v107, v105
	v_mov_b32_e32 v34, v32
	v_mov_b32_e32 v35, v33
	v_mov_b32_dpp v106, v106 row_shl:4 row_mask:0xf bank_mask:0x5
	v_mov_b32_dpp v107, v107 row_shl:4 row_mask:0xf bank_mask:0x5
	v_mov_b32_dpp v34, v34 row_shl:4 row_mask:0xf bank_mask:0x5
	v_mov_b32_dpp v35, v35 row_shl:4 row_mask:0xf bank_mask:0x5
	v_mov_b32_dpp v106, v104 row_shr:4 row_mask:0xf bank_mask:0xa
	v_mov_b32_dpp v107, v105 row_shr:4 row_mask:0xf bank_mask:0xa
	v_mov_b32_dpp v34, v32 row_shr:4 row_mask:0xf bank_mask:0xa
	v_mov_b32_dpp v35, v33 row_shr:4 row_mask:0xf bank_mask:0xa
	v_pk_fma_f32 v[104:105], v[68:69], v[104:105], v[106:107]
	v_pk_fma_f32 v[32:33], v[68:69], v[32:33], v[34:35]
	v_mov_b32_e32 v43, v101
	v_mov_b32_dpp v106, v104 row_ror:8 row_mask:0xf bank_mask:0xf bound_ctrl:1
	v_mov_b32_dpp v107, v105 row_ror:8 row_mask:0xf bank_mask:0xf bound_ctrl:1
	v_mov_b32_dpp v34, v32 row_ror:8 row_mask:0xf bank_mask:0xf bound_ctrl:1
	v_mov_b32_dpp v35, v33 row_ror:8 row_mask:0xf bank_mask:0xf bound_ctrl:1
	v_pk_fma_f32 v[40:41], v[66:67], v[104:105], v[106:107]
	v_pk_fma_f32 v[32:33], v[88:89], v[32:33], v[34:35]
	v_pk_mul_f32 v[34:35], v[40:41], s[40:41] op_sel_hi:[1,0]
	v_pk_mul_f32 v[32:33], v[32:33], s[40:41] op_sel_hi:[1,0]
	v_max_f32_e64 v40, |v34|, |v35|
; __device__ __forceinline__ float xlane1(float t) { return dpp_mov<0xB1, 0xF, true>(0.f, t); }
; __device__ __forceinline__ float xlane2(float t) { return dpp_mov<0x4E, 0xF, true>(0.f, t); }
; __device__ __forceinline__ float xlane4(float t) { const float r = dpp_mov<0x104, 0x5, false>(t, t); return dpp_mov<0x114, 0xA, false>(r, t); }
; __device__ __forceinline__ float xlane8(float t) { return dpp_mov<0x128, 0xF, true>(0.f, t); }
; __device__ __forceinline__ f32x4 rot64(f32x4 t, const RotSigns sg) {
;     { const float p0 = t.x + t.y, p1 = t.x - t.y, p2 = t.z + t.w, p3 = t.z - t.w; t = (f32x4){p0 + p2, p1 + p3, p0 - p2, p1 - p3}; }
;     t = (f32x4){__builtin_fmaf(sg.s1, t.x, xlane1(t.x)), __builtin_fmaf(sg.s1, t.y, xlane1(t.y)), __builtin_fmaf(sg.s1, t.z, xlane1(t.z)), __builtin_fmaf(sg.s1, t.w, xlane1(t.w))};
;     t = (f32x4){__builtin_fmaf(sg.s2, t.x, xlane2(t.x)), __builtin_fmaf(sg.s2, t.y, xlane2(t.y)), __builtin_fmaf(sg.s2, t.z, xlane2(t.z)), __builtin_fmaf(sg.s2, t.w, xlane2(t.w))};
;     t = (f32x4){__builtin_fmaf(sg.s4, t.x, xlane4(t.x)), __builtin_fmaf(sg.s4, t.y, xlane4(t.y)), __builtin_fmaf(sg.s4, t.z, xlane4(t.z)), __builtin_fmaf(sg.s4, t.w, xlane4(t.w))};
;     t = (f32x4){__builtin_fmaf(sg.s8, t.x, xlane8(t.x)), __builtin_fmaf(sg.s8, t.y, xlane8(t.y)), __builtin_fmaf(sg.s8, t.z, xlane8(t.z)), __builtin_fmaf(sg.s8, t.w, xlane8(t.w))};
;     return t * 0.125f;
; }
; __device__ __forceinline__ unsigned pack_q8m(float a, float b, float c, float d, float inv) {
;     const unsigned ua = __float_as_uint(__builtin_fmaf(a, inv, 12582912.0f)), ub = __float_as_uint(__builtin_fmaf(b, inv, 12582912.0f));
;     const unsigned uc = __float_as_uint(__builtin_fmaf(c, inv, 12582912.0f)), ud = __float_as_uint(__builtin_fmaf(d, inv, 12582912.0f));
;     return __builtin_amdgcn_perm(__builtin_amdgcn_perm(ud, uc, 0x0c0c0400u), __builtin_amdgcn_perm(ub, ua, 0x0c0c0400u), 0x05040100u);
; }
; __device__ __forceinline__ void rotq_row(f32x4 (&v)[16], unsigned* q8row, float* rsp, int lane) {
;     float am = 0.f; const RotSigns sg = rot_signs(lane);
; #pragma unroll
;     for (int j = 0; j < 16; ++j) { v[j] = rot64(v[j], sg);
;         am = fmaxf(fmaxf(am, fmaxf(fabsf(v[j].x), fabsf(v[j].y))), fmaxf(fabsf(v[j].z), fabsf(v[j].w))); }
	v_max_f32_e64 v41, |v32|, |v33|
	v_max3_f32 v5, v5, v40, v41
	v_mov_b32_e32 v40, v102
	v_mov_b32_e32 v41, v100
	v_pk_add_f32 v[104:105], v[40:41], v[42:43]
	v_pk_add_f32 v[40:41], v[40:41], v[42:43] neg_lo:[0,1] neg_hi:[0,1]
	v_pk_mov_b32 v[42:43], v[100:101], v[102:103] op_sel:[1,0]
	v_mov_b32_e32 v101, v103
	v_pk_add_f32 v[102:103], v[42:43], v[100:101]
	v_pk_add_f32 v[42:43], v[42:43], v[100:101] neg_lo:[0,1] neg_hi:[0,1]
	v_mov_b32_e32 v105, v41
	v_mov_b32_e32 v103, v43
	v_pk_add_f32 v[100:101], v[102:103], v[104:105]
	v_mov_b32_e32 v103, v41
	v_mov_b32_e32 v105, v43
	v_pk_add_f32 v[40:41], v[102:103], v[104:105] neg_lo:[0,1] neg_hi:[0,1]
	v_mov_b32_dpp v106, v100 quad_perm:[1,0,3,2] row_mask:0xf bank_mask:0xf bound_ctrl:1
	v_mov_b32_dpp v107, v101 quad_perm:[1,0,3,2] row_mask:0xf bank_mask:0xf bound_ctrl:1
	v_mov_b32_dpp v42, v40 quad_perm:[1,0,3,2] row_mask:0xf bank_mask:0xf bound_ctrl:1
	v_mov_b32_dpp v43, v41 quad_perm:[1,0,3,2] row_mask:0xf bank_mask:0xf bound_ctrl:1
	v_pk_fma_f32 v[100:101], v[72:73], v[100:101], v[106:107]
	v_pk_fma_f32 v[40:41], v[72:73], v[40:41], v[42:43]
	v_mov_b32_e32 v102, v51
	v_mov_b32_dpp v106, v100 quad_perm:[2,3,0,1] row_mask:0xf bank_mask:0xf bound_ctrl:1
	v_mov_b32_dpp v107, v101 quad_perm:[2,3,0,1] row_mask:0xf bank_mask:0xf bound_ctrl:1
	v_mov_b32_dpp v42, v40 quad_perm:[2,3,0,1] row_mask:0xf bank_mask:0xf bound_ctrl:1
	v_mov_b32_dpp v43, v41 quad_perm:[2,3,0,1] row_mask:0xf bank_mask:0xf bound_ctrl:1
	v_pk_fma_f32 v[100:101], v[70:71], v[100:101], v[106:107]
	v_pk_fma_f32 v[40:41], v[70:71], v[40:41], v[42:43]
	v_mov_b32_e32 v106, v100
	v_mov_b32_e32 v107, v101
	v_mov_b32_e32 v42, v40
	v_mov_b32_e32 v43, v41
	v_mov_b32_dpp v106, v106 row_shl:4 row_mask:0xf bank_mask:0x5
	v_mov_b32_dpp v107, v107 row_shl:4 row_mask:0xf bank_mask:0x5
	v_mov_b32_dpp v42, v42 row_shl:4 row_mask:0xf bank_mask:0x5
	v_mov_b32_dpp v43, v43 row_shl:4 row_mask:0xf bank_mask:0x5
	v_mov_b32_dpp v106, v100 row_shr:4 row_mask:0xf bank_mask:0xa
	v_mov_b32_dpp v107, v101 row_shr:4 row_mask:0xf bank_mask:0xa
	v_mov_b32_dpp v42, v40 row_shr:4 row_mask:0xf bank_mask:0xa
	v_mov_b32_dpp v43, v41 row_shr:4 row_mask:0xf bank_mask:0xa
	v_pk_fma_f32 v[100:101], v[68:69], v[100:101], v[106:107]
	v_pk_fma_f32 v[40:41], v[68:69], v[40:41], v[42:43]
	v_mov_b32_e32 v103, v49
	v_mov_b32_dpp v106, v100 row_ror:8 row_mask:0xf bank_mask:0xf bound_ctrl:1
	v_mov_b32_dpp v107, v101 row_ror:8 row_mask:0xf bank_mask:0xf bound_ctrl:1
	v_mov_b32_dpp v42, v40 row_ror:8 row_mask:0xf bank_mask:0xf bound_ctrl:1
	v_mov_b32_dpp v43, v41 row_ror:8 row_mask:0xf bank_mask:0xf bound_ctrl:1
	v_pk_fma_f32 v[100:101], v[66:67], v[100:101], v[106:107]
	v_pk_fma_f32 v[40:41], v[88:89], v[40:41], v[42:43]
	v_pk_mul_f32 v[42:43], v[100:101], s[40:41] op_sel_hi:[1,0]
	v_pk_mul_f32 v[40:41], v[40:41], s[40:41] op_sel_hi:[1,0]
	v_max_f32_e64 v100, |v42|, |v43|
	v_max_f32_e64 v101, |v40|, |v41|
	v_max3_f32 v5, v5, v100, v101
	v_mov_b32_e32 v100, v50
	v_mov_b32_e32 v101, v48
	v_pk_add_f32 v[104:105], v[100:101], v[102:103]
	v_pk_add_f32 v[100:101], v[100:101], v[102:103] neg_lo:[0,1] neg_hi:[0,1]
	v_pk_mov_b32 v[102:103], v[48:49], v[50:51] op_sel:[1,0]
	v_mov_b32_e32 v49, v51
	v_pk_add_f32 v[50:51], v[102:103], v[48:49]
	v_pk_add_f32 v[48:49], v[102:103], v[48:49] neg_lo:[0,1] neg_hi:[0,1]
	v_mov_b32_e32 v105, v101
	v_mov_b32_e32 v51, v49
	v_pk_add_f32 v[102:103], v[50:51], v[104:105]
	v_mov_b32_e32 v51, v101
	v_mov_b32_e32 v105, v49
	v_pk_add_f32 v[48:49], v[50:51], v[104:105] neg_lo:[0,1] neg_hi:[0,1]
	v_mov_b32_dpp v106, v102 quad_perm:[1,0,3,2] row_mask:0xf bank_mask:0xf bound_ctrl:1
	v_mov_b32_dpp v107, v103 quad_perm:[1,0,3,2] row_mask:0xf bank_mask:0xf bound_ctrl:1
	v_mov_b32_dpp v50, v48 quad_perm:[1,0,3,2] row_mask:0xf bank_mask:0xf bound_ctrl:1
	v_mov_b32_dpp v51, v49 quad_perm:[1,0,3,2] row_mask:0xf bank_mask:0xf bound_ctrl:1
	v_pk_fma_f32 v[102:103], v[72:73], v[102:103], v[106:107]
	v_pk_fma_f32 v[48:49], v[72:73], v[48:49], v[50:51]
	v_cvt_pk_bf16_f32 v4, v10, v11
	s_nop 0
	v_mov_b32_dpp v106, v102 quad_perm:[2,3,0,1] row_mask:0xf bank_mask:0xf bound_ctrl:1
	v_mov_b32_dpp v107, v103 quad_perm:[2,3,0,1] row_mask:0xf bank_mask:0xf bound_ctrl:1
	v_mov_b32_dpp v50, v48 quad_perm:[2,3,0,1] row_mask:0xf bank_mask:0xf bound_ctrl:1
	v_mov_b32_dpp v51, v49 quad_perm:[2,3,0,1] row_mask:0xf bank_mask:0xf bound_ctrl:1
	v_pk_fma_f32 v[102:103], v[70:71], v[102:103], v[106:107]
	v_pk_fma_f32 v[48:49], v[70:71], v[48:49], v[50:51]
	v_mov_b32_e32 v106, v102
	v_mov_b32_e32 v107, v103
	v_mov_b32_e32 v50, v48
	v_mov_b32_e32 v51, v49
	v_mov_b32_dpp v106, v106 row_shl:4 row_mask:0xf bank_mask:0x5
	v_mov_b32_dpp v107, v107 row_shl:4 row_mask:0xf bank_mask:0x5
	v_mov_b32_dpp v50, v50 row_shl:4 row_mask:0xf bank_mask:0x5
	v_mov_b32_dpp v51, v51 row_shl:4 row_mask:0xf bank_mask:0x5
	v_mov_b32_dpp v106, v102 row_shr:4 row_mask:0xf bank_mask:0xa
	v_mov_b32_dpp v107, v103 row_shr:4 row_mask:0xf bank_mask:0xa
	v_mov_b32_dpp v50, v48 row_shr:4 row_mask:0xf bank_mask:0xa
	v_mov_b32_dpp v51, v49 row_shr:4 row_mask:0xf bank_mask:0xa
	v_pk_fma_f32 v[102:103], v[68:69], v[102:103], v[106:107]
	v_pk_fma_f32 v[48:49], v[68:69], v[48:49], v[50:51]
	s_nop 0
	v_mov_b32_dpp v106, v102 row_ror:8 row_mask:0xf bank_mask:0xf bound_ctrl:1
	v_mov_b32_dpp v107, v103 row_ror:8 row_mask:0xf bank_mask:0xf bound_ctrl:1
	v_mov_b32_dpp v50, v48 row_ror:8 row_mask:0xf bank_mask:0xf bound_ctrl:1
	v_mov_b32_dpp v51, v49 row_ror:8 row_mask:0xf bank_mask:0xf bound_ctrl:1
	v_pk_fma_f32 v[100:101], v[66:67], v[102:103], v[106:107]
	v_pk_fma_f32 v[48:49], v[88:89], v[48:49], v[50:51]
	v_pk_mul_f32 v[50:51], v[100:101], s[40:41] op_sel_hi:[1,0]
; __device__ __forceinline__ float xlane1(float t) { return dpp_mov<0xB1, 0xF, true>(0.f, t); }
; __device__ __forceinline__ float xlane2(float t) { return dpp_mov<0x4E, 0xF, true>(0.f, t); }
; __device__ __forceinline__ float xlane4(float t) { const float r = dpp_mov<0x104, 0x5, false>(t, t); return dpp_mov<0x114, 0xA, false>(r, t); }
; __device__ __forceinline__ float xlane8(float t) { return dpp_mov<0x128, 0xF, true>(0.f, t); }
; __device__ __forceinline__ f32x4 rot64(f32x4 t, const RotSigns sg) {
;     { const float p0 = t.x + t.y, p1 = t.x - t.y, p2 = t.z + t.w, p3 = t.z - t.w; t = (f32x4){p0 + p2, p1 + p3, p0 - p2, p1 - p3}; }
;     t = (f32x4){__builtin_fmaf(sg.s1, t.x, xlane1(t.x)), __builtin_fmaf(sg.s1, t.y, xlane1(t.y)), __builtin_fmaf(sg.s1, t.z, xlane1(t.z)), __builtin_fmaf(sg.s1, t.w, xlane1(t.w))};
;     t = (f32x4){__builtin_fmaf(sg.s2, t.x, xlane2(t.x)), __builtin_fmaf(sg.s2, t.y, xlane2(t.y)), __builtin_fmaf(sg.s2, t.z, xlane2(t.z)), __builtin_fmaf(sg.s2, t.w, xlane2(t.w))};
;     t = (f32x4){__builtin_fmaf(sg.s4, t.x, xlane4(t.x)), __builtin_fmaf(sg.s4, t.y, xlane4(t.y)), __builtin_fmaf(sg.s4, t.z, xlane4(t.z)), __builtin_fmaf(sg.s4, t.w, xlane4(t.w))};
;     t = (f32x4){__builtin_fmaf(sg.s8, t.x, xlane8(t.x)), __builtin_fmaf(sg.s8, t.y, xlane8(t.y)), __builtin_fmaf(sg.s8, t.z, xlane8(t.z)), __builtin_fmaf(sg.s8, t.w, xlane8(t.w))};
;     return t * 0.125f;
; }
; __device__ __forceinline__ unsigned pack_q8m(float a, float b, float c, float d, float inv) {
;     const unsigned ua = __float_as_uint(__builtin_fmaf(a, inv, 12582912.0f)), ub = __float_as_uint(__builtin_fmaf(b, inv, 12582912.0f));
;     const unsigned uc = __float_as_uint(__builtin_fmaf(c, inv, 12582912.0f)), ud = __float_as_uint(__builtin_fmaf(d, inv, 12582912.0f));
;     return __builtin_amdgcn_perm(__builtin_amdgcn_perm(ud, uc, 0x0c0c0400u), __builtin_amdgcn_perm(ub, ua, 0x0c0c0400u), 0x05040100u);
; }
; __device__ __forceinline__ void rotq_row(f32x4 (&v)[16], unsigned* q8row, float* rsp, int lane) {
;     float am = 0.f; const RotSigns sg = rot_signs(lane);
; #pragma unroll
;     for (int j = 0; j < 16; ++j) { v[j] = rot64(v[j], sg);
;         am = fmaxf(fmaxf(am, fmaxf(fabsf(v[j].x), fabsf(v[j].y))), fmaxf(fabsf(v[j].z), fabsf(v[j].w))); }
	v_pk_mul_f32 v[48:49], v[48:49], s[40:41] op_sel_hi:[1,0]
	v_max_f32_e64 v100, |v50|, |v51|
	v_max_f32_e64 v101, |v48|, |v49|
	v_max3_f32 v5, v5, v100, v101
	v_mov_b32_e32 v100, v64
	v_mov_b32_e32 v101, v60
	v_mov_b32_e32 v102, v65
	v_mov_b32_e32 v103, v61
	v_pk_add_f32 v[104:105], v[100:101], v[102:103]
	v_pk_add_f32 v[100:101], v[100:101], v[102:103] neg_lo:[0,1] neg_hi:[0,1]
	v_pk_mov_b32 v[102:103], v[60:61], v[64:65] op_sel:[1,0]
	v_mov_b32_e32 v61, v65
	v_pk_add_f32 v[64:65], v[102:103], v[60:61]
	v_pk_add_f32 v[60:61], v[102:103], v[60:61] neg_lo:[0,1] neg_hi:[0,1]
	v_mov_b32_e32 v105, v101
	v_mov_b32_e32 v65, v61
	v_pk_add_f32 v[102:103], v[64:65], v[104:105]
	v_mov_b32_e32 v65, v101
	v_mov_b32_e32 v105, v61
	v_pk_add_f32 v[60:61], v[64:65], v[104:105] neg_lo:[0,1] neg_hi:[0,1]
	v_mov_b32_dpp v106, v102 quad_perm:[1,0,3,2] row_mask:0xf bank_mask:0xf bound_ctrl:1
	v_mov_b32_dpp v107, v103 quad_perm:[1,0,3,2] row_mask:0xf bank_mask:0xf bound_ctrl:1
	v_mov_b32_dpp v64, v60 quad_perm:[1,0,3,2] row_mask:0xf bank_mask:0xf bound_ctrl:1
	v_mov_b32_dpp v65, v61 quad_perm:[1,0,3,2] row_mask:0xf bank_mask:0xf bound_ctrl:1
	v_pk_fma_f32 v[102:103], v[72:73], v[102:103], v[106:107]
	v_pk_fma_f32 v[60:61], v[72:73], v[60:61], v[64:65]
	s_nop 0
	v_mov_b32_dpp v106, v102 quad_perm:[2,3,0,1] row_mask:0xf bank_mask:0xf bound_ctrl:1
	v_mov_b32_dpp v107, v103 quad_perm:[2,3,0,1] row_mask:0xf bank_mask:0xf bound_ctrl:1
	v_mov_b32_dpp v64, v60 quad_perm:[2,3,0,1] row_mask:0xf bank_mask:0xf bound_ctrl:1
	v_mov_b32_dpp v65, v61 quad_perm:[2,3,0,1] row_mask:0xf bank_mask:0xf bound_ctrl:1
	v_pk_fma_f32 v[102:103], v[70:71], v[102:103], v[106:107]
	v_pk_fma_f32 v[60:61], v[70:71], v[60:61], v[64:65]
	v_mov_b32_e32 v106, v102
	v_mov_b32_e32 v107, v103
	v_mov_b32_e32 v64, v60
	v_mov_b32_e32 v65, v61
	v_mov_b32_dpp v106, v106 row_shl:4 row_mask:0xf bank_mask:0x5
	v_mov_b32_dpp v107, v107 row_shl:4 row_mask:0xf bank_mask:0x5
	v_mov_b32_dpp v64, v64 row_shl:4 row_mask:0xf bank_mask:0x5
	v_mov_b32_dpp v65, v65 row_shl:4 row_mask:0xf bank_mask:0x5
	v_mov_b32_dpp v106, v102 row_shr:4 row_mask:0xf bank_mask:0xa
	v_mov_b32_dpp v107, v103 row_shr:4 row_mask:0xf bank_mask:0xa
	v_mov_b32_dpp v64, v60 row_shr:4 row_mask:0xf bank_mask:0xa
	v_mov_b32_dpp v65, v61 row_shr:4 row_mask:0xf bank_mask:0xa
	v_pk_fma_f32 v[102:103], v[68:69], v[102:103], v[106:107]
	v_pk_fma_f32 v[60:61], v[68:69], v[60:61], v[64:65]
	s_nop 0
	v_mov_b32_dpp v106, v102 row_ror:8 row_mask:0xf bank_mask:0xf bound_ctrl:1
	v_mov_b32_dpp v107, v103 row_ror:8 row_mask:0xf bank_mask:0xf bound_ctrl:1
	v_mov_b32_dpp v64, v60 row_ror:8 row_mask:0xf bank_mask:0xf bound_ctrl:1
	v_mov_b32_dpp v65, v61 row_ror:8 row_mask:0xf bank_mask:0xf bound_ctrl:1
	v_pk_fma_f32 v[100:101], v[66:67], v[102:103], v[106:107]
	v_pk_fma_f32 v[60:61], v[88:89], v[60:61], v[64:65]
	v_pk_mul_f32 v[64:65], v[100:101], s[40:41] op_sel_hi:[1,0]
	v_pk_mul_f32 v[60:61], v[60:61], s[40:41] op_sel_hi:[1,0]
	v_max_f32_e64 v100, |v64|, |v65|
	v_max_f32_e64 v101, |v60|, |v61|
	v_max3_f32 v5, v5, v100, v101
	v_mov_b32_e32 v100, v98
	v_mov_b32_e32 v101, v96
	v_mov_b32_e32 v102, v99
	v_mov_b32_e32 v103, v97
	v_pk_add_f32 v[104:105], v[100:101], v[102:103]
	v_pk_add_f32 v[100:101], v[100:101], v[102:103] neg_lo:[0,1] neg_hi:[0,1]
	v_pk_mov_b32 v[102:103], v[96:97], v[98:99] op_sel:[1,0]
	v_mov_b32_e32 v97, v99
	v_pk_add_f32 v[98:99], v[102:103], v[96:97]
	v_pk_add_f32 v[96:97], v[102:103], v[96:97] neg_lo:[0,1] neg_hi:[0,1]
	v_mov_b32_e32 v105, v101
	v_mov_b32_e32 v99, v97
	v_pk_add_f32 v[102:103], v[98:99], v[104:105]
	v_mov_b32_e32 v99, v101
	v_mov_b32_e32 v105, v97
	v_pk_add_f32 v[96:97], v[98:99], v[104:105] neg_lo:[0,1] neg_hi:[0,1]
	v_mov_b32_dpp v106, v102 quad_perm:[1,0,3,2] row_mask:0xf bank_mask:0xf bound_ctrl:1
	v_mov_b32_dpp v107, v103 quad_perm:[1,0,3,2] row_mask:0xf bank_mask:0xf bound_ctrl:1
	v_mov_b32_dpp v98, v96 quad_perm:[1,0,3,2] row_mask:0xf bank_mask:0xf bound_ctrl:1
	v_mov_b32_dpp v99, v97 quad_perm:[1,0,3,2] row_mask:0xf bank_mask:0xf bound_ctrl:1
	v_pk_fma_f32 v[102:103], v[72:73], v[102:103], v[106:107]
	v_pk_fma_f32 v[96:97], v[72:73], v[96:97], v[98:99]
	s_nop 0
	v_mov_b32_dpp v106, v102 quad_perm:[2,3,0,1] row_mask:0xf bank_mask:0xf bound_ctrl:1
	v_mov_b32_dpp v107, v103 quad_perm:[2,3,0,1] row_mask:0xf bank_mask:0xf bound_ctrl:1
	v_mov_b32_dpp v98, v96 quad_perm:[2,3,0,1] row_mask:0xf bank_mask:0xf bound_ctrl:1
	v_mov_b32_dpp v99, v97 quad_perm:[2,3,0,1] row_mask:0xf bank_mask:0xf bound_ctrl:1
	v_pk_fma_f32 v[102:103], v[70:71], v[102:103], v[106:107]
	v_pk_fma_f32 v[96:97], v[70:71], v[96:97], v[98:99]
	v_mov_b32_e32 v106, v102
	v_mov_b32_e32 v107, v103
	v_mov_b32_e32 v98, v96
	v_mov_b32_e32 v99, v97
	v_mov_b32_dpp v106, v106 row_shl:4 row_mask:0xf bank_mask:0x5
	v_mov_b32_dpp v107, v107 row_shl:4 row_mask:0xf bank_mask:0x5
	v_mov_b32_dpp v98, v98 row_shl:4 row_mask:0xf bank_mask:0x5
	v_mov_b32_dpp v99, v99 row_shl:4 row_mask:0xf bank_mask:0x5
	v_mov_b32_dpp v106, v102 row_shr:4 row_mask:0xf bank_mask:0xa
	v_mov_b32_dpp v107, v103 row_shr:4 row_mask:0xf bank_mask:0xa
	v_mov_b32_dpp v98, v96 row_shr:4 row_mask:0xf bank_mask:0xa
	v_mov_b32_dpp v99, v97 row_shr:4 row_mask:0xf bank_mask:0xa
	v_pk_fma_f32 v[102:103], v[68:69], v[102:103], v[106:107]
	v_pk_fma_f32 v[96:97], v[68:69], v[96:97], v[98:99]
	s_nop 0
	v_mov_b32_dpp v106, v102 row_ror:8 row_mask:0xf bank_mask:0xf bound_ctrl:1
	v_mov_b32_dpp v107, v103 row_ror:8 row_mask:0xf bank_mask:0xf bound_ctrl:1
	v_mov_b32_dpp v98, v96 row_ror:8 row_mask:0xf bank_mask:0xf bound_ctrl:1
	v_mov_b32_dpp v99, v97 row_ror:8 row_mask:0xf bank_mask:0xf bound_ctrl:1
; __device__ __forceinline__ float xlane1(float t) { return dpp_mov<0xB1, 0xF, true>(0.f, t); }
; __device__ __forceinline__ float xlane2(float t) { return dpp_mov<0x4E, 0xF, true>(0.f, t); }
; __device__ __forceinline__ float xlane4(float t) { const float r = dpp_mov<0x104, 0x5, false>(t, t); return dpp_mov<0x114, 0xA, false>(r, t); }
; __device__ __forceinline__ float xlane8(float t) { return dpp_mov<0x128, 0xF, true>(0.f, t); }
; __device__ __forceinline__ f32x4 rot64(f32x4 t, const RotSigns sg) {
;     { const float p0 = t.x + t.y, p1 = t.x - t.y, p2 = t.z + t.w, p3 = t.z - t.w; t = (f32x4){p0 + p2, p1 + p3, p0 - p2, p1 - p3}; }
;     t = (f32x4){__builtin_fmaf(sg.s1, t.x, xlane1(t.x)), __builtin_fmaf(sg.s1, t.y, xlane1(t.y)), __builtin_fmaf(sg.s1, t.z, xlane1(t.z)), __builtin_fmaf(sg.s1, t.w, xlane1(t.w))};
;     t = (f32x4){__builtin_fmaf(sg.s2, t.x, xlane2(t.x)), __builtin_fmaf(sg.s2, t.y, xlane2(t.y)), __builtin_fmaf(sg.s2, t.z, xlane2(t.z)), __builtin_fmaf(sg.s2, t.w, xlane2(t.w))};
;     t = (f32x4){__builtin_fmaf(sg.s4, t.x, xlane4(t.x)), __builtin_fmaf(sg.s4, t.y, xlane4(t.y)), __builtin_fmaf(sg.s4, t.z, xlane4(t.z)), __builtin_fmaf(sg.s4, t.w, xlane4(t.w))};
;     t = (f32x4){__builtin_fmaf(sg.s8, t.x, xlane8(t.x)), __builtin_fmaf(sg.s8, t.y, xlane8(t.y)), __builtin_fmaf(sg.s8, t.z, xlane8(t.z)), __builtin_fmaf(sg.s8, t.w, xlane8(t.w))};
;     return t * 0.125f;
; }
; __device__ __forceinline__ unsigned pack_q8m(float a, float b, float c, float d, float inv) {
;     const unsigned ua = __float_as_uint(__builtin_fmaf(a, inv, 12582912.0f)), ub = __float_as_uint(__builtin_fmaf(b, inv, 12582912.0f));
;     const unsigned uc = __float_as_uint(__builtin_fmaf(c, inv, 12582912.0f)), ud = __float_as_uint(__builtin_fmaf(d, inv, 12582912.0f));
;     return __builtin_amdgcn_perm(__builtin_amdgcn_perm(ud, uc, 0x0c0c0400u), __builtin_amdgcn_perm(ub, ua, 0x0c0c0400u), 0x05040100u);
; }
; __device__ __forceinline__ void rotq_row(f32x4 (&v)[16], unsigned* q8row, float* rsp, int lane) {
;     float am = 0.f; const RotSigns sg = rot_signs(lane);
; #pragma unroll
;     for (int j = 0; j < 16; ++j) { v[j] = rot64(v[j], sg);
;         am = fmaxf(fmaxf(am, fmaxf(fabsf(v[j].x), fabsf(v[j].y))), fmaxf(fabsf(v[j].z), fabsf(v[j].w))); }
	v_pk_fma_f32 v[100:101], v[66:67], v[102:103], v[106:107]
	v_pk_fma_f32 v[96:97], v[88:89], v[96:97], v[98:99]
	v_pk_mul_f32 v[98:99], v[100:101], s[40:41] op_sel_hi:[1,0]
	v_pk_mul_f32 v[96:97], v[96:97], s[40:41] op_sel_hi:[1,0]
	v_max_f32_e64 v100, |v98|, |v99|
	v_max_f32_e64 v101, |v96|, |v97|
	v_max3_f32 v5, v5, v100, v101
	v_mov_b32_e32 v100, v58
	v_mov_b32_e32 v101, v56
	v_mov_b32_e32 v102, v59
	v_mov_b32_e32 v103, v57
	v_pk_add_f32 v[104:105], v[100:101], v[102:103]
	v_pk_add_f32 v[100:101], v[100:101], v[102:103] neg_lo:[0,1] neg_hi:[0,1]
	v_pk_mov_b32 v[102:103], v[56:57], v[58:59] op_sel:[1,0]
	v_mov_b32_e32 v57, v59
	v_pk_add_f32 v[58:59], v[102:103], v[56:57]
	v_pk_add_f32 v[56:57], v[102:103], v[56:57] neg_lo:[0,1] neg_hi:[0,1]
	v_mov_b32_e32 v105, v101
	v_mov_b32_e32 v59, v57
	v_pk_add_f32 v[102:103], v[58:59], v[104:105]
	v_mov_b32_e32 v59, v101
	v_mov_b32_e32 v105, v57
	v_pk_add_f32 v[56:57], v[58:59], v[104:105] neg_lo:[0,1] neg_hi:[0,1]
	v_mov_b32_dpp v106, v102 quad_perm:[1,0,3,2] row_mask:0xf bank_mask:0xf bound_ctrl:1
	v_mov_b32_dpp v107, v103 quad_perm:[1,0,3,2] row_mask:0xf bank_mask:0xf bound_ctrl:1
	v_mov_b32_dpp v58, v56 quad_perm:[1,0,3,2] row_mask:0xf bank_mask:0xf bound_ctrl:1
	v_mov_b32_dpp v59, v57 quad_perm:[1,0,3,2] row_mask:0xf bank_mask:0xf bound_ctrl:1
	v_pk_fma_f32 v[102:103], v[72:73], v[102:103], v[106:107]
	v_pk_fma_f32 v[56:57], v[72:73], v[56:57], v[58:59]
	s_nop 0
	v_mov_b32_dpp v106, v102 quad_perm:[2,3,0,1] row_mask:0xf bank_mask:0xf bound_ctrl:1
	v_mov_b32_dpp v107, v103 quad_perm:[2,3,0,1] row_mask:0xf bank_mask:0xf bound_ctrl:1
	v_mov_b32_dpp v58, v56 quad_perm:[2,3,0,1] row_mask:0xf bank_mask:0xf bound_ctrl:1
	v_mov_b32_dpp v59, v57 quad_perm:[2,3,0,1] row_mask:0xf bank_mask:0xf bound_ctrl:1
	v_pk_fma_f32 v[102:103], v[70:71], v[102:103], v[106:107]
	v_pk_fma_f32 v[56:57], v[70:71], v[56:57], v[58:59]
	v_mov_b32_e32 v106, v102
	v_mov_b32_e32 v107, v103
	v_mov_b32_e32 v58, v56
	v_mov_b32_e32 v59, v57
	v_mov_b32_dpp v106, v106 row_shl:4 row_mask:0xf bank_mask:0x5
	v_mov_b32_dpp v107, v107 row_shl:4 row_mask:0xf bank_mask:0x5
	v_mov_b32_dpp v58, v58 row_shl:4 row_mask:0xf bank_mask:0x5
	v_mov_b32_dpp v59, v59 row_shl:4 row_mask:0xf bank_mask:0x5
	v_mov_b32_dpp v106, v102 row_shr:4 row_mask:0xf bank_mask:0xa
	v_mov_b32_dpp v107, v103 row_shr:4 row_mask:0xf bank_mask:0xa
	v_mov_b32_dpp v58, v56 row_shr:4 row_mask:0xf bank_mask:0xa
	v_mov_b32_dpp v59, v57 row_shr:4 row_mask:0xf bank_mask:0xa
	v_pk_fma_f32 v[102:103], v[68:69], v[102:103], v[106:107]
	v_pk_fma_f32 v[56:57], v[68:69], v[56:57], v[58:59]
	s_nop 0
	v_mov_b32_dpp v106, v102 row_ror:8 row_mask:0xf bank_mask:0xf bound_ctrl:1
	v_mov_b32_dpp v107, v103 row_ror:8 row_mask:0xf bank_mask:0xf bound_ctrl:1
	v_mov_b32_dpp v58, v56 row_ror:8 row_mask:0xf bank_mask:0xf bound_ctrl:1
	v_mov_b32_dpp v59, v57 row_ror:8 row_mask:0xf bank_mask:0xf bound_ctrl:1
	v_pk_fma_f32 v[100:101], v[66:67], v[102:103], v[106:107]
	v_pk_fma_f32 v[56:57], v[88:89], v[56:57], v[58:59]
	v_pk_mul_f32 v[58:59], v[100:101], s[40:41] op_sel_hi:[1,0]
	v_pk_mul_f32 v[56:57], v[56:57], s[40:41] op_sel_hi:[1,0]
	v_max_f32_e64 v100, |v58|, |v59|
	v_max_f32_e64 v101, |v56|, |v57|
	v_max3_f32 v5, v5, v100, v101
	v_mov_b32_e32 v100, v54
	v_mov_b32_e32 v101, v52
	v_mov_b32_e32 v102, v55
	v_mov_b32_e32 v103, v53
	v_pk_add_f32 v[104:105], v[100:101], v[102:103]
	v_pk_add_f32 v[100:101], v[100:101], v[102:103] neg_lo:[0,1] neg_hi:[0,1]
	v_pk_mov_b32 v[102:103], v[52:53], v[54:55] op_sel:[1,0]
	v_mov_b32_e32 v53, v55
	v_pk_add_f32 v[54:55], v[102:103], v[52:53]
	v_pk_add_f32 v[52:53], v[102:103], v[52:53] neg_lo:[0,1] neg_hi:[0,1]
	v_mov_b32_e32 v105, v101
	v_mov_b32_e32 v55, v53
	v_pk_add_f32 v[102:103], v[54:55], v[104:105]
	v_mov_b32_e32 v55, v101
	v_mov_b32_e32 v105, v53
	v_pk_add_f32 v[52:53], v[54:55], v[104:105] neg_lo:[0,1] neg_hi:[0,1]
	v_mov_b32_dpp v106, v102 quad_perm:[1,0,3,2] row_mask:0xf bank_mask:0xf bound_ctrl:1
	v_mov_b32_dpp v107, v103 quad_perm:[1,0,3,2] row_mask:0xf bank_mask:0xf bound_ctrl:1
	v_mov_b32_dpp v54, v52 quad_perm:[1,0,3,2] row_mask:0xf bank_mask:0xf bound_ctrl:1
	v_mov_b32_dpp v55, v53 quad_perm:[1,0,3,2] row_mask:0xf bank_mask:0xf bound_ctrl:1
	v_pk_fma_f32 v[102:103], v[72:73], v[102:103], v[106:107]
	v_pk_fma_f32 v[52:53], v[72:73], v[52:53], v[54:55]
	s_nop 0
	v_mov_b32_dpp v106, v102 quad_perm:[2,3,0,1] row_mask:0xf bank_mask:0xf bound_ctrl:1
	v_mov_b32_dpp v107, v103 quad_perm:[2,3,0,1] row_mask:0xf bank_mask:0xf bound_ctrl:1
	v_mov_b32_dpp v54, v52 quad_perm:[2,3,0,1] row_mask:0xf bank_mask:0xf bound_ctrl:1
	v_mov_b32_dpp v55, v53 quad_perm:[2,3,0,1] row_mask:0xf bank_mask:0xf bound_ctrl:1
	v_pk_fma_f32 v[102:103], v[70:71], v[102:103], v[106:107]
	v_pk_fma_f32 v[52:53], v[70:71], v[52:53], v[54:55]
	v_mov_b32_e32 v106, v102
	v_mov_b32_e32 v107, v103
	v_mov_b32_e32 v54, v52
	v_mov_b32_e32 v55, v53
	v_mov_b32_dpp v106, v106 row_shl:4 row_mask:0xf bank_mask:0x5
	v_mov_b32_dpp v107, v107 row_shl:4 row_mask:0xf bank_mask:0x5
	v_mov_b32_dpp v54, v54 row_shl:4 row_mask:0xf bank_mask:0x5
	v_mov_b32_dpp v55, v55 row_shl:4 row_mask:0xf bank_mask:0x5
	v_mov_b32_dpp v106, v102 row_shr:4 row_mask:0xf bank_mask:0xa
	v_mov_b32_dpp v107, v103 row_shr:4 row_mask:0xf bank_mask:0xa
	v_mov_b32_dpp v54, v52 row_shr:4 row_mask:0xf bank_mask:0xa
	v_mov_b32_dpp v55, v53 row_shr:4 row_mask:0xf bank_mask:0xa
	v_pk_fma_f32 v[102:103], v[68:69], v[102:103], v[106:107]
	v_pk_fma_f32 v[52:53], v[68:69], v[52:53], v[54:55]
	s_nop 0
	v_mov_b32_dpp v106, v102 row_ror:8 row_mask:0xf bank_mask:0xf bound_ctrl:1
	v_mov_b32_dpp v107, v103 row_ror:8 row_mask:0xf bank_mask:0xf bound_ctrl:1
; __device__ __forceinline__ float xlane1(float t) { return dpp_mov<0xB1, 0xF, true>(0.f, t); }
; __device__ __forceinline__ float xlane2(float t) { return dpp_mov<0x4E, 0xF, true>(0.f, t); }
; __device__ __forceinline__ float xlane4(float t) { const float r = dpp_mov<0x104, 0x5, false>(t, t); return dpp_mov<0x114, 0xA, false>(r, t); }
; __device__ __forceinline__ float xlane8(float t) { return dpp_mov<0x128, 0xF, true>(0.f, t); }
; __device__ __forceinline__ f32x4 rot64(f32x4 t, const RotSigns sg) {
;     { const float p0 = t.x + t.y, p1 = t.x - t.y, p2 = t.z + t.w, p3 = t.z - t.w; t = (f32x4){p0 + p2, p1 + p3, p0 - p2, p1 - p3}; }
;     t = (f32x4){__builtin_fmaf(sg.s1, t.x, xlane1(t.x)), __builtin_fmaf(sg.s1, t.y, xlane1(t.y)), __builtin_fmaf(sg.s1, t.z, xlane1(t.z)), __builtin_fmaf(sg.s1, t.w, xlane1(t.w))};
;     t = (f32x4){__builtin_fmaf(sg.s2, t.x, xlane2(t.x)), __builtin_fmaf(sg.s2, t.y, xlane2(t.y)), __builtin_fmaf(sg.s2, t.z, xlane2(t.z)), __builtin_fmaf(sg.s2, t.w, xlane2(t.w))};
;     t = (f32x4){__builtin_fmaf(sg.s4, t.x, xlane4(t.x)), __builtin_fmaf(sg.s4, t.y, xlane4(t.y)), __builtin_fmaf(sg.s4, t.z, xlane4(t.z)), __builtin_fmaf(sg.s4, t.w, xlane4(t.w))};
;     t = (f32x4){__builtin_fmaf(sg.s8, t.x, xlane8(t.x)), __builtin_fmaf(sg.s8, t.y, xlane8(t.y)), __builtin_fmaf(sg.s8, t.z, xlane8(t.z)), __builtin_fmaf(sg.s8, t.w, xlane8(t.w))};
;     return t * 0.125f;
; }
; __device__ __forceinline__ unsigned pack_q8m(float a, float b, float c, float d, float inv) {
;     const unsigned ua = __float_as_uint(__builtin_fmaf(a, inv, 12582912.0f)), ub = __float_as_uint(__builtin_fmaf(b, inv, 12582912.0f));
;     const unsigned uc = __float_as_uint(__builtin_fmaf(c, inv, 12582912.0f)), ud = __float_as_uint(__builtin_fmaf(d, inv, 12582912.0f));
;     return __builtin_amdgcn_perm(__builtin_amdgcn_perm(ud, uc, 0x0c0c0400u), __builtin_amdgcn_perm(ub, ua, 0x0c0c0400u), 0x05040100u);
; }
; __device__ __forceinline__ void rotq_row(f32x4 (&v)[16], unsigned* q8row, float* rsp, int lane) {
;     float am = 0.f; const RotSigns sg = rot_signs(lane);
; #pragma unroll
;     for (int j = 0; j < 16; ++j) { v[j] = rot64(v[j], sg);
;         am = fmaxf(fmaxf(am, fmaxf(fabsf(v[j].x), fabsf(v[j].y))), fmaxf(fabsf(v[j].z), fabsf(v[j].w))); }
	v_mov_b32_dpp v54, v52 row_ror:8 row_mask:0xf bank_mask:0xf bound_ctrl:1
	v_mov_b32_dpp v55, v53 row_ror:8 row_mask:0xf bank_mask:0xf bound_ctrl:1
	v_pk_fma_f32 v[100:101], v[66:67], v[102:103], v[106:107]
	v_pk_fma_f32 v[52:53], v[88:89], v[52:53], v[54:55]
	v_pk_mul_f32 v[54:55], v[100:101], s[40:41] op_sel_hi:[1,0]
	v_pk_mul_f32 v[52:53], v[52:53], s[40:41] op_sel_hi:[1,0]
	v_max_f32_e64 v100, |v54|, |v55|
	v_max_f32_e64 v101, |v52|, |v53|
	v_max3_f32 v5, v5, v100, v101
	v_mov_b32_e32 v100, v46
	v_mov_b32_e32 v101, v44
	v_mov_b32_e32 v102, v47
	v_mov_b32_e32 v103, v45
	v_pk_add_f32 v[104:105], v[100:101], v[102:103]
	v_pk_add_f32 v[100:101], v[100:101], v[102:103] neg_lo:[0,1] neg_hi:[0,1]
	v_pk_mov_b32 v[102:103], v[44:45], v[46:47] op_sel:[1,0]
	v_mov_b32_e32 v45, v47
	v_pk_add_f32 v[46:47], v[102:103], v[44:45]
	v_pk_add_f32 v[44:45], v[102:103], v[44:45] neg_lo:[0,1] neg_hi:[0,1]
	v_mov_b32_e32 v105, v101
	v_mov_b32_e32 v47, v45
	v_pk_add_f32 v[102:103], v[46:47], v[104:105]
	v_mov_b32_e32 v47, v101
	v_mov_b32_e32 v105, v45
	v_pk_add_f32 v[44:45], v[46:47], v[104:105] neg_lo:[0,1] neg_hi:[0,1]
	v_mov_b32_dpp v106, v102 quad_perm:[1,0,3,2] row_mask:0xf bank_mask:0xf bound_ctrl:1
	v_mov_b32_dpp v107, v103 quad_perm:[1,0,3,2] row_mask:0xf bank_mask:0xf bound_ctrl:1
	v_mov_b32_dpp v46, v44 quad_perm:[1,0,3,2] row_mask:0xf bank_mask:0xf bound_ctrl:1
	v_mov_b32_dpp v47, v45 quad_perm:[1,0,3,2] row_mask:0xf bank_mask:0xf bound_ctrl:1
	v_pk_fma_f32 v[102:103], v[72:73], v[102:103], v[106:107]
	v_pk_fma_f32 v[44:45], v[72:73], v[44:45], v[46:47]
	s_nop 0
	v_mov_b32_dpp v106, v102 quad_perm:[2,3,0,1] row_mask:0xf bank_mask:0xf bound_ctrl:1
	v_mov_b32_dpp v107, v103 quad_perm:[2,3,0,1] row_mask:0xf bank_mask:0xf bound_ctrl:1
	v_mov_b32_dpp v46, v44 quad_perm:[2,3,0,1] row_mask:0xf bank_mask:0xf bound_ctrl:1
	v_mov_b32_dpp v47, v45 quad_perm:[2,3,0,1] row_mask:0xf bank_mask:0xf bound_ctrl:1
	v_pk_fma_f32 v[102:103], v[70:71], v[102:103], v[106:107]
	v_pk_fma_f32 v[44:45], v[70:71], v[44:45], v[46:47]
	v_mov_b32_e32 v106, v102
	v_mov_b32_e32 v107, v103
	v_mov_b32_e32 v46, v44
	v_mov_b32_e32 v47, v45
	v_mov_b32_dpp v106, v106 row_shl:4 row_mask:0xf bank_mask:0x5
	v_mov_b32_dpp v107, v107 row_shl:4 row_mask:0xf bank_mask:0x5
	v_mov_b32_dpp v46, v46 row_shl:4 row_mask:0xf bank_mask:0x5
	v_mov_b32_dpp v47, v47 row_shl:4 row_mask:0xf bank_mask:0x5
	v_mov_b32_dpp v106, v102 row_shr:4 row_mask:0xf bank_mask:0xa
	v_mov_b32_dpp v107, v103 row_shr:4 row_mask:0xf bank_mask:0xa
	v_mov_b32_dpp v46, v44 row_shr:4 row_mask:0xf bank_mask:0xa
	v_mov_b32_dpp v47, v45 row_shr:4 row_mask:0xf bank_mask:0xa
	v_pk_fma_f32 v[102:103], v[68:69], v[102:103], v[106:107]
	v_pk_fma_f32 v[44:45], v[68:69], v[44:45], v[46:47]
	s_nop 0
	v_mov_b32_dpp v106, v102 row_ror:8 row_mask:0xf bank_mask:0xf bound_ctrl:1
	v_mov_b32_dpp v107, v103 row_ror:8 row_mask:0xf bank_mask:0xf bound_ctrl:1
	v_mov_b32_dpp v46, v44 row_ror:8 row_mask:0xf bank_mask:0xf bound_ctrl:1
	v_mov_b32_dpp v47, v45 row_ror:8 row_mask:0xf bank_mask:0xf bound_ctrl:1
	v_pk_fma_f32 v[100:101], v[66:67], v[102:103], v[106:107]
	v_pk_fma_f32 v[44:45], v[88:89], v[44:45], v[46:47]
	v_pk_mul_f32 v[46:47], v[100:101], s[40:41] op_sel_hi:[1,0]
	v_pk_mul_f32 v[44:45], v[44:45], s[40:41] op_sel_hi:[1,0]
	v_max_f32_e64 v100, |v46|, |v47|
	v_max_f32_e64 v101, |v44|, |v45|
	v_max3_f32 v5, v5, v100, v101
	v_mov_b32_e32 v100, v38
	v_mov_b32_e32 v101, v36
	v_mov_b32_e32 v102, v39
	v_mov_b32_e32 v103, v37
	v_pk_add_f32 v[104:105], v[100:101], v[102:103]
	v_pk_add_f32 v[100:101], v[100:101], v[102:103] neg_lo:[0,1] neg_hi:[0,1]
	v_pk_mov_b32 v[102:103], v[36:37], v[38:39] op_sel:[1,0]
	v_mov_b32_e32 v37, v39
	v_pk_add_f32 v[38:39], v[102:103], v[36:37]
	v_pk_add_f32 v[36:37], v[102:103], v[36:37] neg_lo:[0,1] neg_hi:[0,1]
	v_mov_b32_e32 v105, v101
	v_mov_b32_e32 v39, v37
	v_pk_add_f32 v[102:103], v[38:39], v[104:105]
	v_mov_b32_e32 v39, v101
	v_mov_b32_e32 v105, v37
	v_pk_add_f32 v[36:37], v[38:39], v[104:105] neg_lo:[0,1] neg_hi:[0,1]
	v_mov_b32_dpp v106, v102 quad_perm:[1,0,3,2] row_mask:0xf bank_mask:0xf bound_ctrl:1
	v_mov_b32_dpp v107, v103 quad_perm:[1,0,3,2] row_mask:0xf bank_mask:0xf bound_ctrl:1
	v_mov_b32_dpp v38, v36 quad_perm:[1,0,3,2] row_mask:0xf bank_mask:0xf bound_ctrl:1
	v_mov_b32_dpp v39, v37 quad_perm:[1,0,3,2] row_mask:0xf bank_mask:0xf bound_ctrl:1
	v_pk_fma_f32 v[102:103], v[72:73], v[102:103], v[106:107]
	v_pk_fma_f32 v[36:37], v[72:73], v[36:37], v[38:39]
	s_nop 0
	v_mov_b32_dpp v106, v102 quad_perm:[2,3,0,1] row_mask:0xf bank_mask:0xf bound_ctrl:1
	v_mov_b32_dpp v107, v103 quad_perm:[2,3,0,1] row_mask:0xf bank_mask:0xf bound_ctrl:1
	v_mov_b32_dpp v38, v36 quad_perm:[2,3,0,1] row_mask:0xf bank_mask:0xf bound_ctrl:1
	v_mov_b32_dpp v39, v37 quad_perm:[2,3,0,1] row_mask:0xf bank_mask:0xf bound_ctrl:1
	v_pk_fma_f32 v[102:103], v[70:71], v[102:103], v[106:107]
	v_pk_fma_f32 v[36:37], v[70:71], v[36:37], v[38:39]
	v_mov_b32_e32 v106, v102
	v_mov_b32_e32 v107, v103
	v_mov_b32_e32 v38, v36
	v_mov_b32_e32 v39, v37
	v_mov_b32_dpp v106, v106 row_shl:4 row_mask:0xf bank_mask:0x5
	v_mov_b32_dpp v107, v107 row_shl:4 row_mask:0xf bank_mask:0x5
	v_mov_b32_dpp v38, v38 row_shl:4 row_mask:0xf bank_mask:0x5
	v_mov_b32_dpp v39, v39 row_shl:4 row_mask:0xf bank_mask:0x5
	v_mov_b32_dpp v106, v102 row_shr:4 row_mask:0xf bank_mask:0xa
	v_mov_b32_dpp v107, v103 row_shr:4 row_mask:0xf bank_mask:0xa
	v_mov_b32_dpp v38, v36 row_shr:4 row_mask:0xf bank_mask:0xa
	v_mov_b32_dpp v39, v37 row_shr:4 row_mask:0xf bank_mask:0xa
	v_pk_fma_f32 v[102:103], v[68:69], v[102:103], v[106:107]
	v_pk_fma_f32 v[36:37], v[68:69], v[36:37], v[38:39]
; __device__ __forceinline__ float xlane1(float t) { return dpp_mov<0xB1, 0xF, true>(0.f, t); }
; __device__ __forceinline__ float xlane2(float t) { return dpp_mov<0x4E, 0xF, true>(0.f, t); }
; __device__ __forceinline__ float xlane4(float t) { const float r = dpp_mov<0x104, 0x5, false>(t, t); return dpp_mov<0x114, 0xA, false>(r, t); }
; __device__ __forceinline__ float xlane8(float t) { return dpp_mov<0x128, 0xF, true>(0.f, t); }
; __device__ __forceinline__ f32x4 rot64(f32x4 t, const RotSigns sg) {
;     { const float p0 = t.x + t.y, p1 = t.x - t.y, p2 = t.z + t.w, p3 = t.z - t.w; t = (f32x4){p0 + p2, p1 + p3, p0 - p2, p1 - p3}; }
;     t = (f32x4){__builtin_fmaf(sg.s1, t.x, xlane1(t.x)), __builtin_fmaf(sg.s1, t.y, xlane1(t.y)), __builtin_fmaf(sg.s1, t.z, xlane1(t.z)), __builtin_fmaf(sg.s1, t.w, xlane1(t.w))};
;     t = (f32x4){__builtin_fmaf(sg.s2, t.x, xlane2(t.x)), __builtin_fmaf(sg.s2, t.y, xlane2(t.y)), __builtin_fmaf(sg.s2, t.z, xlane2(t.z)), __builtin_fmaf(sg.s2, t.w, xlane2(t.w))};
;     t = (f32x4){__builtin_fmaf(sg.s4, t.x, xlane4(t.x)), __builtin_fmaf(sg.s4, t.y, xlane4(t.y)), __builtin_fmaf(sg.s4, t.z, xlane4(t.z)), __builtin_fmaf(sg.s4, t.w, xlane4(t.w))};
;     t = (f32x4){__builtin_fmaf(sg.s8, t.x, xlane8(t.x)), __builtin_fmaf(sg.s8, t.y, xlane8(t.y)), __builtin_fmaf(sg.s8, t.z, xlane8(t.z)), __builtin_fmaf(sg.s8, t.w, xlane8(t.w))};
;     return t * 0.125f;
; }
; __device__ __forceinline__ unsigned pack_q8m(float a, float b, float c, float d, float inv) {
;     const unsigned ua = __float_as_uint(__builtin_fmaf(a, inv, 12582912.0f)), ub = __float_as_uint(__builtin_fmaf(b, inv, 12582912.0f));
;     const unsigned uc = __float_as_uint(__builtin_fmaf(c, inv, 12582912.0f)), ud = __float_as_uint(__builtin_fmaf(d, inv, 12582912.0f));
;     return __builtin_amdgcn_perm(__builtin_amdgcn_perm(ud, uc, 0x0c0c0400u), __builtin_amdgcn_perm(ub, ua, 0x0c0c0400u), 0x05040100u);
; }
; __device__ __forceinline__ void rotq_row(f32x4 (&v)[16], unsigned* q8row, float* rsp, int lane) {
;     float am = 0.f; const RotSigns sg = rot_signs(lane);
; #pragma unroll
;     for (int j = 0; j < 16; ++j) { v[j] = rot64(v[j], sg);
;         am = fmaxf(fmaxf(am, fmaxf(fabsf(v[j].x), fabsf(v[j].y))), fmaxf(fabsf(v[j].z), fabsf(v[j].w))); }
	s_nop 0
	v_mov_b32_dpp v106, v102 row_ror:8 row_mask:0xf bank_mask:0xf bound_ctrl:1
	v_mov_b32_dpp v107, v103 row_ror:8 row_mask:0xf bank_mask:0xf bound_ctrl:1
	v_mov_b32_dpp v38, v36 row_ror:8 row_mask:0xf bank_mask:0xf bound_ctrl:1
	v_mov_b32_dpp v39, v37 row_ror:8 row_mask:0xf bank_mask:0xf bound_ctrl:1
	v_pk_fma_f32 v[100:101], v[66:67], v[102:103], v[106:107]
	v_pk_fma_f32 v[36:37], v[88:89], v[36:37], v[38:39]
	v_pk_mul_f32 v[38:39], v[100:101], s[40:41] op_sel_hi:[1,0]
	v_pk_mul_f32 v[36:37], v[36:37], s[40:41] op_sel_hi:[1,0]
	v_max_f32_e64 v100, |v38|, |v39|
	v_max_f32_e64 v101, |v36|, |v37|
	v_max3_f32 v5, v5, v100, v101
	v_mov_b32_e32 v100, v30
	v_mov_b32_e32 v101, v28
	v_mov_b32_e32 v102, v31
	v_mov_b32_e32 v103, v29
	v_pk_add_f32 v[104:105], v[100:101], v[102:103]
	v_pk_add_f32 v[100:101], v[100:101], v[102:103] neg_lo:[0,1] neg_hi:[0,1]
	v_pk_mov_b32 v[102:103], v[28:29], v[30:31] op_sel:[1,0]
	v_mov_b32_e32 v29, v31
	v_pk_add_f32 v[30:31], v[102:103], v[28:29]
	v_pk_add_f32 v[28:29], v[102:103], v[28:29] neg_lo:[0,1] neg_hi:[0,1]
	v_mov_b32_e32 v105, v101
	v_mov_b32_e32 v31, v29
	v_pk_add_f32 v[102:103], v[30:31], v[104:105]
	v_mov_b32_e32 v31, v101
	v_mov_b32_e32 v105, v29
	v_pk_add_f32 v[28:29], v[30:31], v[104:105] neg_lo:[0,1] neg_hi:[0,1]
	v_mov_b32_dpp v106, v102 quad_perm:[1,0,3,2] row_mask:0xf bank_mask:0xf bound_ctrl:1
	v_mov_b32_dpp v107, v103 quad_perm:[1,0,3,2] row_mask:0xf bank_mask:0xf bound_ctrl:1
	v_mov_b32_dpp v30, v28 quad_perm:[1,0,3,2] row_mask:0xf bank_mask:0xf bound_ctrl:1
	v_mov_b32_dpp v31, v29 quad_perm:[1,0,3,2] row_mask:0xf bank_mask:0xf bound_ctrl:1
	v_pk_fma_f32 v[102:103], v[72:73], v[102:103], v[106:107]
	v_pk_fma_f32 v[28:29], v[72:73], v[28:29], v[30:31]
	s_nop 0
	v_mov_b32_dpp v106, v102 quad_perm:[2,3,0,1] row_mask:0xf bank_mask:0xf bound_ctrl:1
	v_mov_b32_dpp v107, v103 quad_perm:[2,3,0,1] row_mask:0xf bank_mask:0xf bound_ctrl:1
	v_mov_b32_dpp v30, v28 quad_perm:[2,3,0,1] row_mask:0xf bank_mask:0xf bound_ctrl:1
	v_mov_b32_dpp v31, v29 quad_perm:[2,3,0,1] row_mask:0xf bank_mask:0xf bound_ctrl:1
	v_pk_fma_f32 v[102:103], v[70:71], v[102:103], v[106:107]
	v_pk_fma_f32 v[28:29], v[70:71], v[28:29], v[30:31]
	v_mov_b32_e32 v106, v102
	v_mov_b32_e32 v107, v103
	v_mov_b32_e32 v30, v28
	v_mov_b32_e32 v31, v29
	v_mov_b32_dpp v106, v106 row_shl:4 row_mask:0xf bank_mask:0x5
	v_mov_b32_dpp v107, v107 row_shl:4 row_mask:0xf bank_mask:0x5
	v_mov_b32_dpp v30, v30 row_shl:4 row_mask:0xf bank_mask:0x5
	v_mov_b32_dpp v31, v31 row_shl:4 row_mask:0xf bank_mask:0x5
	v_mov_b32_dpp v106, v102 row_shr:4 row_mask:0xf bank_mask:0xa
	v_mov_b32_dpp v107, v103 row_shr:4 row_mask:0xf bank_mask:0xa
	v_mov_b32_dpp v30, v28 row_shr:4 row_mask:0xf bank_mask:0xa
	v_mov_b32_dpp v31, v29 row_shr:4 row_mask:0xf bank_mask:0xa
	v_pk_fma_f32 v[102:103], v[68:69], v[102:103], v[106:107]
	v_pk_fma_f32 v[28:29], v[68:69], v[28:29], v[30:31]
	s_nop 0
	v_mov_b32_dpp v106, v102 row_ror:8 row_mask:0xf bank_mask:0xf bound_ctrl:1
	v_mov_b32_dpp v107, v103 row_ror:8 row_mask:0xf bank_mask:0xf bound_ctrl:1
	v_mov_b32_dpp v30, v28 row_ror:8 row_mask:0xf bank_mask:0xf bound_ctrl:1
	v_mov_b32_dpp v31, v29 row_ror:8 row_mask:0xf bank_mask:0xf bound_ctrl:1
	v_pk_fma_f32 v[100:101], v[66:67], v[102:103], v[106:107]
	v_pk_fma_f32 v[28:29], v[88:89], v[28:29], v[30:31]
	v_pk_mul_f32 v[30:31], v[100:101], s[40:41] op_sel_hi:[1,0]
	v_pk_mul_f32 v[28:29], v[28:29], s[40:41] op_sel_hi:[1,0]
	v_max_f32_e64 v100, |v30|, |v31|
	v_max_f32_e64 v101, |v28|, |v29|
	v_max3_f32 v5, v5, v100, v101
	v_mov_b32_e32 v100, v22
	v_mov_b32_e32 v101, v20
	v_mov_b32_e32 v102, v23
	v_mov_b32_e32 v103, v21
	v_pk_add_f32 v[104:105], v[100:101], v[102:103]
	v_pk_add_f32 v[100:101], v[100:101], v[102:103] neg_lo:[0,1] neg_hi:[0,1]
	v_pk_mov_b32 v[102:103], v[20:21], v[22:23] op_sel:[1,0]
	v_mov_b32_e32 v21, v23
	v_pk_add_f32 v[22:23], v[102:103], v[20:21]
	v_pk_add_f32 v[20:21], v[102:103], v[20:21] neg_lo:[0,1] neg_hi:[0,1]
	v_mov_b32_e32 v105, v101
	v_mov_b32_e32 v23, v21
	v_pk_add_f32 v[102:103], v[22:23], v[104:105]
	v_mov_b32_e32 v23, v101
	v_mov_b32_e32 v105, v21
	v_pk_add_f32 v[20:21], v[22:23], v[104:105] neg_lo:[0,1] neg_hi:[0,1]
	v_mov_b32_dpp v106, v102 quad_perm:[1,0,3,2] row_mask:0xf bank_mask:0xf bound_ctrl:1
	v_mov_b32_dpp v107, v103 quad_perm:[1,0,3,2] row_mask:0xf bank_mask:0xf bound_ctrl:1
	v_mov_b32_dpp v22, v20 quad_perm:[1,0,3,2] row_mask:0xf bank_mask:0xf bound_ctrl:1
	v_mov_b32_dpp v23, v21 quad_perm:[1,0,3,2] row_mask:0xf bank_mask:0xf bound_ctrl:1
	v_pk_fma_f32 v[102:103], v[72:73], v[102:103], v[106:107]
	v_pk_fma_f32 v[20:21], v[72:73], v[20:21], v[22:23]
	s_nop 0
	v_mov_b32_dpp v106, v102 quad_perm:[2,3,0,1] row_mask:0xf bank_mask:0xf bound_ctrl:1
	v_mov_b32_dpp v107, v103 quad_perm:[2,3,0,1] row_mask:0xf bank_mask:0xf bound_ctrl:1
	v_mov_b32_dpp v22, v20 quad_perm:[2,3,0,1] row_mask:0xf bank_mask:0xf bound_ctrl:1
	v_mov_b32_dpp v23, v21 quad_perm:[2,3,0,1] row_mask:0xf bank_mask:0xf bound_ctrl:1
	v_pk_fma_f32 v[102:103], v[70:71], v[102:103], v[106:107]
	v_pk_fma_f32 v[20:21], v[70:71], v[20:21], v[22:23]
	v_mov_b32_e32 v106, v102
	v_mov_b32_e32 v107, v103
	v_mov_b32_e32 v22, v20
	v_mov_b32_e32 v23, v21
	v_mov_b32_dpp v106, v106 row_shl:4 row_mask:0xf bank_mask:0x5
	v_mov_b32_dpp v107, v107 row_shl:4 row_mask:0xf bank_mask:0x5
	v_mov_b32_dpp v22, v22 row_shl:4 row_mask:0xf bank_mask:0x5
	v_mov_b32_dpp v23, v23 row_shl:4 row_mask:0xf bank_mask:0x5
	v_mov_b32_dpp v106, v102 row_shr:4 row_mask:0xf bank_mask:0xa
	v_mov_b32_dpp v107, v103 row_shr:4 row_mask:0xf bank_mask:0xa
	v_mov_b32_dpp v22, v20 row_shr:4 row_mask:0xf bank_mask:0xa
; __device__ __forceinline__ float xlane1(float t) { return dpp_mov<0xB1, 0xF, true>(0.f, t); }
; __device__ __forceinline__ float xlane2(float t) { return dpp_mov<0x4E, 0xF, true>(0.f, t); }
; __device__ __forceinline__ float xlane4(float t) { const float r = dpp_mov<0x104, 0x5, false>(t, t); return dpp_mov<0x114, 0xA, false>(r, t); }
; __device__ __forceinline__ float xlane8(float t) { return dpp_mov<0x128, 0xF, true>(0.f, t); }
; __device__ __forceinline__ f32x4 rot64(f32x4 t, const RotSigns sg) {
;     { const float p0 = t.x + t.y, p1 = t.x - t.y, p2 = t.z + t.w, p3 = t.z - t.w; t = (f32x4){p0 + p2, p1 + p3, p0 - p2, p1 - p3}; }
;     t = (f32x4){__builtin_fmaf(sg.s1, t.x, xlane1(t.x)), __builtin_fmaf(sg.s1, t.y, xlane1(t.y)), __builtin_fmaf(sg.s1, t.z, xlane1(t.z)), __builtin_fmaf(sg.s1, t.w, xlane1(t.w))};
;     t = (f32x4){__builtin_fmaf(sg.s2, t.x, xlane2(t.x)), __builtin_fmaf(sg.s2, t.y, xlane2(t.y)), __builtin_fmaf(sg.s2, t.z, xlane2(t.z)), __builtin_fmaf(sg.s2, t.w, xlane2(t.w))};
;     t = (f32x4){__builtin_fmaf(sg.s4, t.x, xlane4(t.x)), __builtin_fmaf(sg.s4, t.y, xlane4(t.y)), __builtin_fmaf(sg.s4, t.z, xlane4(t.z)), __builtin_fmaf(sg.s4, t.w, xlane4(t.w))};
;     t = (f32x4){__builtin_fmaf(sg.s8, t.x, xlane8(t.x)), __builtin_fmaf(sg.s8, t.y, xlane8(t.y)), __builtin_fmaf(sg.s8, t.z, xlane8(t.z)), __builtin_fmaf(sg.s8, t.w, xlane8(t.w))};
;     return t * 0.125f;
; }
; __device__ __forceinline__ unsigned pack_q8m(float a, float b, float c, float d, float inv) {
;     const unsigned ua = __float_as_uint(__builtin_fmaf(a, inv, 12582912.0f)), ub = __float_as_uint(__builtin_fmaf(b, inv, 12582912.0f));
;     const unsigned uc = __float_as_uint(__builtin_fmaf(c, inv, 12582912.0f)), ud = __float_as_uint(__builtin_fmaf(d, inv, 12582912.0f));
;     return __builtin_amdgcn_perm(__builtin_amdgcn_perm(ud, uc, 0x0c0c0400u), __builtin_amdgcn_perm(ub, ua, 0x0c0c0400u), 0x05040100u);
; }
; __device__ __forceinline__ void rotq_row(f32x4 (&v)[16], unsigned* q8row, float* rsp, int lane) {
;     float am = 0.f; const RotSigns sg = rot_signs(lane);
; #pragma unroll
;     for (int j = 0; j < 16; ++j) { v[j] = rot64(v[j], sg);
;         am = fmaxf(fmaxf(am, fmaxf(fabsf(v[j].x), fabsf(v[j].y))), fmaxf(fabsf(v[j].z), fabsf(v[j].w))); }
; #pragma unroll
;     for (int o = 1; o < 64; o <<= 1) am = fmaxf(am, __shfl_xor(am, o));
	v_mov_b32_dpp v23, v21 row_shr:4 row_mask:0xf bank_mask:0xa
	v_pk_fma_f32 v[102:103], v[68:69], v[102:103], v[106:107]
	v_pk_fma_f32 v[20:21], v[68:69], v[20:21], v[22:23]
	s_nop 0
	v_mov_b32_dpp v106, v102 row_ror:8 row_mask:0xf bank_mask:0xf bound_ctrl:1
	v_mov_b32_dpp v107, v103 row_ror:8 row_mask:0xf bank_mask:0xf bound_ctrl:1
	v_mov_b32_dpp v22, v20 row_ror:8 row_mask:0xf bank_mask:0xf bound_ctrl:1
	v_mov_b32_dpp v23, v21 row_ror:8 row_mask:0xf bank_mask:0xf bound_ctrl:1
	v_pk_fma_f32 v[100:101], v[66:67], v[102:103], v[106:107]
	v_pk_fma_f32 v[20:21], v[88:89], v[20:21], v[22:23]
	v_pk_mul_f32 v[22:23], v[100:101], s[40:41] op_sel_hi:[1,0]
	v_pk_mul_f32 v[20:21], v[20:21], s[40:41] op_sel_hi:[1,0]
	v_max_f32_e64 v100, |v22|, |v23|
	v_max_f32_e64 v101, |v20|, |v21|
	v_max3_f32 v5, v5, v100, v101
	v_mov_b32_e32 v100, v18
	v_mov_b32_e32 v101, v16
	v_mov_b32_e32 v102, v19
	v_mov_b32_e32 v103, v17
	v_pk_add_f32 v[104:105], v[100:101], v[102:103]
	v_pk_add_f32 v[100:101], v[100:101], v[102:103] neg_lo:[0,1] neg_hi:[0,1]
	v_pk_mov_b32 v[102:103], v[16:17], v[18:19] op_sel:[1,0]
	v_mov_b32_e32 v17, v19
	v_pk_add_f32 v[18:19], v[102:103], v[16:17]
	v_pk_add_f32 v[16:17], v[102:103], v[16:17] neg_lo:[0,1] neg_hi:[0,1]
	v_mov_b32_e32 v105, v101
	v_mov_b32_e32 v19, v17
	v_pk_add_f32 v[102:103], v[18:19], v[104:105]
	v_mov_b32_e32 v19, v101
	v_mov_b32_e32 v105, v17
	v_pk_add_f32 v[16:17], v[18:19], v[104:105] neg_lo:[0,1] neg_hi:[0,1]
	v_mov_b32_dpp v106, v102 quad_perm:[1,0,3,2] row_mask:0xf bank_mask:0xf bound_ctrl:1
	v_mov_b32_dpp v107, v103 quad_perm:[1,0,3,2] row_mask:0xf bank_mask:0xf bound_ctrl:1
	v_mov_b32_dpp v18, v16 quad_perm:[1,0,3,2] row_mask:0xf bank_mask:0xf bound_ctrl:1
	v_mov_b32_dpp v19, v17 quad_perm:[1,0,3,2] row_mask:0xf bank_mask:0xf bound_ctrl:1
	v_pk_fma_f32 v[102:103], v[72:73], v[102:103], v[106:107]
	v_pk_fma_f32 v[16:17], v[72:73], v[16:17], v[18:19]
	s_nop 0
	v_mov_b32_dpp v106, v102 quad_perm:[2,3,0,1] row_mask:0xf bank_mask:0xf bound_ctrl:1
	v_mov_b32_dpp v107, v103 quad_perm:[2,3,0,1] row_mask:0xf bank_mask:0xf bound_ctrl:1
	v_mov_b32_dpp v18, v16 quad_perm:[2,3,0,1] row_mask:0xf bank_mask:0xf bound_ctrl:1
	v_mov_b32_dpp v19, v17 quad_perm:[2,3,0,1] row_mask:0xf bank_mask:0xf bound_ctrl:1
	v_pk_fma_f32 v[102:103], v[70:71], v[102:103], v[106:107]
	v_pk_fma_f32 v[16:17], v[70:71], v[16:17], v[18:19]
	v_mov_b32_e32 v106, v102
	v_mov_b32_e32 v107, v103
	v_mov_b32_e32 v18, v16
	v_mov_b32_e32 v19, v17
	v_mov_b32_dpp v106, v106 row_shl:4 row_mask:0xf bank_mask:0x5
	v_mov_b32_dpp v107, v107 row_shl:4 row_mask:0xf bank_mask:0x5
	v_mov_b32_dpp v18, v18 row_shl:4 row_mask:0xf bank_mask:0x5
	v_mov_b32_dpp v19, v19 row_shl:4 row_mask:0xf bank_mask:0x5
	v_mov_b32_dpp v106, v102 row_shr:4 row_mask:0xf bank_mask:0xa
	v_mov_b32_dpp v107, v103 row_shr:4 row_mask:0xf bank_mask:0xa
	v_mov_b32_dpp v18, v16 row_shr:4 row_mask:0xf bank_mask:0xa
	v_mov_b32_dpp v19, v17 row_shr:4 row_mask:0xf bank_mask:0xa
	v_pk_fma_f32 v[102:103], v[68:69], v[102:103], v[106:107]
	v_pk_fma_f32 v[16:17], v[68:69], v[16:17], v[18:19]
	s_nop 0
	v_mov_b32_dpp v106, v102 row_ror:8 row_mask:0xf bank_mask:0xf bound_ctrl:1
	v_mov_b32_dpp v107, v103 row_ror:8 row_mask:0xf bank_mask:0xf bound_ctrl:1
	v_mov_b32_dpp v18, v16 row_ror:8 row_mask:0xf bank_mask:0xf bound_ctrl:1
	v_mov_b32_dpp v19, v17 row_ror:8 row_mask:0xf bank_mask:0xf bound_ctrl:1
	v_pk_fma_f32 v[100:101], v[66:67], v[102:103], v[106:107]
	v_pk_fma_f32 v[16:17], v[88:89], v[16:17], v[18:19]
	v_pk_mul_f32 v[18:19], v[100:101], s[40:41] op_sel_hi:[1,0]
	v_pk_mul_f32 v[16:17], v[16:17], s[40:41] op_sel_hi:[1,0]
	v_max_f32_e64 v100, |v18|, |v19|
	v_max_f32_e64 v101, |v16|, |v17|
	v_max3_f32 v5, v5, v100, v101
	v_mov_b32_e32 v100, v2
	v_mov_b32_e32 v101, v10
	v_mov_b32_e32 v102, v3
	v_mov_b32_e32 v103, v11
	v_pk_add_f32 v[104:105], v[100:101], v[102:103]
	v_pk_add_f32 v[100:101], v[100:101], v[102:103] neg_lo:[0,1] neg_hi:[0,1]
	v_pk_mov_b32 v[102:103], v[10:11], v[2:3] op_sel:[1,0]
	v_mov_b32_e32 v11, v3
	v_pk_add_f32 v[106:107], v[102:103], v[10:11]
	v_pk_add_f32 v[10:11], v[102:103], v[10:11] neg_lo:[0,1] neg_hi:[0,1]
	v_mov_b32_e32 v105, v101
	v_mov_b32_e32 v107, v11
	v_pk_add_f32 v[102:103], v[106:107], v[104:105]
	v_mov_b32_e32 v107, v101
	v_mov_b32_e32 v105, v11
	v_pk_add_f32 v[10:11], v[106:107], v[104:105] neg_lo:[0,1] neg_hi:[0,1]
	v_mov_b32_dpp v108, v102 quad_perm:[1,0,3,2] row_mask:0xf bank_mask:0xf bound_ctrl:1
	v_mov_b32_dpp v109, v103 quad_perm:[1,0,3,2] row_mask:0xf bank_mask:0xf bound_ctrl:1
	v_mov_b32_dpp v100, v10 quad_perm:[1,0,3,2] row_mask:0xf bank_mask:0xf bound_ctrl:1
	v_mov_b32_dpp v101, v11 quad_perm:[1,0,3,2] row_mask:0xf bank_mask:0xf bound_ctrl:1
	v_pk_fma_f32 v[102:103], v[72:73], v[102:103], v[108:109]
	v_pk_fma_f32 v[10:11], v[72:73], v[10:11], v[100:101]
	s_nop 0
	v_mov_b32_dpp v108, v102 quad_perm:[2,3,0,1] row_mask:0xf bank_mask:0xf bound_ctrl:1
	v_mov_b32_dpp v109, v103 quad_perm:[2,3,0,1] row_mask:0xf bank_mask:0xf bound_ctrl:1
	v_mov_b32_dpp v100, v10 quad_perm:[2,3,0,1] row_mask:0xf bank_mask:0xf bound_ctrl:1
	v_mov_b32_dpp v101, v11 quad_perm:[2,3,0,1] row_mask:0xf bank_mask:0xf bound_ctrl:1
	v_pk_fma_f32 v[102:103], v[70:71], v[102:103], v[108:109]
	v_pk_fma_f32 v[10:11], v[70:71], v[10:11], v[100:101]
	v_mov_b32_e32 v108, v102
	v_mov_b32_e32 v109, v103
	v_mov_b32_e32 v100, v10
	v_mov_b32_e32 v101, v11
	v_mov_b32_dpp v108, v108 row_shl:4 row_mask:0xf bank_mask:0x5
	v_mov_b32_dpp v109, v109 row_shl:4 row_mask:0xf bank_mask:0x5
	v_mov_b32_dpp v100, v100 row_shl:4 row_mask:0xf bank_mask:0x5
	v_mov_b32_dpp v101, v101 row_shl:4 row_mask:0xf bank_mask:0x5
	v_mov_b32_dpp v108, v102 row_shr:4 row_mask:0xf bank_mask:0xa
	v_mov_b32_dpp v109, v103 row_shr:4 row_mask:0xf bank_mask:0xa
	v_mov_b32_dpp v100, v10 row_shr:4 row_mask:0xf bank_mask:0xa
	v_mov_b32_dpp v101, v11 row_shr:4 row_mask:0xf bank_mask:0xa
	v_pk_fma_f32 v[102:103], v[68:69], v[102:103], v[108:109]
	v_pk_fma_f32 v[10:11], v[68:69], v[10:11], v[100:101]
	s_nop 0
	v_mov_b32_dpp v108, v102 row_ror:8 row_mask:0xf bank_mask:0xf bound_ctrl:1
	v_mov_b32_dpp v109, v103 row_ror:8 row_mask:0xf bank_mask:0xf bound_ctrl:1
	v_mov_b32_dpp v100, v10 row_ror:8 row_mask:0xf bank_mask:0xf bound_ctrl:1
	v_mov_b32_dpp v101, v11 row_ror:8 row_mask:0xf bank_mask:0xf bound_ctrl:1
	v_pk_fma_f32 v[102:103], v[66:67], v[102:103], v[108:109]
	v_pk_fma_f32 v[10:11], v[88:89], v[10:11], v[100:101]
	v_pk_mul_f32 v[102:103], v[102:103], s[40:41] op_sel_hi:[1,0]
	v_pk_mul_f32 v[100:101], v[10:11], s[40:41] op_sel_hi:[1,0]
	v_max_f32_e64 v10, |v102|, |v103|
	v_max_f32_e64 v11, |v100|, |v101|
	v_max3_f32 v5, v5, v10, v11
	ds_bpermute_b32 v10, v1, v5
	s_waitcnt lgkmcnt(0)
; __device__ __forceinline__ void rotq_row(f32x4 (&v)[16], unsigned* q8row, float* rsp, int lane) {
;     ...
;         am = fmaxf(fmaxf(am, fmaxf(fabsf(v[j].x), fabsf(v[j].y))), fmaxf(fabsf(v[j].z), fabsf(v[j].w))); }
; #pragma unroll
;     for (int o = 1; o < 64; o <<= 1) am = fmaxf(am, __shfl_xor(am, o));
;     am = fmaxf(am, 1e-30f); const float qi = 127.0f / am;
; #pragma unroll
;     for (int j = 0; j < 16; ++j) q8row[lane + 64 * j] = pack_q8m(v[j].x, v[j].y, v[j].z, v[j].w, qi);
;     if (lane == 0) *rsp = am * (1.0f / 127.0f);
; }
	v_max_f32_e32 v10, v10, v10
	v_max_f32_e32 v5, v5, v10
	ds_bpermute_b32 v10, v121, v5
	s_waitcnt lgkmcnt(0)
	v_max_f32_e32 v10, v10, v10
	v_max_f32_e32 v5, v5, v10
	ds_bpermute_b32 v10, v122, v5
	s_waitcnt lgkmcnt(0)
	v_max_f32_e32 v10, v10, v10
	v_max_f32_e32 v5, v5, v10
	ds_bpermute_b32 v10, v123, v5
	s_waitcnt lgkmcnt(0)
	v_max_f32_e32 v10, v10, v10
	v_max_f32_e32 v5, v5, v10
	ds_bpermute_b32 v10, v124, v5
	s_waitcnt lgkmcnt(0)
	v_max_f32_e32 v10, v10, v10
	v_max_f32_e32 v5, v5, v10
	ds_bpermute_b32 v10, v125, v5
	s_waitcnt lgkmcnt(0)
	v_max3_f32 v10, v5, v10, s23
	v_div_scale_f32 v11, s[0:1], v10, v10, s24
	v_rcp_f32_e32 v104, v11
	v_cvt_pk_bf16_f32 v5, v2, v3
	global_store_dwordx2 v[62:63], v[4:5], off offset:3584
	v_fma_f32 v2, -v11, v104, 1.0
	v_fmac_f32_e32 v104, v2, v104
	v_div_scale_f32 v2, vcc, s24, v10, s24
	v_mul_f32_e32 v3, v2, v104
	v_fma_f32 v4, -v11, v3, v2
	v_fmac_f32_e32 v3, v4, v104
	v_fma_f32 v2, -v11, v3, v2
	v_div_fmas_f32 v2, v2, v104, v3
	v_div_fixup_f32 v4, v2, v10, s24
	v_fmaak_f32 v2, v8, v4, 0x4b400000
	v_fmaak_f32 v3, v9, v4, 0x4b400000
	v_fmaak_f32 v5, v6, v4, 0x4b400000
	v_fmaak_f32 v6, v7, v4, 0x4b400000
	v_perm_b32 v5, v6, v5, s25
	v_perm_b32 v2, v3, v2, s25
	v_perm_b32 v5, v5, v2, s26
	v_lshl_add_u64 v[2:3], s[36:37], 0, v[92:93]
	global_store_dword v[2:3], v5, off offset:-2048
	v_fmaak_f32 v5, v14, v4, 0x4b400000
	v_fmaak_f32 v6, v15, v4, 0x4b400000
	v_fmaak_f32 v7, v12, v4, 0x4b400000
	v_fmaak_f32 v8, v13, v4, 0x4b400000
	v_perm_b32 v7, v8, v7, s25
	v_perm_b32 v5, v6, v5, s25
	v_perm_b32 v5, v7, v5, s26
	global_store_dword v[2:3], v5, off offset:-1792
	v_fmaak_f32 v5, v26, v4, 0x4b400000
	v_fmaak_f32 v6, v27, v4, 0x4b400000
	v_fmaak_f32 v7, v24, v4, 0x4b400000
	v_fmaak_f32 v8, v25, v4, 0x4b400000
	v_perm_b32 v7, v8, v7, s25
	v_perm_b32 v5, v6, v5, s25
	v_perm_b32 v5, v7, v5, s26
	global_store_dword v[2:3], v5, off offset:-1536
	v_fmaak_f32 v5, v34, v4, 0x4b400000
	v_fmaak_f32 v6, v35, v4, 0x4b400000
	v_fmaak_f32 v7, v32, v4, 0x4b400000
	v_fmaak_f32 v8, v33, v4, 0x4b400000
	v_perm_b32 v7, v8, v7, s25
	v_perm_b32 v5, v6, v5, s25
	v_perm_b32 v5, v7, v5, s26
	global_store_dword v[2:3], v5, off offset:-1280
	v_fmaak_f32 v5, v42, v4, 0x4b400000
	v_fmaak_f32 v6, v43, v4, 0x4b400000
	v_fmaak_f32 v7, v40, v4, 0x4b400000
	v_fmaak_f32 v8, v41, v4, 0x4b400000
	v_perm_b32 v7, v8, v7, s25
	v_perm_b32 v5, v6, v5, s25
	v_perm_b32 v5, v7, v5, s26
	global_store_dword v[2:3], v5, off offset:-1024
	v_fmaak_f32 v5, v50, v4, 0x4b400000
	v_fmaak_f32 v6, v51, v4, 0x4b400000
	v_fmaak_f32 v7, v48, v4, 0x4b400000
	v_fmaak_f32 v8, v49, v4, 0x4b400000
	v_perm_b32 v7, v8, v7, s25
	v_perm_b32 v5, v6, v5, s25
	v_perm_b32 v5, v7, v5, s26
	global_store_dword v[2:3], v5, off offset:-768
	v_fmaak_f32 v5, v64, v4, 0x4b400000
	v_fmaak_f32 v6, v65, v4, 0x4b400000
	v_fmaak_f32 v7, v60, v4, 0x4b400000
	v_fmaak_f32 v8, v61, v4, 0x4b400000
	v_perm_b32 v7, v8, v7, s25
	v_perm_b32 v5, v6, v5, s25
	v_perm_b32 v5, v7, v5, s26
	global_store_dword v[2:3], v5, off offset:-512
	v_fmaak_f32 v5, v98, v4, 0x4b400000
	v_fmaak_f32 v6, v99, v4, 0x4b400000
	v_fmaak_f32 v7, v96, v4, 0x4b400000
	v_fmaak_f32 v8, v97, v4, 0x4b400000
	v_perm_b32 v7, v8, v7, s25
	v_perm_b32 v5, v6, v5, s25
	v_perm_b32 v5, v7, v5, s26
	global_store_dword v[2:3], v5, off offset:-256
	v_fmaak_f32 v5, v58, v4, 0x4b400000
	v_fmaak_f32 v6, v59, v4, 0x4b400000
	v_fmaak_f32 v7, v56, v4, 0x4b400000
	v_fmaak_f32 v8, v57, v4, 0x4b400000
	v_perm_b32 v7, v8, v7, s25
	v_perm_b32 v5, v6, v5, s25
	v_perm_b32 v5, v7, v5, s26
	global_store_dword v[2:3], v5, off
	v_fmaak_f32 v5, v54, v4, 0x4b400000
	v_fmaak_f32 v6, v55, v4, 0x4b400000
	v_fmaak_f32 v7, v52, v4, 0x4b400000
	v_fmaak_f32 v8, v53, v4, 0x4b400000
	v_perm_b32 v7, v8, v7, s25
	v_perm_b32 v5, v6, v5, s25
	v_perm_b32 v5, v7, v5, s26
	global_store_dword v[2:3], v5, off offset:256
	v_fmaak_f32 v5, v46, v4, 0x4b400000
	v_fmaak_f32 v6, v47, v4, 0x4b400000
	v_fmaak_f32 v7, v44, v4, 0x4b400000
	v_fmaak_f32 v8, v45, v4, 0x4b400000
	v_perm_b32 v7, v8, v7, s25
	v_perm_b32 v5, v6, v5, s25
	v_perm_b32 v5, v7, v5, s26
	global_store_dword v[2:3], v5, off offset:512
	v_fmaak_f32 v5, v38, v4, 0x4b400000
	v_fmaak_f32 v6, v39, v4, 0x4b400000
	v_fmaak_f32 v7, v36, v4, 0x4b400000
	v_fmaak_f32 v8, v37, v4, 0x4b400000
	v_perm_b32 v7, v8, v7, s25
	v_perm_b32 v5, v6, v5, s25
	v_perm_b32 v5, v7, v5, s26
	global_store_dword v[2:3], v5, off offset:768
	v_fmaak_f32 v5, v30, v4, 0x4b400000
	v_fmaak_f32 v6, v31, v4, 0x4b400000
	v_fmaak_f32 v7, v28, v4, 0x4b400000
	v_fmaak_f32 v8, v29, v4, 0x4b400000
	v_perm_b32 v7, v8, v7, s25
	v_perm_b32 v5, v6, v5, s25
	v_perm_b32 v5, v7, v5, s26
	global_store_dword v[2:3], v5, off offset:1024
	v_fmaak_f32 v5, v22, v4, 0x4b400000
	v_fmaak_f32 v6, v23, v4, 0x4b400000
	v_fmaak_f32 v7, v20, v4, 0x4b400000
	v_fmaak_f32 v8, v21, v4, 0x4b400000
	v_perm_b32 v7, v8, v7, s25
	v_perm_b32 v5, v6, v5, s25
	v_perm_b32 v5, v7, v5, s26
	global_store_dword v[2:3], v5, off offset:1280
	v_fmaak_f32 v5, v18, v4, 0x4b400000
	v_fmaak_f32 v6, v19, v4, 0x4b400000
	v_fmaak_f32 v7, v16, v4, 0x4b400000
	v_fmaak_f32 v8, v17, v4, 0x4b400000
	v_perm_b32 v7, v8, v7, s25
	v_perm_b32 v5, v6, v5, s25
	v_perm_b32 v5, v7, v5, s26
	global_store_dword v[2:3], v5, off offset:1536
	v_fmaak_f32 v5, v102, v4, 0x4b400000
	v_fmaak_f32 v6, v103, v4, 0x4b400000
	v_fmaak_f32 v7, v100, v4, 0x4b400000
	v_fmaak_f32 v4, v101, v4, 0x4b400000
	v_perm_b32 v4, v4, v7, s25
	v_perm_b32 v5, v6, v5, s25
	v_perm_b32 v4, v4, v5, s26
	global_store_dword v[2:3], v4, off offset:1792
	s_and_saveexec_b64 s[0:1], s[2:3]
	s_cbranch_execz .LBB0_150
	s_mov_b64 s[36:37], s[70:71]
	s_add_u32 s36, s36, s7
	v_mul_f32_e32 v2, 0x3c010204, v10
	s_addc_u32 s37, s37, s8
	global_store_dword v181, v2, s[36:37]
	s_branch .LBB0_150

; template <int W>
; __device__ __forceinline__ void conv_pool_chunk(const bf16* PROJ, bf16* XC, bf16* POOLED, const float* conv_w, const float* conv_b, int chunk, int ch0) {
;     float cw[4][4], cb[4];
; #pragma unroll
;     for (int k = 0; k < 4; ++k) { const f32x4 a = *(const f32x4*)(conv_w + k * D + ch0); cw[k][0] = a.x; cw[k][1] = a.y; cw[k][2] = a.z; cw[k][3] = a.w; }
;     { const f32x4 a = *(const f32x4*)(conv_b + ch0); cb[0] = a.x; cb[1] = a.y; cb[2] = a.z; cb[3] = a.w; }
;     const size_t row0 = (size_t)chunk * 64; const int t0 = (int)(row0 % SEQ);
;     const bf16* pr = PROJ + row0 * NIN + ch0;
; __global__ void __launch_bounds__(NWAVES * 64, 2) fwd_kernel(Args args) {
;     ...
;         for (int id = gw; id < (M / 64) * 16; id += NGW) { const int chunk = id >> 4, cgp = id & 15, ch0 = cgp * 256 + lane * 4;
;             switch (cgp >> 2) {
;                 case 0: conv_pool_chunk<2>(PROJ, XC, POOLED, conv_w, conv_b, chunk, ch0); break;
;                 case 1: conv_pool_chunk<4>(PROJ, XC, POOLED, conv_w, conv_b, chunk, ch0); break;
;                 case 2: conv_pool_chunk<8>(PROJ, XC, POOLED, conv_w, conv_b, chunk, ch0); break;
;                 default: conv_pool_chunk<16>(PROJ, XC, POOLED, conv_w, conv_b, chunk, ch0); break;
;             }
.LBB0_340:
	s_and_b32 s0, s69, 15
	v_lshl_or_b32 v24, s0, 8, v1
	v_readlane_b32 s36, v249, 9
	s_waitcnt vmcnt(0)
	v_lshlrev_b32_e32 v14, 2, v24
	v_mov_b32_e32 v15, v23
	v_readlane_b32 s50, v249, 23
	v_readlane_b32 s51, v249, 24
	v_readlane_b32 s38, v249, 11
	v_readlane_b32 s39, v249, 12
	v_lshl_add_u64 v[6:7], s[50:51], 0, v[14:15]
	v_add_co_u32_e32 v2, vcc, 0x4000, v6
	v_readlane_b32 s40, v249, 13
	s_nop 0
	v_addc_co_u32_e32 v3, vcc, 0, v7, vcc
	v_add_co_u32_e32 v8, vcc, 0x8000, v6
	v_readlane_b32 s41, v249, 14
	s_nop 0
	v_addc_co_u32_e32 v9, vcc, 0, v7, vcc
	v_add_co_u32_e32 v10, vcc, 0xc000, v6
	global_load_dwordx4 v[2:5], v[2:3], off nt
	s_nop 0
	global_load_dwordx4 v[18:21], v[8:9], off nt
	v_addc_co_u32_e32 v11, vcc, 0, v7, vcc
	global_load_dwordx4 v[6:9], v14, s[50:51] nt
	s_nop 0
	global_load_dwordx4 v[10:13], v[10:11], off nt
	s_nop 0
	global_load_dwordx4 v[14:17], v14, s[52:53] nt
	s_and_b32 s0, s80, 15
	s_ashr_i32 s38, s69, 4
	v_lshl_or_b32 v22, s0, 9, v154
	s_bfe_u32 s17, s69, 0x20002
	s_ashr_i32 s39, s38, 31
	s_lshl_b32 s0, s38, 6
	s_mul_i32 s4, s38, 0x280000
	v_readlane_b32 s40, v249, 60
	s_mul_hi_i32 s1, s38, 0x280000
	v_readlane_b32 s41, v249, 61
	s_add_u32 s4, s40, s4
	s_addc_u32 s5, s41, s1
	s_and_b32 s16, s0, 0x1fc0
	v_readlane_b32 s37, v249, 10
	v_readlane_b32 s42, v249, 15
	v_readlane_b32 s44, v249, 17
	v_readlane_b32 s45, v249, 18
	v_lshlrev_b32_e32 v24, 1, v24
	v_mov_b32_e32 v25, v23
	s_cmp_lg_u32 s16, 0
	v_lshl_add_u64 v[24:25], s[4:5], 0, v[24:25]
	s_cselect_b64 s[44:45], -1, 0
	s_cmp_lt_i32 s17, 2
	s_mov_b64 s[0:1], -1
	s_mov_b32 s36, 0xa000
	s_mov_b32 s37, 0xe000
	s_mov_b32 s42, 0x14000
	v_readlane_b32 s43, v249, 16
	v_readlane_b32 s46, v249, 19
	v_readlane_b32 s47, v249, 20
	v_readlane_b32 s48, v249, 21
	v_readlane_b32 s49, v249, 22
	s_cbranch_scc1 .LBB0_355
	s_mov_b32 s43, s69
	s_cmp_gt_i32 s17, 2
	s_cbranch_scc0 .LBB0_348
	s_andn2_b64 vcc, exec, s[44:45]
	s_mov_b32 s68, 0
	s_cbranch_vccnz .LBB0_344
; __device__ __forceinline__ void unpack4(const v2u q, float (&f)[4]) { f[0] = bf_lo(q.x); f[1] = bf_hi(q.x); f[2] = bf_lo(q.y); f[3] = bf_hi(q.y); }
; template <int W>
; __device__ __forceinline__ void conv_pool_chunk(const bf16* PROJ, bf16* XC, bf16* POOLED, const float* conv_w, const float* conv_b, int chunk, int ch0) {
;     ...
;     if (t0 > 0) {
; #pragma unroll
;         for (int q = 1; q <= 3; ++q) { const v2u x = *(const v2u*)(pr - (ptrdiff_t)q * NIN); unpack4(x, cx[(64 - q) & 3]); }
; #pragma unroll
;         for (int q = 1; q < W; ++q) { const v2u x = *(const v2u*)(pr + 2 * D - (ptrdiff_t)q * NIN); ph[(64 - q) & (W - 1)] = x; float f[4]; unpack4(x, f);
; #pragma unroll
;             for (int j = 0; j < 4; ++j) s[j] += f[j]; }
;     }
	v_add_co_u32_e32 v26, vcc, 0xffff6000, v24
	s_movk_i32 s0, 0xa000
	s_nop 0
	v_addc_co_u32_e32 v27, vcc, -1, v25, vcc
	v_add_co_u32_e32 v28, vcc, 0xfffec000, v24
	global_load_dwordx2 v[26:27], v[26:27], off nt
	s_nop 0
	v_addc_co_u32_e32 v29, vcc, -1, v25, vcc
	v_add_co_u32_e32 v30, vcc, 0xfffe2000, v24
	s_waitcnt vmcnt(0)
	v_lshlrev_b32_e32 v116, 16, v26
	v_addc_co_u32_e32 v31, vcc, -1, v25, vcc
	v_add_co_u32_e32 v32, vcc, s0, v24
	s_mov_b32 s0, 0xffff0000
	s_nop 0
	v_addc_co_u32_e32 v33, vcc, -1, v25, vcc
	global_load_dwordx2 v[28:29], v[28:29], off nt
	s_nop 0
	global_load_dwordx2 v[30:31], v[30:31], off nt
	s_nop 0
	global_load_dwordx2 v[58:59], v[32:33], off nt
	v_add_co_u32_e32 v32, vcc, s0, v24
	s_mov_b32 s0, 0xfffe6000
	s_nop 0
	v_addc_co_u32_e32 v33, vcc, -1, v25, vcc
	global_load_dwordx2 v[54:55], v[32:33], off nt
	v_add_co_u32_e32 v32, vcc, s0, v24
	s_mov_b32 s0, 0xfffdc000
	s_nop 0
	v_addc_co_u32_e32 v33, vcc, -1, v25, vcc
	v_add_co_u32_e32 v34, vcc, s0, v24
	s_mov_b32 s0, 0xfffd2000
	s_nop 0
	v_addc_co_u32_e32 v35, vcc, -1, v25, vcc
	global_load_dwordx2 v[56:57], v[32:33], off nt
	global_load_dwordx2 v[50:51], v[34:35], off nt
	v_add_co_u32_e32 v32, vcc, s0, v24
	s_mov_b32 s0, 0xfffc8000
	s_nop 0
	v_addc_co_u32_e32 v33, vcc, -1, v25, vcc
	global_load_dwordx2 v[52:53], v[32:33], off nt
	v_add_co_u32_e32 v32, vcc, s0, v24
	s_mov_b32 s0, 0xfffbe000
	s_nop 0
	v_addc_co_u32_e32 v33, vcc, -1, v25, vcc
	v_add_co_u32_e32 v34, vcc, s0, v24
	s_mov_b32 s0, 0xfffb4000
	s_nop 0
	v_addc_co_u32_e32 v35, vcc, -1, v25, vcc
	v_add_co_u32_e32 v36, vcc, s0, v24
	s_mov_b32 s0, 0xfffaa000
	s_nop 0
	v_addc_co_u32_e32 v37, vcc, -1, v25, vcc
	v_add_co_u32_e32 v38, vcc, s0, v24
	s_mov_b32 s0, 0xfffa0000
	s_nop 0
	v_addc_co_u32_e32 v39, vcc, -1, v25, vcc
	global_load_dwordx2 v[62:63], v[32:33], off nt
	global_load_dwordx2 v[60:61], v[34:35], off nt
	global_load_dwordx2 v[64:65], v[36:37], off nt
	global_load_dwordx2 v[84:85], v[38:39], off nt
	v_add_co_u32_e32 v32, vcc, s0, v24
	s_mov_b32 s0, 0xfff96000
	s_nop 0
	v_addc_co_u32_e32 v33, vcc, -1, v25, vcc
	global_load_dwordx2 v[88:89], v[32:33], off nt
	v_add_co_u32_e32 v32, vcc, s0, v24
	s_mov_b32 s0, 0xfff8c000
	s_nop 0
	v_addc_co_u32_e32 v33, vcc, -1, v25, vcc
	v_add_co_u32_e32 v34, vcc, s0, v24
	s_mov_b32 s0, 0xfff82000
	s_nop 0
	v_addc_co_u32_e32 v35, vcc, -1, v25, vcc
	v_add_co_u32_e32 v36, vcc, s0, v24
	s_mov_b32 s0, 0xfff78000
	s_nop 0
	v_addc_co_u32_e32 v37, vcc, -1, v25, vcc
	global_load_dwordx2 v[92:93], v[32:33], off nt
	global_load_dwordx2 v[104:105], v[34:35], off nt
	global_load_dwordx2 v[106:107], v[36:37], off nt
	v_add_co_u32_e32 v32, vcc, s0, v24
	s_mov_b32 s0, 0xfff6e000
	s_nop 0
	v_addc_co_u32_e32 v33, vcc, -1, v25, vcc
	global_load_dwordx2 v[108:109], v[32:33], off nt
	v_add_co_u32_e32 v32, vcc, s0, v24
	v_and_b32_e32 v114, 0xffff0000, v26
	s_nop 0
	v_addc_co_u32_e32 v33, vcc, -1, v25, vcc
	global_load_dwordx2 v[118:119], v[32:33], off nt
	v_lshlrev_b32_e32 v112, 16, v27
	v_and_b32_e32 v110, 0xffff0000, v27
	s_waitcnt vmcnt(0)
	v_and_b32_e32 v26, 0xffff0000, v58
	v_lshlrev_b32_e32 v27, 16, v58
	v_lshlrev_b32_e32 v101, 16, v28
	v_and_b32_e32 v99, 0xffff0000, v28
	v_lshlrev_b32_e32 v97, 16, v29
	v_and_b32_e32 v95, 0xffff0000, v29
	v_pk_add_f32 v[26:27], v[26:27], 0 op_sel_hi:[1,0]
	v_and_b32_e32 v28, 0xffff0000, v54
	v_lshlrev_b32_e32 v29, 16, v54
	v_pk_add_f32 v[26:27], v[26:27], v[28:29]
	v_lshlrev_b32_e32 v100, 16, v30
	v_and_b32_e32 v98, 0xffff0000, v30
	v_lshlrev_b32_e32 v96, 16, v31
	v_and_b32_e32 v94, 0xffff0000, v31
	v_and_b32_e32 v30, 0xffff0000, v55
	v_and_b32_e32 v28, 0xffff0000, v56
	v_lshlrev_b32_e32 v29, 16, v56
	v_pk_add_f32 v[26:27], v[26:27], v[28:29]
	v_and_b32_e32 v28, 0xffff0000, v50
	v_lshlrev_b32_e32 v29, 16, v50
	v_pk_add_f32 v[26:27], v[26:27], v[28:29]
	v_lshlrev_b32_e32 v31, 16, v55
	v_and_b32_e32 v28, 0xffff0000, v52
	v_lshlrev_b32_e32 v29, 16, v52
	v_pk_add_f32 v[26:27], v[26:27], v[28:29]
	v_and_b32_e32 v28, 0xffff0000, v59
	v_lshlrev_b32_e32 v29, 16, v59
	v_pk_add_f32 v[28:29], v[28:29], 0 op_sel_hi:[1,0]
	v_lshlrev_b32_e32 v33, 16, v63
	v_pk_add_f32 v[28:29], v[28:29], v[30:31]
	v_and_b32_e32 v30, 0xffff0000, v57
	v_lshlrev_b32_e32 v31, 16, v57
	v_pk_add_f32 v[28:29], v[28:29], v[30:31]
	v_and_b32_e32 v30, 0xffff0000, v51
	v_lshlrev_b32_e32 v31, 16, v51
	v_pk_add_f32 v[28:29], v[28:29], v[30:31]
	v_and_b32_e32 v30, 0xffff0000, v53
	v_lshlrev_b32_e32 v31, 16, v53
	v_pk_add_f32 v[28:29], v[28:29], v[30:31]
	v_lshlrev_b32_e32 v31, 16, v62
	v_and_b32_e32 v30, 0xffff0000, v62
	v_and_b32_e32 v32, 0xffff0000, v63
	v_lshlrev_b32_e32 v35, 16, v60
	v_and_b32_e32 v34, 0xffff0000, v60
	v_lshlrev_b32_e32 v37, 16, v61
	v_and_b32_e32 v36, 0xffff0000, v61
	v_pk_add_f32 v[26:27], v[26:27], v[30:31]
	v_pk_add_f32 v[28:29], v[28:29], v[32:33]
	v_lshlrev_b32_e32 v39, 16, v64
	v_and_b32_e32 v38, 0xffff0000, v64
	v_lshlrev_b32_e32 v41, 16, v65
	v_and_b32_e32 v40, 0xffff0000, v65
	v_pk_add_f32 v[26:27], v[26:27], v[34:35]
	v_pk_add_f32 v[28:29], v[28:29], v[36:37]
	v_pk_add_f32 v[26:27], v[26:27], v[38:39]
	v_and_b32_e32 v30, 0xffff0000, v84
	v_lshlrev_b32_e32 v31, 16, v84
	v_pk_add_f32 v[28:29], v[28:29], v[40:41]
	v_and_b32_e32 v32, 0xffff0000, v85
	v_lshlrev_b32_e32 v33, 16, v85
	v_pk_add_f32 v[26:27], v[26:27], v[30:31]
	v_and_b32_e32 v30, 0xffff0000, v88
	v_lshlrev_b32_e32 v31, 16, v88
	v_pk_add_f32 v[28:29], v[28:29], v[32:33]
	v_and_b32_e32 v32, 0xffff0000, v89
	v_lshlrev_b32_e32 v33, 16, v89
	v_pk_add_f32 v[26:27], v[26:27], v[30:31]
	v_and_b32_e32 v30, 0xffff0000, v92
	v_lshlrev_b32_e32 v31, 16, v92
	v_pk_add_f32 v[28:29], v[28:29], v[32:33]
	v_and_b32_e32 v32, 0xffff0000, v93
	v_lshlrev_b32_e32 v33, 16, v93
	v_pk_add_f32 v[26:27], v[26:27], v[30:31]
	v_and_b32_e32 v30, 0xffff0000, v104
	v_lshlrev_b32_e32 v31, 16, v104
	v_pk_add_f32 v[28:29], v[28:29], v[32:33]
	v_and_b32_e32 v32, 0xffff0000, v105
	v_lshlrev_b32_e32 v33, 16, v105
	v_pk_add_f32 v[26:27], v[26:27], v[30:31]
	v_and_b32_e32 v30, 0xffff0000, v106
	v_lshlrev_b32_e32 v31, 16, v106
	v_pk_add_f32 v[28:29], v[28:29], v[32:33]
	v_and_b32_e32 v32, 0xffff0000, v107
	v_lshlrev_b32_e32 v33, 16, v107
	v_pk_add_f32 v[26:27], v[26:27], v[30:31]
	v_and_b32_e32 v30, 0xffff0000, v108
	v_lshlrev_b32_e32 v31, 16, v108
	v_pk_add_f32 v[28:29], v[28:29], v[32:33]
	v_and_b32_e32 v32, 0xffff0000, v109
	v_lshlrev_b32_e32 v33, 16, v109
	v_pk_add_f32 v[26:27], v[26:27], v[30:31]
	v_and_b32_e32 v30, 0xffff0000, v118
	v_lshlrev_b32_e32 v31, 16, v118
	v_pk_add_f32 v[28:29], v[28:29], v[32:33]
	v_and_b32_e32 v32, 0xffff0000, v119
	v_lshlrev_b32_e32 v33, 16, v119
	v_pk_add_f32 v[90:91], v[26:27], v[30:31]
	v_pk_add_f32 v[86:87], v[28:29], v[32:33]
	s_branch .LBB0_345

; __device__ __forceinline__ unsigned cvt_pk_bf16(float lo, float hi) { unsigned r; asm volatile("v_cvt_pk_bf16_f32 %0, %1, %2" : "=v"(r) : "v"(lo), "v"(hi)); return r; }
; __device__ __forceinline__ void unpack4(const v2u q, float (&f)[4]) { f[0] = bf_lo(q.x); f[1] = bf_hi(q.x); f[2] = bf_lo(q.y); f[3] = bf_hi(q.y); }
; template <int W>
; __device__ __forceinline__ void conv_pool_chunk(const bf16* PROJ, bf16* XC, bf16* POOLED, const float* conv_w, const float* conv_b, int chunk, int ch0) {
;     ...
;             v2u xnb[8], pnb[8];
; #pragma unroll
;             for (int q = 0; q < 8; ++q) { xnb[q] = *(const v2u*)(p + (size_t)q * NIN); pnb[q] = *(const v2u*)(p + (size_t)q * NIN + 2 * D); }
; #pragma unroll
;             for (int q = 0; q < 8; ++q) { const int rr = h8 * 8 + q; const int r = rb * 16 + rr;
;                 const v2u xn = xnb[q], pn = pnb[q];
;                 float xf[4]; unpack4(xn, xf);
;                 float a[4];
; #pragma unroll
;                 for (int j = 0; j < 4; ++j) a[j] = cb[j] + cw[0][j] * cx[(rr + 1) & 3][j] + cw[1][j] * cx[(rr + 2) & 3][j] + cw[2][j] * cx[(rr + 3) & 3][j] + cw[3][j] * xf[j];
; #pragma unroll
;                 for (int j = 0; j < 4; ++j) cx[rr & 3][j] = xf[j];
;                 { v2u o; o.x = cvt_pk_bf16(a[0], a[1]); o.y = cvt_pk_bf16(a[2], a[3]); *(v2u*)(xo + (size_t)q * D) = o; }
;                 float pf[4], of[4]; unpack4(pn, pf); unpack4(ph[rr & (W - 1)], of);
;                 ph[rr & (W - 1)] = pn;
;                 const int t = t0 + r; const int cnt = (t + 1 < W) ? (t + 1) : W; const float inv = 1.0f / (float)cnt;
; #pragma unroll
;                 for (int j = 0; j < 4; ++j) { s[j] += pf[j] - of[j]; a[j] = s[j] * inv - pf[j]; }
;                 { v2u o; o.x = cvt_pk_bf16(a[0], a[1]); o.y = cvt_pk_bf16(a[2], a[3]); *(v2u*)(po + (size_t)q * D) = o; }
.LBB0_346:
	v_lshl_add_u64 v[102:103], s[40:41], 0, v[22:23]
	v_add_co_u32_e32 v66, vcc, s81, v102
	global_load_dwordx2 v[140:141], v[102:103], off nt
	s_nop 0
	v_addc_co_u32_e32 v67, vcc, 0, v103, vcc
	v_add_co_u32_e32 v68, vcc, s36, v102
	global_load_dwordx2 v[66:67], v[66:67], off nt
	s_nop 0
	v_addc_co_u32_e32 v69, vcc, 0, v103, vcc
	global_load_dwordx2 v[142:143], v[68:69], off nt
	v_add_co_u32_e32 v68, vcc, s37, v102
	v_pk_mul_f32 v[128:129], v[38:39], v[100:101]
	s_nop 0
	v_addc_co_u32_e32 v69, vcc, 0, v103, vcc
	v_add_co_u32_e32 v70, vcc, s42, v102
	global_load_dwordx2 v[68:69], v[68:69], off nt
	s_nop 0
	v_addc_co_u32_e32 v71, vcc, 0, v103, vcc
	global_load_dwordx2 v[136:137], v[70:71], off nt
	v_add_co_u32_e32 v70, vcc, s64, v102
	v_add_f32_e32 v100, v14, v128
	s_nop 0
	v_addc_co_u32_e32 v71, vcc, 0, v103, vcc
	v_add_co_u32_e32 v72, vcc, s65, v102
	global_load_dwordx2 v[70:71], v[70:71], off nt
	s_nop 0
	v_addc_co_u32_e32 v73, vcc, 0, v103, vcc
	global_load_dwordx2 v[138:139], v[72:73], off nt
	v_add_co_u32_e32 v72, vcc, s66, v102
	v_add_f32_e32 v115, v129, v100
	s_nop 0
	v_addc_co_u32_e32 v73, vcc, 0, v103, vcc
	v_add_co_u32_e32 v74, vcc, s67, v102
	global_load_dwordx2 v[72:73], v[72:73], off nt
	s_nop 0
	v_addc_co_u32_e32 v75, vcc, 0, v103, vcc
	global_load_dwordx2 v[124:125], v[74:75], off nt
	v_add_co_u32_e32 v74, vcc, s71, v102
	v_pk_mul_f32 v[128:129], v[40:41], v[98:99]
	s_nop 0
	v_addc_co_u32_e32 v75, vcc, 0, v103, vcc
	v_add_co_u32_e32 v76, vcc, s90, v102
	v_add_f32_e32 v98, v15, v128
	s_nop 0
	v_addc_co_u32_e32 v77, vcc, 0, v103, vcc
	global_load_dwordx2 v[126:127], v[76:77], off nt
	v_add_co_u32_e32 v76, vcc, s91, v102
	v_add_f32_e32 v148, v129, v98
	s_nop 0
	v_addc_co_u32_e32 v77, vcc, 0, v103, vcc
	v_add_co_u32_e32 v78, vcc, s92, v102
	v_pk_mul_f32 v[128:129], v[30:31], v[96:97]
	s_nop 0
	v_addc_co_u32_e32 v79, vcc, 0, v103, vcc
	global_load_dwordx2 v[120:121], v[78:79], off nt
	v_add_co_u32_e32 v78, vcc, s93, v102
	s_add_i32 s69, s16, s68
	s_nop 0
	v_addc_co_u32_e32 v79, vcc, 0, v103, vcc
	v_add_co_u32_e32 v80, vcc, s94, v102
	v_add_f32_e32 v96, v16, v128
	s_nop 0
	v_addc_co_u32_e32 v81, vcc, 0, v103, vcc
	global_load_dwordx2 v[122:123], v[80:81], off nt
	v_add_co_u32_e32 v80, vcc, s95, v102
	v_add_f32_e32 v150, v129, v96
	s_nop 0
	v_addc_co_u32_e32 v81, vcc, 0, v103, vcc
	v_pk_mul_f32 v[128:129], v[32:33], v[94:95]
	s_min_u32 vcc_lo, s69, 15
	v_add_f32_e32 v94, v17, v128
	s_add_i32 vcc_lo, vcc_lo, 1
	v_add_f32_e32 v152, v129, v94
	v_cvt_f32_ubyte0_e32 v94, vcc_lo
	v_div_scale_f32 v96, vcc, v94, v94, 1.0
	v_rcp_f32_e32 v98, v96
	s_waitcnt vmcnt(0)
	v_lshlrev_b32_e32 v144, 16, v140
	v_lshlrev_b32_e32 v145, 16, v142
	v_and_b32_e32 v146, 0xffff0000, v140
	v_fma_f32 v100, -v96, v98, 1.0
	v_fmac_f32_e32 v98, v100, v98
	v_div_scale_f32 v100, vcc, 1.0, v94, 1.0
	v_mul_f32_e32 v117, v100, v98
	v_fma_f32 v128, -v96, v117, v100
	v_fmac_f32_e32 v117, v128, v98
	v_fma_f32 v96, -v96, v117, v100
	v_div_fmas_f32 v96, v96, v98, v117
	v_mov_b32_e32 v117, v101
	v_pk_mul_f32 v[100:101], v[46:47], v[116:117]
	v_div_fixup_f32 v155, v96, v94, 1.0
	v_add_f32_e32 v94, v14, v101
	v_mov_b32_e32 v117, v144
	v_add_f32_e32 v94, v100, v94
	v_pk_mul_f32 v[100:101], v[34:35], v[116:117]
	v_and_b32_e32 v147, 0xffff0000, v142
	v_add_f32_e32 v96, v100, v115
	v_add_f32_e32 v96, v96, v101
	v_pk_mul_f32 v[100:101], v[34:35], v[144:145]
	v_mov_b32_e32 v115, v99
	v_add_f32_e32 v94, v94, v100
	v_pk_mul_f32 v[98:99], v[48:49], v[114:115]
	v_add_f32_e32 v156, v94, v101
	v_add_f32_e32 v94, v15, v99
	v_mov_b32_e32 v115, v146
	v_add_f32_e32 v100, v98, v94
	v_pk_mul_f32 v[98:99], v[36:37], v[114:115]
	global_load_dwordx2 v[74:75], v[74:75], off nt
	v_add_f32_e32 v94, v98, v148
	v_add_f32_e32 v94, v94, v99
	v_pk_mul_f32 v[98:99], v[36:37], v[146:147]
	global_load_dwordx2 v[76:77], v[76:77], off nt
	v_lshlrev_b32_e32 v135, 16, v113
	global_load_dwordx2 v[78:79], v[78:79], off nt
	v_and_b32_e32 v134, 0xffff0000, v113
	global_load_dwordx2 v[80:81], v[80:81], off nt
	v_cvt_pk_bf16_f32 v94, v96, v94
	v_add_f32_e32 v96, v100, v98
	v_mov_b32_e32 v113, v97
	v_add_f32_e32 v157, v96, v99
	v_pk_mul_f32 v[96:97], v[42:43], v[112:113]
	v_lshlrev_b32_e32 v148, 16, v141
	v_add_f32_e32 v97, v16, v97
	v_mov_b32_e32 v113, v148
	v_add_f32_e32 v98, v96, v97
	v_pk_mul_f32 v[96:97], v[26:27], v[112:113]
	v_lshlrev_b32_e32 v149, 16, v143
	v_add_f32_e32 v96, v96, v150
	v_add_f32_e32 v99, v96, v97
	v_pk_mul_f32 v[96:97], v[26:27], v[148:149]
	v_lshlrev_b32_e32 v131, 16, v111
	v_and_b32_e32 v130, 0xffff0000, v111
	v_add_f32_e32 v96, v98, v96
	v_mov_b32_e32 v111, v95
	v_add_f32_e32 v158, v96, v97
	v_pk_mul_f32 v[96:97], v[44:45], v[110:111]
	v_and_b32_e32 v150, 0xffff0000, v141
	v_add_f32_e32 v95, v17, v97
	v_mov_b32_e32 v111, v150
	v_lshl_add_u64 v[82:83], s[0:1], 0, v[22:23]
	v_add_f32_e32 v98, v96, v95
	v_pk_mul_f32 v[96:97], v[28:29], v[110:111]
	v_and_b32_e32 v151, 0xffff0000, v143
	v_add_f32_e32 v95, v96, v152
	v_add_co_u32_e32 v96, vcc, s96, v82
	v_add_f32_e32 v95, v95, v97
	s_nop 0
	v_addc_co_u32_e32 v97, vcc, 0, v83, vcc
	v_cvt_pk_bf16_f32 v95, v99, v95
	s_add_i32 vcc_lo, s69, 1
	global_store_dwordx2 v[96:97], v[94:95], off
	v_pk_mul_f32 v[94:95], v[28:29], v[150:151]
	s_min_u32 vcc_lo, vcc_lo, 15
	v_add_f32_e32 v94, v98, v94
	s_add_i32 vcc_lo, vcc_lo, 1
	v_add_f32_e32 v159, v94, v95
	v_cvt_f32_ubyte0_e32 v94, vcc_lo
	v_div_scale_f32 v95, vcc, v94, v94, 1.0
	v_rcp_f32_e32 v96, v95
	v_pk_mul_f32 v[110:111], v[32:33], v[110:111]
	v_pk_mul_f32 v[112:113], v[30:31], v[112:113]
	v_add_f32_e32 v110, v17, v110
	v_fma_f32 v97, -v95, v96, 1.0
	v_fmac_f32_e32 v96, v97, v96
; __device__ __forceinline__ unsigned cvt_pk_bf16(float lo, float hi) { unsigned r; asm volatile("v_cvt_pk_bf16_f32 %0, %1, %2" : "=v"(r) : "v"(lo), "v"(hi)); return r; }
; __device__ __forceinline__ void unpack4(const v2u q, float (&f)[4]) { f[0] = bf_lo(q.x); f[1] = bf_hi(q.x); f[2] = bf_lo(q.y); f[3] = bf_hi(q.y); }
; template <int W>
; __device__ __forceinline__ void conv_pool_chunk(const bf16* PROJ, bf16* XC, bf16* POOLED, const float* conv_w, const float* conv_b, int chunk, int ch0) {
;     ...
;             for (int q = 0; q < 8; ++q) { const int rr = h8 * 8 + q; const int r = rb * 16 + rr;
;                 const v2u xn = xnb[q], pn = pnb[q];
;                 float xf[4]; unpack4(xn, xf);
;                 float a[4];
; #pragma unroll
;                 for (int j = 0; j < 4; ++j) a[j] = cb[j] + cw[0][j] * cx[(rr + 1) & 3][j] + cw[1][j] * cx[(rr + 2) & 3][j] + cw[2][j] * cx[(rr + 3) & 3][j] + cw[3][j] * xf[j];
; #pragma unroll
;                 for (int j = 0; j < 4; ++j) cx[rr & 3][j] = xf[j];
;                 { v2u o; o.x = cvt_pk_bf16(a[0], a[1]); o.y = cvt_pk_bf16(a[2], a[3]); *(v2u*)(xo + (size_t)q * D) = o; }
;                 float pf[4], of[4]; unpack4(pn, pf); unpack4(ph[rr & (W - 1)], of);
;                 ph[rr & (W - 1)] = pn;
;                 const int t = t0 + r; const int cnt = (t + 1 < W) ? (t + 1) : W; const float inv = 1.0f / (float)cnt;
; #pragma unroll
;                 for (int j = 0; j < 4; ++j) { s[j] += pf[j] - of[j]; a[j] = s[j] * inv - pf[j]; }
	v_div_scale_f32 v97, vcc, 1.0, v94, 1.0
	v_mul_f32_e32 v98, v97, v96
	v_fma_f32 v99, -v95, v98, v97
	v_fmac_f32_e32 v98, v99, v96
	v_fma_f32 v95, -v95, v98, v97
	v_div_fmas_f32 v95, v95, v96, v98
	s_add_i32 vcc_lo, s69, 2
	s_min_u32 vcc_lo, vcc_lo, 15
	s_add_i32 vcc_lo, vcc_lo, 1
	v_add_f32_e32 v168, v110, v111
	v_cvt_f32_ubyte0_e32 v110, vcc_lo
	v_add_f32_e32 v112, v16, v112
	v_div_scale_f32 v111, vcc, v110, v110, 1.0
	v_add_f32_e32 v166, v112, v113
	v_rcp_f32_e32 v112, v111
	v_pk_mul_f32 v[114:115], v[40:41], v[114:115]
	v_pk_mul_f32 v[116:117], v[38:39], v[116:117]
	v_add_f32_e32 v114, v15, v114
	v_fma_f32 v113, -v111, v112, 1.0
	v_fmac_f32_e32 v112, v113, v112
	v_div_scale_f32 v113, vcc, 1.0, v110, 1.0
	v_add_f32_e32 v153, v114, v115
	v_mul_f32_e32 v114, v113, v112
	v_fma_f32 v115, -v111, v114, v113
	v_fmac_f32_e32 v114, v115, v112
	v_fma_f32 v111, -v111, v114, v113
	v_div_fmas_f32 v111, v111, v112, v114
	v_lshlrev_b32_e32 v143, 16, v108
	v_and_b32_e32 v142, 0xffff0000, v108
	v_lshlrev_b32_e32 v141, 16, v109
	v_and_b32_e32 v140, 0xffff0000, v109
	v_pk_mul_f32 v[108:109], v[38:39], v[144:145]
	v_lshlrev_b32_e32 v115, 16, v138
	v_lshlrev_b32_e32 v114, 16, v136
	v_add_f32_e32 v116, v14, v116
	v_add_f32_e32 v108, v14, v108
	v_pk_mov_b32 v[144:145], v[144:145], v[114:115] op_sel:[1,0]
	v_add_f32_e32 v152, v116, v117
	v_div_fixup_f32 v161, v111, v110, 1.0
	v_add_f32_e32 v110, v108, v109
	v_pk_mul_f32 v[108:109], v[34:35], v[144:145]
	v_and_b32_e32 v111, 0xffff0000, v138
	v_add_f32_e32 v108, v152, v108
	v_add_f32_e32 v163, v108, v109
	v_pk_mul_f32 v[108:109], v[34:35], v[114:115]
	s_add_i32 vcc_lo, s69, 3
	v_add_f32_e32 v108, v110, v108
	v_add_f32_e32 v162, v108, v109
	v_pk_mul_f32 v[108:109], v[40:41], v[146:147]
	v_and_b32_e32 v110, 0xffff0000, v136
	v_add_f32_e32 v108, v15, v108
	v_pk_mov_b32 v[146:147], v[146:147], v[110:111] op_sel:[1,0]
	v_add_f32_e32 v112, v108, v109
	v_pk_mul_f32 v[108:109], v[36:37], v[146:147]
	s_min_u32 vcc_lo, vcc_lo, 15
	v_add_f32_e32 v108, v153, v108
	v_add_f32_e32 v165, v108, v109
	v_pk_mul_f32 v[108:109], v[36:37], v[110:111]
	s_add_i32 vcc_lo, vcc_lo, 1
	v_add_f32_e32 v108, v112, v108
	v_add_f32_e32 v164, v108, v109
	v_pk_mul_f32 v[108:109], v[30:31], v[148:149]
	v_lshlrev_b32_e32 v173, 16, v106
	v_add_f32_e32 v108, v16, v108
	v_add_f32_e32 v136, v108, v109
	v_lshlrev_b32_e32 v109, 16, v139
	v_lshlrev_b32_e32 v108, 16, v137
	v_pk_mov_b32 v[148:149], v[148:149], v[108:109] op_sel:[1,0]
	v_and_b32_e32 v172, 0xffff0000, v106
	v_pk_mul_f32 v[112:113], v[26:27], v[148:149]
	v_lshlrev_b32_e32 v133, 16, v66
	v_add_f32_e32 v112, v166, v112
	v_add_f32_e32 v167, v112, v113
	v_pk_mul_f32 v[112:113], v[26:27], v[108:109]
	v_and_b32_e32 v132, 0xffff0000, v66
	v_add_f32_e32 v112, v136, v112
	v_add_f32_e32 v166, v112, v113
	v_pk_mul_f32 v[112:113], v[32:33], v[150:151]
	v_div_fixup_f32 v160, v95, v94, 1.0
	v_add_f32_e32 v112, v17, v112
	v_add_f32_e32 v152, v112, v113
	v_and_b32_e32 v113, 0xffff0000, v139
	v_and_b32_e32 v112, 0xffff0000, v137
	v_pk_mov_b32 v[138:139], v[150:151], v[112:113] op_sel:[1,0]
	v_lshlrev_b32_e32 v95, 16, v68
	v_pk_mul_f32 v[136:137], v[28:29], v[138:139]
	v_lshlrev_b32_e32 v101, 16, v118
	v_add_f32_e32 v136, v168, v136
	v_add_f32_e32 v169, v136, v137
	v_pk_mul_f32 v[136:137], v[28:29], v[112:113]
	v_and_b32_e32 v100, 0xffff0000, v118
	v_add_f32_e32 v136, v152, v136
	v_add_f32_e32 v168, v136, v137
	v_cvt_f32_ubyte0_e32 v136, vcc_lo
	v_div_scale_f32 v137, vcc, v136, v136, 1.0
	v_rcp_f32_e32 v150, v137
	v_and_b32_e32 v94, 0xffff0000, v68
	v_pk_add_f32 v[134:135], v[132:133], v[134:135] neg_lo:[0,1] neg_hi:[0,1]
	v_pk_add_f32 v[100:101], v[94:95], v[100:101] neg_lo:[0,1] neg_hi:[0,1]
	v_fma_f32 v151, -v137, v150, 1.0
	v_fmac_f32_e32 v150, v151, v150
	v_div_scale_f32 v151, vcc, 1.0, v136, 1.0
	v_mul_f32_e32 v152, v151, v150
	v_fma_f32 v153, -v137, v152, v151
	v_fmac_f32_e32 v152, v153, v150
	v_fma_f32 v137, -v137, v152, v151
	v_div_fmas_f32 v137, v137, v150, v152
	v_lshlrev_b32_e32 v153, 16, v107
	v_and_b32_e32 v152, 0xffff0000, v107
	v_pk_mul_f32 v[106:107], v[38:39], v[144:145]
	s_add_i32 vcc_lo, s69, 4
	v_add_f32_e32 v106, v14, v106
	v_add_f32_e32 v144, v106, v107
	v_pk_mul_f32 v[106:107], v[40:41], v[146:147]
	s_min_u32 vcc_lo, vcc_lo, 15
	v_add_f32_e32 v106, v15, v106
	v_add_f32_e32 v145, v106, v107
	v_pk_mul_f32 v[106:107], v[30:31], v[148:149]
	s_add_i32 vcc_lo, vcc_lo, 1
	v_add_f32_e32 v106, v16, v106
	v_add_f32_e32 v146, v106, v107
	v_pk_mul_f32 v[106:107], v[32:33], v[138:139]
	v_pk_add_f32 v[90:91], v[90:91], v[134:135]
	v_add_f32_e32 v106, v17, v106
	v_add_f32_e32 v147, v106, v107
	v_cvt_f32_ubyte0_e32 v106, vcc_lo
	v_div_scale_f32 v107, vcc, v106, v106, 1.0
	v_rcp_f32_e32 v138, v107
	v_lshlrev_b32_e32 v99, 16, v119
	v_and_b32_e32 v98, 0xffff0000, v119
	v_lshlrev_b32_e32 v119, 16, v70
	v_fma_f32 v139, -v107, v138, 1.0
	v_fmac_f32_e32 v138, v139, v138
	v_div_scale_f32 v139, vcc, 1.0, v106, 1.0
	v_mul_f32_e32 v148, v139, v138
	v_fma_f32 v149, -v107, v148, v139
	v_fmac_f32_e32 v148, v149, v138
	v_fma_f32 v107, -v107, v148, v139
	v_and_b32_e32 v118, 0xffff0000, v70
	v_div_fmas_f32 v107, v107, v138, v148
	v_lshlrev_b32_e32 v139, 16, v104
	v_and_b32_e32 v138, 0xffff0000, v104
	v_fma_f32 v104, v155, v91, -v133
	v_fma_f32 v132, v155, v90, -v132
	v_pk_add_f32 v[90:91], v[90:91], v[100:101]
	v_div_fixup_f32 v170, v137, v136, 1.0
	v_lshlrev_b32_e32 v137, 16, v72
	v_and_b32_e32 v136, 0xffff0000, v72
	v_cvt_pk_bf16_f32 v104, v104, v132
	v_fma_f32 v132, v160, v91, -v95
	v_fma_f32 v133, v160, v90, -v94
	v_pk_add_f32 v[94:95], v[118:119], v[142:143] neg_lo:[0,1] neg_hi:[0,1]
	v_div_fixup_f32 v148, v107, v106, 1.0
	s_waitcnt vmcnt(0)
; __device__ __forceinline__ unsigned cvt_pk_bf16(float lo, float hi) { unsigned r; asm volatile("v_cvt_pk_bf16_f32 %0, %1, %2" : "=v"(r) : "v"(lo), "v"(hi)); return r; }
; __device__ __forceinline__ void unpack4(const v2u q, float (&f)[4]) { f[0] = bf_lo(q.x); f[1] = bf_hi(q.x); f[2] = bf_lo(q.y); f[3] = bf_hi(q.y); }
; template <int W>
; __device__ __forceinline__ void conv_pool_chunk(const bf16* PROJ, bf16* XC, bf16* POOLED, const float* conv_w, const float* conv_b, int chunk, int ch0) {
;     ...
;                 for (int j = 0; j < 4; ++j) a[j] = cb[j] + cw[0][j] * cx[(rr + 1) & 3][j] + cw[1][j] * cx[(rr + 2) & 3][j] + cw[2][j] * cx[(rr + 3) & 3][j] + cw[3][j] * xf[j];
; #pragma unroll
;                 for (int j = 0; j < 4; ++j) cx[rr & 3][j] = xf[j];
;                 { v2u o; o.x = cvt_pk_bf16(a[0], a[1]); o.y = cvt_pk_bf16(a[2], a[3]); *(v2u*)(xo + (size_t)q * D) = o; }
;                 float pf[4], of[4]; unpack4(pn, pf); unpack4(ph[rr & (W - 1)], of);
;                 ph[rr & (W - 1)] = pn;
;                 const int t = t0 + r; const int cnt = (t + 1 < W) ? (t + 1) : W; const float inv = 1.0f / (float)cnt;
; #pragma unroll
;                 for (int j = 0; j < 4; ++j) { s[j] += pf[j] - of[j]; a[j] = s[j] * inv - pf[j]; }
;                 { v2u o; o.x = cvt_pk_bf16(a[0], a[1]); o.y = cvt_pk_bf16(a[2], a[3]); *(v2u*)(po + (size_t)q * D) = o; }
	v_lshlrev_b32_e32 v107, 16, v74
	v_and_b32_e32 v106, 0xffff0000, v74
	v_pk_add_f32 v[90:91], v[90:91], v[94:95]
	v_pk_add_f32 v[94:95], v[136:137], v[172:173] neg_lo:[0,1] neg_hi:[0,1]
	v_fma_f32 v119, v161, v91, -v119
	v_fma_f32 v118, v161, v90, -v118
	v_pk_add_f32 v[90:91], v[90:91], v[94:95]
	v_pk_add_f32 v[94:95], v[106:107], v[138:139] neg_lo:[0,1] neg_hi:[0,1]
	v_lshlrev_b32_e32 v129, 16, v67
	v_and_b32_e32 v128, 0xffff0000, v67
	v_fma_f32 v134, v170, v91, -v137
	v_fma_f32 v135, v170, v90, -v136
	v_pk_add_f32 v[90:91], v[90:91], v[94:95]
	v_lshlrev_b32_e32 v97, 16, v69
	v_and_b32_e32 v96, 0xffff0000, v69
	v_fma_f32 v136, v148, v91, -v107
	v_fma_f32 v137, v148, v90, -v106
	v_pk_add_f32 v[106:107], v[128:129], v[130:131] neg_lo:[0,1] neg_hi:[0,1]
	v_pk_add_f32 v[98:99], v[96:97], v[98:99] neg_lo:[0,1] neg_hi:[0,1]
	v_pk_add_f32 v[86:87], v[86:87], v[106:107]
	v_lshlrev_b32_e32 v117, 16, v71
	v_and_b32_e32 v116, 0xffff0000, v71
	v_lshlrev_b32_e32 v95, 16, v105
	v_and_b32_e32 v94, 0xffff0000, v105
	v_fma_f32 v105, v155, v87, -v129
	v_fma_f32 v106, v155, v86, -v128
	v_pk_add_f32 v[86:87], v[86:87], v[98:99]
	v_lshlrev_b32_e32 v151, 16, v73
	v_and_b32_e32 v150, 0xffff0000, v73
	v_fma_f32 v107, v160, v87, -v97
	v_fma_f32 v128, v160, v86, -v96
	v_pk_add_f32 v[96:97], v[116:117], v[140:141] neg_lo:[0,1] neg_hi:[0,1]
	v_cvt_pk_bf16_f32 v105, v105, v106
	v_lshlrev_b32_e32 v101, 16, v75
	v_pk_add_f32 v[86:87], v[86:87], v[96:97]
	v_pk_add_f32 v[96:97], v[150:151], v[152:153] neg_lo:[0,1] neg_hi:[0,1]
	v_fma_f32 v117, v161, v87, -v117
	v_fma_f32 v116, v161, v86, -v116
	v_pk_add_f32 v[86:87], v[86:87], v[96:97]
	v_add_co_u32_e32 v96, vcc, s97, v82
	v_and_b32_e32 v100, 0xffff0000, v75
	s_nop 0
	v_addc_co_u32_e32 v97, vcc, 0, v83, vcc
	v_add_co_u32_e32 v98, vcc, s14, v82
	global_store_dwordx2 v[96:97], v[104:105], off
	s_nop 0
	v_addc_co_u32_e32 v99, vcc, 0, v83, vcc
	v_cvt_pk_bf16_f32 v96, v156, v157
	v_cvt_pk_bf16_f32 v97, v158, v159
	global_store_dwordx2 v[98:99], v[96:97], off
	v_add_co_u32_e32 v98, vcc, s54, v82
	v_cvt_pk_bf16_f32 v96, v132, v133
	v_cvt_pk_bf16_f32 v97, v107, v128
	v_pk_add_f32 v[94:95], v[100:101], v[94:95] neg_lo:[0,1] neg_hi:[0,1]
	s_nop 0
	v_addc_co_u32_e32 v99, vcc, 0, v83, vcc
	global_store_dwordx2 v[98:99], v[96:97], off
	v_add_co_u32_e32 v98, vcc, s55, v82
	v_cvt_pk_bf16_f32 v96, v163, v165
	v_cvt_pk_bf16_f32 v97, v167, v169
	v_pk_add_f32 v[94:95], v[86:87], v[94:95]
	s_nop 0
	v_addc_co_u32_e32 v99, vcc, 0, v83, vcc
	global_store_dwordx2 v[98:99], v[96:97], off
	v_add_co_u32_e32 v98, vcc, s58, v82
	v_cvt_pk_bf16_f32 v96, v119, v118
	v_cvt_pk_bf16_f32 v97, v117, v116
	v_fma_f32 v129, v170, v87, -v151
	s_nop 0
	v_addc_co_u32_e32 v99, vcc, 0, v83, vcc
	global_store_dwordx2 v[98:99], v[96:97], off
	v_add_co_u32_e32 v98, vcc, s6, v82
	v_fma_f32 v130, v170, v86, -v150
	s_nop 0
	v_addc_co_u32_e32 v99, vcc, 0, v83, vcc
	v_cvt_pk_bf16_f32 v96, v162, v164
	v_cvt_pk_bf16_f32 v97, v166, v168
	global_store_dwordx2 v[98:99], v[96:97], off
	v_add_co_u32_e32 v98, vcc, s7, v82
	v_fma_f32 v118, v148, v95, -v101
	v_fma_f32 v119, v148, v94, -v100
	v_pk_mul_f32 v[86:87], v[38:39], v[114:115]
	v_lshlrev_b32_e32 v101, 16, v126
	v_lshlrev_b32_e32 v100, 16, v124
	v_cvt_pk_bf16_f32 v96, v134, v135
	v_addc_co_u32_e32 v99, vcc, 0, v83, vcc
	v_add_f32_e32 v86, v14, v86
	v_pk_mov_b32 v[104:105], v[114:115], v[100:101] op_sel:[1,0]
	v_cvt_pk_bf16_f32 v97, v129, v130
	global_store_dwordx2 v[98:99], v[96:97], off
	v_add_f32_e32 v96, v86, v87
	v_pk_mul_f32 v[86:87], v[34:35], v[104:105]
	v_and_b32_e32 v97, 0xffff0000, v126
	v_add_f32_e32 v86, v144, v86
	v_add_f32_e32 v98, v86, v87
	v_pk_mul_f32 v[86:87], v[34:35], v[100:101]
	v_pk_mul_f32 v[104:105], v[38:39], v[104:105]
	v_add_f32_e32 v86, v96, v86
	v_add_f32_e32 v128, v86, v87
	v_pk_mul_f32 v[86:87], v[40:41], v[110:111]
	v_and_b32_e32 v96, 0xffff0000, v124
	v_add_f32_e32 v86, v15, v86
	v_pk_mov_b32 v[106:107], v[110:111], v[96:97] op_sel:[1,0]
	v_add_f32_e32 v114, v86, v87
	v_pk_mul_f32 v[86:87], v[36:37], v[106:107]
	v_lshlrev_b32_e32 v111, 16, v127
	v_add_f32_e32 v86, v145, v86
	v_add_f32_e32 v86, v86, v87
	v_cvt_pk_bf16_f32 v86, v98, v86
	v_pk_mul_f32 v[98:99], v[36:37], v[96:97]
	v_lshlrev_b32_e32 v110, 16, v125
	v_add_f32_e32 v87, v114, v98
	v_add_f32_e32 v124, v87, v99
	v_pk_mul_f32 v[98:99], v[30:31], v[108:109]
	v_pk_mov_b32 v[114:115], v[108:109], v[110:111] op_sel:[1,0]
	v_add_f32_e32 v87, v16, v98
	v_add_f32_e32 v87, v87, v99
	v_pk_mul_f32 v[98:99], v[26:27], v[114:115]
	v_and_b32_e32 v109, 0xffff0000, v127
	v_add_f32_e32 v98, v146, v98
	v_add_f32_e32 v126, v98, v99
	v_pk_mul_f32 v[98:99], v[26:27], v[110:111]
	v_and_b32_e32 v108, 0xffff0000, v125
	v_add_f32_e32 v87, v87, v98
	v_add_f32_e32 v129, v87, v99
	v_pk_mul_f32 v[98:99], v[32:33], v[112:113]
	v_pk_mov_b32 v[116:117], v[112:113], v[108:109] op_sel:[1,0]
	v_add_f32_e32 v87, v17, v98
	v_add_f32_e32 v130, v87, v99
	v_pk_mul_f32 v[98:99], v[28:29], v[116:117]
	v_add_f32_e32 v104, v14, v104
	v_add_f32_e32 v87, v147, v98
	v_add_co_u32_e32 v98, vcc, s15, v82
	v_add_f32_e32 v87, v87, v99
	s_nop 0
	v_addc_co_u32_e32 v99, vcc, 0, v83, vcc
	v_cvt_pk_bf16_f32 v87, v126, v87
	global_store_dwordx2 v[98:99], v[86:87], off
	v_add_co_u32_e32 v98, vcc, s34, v82
	v_cvt_pk_bf16_f32 v86, v136, v137
	v_cvt_pk_bf16_f32 v87, v118, v119
	v_add_f32_e32 v118, v104, v105
	s_nop 0
	v_addc_co_u32_e32 v99, vcc, 0, v83, vcc
	global_store_dwordx2 v[98:99], v[86:87], off
	v_add_co_u32_e32 v98, vcc, s86, v82
	v_pk_mul_f32 v[86:87], v[28:29], v[108:109]
	s_nop 0
	v_addc_co_u32_e32 v99, vcc, 0, v83, vcc
	s_add_i32 vcc_lo, s69, 5
	v_add_f32_e32 v86, v130, v86
; __device__ __forceinline__ unsigned cvt_pk_bf16(float lo, float hi) { unsigned r; asm volatile("v_cvt_pk_bf16_f32 %0, %1, %2" : "=v"(r) : "v"(lo), "v"(hi)); return r; }
; __device__ __forceinline__ void unpack4(const v2u q, float (&f)[4]) { f[0] = bf_lo(q.x); f[1] = bf_hi(q.x); f[2] = bf_lo(q.y); f[3] = bf_hi(q.y); }
; template <int W>
; __device__ __forceinline__ void conv_pool_chunk(const bf16* PROJ, bf16* XC, bf16* POOLED, const float* conv_w, const float* conv_b, int chunk, int ch0) {
;     ...
;                 for (int j = 0; j < 4; ++j) a[j] = cb[j] + cw[0][j] * cx[(rr + 1) & 3][j] + cw[1][j] * cx[(rr + 2) & 3][j] + cw[2][j] * cx[(rr + 3) & 3][j] + cw[3][j] * xf[j];
; #pragma unroll
;                 for (int j = 0; j < 4; ++j) cx[rr & 3][j] = xf[j];
;                 { v2u o; o.x = cvt_pk_bf16(a[0], a[1]); o.y = cvt_pk_bf16(a[2], a[3]); *(v2u*)(xo + (size_t)q * D) = o; }
;                 float pf[4], of[4]; unpack4(pn, pf); unpack4(ph[rr & (W - 1)], of);
;                 ph[rr & (W - 1)] = pn;
;                 const int t = t0 + r; const int cnt = (t + 1 < W) ? (t + 1) : W; const float inv = 1.0f / (float)cnt;
; #pragma unroll
;                 for (int j = 0; j < 4; ++j) { s[j] += pf[j] - of[j]; a[j] = s[j] * inv - pf[j]; }
	s_min_u32 vcc_lo, vcc_lo, 15
	v_add_f32_e32 v87, v86, v87
	v_cvt_pk_bf16_f32 v86, v128, v124
	s_add_i32 vcc_lo, vcc_lo, 1
	v_cvt_pk_bf16_f32 v87, v129, v87
	global_store_dwordx2 v[98:99], v[86:87], off
	v_cvt_f32_ubyte0_e32 v86, vcc_lo
	v_div_scale_f32 v87, vcc, v86, v86, 1.0
	v_rcp_f32_e32 v98, v87
	v_pk_mul_f32 v[104:105], v[40:41], v[106:107]
	v_lshlrev_b32_e32 v107, 16, v88
	v_add_f32_e32 v104, v15, v104
	v_fma_f32 v99, -v87, v98, 1.0
	v_fmac_f32_e32 v98, v99, v98
	v_div_scale_f32 v99, vcc, 1.0, v86, 1.0
	v_mul_f32_e32 v112, v99, v98
	v_fma_f32 v113, -v87, v112, v99
	v_fmac_f32_e32 v112, v113, v98
	v_fma_f32 v87, -v87, v112, v99
	v_div_fmas_f32 v87, v87, v98, v112
	s_add_i32 vcc_lo, s69, 6
	s_min_u32 vcc_lo, vcc_lo, 15
	v_add_f32_e32 v119, v104, v105
	v_pk_mul_f32 v[104:105], v[30:31], v[114:115]
	s_add_i32 vcc_lo, vcc_lo, 1
	v_add_f32_e32 v104, v16, v104
	v_and_b32_e32 v106, 0xffff0000, v88
	v_cvt_f32_ubyte0_e32 v88, vcc_lo
	v_add_f32_e32 v130, v104, v105
	v_pk_mul_f32 v[104:105], v[32:33], v[116:117]
	v_lshlrev_b32_e32 v117, 16, v89
	v_and_b32_e32 v116, 0xffff0000, v89
	v_div_scale_f32 v89, vcc, v88, v88, 1.0
	v_rcp_f32_e32 v124, v89
	v_lshlrev_b32_e32 v129, 16, v123
	v_lshlrev_b32_e32 v128, 16, v121
	v_and_b32_e32 v123, 0xffff0000, v123
	v_fma_f32 v125, -v89, v124, 1.0
	v_fmac_f32_e32 v124, v125, v124
	v_div_scale_f32 v125, vcc, 1.0, v88, 1.0
	v_mul_f32_e32 v126, v125, v124
	v_fma_f32 v127, -v89, v126, v125
	v_fmac_f32_e32 v126, v127, v124
	v_fma_f32 v89, -v89, v126, v125
	v_div_fmas_f32 v89, v89, v124, v126
	v_div_fixup_f32 v140, v89, v88, 1.0
	v_pk_mul_f32 v[88:89], v[38:39], v[100:101]
	v_lshlrev_b32_e32 v125, 16, v122
	v_lshlrev_b32_e32 v124, 16, v120
	v_add_f32_e32 v88, v14, v88
	v_pk_mov_b32 v[100:101], v[100:101], v[124:125] op_sel:[1,0]
	v_add_f32_e32 v126, v88, v89
	v_pk_mul_f32 v[88:89], v[34:35], v[100:101]
	v_and_b32_e32 v127, 0xffff0000, v122
	v_add_f32_e32 v88, v118, v88
	v_add_f32_e32 v142, v88, v89
	v_pk_mul_f32 v[88:89], v[34:35], v[124:125]
	v_and_b32_e32 v122, 0xffff0000, v121
	v_add_f32_e32 v88, v126, v88
	v_add_f32_e32 v133, v88, v89
	v_pk_mul_f32 v[88:89], v[40:41], v[96:97]
	v_and_b32_e32 v126, 0xffff0000, v120
	v_add_f32_e32 v88, v15, v88
	v_pk_mov_b32 v[96:97], v[96:97], v[126:127] op_sel:[1,0]
	v_add_f32_e32 v118, v88, v89
	v_pk_mul_f32 v[88:89], v[36:37], v[96:97]
	v_add_f32_e32 v104, v17, v104
	v_add_f32_e32 v88, v119, v88
	v_add_f32_e32 v160, v88, v89
	v_pk_mul_f32 v[88:89], v[36:37], v[126:127]
	v_add_f32_e32 v131, v104, v105
	v_add_f32_e32 v88, v118, v88
	v_add_f32_e32 v143, v88, v89
	v_pk_mul_f32 v[88:89], v[30:31], v[110:111]
	v_pk_mov_b32 v[118:119], v[110:111], v[128:129] op_sel:[1,0]
	v_add_f32_e32 v88, v16, v88
	v_add_f32_e32 v120, v88, v89
	v_pk_mul_f32 v[88:89], v[26:27], v[118:119]
	s_add_i32 vcc_lo, s69, 7
	v_add_f32_e32 v88, v130, v88
	v_add_f32_e32 v162, v88, v89
	v_pk_mul_f32 v[88:89], v[26:27], v[128:129]
	s_min_u32 vcc_lo, vcc_lo, 15
	v_add_f32_e32 v88, v120, v88
	v_add_f32_e32 v161, v88, v89
	v_pk_mul_f32 v[88:89], v[32:33], v[108:109]
	v_pk_mov_b32 v[120:121], v[108:109], v[122:123] op_sel:[1,0]
	v_add_f32_e32 v88, v17, v88
	v_add_f32_e32 v110, v88, v89
	v_pk_mul_f32 v[88:89], v[28:29], v[120:121]
	s_add_i32 vcc_lo, vcc_lo, 1
	v_add_f32_e32 v88, v131, v88
	v_add_f32_e32 v164, v88, v89
	v_pk_mul_f32 v[88:89], v[28:29], v[122:123]
	v_lshlrev_b32_e32 v111, 16, v84
	v_add_f32_e32 v88, v110, v88
	v_and_b32_e32 v110, 0xffff0000, v84
	v_cvt_f32_ubyte0_e32 v84, vcc_lo
	v_lshlrev_b32_e32 v131, 16, v85
	v_and_b32_e32 v130, 0xffff0000, v85
	v_div_scale_f32 v85, vcc, v84, v84, 1.0
	v_rcp_f32_e32 v134, v85
	v_div_fixup_f32 v132, v87, v86, 1.0
	v_and_b32_e32 v86, 0xffff0000, v76
	v_lshlrev_b32_e32 v87, 16, v76
	v_fma_f32 v135, -v85, v134, 1.0
	v_fmac_f32_e32 v134, v135, v134
	v_div_scale_f32 v135, vcc, 1.0, v84, 1.0
	v_mul_f32_e32 v136, v135, v134
	v_fma_f32 v137, -v85, v136, v135
	v_fmac_f32_e32 v136, v137, v134
	v_fma_f32 v85, -v85, v136, v135
	v_div_fmas_f32 v85, v85, v134, v136
	v_div_fixup_f32 v165, v85, v84, 1.0
	v_pk_mul_f32 v[84:85], v[38:39], v[100:101]
	s_add_i32 vcc_lo, s69, 8
	v_add_f32_e32 v84, v14, v84
	v_add_f32_e32 v155, v84, v85
	v_pk_mul_f32 v[84:85], v[40:41], v[96:97]
	s_min_u32 vcc_lo, vcc_lo, 15
	v_add_f32_e32 v84, v15, v84
	v_add_f32_e32 v144, v84, v85
	v_pk_mul_f32 v[84:85], v[30:31], v[118:119]
	s_add_i32 vcc_lo, vcc_lo, 1
	v_add_f32_e32 v84, v16, v84
	v_add_f32_e32 v153, v84, v85
	v_pk_mul_f32 v[84:85], v[32:33], v[120:121]
	v_lshlrev_b32_e32 v137, 16, v64
	v_and_b32_e32 v136, 0xffff0000, v64
	v_cvt_f32_ubyte0_e32 v64, vcc_lo
	v_add_f32_e32 v84, v17, v84
	v_lshlrev_b32_e32 v135, 16, v65
	v_and_b32_e32 v134, 0xffff0000, v65
	v_div_scale_f32 v65, vcc, v64, v64, 1.0
	v_add_f32_e32 v145, v84, v85
	v_rcp_f32_e32 v84, v65
	v_and_b32_e32 v98, 0xffff0000, v92
	v_lshlrev_b32_e32 v99, 16, v92
	v_pk_add_f32 v[98:99], v[86:87], v[98:99] neg_lo:[0,1] neg_hi:[0,1]
	v_fma_f32 v85, -v65, v84, 1.0
	v_fmac_f32_e32 v84, v85, v84
	v_div_scale_f32 v85, vcc, 1.0, v64, 1.0
	v_mul_f32_e32 v96, v85, v84
	v_fma_f32 v97, -v65, v96, v85
	v_fmac_f32_e32 v96, v97, v84
	v_fma_f32 v65, -v65, v96, v85
	v_div_fmas_f32 v65, v65, v84, v96
	v_div_fixup_f32 v159, v65, v64, 1.0
	v_pk_mul_f32 v[64:65], v[38:39], v[124:125]
	s_add_i32 vcc_lo, s69, 9
	v_add_f32_e32 v64, v14, v64
	v_add_f32_e32 v158, v64, v65
	v_pk_mul_f32 v[64:65], v[40:41], v[126:127]
	s_min_u32 vcc_lo, vcc_lo, 15
	v_add_f32_e32 v64, v15, v64
	v_add_f32_e32 v157, v64, v65
	v_pk_mul_f32 v[64:65], v[30:31], v[128:129]
	s_add_i32 vcc_lo, vcc_lo, 1
	v_add_f32_e32 v64, v16, v64
	v_add_f32_e32 v156, v64, v65
	v_pk_mul_f32 v[64:65], v[32:33], v[122:123]
; __device__ __forceinline__ unsigned cvt_pk_bf16(float lo, float hi) { unsigned r; asm volatile("v_cvt_pk_bf16_f32 %0, %1, %2" : "=v"(r) : "v"(lo), "v"(hi)); return r; }
; __device__ __forceinline__ void unpack4(const v2u q, float (&f)[4]) { f[0] = bf_lo(q.x); f[1] = bf_hi(q.x); f[2] = bf_lo(q.y); f[3] = bf_hi(q.y); }
; template <int W>
; __device__ __forceinline__ void conv_pool_chunk(const bf16* PROJ, bf16* XC, bf16* POOLED, const float* conv_w, const float* conv_b, int chunk, int ch0) {
;     ...
;                 float pf[4], of[4]; unpack4(pn, pf); unpack4(ph[rr & (W - 1)], of);
;                 ph[rr & (W - 1)] = pn;
;                 const int t = t0 + r; const int cnt = (t + 1 < W) ? (t + 1) : W; const float inv = 1.0f / (float)cnt;
; #pragma unroll
;                 for (int j = 0; j < 4; ++j) { s[j] += pf[j] - of[j]; a[j] = s[j] * inv - pf[j]; }
;                 { v2u o; o.x = cvt_pk_bf16(a[0], a[1]); o.y = cvt_pk_bf16(a[2], a[3]); *(v2u*)(po + (size_t)q * D) = o; }
	v_and_b32_e32 v112, 0xffff0000, v77
	v_add_f32_e32 v64, v17, v64
	v_add_f32_e32 v152, v64, v65
	v_cvt_f32_ubyte0_e32 v64, vcc_lo
	v_div_scale_f32 v65, vcc, v64, v64, 1.0
	v_rcp_f32_e32 v84, v65
	v_lshlrev_b32_e32 v113, 16, v77
	v_and_b32_e32 v92, 0xffff0000, v93
	v_lshlrev_b32_e32 v93, 16, v93
	v_fma_f32 v85, -v65, v84, 1.0
	v_fmac_f32_e32 v84, v85, v84
	v_div_scale_f32 v85, vcc, 1.0, v64, 1.0
	v_mul_f32_e32 v96, v85, v84
	v_fma_f32 v97, -v65, v96, v85
	v_fmac_f32_e32 v96, v97, v84
	v_fma_f32 v65, -v65, v96, v85
	v_div_fmas_f32 v65, v65, v84, v96
	s_add_i32 vcc_lo, s69, 10
	s_min_u32 vcc_lo, vcc_lo, 15
	s_add_i32 vcc_lo, vcc_lo, 1
	v_div_fixup_f32 v151, v65, v64, 1.0
	v_cvt_f32_ubyte0_e32 v64, vcc_lo
	v_div_scale_f32 v65, vcc, v64, v64, 1.0
	v_rcp_f32_e32 v84, v65
	v_pk_add_f32 v[92:93], v[112:113], v[92:93] neg_lo:[0,1] neg_hi:[0,1]
	v_lshlrev_b32_e32 v115, 16, v79
	v_and_b32_e32 v114, 0xffff0000, v79
	v_fma_f32 v85, -v65, v84, 1.0
	v_fmac_f32_e32 v84, v85, v84
	v_div_scale_f32 v85, vcc, 1.0, v64, 1.0
	v_mul_f32_e32 v96, v85, v84
	v_fma_f32 v97, -v65, v96, v85
	v_fmac_f32_e32 v96, v97, v84
	v_fma_f32 v65, -v65, v96, v85
	v_div_fmas_f32 v65, v65, v84, v96
	s_add_i32 vcc_lo, s69, 11
	s_min_u32 vcc_lo, vcc_lo, 15
	s_add_i32 vcc_lo, vcc_lo, 1
	v_div_fixup_f32 v150, v65, v64, 1.0
	v_cvt_f32_ubyte0_e32 v64, vcc_lo
	v_div_scale_f32 v65, vcc, v64, v64, 1.0
	v_rcp_f32_e32 v84, v65
	v_pk_add_f32 v[90:91], v[90:91], v[98:99]
	v_add_f32_e32 v163, v88, v89
	v_lshlrev_b32_e32 v89, 16, v81
	v_fma_f32 v85, -v65, v84, 1.0
	v_fmac_f32_e32 v84, v85, v84
	v_div_scale_f32 v85, vcc, 1.0, v64, 1.0
	v_mul_f32_e32 v96, v85, v84
	v_fma_f32 v97, -v65, v96, v85
	v_fmac_f32_e32 v96, v97, v84
	v_fma_f32 v65, -v65, v96, v85
	v_div_fmas_f32 v65, v65, v84, v96
	s_add_i32 vcc_lo, s69, 12
	s_min_u32 vcc_lo, vcc_lo, 15
	s_add_i32 vcc_lo, vcc_lo, 1
	v_div_fixup_f32 v149, v65, v64, 1.0
	v_cvt_f32_ubyte0_e32 v64, vcc_lo
	v_div_scale_f32 v65, vcc, v64, v64, 1.0
	v_rcp_f32_e32 v84, v65
	v_and_b32_e32 v88, 0xffff0000, v81
	v_and_b32_e32 v98, 0xffff0000, v50
	v_lshlrev_b32_e32 v99, 16, v50
	v_fma_f32 v85, -v65, v84, 1.0
	v_fmac_f32_e32 v84, v85, v84
	v_div_scale_f32 v85, vcc, 1.0, v64, 1.0
	v_mul_f32_e32 v96, v85, v84
	v_fma_f32 v97, -v65, v96, v85
	v_fmac_f32_e32 v96, v97, v84
	v_fma_f32 v65, -v65, v96, v85
	v_div_fmas_f32 v65, v65, v84, v96
	s_add_i32 vcc_lo, s69, 13
	s_min_u32 vcc_lo, vcc_lo, 15
	s_add_i32 vcc_lo, vcc_lo, 1
	v_div_fixup_f32 v148, v65, v64, 1.0
	v_cvt_f32_ubyte0_e32 v64, vcc_lo
	v_div_scale_f32 v65, vcc, v64, v64, 1.0
	v_rcp_f32_e32 v84, v65
	s_add_i32 s69, s69, 14
	s_min_u32 s69, s69, 15
	s_add_i32 s69, s69, 1
	v_fma_f32 v85, -v65, v84, 1.0
	v_fmac_f32_e32 v84, v85, v84
	v_div_scale_f32 v85, vcc, 1.0, v64, 1.0
	v_mul_f32_e32 v96, v85, v84
	v_fma_f32 v97, -v65, v96, v85
	v_fmac_f32_e32 v96, v97, v84
	v_fma_f32 v65, -v65, v96, v85
	v_div_fmas_f32 v65, v65, v84, v96
	v_div_fixup_f32 v147, v65, v64, 1.0
	v_cvt_f32_ubyte0_e32 v64, s69
	v_div_scale_f32 v65, vcc, v64, v64, 1.0
	v_rcp_f32_e32 v84, v65
	v_lshlrev_b32_e32 v105, 16, v78
	v_and_b32_e32 v104, 0xffff0000, v78
	v_and_b32_e32 v100, 0xffff0000, v53
	v_fma_f32 v85, -v65, v84, 1.0
	v_fmac_f32_e32 v84, v85, v84
	v_div_scale_f32 v85, vcc, 1.0, v64, 1.0
	v_mul_f32_e32 v96, v85, v84
	v_fma_f32 v97, -v65, v96, v85
	v_fmac_f32_e32 v96, v97, v84
	v_fma_f32 v65, -v65, v96, v85
	v_div_fmas_f32 v65, v65, v84, v96
	v_div_fixup_f32 v146, v65, v64, 1.0
	v_pk_add_f32 v[64:65], v[94:95], v[92:93]
	v_pk_add_f32 v[84:85], v[114:115], v[116:117] neg_lo:[0,1] neg_hi:[0,1]
	v_and_b32_e32 v96, 0xffff0000, v51
	v_lshlrev_b32_e32 v97, 16, v51
	v_fma_f32 v51, v132, v91, -v87
	v_add_co_u32_e32 v50, vcc, s87, v82
	v_fma_f32 v166, v132, v65, -v113
	v_fma_f32 v167, v132, v64, -v112
	v_pk_add_f32 v[64:65], v[64:65], v[84:85]
	v_pk_add_f32 v[84:85], v[88:89], v[130:131] neg_lo:[0,1] neg_hi:[0,1]
	v_lshlrev_b32_e32 v101, 16, v53
	v_fma_f32 v53, v132, v90, -v86
	v_cvt_pk_bf16_f32 v130, v51, v53
	v_addc_co_u32_e32 v51, vcc, 0, v83, vcc
	v_pk_add_f32 v[86:87], v[104:105], v[106:107] neg_lo:[0,1] neg_hi:[0,1]
	v_and_b32_e32 v106, 0xffff0000, v52
	v_lshlrev_b32_e32 v107, 16, v52
	v_add_co_u32_e32 v52, vcc, s75, v82
	v_cvt_pk_bf16_f32 v131, v166, v167
	global_store_dwordx2 v[50:51], v[130:131], off
	s_nop 0
	v_addc_co_u32_e32 v53, vcc, 0, v83, vcc
	v_cvt_pk_bf16_f32 v50, v142, v160
	v_cvt_pk_bf16_f32 v51, v162, v164
	global_store_dwordx2 v[52:53], v[50:51], off
	v_add_co_u32_e32 v52, vcc, s3, v82
	v_pk_add_f32 v[138:139], v[64:65], v[84:85]
	v_pk_add_f32 v[86:87], v[90:91], v[86:87]
	v_addc_co_u32_e32 v53, vcc, 0, v83, vcc
	v_lshlrev_b32_e32 v109, 16, v80
	v_and_b32_e32 v108, 0xffff0000, v80
	v_fma_f32 v115, v140, v65, -v115
	v_fma_f32 v114, v140, v64, -v114
	v_fma_f32 v64, v165, v139, -v89
	v_fma_f32 v65, v165, v138, -v88
	v_and_b32_e32 v92, 0xffff0000, v57
	v_lshlrev_b32_e32 v93, 16, v57
	v_and_b32_e32 v88, 0xffff0000, v55
	v_lshlrev_b32_e32 v89, 16, v55
	v_fma_f32 v55, v140, v87, -v105
	v_fma_f32 v57, v140, v86, -v104
	v_cvt_pk_bf16_f32 v50, v55, v57
	v_cvt_pk_bf16_f32 v51, v115, v114
	global_store_dwordx2 v[52:53], v[50:51], off
	v_add_co_u32_e32 v52, vcc, s33, v82
	v_pk_add_f32 v[90:91], v[108:109], v[110:111] neg_lo:[0,1] neg_hi:[0,1]
	s_nop 0
	v_addc_co_u32_e32 v53, vcc, 0, v83, vcc
	v_pk_add_f32 v[140:141], v[86:87], v[90:91]
	v_cvt_pk_bf16_f32 v50, v133, v143
	v_cvt_pk_bf16_f32 v51, v161, v163
	global_store_dwordx2 v[52:53], v[50:51], off
	v_add_co_u32_e32 v52, vcc, s70, v82
	v_and_b32_e32 v116, 0xffff0000, v61
	v_lshlrev_b32_e32 v117, 16, v61
	v_and_b32_e32 v84, 0xffff0000, v59
	v_lshlrev_b32_e32 v85, 16, v59
	v_fma_f32 v59, v165, v141, -v109
; __device__ __forceinline__ unsigned cvt_pk_bf16(float lo, float hi) { unsigned r; asm volatile("v_cvt_pk_bf16_f32 %0, %1, %2" : "=v"(r) : "v"(lo), "v"(hi)); return r; }
; __device__ __forceinline__ void unpack4(const v2u q, float (&f)[4]) { f[0] = bf_lo(q.x); f[1] = bf_hi(q.x); f[2] = bf_lo(q.y); f[3] = bf_hi(q.y); }
; template <int W>
; __device__ __forceinline__ void conv_pool_chunk(const bf16* PROJ, bf16* XC, bf16* POOLED, const float* conv_w, const float* conv_b, int chunk, int ch0) {
;     ...
;             v2u xnb[8], pnb[8];
; #pragma unroll
;             for (int q = 0; q < 8; ++q) { xnb[q] = *(const v2u*)(p + (size_t)q * NIN); pnb[q] = *(const v2u*)(p + (size_t)q * NIN + 2 * D); }
; #pragma unroll
;             for (int q = 0; q < 8; ++q) { const int rr = h8 * 8 + q; const int r = rb * 16 + rr;
;                 const v2u xn = xnb[q], pn = pnb[q];
;                 float xf[4]; unpack4(xn, xf);
;                 float a[4];
; #pragma unroll
;                 for (int j = 0; j < 4; ++j) a[j] = cb[j] + cw[0][j] * cx[(rr + 1) & 3][j] + cw[1][j] * cx[(rr + 2) & 3][j] + cw[2][j] * cx[(rr + 3) & 3][j] + cw[3][j] * xf[j];
; #pragma unroll
;                 for (int j = 0; j < 4; ++j) cx[rr & 3][j] = xf[j];
;                 { v2u o; o.x = cvt_pk_bf16(a[0], a[1]); o.y = cvt_pk_bf16(a[2], a[3]); *(v2u*)(xo + (size_t)q * D) = o; }
;                 float pf[4], of[4]; unpack4(pn, pf); unpack4(ph[rr & (W - 1)], of);
;                 ph[rr & (W - 1)] = pn;
;                 const int t = t0 + r; const int cnt = (t + 1 < W) ? (t + 1) : W; const float inv = 1.0f / (float)cnt;
; #pragma unroll
;                 for (int j = 0; j < 4; ++j) { s[j] += pf[j] - of[j]; a[j] = s[j] * inv - pf[j]; }
;                 { v2u o; o.x = cvt_pk_bf16(a[0], a[1]); o.y = cvt_pk_bf16(a[2], a[3]); *(v2u*)(po + (size_t)q * D) = o; }
	v_fma_f32 v61, v165, v140, -v108
	v_cvt_pk_bf16_f32 v50, v59, v61
	v_addc_co_u32_e32 v53, vcc, 0, v83, vcc
	v_cvt_pk_bf16_f32 v51, v64, v65
	global_store_dwordx2 v[52:53], v[50:51], off
	v_add_co_u32_e32 v50, vcc, s88, v102
	v_and_b32_e32 v120, 0xffff0000, v60
	s_nop 0
	v_addc_co_u32_e32 v51, vcc, 0, v103, vcc
	global_load_dwordx2 v[164:165], v[50:51], off nt
	v_add_co_u32_e32 v50, vcc, s89, v102
	v_lshlrev_b32_e32 v121, 16, v60
	s_nop 0
	v_addc_co_u32_e32 v51, vcc, 0, v103, vcc
	global_load_dwordx2 v[64:65], v[50:51], off nt
	v_add_co_u32_e32 v50, vcc, s11, v102
	v_and_b32_e32 v112, 0xffff0000, v63
	s_nop 0
	v_addc_co_u32_e32 v51, vcc, 0, v103, vcc
	global_load_dwordx2 v[166:167], v[50:51], off nt
	v_add_co_u32_e32 v50, vcc, s35, v102
	v_lshlrev_b32_e32 v113, 16, v63
	s_nop 0
	v_addc_co_u32_e32 v51, vcc, 0, v103, vcc
	global_load_dwordx2 v[60:61], v[50:51], off nt
	v_add_co_u32_e32 v50, vcc, s78, v102
	v_and_b32_e32 v118, 0xffff0000, v62
	s_nop 0
	v_addc_co_u32_e32 v51, vcc, 0, v103, vcc
	global_load_dwordx2 v[130:131], v[50:51], off nt
	v_add_co_u32_e32 v50, vcc, s79, v102
	v_lshlrev_b32_e32 v119, 16, v62
	s_nop 0
	v_addc_co_u32_e32 v51, vcc, 0, v103, vcc
	global_load_dwordx2 v[62:63], v[50:51], off nt
	v_add_co_u32_e32 v50, vcc, s82, v102
	v_and_b32_e32 v90, 0xffff0000, v54
	s_nop 0
	v_addc_co_u32_e32 v51, vcc, 0, v103, vcc
	global_load_dwordx2 v[132:133], v[50:51], off nt
	v_add_co_u32_e32 v50, vcc, s83, v102
	v_lshlrev_b32_e32 v91, 16, v54
	s_nop 0
	v_addc_co_u32_e32 v51, vcc, 0, v103, vcc
	global_load_dwordx2 v[52:53], v[50:51], off nt
	v_add_co_u32_e32 v50, vcc, s28, v102
	v_and_b32_e32 v94, 0xffff0000, v56
	s_nop 0
	v_addc_co_u32_e32 v51, vcc, 0, v103, vcc
	global_load_dwordx2 v[114:115], v[50:51], off nt
	v_add_co_u32_e32 v50, vcc, s29, v102
	v_lshlrev_b32_e32 v95, 16, v56
	s_nop 0
	v_addc_co_u32_e32 v51, vcc, 0, v103, vcc
	v_add_co_u32_e32 v54, vcc, s10, v102
	v_and_b32_e32 v86, 0xffff0000, v58
	s_nop 0
	v_addc_co_u32_e32 v55, vcc, 0, v103, vcc
	global_load_dwordx2 v[108:109], v[54:55], off nt
	v_add_co_u32_e32 v54, vcc, s72, v102
	v_lshlrev_b32_e32 v87, 16, v58
	s_nop 0
	v_addc_co_u32_e32 v55, vcc, 0, v103, vcc
	global_load_dwordx2 v[56:57], v[54:55], off nt
	v_add_co_u32_e32 v54, vcc, s73, v102
	global_load_dwordx2 v[50:51], v[50:51], off nt
	s_nop 0
	v_addc_co_u32_e32 v55, vcc, 0, v103, vcc
	global_load_dwordx2 v[110:111], v[54:55], off nt
	v_add_co_u32_e32 v54, vcc, s59, v102
	s_add_i32 s68, s68, 16
	s_nop 0
	v_addc_co_u32_e32 v55, vcc, 0, v103, vcc
	v_add_co_u32_e32 v58, vcc, s62, v102
	global_load_dwordx2 v[54:55], v[54:55], off nt
	s_nop 0
	v_addc_co_u32_e32 v59, vcc, 0, v103, vcc
	global_load_dwordx2 v[104:105], v[58:59], off nt
	v_add_co_u32_e32 v58, vcc, s63, v102
	s_add_u32 s0, s0, 0x20000
	s_nop 0
	v_addc_co_u32_e32 v59, vcc, 0, v103, vcc
	s_waitcnt vmcnt(0)
	v_lshlrev_b32_e32 v103, 16, v64
	v_and_b32_e32 v102, 0xffff0000, v64
	v_pk_add_f32 v[136:137], v[102:103], v[136:137] neg_lo:[0,1] neg_hi:[0,1]
	v_lshlrev_b32_e32 v169, 16, v65
	v_and_b32_e32 v168, 0xffff0000, v65
	v_pk_add_f32 v[140:141], v[140:141], v[136:137]
	v_lshlrev_b32_e32 v137, 16, v166
	v_fma_f32 v160, v159, v141, -v103
	v_fma_f32 v161, v159, v140, -v102
	v_pk_add_f32 v[102:103], v[168:169], v[134:135] neg_lo:[0,1] neg_hi:[0,1]
	v_lshlrev_b32_e32 v136, 16, v164
	v_pk_add_f32 v[142:143], v[138:139], v[102:103]
	v_pk_mov_b32 v[138:139], v[124:125], v[136:137] op_sel:[1,0]
	v_and_b32_e32 v135, 0xffff0000, v166
	v_pk_mul_f32 v[102:103], v[34:35], v[138:139]
	v_and_b32_e32 v134, 0xffff0000, v164
	v_add_f32_e32 v102, v155, v102
	v_add_f32_e32 v124, v102, v103
	v_pk_mul_f32 v[102:103], v[34:35], v[136:137]
	v_pk_mov_b32 v[126:127], v[126:127], v[134:135] op_sel:[1,0]
	v_add_f32_e32 v102, v158, v102
	v_add_f32_e32 v155, v102, v103
	v_pk_mul_f32 v[102:103], v[36:37], v[126:127]
	global_load_dwordx2 v[58:59], v[58:59], off nt
	v_add_f32_e32 v102, v144, v102
	v_add_f32_e32 v102, v102, v103
	v_cvt_pk_bf16_f32 v144, v124, v102
	v_pk_mul_f32 v[102:103], v[36:37], v[134:135]
	v_lshlrev_b32_e32 v125, 16, v167
	v_lshlrev_b32_e32 v124, 16, v165
	v_add_f32_e32 v102, v157, v102
	v_pk_mov_b32 v[128:129], v[128:129], v[124:125] op_sel:[1,0]
	v_add_f32_e32 v157, v102, v103
	v_pk_mul_f32 v[102:103], v[26:27], v[128:129]
	v_fma_f32 v162, v159, v143, -v169
	v_add_f32_e32 v102, v153, v102
	v_add_f32_e32 v158, v102, v103
	v_pk_mul_f32 v[102:103], v[26:27], v[124:125]
	v_fma_f32 v159, v159, v142, -v168
	v_add_f32_e32 v102, v156, v102
	v_add_f32_e32 v153, v102, v103
	v_and_b32_e32 v103, 0xffff0000, v167
	v_and_b32_e32 v102, 0xffff0000, v165
	v_pk_mov_b32 v[122:123], v[122:123], v[102:103] op_sel:[1,0]
	v_pk_mul_f32 v[126:127], v[40:41], v[126:127]
	v_pk_mul_f32 v[164:165], v[28:29], v[122:123]
	v_add_f32_e32 v126, v15, v126
	v_add_f32_e32 v145, v145, v164
	v_add_co_u32_e32 v164, vcc, s18, v82
	v_add_f32_e32 v145, v145, v165
	s_nop 0
	v_addc_co_u32_e32 v165, vcc, 0, v83, vcc
	v_cvt_pk_bf16_f32 v145, v158, v145
	v_add_co_u32_e32 v158, vcc, s19, v82
	global_store_dwordx2 v[164:165], v[144:145], off
	v_cvt_pk_bf16_f32 v144, v160, v161
	v_cvt_pk_bf16_f32 v145, v162, v159
	s_nop 0
	v_addc_co_u32_e32 v159, vcc, 0, v83, vcc
	global_store_dwordx2 v[158:159], v[144:145], off
	v_pk_mul_f32 v[144:145], v[28:29], v[102:103]
	v_pk_mul_f32 v[138:139], v[38:39], v[138:139]
	v_add_f32_e32 v144, v152, v144
	v_add_f32_e32 v145, v144, v145
	v_add_co_u32_e32 v152, vcc, s20, v82
	v_cvt_pk_bf16_f32 v144, v155, v157
	v_cvt_pk_bf16_f32 v145, v153, v145
	v_pk_mul_f32 v[122:123], v[32:33], v[122:123]
	s_nop 0
	v_addc_co_u32_e32 v153, vcc, 0, v83, vcc
	global_store_dwordx2 v[152:153], v[144:145], off
; __device__ __forceinline__ unsigned cvt_pk_bf16(float lo, float hi) { unsigned r; asm volatile("v_cvt_pk_bf16_f32 %0, %1, %2" : "=v"(r) : "v"(lo), "v"(hi)); return r; }
; __device__ __forceinline__ void unpack4(const v2u q, float (&f)[4]) { f[0] = bf_lo(q.x); f[1] = bf_hi(q.x); f[2] = bf_lo(q.y); f[3] = bf_hi(q.y); }
; template <int W>
; __device__ __forceinline__ void conv_pool_chunk(const bf16* PROJ, bf16* XC, bf16* POOLED, const float* conv_w, const float* conv_b, int chunk, int ch0) {
;     ...
;                 for (int j = 0; j < 4; ++j) a[j] = cb[j] + cw[0][j] * cx[(rr + 1) & 3][j] + cw[1][j] * cx[(rr + 2) & 3][j] + cw[2][j] * cx[(rr + 3) & 3][j] + cw[3][j] * xf[j];
; #pragma unroll
;                 for (int j = 0; j < 4; ++j) cx[rr & 3][j] = xf[j];
;                 { v2u o; o.x = cvt_pk_bf16(a[0], a[1]); o.y = cvt_pk_bf16(a[2], a[3]); *(v2u*)(xo + (size_t)q * D) = o; }
;                 float pf[4], of[4]; unpack4(pn, pf); unpack4(ph[rr & (W - 1)], of);
;                 ph[rr & (W - 1)] = pn;
;                 const int t = t0 + r; const int cnt = (t + 1 < W) ? (t + 1) : W; const float inv = 1.0f / (float)cnt;
; #pragma unroll
;                 for (int j = 0; j < 4; ++j) { s[j] += pf[j] - of[j]; a[j] = s[j] * inv - pf[j]; }
;                 { v2u o; o.x = cvt_pk_bf16(a[0], a[1]); o.y = cvt_pk_bf16(a[2], a[3]); *(v2u*)(po + (size_t)q * D) = o; }
	v_and_b32_e32 v144, 0xffff0000, v60
	v_lshlrev_b32_e32 v145, 16, v60
	v_and_b32_e32 v152, 0xffff0000, v61
	v_lshlrev_b32_e32 v153, 16, v61
	v_pk_add_f32 v[120:121], v[144:145], v[120:121] neg_lo:[0,1] neg_hi:[0,1]
	v_pk_add_f32 v[116:117], v[152:153], v[116:117] neg_lo:[0,1] neg_hi:[0,1]
	v_pk_add_f32 v[120:121], v[140:141], v[120:121]
	v_pk_add_f32 v[116:117], v[142:143], v[116:117]
	v_fma_f32 v140, v151, v121, -v145
	v_fma_f32 v141, v151, v120, -v144
	v_fma_f32 v142, v151, v117, -v153
	v_fma_f32 v143, v151, v116, -v152
	v_cvt_pk_bf16_f32 v140, v140, v141
	v_cvt_pk_bf16_f32 v141, v142, v143
	v_add_co_u32_e32 v142, vcc, s21, v82
	v_add_f32_e32 v138, v14, v138
	s_nop 0
	v_addc_co_u32_e32 v143, vcc, 0, v83, vcc
	global_store_dwordx2 v[142:143], v[140:141], off
	v_add_f32_e32 v141, v126, v127
	v_pk_mul_f32 v[126:127], v[30:31], v[128:129]
	v_add_f32_e32 v122, v17, v122
	v_add_f32_e32 v126, v16, v126
	v_add_f32_e32 v142, v126, v127
	v_and_b32_e32 v126, 0xffff0000, v63
	v_lshlrev_b32_e32 v127, 16, v63
	v_pk_add_f32 v[112:113], v[126:127], v[112:113] neg_lo:[0,1] neg_hi:[0,1]
	v_add_f32_e32 v140, v138, v139
	v_add_f32_e32 v143, v122, v123
	v_and_b32_e32 v122, 0xffff0000, v62
	v_lshlrev_b32_e32 v123, 16, v62
	v_pk_add_f32 v[138:139], v[116:117], v[112:113]
	v_pk_mul_f32 v[112:113], v[38:39], v[136:137]
	v_pk_add_f32 v[118:119], v[122:123], v[118:119] neg_lo:[0,1] neg_hi:[0,1]
	v_add_f32_e32 v112, v14, v112
	v_pk_add_f32 v[128:129], v[120:121], v[118:119]
	v_add_f32_e32 v118, v112, v113
	v_lshlrev_b32_e32 v112, 16, v130
	v_lshlrev_b32_e32 v113, 16, v132
	v_fma_f32 v144, v150, v129, -v123
	v_fma_f32 v145, v150, v128, -v122
	v_pk_mov_b32 v[122:123], v[136:137], v[112:113] op_sel:[1,0]
	v_fma_f32 v151, v150, v139, -v127
	v_pk_mul_f32 v[116:117], v[34:35], v[122:123]
	v_fma_f32 v150, v150, v138, -v126
	v_add_f32_e32 v116, v140, v116
	v_add_f32_e32 v120, v116, v117
	v_pk_mul_f32 v[116:117], v[34:35], v[112:113]
	s_addc_u32 s1, s1, 0
	v_add_f32_e32 v116, v118, v116
	v_add_f32_e32 v136, v116, v117
	v_pk_mul_f32 v[116:117], v[40:41], v[134:135]
	s_add_u32 s40, s40, 0xa0000
	v_add_f32_e32 v116, v15, v116
	v_add_f32_e32 v121, v116, v117
	v_and_b32_e32 v117, 0xffff0000, v132
	v_and_b32_e32 v116, 0xffff0000, v130
	v_pk_mov_b32 v[126:127], v[134:135], v[116:117] op_sel:[1,0]
	s_addc_u32 s41, s41, 0
	v_pk_mul_f32 v[118:119], v[36:37], v[126:127]
	s_cmp_lg_u32 s68, 64
	v_add_f32_e32 v118, v141, v118
	v_add_f32_e32 v118, v118, v119
	v_cvt_pk_bf16_f32 v130, v120, v118
	v_pk_mul_f32 v[118:119], v[36:37], v[116:117]
	s_nop 0
	v_add_f32_e32 v118, v121, v118
	v_add_f32_e32 v134, v118, v119
	v_pk_mul_f32 v[118:119], v[30:31], v[124:125]
	s_nop 0
	v_add_f32_e32 v118, v16, v118
	v_add_f32_e32 v132, v118, v119
	v_lshlrev_b32_e32 v118, 16, v131
	v_lshlrev_b32_e32 v119, 16, v133
	v_pk_mov_b32 v[124:125], v[124:125], v[118:119] op_sel:[1,0]
	s_nop 0
	v_pk_mul_f32 v[120:121], v[26:27], v[124:125]
	s_nop 0
	v_add_f32_e32 v120, v142, v120
	v_add_f32_e32 v135, v120, v121
	v_pk_mul_f32 v[120:121], v[26:27], v[118:119]
	s_nop 0
	v_add_f32_e32 v120, v132, v120
	v_add_f32_e32 v137, v120, v121
	v_pk_mul_f32 v[120:121], v[32:33], v[102:103]
	s_nop 0
	v_add_f32_e32 v120, v17, v120
	v_add_f32_e32 v140, v120, v121
	v_and_b32_e32 v121, 0xffff0000, v133
	v_and_b32_e32 v120, 0xffff0000, v131
	v_pk_mov_b32 v[102:103], v[102:103], v[120:121] op_sel:[1,0]
	s_nop 0
	v_pk_mul_f32 v[132:133], v[28:29], v[102:103]
	v_pk_mul_f32 v[102:103], v[32:33], v[102:103]
	v_add_f32_e32 v131, v143, v132
	v_add_co_u32_e32 v132, vcc, s22, v82
	v_add_f32_e32 v131, v131, v133
	s_nop 0
	v_addc_co_u32_e32 v133, vcc, 0, v83, vcc
	v_cvt_pk_bf16_f32 v131, v135, v131
	global_store_dwordx2 v[132:133], v[130:131], off
	v_add_co_u32_e32 v132, vcc, s23, v82
	v_cvt_pk_bf16_f32 v130, v144, v145
	v_cvt_pk_bf16_f32 v131, v151, v150
	v_add_f32_e32 v102, v17, v102
	s_nop 0
	v_addc_co_u32_e32 v133, vcc, 0, v83, vcc
	global_store_dwordx2 v[132:133], v[130:131], off
	v_pk_mul_f32 v[130:131], v[28:29], v[120:121]
	v_add_co_u32_e32 v132, vcc, s24, v82
	v_add_f32_e32 v130, v140, v130
	v_add_f32_e32 v131, v130, v131
	v_cvt_pk_bf16_f32 v130, v136, v134
	v_cvt_pk_bf16_f32 v131, v137, v131
	v_addc_co_u32_e32 v133, vcc, 0, v83, vcc
	global_store_dwordx2 v[132:133], v[130:131], off
	v_and_b32_e32 v130, 0xffff0000, v52
	v_lshlrev_b32_e32 v131, 16, v52
	v_and_b32_e32 v132, 0xffff0000, v53
	v_lshlrev_b32_e32 v133, 16, v53
	v_pk_add_f32 v[106:107], v[130:131], v[106:107] neg_lo:[0,1] neg_hi:[0,1]
	v_pk_add_f32 v[100:101], v[132:133], v[100:101] neg_lo:[0,1] neg_hi:[0,1]
	v_pk_add_f32 v[134:135], v[128:129], v[106:107]
	v_pk_add_f32 v[100:101], v[138:139], v[100:101]
	v_fma_f32 v106, v149, v135, -v131
	v_fma_f32 v107, v149, v134, -v130
	v_fma_f32 v128, v149, v101, -v133
	v_fma_f32 v129, v149, v100, -v132
	v_cvt_pk_bf16_f32 v106, v106, v107
	v_cvt_pk_bf16_f32 v107, v128, v129
	v_add_co_u32_e32 v128, vcc, s25, v82
	v_lshlrev_b32_e32 v133, 16, v114
	s_nop 0
	v_addc_co_u32_e32 v129, vcc, 0, v83, vcc
	global_store_dwordx2 v[128:129], v[106:107], off
	v_and_b32_e32 v107, 0xffff0000, v114
	v_lshlrev_b32_e32 v131, 16, v115
	v_and_b32_e32 v129, 0xffff0000, v115
	v_pk_mul_f32 v[114:115], v[38:39], v[122:123]
	v_mov_b32_e32 v132, v113
	v_add_f32_e32 v106, v14, v114
	v_add_f32_e32 v106, v106, v115
	v_pk_mul_f32 v[114:115], v[34:35], v[132:133]
	v_mov_b32_e32 v130, v119
	v_add_f32_e32 v106, v106, v114
	v_add_f32_e32 v122, v106, v115
	v_pk_mul_f32 v[114:115], v[40:41], v[126:127]
	v_mov_b32_e32 v128, v121
	v_add_f32_e32 v106, v15, v114
	v_add_f32_e32 v123, v106, v115
	v_mov_b32_e32 v106, v117
	v_pk_mul_f32 v[114:115], v[36:37], v[106:107]
	s_nop 0
; __device__ __forceinline__ unsigned cvt_pk_bf16(float lo, float hi) { unsigned r; asm volatile("v_cvt_pk_bf16_f32 %0, %1, %2" : "=v"(r) : "v"(lo), "v"(hi)); return r; }
; __device__ __forceinline__ void unpack4(const v2u q, float (&f)[4]) { f[0] = bf_lo(q.x); f[1] = bf_hi(q.x); f[2] = bf_lo(q.y); f[3] = bf_hi(q.y); }
; template <int W>
; __device__ __forceinline__ void conv_pool_chunk(const bf16* PROJ, bf16* XC, bf16* POOLED, const float* conv_w, const float* conv_b, int chunk, int ch0) {
;     ...
;                 for (int j = 0; j < 4; ++j) a[j] = cb[j] + cw[0][j] * cx[(rr + 1) & 3][j] + cw[1][j] * cx[(rr + 2) & 3][j] + cw[2][j] * cx[(rr + 3) & 3][j] + cw[3][j] * xf[j];
; #pragma unroll
;                 for (int j = 0; j < 4; ++j) cx[rr & 3][j] = xf[j];
;                 { v2u o; o.x = cvt_pk_bf16(a[0], a[1]); o.y = cvt_pk_bf16(a[2], a[3]); *(v2u*)(xo + (size_t)q * D) = o; }
;                 float pf[4], of[4]; unpack4(pn, pf); unpack4(ph[rr & (W - 1)], of);
;                 ph[rr & (W - 1)] = pn;
;                 const int t = t0 + r; const int cnt = (t + 1 < W) ? (t + 1) : W; const float inv = 1.0f / (float)cnt;
; #pragma unroll
;                 for (int j = 0; j < 4; ++j) { s[j] += pf[j] - of[j]; a[j] = s[j] * inv - pf[j]; }
;                 { v2u o; o.x = cvt_pk_bf16(a[0], a[1]); o.y = cvt_pk_bf16(a[2], a[3]); *(v2u*)(po + (size_t)q * D) = o; }
	v_add_f32_e32 v114, v123, v114
	v_add_f32_e32 v123, v114, v115
	v_pk_mul_f32 v[114:115], v[30:31], v[124:125]
	s_nop 0
	v_add_f32_e32 v114, v16, v114
	v_add_f32_e32 v124, v114, v115
	v_pk_mul_f32 v[114:115], v[26:27], v[130:131]
	s_nop 0
	v_add_f32_e32 v114, v124, v114
	v_add_f32_e32 v114, v114, v115
	v_add_f32_e32 v115, v102, v103
	v_pk_mul_f32 v[102:103], v[28:29], v[128:129]
	s_nop 0
	v_add_f32_e32 v102, v115, v102
	v_add_f32_e32 v103, v102, v103
	v_cvt_pk_bf16_f32 v102, v122, v123
	v_cvt_pk_bf16_f32 v103, v114, v103
	v_add_co_u32_e32 v114, vcc, s26, v82
	s_nop 1
	v_addc_co_u32_e32 v115, vcc, 0, v83, vcc
	global_store_dwordx2 v[114:115], v[102:103], off
	v_and_b32_e32 v102, 0xffff0000, v50
	v_lshlrev_b32_e32 v103, 16, v50
	v_and_b32_e32 v114, 0xffff0000, v51
	v_lshlrev_b32_e32 v115, 16, v51
	v_pk_add_f32 v[98:99], v[102:103], v[98:99] neg_lo:[0,1] neg_hi:[0,1]
	v_pk_add_f32 v[96:97], v[114:115], v[96:97] neg_lo:[0,1] neg_hi:[0,1]
	v_pk_add_f32 v[98:99], v[134:135], v[98:99]
	v_pk_add_f32 v[96:97], v[100:101], v[96:97]
	v_fma_f32 v102, v148, v98, -v102
	v_fma_f32 v103, v148, v99, -v103
	v_fma_f32 v101, v148, v97, -v115
	v_cvt_pk_bf16_f32 v100, v103, v102
	v_add_co_u32_e32 v102, vcc, s27, v82
	v_fma_f32 v114, v148, v96, -v114
	v_cvt_pk_bf16_f32 v101, v101, v114
	s_nop 0
	v_addc_co_u32_e32 v103, vcc, 0, v83, vcc
	global_store_dwordx2 v[102:103], v[100:101], off
	v_pk_mul_f32 v[100:101], v[38:39], v[112:113]
	v_and_b32_e32 v102, 0xffff0000, v57
	v_add_f32_e32 v100, v14, v100
	v_add_f32_e32 v114, v100, v101
	v_pk_mul_f32 v[100:101], v[40:41], v[116:117]
	v_lshlrev_b32_e32 v103, 16, v57
	v_add_f32_e32 v100, v15, v100
	v_add_f32_e32 v116, v100, v101
	v_pk_mul_f32 v[100:101], v[30:31], v[118:119]
	v_pk_add_f32 v[92:93], v[102:103], v[92:93] neg_lo:[0,1] neg_hi:[0,1]
	v_add_f32_e32 v100, v16, v100
	v_add_f32_e32 v123, v100, v101
	v_pk_mul_f32 v[100:101], v[32:33], v[120:121]
	v_pk_add_f32 v[120:121], v[96:97], v[92:93]
	v_add_f32_e32 v100, v17, v100
	v_add_f32_e32 v126, v100, v101
	v_and_b32_e32 v100, 0xffff0000, v56
	v_lshlrev_b32_e32 v101, 16, v56
	v_pk_add_f32 v[94:95], v[100:101], v[94:95] neg_lo:[0,1] neg_hi:[0,1]
	v_pk_mul_f32 v[92:93], v[38:39], v[132:133]
	v_pk_add_f32 v[118:119], v[98:99], v[94:95]
	v_add_f32_e32 v92, v14, v92
	v_fma_f32 v127, v147, v119, -v101
	v_fma_f32 v134, v147, v118, -v100
	v_lshlrev_b32_e32 v101, 16, v110
	v_lshlrev_b32_e32 v100, 16, v108
	v_add_f32_e32 v96, v92, v93
	v_pk_mov_b32 v[92:93], v[100:101], v[100:101] op_sel:[1,0]
	v_mov_b32_e32 v112, v133
	v_mov_b32_e32 v113, v93
	v_pk_mul_f32 v[94:95], v[34:35], v[112:113]
	v_and_b32_e32 v99, 0xffff0000, v110
	v_add_f32_e32 v93, v114, v94
	v_add_f32_e32 v93, v93, v95
	v_pk_mul_f32 v[94:95], v[34:35], v[100:101]
	v_and_b32_e32 v98, 0xffff0000, v108
	v_add_f32_e32 v94, v96, v94
	v_fma_f32 v135, v147, v121, -v103
	v_fma_f32 v136, v147, v120, -v102
	v_add_f32_e32 v132, v94, v95
	v_pk_mul_f32 v[94:95], v[40:41], v[106:107]
	v_pk_mov_b32 v[102:103], v[98:99], v[98:99] op_sel:[1,0]
	v_add_f32_e32 v94, v15, v94
	v_mov_b32_e32 v114, v107
	v_mov_b32_e32 v115, v103
	v_add_f32_e32 v96, v94, v95
	v_pk_mul_f32 v[94:95], v[36:37], v[114:115]
	v_lshlrev_b32_e32 v97, 16, v111
	v_add_f32_e32 v94, v116, v94
	v_add_f32_e32 v94, v94, v95
	v_cvt_pk_bf16_f32 v122, v93, v94
	v_pk_mul_f32 v[94:95], v[36:37], v[98:99]
	v_mov_b32_e32 v116, v131
	v_add_f32_e32 v93, v96, v94
	v_lshlrev_b32_e32 v96, 16, v109
	v_add_f32_e32 v93, v93, v95
	v_pk_mul_f32 v[94:95], v[30:31], v[130:131]
	v_pk_mov_b32 v[106:107], v[96:97], v[96:97] op_sel:[1,0]
	v_add_f32_e32 v94, v16, v94
	v_mov_b32_e32 v117, v107
	v_add_f32_e32 v103, v94, v95
	v_pk_mul_f32 v[94:95], v[26:27], v[116:117]
	v_mov_b32_e32 v110, v129
	v_add_f32_e32 v94, v123, v94
	v_add_f32_e32 v107, v94, v95
	v_pk_mul_f32 v[94:95], v[26:27], v[96:97]
	s_nop 0
	v_add_f32_e32 v94, v103, v94
	v_add_f32_e32 v103, v94, v95
	v_pk_mul_f32 v[94:95], v[32:33], v[128:129]
	s_nop 0
	v_add_f32_e32 v94, v17, v94
	v_add_f32_e32 v128, v94, v95
	v_and_b32_e32 v95, 0xffff0000, v111
	v_and_b32_e32 v94, 0xffff0000, v109
	v_pk_mov_b32 v[108:109], v[94:95], v[94:95] op_sel:[1,0]
	s_nop 0
	v_mov_b32_e32 v111, v109
	v_pk_mul_f32 v[124:125], v[28:29], v[110:111]
	s_nop 0
	v_add_f32_e32 v109, v126, v124
	v_add_co_u32_e32 v124, vcc, s12, v82
	v_add_f32_e32 v109, v109, v125
	s_nop 0
	v_addc_co_u32_e32 v125, vcc, 0, v83, vcc
	v_cvt_pk_bf16_f32 v123, v107, v109
	global_store_dwordx2 v[124:125], v[122:123], off
	v_add_co_u32_e32 v124, vcc, s13, v82
	v_cvt_pk_bf16_f32 v122, v127, v134
	v_cvt_pk_bf16_f32 v123, v135, v136
	s_nop 1
	v_addc_co_u32_e32 v125, vcc, 0, v83, vcc
	global_store_dwordx2 v[124:125], v[122:123], off
	v_pk_mul_f32 v[122:123], v[28:29], v[94:95]
	v_add_co_u32_e32 v124, vcc, s74, v82
	v_add_f32_e32 v107, v128, v122
	v_add_f32_e32 v107, v107, v123
	v_cvt_pk_bf16_f32 v122, v132, v93
	v_cvt_pk_bf16_f32 v123, v103, v107
	v_addc_co_u32_e32 v125, vcc, 0, v83, vcc
	global_store_dwordx2 v[124:125], v[122:123], off
	v_and_b32_e32 v122, 0xffff0000, v54
	v_lshlrev_b32_e32 v123, 16, v54
	v_and_b32_e32 v124, 0xffff0000, v55
	v_lshlrev_b32_e32 v125, 16, v55
	v_pk_add_f32 v[90:91], v[122:123], v[90:91] neg_lo:[0,1] neg_hi:[0,1]
	v_pk_add_f32 v[88:89], v[124:125], v[88:89] neg_lo:[0,1] neg_hi:[0,1]
	v_pk_add_f32 v[90:91], v[118:119], v[90:91]
	v_pk_add_f32 v[88:89], v[120:121], v[88:89]
	v_fma_f32 v93, v146, v91, -v123
	v_fma_f32 v103, v146, v90, -v122
	v_fma_f32 v107, v146, v89, -v125
	v_fma_f32 v109, v146, v88, -v124
	v_cvt_pk_bf16_f32 v118, v93, v103
	v_cvt_pk_bf16_f32 v119, v107, v109
	v_lshlrev_b32_e32 v93, 16, v104
	v_and_b32_e32 v103, 0xffff0000, v104
	v_lshlrev_b32_e32 v107, 16, v105
; __device__ __forceinline__ unsigned cvt_pk_bf16(float lo, float hi) { unsigned r; asm volatile("v_cvt_pk_bf16_f32 %0, %1, %2" : "=v"(r) : "v"(lo), "v"(hi)); return r; }
; __device__ __forceinline__ void unpack4(const v2u q, float (&f)[4]) { f[0] = bf_lo(q.x); f[1] = bf_hi(q.x); f[2] = bf_lo(q.y); f[3] = bf_hi(q.y); }
; template <int W>
; __device__ __forceinline__ void conv_pool_chunk(const bf16* PROJ, bf16* XC, bf16* POOLED, const float* conv_w, const float* conv_b, int chunk, int ch0) {
;     ...
;     if (t0 > 0) {
; #pragma unroll
;         for (int q = 1; q <= 3; ++q) { const v2u x = *(const v2u*)(pr - (ptrdiff_t)q * NIN); unpack4(x, cx[(64 - q) & 3]); }
; #pragma unroll
;         for (int q = 1; q < W; ++q) { const v2u x = *(const v2u*)(pr + 2 * D - (ptrdiff_t)q * NIN); ph[(64 - q) & (W - 1)] = x; float f[4]; unpack4(x, f);
; #pragma unroll
;             for (int j = 0; j < 4; ++j) s[j] += f[j]; }
;     }
;     ...
;             for (int q = 0; q < 8; ++q) { const int rr = h8 * 8 + q; const int r = rb * 16 + rr;
;                 const v2u xn = xnb[q], pn = pnb[q];
;                 float xf[4]; unpack4(xn, xf);
;                 float a[4];
; #pragma unroll
;                 for (int j = 0; j < 4; ++j) a[j] = cb[j] + cw[0][j] * cx[(rr + 1) & 3][j] + cw[1][j] * cx[(rr + 2) & 3][j] + cw[2][j] * cx[(rr + 3) & 3][j] + cw[3][j] * xf[j];
; #pragma unroll
;                 for (int j = 0; j < 4; ++j) cx[rr & 3][j] = xf[j];
;                 { v2u o; o.x = cvt_pk_bf16(a[0], a[1]); o.y = cvt_pk_bf16(a[2], a[3]); *(v2u*)(xo + (size_t)q * D) = o; }
;                 float pf[4], of[4]; unpack4(pn, pf); unpack4(ph[rr & (W - 1)], of);
;                 ph[rr & (W - 1)] = pn;
;                 const int t = t0 + r; const int cnt = (t + 1 < W) ? (t + 1) : W; const float inv = 1.0f / (float)cnt;
; #pragma unroll
;                 for (int j = 0; j < 4; ++j) { s[j] += pf[j] - of[j]; a[j] = s[j] * inv - pf[j]; }
;                 { v2u o; o.x = cvt_pk_bf16(a[0], a[1]); o.y = cvt_pk_bf16(a[2], a[3]); *(v2u*)(po + (size_t)q * D) = o; }
;             }
;             p += 8 * NIN; xo += 8 * D; po += 8 * D;
	v_and_b32_e32 v109, 0xffff0000, v105
	v_pk_mul_f32 v[104:105], v[38:39], v[112:113]
	v_add_co_u32_e32 v120, vcc, s84, v82
	v_add_f32_e32 v104, v14, v104
	v_add_f32_e32 v112, v104, v105
	v_pk_mul_f32 v[104:105], v[34:35], v[92:93]
	v_addc_co_u32_e32 v121, vcc, 0, v83, vcc
	v_add_f32_e32 v92, v112, v104
	v_add_f32_e32 v92, v92, v105
	v_pk_mul_f32 v[104:105], v[40:41], v[114:115]
	global_store_dwordx2 v[120:121], v[118:119], off
	v_add_f32_e32 v104, v15, v104
	v_add_f32_e32 v112, v104, v105
	v_pk_mul_f32 v[104:105], v[36:37], v[102:103]
	v_mov_b32_e32 v114, v103
	v_add_f32_e32 v102, v112, v104
	v_add_f32_e32 v102, v102, v105
	v_pk_mul_f32 v[104:105], v[30:31], v[116:117]
	v_mov_b32_e32 v116, v93
	v_add_f32_e32 v104, v16, v104
	v_add_f32_e32 v112, v104, v105
	v_pk_mul_f32 v[104:105], v[26:27], v[106:107]
	v_mov_b64_e32 v[118:119], v[68:69]
	v_add_f32_e32 v104, v112, v104
	v_add_f32_e32 v106, v104, v105
	v_pk_mul_f32 v[104:105], v[32:33], v[110:111]
	v_mov_b32_e32 v112, v107
	v_add_f32_e32 v104, v17, v104
	v_add_f32_e32 v110, v104, v105
	v_pk_mul_f32 v[104:105], v[28:29], v[108:109]
	v_mov_b32_e32 v113, v66
	v_add_f32_e32 v104, v110, v104
	v_add_f32_e32 v105, v104, v105
	v_add_co_u32_e32 v110, vcc, s85, v82
	v_cvt_pk_bf16_f32 v104, v92, v102
	v_cvt_pk_bf16_f32 v105, v106, v105
	v_mov_b64_e32 v[106:107], v[72:73]
	s_nop 0
	v_addc_co_u32_e32 v111, vcc, 0, v83, vcc
	global_store_dwordx2 v[110:111], v[104:105], off
	s_waitcnt vmcnt(0)
	v_and_b32_e32 v104, 0xffff0000, v58
	v_lshlrev_b32_e32 v105, 16, v58
	v_and_b32_e32 v110, 0xffff0000, v59
	v_lshlrev_b32_e32 v111, 16, v59
	v_pk_add_f32 v[86:87], v[104:105], v[86:87] neg_lo:[0,1] neg_hi:[0,1]
	v_pk_add_f32 v[84:85], v[110:111], v[84:85] neg_lo:[0,1] neg_hi:[0,1]
	v_pk_add_f32 v[90:91], v[90:91], v[86:87]
	v_pk_add_f32 v[86:87], v[88:89], v[84:85]
	v_add_co_u32_e32 v82, vcc, s77, v82
	v_fma_f32 v85, v87, s76, -v111
	s_nop 0
	v_addc_co_u32_e32 v83, vcc, 0, v83, vcc
	v_fma_f32 v92, v91, s76, -v105
	v_fma_f32 v102, v90, s76, -v104
	v_fma_f32 v88, v86, s76, -v110
	v_cvt_pk_bf16_f32 v84, v92, v102
	v_cvt_pk_bf16_f32 v85, v85, v88
	global_store_dwordx2 v[82:83], v[84:85], off
	v_mov_b32_e32 v110, v109
	v_mov_b64_e32 v[84:85], v[80:81]
	v_mov_b64_e32 v[88:89], v[78:79]
	v_mov_b64_e32 v[92:93], v[76:77]
	v_mov_b64_e32 v[104:105], v[74:75]
	v_mov_b64_e32 v[108:109], v[70:71]
	v_mov_b32_e32 v111, v67
	s_cbranch_scc1 .LBB0_346
	s_mov_b64 s[0:1], 0
.LBB0_348:
	s_and_b64 vcc, exec, s[0:1]
	s_cbranch_vccz .LBB0_354
	s_andn2_b64 vcc, exec, s[44:45]
	s_mov_b32 s68, 0
	s_cbranch_vccnz .LBB0_351
	s_mov_b32 s0, 0xffff0000
	v_add_co_u32_e64 v30, s[0:1], s0, v24
	v_add_co_u32_e32 v26, vcc, 0xffff6000, v24
	s_nop 0
	v_addc_co_u32_e64 v31, s[0:1], -1, v25, s[0:1]
	s_mov_b32 s0, 0xfffe6000
	s_nop 0
	v_add_co_u32_e64 v32, s[0:1], s0, v24
	v_addc_co_u32_e32 v27, vcc, -1, v25, vcc
	s_nop 0
	v_addc_co_u32_e64 v33, s[0:1], -1, v25, s[0:1]
	s_mov_b32 s0, 0xfffdc000
	s_nop 0
	v_add_co_u32_e64 v34, s[0:1], s0, v24
	v_add_co_u32_e32 v28, vcc, 0xfffec000, v24
	s_nop 0
	v_addc_co_u32_e64 v35, s[0:1], -1, v25, s[0:1]
	s_mov_b32 s0, 0xfffd2000
	s_nop 0
	v_add_co_u32_e64 v36, s[0:1], s0, v24
	v_addc_co_u32_e32 v29, vcc, -1, v25, vcc
	s_nop 0
	v_addc_co_u32_e64 v37, s[0:1], -1, v25, s[0:1]
	s_mov_b32 s0, 0xfffc8000
	global_load_dwordx2 v[64:65], v[30:31], off nt
	global_load_dwordx2 v[50:51], v[32:33], off nt
	global_load_dwordx2 v[58:59], v[34:35], off nt
	global_load_dwordx2 v[56:57], v[36:37], off nt
	v_add_co_u32_e64 v30, s[0:1], s0, v24
	s_waitcnt vmcnt(0)
	v_and_b32_e32 v44, 0xffff0000, v65
	v_addc_co_u32_e64 v31, s[0:1], -1, v25, s[0:1]
	s_mov_b32 s0, 0xfffbe000
	global_load_dwordx2 v[54:55], v[30:31], off nt
	v_add_co_u32_e64 v30, s[0:1], s0, v24
	v_lshlrev_b32_e32 v45, 16, v65
	s_nop 0
	v_addc_co_u32_e64 v31, s[0:1], -1, v25, s[0:1]
	global_load_dwordx2 v[52:53], v[30:31], off nt
	v_add_co_u32_e32 v30, vcc, 0xfffe2000, v24
	s_movk_i32 s0, 0xa000
	s_nop 0
	v_addc_co_u32_e32 v31, vcc, -1, v25, vcc
	v_add_co_u32_e32 v32, vcc, s0, v24
	global_load_dwordx2 v[26:27], v[26:27], off nt
	s_nop 0
	global_load_dwordx2 v[28:29], v[28:29], off nt
	v_addc_co_u32_e32 v33, vcc, -1, v25, vcc
	global_load_dwordx2 v[30:31], v[30:31], off nt
	v_and_b32_e32 v34, 0xffff0000, v50
	global_load_dwordx2 v[62:63], v[32:33], off nt
	v_and_b32_e32 v32, 0xffff0000, v64
	v_lshlrev_b32_e32 v33, 16, v64
	v_lshlrev_b32_e32 v35, 16, v50
	v_and_b32_e32 v36, 0xffff0000, v58
	v_lshlrev_b32_e32 v37, 16, v58
	v_and_b32_e32 v38, 0xffff0000, v56
	v_lshlrev_b32_e32 v39, 16, v56
	s_waitcnt vmcnt(0)
	v_and_b32_e32 v40, 0xffff0000, v54
	v_lshlrev_b32_e32 v41, 16, v54
	v_and_b32_e32 v42, 0xffff0000, v52
	v_lshlrev_b32_e32 v43, 16, v52
	v_lshlrev_b32_e32 v110, 16, v26
	v_and_b32_e32 v108, 0xffff0000, v26
	v_lshlrev_b32_e32 v106, 16, v27
	v_and_b32_e32 v104, 0xffff0000, v27
	v_lshlrev_b32_e32 v79, 16, v28
	v_and_b32_e32 v77, 0xffff0000, v28
	v_lshlrev_b32_e32 v75, 16, v29
	v_and_b32_e32 v73, 0xffff0000, v29
	v_and_b32_e32 v26, 0xffff0000, v62
	v_lshlrev_b32_e32 v27, 16, v62
	v_and_b32_e32 v28, 0xffff0000, v63
	v_lshlrev_b32_e32 v29, 16, v63
	v_pk_add_f32 v[26:27], v[26:27], 0 op_sel_hi:[1,0]
	v_pk_add_f32 v[28:29], v[28:29], 0 op_sel_hi:[1,0]
	v_lshlrev_b32_e32 v78, 16, v30
	v_and_b32_e32 v76, 0xffff0000, v30
	v_lshlrev_b32_e32 v74, 16, v31
	v_and_b32_e32 v72, 0xffff0000, v31
	v_pk_add_f32 v[26:27], v[26:27], v[32:33]
	v_pk_add_f32 v[28:29], v[28:29], v[44:45]
	v_and_b32_e32 v30, 0xffff0000, v51
	v_lshlrev_b32_e32 v31, 16, v51
	v_pk_add_f32 v[26:27], v[26:27], v[34:35]
	v_pk_add_f32 v[28:29], v[28:29], v[30:31]
	v_and_b32_e32 v30, 0xffff0000, v59
	v_lshlrev_b32_e32 v31, 16, v59
	v_pk_add_f32 v[26:27], v[26:27], v[36:37]
	v_pk_add_f32 v[28:29], v[28:29], v[30:31]
	v_and_b32_e32 v30, 0xffff0000, v57
	v_lshlrev_b32_e32 v31, 16, v57
	v_pk_add_f32 v[26:27], v[26:27], v[38:39]
	v_pk_add_f32 v[28:29], v[28:29], v[30:31]
	v_and_b32_e32 v30, 0xffff0000, v55
	v_lshlrev_b32_e32 v31, 16, v55
	v_pk_add_f32 v[26:27], v[26:27], v[40:41]
	v_pk_add_f32 v[28:29], v[28:29], v[30:31]
	v_and_b32_e32 v30, 0xffff0000, v53
	v_lshlrev_b32_e32 v31, 16, v53
	v_pk_add_f32 v[68:69], v[26:27], v[42:43]
	v_pk_add_f32 v[70:71], v[28:29], v[30:31]
	s_branch .LBB0_352

; __device__ __forceinline__ unsigned cvt_pk_bf16(float lo, float hi) { unsigned r; asm volatile("v_cvt_pk_bf16_f32 %0, %1, %2" : "=v"(r) : "v"(lo), "v"(hi)); return r; }
; __device__ __forceinline__ void unpack4(const v2u q, float (&f)[4]) { f[0] = bf_lo(q.x); f[1] = bf_hi(q.x); f[2] = bf_lo(q.y); f[3] = bf_hi(q.y); }
; template <int W>
; __device__ __forceinline__ void conv_pool_chunk(const bf16* PROJ, bf16* XC, bf16* POOLED, const float* conv_w, const float* conv_b, int chunk, int ch0) {
;     ...
;             v2u xnb[8], pnb[8];
; #pragma unroll
;             for (int q = 0; q < 8; ++q) { xnb[q] = *(const v2u*)(p + (size_t)q * NIN); pnb[q] = *(const v2u*)(p + (size_t)q * NIN + 2 * D); }
; #pragma unroll
;             for (int q = 0; q < 8; ++q) { const int rr = h8 * 8 + q; const int r = rb * 16 + rr;
;                 const v2u xn = xnb[q], pn = pnb[q];
;                 float xf[4]; unpack4(xn, xf);
;                 float a[4];
; #pragma unroll
;                 for (int j = 0; j < 4; ++j) a[j] = cb[j] + cw[0][j] * cx[(rr + 1) & 3][j] + cw[1][j] * cx[(rr + 2) & 3][j] + cw[2][j] * cx[(rr + 3) & 3][j] + cw[3][j] * xf[j];
; #pragma unroll
;                 for (int j = 0; j < 4; ++j) cx[rr & 3][j] = xf[j];
;                 { v2u o; o.x = cvt_pk_bf16(a[0], a[1]); o.y = cvt_pk_bf16(a[2], a[3]); *(v2u*)(xo + (size_t)q * D) = o; }
;                 float pf[4], of[4]; unpack4(pn, pf); unpack4(ph[rr & (W - 1)], of);
;                 ph[rr & (W - 1)] = pn;
;                 const int t = t0 + r; const int cnt = (t + 1 < W) ? (t + 1) : W; const float inv = 1.0f / (float)cnt;
; #pragma unroll
;                 for (int j = 0; j < 4; ++j) { s[j] += pf[j] - of[j]; a[j] = s[j] * inv - pf[j]; }
.LBB0_353:
	v_lshl_add_u64 v[84:85], s[40:41], 0, v[22:23]
	v_add_co_u32_e32 v80, vcc, s81, v84
	global_load_dwordx2 v[120:121], v[84:85], off nt
	s_nop 0
	v_addc_co_u32_e32 v81, vcc, 0, v85, vcc
	global_load_dwordx2 v[124:125], v[80:81], off nt
	v_add_co_u32_e32 v80, vcc, s36, v84
	s_add_i32 s69, s16, s68
	s_nop 0
	v_addc_co_u32_e32 v81, vcc, 0, v85, vcc
	global_load_dwordx2 v[122:123], v[80:81], off nt
	v_add_co_u32_e32 v80, vcc, s37, v84
	v_lshl_add_u64 v[66:67], s[0:1], 0, v[22:23]
	s_nop 0
	v_addc_co_u32_e32 v81, vcc, 0, v85, vcc
	global_load_dwordx2 v[94:95], v[80:81], off nt
	v_add_co_u32_e32 v80, vcc, s42, v84
	v_and_b32_e32 v166, 0xffff0000, v59
	s_nop 0
	v_addc_co_u32_e32 v81, vcc, 0, v85, vcc
	global_load_dwordx2 v[116:117], v[80:81], off nt
	v_add_co_u32_e32 v80, vcc, s64, v84
	v_lshlrev_b32_e32 v167, 16, v59
	s_nop 0
	v_addc_co_u32_e32 v81, vcc, 0, v85, vcc
	global_load_dwordx2 v[96:97], v[80:81], off nt
	v_add_co_u32_e32 v80, vcc, s65, v84
	s_add_i32 s68, s68, 16
	s_nop 0
	v_addc_co_u32_e32 v81, vcc, 0, v85, vcc
	global_load_dwordx2 v[118:119], v[80:81], off nt
	v_add_co_u32_e32 v80, vcc, s66, v84
	s_waitcnt vmcnt(0)
	v_and_b32_e32 v134, 0xffff0000, v121
	v_addc_co_u32_e32 v81, vcc, 0, v85, vcc
	global_load_dwordx2 v[98:99], v[80:81], off nt
	v_add_co_u32_e32 v80, vcc, s67, v84
	v_lshlrev_b32_e32 v89, 16, v124
	s_nop 0
	v_addc_co_u32_e32 v81, vcc, 0, v85, vcc
	global_load_dwordx2 v[112:113], v[80:81], off nt
	v_add_co_u32_e32 v80, vcc, s71, v84
	v_and_b32_e32 v88, 0xffff0000, v124
	s_nop 0
	v_addc_co_u32_e32 v81, vcc, 0, v85, vcc
	global_load_dwordx2 v[100:101], v[80:81], off nt
	v_add_co_u32_e32 v80, vcc, s90, v84
	v_and_b32_e32 v135, 0xffff0000, v123
	s_nop 0
	v_addc_co_u32_e32 v81, vcc, 0, v85, vcc
	global_load_dwordx2 v[114:115], v[80:81], off nt
	v_add_co_u32_e32 v80, vcc, s91, v84
	s_nop 1
	v_addc_co_u32_e32 v81, vcc, 0, v85, vcc
	global_load_dwordx2 v[92:93], v[80:81], off nt
	v_add_co_u32_e32 v80, vcc, s92, v84
	s_nop 1
	v_addc_co_u32_e32 v81, vcc, 0, v85, vcc
	v_add_co_u32_e32 v82, vcc, s93, v84
	global_load_dwordx2 v[80:81], v[80:81], off nt
	s_nop 0
	v_addc_co_u32_e32 v83, vcc, 0, v85, vcc
	global_load_dwordx2 v[90:91], v[82:83], off nt
	v_add_co_u32_e32 v82, vcc, s94, v84
	s_nop 1
	v_addc_co_u32_e32 v83, vcc, 0, v85, vcc
	v_add_co_u32_e32 v86, vcc, s95, v84
	global_load_dwordx2 v[82:83], v[82:83], off nt
	s_nop 0
	v_addc_co_u32_e32 v87, vcc, 0, v85, vcc
	global_load_dwordx2 v[102:103], v[86:87], off nt
	v_pk_mul_f32 v[86:87], v[38:39], v[78:79]
	s_min_u32 vcc_lo, s69, 7
	v_add_f32_e32 v78, v14, v86
	v_add_f32_e32 v105, v87, v78
	v_pk_mul_f32 v[86:87], v[40:41], v[76:77]
	s_add_i32 vcc_lo, vcc_lo, 1
	v_add_f32_e32 v76, v15, v86
	v_add_f32_e32 v107, v87, v76
	v_pk_mul_f32 v[86:87], v[30:31], v[74:75]
	s_nop 0
	v_add_f32_e32 v74, v16, v86
	v_add_f32_e32 v130, v87, v74
	v_pk_mul_f32 v[86:87], v[32:33], v[72:73]
	s_nop 0
	v_add_f32_e32 v72, v17, v86
	v_add_f32_e32 v131, v87, v72
	v_cvt_f32_ubyte0_e32 v72, vcc_lo
	v_div_scale_f32 v74, vcc, v72, v72, 1.0
	v_rcp_f32_e32 v76, v74
	v_lshlrev_b32_e32 v87, 16, v125
	v_and_b32_e32 v86, 0xffff0000, v125
	v_fma_f32 v78, -v74, v76, 1.0
	v_fmac_f32_e32 v76, v78, v76
	v_div_scale_f32 v78, vcc, 1.0, v72, 1.0
	v_mul_f32_e32 v109, v78, v76
	v_fma_f32 v111, -v74, v109, v78
	v_fmac_f32_e32 v109, v111, v76
	v_fma_f32 v74, -v74, v109, v78
	v_mov_b32_e32 v111, v79
	v_div_fmas_f32 v74, v74, v76, v109
	v_pk_mul_f32 v[78:79], v[46:47], v[110:111]
	v_div_fixup_f32 v124, v74, v72, 1.0
	v_add_f32_e32 v72, v14, v79
	v_add_f32_e32 v72, v78, v72
	v_lshlrev_b32_e32 v78, 16, v120
	v_mov_b32_e32 v111, v78
	v_pk_mul_f32 v[126:127], v[34:35], v[110:111]
	v_lshlrev_b32_e32 v79, 16, v122
	v_add_f32_e32 v74, v126, v105
	v_add_f32_e32 v74, v74, v127
	v_pk_mul_f32 v[126:127], v[34:35], v[78:79]
	v_mov_b32_e32 v109, v77
	v_add_f32_e32 v72, v72, v126
	v_pk_mul_f32 v[76:77], v[48:49], v[108:109]
	v_add_f32_e32 v126, v72, v127
	v_add_f32_e32 v72, v15, v77
	v_add_f32_e32 v105, v76, v72
	v_and_b32_e32 v76, 0xffff0000, v120
	v_mov_b32_e32 v109, v76
	v_pk_mul_f32 v[128:129], v[36:37], v[108:109]
	v_and_b32_e32 v77, 0xffff0000, v122
	v_add_f32_e32 v72, v128, v107
	v_add_f32_e32 v72, v72, v129
	v_pk_mul_f32 v[128:129], v[36:37], v[76:77]
	v_cvt_pk_bf16_f32 v72, v74, v72
	v_mov_b32_e32 v107, v75
	v_add_f32_e32 v74, v105, v128
	v_add_f32_e32 v122, v74, v129
	v_pk_mul_f32 v[74:75], v[42:43], v[106:107]
	s_nop 0
	v_add_f32_e32 v75, v16, v75
	v_add_f32_e32 v105, v74, v75
	v_lshlrev_b32_e32 v74, 16, v121
	v_mov_b32_e32 v107, v74
	v_pk_mul_f32 v[128:129], v[26:27], v[106:107]
	v_lshlrev_b32_e32 v75, 16, v123
	v_add_f32_e32 v120, v128, v130
	v_add_f32_e32 v125, v120, v129
	v_pk_mul_f32 v[128:129], v[26:27], v[74:75]
	s_nop 0
	v_add_f32_e32 v105, v105, v128
	v_add_f32_e32 v127, v105, v129
	v_mov_b32_e32 v105, v73
	v_pk_mul_f32 v[128:129], v[44:45], v[104:105]
	v_mov_b32_e32 v105, v134
	v_add_f32_e32 v73, v17, v129
	v_pk_mul_f32 v[120:121], v[28:29], v[104:105]
	v_add_f32_e32 v128, v128, v73
	v_add_f32_e32 v73, v120, v131
	v_add_co_u32_e32 v120, vcc, s96, v66
	v_add_f32_e32 v73, v73, v121
	s_nop 0
	v_addc_co_u32_e32 v121, vcc, 0, v67, vcc
	v_cvt_pk_bf16_f32 v73, v125, v73
	s_add_i32 vcc_lo, s69, 1
	global_store_dwordx2 v[120:121], v[72:73], off
	v_pk_mul_f32 v[72:73], v[28:29], v[134:135]
	s_min_u32 vcc_lo, vcc_lo, 7
	v_add_f32_e32 v72, v128, v72
	s_add_i32 vcc_lo, vcc_lo, 1
	v_add_f32_e32 v123, v72, v73
	v_cvt_f32_ubyte0_e32 v72, vcc_lo
	v_div_scale_f32 v73, vcc, v72, v72, 1.0
	v_rcp_f32_e32 v120, v73
	s_nop 0
	v_fma_f32 v121, -v73, v120, 1.0
	v_fmac_f32_e32 v120, v121, v120
	v_div_scale_f32 v121, vcc, 1.0, v72, 1.0
; __device__ __forceinline__ unsigned cvt_pk_bf16(float lo, float hi) { unsigned r; asm volatile("v_cvt_pk_bf16_f32 %0, %1, %2" : "=v"(r) : "v"(lo), "v"(hi)); return r; }
; __device__ __forceinline__ void unpack4(const v2u q, float (&f)[4]) { f[0] = bf_lo(q.x); f[1] = bf_hi(q.x); f[2] = bf_lo(q.y); f[3] = bf_hi(q.y); }
; template <int W>
; __device__ __forceinline__ void conv_pool_chunk(const bf16* PROJ, bf16* XC, bf16* POOLED, const float* conv_w, const float* conv_b, int chunk, int ch0) {
;     ...
;                 for (int j = 0; j < 4; ++j) a[j] = cb[j] + cw[0][j] * cx[(rr + 1) & 3][j] + cw[1][j] * cx[(rr + 2) & 3][j] + cw[2][j] * cx[(rr + 3) & 3][j] + cw[3][j] * xf[j];
; #pragma unroll
;                 for (int j = 0; j < 4; ++j) cx[rr & 3][j] = xf[j];
;                 { v2u o; o.x = cvt_pk_bf16(a[0], a[1]); o.y = cvt_pk_bf16(a[2], a[3]); *(v2u*)(xo + (size_t)q * D) = o; }
;                 float pf[4], of[4]; unpack4(pn, pf); unpack4(ph[rr & (W - 1)], of);
;                 ph[rr & (W - 1)] = pn;
;                 const int t = t0 + r; const int cnt = (t + 1 < W) ? (t + 1) : W; const float inv = 1.0f / (float)cnt;
	v_mul_f32_e32 v125, v121, v120
	v_fma_f32 v128, -v73, v125, v121
	v_fmac_f32_e32 v125, v128, v120
	v_fma_f32 v73, -v73, v125, v121
	v_div_fmas_f32 v73, v73, v120, v125
	v_div_fixup_f32 v125, v73, v72, 1.0
	v_pk_mul_f32 v[72:73], v[38:39], v[110:111]
	s_add_i32 vcc_lo, s69, 2
	v_add_f32_e32 v72, v14, v72
	v_add_f32_e32 v110, v72, v73
	v_pk_mul_f32 v[72:73], v[40:41], v[108:109]
	s_min_u32 vcc_lo, vcc_lo, 7
	v_add_f32_e32 v72, v15, v72
	v_add_f32_e32 v108, v72, v73
	v_pk_mul_f32 v[72:73], v[30:31], v[106:107]
	s_add_i32 vcc_lo, vcc_lo, 1
	v_add_f32_e32 v72, v16, v72
	v_add_f32_e32 v111, v72, v73
	v_pk_mul_f32 v[72:73], v[32:33], v[104:105]
	s_nop 0
	v_add_f32_e32 v72, v17, v72
	v_add_f32_e32 v120, v72, v73
	v_cvt_f32_ubyte0_e32 v72, vcc_lo
	v_div_scale_f32 v73, vcc, v72, v72, 1.0
	v_rcp_f32_e32 v104, v73
	s_nop 0
	v_fma_f32 v105, -v73, v104, 1.0
	v_fmac_f32_e32 v104, v105, v104
	v_div_scale_f32 v105, vcc, 1.0, v72, 1.0
	v_mul_f32_e32 v106, v105, v104
	v_fma_f32 v107, -v73, v106, v105
	v_fmac_f32_e32 v106, v107, v104
	v_fma_f32 v73, -v73, v106, v105
	v_div_fmas_f32 v73, v73, v104, v106
	v_div_fixup_f32 v145, v73, v72, 1.0
	v_pk_mul_f32 v[72:73], v[38:39], v[78:79]
	s_add_i32 vcc_lo, s69, 3
	v_add_f32_e32 v72, v14, v72
	v_add_f32_e32 v106, v72, v73
	v_lshlrev_b32_e32 v73, 16, v118
	v_lshlrev_b32_e32 v72, 16, v116
	v_pk_mov_b32 v[78:79], v[78:79], v[72:73] op_sel:[1,0]
	s_min_u32 vcc_lo, vcc_lo, 7
	v_pk_mul_f32 v[104:105], v[34:35], v[78:79]
	s_add_i32 vcc_lo, vcc_lo, 1
	v_add_f32_e32 v104, v110, v104
	v_add_f32_e32 v129, v104, v105
	v_pk_mul_f32 v[104:105], v[34:35], v[72:73]
	v_pk_mul_f32 v[78:79], v[38:39], v[78:79]
	v_add_f32_e32 v104, v106, v104
	v_add_f32_e32 v128, v104, v105
	v_pk_mul_f32 v[104:105], v[40:41], v[76:77]
	v_add_f32_e32 v78, v14, v78
	v_add_f32_e32 v104, v15, v104
	v_add_f32_e32 v109, v104, v105
	v_and_b32_e32 v105, 0xffff0000, v118
	v_and_b32_e32 v104, 0xffff0000, v116
	v_pk_mov_b32 v[76:77], v[76:77], v[104:105] op_sel:[1,0]
	s_nop 0
	v_pk_mul_f32 v[106:107], v[36:37], v[76:77]
	v_pk_mul_f32 v[76:77], v[40:41], v[76:77]
	v_add_f32_e32 v106, v108, v106
	v_add_f32_e32 v131, v106, v107
	v_pk_mul_f32 v[106:107], v[36:37], v[104:105]
	v_add_f32_e32 v76, v15, v76
	v_add_f32_e32 v106, v109, v106
	v_add_f32_e32 v130, v106, v107
	v_pk_mul_f32 v[106:107], v[30:31], v[74:75]
	v_add_f32_e32 v76, v76, v77
	v_add_f32_e32 v106, v16, v106
	v_add_f32_e32 v110, v106, v107
	v_lshlrev_b32_e32 v107, 16, v119
	v_lshlrev_b32_e32 v106, 16, v117
	v_pk_mov_b32 v[74:75], v[74:75], v[106:107] op_sel:[1,0]
	s_nop 0
	v_pk_mul_f32 v[108:109], v[26:27], v[74:75]
	v_pk_mul_f32 v[74:75], v[30:31], v[74:75]
	v_add_f32_e32 v108, v111, v108
	v_add_f32_e32 v133, v108, v109
	v_pk_mul_f32 v[108:109], v[26:27], v[106:107]
	v_add_f32_e32 v74, v16, v74
	v_add_f32_e32 v108, v110, v108
	v_add_f32_e32 v132, v108, v109
	v_pk_mul_f32 v[108:109], v[32:33], v[134:135]
	s_nop 0
	v_add_f32_e32 v108, v17, v108
	v_add_f32_e32 v118, v108, v109
	v_and_b32_e32 v109, 0xffff0000, v119
	v_and_b32_e32 v108, 0xffff0000, v117
	v_pk_mov_b32 v[110:111], v[134:135], v[108:109] op_sel:[1,0]
	s_nop 0
	v_pk_mul_f32 v[116:117], v[28:29], v[110:111]
	s_nop 0
	v_add_f32_e32 v116, v120, v116
	v_add_f32_e32 v135, v116, v117
	v_pk_mul_f32 v[116:117], v[28:29], v[108:109]
	s_nop 0
	v_add_f32_e32 v116, v118, v116
	v_add_f32_e32 v134, v116, v117
	v_cvt_f32_ubyte0_e32 v116, vcc_lo
	v_div_scale_f32 v117, vcc, v116, v116, 1.0
	v_rcp_f32_e32 v118, v117
	s_nop 0
	v_fma_f32 v119, -v117, v118, 1.0
	v_fmac_f32_e32 v118, v119, v118
	v_div_scale_f32 v119, vcc, 1.0, v116, 1.0
	v_mul_f32_e32 v120, v119, v118
	v_fma_f32 v121, -v117, v120, v119
	v_fmac_f32_e32 v120, v121, v118
	v_fma_f32 v117, -v117, v120, v119
	v_div_fmas_f32 v117, v117, v118, v120
	s_add_i32 vcc_lo, s69, 4
	v_div_fixup_f32 v147, v117, v116, 1.0
	v_add_f32_e32 v117, v74, v75
	v_pk_mul_f32 v[74:75], v[32:33], v[110:111]
	s_min_u32 vcc_lo, vcc_lo, 7
	v_add_f32_e32 v74, v17, v74
	s_add_i32 vcc_lo, vcc_lo, 1
	v_add_f32_e32 v118, v74, v75
	v_cvt_f32_ubyte0_e32 v74, vcc_lo
	v_div_scale_f32 v75, vcc, v74, v74, 1.0
	v_rcp_f32_e32 v77, v75
	v_add_f32_e32 v116, v78, v79
	v_lshlrev_b32_e32 v121, 16, v64
	v_and_b32_e32 v120, 0xffff0000, v64
	v_fma_f32 v78, -v75, v77, 1.0
	v_fmac_f32_e32 v77, v78, v77
	v_div_scale_f32 v78, vcc, 1.0, v74, 1.0
	v_mul_f32_e32 v79, v78, v77
	v_fma_f32 v110, -v75, v79, v78
	v_fmac_f32_e32 v79, v110, v77
	v_fma_f32 v75, -v75, v79, v78
	v_div_fmas_f32 v75, v75, v77, v79
	s_waitcnt vmcnt(0)
; __device__ __forceinline__ unsigned cvt_pk_bf16(float lo, float hi) { unsigned r; asm volatile("v_cvt_pk_bf16_f32 %0, %1, %2" : "=v"(r) : "v"(lo), "v"(hi)); return r; }
; __device__ __forceinline__ void unpack4(const v2u q, float (&f)[4]) { f[0] = bf_lo(q.x); f[1] = bf_hi(q.x); f[2] = bf_lo(q.y); f[3] = bf_hi(q.y); }
; template <int W>
; __device__ __forceinline__ void conv_pool_chunk(const bf16* PROJ, bf16* XC, bf16* POOLED, const float* conv_w, const float* conv_b, int chunk, int ch0) {
;     ...
;                 for (int j = 0; j < 4; ++j) a[j] = cb[j] + cw[0][j] * cx[(rr + 1) & 3][j] + cw[1][j] * cx[(rr + 2) & 3][j] + cw[2][j] * cx[(rr + 3) & 3][j] + cw[3][j] * xf[j];
; #pragma unroll
;                 for (int j = 0; j < 4; ++j) cx[rr & 3][j] = xf[j];
;                 { v2u o; o.x = cvt_pk_bf16(a[0], a[1]); o.y = cvt_pk_bf16(a[2], a[3]); *(v2u*)(xo + (size_t)q * D) = o; }
;                 float pf[4], of[4]; unpack4(pn, pf); unpack4(ph[rr & (W - 1)], of);
;                 ph[rr & (W - 1)] = pn;
;                 const int t = t0 + r; const int cnt = (t + 1 < W) ? (t + 1) : W; const float inv = 1.0f / (float)cnt;
	v_lshlrev_b32_e32 v79, 16, v114
	v_lshlrev_b32_e32 v78, 16, v112
	v_pk_mov_b32 v[110:111], v[72:73], v[78:79] op_sel:[1,0]
	v_div_fixup_f32 v148, v75, v74, 1.0
	v_pk_mul_f32 v[74:75], v[38:39], v[72:73]
	v_pk_mul_f32 v[72:73], v[34:35], v[110:111]
	v_add_f32_e32 v74, v14, v74
	v_add_f32_e32 v72, v116, v72
	v_add_f32_e32 v74, v74, v75
	v_add_f32_e32 v137, v72, v73
	v_pk_mul_f32 v[72:73], v[34:35], v[78:79]
	s_add_i32 vcc_lo, s69, 5
	v_add_f32_e32 v72, v74, v72
	v_add_f32_e32 v136, v72, v73
	v_pk_mul_f32 v[72:73], v[40:41], v[104:105]
	s_min_u32 vcc_lo, vcc_lo, 7
	v_add_f32_e32 v72, v15, v72
	v_add_f32_e32 v77, v72, v73
	v_and_b32_e32 v73, 0xffff0000, v114
	v_and_b32_e32 v72, 0xffff0000, v112
	v_pk_mov_b32 v[104:105], v[104:105], v[72:73] op_sel:[1,0]
	s_add_i32 vcc_lo, vcc_lo, 1
	v_pk_mul_f32 v[74:75], v[36:37], v[104:105]
	v_pk_mul_f32 v[104:105], v[40:41], v[104:105]
	v_add_f32_e32 v74, v76, v74
	v_add_f32_e32 v139, v74, v75
	v_pk_mul_f32 v[74:75], v[36:37], v[72:73]
	v_lshlrev_b32_e32 v76, 16, v113
	v_add_f32_e32 v74, v77, v74
	v_add_f32_e32 v138, v74, v75
	v_pk_mul_f32 v[74:75], v[30:31], v[106:107]
	v_lshlrev_b32_e32 v77, 16, v115
	v_add_f32_e32 v74, v16, v74
	v_pk_mov_b32 v[106:107], v[106:107], v[76:77] op_sel:[1,0]
	v_add_f32_e32 v112, v74, v75
	v_pk_mul_f32 v[74:75], v[26:27], v[106:107]
	v_add_f32_e32 v104, v15, v104
	v_add_f32_e32 v74, v117, v74
	v_add_f32_e32 v141, v74, v75
	v_pk_mul_f32 v[74:75], v[26:27], v[76:77]
	s_add_i32 s69, s69, 6
	v_add_f32_e32 v74, v112, v74
	v_add_f32_e32 v140, v74, v75
	v_pk_mul_f32 v[74:75], v[32:33], v[108:109]
	s_min_u32 s69, s69, 7
	v_add_f32_e32 v74, v17, v74
	v_add_f32_e32 v114, v74, v75
	v_and_b32_e32 v75, 0xffff0000, v115
	v_and_b32_e32 v74, 0xffff0000, v113
	v_pk_mov_b32 v[108:109], v[108:109], v[74:75] op_sel:[1,0]
	s_add_i32 s69, s69, 1
	v_pk_mul_f32 v[112:113], v[28:29], v[108:109]
	v_cvt_f32_ubyte0_e32 v64, s69
	v_add_f32_e32 v112, v118, v112
	v_add_f32_e32 v143, v112, v113
	v_pk_mul_f32 v[112:113], v[28:29], v[74:75]
	v_pk_mul_f32 v[110:111], v[38:39], v[110:111]
	v_add_f32_e32 v112, v114, v112
	v_add_f32_e32 v142, v112, v113
	v_cvt_f32_ubyte0_e32 v112, vcc_lo
	v_div_scale_f32 v113, vcc, v112, v112, 1.0
	v_rcp_f32_e32 v114, v113
	v_add_f32_e32 v110, v14, v110
	v_add_f32_e32 v110, v110, v111
	v_and_b32_e32 v118, 0xffff0000, v57
	v_fma_f32 v115, -v113, v114, 1.0
	v_fmac_f32_e32 v114, v115, v114
	v_div_scale_f32 v115, vcc, 1.0, v112, 1.0
	v_mul_f32_e32 v116, v115, v114
	v_fma_f32 v117, -v113, v116, v115
	v_fmac_f32_e32 v116, v117, v114
	v_fma_f32 v113, -v113, v116, v115
	v_div_fmas_f32 v113, v113, v114, v116
	v_div_fixup_f32 v146, v113, v112, 1.0
	v_add_f32_e32 v112, v104, v105
	v_pk_mul_f32 v[104:105], v[30:31], v[106:107]
	v_pk_mul_f32 v[106:107], v[32:33], v[108:109]
	v_add_f32_e32 v104, v16, v104
	v_add_f32_e32 v105, v104, v105
	v_add_f32_e32 v104, v17, v106
	v_add_f32_e32 v104, v104, v107
	v_lshlrev_b32_e32 v107, 16, v65
	v_and_b32_e32 v106, 0xffff0000, v65
	v_div_scale_f32 v65, vcc, v64, v64, 1.0
	v_rcp_f32_e32 v108, v65
	v_and_b32_e32 v115, 0xffff0000, v83
	v_and_b32_e32 v114, 0xffff0000, v81
	v_lshlrev_b32_e32 v117, 16, v63
	v_fma_f32 v109, -v65, v108, 1.0
	v_fmac_f32_e32 v108, v109, v108
	v_div_scale_f32 v109, vcc, 1.0, v64, 1.0
	v_mul_f32_e32 v111, v109, v108
	v_fma_f32 v113, -v65, v111, v109
	v_fmac_f32_e32 v111, v113, v108
	v_fma_f32 v65, -v65, v111, v109
	v_div_fmas_f32 v65, v65, v108, v111
	v_div_fixup_f32 v165, v65, v64, 1.0
	v_pk_mul_f32 v[64:65], v[38:39], v[78:79]
	v_lshlrev_b32_e32 v109, 16, v82
	v_lshlrev_b32_e32 v108, 16, v80
	v_add_f32_e32 v64, v14, v64
	v_pk_mov_b32 v[78:79], v[78:79], v[108:109] op_sel:[1,0]
	v_add_f32_e32 v111, v64, v65
	v_pk_mul_f32 v[64:65], v[34:35], v[78:79]
	v_and_b32_e32 v116, 0xffff0000, v63
	v_add_f32_e32 v64, v110, v64
	v_add_f32_e32 v158, v64, v65
	v_pk_mul_f32 v[64:65], v[34:35], v[108:109]
	v_and_b32_e32 v110, 0xffff0000, v80
	v_add_f32_e32 v64, v111, v64
	v_add_f32_e32 v157, v64, v65
	v_pk_mul_f32 v[64:65], v[40:41], v[72:73]
	v_and_b32_e32 v111, 0xffff0000, v82
	v_add_f32_e32 v64, v15, v64
	v_pk_mov_b32 v[72:73], v[72:73], v[110:111] op_sel:[1,0]
	v_add_f32_e32 v113, v64, v65
	v_pk_mul_f32 v[64:65], v[36:37], v[72:73]
	v_and_b32_e32 v82, 0xffff0000, v102
	v_add_f32_e32 v64, v112, v64
	v_add_f32_e32 v160, v64, v65
	v_pk_mul_f32 v[64:65], v[36:37], v[110:111]
	v_lshlrev_b32_e32 v112, 16, v81
	v_add_f32_e32 v64, v113, v64
	v_add_f32_e32 v159, v64, v65
	v_pk_mul_f32 v[64:65], v[30:31], v[76:77]
	v_lshlrev_b32_e32 v113, 16, v83
	v_add_f32_e32 v64, v16, v64
	v_pk_mov_b32 v[76:77], v[76:77], v[112:113] op_sel:[1,0]
	v_add_f32_e32 v80, v64, v65
	v_pk_mul_f32 v[64:65], v[26:27], v[76:77]
	v_lshlrev_b32_e32 v83, 16, v102
	v_add_f32_e32 v64, v105, v64
	v_add_f32_e32 v162, v64, v65
	v_pk_mul_f32 v[64:65], v[26:27], v[112:113]
	v_lshlrev_b32_e32 v105, 16, v95
	v_add_f32_e32 v64, v80, v64
	v_add_f32_e32 v161, v64, v65
	v_pk_mul_f32 v[64:65], v[32:33], v[74:75]
	v_pk_mov_b32 v[74:75], v[74:75], v[114:115] op_sel:[1,0]
	v_add_f32_e32 v64, v17, v64
	v_add_f32_e32 v80, v64, v65
	v_pk_mul_f32 v[64:65], v[28:29], v[74:75]
	v_lshlrev_b32_e32 v81, 16, v103
	v_add_f32_e32 v64, v104, v64
	v_add_f32_e32 v164, v64, v65
	v_pk_mul_f32 v[64:65], v[28:29], v[114:115]
	v_and_b32_e32 v104, 0xffff0000, v95
	v_add_f32_e32 v64, v80, v64
	v_add_f32_e32 v163, v64, v65
	v_lshlrev_b32_e32 v65, 16, v62
	v_and_b32_e32 v64, 0xffff0000, v62
	v_pk_mul_f32 v[62:63], v[38:39], v[78:79]
	v_and_b32_e32 v80, 0xffff0000, v103
	v_add_f32_e32 v62, v14, v62
	v_add_f32_e32 v153, v62, v63
	v_pk_mul_f32 v[62:63], v[40:41], v[72:73]
	v_and_b32_e32 v102, 0xffff0000, v97
	v_add_f32_e32 v62, v15, v62
; __device__ __forceinline__ unsigned cvt_pk_bf16(float lo, float hi) { unsigned r; asm volatile("v_cvt_pk_bf16_f32 %0, %1, %2" : "=v"(r) : "v"(lo), "v"(hi)); return r; }
; __device__ __forceinline__ void unpack4(const v2u q, float (&f)[4]) { f[0] = bf_lo(q.x); f[1] = bf_hi(q.x); f[2] = bf_lo(q.y); f[3] = bf_hi(q.y); }
; template <int W>
; __device__ __forceinline__ void conv_pool_chunk(const bf16* PROJ, bf16* XC, bf16* POOLED, const float* conv_w, const float* conv_b, int chunk, int ch0) {
;     ...
;                 for (int j = 0; j < 4; ++j) a[j] = cb[j] + cw[0][j] * cx[(rr + 1) & 3][j] + cw[1][j] * cx[(rr + 2) & 3][j] + cw[2][j] * cx[(rr + 3) & 3][j] + cw[3][j] * xf[j];
; #pragma unroll
;                 for (int j = 0; j < 4; ++j) cx[rr & 3][j] = xf[j];
;                 { v2u o; o.x = cvt_pk_bf16(a[0], a[1]); o.y = cvt_pk_bf16(a[2], a[3]); *(v2u*)(xo + (size_t)q * D) = o; }
;                 float pf[4], of[4]; unpack4(pn, pf); unpack4(ph[rr & (W - 1)], of);
;                 ph[rr & (W - 1)] = pn;
;                 const int t = t0 + r; const int cnt = (t + 1 < W) ? (t + 1) : W; const float inv = 1.0f / (float)cnt;
; #pragma unroll
;                 for (int j = 0; j < 4; ++j) { s[j] += pf[j] - of[j]; a[j] = s[j] * inv - pf[j]; }
;                 { v2u o; o.x = cvt_pk_bf16(a[0], a[1]); o.y = cvt_pk_bf16(a[2], a[3]); *(v2u*)(po + (size_t)q * D) = o; }
	v_add_f32_e32 v151, v62, v63
	v_pk_mul_f32 v[62:63], v[30:31], v[76:77]
	v_lshlrev_b32_e32 v103, 16, v97
	v_add_f32_e32 v62, v16, v62
	v_add_f32_e32 v150, v62, v63
	v_pk_mul_f32 v[62:63], v[32:33], v[74:75]
	v_and_b32_e32 v74, 0xffff0000, v53
	v_add_f32_e32 v62, v17, v62
	v_add_f32_e32 v149, v62, v63
	v_pk_mul_f32 v[62:63], v[38:39], v[108:109]
	v_lshlrev_b32_e32 v75, 16, v53
	v_add_f32_e32 v62, v14, v62
	v_add_f32_e32 v156, v62, v63
	v_pk_mul_f32 v[62:63], v[40:41], v[110:111]
	v_and_b32_e32 v78, 0xffff0000, v55
	v_add_f32_e32 v62, v15, v62
	v_add_f32_e32 v155, v62, v63
	v_pk_mul_f32 v[62:63], v[30:31], v[112:113]
	v_lshlrev_b32_e32 v79, 16, v55
	v_add_f32_e32 v62, v16, v62
	v_add_f32_e32 v152, v62, v63
	v_pk_mul_f32 v[62:63], v[32:33], v[114:115]
	v_and_b32_e32 v76, 0xffff0000, v99
	v_add_f32_e32 v62, v17, v62
	v_add_f32_e32 v144, v62, v63
	v_and_b32_e32 v62, 0xffff0000, v61
	v_lshlrev_b32_e32 v63, 16, v61
	v_pk_add_f32 v[62:63], v[86:87], v[62:63] neg_lo:[0,1] neg_hi:[0,1]
	v_lshlrev_b32_e32 v77, 16, v99
	v_pk_add_f32 v[62:63], v[70:71], v[62:63]
	v_pk_add_f32 v[70:71], v[104:105], v[74:75] neg_lo:[0,1] neg_hi:[0,1]
	v_and_b32_e32 v72, 0xffff0000, v101
	v_lshlrev_b32_e32 v73, 16, v101
	v_lshlrev_b32_e32 v119, 16, v57
	v_fma_f32 v99, v124, v63, -v87
	v_fma_f32 v101, v124, v62, -v86
	v_pk_add_f32 v[62:63], v[62:63], v[70:71]
	v_pk_add_f32 v[70:71], v[102:103], v[78:79] neg_lo:[0,1] neg_hi:[0,1]
	v_fma_f32 v168, v125, v63, -v105
	v_fma_f32 v169, v125, v62, -v104
	v_pk_add_f32 v[62:63], v[62:63], v[70:71]
	v_pk_add_f32 v[70:71], v[76:77], v[118:119] neg_lo:[0,1] neg_hi:[0,1]
	v_fma_f32 v170, v145, v63, -v103
	v_fma_f32 v171, v145, v62, -v102
	v_pk_add_f32 v[62:63], v[62:63], v[70:71]
	v_pk_add_f32 v[70:71], v[72:73], v[166:167] neg_lo:[0,1] neg_hi:[0,1]
	v_fma_f32 v172, v147, v63, -v77
	v_fma_f32 v173, v147, v62, -v76
	v_pk_add_f32 v[62:63], v[62:63], v[70:71]
	v_and_b32_e32 v74, 0xffff0000, v93
	v_lshlrev_b32_e32 v75, 16, v93
	v_and_b32_e32 v70, 0xffff0000, v51
	v_lshlrev_b32_e32 v71, 16, v51
	v_pk_add_f32 v[70:71], v[74:75], v[70:71] neg_lo:[0,1] neg_hi:[0,1]
	v_fma_f32 v166, v148, v63, -v73
	v_fma_f32 v167, v148, v62, -v72
	v_pk_add_f32 v[62:63], v[62:63], v[70:71]
	v_and_b32_e32 v70, 0xffff0000, v91
	v_lshlrev_b32_e32 v71, 16, v91
	v_pk_add_f32 v[78:79], v[70:71], v[106:107] neg_lo:[0,1] neg_hi:[0,1]
	v_fma_f32 v93, v146, v63, -v75
	v_fma_f32 v174, v146, v62, -v74
	v_pk_add_f32 v[62:63], v[62:63], v[78:79]
	v_pk_add_f32 v[78:79], v[80:81], v[116:117] neg_lo:[0,1] neg_hi:[0,1]
	v_fma_f32 v91, v165, v63, -v71
	v_fma_f32 v175, v165, v62, -v70
	v_pk_add_f32 v[118:119], v[62:63], v[78:79]
	v_and_b32_e32 v62, 0xffff0000, v60
	v_lshlrev_b32_e32 v63, 16, v60
	v_and_b32_e32 v116, 0xffff0000, v94
	v_lshlrev_b32_e32 v117, 16, v94
	v_and_b32_e32 v60, 0xffff0000, v52
	v_lshlrev_b32_e32 v61, 16, v52
	v_and_b32_e32 v52, 0xffff0000, v54
	v_lshlrev_b32_e32 v53, 16, v54
	v_and_b32_e32 v54, 0xffff0000, v56
	v_lshlrev_b32_e32 v55, 16, v56
	v_and_b32_e32 v56, 0xffff0000, v58
	v_lshlrev_b32_e32 v57, 16, v58
	v_pk_add_f32 v[58:59], v[88:89], v[62:63] neg_lo:[0,1] neg_hi:[0,1]
	v_and_b32_e32 v106, 0xffff0000, v96
	v_lshlrev_b32_e32 v107, 16, v96
	v_pk_add_f32 v[58:59], v[68:69], v[58:59]
	v_pk_add_f32 v[60:61], v[116:117], v[60:61] neg_lo:[0,1] neg_hi:[0,1]
	v_and_b32_e32 v96, 0xffff0000, v98
	v_lshlrev_b32_e32 v97, 16, v98
	v_fma_f32 v51, v124, v59, -v89
	v_fma_f32 v62, v124, v58, -v88
	v_pk_add_f32 v[58:59], v[58:59], v[60:61]
	v_pk_add_f32 v[52:53], v[106:107], v[52:53] neg_lo:[0,1] neg_hi:[0,1]
	v_and_b32_e32 v78, 0xffff0000, v100
	v_lshlrev_b32_e32 v79, 16, v100
	v_pk_add_f32 v[52:53], v[58:59], v[52:53]
	v_pk_add_f32 v[54:55], v[96:97], v[54:55] neg_lo:[0,1] neg_hi:[0,1]
	v_fma_f32 v60, v125, v59, -v117
	v_fma_f32 v61, v125, v58, -v116
	v_fma_f32 v58, v145, v53, -v107
	v_fma_f32 v59, v145, v52, -v106
	v_pk_add_f32 v[52:53], v[52:53], v[54:55]
	v_pk_add_f32 v[54:55], v[78:79], v[56:57] neg_lo:[0,1] neg_hi:[0,1]
	v_fma_f32 v98, v147, v53, -v97
	v_fma_f32 v100, v147, v52, -v96
	v_pk_add_f32 v[52:53], v[52:53], v[54:55]
	v_and_b32_e32 v94, 0xffff0000, v92
	v_lshlrev_b32_e32 v95, 16, v92
	v_and_b32_e32 v54, 0xffff0000, v50
	v_lshlrev_b32_e32 v55, 16, v50
	v_cvt_pk_bf16_f32 v62, v51, v62
	v_pk_add_f32 v[50:51], v[94:95], v[54:55] neg_lo:[0,1] neg_hi:[0,1]
	v_and_b32_e32 v68, 0xffff0000, v90
	v_lshlrev_b32_e32 v69, 16, v90
	v_fma_f32 v56, v148, v53, -v79
	v_fma_f32 v57, v148, v52, -v78
	v_pk_add_f32 v[50:51], v[52:53], v[50:51]
	v_pk_add_f32 v[52:53], v[68:69], v[120:121] neg_lo:[0,1] neg_hi:[0,1]
	v_fma_f32 v54, v146, v51, -v95
	v_fma_f32 v55, v146, v50, -v94
	v_pk_add_f32 v[50:51], v[50:51], v[52:53]
	v_pk_add_f32 v[52:53], v[82:83], v[64:65] neg_lo:[0,1] neg_hi:[0,1]
	v_fma_f32 v92, v165, v50, -v68
	v_pk_add_f32 v[124:125], v[50:51], v[52:53]
	v_add_co_u32_e32 v50, vcc, s97, v66
	v_fma_f32 v90, v165, v51, -v69
	s_nop 0
	v_addc_co_u32_e32 v51, vcc, 0, v67, vcc
	v_add_co_u32_e32 v52, vcc, s14, v66
	v_cvt_pk_bf16_f32 v63, v99, v101
	global_store_dwordx2 v[50:51], v[62:63], off
	s_nop 0
	v_addc_co_u32_e32 v53, vcc, 0, v67, vcc
	v_cvt_pk_bf16_f32 v50, v126, v122
	v_cvt_pk_bf16_f32 v51, v127, v123
	global_store_dwordx2 v[52:53], v[50:51], off
	v_add_co_u32_e32 v52, vcc, s54, v66
	v_cvt_pk_bf16_f32 v50, v60, v61
	v_cvt_pk_bf16_f32 v51, v168, v169
	v_fma_f32 v64, v125, s8, -v83
	s_nop 0
	v_addc_co_u32_e32 v53, vcc, 0, v67, vcc
	global_store_dwordx2 v[52:53], v[50:51], off
	v_add_co_u32_e32 v52, vcc, s55, v66
	v_cvt_pk_bf16_f32 v50, v129, v131
	v_cvt_pk_bf16_f32 v51, v133, v135
	v_fma_f32 v65, v124, s8, -v82
	s_nop 0
	v_addc_co_u32_e32 v53, vcc, 0, v67, vcc
; __device__ __forceinline__ unsigned cvt_pk_bf16(float lo, float hi) { unsigned r; asm volatile("v_cvt_pk_bf16_f32 %0, %1, %2" : "=v"(r) : "v"(lo), "v"(hi)); return r; }
; __device__ __forceinline__ void unpack4(const v2u q, float (&f)[4]) { f[0] = bf_lo(q.x); f[1] = bf_hi(q.x); f[2] = bf_lo(q.y); f[3] = bf_hi(q.y); }
; template <int W>
; __device__ __forceinline__ void conv_pool_chunk(const bf16* PROJ, bf16* XC, bf16* POOLED, const float* conv_w, const float* conv_b, int chunk, int ch0) {
;     ...
;             v2u xnb[8], pnb[8];
; #pragma unroll
;             for (int q = 0; q < 8; ++q) { xnb[q] = *(const v2u*)(p + (size_t)q * NIN); pnb[q] = *(const v2u*)(p + (size_t)q * NIN + 2 * D); }
;     ...
;                 { v2u o; o.x = cvt_pk_bf16(a[0], a[1]); o.y = cvt_pk_bf16(a[2], a[3]); *(v2u*)(xo + (size_t)q * D) = o; }
;                 float pf[4], of[4]; unpack4(pn, pf); unpack4(ph[rr & (W - 1)], of);
;                 ph[rr & (W - 1)] = pn;
;                 const int t = t0 + r; const int cnt = (t + 1 < W) ? (t + 1) : W; const float inv = 1.0f / (float)cnt;
; #pragma unroll
;                 for (int j = 0; j < 4; ++j) { s[j] += pf[j] - of[j]; a[j] = s[j] * inv - pf[j]; }
;                 { v2u o; o.x = cvt_pk_bf16(a[0], a[1]); o.y = cvt_pk_bf16(a[2], a[3]); *(v2u*)(po + (size_t)q * D) = o; }
	global_store_dwordx2 v[52:53], v[50:51], off
	v_add_co_u32_e32 v52, vcc, s58, v66
	v_cvt_pk_bf16_f32 v50, v58, v59
	v_cvt_pk_bf16_f32 v51, v170, v171
	v_fma_f32 v176, v119, s8, -v81
	s_nop 0
	v_addc_co_u32_e32 v53, vcc, 0, v67, vcc
	global_store_dwordx2 v[52:53], v[50:51], off
	v_add_co_u32_e32 v52, vcc, s6, v66
	v_cvt_pk_bf16_f32 v50, v128, v130
	v_cvt_pk_bf16_f32 v51, v132, v134
	v_fma_f32 v177, v118, s8, -v80
	s_nop 0
	v_addc_co_u32_e32 v53, vcc, 0, v67, vcc
	global_store_dwordx2 v[52:53], v[50:51], off
	v_add_co_u32_e32 v52, vcc, s7, v66
	v_cvt_pk_bf16_f32 v50, v98, v100
	v_cvt_pk_bf16_f32 v51, v172, v173
	s_add_u32 s0, s0, 0x20000
	s_nop 0
	v_addc_co_u32_e32 v53, vcc, 0, v67, vcc
	global_store_dwordx2 v[52:53], v[50:51], off
	v_add_co_u32_e32 v52, vcc, s15, v66
	v_cvt_pk_bf16_f32 v50, v137, v139
	v_cvt_pk_bf16_f32 v51, v141, v143
	s_addc_u32 s1, s1, 0
	s_nop 0
	v_addc_co_u32_e32 v53, vcc, 0, v67, vcc
	global_store_dwordx2 v[52:53], v[50:51], off
	v_add_co_u32_e32 v52, vcc, s34, v66
	v_cvt_pk_bf16_f32 v50, v56, v57
	v_cvt_pk_bf16_f32 v51, v166, v167
	s_add_u32 s40, s40, 0xa0000
	s_nop 0
	v_addc_co_u32_e32 v53, vcc, 0, v67, vcc
	global_store_dwordx2 v[52:53], v[50:51], off
	v_add_co_u32_e32 v52, vcc, s86, v66
	v_cvt_pk_bf16_f32 v50, v136, v138
	v_cvt_pk_bf16_f32 v51, v140, v142
	s_addc_u32 s41, s41, 0
	s_nop 0
	v_addc_co_u32_e32 v53, vcc, 0, v67, vcc
	global_store_dwordx2 v[52:53], v[50:51], off
	v_add_co_u32_e32 v52, vcc, s87, v66
	v_cvt_pk_bf16_f32 v50, v54, v55
	v_cvt_pk_bf16_f32 v51, v93, v174
	s_cmp_eq_u32 s68, 64
	s_nop 0
	v_addc_co_u32_e32 v53, vcc, 0, v67, vcc
	global_store_dwordx2 v[52:53], v[50:51], off
	v_add_co_u32_e32 v52, vcc, s75, v66
	v_cvt_pk_bf16_f32 v50, v158, v160
	v_cvt_pk_bf16_f32 v51, v162, v164
	s_nop 1
	v_addc_co_u32_e32 v53, vcc, 0, v67, vcc
	global_store_dwordx2 v[52:53], v[50:51], off
	v_add_co_u32_e32 v52, vcc, s3, v66
	v_cvt_pk_bf16_f32 v50, v90, v92
	v_cvt_pk_bf16_f32 v51, v91, v175
	s_nop 1
	v_addc_co_u32_e32 v53, vcc, 0, v67, vcc
	global_store_dwordx2 v[52:53], v[50:51], off
	v_add_co_u32_e32 v52, vcc, s33, v66
	v_cvt_pk_bf16_f32 v50, v157, v159
	v_cvt_pk_bf16_f32 v51, v161, v163
	s_nop 1
	v_addc_co_u32_e32 v53, vcc, 0, v67, vcc
	global_store_dwordx2 v[52:53], v[50:51], off
	v_add_co_u32_e32 v52, vcc, s70, v66
	v_cvt_pk_bf16_f32 v50, v64, v65
	v_cvt_pk_bf16_f32 v51, v176, v177
	s_nop 1
	v_addc_co_u32_e32 v53, vcc, 0, v67, vcc
	global_store_dwordx2 v[52:53], v[50:51], off
	v_add_co_u32_e32 v50, vcc, s88, v84
	s_nop 1
	v_addc_co_u32_e32 v51, vcc, 0, v85, vcc
	global_load_dwordx2 v[128:129], v[50:51], off nt
	v_add_co_u32_e32 v50, vcc, s89, v84
	s_nop 1
	v_addc_co_u32_e32 v51, vcc, 0, v85, vcc
	global_load_dwordx2 v[60:61], v[50:51], off nt
	v_add_co_u32_e32 v50, vcc, s11, v84
	s_waitcnt vmcnt(0)
	v_lshlrev_b32_e32 v133, 16, v61
	v_addc_co_u32_e32 v51, vcc, 0, v85, vcc
	global_load_dwordx2 v[130:131], v[50:51], off nt
	v_add_co_u32_e32 v50, vcc, s35, v84
	v_and_b32_e32 v132, 0xffff0000, v61
	s_nop 0
	v_addc_co_u32_e32 v51, vcc, 0, v85, vcc
	global_load_dwordx2 v[52:53], v[50:51], off nt
	v_add_co_u32_e32 v50, vcc, s78, v84
	s_nop 1
	v_addc_co_u32_e32 v51, vcc, 0, v85, vcc
	global_load_dwordx2 v[120:121], v[50:51], off nt
	v_add_co_u32_e32 v50, vcc, s79, v84
	s_nop 1
	v_addc_co_u32_e32 v51, vcc, 0, v85, vcc
	global_load_dwordx2 v[54:55], v[50:51], off nt
	v_add_co_u32_e32 v50, vcc, s82, v84
	s_nop 1
	v_addc_co_u32_e32 v51, vcc, 0, v85, vcc
	global_load_dwordx2 v[122:123], v[50:51], off nt
	v_add_co_u32_e32 v50, vcc, s83, v84
	s_nop 1
	v_addc_co_u32_e32 v51, vcc, 0, v85, vcc
	global_load_dwordx2 v[56:57], v[50:51], off nt
	v_add_co_u32_e32 v50, vcc, s28, v84
	s_nop 1
	v_addc_co_u32_e32 v51, vcc, 0, v85, vcc
	global_load_dwordx2 v[100:101], v[50:51], off nt
	v_add_co_u32_e32 v50, vcc, s29, v84
	s_nop 1
	v_addc_co_u32_e32 v51, vcc, 0, v85, vcc
	global_load_dwordx2 v[58:59], v[50:51], off nt
	v_add_co_u32_e32 v50, vcc, s10, v84
	s_nop 1
	v_addc_co_u32_e32 v51, vcc, 0, v85, vcc
	global_load_dwordx2 v[90:91], v[50:51], off nt
	v_add_co_u32_e32 v50, vcc, s72, v84
	s_nop 1
	v_addc_co_u32_e32 v51, vcc, 0, v85, vcc
	v_add_co_u32_e32 v62, vcc, s73, v84
	global_load_dwordx2 v[50:51], v[50:51], off nt
	s_nop 0
	v_addc_co_u32_e32 v63, vcc, 0, v85, vcc
	global_load_dwordx2 v[98:99], v[62:63], off nt
	v_add_co_u32_e32 v62, vcc, s59, v84
	s_nop 1
	v_addc_co_u32_e32 v63, vcc, 0, v85, vcc
	global_load_dwordx2 v[64:65], v[62:63], off nt
	v_add_co_u32_e32 v62, vcc, s62, v84
	s_nop 1
	v_addc_co_u32_e32 v63, vcc, 0, v85, vcc
	global_load_dwordx2 v[92:93], v[62:63], off nt
	v_add_co_u32_e32 v62, vcc, s63, v84
	v_and_b32_e32 v84, 0xffff0000, v60
	s_nop 0
	v_addc_co_u32_e32 v63, vcc, 0, v85, vcc
	v_lshlrev_b32_e32 v85, 16, v60
	v_pk_add_f32 v[88:89], v[84:85], v[88:89] neg_lo:[0,1] neg_hi:[0,1]
	global_load_dwordx2 v[62:63], v[62:63], off nt
	v_pk_add_f32 v[124:125], v[124:125], v[88:89]
	s_nop 0
	v_fma_f32 v134, v125, s8, -v85
	v_fma_f32 v135, v124, s8, -v84
	v_pk_add_f32 v[84:85], v[132:133], v[86:87] neg_lo:[0,1] neg_hi:[0,1]
	s_waitcnt vmcnt(0)
; __device__ __forceinline__ unsigned cvt_pk_bf16(float lo, float hi) { unsigned r; asm volatile("v_cvt_pk_bf16_f32 %0, %1, %2" : "=v"(r) : "v"(lo), "v"(hi)); return r; }
; __device__ __forceinline__ void unpack4(const v2u q, float (&f)[4]) { f[0] = bf_lo(q.x); f[1] = bf_hi(q.x); f[2] = bf_lo(q.y); f[3] = bf_hi(q.y); }
; template <int W>
; __device__ __forceinline__ void conv_pool_chunk(const bf16* PROJ, bf16* XC, bf16* POOLED, const float* conv_w, const float* conv_b, int chunk, int ch0) {
;     ...
;                 for (int j = 0; j < 4; ++j) a[j] = cb[j] + cw[0][j] * cx[(rr + 1) & 3][j] + cw[1][j] * cx[(rr + 2) & 3][j] + cw[2][j] * cx[(rr + 3) & 3][j] + cw[3][j] * xf[j];
; #pragma unroll
;                 for (int j = 0; j < 4; ++j) cx[rr & 3][j] = xf[j];
;                 { v2u o; o.x = cvt_pk_bf16(a[0], a[1]); o.y = cvt_pk_bf16(a[2], a[3]); *(v2u*)(xo + (size_t)q * D) = o; }
;                 float pf[4], of[4]; unpack4(pn, pf); unpack4(ph[rr & (W - 1)], of);
;                 ph[rr & (W - 1)] = pn;
;                 const int t = t0 + r; const int cnt = (t + 1 < W) ? (t + 1) : W; const float inv = 1.0f / (float)cnt;
; #pragma unroll
;                 for (int j = 0; j < 4; ++j) { s[j] += pf[j] - of[j]; a[j] = s[j] * inv - pf[j]; }
;                 { v2u o; o.x = cvt_pk_bf16(a[0], a[1]); o.y = cvt_pk_bf16(a[2], a[3]); *(v2u*)(po + (size_t)q * D) = o; }
	v_lshlrev_b32_e32 v87, 16, v130
	v_lshlrev_b32_e32 v86, 16, v128
	v_pk_add_f32 v[126:127], v[118:119], v[84:85]
	v_pk_mov_b32 v[84:85], v[108:109], v[86:87] op_sel:[1,0]
	v_fma_f32 v133, v127, s8, -v133
	v_pk_mul_f32 v[88:89], v[34:35], v[84:85]
	v_fma_f32 v132, v126, s8, -v132
	v_add_f32_e32 v88, v153, v88
	v_add_f32_e32 v136, v88, v89
	v_pk_mul_f32 v[88:89], v[34:35], v[86:87]
	v_pk_mul_f32 v[84:85], v[38:39], v[84:85]
	v_add_f32_e32 v88, v156, v88
	v_add_f32_e32 v137, v88, v89
	v_and_b32_e32 v89, 0xffff0000, v130
	v_and_b32_e32 v88, 0xffff0000, v128
	v_pk_mov_b32 v[118:119], v[110:111], v[88:89] op_sel:[1,0]
	v_lshlrev_b32_e32 v111, 16, v131
	v_pk_mul_f32 v[108:109], v[36:37], v[118:119]
	v_lshlrev_b32_e32 v110, 16, v129
	v_add_f32_e32 v108, v151, v108
	v_add_f32_e32 v108, v108, v109
	v_cvt_pk_bf16_f32 v128, v136, v108
	v_pk_mul_f32 v[108:109], v[36:37], v[88:89]
	v_pk_mov_b32 v[112:113], v[112:113], v[110:111] op_sel:[1,0]
	v_add_f32_e32 v108, v155, v108
	v_add_f32_e32 v136, v108, v109
	v_pk_mul_f32 v[108:109], v[26:27], v[112:113]
	v_add_f32_e32 v84, v14, v84
	v_add_f32_e32 v108, v150, v108
	v_add_f32_e32 v138, v108, v109
	v_pk_mul_f32 v[108:109], v[26:27], v[110:111]
	s_nop 0
	v_add_f32_e32 v108, v152, v108
	v_add_f32_e32 v139, v108, v109
	v_and_b32_e32 v109, 0xffff0000, v131
	v_and_b32_e32 v108, 0xffff0000, v129
	v_pk_mov_b32 v[114:115], v[114:115], v[108:109] op_sel:[1,0]
	s_nop 0
	v_pk_mul_f32 v[130:131], v[28:29], v[114:115]
	s_nop 0
	v_add_f32_e32 v129, v149, v130
	v_add_co_u32_e32 v130, vcc, s18, v66
	v_add_f32_e32 v129, v129, v131
	s_nop 0
	v_addc_co_u32_e32 v131, vcc, 0, v67, vcc
	v_cvt_pk_bf16_f32 v129, v138, v129
	global_store_dwordx2 v[130:131], v[128:129], off
	v_add_co_u32_e32 v130, vcc, s19, v66
	v_cvt_pk_bf16_f32 v128, v134, v135
	v_cvt_pk_bf16_f32 v129, v133, v132
	s_nop 1
	v_addc_co_u32_e32 v131, vcc, 0, v67, vcc
	global_store_dwordx2 v[130:131], v[128:129], off
	v_pk_mul_f32 v[128:129], v[28:29], v[108:109]
	v_add_co_u32_e32 v130, vcc, s20, v66
	v_add_f32_e32 v128, v144, v128
	v_add_f32_e32 v129, v128, v129
	v_cvt_pk_bf16_f32 v128, v137, v136
	v_cvt_pk_bf16_f32 v129, v139, v129
	v_addc_co_u32_e32 v131, vcc, 0, v67, vcc
	global_store_dwordx2 v[130:131], v[128:129], off
	v_and_b32_e32 v128, 0xffff0000, v52
	v_lshlrev_b32_e32 v129, 16, v52
	v_and_b32_e32 v130, 0xffff0000, v53
	v_lshlrev_b32_e32 v131, 16, v53
	v_pk_add_f32 v[116:117], v[128:129], v[116:117] neg_lo:[0,1] neg_hi:[0,1]
	v_pk_add_f32 v[104:105], v[130:131], v[104:105] neg_lo:[0,1] neg_hi:[0,1]
	v_pk_add_f32 v[116:117], v[124:125], v[116:117]
	v_pk_add_f32 v[104:105], v[126:127], v[104:105]
	v_fma_f32 v124, v117, s8, -v129
	v_fma_f32 v125, v116, s8, -v128
	v_fma_f32 v126, v105, s8, -v131
	v_fma_f32 v127, v104, s8, -v130
	v_cvt_pk_bf16_f32 v124, v124, v125
	v_cvt_pk_bf16_f32 v125, v126, v127
	v_add_co_u32_e32 v126, vcc, s21, v66
	s_nop 1
	v_addc_co_u32_e32 v127, vcc, 0, v67, vcc
	global_store_dwordx2 v[126:127], v[124:125], off
	v_add_f32_e32 v124, v84, v85
	v_pk_mul_f32 v[84:85], v[40:41], v[118:119]
	v_and_b32_e32 v118, 0xffff0000, v55
	v_add_f32_e32 v84, v15, v84
	v_add_f32_e32 v125, v84, v85
	v_pk_mul_f32 v[84:85], v[30:31], v[112:113]
	v_lshlrev_b32_e32 v119, 16, v55
	v_add_f32_e32 v84, v16, v84
	v_add_f32_e32 v126, v84, v85
	v_pk_mul_f32 v[84:85], v[32:33], v[114:115]
	s_nop 0
	v_add_f32_e32 v84, v17, v84
	v_add_f32_e32 v127, v84, v85
	v_and_b32_e32 v84, 0xffff0000, v54
	v_lshlrev_b32_e32 v85, 16, v54
	v_pk_add_f32 v[106:107], v[84:85], v[106:107] neg_lo:[0,1] neg_hi:[0,1]
	s_nop 0
	v_pk_add_f32 v[112:113], v[116:117], v[106:107]
	s_nop 0
	v_fma_f32 v128, v113, s8, -v85
	v_fma_f32 v129, v112, s8, -v84
	v_pk_add_f32 v[84:85], v[118:119], v[102:103] neg_lo:[0,1] neg_hi:[0,1]
	s_nop 0
	v_pk_add_f32 v[114:115], v[104:105], v[84:85]
	v_pk_mul_f32 v[84:85], v[38:39], v[86:87]
	v_fma_f32 v130, v115, s8, -v119
	v_add_f32_e32 v84, v14, v84
	v_add_f32_e32 v102, v84, v85
	v_lshlrev_b32_e32 v84, 16, v120
	v_lshlrev_b32_e32 v85, 16, v122
	v_pk_mov_b32 v[104:105], v[86:87], v[84:85] op_sel:[1,0]
	v_fma_f32 v131, v114, s8, -v118
	v_pk_mul_f32 v[86:87], v[34:35], v[104:105]
	s_nop 0
	v_add_f32_e32 v86, v124, v86
	v_add_f32_e32 v103, v86, v87
	v_pk_mul_f32 v[86:87], v[34:35], v[84:85]
	s_nop 0
	v_add_f32_e32 v86, v102, v86
	v_add_f32_e32 v124, v86, v87
	v_pk_mul_f32 v[86:87], v[40:41], v[88:89]
	s_nop 0
	v_add_f32_e32 v86, v15, v86
	v_add_f32_e32 v102, v86, v87
	v_and_b32_e32 v87, 0xffff0000, v122
	v_and_b32_e32 v86, 0xffff0000, v120
	v_pk_mov_b32 v[106:107], v[88:89], v[86:87] op_sel:[1,0]
	s_nop 0
	v_pk_mul_f32 v[88:89], v[36:37], v[106:107]
	s_nop 0
	v_add_f32_e32 v88, v125, v88
	v_add_f32_e32 v88, v88, v89
	v_cvt_pk_bf16_f32 v116, v103, v88
	v_pk_mul_f32 v[88:89], v[36:37], v[86:87]
	s_nop 0
	v_add_f32_e32 v88, v102, v88
	v_add_f32_e32 v120, v88, v89
	v_pk_mul_f32 v[88:89], v[30:31], v[110:111]
	s_nop 0
	v_add_f32_e32 v88, v16, v88
	v_add_f32_e32 v117, v88, v89
	v_lshlrev_b32_e32 v88, 16, v121
	v_lshlrev_b32_e32 v89, 16, v123
	v_pk_mov_b32 v[110:111], v[110:111], v[88:89] op_sel:[1,0]
	s_nop 0
	v_pk_mul_f32 v[102:103], v[26:27], v[110:111]
	s_nop 0
	v_add_f32_e32 v102, v126, v102
	v_add_f32_e32 v122, v102, v103
	v_pk_mul_f32 v[102:103], v[26:27], v[88:89]
	s_nop 0
	v_add_f32_e32 v102, v117, v102
	v_add_f32_e32 v125, v102, v103
	v_pk_mul_f32 v[102:103], v[32:33], v[108:109]
	s_nop 0
	v_add_f32_e32 v102, v17, v102
	v_add_f32_e32 v126, v102, v103
	v_and_b32_e32 v103, 0xffff0000, v123
	v_and_b32_e32 v102, 0xffff0000, v121
	v_pk_mov_b32 v[108:109], v[108:109], v[102:103] op_sel:[1,0]
	v_lshlrev_b32_e32 v121, 16, v57
	v_pk_mul_f32 v[118:119], v[28:29], v[108:109]
; __device__ __forceinline__ unsigned cvt_pk_bf16(float lo, float hi) { unsigned r; asm volatile("v_cvt_pk_bf16_f32 %0, %1, %2" : "=v"(r) : "v"(lo), "v"(hi)); return r; }
; __device__ __forceinline__ void unpack4(const v2u q, float (&f)[4]) { f[0] = bf_lo(q.x); f[1] = bf_hi(q.x); f[2] = bf_lo(q.y); f[3] = bf_hi(q.y); }
; template <int W>
; __device__ __forceinline__ void conv_pool_chunk(const bf16* PROJ, bf16* XC, bf16* POOLED, const float* conv_w, const float* conv_b, int chunk, int ch0) {
;     ...
;                 for (int j = 0; j < 4; ++j) a[j] = cb[j] + cw[0][j] * cx[(rr + 1) & 3][j] + cw[1][j] * cx[(rr + 2) & 3][j] + cw[2][j] * cx[(rr + 3) & 3][j] + cw[3][j] * xf[j];
; #pragma unroll
;                 for (int j = 0; j < 4; ++j) cx[rr & 3][j] = xf[j];
;                 { v2u o; o.x = cvt_pk_bf16(a[0], a[1]); o.y = cvt_pk_bf16(a[2], a[3]); *(v2u*)(xo + (size_t)q * D) = o; }
;                 float pf[4], of[4]; unpack4(pn, pf); unpack4(ph[rr & (W - 1)], of);
;                 ph[rr & (W - 1)] = pn;
;                 const int t = t0 + r; const int cnt = (t + 1 < W) ? (t + 1) : W; const float inv = 1.0f / (float)cnt;
; #pragma unroll
;                 for (int j = 0; j < 4; ++j) { s[j] += pf[j] - of[j]; a[j] = s[j] * inv - pf[j]; }
;                 { v2u o; o.x = cvt_pk_bf16(a[0], a[1]); o.y = cvt_pk_bf16(a[2], a[3]); *(v2u*)(po + (size_t)q * D) = o; }
	s_nop 0
	v_add_f32_e32 v117, v127, v118
	v_add_co_u32_e32 v118, vcc, s22, v66
	v_add_f32_e32 v117, v117, v119
	s_nop 0
	v_addc_co_u32_e32 v119, vcc, 0, v67, vcc
	v_cvt_pk_bf16_f32 v117, v122, v117
	global_store_dwordx2 v[118:119], v[116:117], off
	v_add_co_u32_e32 v118, vcc, s23, v66
	v_cvt_pk_bf16_f32 v116, v128, v129
	v_cvt_pk_bf16_f32 v117, v130, v131
	s_nop 1
	v_addc_co_u32_e32 v119, vcc, 0, v67, vcc
	global_store_dwordx2 v[118:119], v[116:117], off
	v_pk_mul_f32 v[116:117], v[28:29], v[102:103]
	v_add_co_u32_e32 v118, vcc, s24, v66
	v_add_f32_e32 v116, v126, v116
	v_add_f32_e32 v117, v116, v117
	v_addc_co_u32_e32 v119, vcc, 0, v67, vcc
	v_cvt_pk_bf16_f32 v116, v124, v120
	v_cvt_pk_bf16_f32 v117, v125, v117
	global_store_dwordx2 v[118:119], v[116:117], off
	v_and_b32_e32 v118, 0xffff0000, v56
	v_lshlrev_b32_e32 v119, 16, v56
	v_and_b32_e32 v120, 0xffff0000, v57
	v_pk_add_f32 v[96:97], v[118:119], v[96:97] neg_lo:[0,1] neg_hi:[0,1]
	v_pk_add_f32 v[76:77], v[120:121], v[76:77] neg_lo:[0,1] neg_hi:[0,1]
	v_pk_add_f32 v[116:117], v[112:113], v[96:97]
	v_and_b32_e32 v113, 0xffff0000, v101
	v_fma_f32 v96, v117, s8, -v119
	v_fma_f32 v97, v116, s8, -v118
	v_pk_add_f32 v[118:119], v[114:115], v[76:77]
	v_cvt_pk_bf16_f32 v76, v96, v97
	v_add_co_u32_e32 v96, vcc, s25, v66
	v_fma_f32 v77, v119, s8, -v121
	v_fma_f32 v112, v118, s8, -v120
	v_cvt_pk_bf16_f32 v77, v77, v112
	v_addc_co_u32_e32 v97, vcc, 0, v67, vcc
	global_store_dwordx2 v[96:97], v[76:77], off
	v_lshlrev_b32_e32 v77, 16, v100
	v_and_b32_e32 v97, 0xffff0000, v100
	v_lshlrev_b32_e32 v115, 16, v101
	v_pk_mul_f32 v[100:101], v[38:39], v[104:105]
	v_mov_b32_e32 v114, v89
	v_add_f32_e32 v76, v14, v100
	v_add_f32_e32 v96, v76, v101
	v_mov_b32_e32 v76, v85
	v_pk_mul_f32 v[100:101], v[34:35], v[76:77]
	v_mov_b32_e32 v112, v103
	v_add_f32_e32 v96, v96, v100
	v_add_f32_e32 v104, v96, v101
	v_pk_mul_f32 v[100:101], v[40:41], v[106:107]
	v_pk_mul_f32 v[84:85], v[38:39], v[84:85]
	v_add_f32_e32 v96, v15, v100
	v_add_f32_e32 v105, v96, v101
	v_mov_b32_e32 v96, v87
	v_pk_mul_f32 v[100:101], v[36:37], v[96:97]
	v_add_f32_e32 v84, v14, v84
	v_add_f32_e32 v100, v105, v100
	v_add_f32_e32 v105, v100, v101
	v_pk_mul_f32 v[100:101], v[30:31], v[110:111]
	s_nop 0
	v_add_f32_e32 v100, v16, v100
	v_add_f32_e32 v106, v100, v101
	v_pk_mul_f32 v[100:101], v[26:27], v[114:115]
	s_nop 0
	v_add_f32_e32 v100, v106, v100
	v_add_f32_e32 v106, v100, v101
	v_pk_mul_f32 v[100:101], v[32:33], v[108:109]
	s_nop 0
	v_add_f32_e32 v100, v17, v100
	v_add_f32_e32 v107, v100, v101
	v_pk_mul_f32 v[100:101], v[28:29], v[112:113]
	s_nop 0
	v_add_f32_e32 v100, v107, v100
	v_add_f32_e32 v101, v100, v101
	v_cvt_pk_bf16_f32 v100, v104, v105
	v_add_co_u32_e32 v104, vcc, s26, v66
	v_cvt_pk_bf16_f32 v101, v106, v101
	s_nop 1
	v_addc_co_u32_e32 v105, vcc, 0, v67, vcc
	global_store_dwordx2 v[104:105], v[100:101], off
	v_and_b32_e32 v100, 0xffff0000, v58
	v_lshlrev_b32_e32 v101, 16, v58
	v_and_b32_e32 v104, 0xffff0000, v59
	v_lshlrev_b32_e32 v105, 16, v59
	v_pk_add_f32 v[78:79], v[100:101], v[78:79] neg_lo:[0,1] neg_hi:[0,1]
	v_pk_add_f32 v[72:73], v[104:105], v[72:73] neg_lo:[0,1] neg_hi:[0,1]
	v_pk_add_f32 v[78:79], v[116:117], v[78:79]
	v_pk_add_f32 v[72:73], v[118:119], v[72:73]
	v_fma_f32 v101, v79, s8, -v101
	v_fma_f32 v100, v78, s8, -v100
	v_fma_f32 v104, v72, s8, -v104
	v_fma_f32 v105, v73, s8, -v105
	v_cvt_pk_bf16_f32 v100, v101, v100
	v_cvt_pk_bf16_f32 v101, v105, v104
	v_add_co_u32_e32 v104, vcc, s27, v66
	s_nop 1
	v_addc_co_u32_e32 v105, vcc, 0, v67, vcc
	global_store_dwordx2 v[104:105], v[100:101], off
	v_add_f32_e32 v100, v84, v85
	v_pk_mul_f32 v[84:85], v[40:41], v[86:87]
	v_and_b32_e32 v86, 0xffff0000, v51
	v_add_f32_e32 v84, v15, v84
	v_add_f32_e32 v101, v84, v85
	v_pk_mul_f32 v[84:85], v[30:31], v[88:89]
	v_lshlrev_b32_e32 v87, 16, v51
	v_add_f32_e32 v84, v16, v84
	v_add_f32_e32 v107, v84, v85
	v_pk_mul_f32 v[84:85], v[32:33], v[102:103]
	v_pk_add_f32 v[74:75], v[86:87], v[74:75] neg_lo:[0,1] neg_hi:[0,1]
	v_add_f32_e32 v84, v17, v84
	v_add_f32_e32 v110, v84, v85
	v_and_b32_e32 v84, 0xffff0000, v50
	v_lshlrev_b32_e32 v85, 16, v50
	v_pk_add_f32 v[88:89], v[84:85], v[94:95] neg_lo:[0,1] neg_hi:[0,1]
	v_pk_add_f32 v[104:105], v[72:73], v[74:75]
	v_pk_add_f32 v[102:103], v[78:79], v[88:89]
	v_lshlrev_b32_e32 v79, 16, v98
	v_lshlrev_b32_e32 v78, 16, v90
	v_fma_f32 v111, v103, s8, -v85
	v_fma_f32 v116, v102, s8, -v84
	v_pk_mul_f32 v[72:73], v[38:39], v[76:77]
	v_pk_mov_b32 v[84:85], v[78:79], v[78:79] op_sel:[1,0]
	v_add_f32_e32 v72, v14, v72
	v_mov_b32_e32 v94, v77
	v_mov_b32_e32 v95, v85
	v_add_f32_e32 v74, v72, v73
	v_pk_mul_f32 v[72:73], v[34:35], v[94:95]
	v_and_b32_e32 v77, 0xffff0000, v98
	v_add_f32_e32 v72, v100, v72
	v_add_f32_e32 v75, v72, v73
	v_pk_mul_f32 v[72:73], v[34:35], v[78:79]
	v_and_b32_e32 v76, 0xffff0000, v90
; __device__ __forceinline__ unsigned cvt_pk_bf16(float lo, float hi) { unsigned r; asm volatile("v_cvt_pk_bf16_f32 %0, %1, %2" : "=v"(r) : "v"(lo), "v"(hi)); return r; }
; __device__ __forceinline__ void unpack4(const v2u q, float (&f)[4]) { f[0] = bf_lo(q.x); f[1] = bf_hi(q.x); f[2] = bf_lo(q.y); f[3] = bf_hi(q.y); }
; template <int W>
; __device__ __forceinline__ void conv_pool_chunk(const bf16* PROJ, bf16* XC, bf16* POOLED, const float* conv_w, const float* conv_b, int chunk, int ch0) {
;     ...
;                 for (int j = 0; j < 4; ++j) a[j] = cb[j] + cw[0][j] * cx[(rr + 1) & 3][j] + cw[1][j] * cx[(rr + 2) & 3][j] + cw[2][j] * cx[(rr + 3) & 3][j] + cw[3][j] * xf[j];
; #pragma unroll
;                 for (int j = 0; j < 4; ++j) cx[rr & 3][j] = xf[j];
;                 { v2u o; o.x = cvt_pk_bf16(a[0], a[1]); o.y = cvt_pk_bf16(a[2], a[3]); *(v2u*)(xo + (size_t)q * D) = o; }
;                 float pf[4], of[4]; unpack4(pn, pf); unpack4(ph[rr & (W - 1)], of);
;                 ph[rr & (W - 1)] = pn;
;                 const int t = t0 + r; const int cnt = (t + 1 < W) ? (t + 1) : W; const float inv = 1.0f / (float)cnt;
; #pragma unroll
;                 for (int j = 0; j < 4; ++j) { s[j] += pf[j] - of[j]; a[j] = s[j] * inv - pf[j]; }
;                 { v2u o; o.x = cvt_pk_bf16(a[0], a[1]); o.y = cvt_pk_bf16(a[2], a[3]); *(v2u*)(po + (size_t)q * D) = o; }
;             }
;             p += 8 * NIN; xo += 8 * D; po += 8 * D;
	v_add_f32_e32 v72, v74, v72
	v_fma_f32 v117, v105, s8, -v87
	v_fma_f32 v118, v104, s8, -v86
	v_add_f32_e32 v85, v72, v73
	v_pk_mul_f32 v[72:73], v[40:41], v[96:97]
	v_pk_mov_b32 v[86:87], v[76:77], v[76:77] op_sel:[1,0]
	v_add_f32_e32 v72, v15, v72
	v_mov_b32_e32 v96, v97
	v_mov_b32_e32 v97, v87
	v_add_f32_e32 v74, v72, v73
	v_pk_mul_f32 v[72:73], v[36:37], v[96:97]
	v_mov_b32_e32 v100, v115
	v_add_f32_e32 v72, v101, v72
	v_add_f32_e32 v72, v72, v73
	v_cvt_pk_bf16_f32 v106, v75, v72
	v_pk_mul_f32 v[72:73], v[36:37], v[76:77]
	v_lshlrev_b32_e32 v75, 16, v99
	v_add_f32_e32 v72, v74, v72
	v_lshlrev_b32_e32 v74, 16, v91
	v_add_f32_e32 v87, v72, v73
	v_pk_mul_f32 v[72:73], v[30:31], v[114:115]
	v_pk_mov_b32 v[88:89], v[74:75], v[74:75] op_sel:[1,0]
	v_add_f32_e32 v72, v16, v72
	v_mov_b32_e32 v101, v89
	v_add_f32_e32 v90, v72, v73
	v_pk_mul_f32 v[72:73], v[26:27], v[100:101]
	v_mov_b32_e32 v98, v113
	v_add_f32_e32 v72, v107, v72
	v_add_f32_e32 v89, v72, v73
	v_pk_mul_f32 v[72:73], v[26:27], v[74:75]
	s_nop 0
	v_add_f32_e32 v72, v90, v72
	v_add_f32_e32 v114, v72, v73
	v_pk_mul_f32 v[72:73], v[32:33], v[112:113]
	s_nop 0
	v_add_f32_e32 v72, v17, v72
	v_add_f32_e32 v112, v72, v73
	v_and_b32_e32 v73, 0xffff0000, v99
	v_and_b32_e32 v72, 0xffff0000, v91
	v_pk_mov_b32 v[90:91], v[72:73], v[72:73] op_sel:[1,0]
	s_nop 0
	v_mov_b32_e32 v99, v91
	v_pk_mul_f32 v[108:109], v[28:29], v[98:99]
	s_nop 0
	v_add_f32_e32 v91, v110, v108
	v_add_co_u32_e32 v108, vcc, s12, v66
	v_add_f32_e32 v91, v91, v109
	s_nop 0
	v_addc_co_u32_e32 v109, vcc, 0, v67, vcc
	v_cvt_pk_bf16_f32 v107, v89, v91
	global_store_dwordx2 v[108:109], v[106:107], off
	v_add_co_u32_e32 v108, vcc, s13, v66
	v_cvt_pk_bf16_f32 v106, v111, v116
	v_cvt_pk_bf16_f32 v107, v117, v118
	s_nop 1
	v_addc_co_u32_e32 v109, vcc, 0, v67, vcc
	global_store_dwordx2 v[108:109], v[106:107], off
	v_pk_mul_f32 v[106:107], v[28:29], v[72:73]
	v_add_co_u32_e32 v108, vcc, s74, v66
	v_add_f32_e32 v89, v112, v106
	v_add_f32_e32 v89, v89, v107
	v_cvt_pk_bf16_f32 v106, v85, v87
	v_cvt_pk_bf16_f32 v107, v114, v89
	v_addc_co_u32_e32 v109, vcc, 0, v67, vcc
	global_store_dwordx2 v[108:109], v[106:107], off
	v_and_b32_e32 v106, 0xffff0000, v64
	v_lshlrev_b32_e32 v107, 16, v64
	v_and_b32_e32 v108, 0xffff0000, v65
	v_lshlrev_b32_e32 v109, 16, v65
	v_pk_add_f32 v[68:69], v[106:107], v[68:69] neg_lo:[0,1] neg_hi:[0,1]
	v_pk_add_f32 v[70:71], v[108:109], v[70:71] neg_lo:[0,1] neg_hi:[0,1]
	v_pk_add_f32 v[68:69], v[102:103], v[68:69]
	v_pk_add_f32 v[70:71], v[104:105], v[70:71]
	v_fma_f32 v85, v69, s8, -v107
	v_fma_f32 v87, v68, s8, -v106
	v_fma_f32 v89, v71, s8, -v109
	v_fma_f32 v91, v70, s8, -v108
	v_cvt_pk_bf16_f32 v102, v85, v87
	v_cvt_pk_bf16_f32 v103, v89, v91
	v_lshlrev_b32_e32 v85, 16, v92
	v_and_b32_e32 v87, 0xffff0000, v92
	v_lshlrev_b32_e32 v89, 16, v93
	v_and_b32_e32 v91, 0xffff0000, v93
	v_pk_mul_f32 v[92:93], v[38:39], v[94:95]
	v_add_co_u32_e32 v104, vcc, s84, v66
	v_add_f32_e32 v92, v14, v92
	v_add_f32_e32 v94, v92, v93
	v_pk_mul_f32 v[92:93], v[34:35], v[84:85]
	v_addc_co_u32_e32 v105, vcc, 0, v67, vcc
	v_add_f32_e32 v84, v94, v92
	v_add_f32_e32 v84, v84, v93
	v_pk_mul_f32 v[92:93], v[40:41], v[96:97]
	global_store_dwordx2 v[104:105], v[102:103], off
	v_add_f32_e32 v92, v15, v92
	v_add_f32_e32 v94, v92, v93
	v_pk_mul_f32 v[92:93], v[36:37], v[86:87]
	v_mov_b32_e32 v104, v91
	v_add_f32_e32 v86, v94, v92
	v_add_f32_e32 v86, v86, v93
	v_pk_mul_f32 v[92:93], v[30:31], v[100:101]
	v_mov_b32_e32 v106, v89
	v_add_f32_e32 v92, v16, v92
	v_add_f32_e32 v94, v92, v93
	v_pk_mul_f32 v[92:93], v[26:27], v[88:89]
	v_mov_b32_e32 v108, v87
	v_add_f32_e32 v88, v94, v92
	v_add_f32_e32 v88, v88, v93
	v_pk_mul_f32 v[92:93], v[32:33], v[98:99]
	v_mov_b32_e32 v110, v85
	v_add_f32_e32 v92, v17, v92
	v_add_f32_e32 v94, v92, v93
	v_pk_mul_f32 v[92:93], v[28:29], v[90:91]
	s_nop 0
	v_add_f32_e32 v90, v94, v92
	v_add_co_u32_e32 v94, vcc, s85, v66
	v_add_f32_e32 v90, v90, v93
	s_nop 0
	v_addc_co_u32_e32 v95, vcc, 0, v67, vcc
	v_cvt_pk_bf16_f32 v92, v84, v86
	v_cvt_pk_bf16_f32 v93, v88, v90
	global_store_dwordx2 v[94:95], v[92:93], off
	v_and_b32_e32 v94, 0xffff0000, v63
	v_lshlrev_b32_e32 v95, 16, v63
	v_and_b32_e32 v92, 0xffff0000, v62
	v_lshlrev_b32_e32 v93, 16, v62
	v_pk_add_f32 v[80:81], v[94:95], v[80:81] neg_lo:[0,1] neg_hi:[0,1]
	v_pk_add_f32 v[82:83], v[92:93], v[82:83] neg_lo:[0,1] neg_hi:[0,1]
	v_pk_add_f32 v[70:71], v[70:71], v[80:81]
	v_add_co_u32_e32 v66, vcc, s77, v66
	v_pk_add_f32 v[68:69], v[68:69], v[82:83]
	v_fma_f32 v81, v71, s8, -v95
	v_addc_co_u32_e32 v67, vcc, 0, v67, vcc
	v_fma_f32 v82, v69, s8, -v93
	v_fma_f32 v83, v68, s8, -v92
	v_fma_f32 v84, v70, s8, -v94
	v_cvt_pk_bf16_f32 v80, v82, v83
	v_cvt_pk_bf16_f32 v81, v81, v84
	global_store_dwordx2 v[66:67], v[80:81], off
	s_cbranch_scc0 .LBB0_353

; __device__ __forceinline__ void unpack4(const v2u q, float (&f)[4]) { f[0] = bf_lo(q.x); f[1] = bf_hi(q.x); f[2] = bf_lo(q.y); f[3] = bf_hi(q.y); }
; template <int W>
; __device__ __forceinline__ void conv_pool_chunk(const bf16* PROJ, bf16* XC, bf16* POOLED, const float* conv_w, const float* conv_b, int chunk, int ch0) {
;     ...
;     if (t0 > 0) {
; #pragma unroll
;         for (int q = 1; q <= 3; ++q) { const v2u x = *(const v2u*)(pr - (ptrdiff_t)q * NIN); unpack4(x, cx[(64 - q) & 3]); }
; #pragma unroll
;         for (int q = 1; q < W; ++q) { const v2u x = *(const v2u*)(pr + 2 * D - (ptrdiff_t)q * NIN); ph[(64 - q) & (W - 1)] = x; float f[4]; unpack4(x, f);
; #pragma unroll
;             for (int j = 0; j < 4; ++j) s[j] += f[j]; }
;     }
.LBB0_355:
	s_andn2_b64 vcc, exec, s[0:1]
	s_cbranch_vccnz .LBB0_339
	v_cndmask_b32_e64 v26, 0, 1, s[44:45]
	s_mov_b64 s[0:1], -1
	s_cmp_eq_u32 s17, 1
	v_cmp_ne_u32_e64 s[44:45], 1, v26
	s_cbranch_scc1 .LBB0_363
	s_and_b64 vcc, exec, s[44:45]
	s_mov_b32 s17, 0
	s_cbranch_vccnz .LBB0_359
	v_add_co_u32_e32 v26, vcc, 0xffff6000, v24
	s_movk_i32 s0, 0xa000
	s_nop 0
	v_addc_co_u32_e32 v27, vcc, -1, v25, vcc
	v_add_co_u32_e32 v28, vcc, 0xfffec000, v24
	s_nop 1
	v_addc_co_u32_e32 v29, vcc, -1, v25, vcc
	v_add_co_u32_e32 v30, vcc, 0xfffe2000, v24
	global_load_dwordx2 v[26:27], v[26:27], off nt
	s_nop 0
	global_load_dwordx2 v[28:29], v[28:29], off nt
	v_addc_co_u32_e32 v31, vcc, -1, v25, vcc
	v_add_co_u32_e32 v32, vcc, s0, v24
	global_load_dwordx2 v[30:31], v[30:31], off nt
	s_nop 0
	v_addc_co_u32_e32 v33, vcc, -1, v25, vcc
	global_load_dwordx2 v[44:45], v[32:33], off nt
	s_waitcnt vmcnt(0)
	v_and_b32_e32 v59, 0xffff0000, v26
	v_lshlrev_b32_e32 v55, 16, v27
	v_and_b32_e32 v51, 0xffff0000, v27
	v_lshlrev_b32_e32 v63, 16, v26
	v_lshlrev_b32_e32 v108, 16, v28
	v_and_b32_e32 v61, 0xffff0000, v28
	v_lshlrev_b32_e32 v57, 16, v29
	v_and_b32_e32 v53, 0xffff0000, v29
	v_lshlrev_b32_e32 v62, 16, v30
	v_and_b32_e32 v26, 0xffff0000, v44
	v_lshlrev_b32_e32 v27, 16, v44
	v_and_b32_e32 v28, 0xffff0000, v45
	v_lshlrev_b32_e32 v29, 16, v45
	v_and_b32_e32 v60, 0xffff0000, v30
	v_lshlrev_b32_e32 v56, 16, v31
	v_and_b32_e32 v52, 0xffff0000, v31
	v_pk_add_f32 v[64:65], v[26:27], 0 op_sel_hi:[1,0]
	v_pk_add_f32 v[66:67], v[28:29], 0 op_sel_hi:[1,0]
	s_branch .LBB0_360

; __device__ __forceinline__ unsigned cvt_pk_bf16(float lo, float hi) { unsigned r; asm volatile("v_cvt_pk_bf16_f32 %0, %1, %2" : "=v"(r) : "v"(lo), "v"(hi)); return r; }
; __device__ __forceinline__ void unpack4(const v2u q, float (&f)[4]) { f[0] = bf_lo(q.x); f[1] = bf_hi(q.x); f[2] = bf_lo(q.y); f[3] = bf_hi(q.y); }
; template <int W>
; __device__ __forceinline__ void conv_pool_chunk(const bf16* PROJ, bf16* XC, bf16* POOLED, const float* conv_w, const float* conv_b, int chunk, int ch0) {
;     ...
;             v2u xnb[8], pnb[8];
; #pragma unroll
;             for (int q = 0; q < 8; ++q) { xnb[q] = *(const v2u*)(p + (size_t)q * NIN); pnb[q] = *(const v2u*)(p + (size_t)q * NIN + 2 * D); }
; #pragma unroll
;             for (int q = 0; q < 8; ++q) { const int rr = h8 * 8 + q; const int r = rb * 16 + rr;
;                 const v2u xn = xnb[q], pn = pnb[q];
;                 float xf[4]; unpack4(xn, xf);
;                 float a[4];
; #pragma unroll
;                 for (int j = 0; j < 4; ++j) a[j] = cb[j] + cw[0][j] * cx[(rr + 1) & 3][j] + cw[1][j] * cx[(rr + 2) & 3][j] + cw[2][j] * cx[(rr + 3) & 3][j] + cw[3][j] * xf[j];
; #pragma unroll
;                 for (int j = 0; j < 4; ++j) cx[rr & 3][j] = xf[j];
;                 { v2u o; o.x = cvt_pk_bf16(a[0], a[1]); o.y = cvt_pk_bf16(a[2], a[3]); *(v2u*)(xo + (size_t)q * D) = o; }
;                 float pf[4], of[4]; unpack4(pn, pf); unpack4(ph[rr & (W - 1)], of);
;                 ph[rr & (W - 1)] = pn;
;                 const int t = t0 + r; const int cnt = (t + 1 < W) ? (t + 1) : W; const float inv = 1.0f / (float)cnt;
; #pragma unroll
;                 for (int j = 0; j < 4; ++j) { s[j] += pf[j] - of[j]; a[j] = s[j] * inv - pf[j]; }
.LBB0_361:
	v_lshl_add_u64 v[68:69], s[40:41], 0, v[22:23]
	v_add_co_u32_e32 v70, vcc, s81, v68
	global_load_dwordx2 v[76:77], v[68:69], off nt
	s_nop 0
	v_addc_co_u32_e32 v71, vcc, 0, v69, vcc
	global_load_dwordx2 v[110:111], v[70:71], off nt
	v_add_co_u32_e32 v70, vcc, s36, v68
	v_mov_b32_e32 v109, v62
	s_nop 0
	v_addc_co_u32_e32 v71, vcc, 0, v69, vcc
	global_load_dwordx2 v[104:105], v[70:71], off nt
	v_add_co_u32_e32 v70, vcc, s37, v68
	v_lshlrev_b32_e32 v101, 16, v46
	s_nop 0
	v_addc_co_u32_e32 v71, vcc, 0, v69, vcc
	global_load_dwordx2 v[98:99], v[70:71], off nt
	v_add_co_u32_e32 v70, vcc, s42, v68
	v_and_b32_e32 v100, 0xffff0000, v46
	s_nop 0
	v_addc_co_u32_e32 v71, vcc, 0, v69, vcc
	global_load_dwordx2 v[80:81], v[70:71], off nt
	v_add_co_u32_e32 v70, vcc, s64, v68
	v_lshlrev_b32_e32 v107, 16, v47
	s_nop 0
	v_addc_co_u32_e32 v71, vcc, 0, v69, vcc
	global_load_dwordx2 v[92:93], v[70:71], off nt
	v_add_co_u32_e32 v70, vcc, s65, v68
	v_and_b32_e32 v106, 0xffff0000, v47
	s_nop 0
	v_addc_co_u32_e32 v71, vcc, 0, v69, vcc
	global_load_dwordx2 v[96:97], v[70:71], off nt
	v_add_co_u32_e32 v70, vcc, s66, v68
	v_mov_b32_e32 v58, v61
	s_nop 0
	v_addc_co_u32_e32 v71, vcc, 0, v69, vcc
	global_load_dwordx2 v[82:83], v[70:71], off nt
	v_add_co_u32_e32 v70, vcc, s67, v68
	v_lshl_add_u64 v[48:49], s[0:1], 0, v[22:23]
	s_nop 0
	v_addc_co_u32_e32 v71, vcc, 0, v69, vcc
	global_load_dwordx2 v[74:75], v[70:71], off nt
	v_add_co_u32_e32 v70, vcc, s71, v68
	v_lshlrev_b32_e32 v133, 16, v45
	s_nop 0
	v_addc_co_u32_e32 v71, vcc, 0, v69, vcc
	global_load_dwordx2 v[94:95], v[70:71], off nt
	v_add_co_u32_e32 v70, vcc, s90, v68
	v_and_b32_e32 v132, 0xffff0000, v45
	s_nop 0
	v_addc_co_u32_e32 v71, vcc, 0, v69, vcc
	global_load_dwordx2 v[90:91], v[70:71], off nt
	v_add_co_u32_e32 v70, vcc, s91, v68
	s_or_b32 s68, s17, s16
	s_nop 0
	v_addc_co_u32_e32 v71, vcc, 0, v69, vcc
	global_load_dwordx2 v[88:89], v[70:71], off nt
	v_add_co_u32_e32 v70, vcc, s92, v68
	s_cmp_eq_u32 s68, 0
	s_nop 0
	v_addc_co_u32_e32 v71, vcc, 0, v69, vcc
	global_load_dwordx2 v[84:85], v[70:71], off nt
	v_add_co_u32_e32 v70, vcc, s93, v68
	s_cselect_b32 s68, 1.0, 0.5
	s_nop 0
	v_addc_co_u32_e32 v71, vcc, 0, v69, vcc
	global_load_dwordx2 v[86:87], v[70:71], off nt
	v_add_co_u32_e32 v70, vcc, s94, v68
	s_add_i32 s17, s17, 1
	s_nop 0
	v_addc_co_u32_e32 v71, vcc, 0, v69, vcc
	v_add_co_u32_e32 v72, vcc, s95, v68
	s_waitcnt vmcnt(0)
	v_lshlrev_b32_e32 v103, 16, v111
	v_addc_co_u32_e32 v73, vcc, 0, v69, vcc
	global_load_dwordx2 v[78:79], v[72:73], off nt
	v_pk_mul_f32 v[72:73], v[38:39], v[108:109]
	v_mov_b32_e32 v109, v63
	v_add_f32_e32 v50, v14, v73
	v_add_f32_e32 v50, v72, v50
	v_pk_mul_f32 v[72:73], v[40:41], v[60:61]
	v_pk_mul_f32 v[46:47], v[42:43], v[108:109]
	v_add_f32_e32 v54, v15, v72
	v_add_f32_e32 v54, v73, v54
	v_pk_mul_f32 v[72:73], v[30:31], v[56:57]
	v_lshlrev_b32_e32 v109, 16, v104
	v_add_f32_e32 v56, v16, v72
	v_add_f32_e32 v114, v73, v56
	v_pk_mul_f32 v[72:73], v[32:33], v[52:53]
	v_lshlrev_b32_e32 v108, 16, v76
	v_add_f32_e32 v52, v17, v72
	v_add_f32_e32 v46, v14, v46
	v_pk_mov_b32 v[62:63], v[62:63], v[108:109] op_sel:[1,0]
	v_add_f32_e32 v116, v73, v52
	v_add_f32_e32 v52, v46, v47
	v_pk_mul_f32 v[46:47], v[34:35], v[62:63]
	v_and_b32_e32 v60, 0xffff0000, v76
	v_add_f32_e32 v46, v50, v46
	v_add_f32_e32 v50, v46, v47
	v_pk_mul_f32 v[46:47], v[34:35], v[108:109]
	v_and_b32_e32 v61, 0xffff0000, v104
	v_add_f32_e32 v46, v52, v46
	v_add_f32_e32 v112, v46, v47
	v_pk_mul_f32 v[46:47], v[40:41], v[58:59]
	v_mov_b32_e32 v58, v59
	v_add_f32_e32 v46, v15, v46
	v_mov_b32_e32 v59, v60
	v_add_f32_e32 v52, v46, v47
	v_pk_mul_f32 v[46:47], v[36:37], v[58:59]
	v_lshlrev_b32_e32 v73, 16, v110
	v_and_b32_e32 v72, 0xffff0000, v110
	v_and_b32_e32 v102, 0xffff0000, v111
	v_add_f32_e32 v46, v54, v46
	v_pk_mul_f32 v[110:111], v[36:37], v[60:61]
	v_mov_b32_e32 v54, v57
	v_add_f32_e32 v46, v46, v47
	v_add_f32_e32 v47, v52, v110
	v_pk_mul_f32 v[56:57], v[30:31], v[54:55]
	v_add_f32_e32 v113, v47, v111
	v_add_f32_e32 v47, v16, v56
	v_lshlrev_b32_e32 v56, 16, v77
	v_mov_b32_e32 v54, v55
	v_mov_b32_e32 v55, v56
	global_load_dwordx2 v[70:71], v[70:71], off nt
	v_pk_mul_f32 v[110:111], v[26:27], v[54:55]
	v_cvt_pk_bf16_f32 v46, v50, v46
	v_add_f32_e32 v47, v47, v57
	v_lshlrev_b32_e32 v57, 16, v105
	v_add_f32_e32 v50, v114, v110
	v_add_f32_e32 v104, v50, v111
	v_pk_mul_f32 v[110:111], v[26:27], v[56:57]
	v_mov_b32_e32 v50, v53
	v_add_f32_e32 v47, v47, v110
	v_pk_mul_f32 v[52:53], v[32:33], v[50:51]
	v_add_f32_e32 v115, v47, v111
	v_add_f32_e32 v47, v17, v52
	v_and_b32_e32 v52, 0xffff0000, v77
	v_mov_b32_e32 v50, v51
	v_mov_b32_e32 v51, v52
	v_pk_mul_f32 v[76:77], v[28:29], v[50:51]
	v_add_f32_e32 v110, v47, v53
	v_add_f32_e32 v47, v116, v76
	v_add_co_u32_e32 v76, vcc, s96, v48
	v_add_f32_e32 v47, v47, v77
	s_nop 0
	v_addc_co_u32_e32 v77, vcc, 0, v49, vcc
	v_cvt_pk_bf16_f32 v47, v104, v47
	global_store_dwordx2 v[76:77], v[46:47], off
	v_lshlrev_b32_e32 v77, 16, v44
	v_and_b32_e32 v76, 0xffff0000, v44
	v_pk_mul_f32 v[44:45], v[42:43], v[62:63]
	v_and_b32_e32 v53, 0xffff0000, v105
	v_add_f32_e32 v44, v14, v44
	v_add_f32_e32 v62, v44, v45
	v_pk_mul_f32 v[44:45], v[40:41], v[58:59]
	v_pk_mul_f32 v[46:47], v[28:29], v[52:53]
	v_add_f32_e32 v44, v15, v44
	v_add_f32_e32 v63, v44, v45
	v_pk_mul_f32 v[44:45], v[30:31], v[54:55]
	v_add_f32_e32 v46, v110, v46
	v_add_f32_e32 v44, v16, v44
	v_add_f32_e32 v124, v46, v47
	v_lshlrev_b32_e32 v47, 16, v98
	v_and_b32_e32 v46, 0xffff0000, v98
	v_add_f32_e32 v98, v44, v45
	v_pk_mul_f32 v[44:45], v[32:33], v[50:51]
	v_lshlrev_b32_e32 v131, 16, v99
	v_add_f32_e32 v44, v17, v44
; template <int W>
; __device__ __forceinline__ void conv_pool_chunk(const bf16* PROJ, bf16* XC, bf16* POOLED, const float* conv_w, const float* conv_b, int chunk, int ch0) {
;     ...
;                 for (int j = 0; j < 4; ++j) a[j] = cb[j] + cw[0][j] * cx[(rr + 1) & 3][j] + cw[1][j] * cx[(rr + 2) & 3][j] + cw[2][j] * cx[(rr + 3) & 3][j] + cw[3][j] * xf[j];
; #pragma unroll
;                 for (int j = 0; j < 4; ++j) cx[rr & 3][j] = xf[j];
	v_and_b32_e32 v130, 0xffff0000, v99
	v_add_f32_e32 v99, v44, v45
	v_pk_mul_f32 v[44:45], v[42:43], v[108:109]
	v_lshlrev_b32_e32 v51, 16, v96
	v_add_f32_e32 v44, v14, v44
	v_lshlrev_b32_e32 v50, 16, v80
	v_add_f32_e32 v58, v44, v45
	v_pk_mov_b32 v[44:45], v[108:109], v[50:51] op_sel:[1,0]
	v_lshlrev_b32_e32 v137, 16, v93
	v_pk_mul_f32 v[54:55], v[34:35], v[44:45]
	v_pk_mul_f32 v[44:45], v[42:43], v[44:45]
	v_add_f32_e32 v54, v62, v54
	v_add_f32_e32 v125, v54, v55
	v_pk_mul_f32 v[54:55], v[34:35], v[50:51]
	v_add_f32_e32 v44, v14, v44
	v_add_f32_e32 v54, v58, v54
	v_add_f32_e32 v118, v54, v55
	v_pk_mul_f32 v[54:55], v[40:41], v[60:61]
	v_and_b32_e32 v136, 0xffff0000, v93
	v_add_f32_e32 v54, v15, v54
	v_add_f32_e32 v62, v54, v55
	v_and_b32_e32 v55, 0xffff0000, v96
	v_and_b32_e32 v54, 0xffff0000, v80
	v_pk_mov_b32 v[58:59], v[60:61], v[54:55] op_sel:[1,0]
	v_and_b32_e32 v93, 0xffff0000, v90
	v_pk_mul_f32 v[60:61], v[36:37], v[58:59]
	v_lshlrev_b32_e32 v139, 16, v95
	v_add_f32_e32 v60, v63, v60
	v_add_f32_e32 v126, v60, v61
	v_pk_mul_f32 v[60:61], v[36:37], v[54:55]
	v_and_b32_e32 v138, 0xffff0000, v95
	v_add_f32_e32 v60, v62, v60
	v_add_f32_e32 v120, v60, v61
	v_pk_mul_f32 v[60:61], v[30:31], v[56:57]
	v_and_b32_e32 v105, 0xffff0000, v91
	v_add_f32_e32 v60, v16, v60
	v_add_f32_e32 v80, v60, v61
	v_lshlrev_b32_e32 v61, 16, v97
	v_lshlrev_b32_e32 v60, 16, v81
	v_pk_mov_b32 v[56:57], v[56:57], v[60:61] op_sel:[1,0]
	v_and_b32_e32 v104, 0xffff0000, v75
	v_pk_mul_f32 v[62:63], v[26:27], v[56:57]
	v_lshlrev_b32_e32 v141, 16, v89
	v_add_f32_e32 v62, v98, v62
	v_add_f32_e32 v127, v62, v63
	v_pk_mul_f32 v[62:63], v[26:27], v[60:61]
	v_lshlrev_b32_e32 v98, 16, v75
	v_add_f32_e32 v62, v80, v62
	v_add_f32_e32 v122, v62, v63
	v_pk_mul_f32 v[62:63], v[32:33], v[52:53]
	v_lshlrev_b32_e32 v75, 16, v88
	v_add_f32_e32 v62, v17, v62
	v_add_f32_e32 v96, v62, v63
	v_and_b32_e32 v63, 0xffff0000, v97
	v_and_b32_e32 v62, 0xffff0000, v81
	v_pk_mov_b32 v[52:53], v[52:53], v[62:63] op_sel:[1,0]
	v_and_b32_e32 v140, 0xffff0000, v89
	v_pk_mul_f32 v[80:81], v[28:29], v[52:53]
	v_pk_add_f32 v[106:107], v[102:103], v[106:107] neg_lo:[0,1] neg_hi:[0,1]
	v_add_f32_e32 v80, v99, v80
	v_add_f32_e32 v128, v80, v81
	v_pk_mul_f32 v[80:81], v[28:29], v[62:63]
	v_lshlrev_b32_e32 v99, 16, v91
	v_add_f32_e32 v80, v96, v80
	v_add_f32_e32 v96, v44, v45
	v_pk_mul_f32 v[44:45], v[40:41], v[58:59]
	v_add_f32_e32 v123, v80, v81
	v_add_f32_e32 v44, v15, v44
	v_add_f32_e32 v58, v44, v45
	v_pk_mul_f32 v[44:45], v[30:31], v[56:57]
	v_lshlrev_b32_e32 v81, 16, v92
	v_add_f32_e32 v44, v16, v44
	v_add_f32_e32 v97, v44, v45
	v_pk_mul_f32 v[44:45], v[32:33], v[52:53]
	v_pk_mul_f32 v[52:53], v[42:43], v[50:51]
	v_add_f32_e32 v44, v17, v44
	v_add_f32_e32 v52, v14, v52
	v_add_f32_e32 v59, v52, v53
	v_lshlrev_b32_e32 v53, 16, v90
	v_lshlrev_b32_e32 v52, 16, v74
	v_pk_mov_b32 v[50:51], v[50:51], v[52:53] op_sel:[1,0]
	v_add_f32_e32 v108, v44, v45
	v_pk_mul_f32 v[56:57], v[34:35], v[50:51]
	v_lshlrev_b32_e32 v45, 16, v94
	v_add_f32_e32 v56, v96, v56
	v_add_f32_e32 v116, v56, v57
	v_pk_mul_f32 v[56:57], v[34:35], v[52:53]
	v_and_b32_e32 v80, 0xffff0000, v92
	v_add_f32_e32 v56, v59, v56
	v_and_b32_e32 v44, 0xffff0000, v94
	v_add_f32_e32 v94, v56, v57
	v_pk_mul_f32 v[56:57], v[40:41], v[54:55]
	v_and_b32_e32 v92, 0xffff0000, v74
	v_add_f32_e32 v56, v15, v56
	v_pk_mov_b32 v[54:55], v[54:55], v[92:93] op_sel:[1,0]
	v_add_f32_e32 v59, v56, v57
	v_pk_mul_f32 v[56:57], v[36:37], v[54:55]
	v_pk_mul_f32 v[50:51], v[42:43], v[50:51]
	v_add_f32_e32 v56, v58, v56
	v_add_f32_e32 v117, v56, v57
	v_pk_mul_f32 v[56:57], v[36:37], v[92:93]
	v_add_f32_e32 v50, v14, v50
	v_add_f32_e32 v56, v59, v56
	v_add_f32_e32 v95, v56, v57
	v_pk_mul_f32 v[56:57], v[30:31], v[60:61]
	v_pk_add_f32 v[66:67], v[66:67], v[106:107]
	v_add_f32_e32 v56, v16, v56
	v_add_f32_e32 v74, v56, v57
	v_pk_mov_b32 v[56:57], v[60:61], v[98:99] op_sel:[1,0]
	v_pk_add_f32 v[106:107], v[130:131], v[132:133] neg_lo:[0,1] neg_hi:[0,1]
	v_pk_mul_f32 v[58:59], v[26:27], v[56:57]
	v_fma_f32 v142, s68, v67, -v103
	v_add_f32_e32 v58, v97, v58
	v_add_f32_e32 v119, v58, v59
	v_pk_mul_f32 v[58:59], v[26:27], v[98:99]
	v_fma_f32 v143, s68, v66, -v102
	v_add_f32_e32 v58, v74, v58
	v_add_f32_e32 v96, v58, v59
	v_pk_mul_f32 v[58:59], v[32:33], v[62:63]
	v_pk_add_f32 v[66:67], v[66:67], v[106:107]
	v_add_f32_e32 v58, v17, v58
	v_add_f32_e32 v74, v58, v59
	v_pk_mov_b32 v[58:59], v[62:63], v[104:105] op_sel:[1,0]
	v_add_f32_e32 v62, v50, v51
	v_pk_mul_f32 v[50:51], v[40:41], v[54:55]
	v_pk_mul_f32 v[60:61], v[28:29], v[58:59]
	v_add_f32_e32 v50, v15, v50
	v_add_f32_e32 v63, v50, v51
	v_pk_mul_f32 v[50:51], v[30:31], v[56:57]
	s_waitcnt vmcnt(0)
; __device__ __forceinline__ unsigned cvt_pk_bf16(float lo, float hi) { unsigned r; asm volatile("v_cvt_pk_bf16_f32 %0, %1, %2" : "=v"(r) : "v"(lo), "v"(hi)); return r; }
; __device__ __forceinline__ void unpack4(const v2u q, float (&f)[4]) { f[0] = bf_lo(q.x); f[1] = bf_hi(q.x); f[2] = bf_lo(q.y); f[3] = bf_hi(q.y); }
; template <int W>
; __device__ __forceinline__ void conv_pool_chunk(const bf16* PROJ, bf16* XC, bf16* POOLED, const float* conv_w, const float* conv_b, int chunk, int ch0) {
;     ...
;                 for (int j = 0; j < 4; ++j) a[j] = cb[j] + cw[0][j] * cx[(rr + 1) & 3][j] + cw[1][j] * cx[(rr + 2) & 3][j] + cw[2][j] * cx[(rr + 3) & 3][j] + cw[3][j] * xf[j];
; #pragma unroll
;                 for (int j = 0; j < 4; ++j) cx[rr & 3][j] = xf[j];
;                 { v2u o; o.x = cvt_pk_bf16(a[0], a[1]); o.y = cvt_pk_bf16(a[2], a[3]); *(v2u*)(xo + (size_t)q * D) = o; }
;                 float pf[4], of[4]; unpack4(pn, pf); unpack4(ph[rr & (W - 1)], of);
;                 ph[rr & (W - 1)] = pn;
;                 const int t = t0 + r; const int cnt = (t + 1 < W) ? (t + 1) : W; const float inv = 1.0f / (float)cnt;
; #pragma unroll
;                 for (int j = 0; j < 4; ++j) { s[j] += pf[j] - of[j]; a[j] = s[j] * inv - pf[j]; }
;                 { v2u o; o.x = cvt_pk_bf16(a[0], a[1]); o.y = cvt_pk_bf16(a[2], a[3]); *(v2u*)(po + (size_t)q * D) = o; }
	v_lshlrev_b32_e32 v55, 16, v70
	v_add_f32_e32 v50, v16, v50
	v_add_f32_e32 v90, v50, v51
	v_pk_mul_f32 v[50:51], v[32:33], v[58:59]
	v_lshlrev_b32_e32 v54, 16, v84
	v_add_f32_e32 v50, v17, v50
	v_add_f32_e32 v91, v50, v51
	v_pk_mul_f32 v[50:51], v[42:43], v[52:53]
	v_add_f32_e32 v60, v108, v60
	v_add_f32_e32 v50, v14, v50
	v_pk_mov_b32 v[108:109], v[52:53], v[54:55] op_sel:[1,0]
	v_add_f32_e32 v58, v50, v51
	v_pk_mul_f32 v[50:51], v[34:35], v[108:109]
	v_add_f32_e32 v121, v60, v61
	v_pk_mul_f32 v[60:61], v[28:29], v[104:105]
	v_add_f32_e32 v50, v62, v50
	v_add_f32_e32 v60, v74, v60
	v_and_b32_e32 v74, 0xffff0000, v88
	v_add_f32_e32 v88, v50, v51
	v_pk_mul_f32 v[50:51], v[34:35], v[54:55]
	v_add_f32_e32 v114, v60, v61
	v_add_f32_e32 v50, v58, v50
	v_lshlrev_b32_e32 v61, 16, v86
	v_and_b32_e32 v60, 0xffff0000, v86
	v_add_f32_e32 v86, v50, v51
	v_pk_mul_f32 v[50:51], v[40:41], v[92:93]
	v_and_b32_e32 v59, 0xffff0000, v70
	v_and_b32_e32 v58, 0xffff0000, v84
	v_add_f32_e32 v50, v15, v50
	v_pk_mov_b32 v[110:111], v[92:93], v[58:59] op_sel:[1,0]
	v_add_f32_e32 v52, v50, v51
	v_pk_mul_f32 v[50:51], v[36:37], v[110:111]
	v_lshlrev_b32_e32 v62, 16, v85
	v_add_f32_e32 v50, v63, v50
	v_add_f32_e32 v89, v50, v51
	v_pk_mul_f32 v[50:51], v[36:37], v[58:59]
	v_lshlrev_b32_e32 v63, 16, v71
	v_add_f32_e32 v50, v52, v50
	v_add_f32_e32 v84, v50, v51
	v_pk_mul_f32 v[50:51], v[30:31], v[98:99]
	v_pk_mov_b32 v[134:135], v[98:99], v[62:63] op_sel:[1,0]
	v_add_f32_e32 v50, v16, v50
	v_add_f32_e32 v52, v50, v51
	v_pk_mul_f32 v[50:51], v[26:27], v[134:135]
	v_lshlrev_b32_e32 v57, 16, v87
	v_add_f32_e32 v50, v90, v50
	v_add_f32_e32 v90, v50, v51
	v_pk_mul_f32 v[50:51], v[26:27], v[62:63]
	v_and_b32_e32 v56, 0xffff0000, v87
	v_add_f32_e32 v50, v52, v50
	v_add_f32_e32 v87, v50, v51
	v_pk_mul_f32 v[50:51], v[32:33], v[104:105]
	v_and_b32_e32 v71, 0xffff0000, v71
	v_and_b32_e32 v70, 0xffff0000, v85
	v_add_f32_e32 v50, v17, v50
	v_pk_mov_b32 v[104:105], v[104:105], v[70:71] op_sel:[1,0]
	v_add_f32_e32 v52, v50, v51
	v_pk_mul_f32 v[50:51], v[28:29], v[104:105]
	v_lshlrev_b32_e32 v53, 16, v78
	v_add_f32_e32 v50, v91, v50
	v_add_f32_e32 v93, v50, v51
	v_pk_mul_f32 v[50:51], v[28:29], v[70:71]
	v_pk_add_f32 v[102:103], v[136:137], v[102:103] neg_lo:[0,1] neg_hi:[0,1]
	v_add_f32_e32 v50, v52, v50
	v_add_f32_e32 v85, v50, v51
	v_and_b32_e32 v52, 0xffff0000, v78
	v_lshlrev_b32_e32 v51, 16, v79
	v_and_b32_e32 v50, 0xffff0000, v79
	v_pk_mul_f32 v[78:79], v[42:43], v[108:109]
	v_pk_add_f32 v[76:77], v[46:47], v[76:77] neg_lo:[0,1] neg_hi:[0,1]
	v_add_f32_e32 v78, v14, v78
	v_add_f32_e32 v99, v78, v79
	v_pk_mul_f32 v[78:79], v[40:41], v[110:111]
	s_add_u32 s0, s0, 0x20000
	v_add_f32_e32 v78, v15, v78
	v_add_f32_e32 v98, v78, v79
	v_pk_mul_f32 v[78:79], v[30:31], v[134:135]
	v_fma_f32 v134, v67, 0.5, -v131
	v_add_f32_e32 v78, v16, v78
	v_add_f32_e32 v108, v78, v79
	v_pk_mul_f32 v[78:79], v[32:33], v[104:105]
	v_fma_f32 v135, v66, 0.5, -v130
	v_add_f32_e32 v78, v17, v78
	v_add_f32_e32 v105, v78, v79
	v_pk_mul_f32 v[78:79], v[42:43], v[54:55]
	v_pk_add_f32 v[66:67], v[66:67], v[102:103]
	v_add_f32_e32 v78, v14, v78
	v_add_f32_e32 v111, v78, v79
	v_pk_mul_f32 v[78:79], v[40:41], v[58:59]
	v_fma_f32 v132, v67, 0.5, -v137
	v_add_f32_e32 v78, v15, v78
	v_add_f32_e32 v110, v78, v79
	v_pk_mul_f32 v[78:79], v[30:31], v[62:63]
	v_fma_f32 v133, v66, 0.5, -v136
	v_add_f32_e32 v78, v16, v78
	v_add_f32_e32 v109, v78, v79
	v_pk_mul_f32 v[78:79], v[32:33], v[70:71]
	v_pk_add_f32 v[102:103], v[138:139], v[136:137] neg_lo:[0,1] neg_hi:[0,1]
	v_add_f32_e32 v78, v17, v78
	v_add_f32_e32 v104, v78, v79
	v_and_b32_e32 v78, 0xffff0000, v83
	v_lshlrev_b32_e32 v79, 16, v83
	v_pk_add_f32 v[106:107], v[78:79], v[130:131] neg_lo:[0,1] neg_hi:[0,1]
	s_addc_u32 s1, s1, 0
	v_pk_add_f32 v[66:67], v[66:67], v[106:107]
	s_add_u32 s40, s40, 0xa0000
	v_fma_f32 v130, v67, 0.5, -v79
	v_pk_add_f32 v[102:103], v[66:67], v[102:103]
	v_fma_f32 v131, v66, 0.5, -v78
	v_pk_add_f32 v[66:67], v[140:141], v[78:79] neg_lo:[0,1] neg_hi:[0,1]
	v_pk_add_f32 v[78:79], v[56:57], v[138:139] neg_lo:[0,1] neg_hi:[0,1]
	v_pk_add_f32 v[66:67], v[102:103], v[66:67]
	v_fma_f32 v107, v103, 0.5, -v139
	v_fma_f32 v103, v67, 0.5, -v141
	v_fma_f32 v106, v66, 0.5, -v140
	v_pk_add_f32 v[66:67], v[66:67], v[78:79]
	v_pk_add_f32 v[78:79], v[50:51], v[140:141] neg_lo:[0,1] neg_hi:[0,1]
	v_fma_f32 v129, v102, 0.5, -v138
	v_fma_f32 v97, v67, 0.5, -v57
	v_fma_f32 v102, v66, 0.5, -v56
	v_pk_add_f32 v[66:67], v[66:67], v[78:79]
	v_and_b32_e32 v78, 0xffff0000, v82
	v_lshlrev_b32_e32 v79, 16, v82
	v_pk_add_f32 v[82:83], v[72:73], v[100:101] neg_lo:[0,1] neg_hi:[0,1]
	v_add_co_u32_e32 v100, vcc, s97, v48
	v_pk_add_f32 v[64:65], v[64:65], v[82:83]
	s_nop 0
	v_addc_co_u32_e32 v101, vcc, 0, v49, vcc
	v_fma_f32 v82, s68, v65, -v73
	v_fma_f32 v83, s68, v64, -v72
	v_cvt_pk_bf16_f32 v82, v82, v83
	v_cvt_pk_bf16_f32 v83, v142, v143
	global_store_dwordx2 v[100:101], v[82:83], off
	v_add_co_u32_e32 v100, vcc, s14, v48
	v_cvt_pk_bf16_f32 v82, v112, v113
	v_cvt_pk_bf16_f32 v83, v115, v124
	v_pk_add_f32 v[64:65], v[64:65], v[76:77]
	s_nop 0
	v_addc_co_u32_e32 v101, vcc, 0, v49, vcc
	global_store_dwordx2 v[100:101], v[82:83], off
	v_add_co_u32_e32 v82, vcc, s54, v48
	v_fma_f32 v76, v65, 0.5, -v47
	v_fma_f32 v77, v64, 0.5, -v46
	v_addc_co_u32_e32 v83, vcc, 0, v49, vcc
	v_cvt_pk_bf16_f32 v76, v76, v77
	v_cvt_pk_bf16_f32 v77, v134, v135
	global_store_dwordx2 v[82:83], v[76:77], off
	v_add_co_u32_e32 v82, vcc, s55, v48
	v_pk_add_f32 v[72:73], v[80:81], v[72:73] neg_lo:[0,1] neg_hi:[0,1]
	v_cvt_pk_bf16_f32 v76, v125, v126
	v_cvt_pk_bf16_f32 v77, v127, v128
	s_nop 0
; __device__ __forceinline__ unsigned cvt_pk_bf16(float lo, float hi) { unsigned r; asm volatile("v_cvt_pk_bf16_f32 %0, %1, %2" : "=v"(r) : "v"(lo), "v"(hi)); return r; }
; __device__ __forceinline__ void unpack4(const v2u q, float (&f)[4]) { f[0] = bf_lo(q.x); f[1] = bf_hi(q.x); f[2] = bf_lo(q.y); f[3] = bf_hi(q.y); }
; template <int W>
; __device__ __forceinline__ void conv_pool_chunk(const bf16* PROJ, bf16* XC, bf16* POOLED, const float* conv_w, const float* conv_b, int chunk, int ch0) {
;     ...
;             for (int q = 0; q < 8; ++q) { xnb[q] = *(const v2u*)(p + (size_t)q * NIN); pnb[q] = *(const v2u*)(p + (size_t)q * NIN + 2 * D); }
; #pragma unroll
;             for (int q = 0; q < 8; ++q) { const int rr = h8 * 8 + q; const int r = rb * 16 + rr;
;                 const v2u xn = xnb[q], pn = pnb[q];
;                 float xf[4]; unpack4(xn, xf);
;                 float a[4];
; #pragma unroll
;                 for (int j = 0; j < 4; ++j) a[j] = cb[j] + cw[0][j] * cx[(rr + 1) & 3][j] + cw[1][j] * cx[(rr + 2) & 3][j] + cw[2][j] * cx[(rr + 3) & 3][j] + cw[3][j] * xf[j];
; #pragma unroll
;                 for (int j = 0; j < 4; ++j) cx[rr & 3][j] = xf[j];
;                 { v2u o; o.x = cvt_pk_bf16(a[0], a[1]); o.y = cvt_pk_bf16(a[2], a[3]); *(v2u*)(xo + (size_t)q * D) = o; }
;                 float pf[4], of[4]; unpack4(pn, pf); unpack4(ph[rr & (W - 1)], of);
;                 ph[rr & (W - 1)] = pn;
;                 const int t = t0 + r; const int cnt = (t + 1 < W) ? (t + 1) : W; const float inv = 1.0f / (float)cnt;
; #pragma unroll
;                 for (int j = 0; j < 4; ++j) { s[j] += pf[j] - of[j]; a[j] = s[j] * inv - pf[j]; }
;                 { v2u o; o.x = cvt_pk_bf16(a[0], a[1]); o.y = cvt_pk_bf16(a[2], a[3]); *(v2u*)(po + (size_t)q * D) = o; }
;             }
;             p += 8 * NIN; xo += 8 * D; po += 8 * D;
	v_addc_co_u32_e32 v83, vcc, 0, v49, vcc
	v_pk_add_f32 v[64:65], v[64:65], v[72:73]
	global_store_dwordx2 v[82:83], v[76:77], off
	v_fma_f32 v73, v64, 0.5, -v80
	v_pk_add_f32 v[76:77], v[44:45], v[80:81] neg_lo:[0,1] neg_hi:[0,1]
	v_add_co_u32_e32 v80, vcc, s58, v48
	v_fma_f32 v72, v65, 0.5, -v81
	s_nop 0
	v_addc_co_u32_e32 v81, vcc, 0, v49, vcc
	v_cvt_pk_bf16_f32 v72, v72, v73
	v_cvt_pk_bf16_f32 v73, v132, v133
	global_store_dwordx2 v[80:81], v[72:73], off
	v_add_co_u32_e32 v80, vcc, s6, v48
	v_pk_add_f32 v[46:47], v[78:79], v[46:47] neg_lo:[0,1] neg_hi:[0,1]
	v_cvt_pk_bf16_f32 v72, v118, v120
	s_nop 0
	v_addc_co_u32_e32 v81, vcc, 0, v49, vcc
	v_pk_add_f32 v[46:47], v[64:65], v[46:47]
	v_cvt_pk_bf16_f32 v73, v122, v123
	global_store_dwordx2 v[80:81], v[72:73], off
	v_fma_f32 v72, v47, 0.5, -v79
	v_pk_add_f32 v[64:65], v[46:47], v[76:77]
	v_fma_f32 v46, v46, 0.5, -v78
	v_cvt_pk_bf16_f32 v46, v72, v46
	v_add_co_u32_e32 v72, vcc, s7, v48
	v_cvt_pk_bf16_f32 v47, v130, v131
	v_fma_f32 v76, v65, 0.5, -v45
	s_nop 0
	v_addc_co_u32_e32 v73, vcc, 0, v49, vcc
	global_store_dwordx2 v[72:73], v[46:47], off
	v_add_co_u32_e32 v72, vcc, s15, v48
	v_cvt_pk_bf16_f32 v46, v116, v117
	v_cvt_pk_bf16_f32 v47, v119, v121
	v_fma_f32 v77, v64, 0.5, -v44
	s_nop 0
	v_addc_co_u32_e32 v73, vcc, 0, v49, vcc
	global_store_dwordx2 v[72:73], v[46:47], off
	v_add_co_u32_e32 v72, vcc, s34, v48
	v_cvt_pk_bf16_f32 v46, v76, v77
	v_cvt_pk_bf16_f32 v47, v107, v129
	v_pk_add_f32 v[44:45], v[60:61], v[44:45] neg_lo:[0,1] neg_hi:[0,1]
	s_nop 0
	v_addc_co_u32_e32 v73, vcc, 0, v49, vcc
	global_store_dwordx2 v[72:73], v[46:47], off
	v_add_co_u32_e32 v72, vcc, s86, v48
	v_cvt_pk_bf16_f32 v46, v94, v95
	v_cvt_pk_bf16_f32 v47, v96, v114
	v_fma_f32 v91, v67, 0.5, -v51
	s_nop 0
	v_addc_co_u32_e32 v73, vcc, 0, v49, vcc
	global_store_dwordx2 v[72:73], v[46:47], off
	v_pk_add_f32 v[46:47], v[74:75], v[78:79] neg_lo:[0,1] neg_hi:[0,1]
	v_fma_f32 v92, v66, 0.5, -v50
	v_pk_add_f32 v[46:47], v[64:65], v[46:47]
	s_addc_u32 s41, s41, 0
	v_fma_f32 v64, v47, 0.5, -v75
	v_fma_f32 v65, v46, 0.5, -v74
	v_pk_add_f32 v[44:45], v[46:47], v[44:45]
	v_pk_add_f32 v[46:47], v[52:53], v[74:75] neg_lo:[0,1] neg_hi:[0,1]
	v_fma_f32 v73, v44, 0.5, -v60
	v_pk_add_f32 v[94:95], v[44:45], v[46:47]
	v_add_co_u32_e32 v44, vcc, s87, v48
	v_fma_f32 v72, v45, 0.5, -v61
	s_nop 0
	v_addc_co_u32_e32 v45, vcc, 0, v49, vcc
	v_add_co_u32_e32 v46, vcc, s75, v48
	v_cvt_pk_bf16_f32 v64, v64, v65
	v_cvt_pk_bf16_f32 v65, v103, v106
	global_store_dwordx2 v[44:45], v[64:65], off
	s_nop 0
	v_addc_co_u32_e32 v47, vcc, 0, v49, vcc
	v_cvt_pk_bf16_f32 v44, v88, v89
	v_cvt_pk_bf16_f32 v45, v90, v93
	global_store_dwordx2 v[46:47], v[44:45], off
	v_add_co_u32_e32 v46, vcc, s3, v48
	v_cvt_pk_bf16_f32 v44, v72, v73
	v_cvt_pk_bf16_f32 v45, v97, v102
	v_fma_f32 v74, v95, 0.5, -v53
	s_nop 0
	v_addc_co_u32_e32 v47, vcc, 0, v49, vcc
	global_store_dwordx2 v[46:47], v[44:45], off
	v_add_co_u32_e32 v46, vcc, s33, v48
	v_cvt_pk_bf16_f32 v44, v86, v84
	v_cvt_pk_bf16_f32 v45, v87, v85
	v_fma_f32 v75, v94, 0.5, -v52
	s_nop 0
	v_addc_co_u32_e32 v47, vcc, 0, v49, vcc
	global_store_dwordx2 v[46:47], v[44:45], off
	v_add_co_u32_e32 v46, vcc, s70, v48
	v_cvt_pk_bf16_f32 v44, v74, v75
	v_cvt_pk_bf16_f32 v45, v91, v92
	s_cmp_eq_u32 s17, 4
	s_nop 0
	v_addc_co_u32_e32 v47, vcc, 0, v49, vcc
	global_store_dwordx2 v[46:47], v[44:45], off
	v_add_co_u32_e32 v44, vcc, s88, v68
	s_nop 1
	v_addc_co_u32_e32 v45, vcc, 0, v69, vcc
	global_load_dwordx2 v[106:107], v[44:45], off nt
	v_add_co_u32_e32 v44, vcc, s89, v68
	s_nop 1
	v_addc_co_u32_e32 v45, vcc, 0, v69, vcc
	global_load_dwordx2 v[96:97], v[44:45], off nt
	v_add_co_u32_e32 v44, vcc, s11, v68
	s_waitcnt vmcnt(0)
	v_lshlrev_b32_e32 v93, 16, v96
	v_addc_co_u32_e32 v45, vcc, 0, v69, vcc
	global_load_dwordx2 v[112:113], v[44:45], off nt
	v_add_co_u32_e32 v44, vcc, s35, v68
	v_and_b32_e32 v92, 0xffff0000, v96
	s_nop 0
	v_addc_co_u32_e32 v45, vcc, 0, v69, vcc
	global_load_dwordx2 v[90:91], v[44:45], off nt
	v_add_co_u32_e32 v44, vcc, s78, v68
	v_pk_add_f32 v[60:61], v[92:93], v[60:61] neg_lo:[0,1] neg_hi:[0,1]
	s_nop 0
	v_addc_co_u32_e32 v45, vcc, 0, v69, vcc
	global_load_dwordx2 v[84:85], v[44:45], off nt
	v_add_co_u32_e32 v44, vcc, s79, v68
	v_lshlrev_b32_e32 v96, 16, v106
	s_nop 0
	v_addc_co_u32_e32 v45, vcc, 0, v69, vcc
	global_load_dwordx2 v[88:89], v[44:45], off nt
	v_add_co_u32_e32 v44, vcc, s82, v68
	v_pk_add_f32 v[100:101], v[94:95], v[60:61]
	s_nop 0
	v_addc_co_u32_e32 v45, vcc, 0, v69, vcc
	global_load_dwordx2 v[86:87], v[44:45], off nt
	v_add_co_u32_e32 v44, vcc, s83, v68
	v_and_b32_e32 v94, 0xffff0000, v107
	s_nop 0
	v_addc_co_u32_e32 v45, vcc, 0, v69, vcc
	global_load_dwordx2 v[82:83], v[44:45], off nt
	v_add_co_u32_e32 v44, vcc, s28, v68
	v_fma_f32 v114, v101, 0.5, -v93
	s_nop 0
	v_addc_co_u32_e32 v45, vcc, 0, v69, vcc
	global_load_dwordx2 v[80:81], v[44:45], off nt
	v_add_co_u32_e32 v44, vcc, s29, v68
	v_fma_f32 v115, v100, 0.5, -v92
	s_nop 0
	v_addc_co_u32_e32 v45, vcc, 0, v69, vcc
	global_load_dwordx2 v[78:79], v[44:45], off nt
	v_add_co_u32_e32 v44, vcc, s10, v68
	s_waitcnt vmcnt(0)
; __device__ __forceinline__ unsigned cvt_pk_bf16(float lo, float hi) { unsigned r; asm volatile("v_cvt_pk_bf16_f32 %0, %1, %2" : "=v"(r) : "v"(lo), "v"(hi)); return r; }
; __device__ __forceinline__ void unpack4(const v2u q, float (&f)[4]) { f[0] = bf_lo(q.x); f[1] = bf_hi(q.x); f[2] = bf_lo(q.y); f[3] = bf_hi(q.y); }
; template <int W>
; __device__ __forceinline__ void conv_pool_chunk(const bf16* PROJ, bf16* XC, bf16* POOLED, const float* conv_w, const float* conv_b, int chunk, int ch0) {
;     ...
;             for (int q = 0; q < 8; ++q) { xnb[q] = *(const v2u*)(p + (size_t)q * NIN); pnb[q] = *(const v2u*)(p + (size_t)q * NIN + 2 * D); }
; #pragma unroll
;             for (int q = 0; q < 8; ++q) { const int rr = h8 * 8 + q; const int r = rb * 16 + rr;
;                 const v2u xn = xnb[q], pn = pnb[q];
;                 float xf[4]; unpack4(xn, xf);
;                 float a[4];
; #pragma unroll
;                 for (int j = 0; j < 4; ++j) a[j] = cb[j] + cw[0][j] * cx[(rr + 1) & 3][j] + cw[1][j] * cx[(rr + 2) & 3][j] + cw[2][j] * cx[(rr + 3) & 3][j] + cw[3][j] * xf[j];
; #pragma unroll
;                 for (int j = 0; j < 4; ++j) cx[rr & 3][j] = xf[j];
;                 { v2u o; o.x = cvt_pk_bf16(a[0], a[1]); o.y = cvt_pk_bf16(a[2], a[3]); *(v2u*)(xo + (size_t)q * D) = o; }
;                 float pf[4], of[4]; unpack4(pn, pf); unpack4(ph[rr & (W - 1)], of);
;                 ph[rr & (W - 1)] = pn;
;                 const int t = t0 + r; const int cnt = (t + 1 < W) ? (t + 1) : W; const float inv = 1.0f / (float)cnt;
; #pragma unroll
;                 for (int j = 0; j < 4; ++j) { s[j] += pf[j] - of[j]; a[j] = s[j] * inv - pf[j]; }
;                 { v2u o; o.x = cvt_pk_bf16(a[0], a[1]); o.y = cvt_pk_bf16(a[2], a[3]); *(v2u*)(po + (size_t)q * D) = o; }
	v_and_b32_e32 v95, 0xffff0000, v113
	v_addc_co_u32_e32 v45, vcc, 0, v69, vcc
	global_load_dwordx2 v[64:65], v[44:45], off nt
	v_add_co_u32_e32 v44, vcc, s72, v68
	v_pk_mov_b32 v[70:71], v[70:71], v[94:95] op_sel:[1,0]
	s_nop 0
	v_addc_co_u32_e32 v45, vcc, 0, v69, vcc
	global_load_dwordx2 v[76:77], v[44:45], off nt
	v_add_co_u32_e32 v44, vcc, s73, v68
	s_nop 1
	v_addc_co_u32_e32 v45, vcc, 0, v69, vcc
	global_load_dwordx2 v[74:75], v[44:45], off nt
	v_add_co_u32_e32 v44, vcc, s59, v68
	s_nop 1
	v_addc_co_u32_e32 v45, vcc, 0, v69, vcc
	global_load_dwordx2 v[46:47], v[44:45], off nt
	v_add_co_u32_e32 v44, vcc, s62, v68
	s_nop 1
	v_addc_co_u32_e32 v45, vcc, 0, v69, vcc
	global_load_dwordx2 v[72:73], v[44:45], off nt
	v_add_co_u32_e32 v44, vcc, s63, v68
	v_and_b32_e32 v68, 0xffff0000, v97
	s_nop 0
	v_addc_co_u32_e32 v45, vcc, 0, v69, vcc
	v_lshlrev_b32_e32 v69, 16, v97
	v_lshlrev_b32_e32 v97, 16, v112
	v_pk_mov_b32 v[60:61], v[54:55], v[96:97] op_sel:[1,0]
	v_pk_add_f32 v[56:57], v[68:69], v[56:57] neg_lo:[0,1] neg_hi:[0,1]
	v_pk_mul_f32 v[54:55], v[34:35], v[60:61]
	v_pk_add_f32 v[102:103], v[66:67], v[56:57]
	v_add_f32_e32 v54, v99, v54
	v_add_f32_e32 v66, v54, v55
	v_pk_mul_f32 v[54:55], v[34:35], v[96:97]
	global_load_dwordx2 v[44:45], v[44:45], off nt
	v_add_f32_e32 v54, v111, v54
	v_add_f32_e32 v111, v54, v55
	v_and_b32_e32 v55, 0xffff0000, v112
	v_and_b32_e32 v54, 0xffff0000, v106
	v_pk_mov_b32 v[58:59], v[58:59], v[54:55] op_sel:[1,0]
	v_fma_f32 v116, v103, 0.5, -v69
	v_pk_mul_f32 v[56:57], v[36:37], v[58:59]
	v_fma_f32 v117, v102, 0.5, -v68
	v_add_f32_e32 v56, v98, v56
	v_add_f32_e32 v56, v56, v57
	v_cvt_pk_bf16_f32 v66, v66, v56
	v_pk_mul_f32 v[56:57], v[36:37], v[54:55]
	v_pk_mul_f32 v[58:59], v[40:41], v[58:59]
	v_add_f32_e32 v56, v110, v56
	v_add_f32_e32 v106, v56, v57
	v_lshlrev_b32_e32 v57, 16, v113
	v_lshlrev_b32_e32 v56, 16, v107
	v_pk_mov_b32 v[98:99], v[62:63], v[56:57] op_sel:[1,0]
	v_add_f32_e32 v58, v15, v58
	v_pk_mul_f32 v[62:63], v[26:27], v[98:99]
	v_pk_mul_f32 v[60:61], v[42:43], v[60:61]
	v_add_f32_e32 v62, v108, v62
	v_add_f32_e32 v67, v62, v63
	v_pk_mul_f32 v[62:63], v[26:27], v[56:57]
	v_add_f32_e32 v60, v14, v60
	v_add_f32_e32 v62, v109, v62
	v_add_f32_e32 v108, v62, v63
	v_pk_mul_f32 v[62:63], v[28:29], v[70:71]
	s_nop 0
	v_add_f32_e32 v62, v105, v62
	v_add_f32_e32 v62, v62, v63
	v_cvt_pk_bf16_f32 v67, v67, v62
	v_add_co_u32_e32 v62, vcc, s18, v48
	s_nop 1
	v_addc_co_u32_e32 v63, vcc, 0, v49, vcc
	global_store_dwordx2 v[62:63], v[66:67], off
	v_add_co_u32_e32 v66, vcc, s19, v48
	v_cvt_pk_bf16_f32 v62, v114, v115
	v_cvt_pk_bf16_f32 v63, v116, v117
	s_nop 1
	v_addc_co_u32_e32 v67, vcc, 0, v49, vcc
	global_store_dwordx2 v[66:67], v[62:63], off
	v_pk_mul_f32 v[62:63], v[28:29], v[94:95]
	v_add_co_u32_e32 v66, vcc, s20, v48
	v_add_f32_e32 v62, v104, v62
	v_add_f32_e32 v63, v62, v63
	v_cvt_pk_bf16_f32 v62, v111, v106
	v_cvt_pk_bf16_f32 v63, v108, v63
	v_addc_co_u32_e32 v67, vcc, 0, v49, vcc
	global_store_dwordx2 v[66:67], v[62:63], off
	v_and_b32_e32 v66, 0xffff0000, v90
	v_lshlrev_b32_e32 v67, 16, v90
	v_and_b32_e32 v62, 0xffff0000, v91
	v_lshlrev_b32_e32 v63, 16, v91
	v_pk_add_f32 v[52:53], v[66:67], v[52:53] neg_lo:[0,1] neg_hi:[0,1]
	v_pk_add_f32 v[50:51], v[62:63], v[50:51] neg_lo:[0,1] neg_hi:[0,1]
	v_pk_add_f32 v[52:53], v[100:101], v[52:53]
	v_pk_add_f32 v[50:51], v[102:103], v[50:51]
	v_fma_f32 v90, v53, 0.5, -v67
	v_fma_f32 v91, v52, 0.5, -v66
	v_fma_f32 v100, v51, 0.5, -v63
	v_fma_f32 v101, v50, 0.5, -v62
	v_cvt_pk_bf16_f32 v90, v90, v91
	v_cvt_pk_bf16_f32 v91, v100, v101
	v_add_co_u32_e32 v100, vcc, s21, v48
	s_nop 1
	v_addc_co_u32_e32 v101, vcc, 0, v49, vcc
	global_store_dwordx2 v[100:101], v[90:91], off
	v_add_f32_e32 v101, v58, v59
	v_pk_mul_f32 v[58:59], v[30:31], v[98:99]
	v_add_f32_e32 v100, v60, v61
	v_add_f32_e32 v58, v16, v58
	v_add_f32_e32 v98, v58, v59
	v_pk_mul_f32 v[58:59], v[32:33], v[70:71]
	v_and_b32_e32 v60, 0xffff0000, v88
	v_add_f32_e32 v58, v17, v58
	v_lshlrev_b32_e32 v61, 16, v88
	v_add_f32_e32 v99, v58, v59
	v_and_b32_e32 v58, 0xffff0000, v89
	v_lshlrev_b32_e32 v59, 16, v89
	v_pk_add_f32 v[70:71], v[60:61], v[92:93] neg_lo:[0,1] neg_hi:[0,1]
	s_nop 0
	v_pk_add_f32 v[90:91], v[52:53], v[70:71]
	v_pk_add_f32 v[52:53], v[58:59], v[68:69] neg_lo:[0,1] neg_hi:[0,1]
	v_fma_f32 v102, v91, 0.5, -v61
	v_pk_add_f32 v[92:93], v[50:51], v[52:53]
	v_pk_mul_f32 v[50:51], v[42:43], v[96:97]
	v_fma_f32 v103, v90, 0.5, -v60
	v_add_f32_e32 v50, v14, v50
	v_add_f32_e32 v70, v50, v51
	v_lshlrev_b32_e32 v50, 16, v84
	v_lshlrev_b32_e32 v51, 16, v86
	v_pk_mov_b32 v[68:69], v[96:97], v[50:51] op_sel:[1,0]
	v_fma_f32 v104, v93, 0.5, -v59
	v_pk_mul_f32 v[52:53], v[34:35], v[68:69]
	v_fma_f32 v105, v92, 0.5, -v58
	v_add_f32_e32 v52, v100, v52
	v_add_f32_e32 v88, v52, v53
	v_pk_mul_f32 v[52:53], v[34:35], v[50:51]
	v_pk_mul_f32 v[68:69], v[42:43], v[68:69]
	v_add_f32_e32 v52, v70, v52
	v_add_f32_e32 v96, v52, v53
	v_pk_mul_f32 v[52:53], v[40:41], v[54:55]
	s_nop 0
	v_add_f32_e32 v52, v15, v52
	v_add_f32_e32 v89, v52, v53
	v_and_b32_e32 v53, 0xffff0000, v86
	v_and_b32_e32 v52, 0xffff0000, v84
	v_pk_mov_b32 v[70:71], v[54:55], v[52:53] op_sel:[1,0]
	s_nop 0
	v_pk_mul_f32 v[54:55], v[36:37], v[70:71]
	s_nop 0
	v_add_f32_e32 v54, v101, v54
	v_add_f32_e32 v54, v54, v55
	v_cvt_pk_bf16_f32 v86, v88, v54
	v_pk_mul_f32 v[54:55], v[36:37], v[52:53]
	s_nop 0
	v_add_f32_e32 v54, v89, v54
	v_add_f32_e32 v97, v54, v55
	v_pk_mul_f32 v[54:55], v[30:31], v[56:57]
	s_nop 0
	v_add_f32_e32 v54, v16, v54
	v_add_f32_e32 v84, v54, v55
	v_lshlrev_b32_e32 v54, 16, v85
	v_lshlrev_b32_e32 v55, 16, v87
	v_pk_mov_b32 v[88:89], v[56:57], v[54:55] op_sel:[1,0]
; __device__ __forceinline__ unsigned cvt_pk_bf16(float lo, float hi) { unsigned r; asm volatile("v_cvt_pk_bf16_f32 %0, %1, %2" : "=v"(r) : "v"(lo), "v"(hi)); return r; }
; __device__ __forceinline__ void unpack4(const v2u q, float (&f)[4]) { f[0] = bf_lo(q.x); f[1] = bf_hi(q.x); f[2] = bf_lo(q.y); f[3] = bf_hi(q.y); }
; template <int W>
; __device__ __forceinline__ void conv_pool_chunk(const bf16* PROJ, bf16* XC, bf16* POOLED, const float* conv_w, const float* conv_b, int chunk, int ch0) {
;     ...
;             for (int q = 0; q < 8; ++q) { const int rr = h8 * 8 + q; const int r = rb * 16 + rr;
;                 const v2u xn = xnb[q], pn = pnb[q];
;                 float xf[4]; unpack4(xn, xf);
;                 float a[4];
; #pragma unroll
;                 for (int j = 0; j < 4; ++j) a[j] = cb[j] + cw[0][j] * cx[(rr + 1) & 3][j] + cw[1][j] * cx[(rr + 2) & 3][j] + cw[2][j] * cx[(rr + 3) & 3][j] + cw[3][j] * xf[j];
; #pragma unroll
;                 for (int j = 0; j < 4; ++j) cx[rr & 3][j] = xf[j];
;                 { v2u o; o.x = cvt_pk_bf16(a[0], a[1]); o.y = cvt_pk_bf16(a[2], a[3]); *(v2u*)(xo + (size_t)q * D) = o; }
;                 float pf[4], of[4]; unpack4(pn, pf); unpack4(ph[rr & (W - 1)], of);
;                 ph[rr & (W - 1)] = pn;
;                 const int t = t0 + r; const int cnt = (t + 1 < W) ? (t + 1) : W; const float inv = 1.0f / (float)cnt;
; #pragma unroll
;                 for (int j = 0; j < 4; ++j) { s[j] += pf[j] - of[j]; a[j] = s[j] * inv - pf[j]; }
;                 { v2u o; o.x = cvt_pk_bf16(a[0], a[1]); o.y = cvt_pk_bf16(a[2], a[3]); *(v2u*)(po + (size_t)q * D) = o; }
	s_nop 0
	v_pk_mul_f32 v[56:57], v[26:27], v[88:89]
	s_nop 0
	v_add_f32_e32 v56, v98, v56
	v_add_f32_e32 v98, v56, v57
	v_pk_mul_f32 v[56:57], v[26:27], v[54:55]
	s_nop 0
	v_add_f32_e32 v56, v84, v56
	v_add_f32_e32 v100, v56, v57
	v_pk_mul_f32 v[56:57], v[32:33], v[94:95]
	s_nop 0
	v_add_f32_e32 v56, v17, v56
	v_add_f32_e32 v101, v56, v57
	v_and_b32_e32 v57, 0xffff0000, v87
	v_and_b32_e32 v56, 0xffff0000, v85
	v_pk_mov_b32 v[84:85], v[94:95], v[56:57] op_sel:[1,0]
	s_nop 0
	v_pk_mul_f32 v[94:95], v[28:29], v[84:85]
	s_nop 0
	v_add_f32_e32 v87, v99, v94
	v_add_co_u32_e32 v94, vcc, s22, v48
	v_add_f32_e32 v87, v87, v95
	s_nop 0
	v_addc_co_u32_e32 v95, vcc, 0, v49, vcc
	v_cvt_pk_bf16_f32 v87, v98, v87
	global_store_dwordx2 v[94:95], v[86:87], off
	v_add_co_u32_e32 v94, vcc, s23, v48
	v_cvt_pk_bf16_f32 v86, v102, v103
	v_cvt_pk_bf16_f32 v87, v104, v105
	v_and_b32_e32 v98, 0xffff0000, v78
	s_nop 0
	v_addc_co_u32_e32 v95, vcc, 0, v49, vcc
	global_store_dwordx2 v[94:95], v[86:87], off
	v_pk_mul_f32 v[86:87], v[28:29], v[56:57]
	v_add_co_u32_e32 v94, vcc, s24, v48
	v_add_f32_e32 v86, v101, v86
	v_add_f32_e32 v87, v86, v87
	v_cvt_pk_bf16_f32 v86, v96, v97
	v_cvt_pk_bf16_f32 v87, v100, v87
	v_addc_co_u32_e32 v95, vcc, 0, v49, vcc
	global_store_dwordx2 v[94:95], v[86:87], off
	v_and_b32_e32 v86, 0xffff0000, v82
	v_lshlrev_b32_e32 v87, 16, v82
	v_pk_add_f32 v[66:67], v[86:87], v[66:67] neg_lo:[0,1] neg_hi:[0,1]
	v_and_b32_e32 v82, 0xffff0000, v83
	v_lshlrev_b32_e32 v83, 16, v83
	v_pk_add_f32 v[66:67], v[90:91], v[66:67]
	v_pk_add_f32 v[62:63], v[82:83], v[62:63] neg_lo:[0,1] neg_hi:[0,1]
	v_fma_f32 v90, v67, 0.5, -v87
	v_fma_f32 v91, v66, 0.5, -v86
	v_pk_add_f32 v[96:97], v[92:93], v[62:63]
	v_cvt_pk_bf16_f32 v62, v90, v91
	v_add_co_u32_e32 v90, vcc, s25, v48
	v_fma_f32 v63, v97, 0.5, -v83
	s_nop 0
	v_addc_co_u32_e32 v91, vcc, 0, v49, vcc
	v_fma_f32 v92, v96, 0.5, -v82
	v_cvt_pk_bf16_f32 v63, v63, v92
	global_store_dwordx2 v[90:91], v[62:63], off
	v_lshlrev_b32_e32 v91, 16, v80
	v_add_f32_e32 v62, v14, v68
	v_mov_b32_e32 v90, v51
	v_add_f32_e32 v62, v62, v69
	v_pk_mul_f32 v[68:69], v[34:35], v[90:91]
	v_and_b32_e32 v95, 0xffff0000, v80
	v_add_f32_e32 v62, v62, v68
	v_add_f32_e32 v80, v62, v69
	v_pk_mul_f32 v[68:69], v[40:41], v[70:71]
	v_mov_b32_e32 v94, v53
	v_add_f32_e32 v62, v15, v68
	v_add_f32_e32 v62, v62, v69
	v_pk_mul_f32 v[68:69], v[36:37], v[94:95]
	v_lshlrev_b32_e32 v93, 16, v81
	v_add_f32_e32 v62, v62, v68
	v_add_f32_e32 v70, v62, v69
	v_pk_mul_f32 v[68:69], v[30:31], v[88:89]
	v_mov_b32_e32 v92, v55
	v_add_f32_e32 v62, v16, v68
	v_add_f32_e32 v62, v62, v69
	v_pk_mul_f32 v[68:69], v[26:27], v[92:93]
	v_and_b32_e32 v63, 0xffff0000, v81
	v_add_f32_e32 v62, v62, v68
	v_add_f32_e32 v71, v62, v69
	v_pk_mul_f32 v[68:69], v[32:33], v[84:85]
	v_lshlrev_b32_e32 v99, 16, v78
	v_add_f32_e32 v62, v17, v68
	v_add_f32_e32 v81, v62, v69
	v_mov_b32_e32 v62, v57
	v_pk_mul_f32 v[68:69], v[28:29], v[62:63]
	v_and_b32_e32 v100, 0xffff0000, v79
	v_add_f32_e32 v68, v81, v68
	v_lshlrev_b32_e32 v101, 16, v79
	v_add_f32_e32 v69, v68, v69
	v_cvt_pk_bf16_f32 v68, v80, v70
	v_add_co_u32_e32 v70, vcc, s26, v48
	v_pk_add_f32 v[60:61], v[98:99], v[60:61] neg_lo:[0,1] neg_hi:[0,1]
	v_pk_add_f32 v[58:59], v[100:101], v[58:59] neg_lo:[0,1] neg_hi:[0,1]
	v_cvt_pk_bf16_f32 v69, v71, v69
	v_addc_co_u32_e32 v71, vcc, 0, v49, vcc
	v_pk_add_f32 v[60:61], v[66:67], v[60:61]
	v_pk_add_f32 v[58:59], v[96:97], v[58:59]
	global_store_dwordx2 v[70:71], v[68:69], off
	v_fma_f32 v66, v61, 0.5, -v99
	v_fma_f32 v67, v60, 0.5, -v98
	v_fma_f32 v68, v59, 0.5, -v101
	v_fma_f32 v69, v58, 0.5, -v100
	v_cvt_pk_bf16_f32 v66, v66, v67
	v_cvt_pk_bf16_f32 v67, v68, v69
	v_add_co_u32_e32 v68, vcc, s27, v48
	v_pk_mul_f32 v[50:51], v[42:43], v[50:51]
	s_nop 0
	v_addc_co_u32_e32 v69, vcc, 0, v49, vcc
	v_add_f32_e32 v50, v14, v50
	global_store_dwordx2 v[68:69], v[66:67], off
	v_add_f32_e32 v68, v50, v51
	v_pk_mul_f32 v[50:51], v[40:41], v[52:53]
	s_waitcnt vmcnt(0)
	v_and_b32_e32 v70, 0xffff0000, v76
	v_add_f32_e32 v50, v15, v50
	v_add_f32_e32 v52, v50, v51
	v_pk_mul_f32 v[50:51], v[30:31], v[54:55]
	v_lshlrev_b32_e32 v71, 16, v76
	v_add_f32_e32 v50, v16, v50
	v_add_f32_e32 v53, v50, v51
	v_pk_mul_f32 v[50:51], v[32:33], v[56:57]
	v_and_b32_e32 v66, 0xffff0000, v77
	v_add_f32_e32 v50, v17, v50
	v_add_f32_e32 v85, v50, v51
	v_lshlrev_b32_e32 v67, 16, v77
	v_pk_add_f32 v[50:51], v[70:71], v[86:87] neg_lo:[0,1] neg_hi:[0,1]
	v_mov_b32_e32 v78, v95
	v_pk_add_f32 v[76:77], v[60:61], v[50:51]
	v_pk_add_f32 v[50:51], v[66:67], v[82:83] neg_lo:[0,1] neg_hi:[0,1]
	v_and_b32_e32 v61, 0xffff0000, v74
	v_pk_add_f32 v[96:97], v[58:59], v[50:51]
	v_pk_mul_f32 v[50:51], v[42:43], v[90:91]
	v_and_b32_e32 v60, 0xffff0000, v64
	v_add_f32_e32 v50, v14, v50
	v_add_f32_e32 v84, v50, v51
	v_pk_mul_f32 v[50:51], v[40:41], v[94:95]
	v_pk_mov_b32 v[58:59], v[60:61], v[60:61] op_sel:[1,0]
	v_add_f32_e32 v50, v15, v50
	v_mov_b32_e32 v79, v59
	v_add_f32_e32 v54, v50, v51
	v_pk_mul_f32 v[50:51], v[36:37], v[78:79]
	v_lshlrev_b32_e32 v57, 16, v75
	v_add_f32_e32 v50, v52, v50
	v_add_f32_e32 v94, v50, v51
	v_pk_mul_f32 v[50:51], v[36:37], v[60:61]
	v_lshlrev_b32_e32 v56, 16, v65
	v_add_f32_e32 v50, v54, v50
	v_add_f32_e32 v89, v50, v51
	v_pk_mul_f32 v[50:51], v[30:31], v[92:93]
	v_pk_mov_b32 v[54:55], v[56:57], v[56:57] op_sel:[1,0]
	v_add_f32_e32 v50, v16, v50
	v_mov_b32_e32 v80, v93
	v_mov_b32_e32 v81, v55
	v_add_f32_e32 v52, v50, v51
	v_pk_mul_f32 v[50:51], v[26:27], v[80:81]
	v_mov_b32_e32 v82, v63
	v_add_f32_e32 v50, v53, v50
	v_add_f32_e32 v95, v50, v51
	v_pk_mul_f32 v[50:51], v[26:27], v[56:57]
	v_and_b32_e32 v53, 0xffff0000, v75
; __device__ __forceinline__ unsigned cvt_pk_bf16(float lo, float hi) { unsigned r; asm volatile("v_cvt_pk_bf16_f32 %0, %1, %2" : "=v"(r) : "v"(lo), "v"(hi)); return r; }
; __device__ __forceinline__ void unpack4(const v2u q, float (&f)[4]) { f[0] = bf_lo(q.x); f[1] = bf_hi(q.x); f[2] = bf_lo(q.y); f[3] = bf_hi(q.y); }
; template <int W>
; __device__ __forceinline__ void conv_pool_chunk(const bf16* PROJ, bf16* XC, bf16* POOLED, const float* conv_w, const float* conv_b, int chunk, int ch0) {
;     ...
;     if (t0 > 0) {
; #pragma unroll
;         for (int q = 1; q <= 3; ++q) { const v2u x = *(const v2u*)(pr - (ptrdiff_t)q * NIN); unpack4(x, cx[(64 - q) & 3]); }
; #pragma unroll
;         for (int q = 1; q < W; ++q) { const v2u x = *(const v2u*)(pr + 2 * D - (ptrdiff_t)q * NIN); ph[(64 - q) & (W - 1)] = x; float f[4]; unpack4(x, f);
; #pragma unroll
;             for (int j = 0; j < 4; ++j) s[j] += f[j]; }
;     }
;     ...
;             for (int q = 0; q < 8; ++q) { const int rr = h8 * 8 + q; const int r = rb * 16 + rr;
;                 const v2u xn = xnb[q], pn = pnb[q];
;                 float xf[4]; unpack4(xn, xf);
;                 float a[4];
; #pragma unroll
;                 for (int j = 0; j < 4; ++j) a[j] = cb[j] + cw[0][j] * cx[(rr + 1) & 3][j] + cw[1][j] * cx[(rr + 2) & 3][j] + cw[2][j] * cx[(rr + 3) & 3][j] + cw[3][j] * xf[j];
; #pragma unroll
;                 for (int j = 0; j < 4; ++j) cx[rr & 3][j] = xf[j];
;                 { v2u o; o.x = cvt_pk_bf16(a[0], a[1]); o.y = cvt_pk_bf16(a[2], a[3]); *(v2u*)(xo + (size_t)q * D) = o; }
;                 float pf[4], of[4]; unpack4(pn, pf); unpack4(ph[rr & (W - 1)], of);
;                 ph[rr & (W - 1)] = pn;
;                 const int t = t0 + r; const int cnt = (t + 1 < W) ? (t + 1) : W; const float inv = 1.0f / (float)cnt;
; #pragma unroll
;                 for (int j = 0; j < 4; ++j) { s[j] += pf[j] - of[j]; a[j] = s[j] * inv - pf[j]; }
;                 { v2u o; o.x = cvt_pk_bf16(a[0], a[1]); o.y = cvt_pk_bf16(a[2], a[3]); *(v2u*)(po + (size_t)q * D) = o; }
;             }
;             p += 8 * NIN; xo += 8 * D; po += 8 * D;
	v_add_f32_e32 v50, v52, v50
	v_add_f32_e32 v90, v50, v51
	v_pk_mul_f32 v[50:51], v[32:33], v[62:63]
	v_and_b32_e32 v52, 0xffff0000, v65
	v_add_f32_e32 v50, v17, v50
	v_add_f32_e32 v55, v50, v51
	v_pk_mov_b32 v[50:51], v[52:53], v[52:53] op_sel:[1,0]
	v_lshlrev_b32_e32 v69, 16, v74
	v_mov_b32_e32 v83, v51
	v_pk_mul_f32 v[62:63], v[28:29], v[82:83]
	v_and_b32_e32 v92, 0xffff0000, v47
	v_add_f32_e32 v51, v85, v62
	v_add_f32_e32 v106, v51, v63
	v_pk_mul_f32 v[62:63], v[28:29], v[52:53]
	v_lshlrev_b32_e32 v93, 16, v47
	v_add_f32_e32 v51, v55, v62
	v_add_f32_e32 v107, v51, v63
	v_and_b32_e32 v62, 0xffff0000, v46
	v_lshlrev_b32_e32 v63, 16, v46
	v_pk_add_f32 v[74:75], v[62:63], v[98:99] neg_lo:[0,1] neg_hi:[0,1]
	v_fma_f32 v102, v77, 0.5, -v71
	v_pk_add_f32 v[74:75], v[76:77], v[74:75]
	v_fma_f32 v103, v76, 0.5, -v70
	v_fma_f32 v85, v75, 0.5, -v63
	v_fma_f32 v86, v74, 0.5, -v62
	v_pk_add_f32 v[62:63], v[92:93], v[100:101] neg_lo:[0,1] neg_hi:[0,1]
	v_and_b32_e32 v59, 0xffff0000, v72
	v_pk_add_f32 v[76:77], v[96:97], v[62:63]
	v_lshlrev_b32_e32 v62, 16, v64
	v_mov_b32_e32 v64, v91
	v_mov_b32_e32 v65, v62
	v_fma_f32 v88, v76, 0.5, -v92
	v_lshlrev_b32_e32 v55, 16, v73
	v_and_b32_e32 v51, 0xffff0000, v73
	v_lshlrev_b32_e32 v63, 16, v72
	v_pk_mul_f32 v[72:73], v[34:35], v[64:65]
	v_add_co_u32_e32 v92, vcc, s12, v48
	v_fma_f32 v87, v77, 0.5, -v93
	v_add_f32_e32 v68, v68, v72
	v_addc_co_u32_e32 v93, vcc, 0, v49, vcc
	v_add_f32_e32 v68, v68, v73
	v_cvt_pk_bf16_f32 v72, v68, v94
	v_cvt_pk_bf16_f32 v73, v95, v106
	global_store_dwordx2 v[92:93], v[72:73], off
	v_add_co_u32_e32 v92, vcc, s13, v48
	v_fma_f32 v104, v97, 0.5, -v67
	v_fma_f32 v105, v96, 0.5, -v66
	v_cvt_pk_bf16_f32 v72, v102, v103
	v_cvt_pk_bf16_f32 v73, v104, v105
	v_addc_co_u32_e32 v93, vcc, 0, v49, vcc
	v_mov_b32_e32 v68, v62
	global_store_dwordx2 v[92:93], v[72:73], off
	v_pk_mul_f32 v[72:73], v[34:35], v[68:69]
	v_pk_mul_f32 v[64:65], v[42:43], v[64:65]
	v_add_f32_e32 v68, v84, v72
	v_add_f32_e32 v68, v68, v73
	v_add_f32_e32 v64, v14, v64
	v_cvt_pk_bf16_f32 v72, v68, v89
	v_add_f32_e32 v68, v64, v65
	v_mov_b32_e32 v64, v69
	v_mov_b32_e32 v65, v63
	v_cvt_pk_bf16_f32 v73, v90, v107
	v_add_co_u32_e32 v90, vcc, s74, v48
	v_pk_mul_f32 v[64:65], v[34:35], v[64:65]
	s_nop 0
	v_addc_co_u32_e32 v91, vcc, 0, v49, vcc
	v_add_f32_e32 v64, v68, v64
	v_add_co_u32_e32 v84, vcc, s84, v48
	v_add_f32_e32 v68, v64, v65
	v_pk_mul_f32 v[64:65], v[40:41], v[78:79]
	global_store_dwordx2 v[90:91], v[72:73], off
	v_cvt_pk_bf16_f32 v72, v85, v86
	v_addc_co_u32_e32 v85, vcc, 0, v49, vcc
	v_add_f32_e32 v64, v15, v64
	v_cvt_pk_bf16_f32 v73, v87, v88
	global_store_dwordx2 v[84:85], v[72:73], off
	v_add_f32_e32 v72, v64, v65
	v_pk_mul_f32 v[64:65], v[36:37], v[58:59]
	v_and_b32_e32 v78, 0xffff0000, v45
	v_add_f32_e32 v58, v72, v64
	v_add_f32_e32 v58, v58, v65
	v_pk_mul_f32 v[64:65], v[30:31], v[80:81]
	v_lshlrev_b32_e32 v79, 16, v45
	v_add_f32_e32 v64, v16, v64
	v_add_f32_e32 v72, v64, v65
	v_pk_mul_f32 v[64:65], v[26:27], v[54:55]
	v_pk_add_f32 v[66:67], v[78:79], v[66:67] neg_lo:[0,1] neg_hi:[0,1]
	v_add_f32_e32 v54, v72, v64
	v_add_f32_e32 v54, v54, v65
	v_pk_mul_f32 v[64:65], v[32:33], v[82:83]
	v_pk_add_f32 v[66:67], v[76:77], v[66:67]
	v_add_f32_e32 v64, v17, v64
	v_add_f32_e32 v72, v64, v65
	v_pk_mul_f32 v[64:65], v[28:29], v[50:51]
	v_mov_b32_e32 v108, v69
	v_add_f32_e32 v50, v72, v64
	v_add_co_u32_e32 v72, vcc, s85, v48
	v_add_f32_e32 v50, v50, v65
	s_nop 0
	v_addc_co_u32_e32 v73, vcc, 0, v49, vcc
	v_cvt_pk_bf16_f32 v64, v68, v58
	v_cvt_pk_bf16_f32 v65, v54, v50
	global_store_dwordx2 v[72:73], v[64:65], off
	v_and_b32_e32 v72, 0xffff0000, v44
	v_lshlrev_b32_e32 v73, 16, v44
	v_pk_add_f32 v[64:65], v[72:73], v[70:71] neg_lo:[0,1] neg_hi:[0,1]
	v_add_co_u32_e32 v48, vcc, s77, v48
	v_pk_add_f32 v[64:65], v[74:75], v[64:65]
	s_nop 0
	v_addc_co_u32_e32 v49, vcc, 0, v49, vcc
	v_fma_f32 v50, v65, 0.5, -v73
	v_fma_f32 v54, v64, 0.5, -v72
	v_fma_f32 v58, v67, 0.5, -v79
	v_fma_f32 v68, v66, 0.5, -v78
	v_cvt_pk_bf16_f32 v70, v50, v54
	v_cvt_pk_bf16_f32 v71, v58, v68
	global_store_dwordx2 v[48:49], v[70:71], off
	s_cbranch_scc0 .LBB0_361
	s_mov_b64 s[0:1], 0
.LBB0_363:
	s_and_b64 vcc, exec, s[0:1]
	s_cbranch_vccz .LBB0_339
	s_and_b64 vcc, exec, s[44:45]
	s_mov_b32 s17, 0
	s_cbranch_vccnz .LBB0_366
	v_add_co_u32_e32 v26, vcc, 0xffff6000, v24
	s_mov_b32 s0, 0xffff0000
	s_nop 0
	v_addc_co_u32_e32 v27, vcc, -1, v25, vcc
	v_add_co_u32_e32 v28, vcc, s0, v24
	s_mov_b32 s0, 0xfffe6000
	s_nop 0
	v_addc_co_u32_e32 v29, vcc, -1, v25, vcc
	global_load_dwordx2 v[34:35], v[28:29], off nt
	v_add_co_u32_e32 v28, vcc, s0, v24
	s_movk_i32 s0, 0xa000
	s_nop 0
	v_addc_co_u32_e32 v29, vcc, -1, v25, vcc
	global_load_dwordx2 v[36:37], v[28:29], off nt
	v_add_co_u32_e32 v28, vcc, 0xfffec000, v24
	s_waitcnt vmcnt(0)
	v_and_b32_e32 v40, 0xffff0000, v35
	v_addc_co_u32_e32 v29, vcc, -1, v25, vcc
	v_add_co_u32_e32 v30, vcc, 0xfffe2000, v24
	global_load_dwordx2 v[26:27], v[26:27], off nt
	s_nop 0
	global_load_dwordx2 v[28:29], v[28:29], off nt
	v_addc_co_u32_e32 v31, vcc, -1, v25, vcc
	v_add_co_u32_e32 v24, vcc, s0, v24
	global_load_dwordx2 v[30:31], v[30:31], off nt
	s_nop 0
	v_addc_co_u32_e32 v25, vcc, -1, v25, vcc
	global_load_dwordx2 v[32:33], v[24:25], off nt
	v_and_b32_e32 v24, 0xffff0000, v34
	v_lshlrev_b32_e32 v25, 16, v34
	v_lshlrev_b32_e32 v41, 16, v35
	v_and_b32_e32 v38, 0xffff0000, v36
	v_lshlrev_b32_e32 v39, 16, v36
	v_and_b32_e32 v52, 0xffff0000, v37
	v_lshlrev_b32_e32 v53, 16, v37
	s_waitcnt vmcnt(0)
	v_lshlrev_b32_e32 v86, 16, v26
	v_and_b32_e32 v80, 0xffff0000, v26
	v_lshlrev_b32_e32 v78, 16, v27
	v_and_b32_e32 v62, 0xffff0000, v27
	v_lshlrev_b32_e32 v51, 16, v28
	v_and_b32_e32 v49, 0xffff0000, v28
	v_lshlrev_b32_e32 v47, 16, v29
	v_and_b32_e32 v45, 0xffff0000, v29
	v_lshlrev_b32_e32 v50, 16, v30
	v_and_b32_e32 v26, 0xffff0000, v32
	v_lshlrev_b32_e32 v27, 16, v32
	v_and_b32_e32 v28, 0xffff0000, v33
	v_lshlrev_b32_e32 v29, 16, v33
	v_pk_add_f32 v[26:27], v[26:27], 0 op_sel_hi:[1,0]
	v_pk_add_f32 v[28:29], v[28:29], 0 op_sel_hi:[1,0]
	v_pk_add_f32 v[24:25], v[26:27], v[24:25]
	v_pk_add_f32 v[26:27], v[28:29], v[40:41]
	v_and_b32_e32 v48, 0xffff0000, v30
	v_lshlrev_b32_e32 v46, 16, v31
	v_and_b32_e32 v44, 0xffff0000, v31
	v_pk_add_f32 v[42:43], v[24:25], v[38:39]
	v_pk_add_f32 v[52:53], v[26:27], v[52:53]
	s_branch .LBB0_367

; __device__ __forceinline__ unsigned cvt_pk_bf16(float lo, float hi) { unsigned r; asm volatile("v_cvt_pk_bf16_f32 %0, %1, %2" : "=v"(r) : "v"(lo), "v"(hi)); return r; }
; __device__ __forceinline__ void unpack4(const v2u q, float (&f)[4]) { f[0] = bf_lo(q.x); f[1] = bf_hi(q.x); f[2] = bf_lo(q.y); f[3] = bf_hi(q.y); }
; template <int W>
; __device__ __forceinline__ void conv_pool_chunk(const bf16* PROJ, bf16* XC, bf16* POOLED, const float* conv_w, const float* conv_b, int chunk, int ch0) {
;     ...
;             v2u xnb[8], pnb[8];
; #pragma unroll
;             for (int q = 0; q < 8; ++q) { xnb[q] = *(const v2u*)(p + (size_t)q * NIN); pnb[q] = *(const v2u*)(p + (size_t)q * NIN + 2 * D); }
; #pragma unroll
;             for (int q = 0; q < 8; ++q) { const int rr = h8 * 8 + q; const int r = rb * 16 + rr;
;                 const v2u xn = xnb[q], pn = pnb[q];
;                 float xf[4]; unpack4(xn, xf);
;                 float a[4];
; #pragma unroll
;                 for (int j = 0; j < 4; ++j) a[j] = cb[j] + cw[0][j] * cx[(rr + 1) & 3][j] + cw[1][j] * cx[(rr + 2) & 3][j] + cw[2][j] * cx[(rr + 3) & 3][j] + cw[3][j] * xf[j];
; #pragma unroll
;                 for (int j = 0; j < 4; ++j) cx[rr & 3][j] = xf[j];
;                 { v2u o; o.x = cvt_pk_bf16(a[0], a[1]); o.y = cvt_pk_bf16(a[2], a[3]); *(v2u*)(xo + (size_t)q * D) = o; }
;                 float pf[4], of[4]; unpack4(pn, pf); unpack4(ph[rr & (W - 1)], of);
;                 ph[rr & (W - 1)] = pn;
;                 const int t = t0 + r; const int cnt = (t + 1 < W) ? (t + 1) : W; const float inv = 1.0f / (float)cnt;
; #pragma unroll
;                 for (int j = 0; j < 4; ++j) { s[j] += pf[j] - of[j]; a[j] = s[j] * inv - pf[j]; }
;                 { v2u o; o.x = cvt_pk_bf16(a[0], a[1]); o.y = cvt_pk_bf16(a[2], a[3]); *(v2u*)(po + (size_t)q * D) = o; }
.LBB0_368:
	v_lshl_add_u64 v[54:55], s[4:5], 0, v[22:23]
	v_add_co_u32_e32 v56, vcc, s81, v54
	global_load_dwordx2 v[74:75], v[54:55], off nt
	s_nop 0
	v_addc_co_u32_e32 v57, vcc, 0, v55, vcc
	global_load_dwordx2 v[102:103], v[56:57], off nt
	v_add_co_u32_e32 v56, vcc, s36, v54
	s_add_i32 s38, s16, s17
	s_nop 0
	v_addc_co_u32_e32 v57, vcc, 0, v55, vcc
	global_load_dwordx2 v[76:77], v[56:57], off nt
	v_add_co_u32_e32 v56, vcc, s37, v54
	s_min_u32 s39, s38, 3
	s_nop 0
	v_addc_co_u32_e32 v57, vcc, 0, v55, vcc
	global_load_dwordx2 v[98:99], v[56:57], off nt
	v_add_co_u32_e32 v56, vcc, s42, v54
	s_add_i32 s39, s39, 1
	s_nop 0
	v_addc_co_u32_e32 v57, vcc, 0, v55, vcc
	global_load_dwordx2 v[92:93], v[56:57], off nt
	v_add_co_u32_e32 v56, vcc, s64, v54
	v_mov_b32_e32 v87, v51
	s_nop 0
	v_addc_co_u32_e32 v57, vcc, 0, v55, vcc
	global_load_dwordx2 v[96:97], v[56:57], off nt
	v_add_co_u32_e32 v56, vcc, s65, v54
	v_lshlrev_b32_e32 v71, 16, v38
	s_nop 0
	v_addc_co_u32_e32 v57, vcc, 0, v55, vcc
	global_load_dwordx2 v[94:95], v[56:57], off nt
	v_add_co_u32_e32 v56, vcc, s66, v54
	v_and_b32_e32 v70, 0xffff0000, v38
	s_nop 0
	v_addc_co_u32_e32 v57, vcc, 0, v55, vcc
	global_load_dwordx2 v[90:91], v[56:57], off nt
	v_add_co_u32_e32 v56, vcc, s67, v54
	v_lshlrev_b32_e32 v101, 16, v39
	s_nop 0
	v_addc_co_u32_e32 v57, vcc, 0, v55, vcc
	global_load_dwordx2 v[64:65], v[56:57], off nt
	v_add_co_u32_e32 v56, vcc, s71, v54
	v_and_b32_e32 v100, 0xffff0000, v39
	s_nop 0
	v_addc_co_u32_e32 v57, vcc, 0, v55, vcc
	global_load_dwordx2 v[88:89], v[56:57], off nt
	v_add_co_u32_e32 v56, vcc, s90, v54
	v_pk_mul_f32 v[38:39], v[2:3], v[86:87]
	s_nop 0
	v_addc_co_u32_e32 v57, vcc, 0, v55, vcc
	global_load_dwordx2 v[66:67], v[56:57], off nt
	v_add_co_u32_e32 v56, vcc, s91, v54
	v_add_f32_e32 v39, v14, v39
	s_nop 0
	v_addc_co_u32_e32 v57, vcc, 0, v55, vcc
	v_add_co_u32_e32 v58, vcc, s92, v54
	v_mov_b32_e32 v81, v49
	s_nop 0
	v_addc_co_u32_e32 v59, vcc, 0, v55, vcc
	global_load_dwordx2 v[84:85], v[58:59], off nt
	v_add_co_u32_e32 v58, vcc, s93, v54
	global_load_dwordx2 v[56:57], v[56:57], off nt
	s_nop 0
	v_addc_co_u32_e32 v59, vcc, 0, v55, vcc
	v_add_co_u32_e32 v60, vcc, s94, v54
	global_load_dwordx2 v[58:59], v[58:59], off nt
	s_nop 0
	v_addc_co_u32_e32 v61, vcc, 0, v55, vcc
	global_load_dwordx2 v[68:69], v[60:61], off nt
	v_add_co_u32_e32 v60, vcc, s95, v54
	v_lshl_add_u64 v[40:41], s[0:1], 0, v[22:23]
	s_nop 0
	v_addc_co_u32_e32 v61, vcc, 0, v55, vcc
	global_load_dwordx2 v[82:83], v[60:61], off nt
	v_pk_mul_f32 v[60:61], v[18:19], v[50:51]
	s_waitcnt vmcnt(0)
	v_lshlrev_b32_e32 v73, 16, v103
	v_add_f32_e32 v50, v14, v60
	v_add_f32_e32 v63, v61, v50
	v_pk_mul_f32 v[60:61], v[30:31], v[48:49]
	v_lshlrev_b32_e32 v51, 16, v76
	v_add_f32_e32 v48, v15, v60
	v_add_f32_e32 v79, v61, v48
	v_pk_mul_f32 v[60:61], v[20:21], v[46:47]
	v_and_b32_e32 v49, 0xffff0000, v76
	v_add_f32_e32 v46, v16, v60
	v_add_f32_e32 v104, v61, v46
	v_pk_mul_f32 v[60:61], v[26:27], v[44:45]
	v_and_b32_e32 v72, 0xffff0000, v103
	v_add_f32_e32 v44, v17, v60
	v_add_f32_e32 v105, v61, v44
	v_cvt_f32_ubyte0_e32 v44, s39
	v_div_scale_f32 v46, s[40:41], v44, v44, 1.0
	v_rcp_f32_e32 v48, v46
	s_add_i32 s39, s38, 1
	s_min_u32 s39, s39, 3
	s_add_i32 s39, s39, 1
	v_fma_f32 v50, -v46, v48, 1.0
	v_fmac_f32_e32 v48, v50, v48
	v_div_scale_f32 v50, vcc, 1.0, v44, 1.0
	v_mul_f32_e32 v60, v50, v48
	v_fma_f32 v61, -v46, v60, v50
	v_fmac_f32_e32 v60, v61, v48
	v_fma_f32 v46, -v46, v60, v50
	v_lshlrev_b32_e32 v50, 16, v74
	v_div_fmas_f32 v46, v46, v48, v60
	v_mov_b32_e32 v87, v50
	v_div_fixup_f32 v110, v46, v44, 1.0
	v_add_f32_e32 v44, v38, v39
	v_pk_mul_f32 v[38:39], v[28:29], v[86:87]
	v_and_b32_e32 v48, 0xffff0000, v74
	v_add_f32_e32 v38, v38, v63
	v_add_f32_e32 v46, v38, v39
	v_pk_mul_f32 v[38:39], v[28:29], v[50:51]
	v_lshlrev_b32_e32 v61, 16, v102
	v_add_f32_e32 v38, v44, v38
	v_add_f32_e32 v117, v38, v39
	v_pk_mul_f32 v[38:39], v[6:7], v[80:81]
	v_mov_b32_e32 v81, v48
	v_add_f32_e32 v39, v15, v39
	v_add_f32_e32 v44, v38, v39
	v_pk_mul_f32 v[38:39], v[10:11], v[80:81]
	v_and_b32_e32 v60, 0xffff0000, v102
	v_add_f32_e32 v38, v38, v79
	v_add_f32_e32 v38, v38, v39
	v_pk_mul_f32 v[102:103], v[10:11], v[48:49]
	v_mov_b32_e32 v79, v47
	v_cvt_pk_bf16_f32 v38, v46, v38
	v_add_f32_e32 v39, v44, v102
	v_pk_mul_f32 v[46:47], v[4:5], v[78:79]
	v_add_f32_e32 v118, v39, v103
	v_add_f32_e32 v39, v16, v47
	v_add_f32_e32 v39, v46, v39
	v_lshlrev_b32_e32 v46, 16, v75
	v_mov_b32_e32 v79, v46
	v_pk_mul_f32 v[102:103], v[24:25], v[78:79]
	v_lshlrev_b32_e32 v47, 16, v77
	v_add_f32_e32 v44, v102, v104
	v_add_f32_e32 v76, v44, v103
	v_pk_mul_f32 v[102:103], v[24:25], v[46:47]
	v_mov_b32_e32 v63, v45
	v_add_f32_e32 v39, v39, v102
	v_pk_mul_f32 v[44:45], v[8:9], v[62:63]
	v_add_f32_e32 v119, v39, v103
	v_add_f32_e32 v39, v17, v45
	v_add_f32_e32 v102, v44, v39
	v_and_b32_e32 v44, 0xffff0000, v75
	v_mov_b32_e32 v63, v44
	v_pk_mul_f32 v[74:75], v[12:13], v[62:63]
	v_and_b32_e32 v45, 0xffff0000, v77
	v_add_f32_e32 v39, v74, v105
	v_add_f32_e32 v39, v39, v75
	v_add_co_u32_e32 v74, vcc, s96, v40
	v_cvt_pk_bf16_f32 v39, v76, v39
	v_lshlrev_b32_e32 v103, 16, v37
	s_nop 0
	v_addc_co_u32_e32 v75, vcc, 0, v41, vcc
	global_store_dwordx2 v[74:75], v[38:39], off
	v_pk_mul_f32 v[38:39], v[12:13], v[44:45]
	s_add_i32 s38, s38, 2
	v_add_f32_e32 v38, v102, v38
	v_add_f32_e32 v120, v38, v39
	v_cvt_f32_ubyte0_e32 v38, s39
	v_div_scale_f32 v39, s[40:41], v38, v38, 1.0
	v_rcp_f32_e32 v74, v39
	v_and_b32_e32 v102, 0xffff0000, v37
	s_min_u32 s38, s38, 3
	s_add_i32 s38, s38, 1
	v_fma_f32 v75, -v39, v74, 1.0
	v_fmac_f32_e32 v74, v75, v74
	v_div_scale_f32 v75, vcc, 1.0, v38, 1.0
; __device__ __forceinline__ unsigned cvt_pk_bf16(float lo, float hi) { unsigned r; asm volatile("v_cvt_pk_bf16_f32 %0, %1, %2" : "=v"(r) : "v"(lo), "v"(hi)); return r; }
; __device__ __forceinline__ void unpack4(const v2u q, float (&f)[4]) { f[0] = bf_lo(q.x); f[1] = bf_hi(q.x); f[2] = bf_lo(q.y); f[3] = bf_hi(q.y); }
; template <int W>
; __device__ __forceinline__ void conv_pool_chunk(const bf16* PROJ, bf16* XC, bf16* POOLED, const float* conv_w, const float* conv_b, int chunk, int ch0) {
;     ...
;             for (int q = 0; q < 8; ++q) { const int rr = h8 * 8 + q; const int r = rb * 16 + rr;
;                 const v2u xn = xnb[q], pn = pnb[q];
;                 float xf[4]; unpack4(xn, xf);
;                 float a[4];
; #pragma unroll
;                 for (int j = 0; j < 4; ++j) a[j] = cb[j] + cw[0][j] * cx[(rr + 1) & 3][j] + cw[1][j] * cx[(rr + 2) & 3][j] + cw[2][j] * cx[(rr + 3) & 3][j] + cw[3][j] * xf[j];
; #pragma unroll
;                 for (int j = 0; j < 4; ++j) cx[rr & 3][j] = xf[j];
;                 { v2u o; o.x = cvt_pk_bf16(a[0], a[1]); o.y = cvt_pk_bf16(a[2], a[3]); *(v2u*)(xo + (size_t)q * D) = o; }
;                 float pf[4], of[4]; unpack4(pn, pf); unpack4(ph[rr & (W - 1)], of);
;                 ph[rr & (W - 1)] = pn;
;                 const int t = t0 + r; const int cnt = (t + 1 < W) ? (t + 1) : W; const float inv = 1.0f / (float)cnt;
; #pragma unroll
;                 for (int j = 0; j < 4; ++j) { s[j] += pf[j] - of[j]; a[j] = s[j] * inv - pf[j]; }
	v_mul_f32_e32 v76, v75, v74
	v_fma_f32 v77, -v39, v76, v75
	v_fmac_f32_e32 v76, v77, v74
	v_fma_f32 v39, -v39, v76, v75
	v_div_fmas_f32 v39, v39, v74, v76
	v_lshlrev_b32_e32 v75, 16, v36
	v_and_b32_e32 v74, 0xffff0000, v36
	v_pk_mul_f32 v[36:37], v[18:19], v[86:87]
	v_lshlrev_b32_e32 v133, 16, v35
	v_add_f32_e32 v36, v14, v36
	v_add_f32_e32 v86, v36, v37
	v_pk_mul_f32 v[36:37], v[30:31], v[80:81]
	v_and_b32_e32 v132, 0xffff0000, v35
	v_add_f32_e32 v36, v15, v36
	v_add_f32_e32 v87, v36, v37
	v_pk_mul_f32 v[36:37], v[20:21], v[78:79]
	v_lshlrev_b32_e32 v81, 16, v97
	v_add_f32_e32 v36, v16, v36
	v_add_f32_e32 v104, v36, v37
	v_pk_mul_f32 v[36:37], v[26:27], v[62:63]
	v_and_b32_e32 v80, 0xffff0000, v97
	v_add_f32_e32 v36, v17, v36
	v_add_f32_e32 v105, v36, v37
	v_cvt_f32_ubyte0_e32 v36, s38
	v_div_scale_f32 v37, s[38:39], v36, v36, 1.0
	v_rcp_f32_e32 v62, v37
	v_and_b32_e32 v97, 0xffff0000, v94
	v_div_fixup_f32 v121, v39, v38, 1.0
	v_lshlrev_b32_e32 v39, 16, v98
	v_fma_f32 v63, -v37, v62, 1.0
	v_fmac_f32_e32 v62, v63, v62
	v_div_scale_f32 v63, vcc, 1.0, v36, 1.0
	v_mul_f32_e32 v78, v63, v62
	v_fma_f32 v79, -v37, v78, v63
	v_fmac_f32_e32 v78, v79, v62
	v_fma_f32 v37, -v37, v78, v63
	v_div_fmas_f32 v37, v37, v62, v78
	v_lshlrev_b32_e32 v79, 16, v34
	v_and_b32_e32 v78, 0xffff0000, v34
	v_pk_mul_f32 v[34:35], v[18:19], v[50:51]
	v_lshlrev_b32_e32 v63, 16, v94
	v_lshlrev_b32_e32 v62, 16, v92
	v_add_f32_e32 v34, v14, v34
	v_pk_mov_b32 v[50:51], v[50:51], v[62:63] op_sel:[1,0]
	v_div_fixup_f32 v122, v37, v36, 1.0
	v_lshlrev_b32_e32 v37, 16, v96
	v_and_b32_e32 v36, 0xffff0000, v96
	v_add_f32_e32 v96, v34, v35
	v_pk_mul_f32 v[34:35], v[28:29], v[50:51]
	v_and_b32_e32 v38, 0xffff0000, v98
	v_add_f32_e32 v34, v86, v34
	v_add_f32_e32 v124, v34, v35
	v_pk_mul_f32 v[34:35], v[28:29], v[62:63]
	v_lshlrev_b32_e32 v77, 16, v99
	v_add_f32_e32 v34, v96, v34
	v_add_f32_e32 v123, v34, v35
	v_pk_mul_f32 v[34:35], v[30:31], v[48:49]
	v_and_b32_e32 v96, 0xffff0000, v92
	v_add_f32_e32 v34, v15, v34
	v_pk_mov_b32 v[48:49], v[48:49], v[96:97] op_sel:[1,0]
	v_add_f32_e32 v86, v34, v35
	v_pk_mul_f32 v[34:35], v[10:11], v[48:49]
	v_and_b32_e32 v76, 0xffff0000, v99
	v_add_f32_e32 v34, v87, v34
	v_add_f32_e32 v126, v34, v35
	v_pk_mul_f32 v[34:35], v[10:11], v[96:97]
	v_lshlrev_b32_e32 v99, 16, v95
	v_add_f32_e32 v34, v86, v34
	v_add_f32_e32 v125, v34, v35
	v_pk_mul_f32 v[34:35], v[20:21], v[46:47]
	v_lshlrev_b32_e32 v98, 16, v93
	v_add_f32_e32 v34, v16, v34
	v_pk_mov_b32 v[46:47], v[46:47], v[98:99] op_sel:[1,0]
	v_add_f32_e32 v86, v34, v35
	v_pk_mul_f32 v[34:35], v[24:25], v[46:47]
	v_and_b32_e32 v95, 0xffff0000, v95
	v_add_f32_e32 v34, v104, v34
	v_add_f32_e32 v128, v34, v35
	v_pk_mul_f32 v[34:35], v[24:25], v[98:99]
	v_and_b32_e32 v94, 0xffff0000, v93
	v_add_f32_e32 v34, v86, v34
	v_add_f32_e32 v127, v34, v35
	v_pk_mul_f32 v[34:35], v[26:27], v[44:45]
	v_pk_mov_b32 v[44:45], v[44:45], v[94:95] op_sel:[1,0]
	v_add_f32_e32 v34, v17, v34
	v_add_f32_e32 v86, v34, v35
	v_pk_mul_f32 v[34:35], v[12:13], v[44:45]
	v_pk_mul_f32 v[44:45], v[26:27], v[44:45]
	v_add_f32_e32 v34, v105, v34
	v_add_f32_e32 v44, v17, v44
	v_add_f32_e32 v130, v34, v35
	v_pk_mul_f32 v[34:35], v[12:13], v[94:95]
	v_pk_mul_f32 v[50:51], v[18:19], v[50:51]
	v_add_f32_e32 v111, v44, v45
	v_pk_mul_f32 v[44:45], v[18:19], v[62:63]
	v_add_f32_e32 v34, v86, v34
	v_add_f32_e32 v50, v14, v50
	v_pk_mul_f32 v[46:47], v[20:21], v[46:47]
	v_add_f32_e32 v44, v14, v44
	v_add_f32_e32 v129, v34, v35
	v_lshlrev_b32_e32 v35, 16, v90
	v_and_b32_e32 v34, 0xffff0000, v90
	v_add_f32_e32 v90, v50, v51
	v_add_f32_e32 v46, v16, v46
	v_lshlrev_b32_e32 v51, 16, v88
	v_and_b32_e32 v50, 0xffff0000, v88
	v_add_f32_e32 v88, v44, v45
	v_lshlrev_b32_e32 v45, 16, v66
	v_lshlrev_b32_e32 v44, 16, v64
	v_add_f32_e32 v108, v46, v47
	v_pk_mov_b32 v[46:47], v[62:63], v[44:45] op_sel:[1,0]
	v_lshlrev_b32_e32 v87, 16, v91
	v_pk_mul_f32 v[62:63], v[28:29], v[46:47]
	v_and_b32_e32 v86, 0xffff0000, v91
	v_add_f32_e32 v62, v90, v62
	v_add_f32_e32 v91, v62, v63
	v_pk_mul_f32 v[62:63], v[28:29], v[44:45]
	v_pk_mul_f32 v[48:49], v[30:31], v[48:49]
	v_add_f32_e32 v62, v88, v62
	v_add_f32_e32 v48, v15, v48
	v_add_f32_e32 v90, v62, v63
	v_pk_mul_f32 v[62:63], v[30:31], v[96:97]
	v_add_f32_e32 v104, v48, v49
	v_lshlrev_b32_e32 v49, 16, v89
	v_and_b32_e32 v48, 0xffff0000, v89
	v_add_f32_e32 v62, v15, v62
	v_and_b32_e32 v89, 0xffff0000, v66
	v_and_b32_e32 v88, 0xffff0000, v64
	v_add_f32_e32 v105, v62, v63
	v_pk_mov_b32 v[62:63], v[96:97], v[88:89] op_sel:[1,0]
	v_pk_mul_f32 v[96:97], v[10:11], v[88:89]
	v_pk_mul_f32 v[92:93], v[10:11], v[62:63]
	v_and_b32_e32 v109, 0xffff0000, v67
	v_add_f32_e32 v64, v104, v92
	v_add_f32_e32 v93, v64, v93
	v_add_f32_e32 v64, v105, v96
	v_add_f32_e32 v92, v64, v97
	v_pk_mul_f32 v[96:97], v[20:21], v[98:99]
	v_lshlrev_b32_e32 v105, 16, v67
	v_add_f32_e32 v64, v16, v96
	v_lshlrev_b32_e32 v104, 16, v65
	v_add_f32_e32 v64, v64, v97
	v_pk_mov_b32 v[106:107], v[98:99], v[104:105] op_sel:[1,0]
	v_pk_mul_f32 v[98:99], v[24:25], v[104:105]
	v_pk_mul_f32 v[96:97], v[24:25], v[106:107]
	v_add_f32_e32 v64, v64, v98
	v_add_f32_e32 v66, v108, v96
	v_add_f32_e32 v96, v64, v99
	v_pk_mul_f32 v[98:99], v[26:27], v[94:95]
	v_and_b32_e32 v108, 0xffff0000, v65
	v_add_f32_e32 v64, v17, v98
	v_add_f32_e32 v98, v64, v99
	v_pk_mov_b32 v[64:65], v[94:95], v[108:109] op_sel:[1,0]
	v_add_f32_e32 v97, v66, v97
	v_pk_mul_f32 v[66:67], v[12:13], v[64:65]
	v_pk_mul_f32 v[46:47], v[18:19], v[46:47]
	v_add_f32_e32 v66, v111, v66
	v_add_f32_e32 v111, v66, v67
	v_pk_mul_f32 v[66:67], v[12:13], v[108:109]
	v_add_f32_e32 v46, v14, v46
	v_add_f32_e32 v66, v98, v66
; __device__ __forceinline__ unsigned cvt_pk_bf16(float lo, float hi) { unsigned r; asm volatile("v_cvt_pk_bf16_f32 %0, %1, %2" : "=v"(r) : "v"(lo), "v"(hi)); return r; }
; __device__ __forceinline__ void unpack4(const v2u q, float (&f)[4]) { f[0] = bf_lo(q.x); f[1] = bf_hi(q.x); f[2] = bf_lo(q.y); f[3] = bf_hi(q.y); }
; template <int W>
; __device__ __forceinline__ void conv_pool_chunk(const bf16* PROJ, bf16* XC, bf16* POOLED, const float* conv_w, const float* conv_b, int chunk, int ch0) {
;     ...
;             for (int q = 0; q < 8; ++q) { const int rr = h8 * 8 + q; const int r = rb * 16 + rr;
;                 const v2u xn = xnb[q], pn = pnb[q];
;                 float xf[4]; unpack4(xn, xf);
;                 float a[4];
; #pragma unroll
;                 for (int j = 0; j < 4; ++j) a[j] = cb[j] + cw[0][j] * cx[(rr + 1) & 3][j] + cw[1][j] * cx[(rr + 2) & 3][j] + cw[2][j] * cx[(rr + 3) & 3][j] + cw[3][j] * xf[j];
; #pragma unroll
;                 for (int j = 0; j < 4; ++j) cx[rr & 3][j] = xf[j];
;                 { v2u o; o.x = cvt_pk_bf16(a[0], a[1]); o.y = cvt_pk_bf16(a[2], a[3]); *(v2u*)(xo + (size_t)q * D) = o; }
;                 float pf[4], of[4]; unpack4(pn, pf); unpack4(ph[rr & (W - 1)], of);
;                 ph[rr & (W - 1)] = pn;
;                 const int t = t0 + r; const int cnt = (t + 1 < W) ? (t + 1) : W; const float inv = 1.0f / (float)cnt;
; #pragma unroll
;                 for (int j = 0; j < 4; ++j) { s[j] += pf[j] - of[j]; a[j] = s[j] * inv - pf[j]; }
;                 { v2u o; o.x = cvt_pk_bf16(a[0], a[1]); o.y = cvt_pk_bf16(a[2], a[3]); *(v2u*)(po + (size_t)q * D) = o; }
;             }
;             p += 8 * NIN; xo += 8 * D; po += 8 * D;
	v_add_f32_e32 v98, v66, v67
	v_add_f32_e32 v66, v46, v47
	v_pk_mul_f32 v[46:47], v[30:31], v[62:63]
	v_lshlrev_b32_e32 v63, 16, v68
	v_add_f32_e32 v46, v15, v46
	v_add_f32_e32 v67, v46, v47
	v_pk_mul_f32 v[46:47], v[20:21], v[106:107]
	v_lshlrev_b32_e32 v62, 16, v84
	v_add_f32_e32 v46, v16, v46
	v_add_f32_e32 v106, v46, v47
	v_pk_mul_f32 v[46:47], v[26:27], v[64:65]
	v_pk_mov_b32 v[94:95], v[44:45], v[62:63] op_sel:[1,0]
	v_add_f32_e32 v46, v17, v46
	v_add_f32_e32 v107, v46, v47
	v_pk_mul_f32 v[46:47], v[18:19], v[44:45]
	v_pk_mul_f32 v[44:45], v[28:29], v[94:95]
	v_add_f32_e32 v46, v14, v46
	v_add_f32_e32 v44, v66, v44
	v_add_f32_e32 v46, v46, v47
	v_add_f32_e32 v112, v44, v45
	v_pk_mul_f32 v[44:45], v[28:29], v[62:63]
	v_and_b32_e32 v65, 0xffff0000, v68
	v_add_f32_e32 v44, v46, v44
	v_add_f32_e32 v99, v44, v45
	v_pk_mul_f32 v[44:45], v[30:31], v[88:89]
	v_and_b32_e32 v64, 0xffff0000, v84
	v_add_f32_e32 v44, v15, v44
	v_pk_mov_b32 v[88:89], v[88:89], v[64:65] op_sel:[1,0]
	v_add_f32_e32 v46, v44, v45
	v_pk_mul_f32 v[44:45], v[10:11], v[88:89]
	v_lshlrev_b32_e32 v66, 16, v85
	v_add_f32_e32 v44, v67, v44
	v_add_f32_e32 v113, v44, v45
	v_pk_mul_f32 v[44:45], v[10:11], v[64:65]
	v_lshlrev_b32_e32 v67, 16, v69
	v_add_f32_e32 v44, v46, v44
	v_add_f32_e32 v84, v44, v45
	v_pk_mul_f32 v[44:45], v[20:21], v[104:105]
	v_pk_mov_b32 v[104:105], v[104:105], v[66:67] op_sel:[1,0]
	v_add_f32_e32 v44, v16, v44
	v_add_f32_e32 v46, v44, v45
	v_pk_mul_f32 v[44:45], v[24:25], v[104:105]
	v_and_b32_e32 v69, 0xffff0000, v69
	v_add_f32_e32 v44, v106, v44
	v_add_f32_e32 v115, v44, v45
	v_pk_mul_f32 v[44:45], v[24:25], v[66:67]
	v_and_b32_e32 v68, 0xffff0000, v85
	v_add_f32_e32 v44, v46, v44
	v_add_f32_e32 v114, v44, v45
	v_pk_mul_f32 v[44:45], v[26:27], v[108:109]
	v_pk_mov_b32 v[108:109], v[108:109], v[68:69] op_sel:[1,0]
	v_add_f32_e32 v44, v17, v44
	v_add_f32_e32 v46, v44, v45
	v_pk_mul_f32 v[44:45], v[12:13], v[108:109]
	v_lshlrev_b32_e32 v47, 16, v82
	v_add_f32_e32 v44, v107, v44
	v_add_f32_e32 v116, v44, v45
	v_pk_mul_f32 v[44:45], v[12:13], v[68:69]
	v_pk_add_f32 v[70:71], v[60:61], v[70:71] neg_lo:[0,1] neg_hi:[0,1]
	v_add_f32_e32 v44, v46, v44
	v_add_f32_e32 v85, v44, v45
	v_and_b32_e32 v46, 0xffff0000, v82
	v_lshlrev_b32_e32 v45, 16, v83
	v_and_b32_e32 v44, 0xffff0000, v83
	v_pk_mul_f32 v[82:83], v[18:19], v[94:95]
	v_pk_add_f32 v[42:43], v[42:43], v[70:71]
	v_add_f32_e32 v82, v14, v82
	v_add_f32_e32 v95, v82, v83
	v_pk_mul_f32 v[82:83], v[30:31], v[88:89]
	v_fma_f32 v70, v110, v42, -v60
	v_add_f32_e32 v82, v15, v82
	v_add_f32_e32 v94, v82, v83
	v_pk_mul_f32 v[82:83], v[20:21], v[104:105]
	s_add_i32 s17, s17, 16
	v_add_f32_e32 v82, v16, v82
	v_add_f32_e32 v106, v82, v83
	v_pk_mul_f32 v[82:83], v[26:27], v[108:109]
	s_add_u32 s0, s0, 0x20000
	v_add_f32_e32 v82, v17, v82
	v_add_f32_e32 v105, v82, v83
	v_pk_mul_f32 v[82:83], v[18:19], v[62:63]
	s_addc_u32 s1, s1, 0
	v_add_f32_e32 v82, v14, v82
	v_add_f32_e32 v109, v82, v83
	v_pk_mul_f32 v[82:83], v[30:31], v[64:65]
	s_add_u32 s4, s4, 0xa0000
	v_add_f32_e32 v82, v15, v82
	v_add_f32_e32 v108, v82, v83
	v_pk_mul_f32 v[82:83], v[20:21], v[66:67]
	s_addc_u32 s5, s5, 0
	v_add_f32_e32 v82, v16, v82
	v_add_f32_e32 v107, v82, v83
	v_pk_mul_f32 v[82:83], v[26:27], v[68:69]
	s_cmp_eq_u32 s17, 64
	v_add_f32_e32 v82, v17, v82
	v_add_f32_e32 v104, v82, v83
	v_pk_add_f32 v[82:83], v[72:73], v[100:101] neg_lo:[0,1] neg_hi:[0,1]
	s_nop 0
	v_pk_add_f32 v[52:53], v[52:53], v[82:83]
	v_pk_add_f32 v[82:83], v[76:77], v[102:103] neg_lo:[0,1] neg_hi:[0,1]
	v_fma_f32 v100, v110, v53, -v73
	v_fma_f32 v101, v110, v52, -v72
	v_pk_add_f32 v[52:53], v[52:53], v[82:83]
	v_pk_add_f32 v[82:83], v[80:81], v[132:133] neg_lo:[0,1] neg_hi:[0,1]
	v_and_b32_e32 v102, 0xffff0000, v33
	v_lshlrev_b32_e32 v103, 16, v33
	v_fma_f32 v88, v121, v53, -v77
	v_fma_f32 v89, v121, v52, -v76
	v_pk_add_f32 v[52:53], v[52:53], v[82:83]
	v_pk_add_f32 v[102:103], v[86:87], v[102:103] neg_lo:[0,1] neg_hi:[0,1]
	v_fma_f32 v82, v122, v53, -v81
	v_fma_f32 v83, v122, v52, -v80
	v_pk_add_f32 v[52:53], v[52:53], v[102:103]
	v_pk_add_f32 v[72:73], v[48:49], v[72:73] neg_lo:[0,1] neg_hi:[0,1]
	v_fma_f32 v135, v53, s2, -v87
	v_fma_f32 v136, v52, s2, -v86
	v_pk_add_f32 v[52:53], v[52:53], v[72:73]
	v_and_b32_e32 v72, 0xffff0000, v57
	v_lshlrev_b32_e32 v73, 16, v57
	v_pk_add_f32 v[76:77], v[72:73], v[76:77] neg_lo:[0,1] neg_hi:[0,1]
	v_fma_f32 v133, v53, s2, -v49
	v_fma_f32 v134, v52, s2, -v48
	v_pk_add_f32 v[76:77], v[52:53], v[76:77]
	v_and_b32_e32 v52, 0xffff0000, v59
	v_lshlrev_b32_e32 v53, 16, v59
	v_pk_add_f32 v[80:81], v[52:53], v[80:81] neg_lo:[0,1] neg_hi:[0,1]
	v_fma_f32 v131, v77, s2, -v73
	v_fma_f32 v132, v76, s2, -v72
	v_pk_add_f32 v[76:77], v[76:77], v[80:81]
	v_pk_add_f32 v[80:81], v[44:45], v[86:87] neg_lo:[0,1] neg_hi:[0,1]
	v_fma_f32 v103, v76, s2, -v52
	v_pk_add_f32 v[80:81], v[76:77], v[80:81]
	v_add_co_u32_e32 v76, vcc, s97, v40
	v_fma_f32 v102, v77, s2, -v53
	s_nop 0
	v_addc_co_u32_e32 v77, vcc, 0, v41, vcc
	v_fma_f32 v33, v110, v43, -v61
	v_cvt_pk_bf16_f32 v70, v33, v70
	v_cvt_pk_bf16_f32 v71, v100, v101
	global_store_dwordx2 v[76:77], v[70:71], off
	v_add_co_u32_e32 v76, vcc, s14, v40
	v_cvt_pk_bf16_f32 v70, v117, v118
	v_cvt_pk_bf16_f32 v71, v119, v120
	v_pk_add_f32 v[60:61], v[50:51], v[60:61] neg_lo:[0,1] neg_hi:[0,1]
	s_nop 0
	v_addc_co_u32_e32 v77, vcc, 0, v41, vcc
	global_store_dwordx2 v[76:77], v[70:71], off
	v_pk_add_f32 v[70:71], v[38:39], v[74:75] neg_lo:[0,1] neg_hi:[0,1]
	v_add_co_u32_e32 v74, vcc, s54, v40
	v_pk_add_f32 v[42:43], v[42:43], v[70:71]
	s_nop 0
	v_addc_co_u32_e32 v75, vcc, 0, v41, vcc
	v_fma_f32 v70, v121, v42, -v38
; __device__ __forceinline__ unsigned cvt_pk_bf16(float lo, float hi) { unsigned r; asm volatile("v_cvt_pk_bf16_f32 %0, %1, %2" : "=v"(r) : "v"(lo), "v"(hi)); return r; }
; __device__ __forceinline__ void unpack4(const v2u q, float (&f)[4]) { f[0] = bf_lo(q.x); f[1] = bf_hi(q.x); f[2] = bf_lo(q.y); f[3] = bf_hi(q.y); }
; template <int W>
; __device__ __forceinline__ void conv_pool_chunk(const bf16* PROJ, bf16* XC, bf16* POOLED, const float* conv_w, const float* conv_b, int chunk, int ch0) {
;     ...
;             for (int q = 0; q < 8; ++q) { xnb[q] = *(const v2u*)(p + (size_t)q * NIN); pnb[q] = *(const v2u*)(p + (size_t)q * NIN + 2 * D); }
; #pragma unroll
;             for (int q = 0; q < 8; ++q) { const int rr = h8 * 8 + q; const int r = rb * 16 + rr;
;                 const v2u xn = xnb[q], pn = pnb[q];
;                 float xf[4]; unpack4(xn, xf);
;                 float a[4];
; #pragma unroll
;                 for (int j = 0; j < 4; ++j) a[j] = cb[j] + cw[0][j] * cx[(rr + 1) & 3][j] + cw[1][j] * cx[(rr + 2) & 3][j] + cw[2][j] * cx[(rr + 3) & 3][j] + cw[3][j] * xf[j];
; #pragma unroll
;                 for (int j = 0; j < 4; ++j) cx[rr & 3][j] = xf[j];
;                 { v2u o; o.x = cvt_pk_bf16(a[0], a[1]); o.y = cvt_pk_bf16(a[2], a[3]); *(v2u*)(xo + (size_t)q * D) = o; }
;                 float pf[4], of[4]; unpack4(pn, pf); unpack4(ph[rr & (W - 1)], of);
;                 ph[rr & (W - 1)] = pn;
;                 const int t = t0 + r; const int cnt = (t + 1 < W) ? (t + 1) : W; const float inv = 1.0f / (float)cnt;
; #pragma unroll
;                 for (int j = 0; j < 4; ++j) { s[j] += pf[j] - of[j]; a[j] = s[j] * inv - pf[j]; }
;                 { v2u o; o.x = cvt_pk_bf16(a[0], a[1]); o.y = cvt_pk_bf16(a[2], a[3]); *(v2u*)(po + (size_t)q * D) = o; }
	v_fma_f32 v33, v121, v43, -v39
	v_cvt_pk_bf16_f32 v70, v33, v70
	v_cvt_pk_bf16_f32 v71, v88, v89
	global_store_dwordx2 v[74:75], v[70:71], off
	v_add_co_u32_e32 v74, vcc, s55, v40
	v_pk_add_f32 v[70:71], v[36:37], v[78:79] neg_lo:[0,1] neg_hi:[0,1]
	s_nop 0
	v_addc_co_u32_e32 v75, vcc, 0, v41, vcc
	v_pk_add_f32 v[42:43], v[42:43], v[70:71]
	v_cvt_pk_bf16_f32 v70, v124, v126
	v_cvt_pk_bf16_f32 v71, v128, v130
	global_store_dwordx2 v[74:75], v[70:71], off
	v_add_co_u32_e32 v74, vcc, s58, v40
	v_fma_f32 v33, v122, v43, -v37
	s_nop 0
	v_addc_co_u32_e32 v75, vcc, 0, v41, vcc
	v_fma_f32 v76, v122, v42, -v36
	v_cvt_pk_bf16_f32 v70, v33, v76
	v_cvt_pk_bf16_f32 v71, v82, v83
	global_store_dwordx2 v[74:75], v[70:71], off
	v_add_co_u32_e32 v74, vcc, s6, v40
	v_cvt_pk_bf16_f32 v70, v123, v125
	v_cvt_pk_bf16_f32 v71, v127, v129
	v_and_b32_e32 v76, 0xffff0000, v56
	s_nop 0
	v_addc_co_u32_e32 v75, vcc, 0, v41, vcc
	global_store_dwordx2 v[74:75], v[70:71], off
	v_and_b32_e32 v70, 0xffff0000, v32
	v_lshlrev_b32_e32 v71, 16, v32
	v_pk_add_f32 v[32:33], v[34:35], v[70:71] neg_lo:[0,1] neg_hi:[0,1]
	v_lshlrev_b32_e32 v77, 16, v56
	v_pk_add_f32 v[42:43], v[42:43], v[32:33]
	v_pk_add_f32 v[38:39], v[76:77], v[38:39] neg_lo:[0,1] neg_hi:[0,1]
	v_fma_f32 v32, v43, s2, -v35
	v_fma_f32 v33, v42, s2, -v34
	v_pk_add_f32 v[42:43], v[42:43], v[60:61]
	v_and_b32_e32 v74, 0xffff0000, v58
	v_lshlrev_b32_e32 v75, 16, v58
	v_pk_add_f32 v[38:39], v[42:43], v[38:39]
	v_pk_add_f32 v[36:37], v[74:75], v[36:37] neg_lo:[0,1] neg_hi:[0,1]
	v_pk_add_f32 v[34:35], v[46:47], v[34:35] neg_lo:[0,1] neg_hi:[0,1]
	v_pk_add_f32 v[36:37], v[38:39], v[36:37]
	v_cvt_pk_bf16_f32 v32, v32, v33
	v_cvt_pk_bf16_f32 v33, v135, v136
	v_fma_f32 v60, v43, s2, -v51
	v_pk_add_f32 v[88:89], v[36:37], v[34:35]
	v_add_co_u32_e32 v34, vcc, s7, v40
	v_fma_f32 v61, v42, s2, -v50
	s_nop 0
	v_addc_co_u32_e32 v35, vcc, 0, v41, vcc
	global_store_dwordx2 v[34:35], v[32:33], off
	v_add_co_u32_e32 v34, vcc, s15, v40
	v_cvt_pk_bf16_f32 v32, v91, v93
	v_cvt_pk_bf16_f32 v33, v97, v111
	v_fma_f32 v42, v39, s2, -v77
	s_nop 0
	v_addc_co_u32_e32 v35, vcc, 0, v41, vcc
	global_store_dwordx2 v[34:35], v[32:33], off
	v_add_co_u32_e32 v34, vcc, s34, v40
	v_cvt_pk_bf16_f32 v32, v60, v61
	v_cvt_pk_bf16_f32 v33, v133, v134
	v_fma_f32 v43, v38, s2, -v76
	s_nop 0
	v_addc_co_u32_e32 v35, vcc, 0, v41, vcc
	global_store_dwordx2 v[34:35], v[32:33], off
	v_add_co_u32_e32 v34, vcc, s86, v40
	v_cvt_pk_bf16_f32 v32, v90, v92
	v_cvt_pk_bf16_f32 v33, v96, v98
	v_fma_f32 v38, v37, s2, -v75
	s_nop 0
	v_addc_co_u32_e32 v35, vcc, 0, v41, vcc
	global_store_dwordx2 v[34:35], v[32:33], off
	v_add_co_u32_e32 v34, vcc, s87, v40
	v_cvt_pk_bf16_f32 v32, v42, v43
	v_cvt_pk_bf16_f32 v33, v131, v132
	v_fma_f32 v39, v36, s2, -v74
	s_nop 0
	v_addc_co_u32_e32 v35, vcc, 0, v41, vcc
	global_store_dwordx2 v[34:35], v[32:33], off
	v_add_co_u32_e32 v34, vcc, s75, v40
	v_cvt_pk_bf16_f32 v32, v112, v113
	v_cvt_pk_bf16_f32 v33, v115, v116
	v_fma_f32 v36, v89, s2, -v47
	s_nop 0
	v_addc_co_u32_e32 v35, vcc, 0, v41, vcc
	global_store_dwordx2 v[34:35], v[32:33], off
	v_add_co_u32_e32 v34, vcc, s3, v40
	v_cvt_pk_bf16_f32 v32, v38, v39
	v_cvt_pk_bf16_f32 v33, v102, v103
	v_fma_f32 v37, v88, s2, -v46
	s_nop 0
	v_addc_co_u32_e32 v35, vcc, 0, v41, vcc
	global_store_dwordx2 v[34:35], v[32:33], off
	v_add_co_u32_e32 v34, vcc, s33, v40
	v_cvt_pk_bf16_f32 v32, v99, v84
	v_cvt_pk_bf16_f32 v33, v114, v85
	v_fma_f32 v57, v81, s2, -v45
	s_nop 0
	v_addc_co_u32_e32 v35, vcc, 0, v41, vcc
	global_store_dwordx2 v[34:35], v[32:33], off
	v_add_co_u32_e32 v34, vcc, s70, v40
	v_cvt_pk_bf16_f32 v32, v36, v37
	v_fma_f32 v59, v80, s2, -v44
	s_nop 0
	v_addc_co_u32_e32 v35, vcc, 0, v41, vcc
	v_cvt_pk_bf16_f32 v33, v57, v59
	global_store_dwordx2 v[34:35], v[32:33], off
	v_add_co_u32_e32 v32, vcc, s88, v54
	s_nop 1
	v_addc_co_u32_e32 v33, vcc, 0, v55, vcc
	global_load_dwordx2 v[100:101], v[32:33], off nt
	v_add_co_u32_e32 v32, vcc, s89, v54
	s_nop 1
	v_addc_co_u32_e32 v33, vcc, 0, v55, vcc
	global_load_dwordx2 v[92:93], v[32:33], off nt
	v_add_co_u32_e32 v32, vcc, s11, v54
	s_waitcnt vmcnt(0)
	v_lshlrev_b32_e32 v57, 16, v92
	v_addc_co_u32_e32 v33, vcc, 0, v55, vcc
	global_load_dwordx2 v[102:103], v[32:33], off nt
	v_add_co_u32_e32 v32, vcc, s35, v54
	v_and_b32_e32 v56, 0xffff0000, v92
	s_nop 0
	v_addc_co_u32_e32 v33, vcc, 0, v55, vcc
	global_load_dwordx2 v[90:91], v[32:33], off nt
	v_add_co_u32_e32 v32, vcc, s78, v54
	v_lshlrev_b32_e32 v92, 16, v100
	s_nop 0
	v_addc_co_u32_e32 v33, vcc, 0, v55, vcc
	global_load_dwordx2 v[82:83], v[32:33], off nt
	v_add_co_u32_e32 v32, vcc, s79, v54
	v_pk_add_f32 v[50:51], v[56:57], v[50:51] neg_lo:[0,1] neg_hi:[0,1]
	s_nop 0
	v_addc_co_u32_e32 v33, vcc, 0, v55, vcc
	global_load_dwordx2 v[86:87], v[32:33], off nt
	v_add_co_u32_e32 v32, vcc, s82, v54
	v_pk_add_f32 v[96:97], v[88:89], v[50:51]
	s_nop 0
	v_addc_co_u32_e32 v33, vcc, 0, v55, vcc
	global_load_dwordx2 v[84:85], v[32:33], off nt
	v_add_co_u32_e32 v32, vcc, s83, v54
	v_and_b32_e32 v88, 0xffff0000, v100
	s_nop 0
	v_addc_co_u32_e32 v33, vcc, 0, v55, vcc
	global_load_dwordx2 v[78:79], v[32:33], off nt
	v_add_co_u32_e32 v32, vcc, s28, v54
	v_fma_f32 v110, v97, s2, -v57
	s_nop 0
	v_addc_co_u32_e32 v33, vcc, 0, v55, vcc
	global_load_dwordx2 v[58:59], v[32:33], off nt
	v_add_co_u32_e32 v32, vcc, s29, v54
	v_fma_f32 v111, v96, s2, -v56
	s_nop 0
	v_addc_co_u32_e32 v33, vcc, 0, v55, vcc
	global_load_dwordx2 v[38:39], v[32:33], off nt
	v_add_co_u32_e32 v32, vcc, s10, v54
	s_waitcnt vmcnt(0)
; __device__ __forceinline__ unsigned cvt_pk_bf16(float lo, float hi) { unsigned r; asm volatile("v_cvt_pk_bf16_f32 %0, %1, %2" : "=v"(r) : "v"(lo), "v"(hi)); return r; }
; __device__ __forceinline__ void unpack4(const v2u q, float (&f)[4]) { f[0] = bf_lo(q.x); f[1] = bf_hi(q.x); f[2] = bf_lo(q.y); f[3] = bf_hi(q.y); }
; template <int W>
; __device__ __forceinline__ void conv_pool_chunk(const bf16* PROJ, bf16* XC, bf16* POOLED, const float* conv_w, const float* conv_b, int chunk, int ch0) {
;     ...
;             for (int q = 0; q < 8; ++q) { xnb[q] = *(const v2u*)(p + (size_t)q * NIN); pnb[q] = *(const v2u*)(p + (size_t)q * NIN + 2 * D); }
; #pragma unroll
;             for (int q = 0; q < 8; ++q) { const int rr = h8 * 8 + q; const int r = rb * 16 + rr;
;                 const v2u xn = xnb[q], pn = pnb[q];
;                 float xf[4]; unpack4(xn, xf);
;                 float a[4];
; #pragma unroll
;                 for (int j = 0; j < 4; ++j) a[j] = cb[j] + cw[0][j] * cx[(rr + 1) & 3][j] + cw[1][j] * cx[(rr + 2) & 3][j] + cw[2][j] * cx[(rr + 3) & 3][j] + cw[3][j] * xf[j];
; #pragma unroll
;                 for (int j = 0; j < 4; ++j) cx[rr & 3][j] = xf[j];
;                 { v2u o; o.x = cvt_pk_bf16(a[0], a[1]); o.y = cvt_pk_bf16(a[2], a[3]); *(v2u*)(xo + (size_t)q * D) = o; }
;                 float pf[4], of[4]; unpack4(pn, pf); unpack4(ph[rr & (W - 1)], of);
;                 ph[rr & (W - 1)] = pn;
;                 const int t = t0 + r; const int cnt = (t + 1 < W) ? (t + 1) : W; const float inv = 1.0f / (float)cnt;
; #pragma unroll
;                 for (int j = 0; j < 4; ++j) { s[j] += pf[j] - of[j]; a[j] = s[j] * inv - pf[j]; }
;                 { v2u o; o.x = cvt_pk_bf16(a[0], a[1]); o.y = cvt_pk_bf16(a[2], a[3]); *(v2u*)(po + (size_t)q * D) = o; }
	v_and_b32_e32 v89, 0xffff0000, v102
	v_addc_co_u32_e32 v33, vcc, 0, v55, vcc
	global_load_dwordx2 v[60:61], v[32:33], off nt
	v_add_co_u32_e32 v32, vcc, s72, v54
	v_pk_mov_b32 v[64:65], v[64:65], v[88:89] op_sel:[1,0]
	s_nop 0
	v_addc_co_u32_e32 v33, vcc, 0, v55, vcc
	global_load_dwordx2 v[36:37], v[32:33], off nt
	v_add_co_u32_e32 v32, vcc, s73, v54
	s_nop 1
	v_addc_co_u32_e32 v33, vcc, 0, v55, vcc
	global_load_dwordx2 v[70:71], v[32:33], off nt
	v_add_co_u32_e32 v32, vcc, s59, v54
	s_nop 1
	v_addc_co_u32_e32 v33, vcc, 0, v55, vcc
	global_load_dwordx2 v[34:35], v[32:33], off nt
	v_add_co_u32_e32 v32, vcc, s62, v54
	s_nop 1
	v_addc_co_u32_e32 v33, vcc, 0, v55, vcc
	global_load_dwordx2 v[42:43], v[32:33], off nt
	v_add_co_u32_e32 v32, vcc, s63, v54
	v_and_b32_e32 v54, 0xffff0000, v93
	s_nop 0
	v_addc_co_u32_e32 v33, vcc, 0, v55, vcc
	v_lshlrev_b32_e32 v55, 16, v93
	v_lshlrev_b32_e32 v93, 16, v102
	v_pk_add_f32 v[48:49], v[54:55], v[48:49] neg_lo:[0,1] neg_hi:[0,1]
	v_pk_mov_b32 v[62:63], v[62:63], v[92:93] op_sel:[1,0]
	v_pk_add_f32 v[98:99], v[80:81], v[48:49]
	v_pk_mul_f32 v[48:49], v[28:29], v[62:63]
	global_load_dwordx2 v[32:33], v[32:33], off nt
	v_add_f32_e32 v48, v95, v48
	v_add_f32_e32 v50, v48, v49
	v_pk_mul_f32 v[48:49], v[28:29], v[92:93]
	v_lshlrev_b32_e32 v81, 16, v103
	v_add_f32_e32 v48, v109, v48
	v_add_f32_e32 v109, v48, v49
	v_pk_mul_f32 v[48:49], v[10:11], v[64:65]
	v_lshlrev_b32_e32 v80, 16, v101
	v_add_f32_e32 v48, v94, v48
	v_add_f32_e32 v48, v48, v49
	v_cvt_pk_bf16_f32 v48, v50, v48
	v_pk_mul_f32 v[50:51], v[10:11], v[88:89]
	v_pk_mov_b32 v[94:95], v[66:67], v[80:81] op_sel:[1,0]
	v_add_f32_e32 v49, v108, v50
	v_add_f32_e32 v100, v49, v51
	v_pk_mul_f32 v[50:51], v[24:25], v[94:95]
	v_and_b32_e32 v67, 0xffff0000, v103
	v_add_f32_e32 v49, v106, v50
	v_add_f32_e32 v49, v49, v51
	v_pk_mul_f32 v[50:51], v[24:25], v[80:81]
	v_and_b32_e32 v66, 0xffff0000, v101
	v_add_f32_e32 v50, v107, v50
	v_pk_mov_b32 v[68:69], v[68:69], v[66:67] op_sel:[1,0]
	v_add_f32_e32 v102, v50, v51
	v_pk_mul_f32 v[50:51], v[12:13], v[68:69]
	v_fma_f32 v112, v99, s2, -v55
	v_add_f32_e32 v50, v105, v50
	v_add_f32_e32 v50, v50, v51
	v_cvt_pk_bf16_f32 v49, v49, v50
	v_add_co_u32_e32 v50, vcc, s18, v40
	v_fma_f32 v113, v98, s2, -v54
	s_nop 0
	v_addc_co_u32_e32 v51, vcc, 0, v41, vcc
	global_store_dwordx2 v[50:51], v[48:49], off
	v_add_co_u32_e32 v50, vcc, s19, v40
	v_cvt_pk_bf16_f32 v48, v110, v111
	v_cvt_pk_bf16_f32 v49, v112, v113
	v_pk_mul_f32 v[62:63], v[18:19], v[62:63]
	s_nop 0
	v_addc_co_u32_e32 v51, vcc, 0, v41, vcc
	global_store_dwordx2 v[50:51], v[48:49], off
	v_pk_mul_f32 v[48:49], v[12:13], v[66:67]
	v_add_co_u32_e32 v50, vcc, s20, v40
	v_add_f32_e32 v48, v104, v48
	v_add_f32_e32 v49, v48, v49
	v_cvt_pk_bf16_f32 v48, v109, v100
	v_cvt_pk_bf16_f32 v49, v102, v49
	v_addc_co_u32_e32 v51, vcc, 0, v41, vcc
	global_store_dwordx2 v[50:51], v[48:49], off
	v_and_b32_e32 v50, 0xffff0000, v90
	v_lshlrev_b32_e32 v51, 16, v90
	v_and_b32_e32 v48, 0xffff0000, v91
	v_lshlrev_b32_e32 v49, 16, v91
	v_pk_add_f32 v[76:77], v[50:51], v[76:77] neg_lo:[0,1] neg_hi:[0,1]
	v_pk_add_f32 v[72:73], v[48:49], v[72:73] neg_lo:[0,1] neg_hi:[0,1]
	v_pk_add_f32 v[76:77], v[96:97], v[76:77]
	v_pk_add_f32 v[72:73], v[98:99], v[72:73]
	v_fma_f32 v90, v77, s2, -v51
	v_fma_f32 v91, v76, s2, -v50
	v_fma_f32 v96, v73, s2, -v49
	v_fma_f32 v97, v72, s2, -v48
	v_cvt_pk_bf16_f32 v90, v90, v91
	v_cvt_pk_bf16_f32 v91, v96, v97
	v_add_co_u32_e32 v96, vcc, s21, v40
	v_add_f32_e32 v62, v14, v62
	s_nop 0
	v_addc_co_u32_e32 v97, vcc, 0, v41, vcc
	global_store_dwordx2 v[96:97], v[90:91], off
	v_add_f32_e32 v96, v62, v63
	v_pk_mul_f32 v[62:63], v[30:31], v[64:65]
	v_and_b32_e32 v64, 0xffff0000, v86
	v_add_f32_e32 v62, v15, v62
	v_add_f32_e32 v97, v62, v63
	v_pk_mul_f32 v[62:63], v[20:21], v[94:95]
	v_lshlrev_b32_e32 v65, 16, v86
	v_add_f32_e32 v62, v16, v62
	v_add_f32_e32 v98, v62, v63
	v_pk_mul_f32 v[62:63], v[26:27], v[68:69]
	v_pk_add_f32 v[68:69], v[64:65], v[74:75] neg_lo:[0,1] neg_hi:[0,1]
	v_add_f32_e32 v62, v17, v62
	v_add_f32_e32 v99, v62, v63
	v_and_b32_e32 v62, 0xffff0000, v87
	v_lshlrev_b32_e32 v63, 16, v87
	v_pk_add_f32 v[52:53], v[62:63], v[52:53] neg_lo:[0,1] neg_hi:[0,1]
	v_pk_add_f32 v[90:91], v[76:77], v[68:69]
	v_pk_add_f32 v[94:95], v[72:73], v[52:53]
	v_pk_mul_f32 v[52:53], v[18:19], v[92:93]
	v_lshlrev_b32_e32 v68, 16, v82
	v_lshlrev_b32_e32 v69, 16, v84
	v_add_f32_e32 v52, v14, v52
	v_pk_mov_b32 v[86:87], v[92:93], v[68:69] op_sel:[1,0]
	v_add_f32_e32 v72, v52, v53
	v_pk_mul_f32 v[52:53], v[28:29], v[86:87]
	v_and_b32_e32 v73, 0xffff0000, v84
	v_add_f32_e32 v52, v96, v52
	v_add_f32_e32 v74, v52, v53
	v_pk_mul_f32 v[52:53], v[28:29], v[68:69]
	v_fma_f32 v100, v91, s2, -v65
	v_add_f32_e32 v52, v72, v52
	v_add_f32_e32 v92, v52, v53
	v_pk_mul_f32 v[52:53], v[30:31], v[88:89]
	v_and_b32_e32 v72, 0xffff0000, v82
	v_add_f32_e32 v52, v15, v52
	v_pk_mov_b32 v[88:89], v[88:89], v[72:73] op_sel:[1,0]
	v_add_f32_e32 v76, v52, v53
	v_pk_mul_f32 v[52:53], v[10:11], v[88:89]
	v_fma_f32 v101, v90, s2, -v64
	v_add_f32_e32 v52, v97, v52
	v_add_f32_e32 v52, v52, v53
	v_cvt_pk_bf16_f32 v52, v74, v52
	v_pk_mul_f32 v[74:75], v[10:11], v[72:73]
	v_fma_f32 v102, v95, s2, -v63
	v_add_f32_e32 v53, v76, v74
	v_add_f32_e32 v84, v53, v75
	v_pk_mul_f32 v[74:75], v[20:21], v[80:81]
	v_fma_f32 v103, v94, s2, -v62
	v_add_f32_e32 v53, v16, v74
	v_add_f32_e32 v53, v53, v75
	v_lshlrev_b32_e32 v74, 16, v83
	v_lshlrev_b32_e32 v75, 16, v85
	v_pk_mov_b32 v[80:81], v[80:81], v[74:75] op_sel:[1,0]
	s_nop 0
	v_pk_mul_f32 v[76:77], v[24:25], v[80:81]
	s_nop 0
	v_add_f32_e32 v76, v98, v76
	v_add_f32_e32 v93, v76, v77
; __device__ __forceinline__ unsigned cvt_pk_bf16(float lo, float hi) { unsigned r; asm volatile("v_cvt_pk_bf16_f32 %0, %1, %2" : "=v"(r) : "v"(lo), "v"(hi)); return r; }
; __device__ __forceinline__ void unpack4(const v2u q, float (&f)[4]) { f[0] = bf_lo(q.x); f[1] = bf_hi(q.x); f[2] = bf_lo(q.y); f[3] = bf_hi(q.y); }
; template <int W>
; __device__ __forceinline__ void conv_pool_chunk(const bf16* PROJ, bf16* XC, bf16* POOLED, const float* conv_w, const float* conv_b, int chunk, int ch0) {
;     ...
;             for (int q = 0; q < 8; ++q) { const int rr = h8 * 8 + q; const int r = rb * 16 + rr;
;                 const v2u xn = xnb[q], pn = pnb[q];
;                 float xf[4]; unpack4(xn, xf);
;                 float a[4];
; #pragma unroll
;                 for (int j = 0; j < 4; ++j) a[j] = cb[j] + cw[0][j] * cx[(rr + 1) & 3][j] + cw[1][j] * cx[(rr + 2) & 3][j] + cw[2][j] * cx[(rr + 3) & 3][j] + cw[3][j] * xf[j];
; #pragma unroll
;                 for (int j = 0; j < 4; ++j) cx[rr & 3][j] = xf[j];
;                 { v2u o; o.x = cvt_pk_bf16(a[0], a[1]); o.y = cvt_pk_bf16(a[2], a[3]); *(v2u*)(xo + (size_t)q * D) = o; }
;                 float pf[4], of[4]; unpack4(pn, pf); unpack4(ph[rr & (W - 1)], of);
;                 ph[rr & (W - 1)] = pn;
;                 const int t = t0 + r; const int cnt = (t + 1 < W) ? (t + 1) : W; const float inv = 1.0f / (float)cnt;
; #pragma unroll
;                 for (int j = 0; j < 4; ++j) { s[j] += pf[j] - of[j]; a[j] = s[j] * inv - pf[j]; }
;                 { v2u o; o.x = cvt_pk_bf16(a[0], a[1]); o.y = cvt_pk_bf16(a[2], a[3]); *(v2u*)(po + (size_t)q * D) = o; }
	v_pk_mul_f32 v[76:77], v[24:25], v[74:75]
	s_nop 0
	v_add_f32_e32 v53, v53, v76
	v_add_f32_e32 v96, v53, v77
	v_pk_mul_f32 v[76:77], v[26:27], v[66:67]
	s_nop 0
	v_add_f32_e32 v53, v17, v76
	v_add_f32_e32 v97, v53, v77
	v_and_b32_e32 v77, 0xffff0000, v85
	v_and_b32_e32 v76, 0xffff0000, v83
	v_pk_mov_b32 v[82:83], v[66:67], v[76:77] op_sel:[1,0]
	v_and_b32_e32 v85, 0xffff0000, v59
	v_pk_mul_f32 v[66:67], v[12:13], v[82:83]
	s_nop 0
	v_add_f32_e32 v53, v99, v66
	v_add_co_u32_e32 v66, vcc, s22, v40
	v_add_f32_e32 v53, v53, v67
	s_nop 0
	v_addc_co_u32_e32 v67, vcc, 0, v41, vcc
	v_cvt_pk_bf16_f32 v53, v93, v53
	global_store_dwordx2 v[66:67], v[52:53], off
	v_add_co_u32_e32 v66, vcc, s23, v40
	v_cvt_pk_bf16_f32 v52, v100, v101
	v_cvt_pk_bf16_f32 v53, v102, v103
	s_nop 1
	v_addc_co_u32_e32 v67, vcc, 0, v41, vcc
	global_store_dwordx2 v[66:67], v[52:53], off
	v_pk_mul_f32 v[52:53], v[12:13], v[76:77]
	v_add_co_u32_e32 v66, vcc, s24, v40
	v_add_f32_e32 v52, v97, v52
	v_add_f32_e32 v53, v52, v53
	v_addc_co_u32_e32 v67, vcc, 0, v41, vcc
	v_cvt_pk_bf16_f32 v52, v92, v84
	v_cvt_pk_bf16_f32 v53, v96, v53
	global_store_dwordx2 v[66:67], v[52:53], off
	v_and_b32_e32 v66, 0xffff0000, v78
	v_lshlrev_b32_e32 v67, 16, v78
	v_and_b32_e32 v52, 0xffff0000, v79
	v_lshlrev_b32_e32 v53, 16, v79
	v_pk_add_f32 v[46:47], v[66:67], v[46:47] neg_lo:[0,1] neg_hi:[0,1]
	v_pk_add_f32 v[44:45], v[52:53], v[44:45] neg_lo:[0,1] neg_hi:[0,1]
	v_pk_add_f32 v[78:79], v[90:91], v[46:47]
	v_pk_add_f32 v[92:93], v[94:95], v[44:45]
	v_fma_f32 v46, v79, s2, -v67
	v_fma_f32 v47, v78, s2, -v66
	v_fma_f32 v45, v93, s2, -v53
	v_cvt_pk_bf16_f32 v44, v46, v47
	v_add_co_u32_e32 v46, vcc, s25, v40
	v_fma_f32 v84, v92, s2, -v52
	v_cvt_pk_bf16_f32 v45, v45, v84
	s_nop 0
	v_addc_co_u32_e32 v47, vcc, 0, v41, vcc
	global_store_dwordx2 v[46:47], v[44:45], off
	v_lshlrev_b32_e32 v91, 16, v58
	v_and_b32_e32 v47, 0xffff0000, v58
	v_lshlrev_b32_e32 v45, 16, v59
	v_pk_mul_f32 v[58:59], v[18:19], v[86:87]
	v_mov_b32_e32 v90, v69
	v_add_f32_e32 v44, v14, v58
	v_add_f32_e32 v44, v44, v59
	v_pk_mul_f32 v[58:59], v[28:29], v[90:91]
	v_mov_b32_e32 v46, v73
	v_add_f32_e32 v44, v44, v58
	v_add_f32_e32 v86, v44, v59
	v_pk_mul_f32 v[58:59], v[30:31], v[88:89]
	v_mov_b32_e32 v84, v77
	v_add_f32_e32 v44, v15, v58
	v_add_f32_e32 v44, v44, v59
	v_pk_mul_f32 v[58:59], v[10:11], v[46:47]
	s_nop 0
	v_add_f32_e32 v44, v44, v58
	v_add_f32_e32 v87, v44, v59
	v_pk_mul_f32 v[58:59], v[20:21], v[80:81]
	s_nop 0
	v_add_f32_e32 v44, v16, v58
	v_add_f32_e32 v80, v44, v59
	v_mov_b32_e32 v44, v75
	v_pk_mul_f32 v[58:59], v[24:25], v[44:45]
	s_nop 0
	v_add_f32_e32 v58, v80, v58
	v_add_f32_e32 v80, v58, v59
	v_pk_mul_f32 v[58:59], v[26:27], v[82:83]
	s_nop 0
	v_add_f32_e32 v58, v17, v58
	v_add_f32_e32 v81, v58, v59
	v_pk_mul_f32 v[58:59], v[12:13], v[84:85]
	s_nop 0
	v_add_f32_e32 v58, v81, v58
	v_add_f32_e32 v59, v58, v59
	v_cvt_pk_bf16_f32 v58, v86, v87
	v_cvt_pk_bf16_f32 v59, v80, v59
	v_add_co_u32_e32 v80, vcc, s26, v40
	s_nop 1
	v_addc_co_u32_e32 v81, vcc, 0, v41, vcc
	global_store_dwordx2 v[80:81], v[58:59], off
	v_and_b32_e32 v58, 0xffff0000, v38
	v_lshlrev_b32_e32 v59, 16, v38
	v_and_b32_e32 v80, 0xffff0000, v39
	v_lshlrev_b32_e32 v81, 16, v39
	v_pk_add_f32 v[56:57], v[58:59], v[56:57] neg_lo:[0,1] neg_hi:[0,1]
	v_pk_add_f32 v[54:55], v[80:81], v[54:55] neg_lo:[0,1] neg_hi:[0,1]
	v_pk_add_f32 v[56:57], v[78:79], v[56:57]
	v_pk_add_f32 v[54:55], v[92:93], v[54:55]
	v_fma_f32 v59, v57, s2, -v59
	v_fma_f32 v58, v56, s2, -v58
	v_fma_f32 v78, v55, s2, -v81
	v_fma_f32 v79, v54, s2, -v80
	v_cvt_pk_bf16_f32 v58, v59, v58
	v_cvt_pk_bf16_f32 v59, v78, v79
	v_add_co_u32_e32 v78, vcc, s27, v40
	s_nop 1
	v_addc_co_u32_e32 v79, vcc, 0, v41, vcc
	global_store_dwordx2 v[78:79], v[58:59], off
	v_pk_mul_f32 v[58:59], v[18:19], v[68:69]
	s_waitcnt vmcnt(0)
; __device__ __forceinline__ unsigned cvt_pk_bf16(float lo, float hi) { unsigned r; asm volatile("v_cvt_pk_bf16_f32 %0, %1, %2" : "=v"(r) : "v"(lo), "v"(hi)); return r; }
; __device__ __forceinline__ void unpack4(const v2u q, float (&f)[4]) { f[0] = bf_lo(q.x); f[1] = bf_hi(q.x); f[2] = bf_lo(q.y); f[3] = bf_hi(q.y); }
; template <int W>
; __device__ __forceinline__ void conv_pool_chunk(const bf16* PROJ, bf16* XC, bf16* POOLED, const float* conv_w, const float* conv_b, int chunk, int ch0) {
;     ...
;             for (int q = 0; q < 8; ++q) { const int rr = h8 * 8 + q; const int r = rb * 16 + rr;
;                 const v2u xn = xnb[q], pn = pnb[q];
;                 float xf[4]; unpack4(xn, xf);
;                 float a[4];
; #pragma unroll
;                 for (int j = 0; j < 4; ++j) a[j] = cb[j] + cw[0][j] * cx[(rr + 1) & 3][j] + cw[1][j] * cx[(rr + 2) & 3][j] + cw[2][j] * cx[(rr + 3) & 3][j] + cw[3][j] * xf[j];
; #pragma unroll
;                 for (int j = 0; j < 4; ++j) cx[rr & 3][j] = xf[j];
;                 { v2u o; o.x = cvt_pk_bf16(a[0], a[1]); o.y = cvt_pk_bf16(a[2], a[3]); *(v2u*)(xo + (size_t)q * D) = o; }
;                 float pf[4], of[4]; unpack4(pn, pf); unpack4(ph[rr & (W - 1)], of);
;                 ph[rr & (W - 1)] = pn;
;                 const int t = t0 + r; const int cnt = (t + 1 < W) ? (t + 1) : W; const float inv = 1.0f / (float)cnt;
; #pragma unroll
;                 for (int j = 0; j < 4; ++j) { s[j] += pf[j] - of[j]; a[j] = s[j] * inv - pf[j]; }
;                 { v2u o; o.x = cvt_pk_bf16(a[0], a[1]); o.y = cvt_pk_bf16(a[2], a[3]); *(v2u*)(po + (size_t)q * D) = o; }
;             }
;             p += 8 * NIN; xo += 8 * D; po += 8 * D;
	v_and_b32_e32 v68, 0xffff0000, v37
	v_add_f32_e32 v58, v14, v58
	v_add_f32_e32 v80, v58, v59
	v_pk_mul_f32 v[58:59], v[30:31], v[72:73]
	v_lshlrev_b32_e32 v69, 16, v37
	v_add_f32_e32 v58, v15, v58
	v_add_f32_e32 v81, v58, v59
	v_pk_mul_f32 v[58:59], v[20:21], v[74:75]
	v_pk_add_f32 v[48:49], v[68:69], v[48:49] neg_lo:[0,1] neg_hi:[0,1]
	v_add_f32_e32 v58, v16, v58
	v_add_f32_e32 v82, v58, v59
	v_pk_mul_f32 v[58:59], v[26:27], v[76:77]
	v_pk_add_f32 v[78:79], v[54:55], v[48:49]
	v_add_f32_e32 v58, v17, v58
	v_add_f32_e32 v86, v58, v59
	v_and_b32_e32 v58, 0xffff0000, v36
	v_lshlrev_b32_e32 v59, 16, v36
	v_pk_add_f32 v[50:51], v[58:59], v[50:51] neg_lo:[0,1] neg_hi:[0,1]
	v_pk_mul_f32 v[48:49], v[18:19], v[90:91]
	v_pk_add_f32 v[76:77], v[56:57], v[50:51]
	v_lshlrev_b32_e32 v51, 16, v70
	v_lshlrev_b32_e32 v50, 16, v60
	v_pk_mov_b32 v[54:55], v[50:51], v[50:51] op_sel:[1,0]
	v_fma_f32 v89, v79, s2, -v69
	v_fma_f32 v92, v78, s2, -v68
	v_add_f32_e32 v48, v14, v48
	v_mov_b32_e32 v68, v91
	v_mov_b32_e32 v69, v55
	v_add_f32_e32 v56, v48, v49
	v_pk_mul_f32 v[48:49], v[28:29], v[68:69]
	v_fma_f32 v88, v76, s2, -v58
	v_add_f32_e32 v48, v80, v48
	v_add_f32_e32 v55, v48, v49
	v_pk_mul_f32 v[48:49], v[28:29], v[50:51]
	v_mov_b32_e32 v72, v47
	v_add_f32_e32 v48, v56, v48
	v_add_f32_e32 v90, v48, v49
	v_pk_mul_f32 v[48:49], v[30:31], v[46:47]
	v_fma_f32 v87, v77, s2, -v59
	v_add_f32_e32 v46, v15, v48
	v_add_f32_e32 v58, v46, v49
	v_and_b32_e32 v49, 0xffff0000, v70
	v_and_b32_e32 v48, 0xffff0000, v60
	v_pk_mov_b32 v[56:57], v[48:49], v[48:49] op_sel:[1,0]
	v_mov_b32_e32 v74, v45
	v_mov_b32_e32 v73, v57
	v_pk_mul_f32 v[46:47], v[10:11], v[72:73]
	v_mov_b32_e32 v70, v85
	v_add_f32_e32 v46, v81, v46
	v_add_f32_e32 v46, v46, v47
	v_cvt_pk_bf16_f32 v80, v55, v46
	v_pk_mul_f32 v[46:47], v[10:11], v[48:49]
	s_nop 0
	v_add_f32_e32 v46, v58, v46
	v_add_f32_e32 v55, v46, v47
	v_pk_mul_f32 v[46:47], v[20:21], v[44:45]
	s_nop 0
	v_add_f32_e32 v44, v16, v46
	v_add_f32_e32 v57, v44, v47
	v_lshlrev_b32_e32 v47, 16, v71
	v_lshlrev_b32_e32 v46, 16, v61
	v_pk_mov_b32 v[58:59], v[46:47], v[46:47] op_sel:[1,0]
	s_nop 0
	v_mov_b32_e32 v75, v59
	v_pk_mul_f32 v[44:45], v[24:25], v[74:75]
	s_nop 0
	v_add_f32_e32 v44, v82, v44
	v_add_f32_e32 v59, v44, v45
	v_pk_mul_f32 v[44:45], v[24:25], v[46:47]
	s_nop 0
	v_add_f32_e32 v44, v57, v44
	v_add_f32_e32 v57, v44, v45
	v_pk_mul_f32 v[44:45], v[26:27], v[84:85]
	s_nop 0
	v_add_f32_e32 v44, v17, v44
	v_add_f32_e32 v84, v44, v45
	v_and_b32_e32 v45, 0xffff0000, v71
	v_and_b32_e32 v44, 0xffff0000, v61
	v_pk_mov_b32 v[60:61], v[44:45], v[44:45] op_sel:[1,0]
	s_nop 0
	v_mov_b32_e32 v71, v61
	v_pk_mul_f32 v[82:83], v[12:13], v[70:71]
	s_nop 0
	v_add_f32_e32 v61, v86, v82
	v_add_co_u32_e32 v82, vcc, s12, v40
	v_add_f32_e32 v61, v61, v83
	s_nop 0
	v_addc_co_u32_e32 v83, vcc, 0, v41, vcc
	v_cvt_pk_bf16_f32 v81, v59, v61
	global_store_dwordx2 v[82:83], v[80:81], off
	v_add_co_u32_e32 v82, vcc, s13, v40
	v_cvt_pk_bf16_f32 v80, v87, v88
	v_cvt_pk_bf16_f32 v81, v89, v92
	s_nop 1
	v_addc_co_u32_e32 v83, vcc, 0, v41, vcc
	global_store_dwordx2 v[82:83], v[80:81], off
	v_pk_mul_f32 v[80:81], v[12:13], v[44:45]
	v_add_co_u32_e32 v82, vcc, s74, v40
	v_add_f32_e32 v59, v84, v80
	v_add_f32_e32 v59, v59, v81
	v_cvt_pk_bf16_f32 v80, v90, v55
	v_cvt_pk_bf16_f32 v81, v57, v59
	v_addc_co_u32_e32 v83, vcc, 0, v41, vcc
	global_store_dwordx2 v[82:83], v[80:81], off
	v_and_b32_e32 v80, 0xffff0000, v34
	v_lshlrev_b32_e32 v81, 16, v34
	v_and_b32_e32 v82, 0xffff0000, v35
	v_lshlrev_b32_e32 v83, 16, v35
	v_pk_add_f32 v[64:65], v[80:81], v[64:65] neg_lo:[0,1] neg_hi:[0,1]
	v_pk_add_f32 v[62:63], v[82:83], v[62:63] neg_lo:[0,1] neg_hi:[0,1]
	v_pk_add_f32 v[64:65], v[76:77], v[64:65]
	v_pk_add_f32 v[62:63], v[78:79], v[62:63]
	v_fma_f32 v55, v65, s2, -v81
	v_fma_f32 v57, v64, s2, -v80
	v_fma_f32 v59, v63, s2, -v83
	v_fma_f32 v61, v62, s2, -v82
	v_cvt_pk_bf16_f32 v76, v55, v57
	v_cvt_pk_bf16_f32 v77, v59, v61
	v_lshlrev_b32_e32 v55, 16, v42
	v_and_b32_e32 v57, 0xffff0000, v42
	v_lshlrev_b32_e32 v59, 16, v43
	v_and_b32_e32 v61, 0xffff0000, v43
	v_pk_mul_f32 v[42:43], v[18:19], v[68:69]
	v_add_co_u32_e32 v78, vcc, s84, v40
	v_add_f32_e32 v42, v14, v42
	v_add_f32_e32 v68, v42, v43
	v_pk_mul_f32 v[42:43], v[28:29], v[54:55]
	v_addc_co_u32_e32 v79, vcc, 0, v41, vcc
	v_add_f32_e32 v42, v68, v42
	v_add_f32_e32 v54, v42, v43
	v_pk_mul_f32 v[42:43], v[30:31], v[72:73]
	global_store_dwordx2 v[78:79], v[76:77], off
	v_add_f32_e32 v42, v15, v42
	v_add_f32_e32 v68, v42, v43
	v_pk_mul_f32 v[42:43], v[10:11], v[56:57]
	v_mov_b32_e32 v78, v59
	v_add_f32_e32 v42, v68, v42
	v_add_f32_e32 v56, v42, v43
	v_pk_mul_f32 v[42:43], v[20:21], v[74:75]
	v_mov_b32_e32 v80, v57
	v_add_f32_e32 v42, v16, v42
	v_add_f32_e32 v68, v42, v43
	v_pk_mul_f32 v[42:43], v[24:25], v[58:59]
	v_mov_b32_e32 v86, v55
	v_add_f32_e32 v42, v68, v42
	v_add_f32_e32 v58, v42, v43
	v_pk_mul_f32 v[42:43], v[26:27], v[70:71]
	v_and_b32_e32 v70, 0xffff0000, v33
	v_add_f32_e32 v42, v17, v42
	v_add_f32_e32 v68, v42, v43
	v_pk_mul_f32 v[42:43], v[12:13], v[60:61]
	v_lshlrev_b32_e32 v71, 16, v33
	v_add_f32_e32 v42, v68, v42
	v_add_co_u32_e32 v68, vcc, s85, v40
	v_add_f32_e32 v43, v42, v43
	s_nop 0
	v_addc_co_u32_e32 v69, vcc, 0, v41, vcc
	v_cvt_pk_bf16_f32 v42, v54, v56
	v_cvt_pk_bf16_f32 v43, v58, v43
	global_store_dwordx2 v[68:69], v[42:43], off
	v_and_b32_e32 v68, 0xffff0000, v32
	v_lshlrev_b32_e32 v69, 16, v32
	v_pk_add_f32 v[42:43], v[68:69], v[66:67] neg_lo:[0,1] neg_hi:[0,1]
	v_pk_add_f32 v[52:53], v[70:71], v[52:53] neg_lo:[0,1] neg_hi:[0,1]
	v_add_co_u32_e32 v40, vcc, s77, v40
	v_pk_add_f32 v[42:43], v[64:65], v[42:43]
	v_pk_add_f32 v[52:53], v[62:63], v[52:53]
	v_addc_co_u32_e32 v41, vcc, 0, v41, vcc
	v_fma_f32 v54, v43, s2, -v69
	v_fma_f32 v56, v42, s2, -v68
	v_fma_f32 v58, v53, s2, -v71
	v_fma_f32 v60, v52, s2, -v70
	v_cvt_pk_bf16_f32 v62, v54, v56
	v_cvt_pk_bf16_f32 v63, v58, v60
	global_store_dwordx2 v[40:41], v[62:63], off
	v_mov_b32_e32 v62, v61
	s_cbranch_scc0 .LBB0_368
	s_branch .LBB0_339

; #define LAS __attribute__((address_space(3)))
; template <class MapF>
; __device__ __forceinline__ void strip_quant(const float* W, int ldw, unsigned char* W8o, float* cso, int nstrips, int s0, int sstride, LAS unsigned char* lds, int lane, int wave, const MapF map) {
;     LAS unsigned char* sbuf = lds; LAS float* red = (LAS float*)(lds + RING_BYTES + 8192);
;     const int nn = lane & 15, kh = lane >> 4;
;     const float s16 = (kh & 1) ? -1.f : 1.f, s32 = (kh & 2) ? -0.125f : 0.125f;
;     float va[16], vb[16];
;     if (s0 >= nstrips) return;
;     int n0, drow0; map(s0, n0, drow0);
;     const float* wp = W + (size_t)(512 * wave + 16 * kh) * ldw + n0 + nn;
; #pragma unroll
;     for (int i = 0; i < 16; ++i) { va[i] = wp[(size_t)i * ldw]; vb[i] = wp[(size_t)(64 + i) * ldw]; }
.LBB0_721:
	s_mov_b64 s[0:1], s[78:79]
	s_add_u32 s40, s0, 0xc0000
	s_addc_u32 s41, s1, 0
	s_add_u32 s48, s0, 0x4ce00000
	s_addc_u32 s49, s1, 0
	s_add_u32 s50, s0, 0x4ce10000
	s_addc_u32 s51, s1, 0
	s_add_u32 s42, s0, 0x23a00000
	s_addc_u32 s43, s1, 0
	s_add_u32 s38, s0, 0x48e00000
	s_addc_u32 s39, s1, 0
	s_cmp_lt_i32 s28, 10
	s_cselect_b64 s[0:1], -1, 0
	s_cmp_gt_i32 s29, 9
	s_cselect_b64 s[2:3], -1, 0
	s_and_b64 s[0:1], s[0:1], s[2:3]
	s_andn2_b64 vcc, exec, s[0:1]
	s_cbranch_vccnz .LBB0_831
	v_readlane_b32 s0, v249, 38
	v_readlane_b32 s1, v249, 39
	s_lshl_b32 s1, s0, 14
	s_waitcnt vmcnt(0)
	v_mov_b32_e32 v1, 0xbe000000
	v_mov_b32_e32 v2, 0x3e000000
	v_cmp_gt_u32_e64 s[2:3], 32, v178
	s_mov_b32 s0, 0x3e000000
	s_cmpk_gt_i32 s34, 0x55f
	v_cndmask_b32_e64 v34, v1, v2, s[2:3]
	s_cbranch_scc1 .LBB0_737
	v_readlane_b32 s52, v249, 43
	v_readlane_b32 s60, v249, 51
	v_readlane_b32 s61, v249, 52
	v_readlane_b32 s62, v249, 53
	v_readlane_b32 s63, v249, 54
	v_readlane_b32 s64, v249, 55
	v_readlane_b32 s65, v249, 56
	v_readlane_b32 s66, v249, 57
	v_readlane_b32 s67, v249, 58
	s_mov_b64 s[20:21], s[60:61]
	s_mov_b64 s[22:23], s[62:63]
	v_and_b32_e32 v1, 48, v0
	v_readlane_b32 s4, v249, 38
	v_mov_b32_e32 v2, s22
	v_mov_b32_e32 v3, s23
	v_readlane_b32 s5, v249, 39
	v_lshl_or_b32 v18, s4, 9, v1
	s_mov_b32 s4, 0x15800
	v_mad_i64_i32 v[22:23], s[4:5], v18, s4, v[2:3]
	v_readlane_b32 s4, v249, 37
	s_add_i32 s7, 0, 0x22000
	s_and_b32 s6, s4, 0xffffffc0
	s_cmp_lt_u32 s4, 64
	v_readlane_b32 s53, v249, 44
	s_cselect_b64 s[22:23], -1, 0
	s_lshl_b32 s52, s34, 4
	v_and_b32_e32 v36, 15, v0
	s_ashr_i32 s53, s52, 31
	v_mov_b32_e32 v21, 0
	v_lshlrev_b32_e32 v20, 2, v36
	v_lshl_add_u64 v[2:3], s[52:53], 2, v[22:23]
	v_lshl_add_u64 v[38:39], v[2:3], 0, v[20:21]
	s_mov_b32 s4, 0x560000
	v_add_co_u32_e32 v2, vcc, s4, v38
	s_mov_b32 s4, 0x575000
	s_nop 0
	v_addc_co_u32_e32 v3, vcc, 0, v39, vcc
	v_add_co_u32_e32 v4, vcc, s4, v38
	s_mov_b32 s4, 0x58b000
	s_nop 0
	v_addc_co_u32_e32 v5, vcc, 0, v39, vcc
	v_add_co_u32_e32 v6, vcc, s4, v38
	s_mov_b32 s4, 0x5a0000
	s_nop 0
	v_addc_co_u32_e32 v7, vcc, 0, v39, vcc
	v_add_co_u32_e32 v8, vcc, s4, v38
	s_mov_b32 s4, 0x5b6000
	s_nop 0
	v_addc_co_u32_e32 v9, vcc, 0, v39, vcc
	v_add_co_u32_e32 v10, vcc, s4, v38
	s_mov_b32 s4, 0x5cb000
	s_nop 0
	v_addc_co_u32_e32 v11, vcc, 0, v39, vcc
	v_add_co_u32_e32 v12, vcc, s4, v38
	s_mov_b32 s4, 0x5e1000
	s_nop 0
	v_addc_co_u32_e32 v13, vcc, 0, v39, vcc
	v_add_co_u32_e32 v14, vcc, s4, v38
	s_mov_b32 s4, 0x5f6000
	s_nop 0
	v_addc_co_u32_e32 v15, vcc, 0, v39, vcc
	v_add_co_u32_e32 v16, vcc, s4, v38
	s_mov_b32 s4, 0x60c000
	s_nop 0
	v_addc_co_u32_e32 v17, vcc, 0, v39, vcc
	global_load_dword v44, v[2:3], off nt
	global_load_dword v45, v[4:5], off offset:2048 nt
	global_load_dword v48, v[6:7], off nt
	global_load_dword v49, v[8:9], off offset:2048 nt
	global_load_dword v50, v[10:11], off nt
	global_load_dword v51, v[12:13], off offset:2048 nt
	global_load_dword v52, v[14:15], off nt
	global_load_dword v53, v[16:17], off offset:2048 nt
	v_add_co_u32_e32 v2, vcc, s4, v38
	s_mov_b32 s4, 0x621000
	s_nop 0
	v_addc_co_u32_e32 v3, vcc, 0, v39, vcc
	v_add_co_u32_e32 v4, vcc, s4, v38
	s_mov_b32 s4, 0x637000
	s_nop 0
	v_addc_co_u32_e32 v5, vcc, 0, v39, vcc
	v_add_co_u32_e32 v6, vcc, s4, v38
	s_mov_b32 s4, 0x64c000
	s_nop 0
	v_addc_co_u32_e32 v7, vcc, 0, v39, vcc
	v_add_co_u32_e32 v8, vcc, s4, v38
	s_mov_b32 s4, 0x662000
	s_nop 0
	v_addc_co_u32_e32 v9, vcc, 0, v39, vcc
	v_add_co_u32_e32 v10, vcc, s4, v38
	s_mov_b32 s4, 0x677000
	s_nop 0
	v_addc_co_u32_e32 v11, vcc, 0, v39, vcc
	v_add_co_u32_e32 v12, vcc, s4, v38
	s_mov_b32 s4, 0x68d000
	s_nop 0
	v_addc_co_u32_e32 v13, vcc, 0, v39, vcc
	v_add_co_u32_e32 v14, vcc, s4, v38
	s_mov_b32 s4, 0x6a2000
	s_nop 0
	v_addc_co_u32_e32 v15, vcc, 0, v39, vcc
	v_add_co_u32_e32 v16, vcc, s4, v38
	s_mov_b32 s4, 0x15000
	s_nop 0
	v_addc_co_u32_e32 v17, vcc, 0, v39, vcc
	global_load_dword v54, v[2:3], off nt
	global_load_dword v55, v[4:5], off offset:2048 nt
	global_load_dword v56, v[6:7], off nt
	global_load_dword v57, v[8:9], off offset:2048 nt
	global_load_dword v58, v[10:11], off nt
	global_load_dword v59, v[12:13], off offset:2048 nt
	global_load_dword v60, v[14:15], off nt
	global_load_dword v61, v[16:17], off offset:2048 nt
	v_add_co_u32_e32 v2, vcc, s4, v38
	s_mov_b32 s4, 0x2b000
	s_nop 0
; template <class MapF>
; __device__ __forceinline__ void strip_quant(const float* W, int ldw, unsigned char* W8o, float* cso, int nstrips, int s0, int sstride, LAS unsigned char* lds, int lane, int wave, const MapF map) {
;     ...
;     const int nn = lane & 15, kh = lane >> 4;
;     const float s16 = (kh & 1) ? -1.f : 1.f, s32 = (kh & 2) ? -0.125f : 0.125f;
;     float va[16], vb[16];
;     if (s0 >= nstrips) return;
;     int n0, drow0; map(s0, n0, drow0);
;     const float* wp = W + (size_t)(512 * wave + 16 * kh) * ldw + n0 + nn;
; #pragma unroll
;     for (int i = 0; i < 16; ++i) { va[i] = wp[(size_t)i * ldw]; vb[i] = wp[(size_t)(64 + i) * ldw]; }
	v_addc_co_u32_e32 v3, vcc, 0, v39, vcc
	v_add_co_u32_e32 v4, vcc, s4, v38
	s_mov_b32 s4, 0x40000
	s_nop 0
	v_addc_co_u32_e32 v5, vcc, 0, v39, vcc
	v_add_co_u32_e32 v6, vcc, s4, v38
	s_mov_b32 s4, 0x56000
	s_nop 0
	v_addc_co_u32_e32 v7, vcc, 0, v39, vcc
	v_add_co_u32_e32 v8, vcc, s4, v38
	s_mov_b32 s4, 0x6b000
	s_nop 0
	v_addc_co_u32_e32 v9, vcc, 0, v39, vcc
	v_add_co_u32_e32 v10, vcc, s4, v38
	s_mov_b32 s4, 0x81000
	s_nop 0
	v_addc_co_u32_e32 v11, vcc, 0, v39, vcc
	v_add_co_u32_e32 v12, vcc, s4, v38
	s_mov_b32 s4, 0x96000
	s_nop 0
	v_addc_co_u32_e32 v13, vcc, 0, v39, vcc
	v_add_co_u32_e32 v14, vcc, s4, v38
	s_mov_b32 s4, 0xac000
	s_nop 0
	v_addc_co_u32_e32 v15, vcc, 0, v39, vcc
	v_add_co_u32_e32 v16, vcc, s4, v38
	s_mov_b32 s4, 0xc1000
	s_nop 0
	v_addc_co_u32_e32 v17, vcc, 0, v39, vcc
	global_load_dword v3, v[2:3], off offset:2048 nt
	s_nop 0
	global_load_dword v4, v[4:5], off nt
	s_nop 0
	global_load_dword v5, v[6:7], off offset:2048 nt
	s_nop 0
	global_load_dword v6, v[8:9], off nt
	global_load_dword v7, v[10:11], off offset:2048 nt
	s_nop 0
	global_load_dword v8, v[12:13], off nt
	global_load_dword v9, v[14:15], off offset:2048 nt
	global_load_dword v10, v[16:17], off nt
	v_add_co_u32_e32 v12, vcc, s4, v38
	s_mov_b32 s4, 0xd7000
	s_nop 0
	v_addc_co_u32_e32 v13, vcc, 0, v39, vcc
	v_add_co_u32_e32 v14, vcc, s4, v38
	s_mov_b32 s4, 0xec000
	s_nop 0
	v_addc_co_u32_e32 v15, vcc, 0, v39, vcc
	v_add_co_u32_e32 v16, vcc, s4, v38
	s_mov_b32 s4, 0x102000
	s_nop 0
	v_addc_co_u32_e32 v17, vcc, 0, v39, vcc
	v_add_co_u32_e32 v24, vcc, s4, v38
	s_mov_b32 s4, 0x117000
	s_nop 0
	v_addc_co_u32_e32 v25, vcc, 0, v39, vcc
	v_add_co_u32_e32 v26, vcc, s4, v38
	s_mov_b32 s4, 0x12d000
	s_nop 0
	v_addc_co_u32_e32 v27, vcc, 0, v39, vcc
	v_add_co_u32_e32 v28, vcc, s4, v38
	s_mov_b32 s4, 0x142000
	s_nop 0
	v_addc_co_u32_e32 v29, vcc, 0, v39, vcc
	v_add_co_u32_e32 v30, vcc, s4, v38
	v_and_b32_e32 v1, 16, v0
	s_nop 0
	v_addc_co_u32_e32 v31, vcc, 0, v39, vcc
	global_load_dword v2, v[38:39], off nt
	global_load_dword v11, v[12:13], off offset:2048 nt
	s_nop 0
	global_load_dword v12, v[14:15], off nt
	global_load_dword v13, v[16:17], off offset:2048 nt
	s_nop 0
	global_load_dword v14, v[24:25], off nt
	global_load_dword v15, v[26:27], off offset:2048 nt
	global_load_dword v16, v[28:29], off nt
	global_load_dword v17, v[30:31], off offset:2048 nt
	v_mbcnt_lo_u32_b32 v29, -1, 0
	v_mbcnt_hi_u32_b32 v29, -1, v29
	v_cmp_gt_u32_e64 s[4:5], 16, v178
	v_and_b32_e32 v31, 64, v29
	v_cmp_eq_u32_e32 vcc, 0, v1
	v_lshl_add_u64 v[42:43], v[22:23], 0, v[20:21]
	v_lshl_add_u32 v21, v178, 2, s7
	v_add_u32_e32 v1, s7, v20
	s_and_b64 s[22:23], s[4:5], s[22:23]
	s_and_b32 s7, s52, 0x70
	v_xor_b32_e32 v30, 16, v29
	v_add_u32_e32 v31, 64, v31
	v_cndmask_b32_e64 v40, -1.0, 1.0, vcc
	s_cmpk_gt_i32 s34, 0x2af
	v_cmp_lt_i32_e32 vcc, v30, v31
	v_ashrrev_i32_e32 v19, 31, v18
	s_cselect_b32 s11, 0xffffd500, 0
	v_cndmask_b32_e32 v30, v29, v30, vcc
	v_or_b32_e32 v20, v18, v36
	s_cselect_b32 s8, 0x80, 0
	s_add_i32 s11, s11, s52
	v_lshlrev_b32_e32 v64, 2, v30
	v_xor_b32_e32 v30, 32, v29
	v_lshl_add_u64 v[46:47], s[96:97], 0, v[18:19]
	v_lshlrev_b32_e32 v18, 5, v178
	v_lshlrev_b32_e32 v37, 5, v20
	s_or_b32 s7, s7, s8
	s_lshl_b32 s8, s11, 1
	v_cmp_lt_i32_e32 vcc, v30, v31
	v_and_b32_e32 v18, 0x600, v18
	v_lshlrev_b32_e32 v22, 5, v36
	v_or_b32_e32 v20, 0x800, v37
	v_or_b32_e32 v23, 0x1000, v37
	v_or_b32_e32 v24, 0x1800, v37
	v_or_b32_e32 v25, 0x2000, v37
	v_or_b32_e32 v26, 0x2800, v37
	v_or_b32_e32 v27, 0x3000, v37
	v_or_b32_e32 v28, 0x3800, v37
	s_and_b32 s8, s8, 0xffffff00
	v_cndmask_b32_e32 v29, v29, v30, vcc
	v_add_u32_e32 v18, s1, v18
	s_or_b32 s16, s7, s8
	v_lshlrev_b32_e32 v65, 2, v29
	v_mov_b32_e32 v41, v40
	v_mov_b32_e32 v35, v34
	v_add3_u32 v66, v18, v22, 0
	v_add_u32_e32 v67, s6, v21
	s_mov_b32 s6, 0xda24260
	s_mov_b32 s7, 0x42fe0000
	s_mov_b32 s8, 0xc0c0400
	s_mov_b32 s11, 0x5040100
	v_add_u32_e32 v68, 0, v20
	v_add_u32_e32 v69, 0, v23
	v_add_u32_e32 v70, 0, v24
	v_add_u32_e32 v71, 0, v25
	v_add_u32_e32 v72, 0, v26
	v_add_u32_e32 v73, 0, v27
	v_add_u32_e32 v74, 0, v28
	s_mov_b32 s12, s34
	v_readlane_b32 s54, v249, 45
	v_readlane_b32 s55, v249, 46
	v_readlane_b32 s56, v249, 47
	v_readlane_b32 s57, v249, 48
	v_readlane_b32 s58, v249, 49
	v_readlane_b32 s59, v249, 50
	s_mov_b64 s[24:25], s[64:65]
	s_mov_b64 s[26:27], s[66:67]
	s_branch .LBB0_725

; #define SQ_LOAD(v, blk) do { _Pragma("unroll") for (int i = 0; i < 16; ++i) v[i] = wp[(size_t)(64 * (blk) + i) * ldw]; } while (0)
; template <class MapF>
; __device__ __forceinline__ void strip_quant(const float* W, int ldw, unsigned char* W8o, float* cso, int nstrips, int s0, int sstride, LAS unsigned char* lds, int lane, int wave, const MapF map) {
;     ...
; #pragma unroll 1
;         for (int blk = 0; blk < 8; blk += 2) {
;             if (blk != 0) SQ_LOAD(vb, blk + 1);
;             SQ_FIN(va, blk);
;             if (blk + 2 < 8) SQ_LOAD(va, blk + 2);
;             SQ_FIN(vb, blk + 1);
;         }
.LBB0_727:
	s_cmp_eq_u32 s52, 0
	v_lshl_add_u64 v[62:63], v[38:39], 0, s[52:53]
	s_cbranch_scc1 .LBB0_729
	v_add_co_u32_e32 v18, vcc, 0x560000, v62
	s_nop 1
	v_addc_co_u32_e32 v19, vcc, 0, v63, vcc
	v_add_co_u32_e32 v20, vcc, 0x575000, v62
	s_nop 1
	v_addc_co_u32_e32 v21, vcc, 0, v63, vcc
	v_add_co_u32_e32 v22, vcc, 0x58b000, v62
	s_nop 1
	v_addc_co_u32_e32 v23, vcc, 0, v63, vcc
	v_add_co_u32_e32 v24, vcc, 0x5a0000, v62
	s_nop 1
	v_addc_co_u32_e32 v25, vcc, 0, v63, vcc
	v_add_co_u32_e32 v26, vcc, 0x5b6000, v62
	s_nop 1
	v_addc_co_u32_e32 v27, vcc, 0, v63, vcc
	v_add_co_u32_e32 v28, vcc, 0x5cb000, v62
	s_nop 1
	v_addc_co_u32_e32 v29, vcc, 0, v63, vcc
	v_add_co_u32_e32 v30, vcc, 0x5e1000, v62
	s_nop 1
	v_addc_co_u32_e32 v31, vcc, 0, v63, vcc
	v_add_co_u32_e32 v32, vcc, 0x5f6000, v62
	s_nop 1
	v_addc_co_u32_e32 v33, vcc, 0, v63, vcc
	global_load_dword v44, v[18:19], off nt
	global_load_dword v45, v[20:21], off offset:2048 nt
	global_load_dword v48, v[22:23], off nt
	global_load_dword v49, v[24:25], off offset:2048 nt
	global_load_dword v50, v[26:27], off nt
	global_load_dword v51, v[28:29], off offset:2048 nt
	global_load_dword v52, v[30:31], off nt
	global_load_dword v53, v[32:33], off offset:2048 nt
	v_add_co_u32_e32 v18, vcc, 0x60c000, v62
	s_nop 1
	v_addc_co_u32_e32 v19, vcc, 0, v63, vcc
	v_add_co_u32_e32 v20, vcc, 0x621000, v62
	s_nop 1
	v_addc_co_u32_e32 v21, vcc, 0, v63, vcc
	v_add_co_u32_e32 v22, vcc, 0x637000, v62
	s_nop 1
	v_addc_co_u32_e32 v23, vcc, 0, v63, vcc
	v_add_co_u32_e32 v24, vcc, 0x64c000, v62
	s_nop 1
	v_addc_co_u32_e32 v25, vcc, 0, v63, vcc
	v_add_co_u32_e32 v26, vcc, 0x662000, v62
	s_nop 1
	v_addc_co_u32_e32 v27, vcc, 0, v63, vcc
	v_add_co_u32_e32 v28, vcc, 0x677000, v62
	s_nop 1
	v_addc_co_u32_e32 v29, vcc, 0, v63, vcc
	v_add_co_u32_e32 v30, vcc, 0x68d000, v62
	s_nop 1
	v_addc_co_u32_e32 v31, vcc, 0, v63, vcc
	v_add_co_u32_e32 v32, vcc, 0x6a2000, v62
	s_nop 1
	v_addc_co_u32_e32 v33, vcc, 0, v63, vcc
	global_load_dword v54, v[18:19], off nt
	global_load_dword v55, v[20:21], off offset:2048 nt
	global_load_dword v56, v[22:23], off nt
	global_load_dword v57, v[24:25], off offset:2048 nt
	global_load_dword v58, v[26:27], off nt
	global_load_dword v59, v[28:29], off offset:2048 nt
	global_load_dword v60, v[30:31], off nt
	global_load_dword v61, v[32:33], off offset:2048 nt
.LBB0_729:
	s_waitcnt vmcnt(0)
	v_mov_b32_e32 v24, v10
	v_mov_b32_e32 v25, v14
	v_mov_b32_e32 v26, v11
	v_mov_b32_e32 v27, v15
	v_pk_add_f32 v[24:25], v[24:25], v[26:27]
	v_mov_b32_e32 v26, v12
	v_mov_b32_e32 v27, v16
	v_mov_b32_e32 v28, v13
	v_mov_b32_e32 v29, v17
	v_pk_add_f32 v[26:27], v[26:27], v[28:29]
	v_mov_b32_e32 v28, v2
	v_mov_b32_e32 v29, v10
	v_mov_b32_e32 v10, v3
	v_mov_b32_e32 v18, v2
	v_mov_b32_e32 v19, v6
	v_mov_b32_e32 v20, v3
	v_mov_b32_e32 v21, v7
	v_pk_add_f32 v[2:3], v[28:29], v[10:11] neg_lo:[0,1] neg_hi:[0,1]
	v_mov_b32_e32 v10, v4
	v_mov_b32_e32 v11, v12
	v_mov_b32_e32 v12, v5
	v_pk_add_f32 v[18:19], v[18:19], v[20:21]
	v_mov_b32_e32 v20, v4
	v_mov_b32_e32 v21, v8
	v_mov_b32_e32 v22, v5
	v_mov_b32_e32 v23, v9
	v_pk_add_f32 v[4:5], v[10:11], v[12:13] neg_lo:[0,1] neg_hi:[0,1]
	v_mov_b32_e32 v10, v6
	v_mov_b32_e32 v11, v14
	v_mov_b32_e32 v14, v7
	v_pk_add_f32 v[20:21], v[20:21], v[22:23]
	v_pk_add_f32 v[6:7], v[10:11], v[14:15] neg_lo:[0,1] neg_hi:[0,1]
	v_mov_b32_e32 v10, v8
	v_mov_b32_e32 v11, v16
	v_mov_b32_e32 v16, v9
	v_pk_add_f32 v[8:9], v[10:11], v[16:17] neg_lo:[0,1] neg_hi:[0,1]
	v_mov_b32_e32 v14, v18
	v_mov_b32_e32 v15, v2
	v_mov_b32_e32 v16, v20
	v_mov_b32_e32 v17, v4
	v_pk_add_f32 v[22:23], v[18:19], v[20:21] neg_lo:[0,1] neg_hi:[0,1]
	v_pk_add_f32 v[10:11], v[2:3], v[4:5] neg_lo:[0,1] neg_hi:[0,1]
	v_pk_add_f32 v[12:13], v[6:7], v[8:9] neg_lo:[0,1] neg_hi:[0,1]
	v_pk_add_f32 v[14:15], v[14:15], v[16:17]
	v_pk_mov_b32 v[16:17], v[18:19], v[6:7] op_sel:[1,0]
	v_pk_mov_b32 v[18:19], v[20:21], v[8:9] op_sel:[1,0]
	v_mov_b32_e32 v2, v24
	v_mov_b32_e32 v4, v26
	v_mov_b32_e32 v6, v25
	v_mov_b32_e32 v8, v27
	v_pk_add_f32 v[16:17], v[16:17], v[18:19]
	v_pk_add_f32 v[2:3], v[2:3], v[4:5]
	v_pk_add_f32 v[4:5], v[6:7], v[8:9]
	v_pk_add_f32 v[24:25], v[24:25], v[26:27] neg_lo:[0,1] neg_hi:[0,1]
	v_pk_add_f32 v[6:7], v[14:15], v[16:17]
	v_pk_add_f32 v[8:9], v[2:3], v[4:5]
	v_pk_add_f32 v[28:29], v[22:23], v[22:23] op_sel:[0,1] op_sel_hi:[1,0] neg_lo:[0,1] neg_hi:[0,1]
	v_pk_add_f32 v[26:27], v[10:11], v[12:13] neg_lo:[0,1] neg_hi:[0,1]
	v_mov_b32_e32 v32, v22
	v_mov_b32_e32 v33, v10
	v_pk_mov_b32 v[22:23], v[22:23], v[12:13] op_sel:[1,0]
	v_mov_b32_e32 v10, v24
	v_mov_b32_e32 v12, v25
	v_pk_add_f32 v[18:19], v[6:7], v[8:9]
	v_pk_add_f32 v[32:33], v[32:33], v[22:23]
	v_pk_add_f32 v[10:11], v[10:11], v[12:13]
	ds_bpermute_b32 v20, v64, v18
	ds_bpermute_b32 v21, v64, v19
	v_pk_add_f32 v[12:13], v[32:33], v[10:11]
	v_pk_add_f32 v[14:15], v[14:15], v[16:17] neg_lo:[0,1] neg_hi:[0,1]
	v_pk_add_f32 v[2:3], v[2:3], v[4:5] neg_lo:[0,1] neg_hi:[0,1]
	ds_bpermute_b32 v22, v64, v12
	ds_bpermute_b32 v23, v64, v13
	v_pk_add_f32 v[4:5], v[14:15], v[2:3]
	ds_bpermute_b32 v16, v64, v4
	ds_bpermute_b32 v17, v64, v5
	s_waitcnt lgkmcnt(0)
	v_pk_fma_f32 v[18:19], v[18:19], v[40:41], v[20:21]
	ds_bpermute_b32 v20, v65, v18
	ds_bpermute_b32 v21, v65, v19
	v_pk_fma_f32 v[12:13], v[12:13], v[40:41], v[22:23]
	ds_bpermute_b32 v22, v65, v12
	ds_bpermute_b32 v23, v65, v13
	v_pk_fma_f32 v[4:5], v[4:5], v[40:41], v[16:17]
	ds_bpermute_b32 v16, v65, v4
	ds_bpermute_b32 v17, v65, v5
	v_pk_add_f32 v[30:31], v[24:25], v[24:25] op_sel:[0,1] op_sel_hi:[1,0] neg_lo:[0,1] neg_hi:[0,1]
	s_waitcnt lgkmcnt(4)
; #define SQ_LOAD(v, blk) do { _Pragma("unroll") for (int i = 0; i < 16; ++i) v[i] = wp[(size_t)(64 * (blk) + i) * ldw]; } while (0)
; template <class MapF>
; __device__ __forceinline__ void strip_quant(const float* W, int ldw, unsigned char* W8o, float* cso, int nstrips, int s0, int sstride, LAS unsigned char* lds, int lane, int wave, const MapF map) {
;     ...
; #pragma unroll 1
;         for (int blk = 0; blk < 8; blk += 2) {
;             if (blk != 0) SQ_LOAD(vb, blk + 1);
;             SQ_FIN(va, blk);
;             if (blk + 2 < 8) SQ_LOAD(va, blk + 2);
;             SQ_FIN(vb, blk + 1);
;         }
	v_pk_mul_f32 v[20:21], v[20:21], s[0:1] op_sel_hi:[1,0]
	v_mov_b32_e32 v29, v26
	v_pk_fma_f32 v[18:19], v[18:19], v[34:35], v[20:21]
	s_waitcnt lgkmcnt(2)
	v_pk_mul_f32 v[20:21], v[22:23], s[0:1] op_sel_hi:[1,0]
	v_mov_b32_e32 v31, v27
	v_pk_fma_f32 v[20:21], v[12:13], v[34:35], v[20:21]
	s_waitcnt lgkmcnt(0)
	v_pk_mul_f32 v[12:13], v[16:17], s[0:1] op_sel_hi:[1,0]
	v_pk_add_f32 v[16:17], v[28:29], v[30:31]
	ds_bpermute_b32 v24, v64, v16
	ds_bpermute_b32 v25, v64, v17
	v_pk_add_f32 v[6:7], v[6:7], v[8:9] neg_lo:[0,1] neg_hi:[0,1]
	ds_bpermute_b32 v8, v64, v6
	ds_bpermute_b32 v9, v64, v7
	v_pk_fma_f32 v[22:23], v[4:5], v[34:35], v[12:13]
	s_waitcnt lgkmcnt(2)
	v_pk_fma_f32 v[4:5], v[16:17], v[40:41], v[24:25]
	ds_bpermute_b32 v12, v65, v4
	ds_bpermute_b32 v13, v65, v5
	s_waitcnt lgkmcnt(2)
	v_pk_fma_f32 v[6:7], v[6:7], v[40:41], v[8:9]
	ds_bpermute_b32 v8, v65, v6
	ds_bpermute_b32 v9, v65, v7
	v_pk_add_f32 v[10:11], v[32:33], v[10:11] neg_lo:[0,1] neg_hi:[0,1]
	ds_bpermute_b32 v16, v64, v10
	ds_bpermute_b32 v17, v64, v11
	s_waitcnt lgkmcnt(4)
	v_pk_mul_f32 v[12:13], v[12:13], s[0:1] op_sel_hi:[1,0]
	v_pk_add_f32 v[2:3], v[14:15], v[2:3] neg_lo:[0,1] neg_hi:[0,1]
	v_pk_fma_f32 v[24:25], v[4:5], v[34:35], v[12:13]
	s_waitcnt lgkmcnt(2)
	v_pk_mul_f32 v[4:5], v[8:9], s[0:1] op_sel_hi:[1,0]
	ds_bpermute_b32 v8, v64, v2
	v_pk_fma_f32 v[26:27], v[6:7], v[34:35], v[4:5]
	s_waitcnt lgkmcnt(1)
	v_pk_fma_f32 v[4:5], v[10:11], v[40:41], v[16:17]
	ds_bpermute_b32 v9, v64, v3
	v_pk_add_f32 v[10:11], v[28:29], v[30:31] neg_lo:[0,1] neg_hi:[0,1]
	ds_bpermute_b32 v12, v64, v10
	ds_bpermute_b32 v13, v64, v11
	ds_bpermute_b32 v6, v65, v4
	ds_bpermute_b32 v7, v65, v5
	s_waitcnt lgkmcnt(4)
	v_pk_fma_f32 v[2:3], v[2:3], v[40:41], v[8:9]
	ds_bpermute_b32 v8, v65, v2
	ds_bpermute_b32 v9, v65, v3
	s_waitcnt lgkmcnt(4)
	v_pk_fma_f32 v[10:11], v[10:11], v[40:41], v[12:13]
	ds_bpermute_b32 v12, v65, v10
	ds_bpermute_b32 v13, v65, v11
	s_waitcnt lgkmcnt(4)
	v_pk_mul_f32 v[6:7], v[6:7], s[0:1] op_sel_hi:[1,0]
	s_cmp_gt_u32 s16, 5
	v_pk_fma_f32 v[28:29], v[4:5], v[34:35], v[6:7]
	s_waitcnt lgkmcnt(2)
	v_pk_mul_f32 v[4:5], v[8:9], s[0:1] op_sel_hi:[1,0]
	s_cselect_b64 s[54:55], -1, 0
	v_pk_fma_f32 v[30:31], v[2:3], v[34:35], v[4:5]
	s_waitcnt lgkmcnt(0)
	v_pk_mul_f32 v[2:3], v[12:13], s[0:1] op_sel_hi:[1,0]
	s_and_b64 vcc, exec, s[54:55]
	v_pk_fma_f32 v[32:33], v[10:11], v[34:35], v[2:3]
	v_cvt_pk_bf16_f32 v2, v18, v19
	v_cvt_pk_bf16_f32 v3, v20, v21
	v_cvt_pk_bf16_f32 v4, v22, v23
	v_cvt_pk_bf16_f32 v5, v24, v25
	v_cvt_pk_bf16_f32 v6, v26, v27
	v_cvt_pk_bf16_f32 v7, v28, v29
	v_cvt_pk_bf16_f32 v8, v30, v31
	s_nop 0
	v_cvt_pk_bf16_f32 v9, v32, v33
	ds_write_b128 v75, v[2:5]
	ds_write_b128 v75, v[6:9] offset:16
	v_mov_b64_e32 v[2:3], v[18:19]
	v_mov_b64_e32 v[4:5], v[20:21]
	v_mov_b64_e32 v[6:7], v[22:23]
	v_mov_b64_e32 v[8:9], v[24:25]
	v_mov_b64_e32 v[10:11], v[26:27]
	v_mov_b64_e32 v[12:13], v[28:29]
	v_mov_b64_e32 v[14:15], v[30:31]
	v_mov_b64_e32 v[16:17], v[32:33]
	s_cbranch_vccnz .LBB0_726
	v_add_co_u32_e32 v2, vcc, 0xac0000, v62
	s_nop 1
	v_addc_co_u32_e32 v3, vcc, 0, v63, vcc
	v_add_co_u32_e32 v4, vcc, 0xad5000, v62
	s_nop 1
	v_addc_co_u32_e32 v5, vcc, 0, v63, vcc
	v_add_co_u32_e32 v6, vcc, 0xaeb000, v62
	s_nop 1
	v_addc_co_u32_e32 v7, vcc, 0, v63, vcc
	v_add_co_u32_e32 v8, vcc, 0xb00000, v62
	s_nop 1
	v_addc_co_u32_e32 v9, vcc, 0, v63, vcc
	v_add_co_u32_e32 v10, vcc, 0xb16000, v62
	s_nop 1
	v_addc_co_u32_e32 v11, vcc, 0, v63, vcc
	v_add_co_u32_e32 v12, vcc, 0xb2b000, v62
	s_nop 1
	v_addc_co_u32_e32 v13, vcc, 0, v63, vcc
	v_add_co_u32_e32 v14, vcc, 0xb41000, v62
	s_nop 1
	v_addc_co_u32_e32 v15, vcc, 0, v63, vcc
	v_add_co_u32_e32 v16, vcc, 0xb56000, v62
	s_nop 1
	v_addc_co_u32_e32 v17, vcc, 0, v63, vcc
	global_load_dword v2, v[2:3], off nt
	s_nop 0
	global_load_dword v3, v[4:5], off offset:2048 nt
	s_nop 0
	global_load_dword v4, v[6:7], off nt
	global_load_dword v5, v[8:9], off offset:2048 nt
	s_nop 0
	global_load_dword v6, v[10:11], off nt
	global_load_dword v7, v[12:13], off offset:2048 nt
	global_load_dword v8, v[14:15], off nt
	global_load_dword v9, v[16:17], off offset:2048 nt
	v_add_co_u32_e32 v10, vcc, 0xb6c000, v62
	s_nop 1
	v_addc_co_u32_e32 v11, vcc, 0, v63, vcc
	v_add_co_u32_e32 v12, vcc, 0xb81000, v62
	s_nop 1
	v_addc_co_u32_e32 v13, vcc, 0, v63, vcc
	v_add_co_u32_e32 v14, vcc, 0xb97000, v62
	s_nop 1
	v_addc_co_u32_e32 v15, vcc, 0, v63, vcc
	v_add_co_u32_e32 v16, vcc, 0xbac000, v62
	s_nop 1
	v_addc_co_u32_e32 v17, vcc, 0, v63, vcc
	v_add_co_u32_e32 v78, vcc, 0xbc2000, v62
	s_nop 1
	v_addc_co_u32_e32 v79, vcc, 0, v63, vcc
	v_add_co_u32_e32 v80, vcc, 0xbd7000, v62
	s_nop 1
	v_addc_co_u32_e32 v81, vcc, 0, v63, vcc
	v_add_co_u32_e32 v82, vcc, 0xbed000, v62
	s_nop 1
	v_addc_co_u32_e32 v83, vcc, 0, v63, vcc
	v_add_co_u32_e32 v62, vcc, 0xc02000, v62
	s_nop 1
	v_addc_co_u32_e32 v63, vcc, 0, v63, vcc
	global_load_dword v10, v[10:11], off nt
	s_nop 0
	global_load_dword v11, v[12:13], off offset:2048 nt
	s_nop 0
	global_load_dword v12, v[14:15], off nt
	global_load_dword v13, v[16:17], off offset:2048 nt
	s_nop 0
	global_load_dword v14, v[78:79], off nt
	global_load_dword v15, v[80:81], off offset:2048 nt
	global_load_dword v16, v[82:83], off nt
	global_load_dword v17, v[62:63], off offset:2048 nt
	s_branch .LBB0_726

; template <class MapF>
; __device__ __forceinline__ void strip_quant(const float* W, int ldw, unsigned char* W8o, float* cso, int nstrips, int s0, int sstride, LAS unsigned char* lds, int lane, int wave, const MapF map) {
;     ...
;         cm = fmaxf(cm, __shfl_xor(cm, 16)); cm = fmaxf(cm, __shfl_xor(cm, 32));
;         if (kh == 0) red[wave * 16 + nn] = cm;
;         const int drow_cur = drow0;
;         if (strip + sstride < nstrips) { map(strip + sstride, n0, drow0); wp = W + (size_t)(512 * wave + 16 * kh) * ldw + n0 + nn;
; #pragma unroll
;             for (int i = 0; i < 16; ++i) { va[i] = wp[(size_t)i * ldw]; vb[i] = wp[(size_t)(64 + i) * ldw]; } }
.LBB0_733:
	s_or_b64 exec, exec, s[52:53]
	s_add_i32 s12, s12, s10
	s_cmpk_gt_i32 s12, 0x55f
	s_cselect_b64 s[52:53], -1, 0
	s_and_b64 vcc, exec, s[52:53]
	s_mov_b32 s16, s13
	s_cbranch_vccnz .LBB0_735
	s_lshl_b32 s54, s12, 4
	s_cmpk_gt_i32 s12, 0x2af
	s_cselect_b32 s17, 0xffffd500, 0
	s_cselect_b32 s16, 0x80, 0
	s_ashr_i32 s55, s54, 31
	v_lshl_add_u64 v[38:39], s[54:55], 2, v[42:43]
	s_waitcnt vmcnt(15)
	v_add_co_u32_e32 v2, vcc, 0x560000, v38
	s_add_i32 s17, s17, s54
	s_waitcnt vmcnt(14)
	v_addc_co_u32_e32 v3, vcc, 0, v39, vcc
	s_waitcnt vmcnt(13)
	v_add_co_u32_e32 v4, vcc, 0x15000, v38
	s_lshl_b32 s17, s17, 1
	s_waitcnt vmcnt(12)
	v_addc_co_u32_e32 v5, vcc, 0, v39, vcc
	s_waitcnt vmcnt(11)
	v_add_co_u32_e32 v6, vcc, 0x575000, v38
	s_and_b32 s18, s54, 0x70
	s_waitcnt vmcnt(10)
	v_addc_co_u32_e32 v7, vcc, 0, v39, vcc
	s_waitcnt vmcnt(9)
	v_add_co_u32_e32 v8, vcc, 0x2b000, v38
	s_or_b32 s16, s18, s16
	s_waitcnt vmcnt(8)
	v_addc_co_u32_e32 v9, vcc, 0, v39, vcc
	s_waitcnt vmcnt(7)
	v_add_co_u32_e32 v10, vcc, 0x58b000, v38
	s_and_b32 s17, s17, 0xffffff00
	s_waitcnt vmcnt(6)
	v_addc_co_u32_e32 v11, vcc, 0, v39, vcc
	s_waitcnt vmcnt(5)
	v_add_co_u32_e32 v12, vcc, 0x40000, v38
	s_or_b32 s16, s16, s17
	s_waitcnt vmcnt(4)
	v_addc_co_u32_e32 v13, vcc, 0, v39, vcc
	s_waitcnt vmcnt(3)
	v_add_co_u32_e32 v14, vcc, 0x5a0000, v38
	s_waitcnt vmcnt(2)
	s_nop 0
	v_addc_co_u32_e32 v15, vcc, 0, v39, vcc
	s_waitcnt vmcnt(1)
	v_add_co_u32_e32 v16, vcc, 0x56000, v38
	s_waitcnt vmcnt(0)
	s_nop 0
	v_addc_co_u32_e32 v17, vcc, 0, v39, vcc
	global_load_dword v44, v[2:3], off nt
	s_nop 0
	global_load_dword v3, v[4:5], off offset:2048 nt
	global_load_dword v45, v[6:7], off offset:2048 nt
	s_nop 0
	global_load_dword v4, v[8:9], off nt
	global_load_dword v48, v[10:11], off nt
	global_load_dword v5, v[12:13], off offset:2048 nt
	global_load_dword v49, v[14:15], off offset:2048 nt
	global_load_dword v6, v[16:17], off nt
	v_add_co_u32_e32 v8, vcc, 0x5b6000, v38
	s_nop 1
	v_addc_co_u32_e32 v9, vcc, 0, v39, vcc
	v_add_co_u32_e32 v10, vcc, 0x6b000, v38
	s_nop 1
	v_addc_co_u32_e32 v11, vcc, 0, v39, vcc
	v_add_co_u32_e32 v12, vcc, 0x5cb000, v38
	s_nop 1
	v_addc_co_u32_e32 v13, vcc, 0, v39, vcc
	v_add_co_u32_e32 v14, vcc, 0x81000, v38
	s_nop 1
	v_addc_co_u32_e32 v15, vcc, 0, v39, vcc
	v_add_co_u32_e32 v16, vcc, 0x5e1000, v38
	s_nop 1
	v_addc_co_u32_e32 v17, vcc, 0, v39, vcc
	v_add_co_u32_e32 v18, vcc, 0x96000, v38
	s_waitcnt lgkmcnt(0)
	s_nop 0
	v_addc_co_u32_e32 v19, vcc, 0, v39, vcc
	v_add_co_u32_e32 v20, vcc, 0x5f6000, v38
	s_nop 1
	v_addc_co_u32_e32 v21, vcc, 0, v39, vcc
	v_add_co_u32_e32 v22, vcc, 0xac000, v38
	s_nop 1
	v_addc_co_u32_e32 v23, vcc, 0, v39, vcc
	global_load_dword v50, v[8:9], off nt
	global_load_dword v7, v[10:11], off offset:2048 nt
	global_load_dword v51, v[12:13], off offset:2048 nt
	s_nop 0
	global_load_dword v8, v[14:15], off nt
	global_load_dword v52, v[16:17], off nt
	global_load_dword v9, v[18:19], off offset:2048 nt
	global_load_dword v53, v[20:21], off offset:2048 nt
	global_load_dword v10, v[22:23], off nt
	v_add_co_u32_e32 v12, vcc, 0x60c000, v38
	s_nop 1
	v_addc_co_u32_e32 v13, vcc, 0, v39, vcc
	v_add_co_u32_e32 v14, vcc, 0xc1000, v38
	s_nop 1
	v_addc_co_u32_e32 v15, vcc, 0, v39, vcc
	v_add_co_u32_e32 v16, vcc, 0x621000, v38
	s_nop 1
	v_addc_co_u32_e32 v17, vcc, 0, v39, vcc
	v_add_co_u32_e32 v18, vcc, 0xd7000, v38
	s_nop 1
	v_addc_co_u32_e32 v19, vcc, 0, v39, vcc
	v_add_co_u32_e32 v20, vcc, 0x637000, v38
	s_nop 1
	v_addc_co_u32_e32 v21, vcc, 0, v39, vcc
	v_add_co_u32_e32 v22, vcc, 0xec000, v38
	s_nop 1
	v_addc_co_u32_e32 v23, vcc, 0, v39, vcc
	v_add_co_u32_e32 v24, vcc, 0x64c000, v38
	s_nop 1
	v_addc_co_u32_e32 v25, vcc, 0, v39, vcc
	v_add_co_u32_e32 v26, vcc, 0x102000, v38
	s_nop 1
	v_addc_co_u32_e32 v27, vcc, 0, v39, vcc
	global_load_dword v54, v[12:13], off nt
	global_load_dword v11, v[14:15], off offset:2048 nt
	global_load_dword v55, v[16:17], off offset:2048 nt
	s_nop 0
	global_load_dword v12, v[18:19], off nt
	global_load_dword v56, v[20:21], off nt
	global_load_dword v13, v[22:23], off offset:2048 nt
	global_load_dword v57, v[24:25], off offset:2048 nt
	global_load_dword v14, v[26:27], off nt
	v_add_co_u32_e32 v16, vcc, 0x662000, v38
	s_nop 1
	v_addc_co_u32_e32 v17, vcc, 0, v39, vcc
	v_add_co_u32_e32 v18, vcc, 0x117000, v38
	s_nop 1
	v_addc_co_u32_e32 v19, vcc, 0, v39, vcc
	v_add_co_u32_e32 v20, vcc, 0x677000, v38
	s_nop 1
	v_addc_co_u32_e32 v21, vcc, 0, v39, vcc
	v_add_co_u32_e32 v22, vcc, 0x12d000, v38
	s_nop 1
	v_addc_co_u32_e32 v23, vcc, 0, v39, vcc
	v_add_co_u32_e32 v24, vcc, 0x68d000, v38
	s_nop 1
	v_addc_co_u32_e32 v25, vcc, 0, v39, vcc
	v_add_co_u32_e32 v26, vcc, 0x142000, v38
	s_nop 1
	v_addc_co_u32_e32 v27, vcc, 0, v39, vcc
	v_add_co_u32_e32 v28, vcc, 0x6a2000, v38
	s_nop 1
	v_addc_co_u32_e32 v29, vcc, 0, v39, vcc
	global_load_dword v2, v[38:39], off nt
	global_load_dword v58, v[16:17], off nt
	global_load_dword v15, v[18:19], off offset:2048 nt
	global_load_dword v59, v[20:21], off offset:2048 nt
	s_nop 0
	global_load_dword v16, v[22:23], off nt
	global_load_dword v60, v[24:25], off nt
	global_load_dword v17, v[26:27], off offset:2048 nt
	global_load_dword v61, v[28:29], off offset:2048 nt

; __global__ void __launch_bounds__(NWAVES * 64, 2) fwd_kernel(Args args) {
;     ...
;             __syncthreads();
;             if (((M / 256) * (NGU / 256)) % G == 0) { const int nblk = D / 32, nitems = (DFF / 64) * nblk;
;                 rot_stream(w_dn, D, Wdn_t, DFF, scr, lane, cmaxd, gw, nitems, NGW, MapDn{}); }
;             else if (G == 256 && vcu >= WGU_SHORT0)
;                 rot_stream(w_dn, D, Wdn_t, DFF, scr, lane, cmaxd, (vcu - WGU_SHORT0) * NWAVES + wave, WDN_P9_ITEMS, (256 - WGU_SHORT0) * NWAVES, MapDn{});
.LBB0_737:
	s_waitcnt vmcnt(0)
	v_and_b32_e32 v2, 31, v0
	s_add_i32 s0, s1, 0
	v_lshlrev_b32_e32 v2, 2, v2
	v_and_b32_e32 v1, 32, v0
	v_add_u32_e32 v90, s0, v2
	s_movk_i32 s1, 0x84
	v_mov_b32_e32 v3, 0
	v_mad_u32_u24 v91, v1, s1, v90
	s_abs_i32 s1, s10
	v_lshl_add_u64 v[4:5], s[40:41], 0, v[2:3]
	v_mov_b32_e32 v7, v3
	v_cvt_f32_u32_e32 v3, s1
	v_or_b32_e32 v6, 31, v178
	v_mul_u32_u24_e32 v92, 0x84, v6
	v_lshlrev_b32_e32 v6, 3, v0
	v_rcp_iflag_f32_e32 v3, v3
	v_lshrrev_b32_e32 v93, 3, v178
	v_and_b32_e32 v6, 56, v6
	v_mul_u32_u24_e32 v8, 0x84, v6
	v_mul_f32_e32 v3, 0x4f7ffffe, v3
	v_cvt_u32_f32_e32 v3, v3
	v_lshlrev_b32_e32 v9, 2, v93
	v_add3_u32 v94, s0, v8, v9
	s_sub_i32 s0, 0, s1
	v_readfirstlane_b32 s4, v3
	s_mul_i32 s0, s0, s4
	s_mul_hi_u32 s0, s4, s0
	s_add_i32 s4, s4, s0
	s_mul_hi_u32 s0, s4, 0x1580
	s_mul_i32 s0, s0, s1
	s_sub_i32 s0, 0x1580, s0
	s_sub_i32 s4, s0, s1
	s_cmp_ge_u32 s0, s1
	s_cselect_b32 s0, s4, s0
	s_sub_i32 s4, s0, s1
	s_cmp_ge_u32 s0, s1
	v_lshlrev_b32_e32 v6, 1, v6
	s_cselect_b32 s0, s4, s0
	v_lshl_add_u64 v[6:7], s[42:43], 0, v[6:7]
	v_or_b32_e32 v95, 8, v93
	v_or_b32_e32 v96, 16, v93
	v_or_b32_e32 v97, 24, v93
	s_cmp_lg_u32 s0, 0
	s_waitcnt lgkmcnt(0)
	s_barrier
	s_cbranch_scc0 .LBB0_753
	s_cmpk_lg_i32 s10, 0x100
	s_cselect_b64 s[0:1], -1, 0
	s_cmpk_lt_i32 s34, 0x60
	s_cselect_b64 s[4:5], -1, 0
	s_or_b64 s[4:5], s[0:1], s[4:5]
	v_readlane_b32 s0, v249, 40
	s_add_i32 s1, s0, 0xfffffd00
	s_cmpk_gt_i32 s1, 0x27ff
	s_cselect_b64 s[6:7], -1, 0
	s_or_b64 s[4:5], s[4:5], s[6:7]
	s_and_b64 vcc, exec, s[4:5]
	s_cbranch_vccnz .LBB0_752
; #define LAS __attribute__((address_space(3)))
; __device__ __forceinline__ void rot_load(float (&v)[32], const float* W, int ld, const RotItem r, int lane) {
;     const float* wp = W + (size_t)(r.k0 + 32 * (lane >> 5)) * ld + r.n0 + (lane & 31);
; #pragma unroll
;     for (int i = 0; i < 32; ++i) v[i] = wp[(size_t)i * ld];
; }
; template <class MapF>
; __device__ __forceinline__ void rot_stream(const float* W, int ld, bf16* WT, int ldk, LAS float* scr, int lane, unsigned* cmax, int it, int nitems, int stride, const MapF map) {
;     if (it >= nitems) return;
;     float va[32], vb[32]; RotItem ra = map(it), rb = ra;
;     rot_load(va, W, ld, ra, lane);
	s_ashr_i32 s0, s1, 31
	s_lshr_b32 s0, s0, 25
	s_add_i32 s0, s1, s0
	s_ashr_i32 s4, s0, 7
	s_and_b32 s0, s0, 0x7ffff80
	s_sub_i32 s5, s1, s0
	s_lshl_b32 s0, s4, 6
	v_or_b32_e32 v8, s0, v1
	v_ashrrev_i32_e32 v9, 31, v8
	v_readlane_b32 s52, v249, 43
	s_lshl_b32 s4, s5, 5
	v_lshlrev_b64 v[8:9], 14, v[8:9]
	v_readlane_b32 s64, v249, 55
	v_readlane_b32 s65, v249, 56
	s_ashr_i32 s5, s4, 31
	v_mov_b32_e32 v3, 0
	v_lshl_add_u64 v[8:9], s[64:65], 0, v[8:9]
	v_lshl_add_u64 v[8:9], s[4:5], 2, v[8:9]
	v_lshl_add_u64 v[16:17], v[8:9], 0, v[2:3]
	s_movk_i32 s6, 0x4000
	v_add_co_u32_e32 v8, vcc, s6, v16
	s_mov_b32 s7, 0x8000
	s_nop 0
	v_addc_co_u32_e32 v9, vcc, 0, v17, vcc
	v_add_co_u32_e32 v10, vcc, s7, v16
	s_mov_b32 s8, 0xc000
	s_nop 0
	v_addc_co_u32_e32 v11, vcc, 0, v17, vcc
	v_add_co_u32_e32 v12, vcc, s8, v16
	s_mov_b32 s11, 0x10000
	s_nop 0
	v_addc_co_u32_e32 v13, vcc, 0, v17, vcc
	v_add_co_u32_e32 v14, vcc, s11, v16
	s_mov_b32 s12, 0x14000
	s_nop 0
	v_addc_co_u32_e32 v15, vcc, 0, v17, vcc
	v_add_co_u32_e32 v18, vcc, s12, v16
	s_mov_b32 s13, 0x18000
	s_nop 0
	v_addc_co_u32_e32 v19, vcc, 0, v17, vcc
	v_add_co_u32_e32 v20, vcc, s13, v16
	s_mov_b32 s16, 0x1c000
	s_nop 0
	v_addc_co_u32_e32 v21, vcc, 0, v17, vcc
	v_add_co_u32_e32 v22, vcc, s16, v16
	s_mov_b32 s17, 0x20000
	s_nop 0
	v_addc_co_u32_e32 v23, vcc, 0, v17, vcc
	global_load_dword v59, v[16:17], off nt
	s_nop 0
	global_load_dword v9, v[8:9], off nt
	s_nop 0
	global_load_dword v58, v[10:11], off nt
	global_load_dword v8, v[12:13], off nt
	global_load_dword v55, v[14:15], off nt
	s_nop 0
	global_load_dword v11, v[18:19], off nt
	global_load_dword v54, v[20:21], off nt
	global_load_dword v10, v[22:23], off nt
	v_add_co_u32_e32 v12, vcc, s17, v16
	s_mov_b32 s18, 0x24000
	s_nop 0
	v_addc_co_u32_e32 v13, vcc, 0, v17, vcc
	v_add_co_u32_e32 v14, vcc, s18, v16
	s_mov_b32 s19, 0x28000
	s_nop 0
	v_addc_co_u32_e32 v15, vcc, 0, v17, vcc
	v_add_co_u32_e32 v18, vcc, s19, v16
	s_mov_b32 s20, 0x2c000
	s_nop 0
	v_addc_co_u32_e32 v19, vcc, 0, v17, vcc
	v_add_co_u32_e32 v20, vcc, s20, v16
	s_mov_b32 s21, 0x30000
	s_nop 0
	v_addc_co_u32_e32 v21, vcc, 0, v17, vcc
	v_add_co_u32_e32 v22, vcc, s21, v16
	s_mov_b32 s23, 0x34000
	s_nop 0
	v_addc_co_u32_e32 v23, vcc, 0, v17, vcc
	v_add_co_u32_e32 v24, vcc, s23, v16
	s_mov_b32 s24, 0x38000
	s_nop 0
	v_addc_co_u32_e32 v25, vcc, 0, v17, vcc
	v_add_co_u32_e32 v26, vcc, s24, v16
	s_mov_b32 s25, 0x3c000
	s_nop 0
	v_addc_co_u32_e32 v27, vcc, 0, v17, vcc
	v_add_co_u32_e32 v28, vcc, s25, v16
	s_mov_b32 s26, 0x40000
	s_nop 0
	v_addc_co_u32_e32 v29, vcc, 0, v17, vcc
	global_load_dword v65, v[12:13], off nt
	s_nop 0
	global_load_dword v13, v[14:15], off nt
	global_load_dword v64, v[18:19], off nt
	global_load_dword v12, v[20:21], off nt
	global_load_dword v63, v[22:23], off nt
	s_nop 0
	global_load_dword v15, v[24:25], off nt
	global_load_dword v62, v[26:27], off nt
	global_load_dword v14, v[28:29], off nt
	v_add_co_u32_e32 v18, vcc, s26, v16
	s_mov_b32 s27, 0x44000
	s_nop 0
	v_addc_co_u32_e32 v19, vcc, 0, v17, vcc
	v_add_co_u32_e32 v20, vcc, s27, v16
	s_mov_b32 s28, 0x48000
	s_nop 0
	v_addc_co_u32_e32 v21, vcc, 0, v17, vcc
	v_add_co_u32_e32 v22, vcc, s28, v16
	s_mov_b32 s29, 0x4c000
	s_nop 0
	v_addc_co_u32_e32 v23, vcc, 0, v17, vcc
	v_add_co_u32_e32 v24, vcc, s29, v16
	s_mov_b32 s33, 0x50000
	s_nop 0
	v_addc_co_u32_e32 v25, vcc, 0, v17, vcc
	v_add_co_u32_e32 v28, vcc, s33, v16
	s_mov_b32 s35, 0x54000
	s_nop 0
	v_addc_co_u32_e32 v29, vcc, 0, v17, vcc
	v_add_co_u32_e32 v30, vcc, s35, v16
	s_mov_b32 s36, 0x58000
	s_nop 0
	v_addc_co_u32_e32 v31, vcc, 0, v17, vcc
	v_add_co_u32_e32 v32, vcc, s36, v16
	s_mov_b32 s37, 0x5c000
	s_nop 0
	v_addc_co_u32_e32 v33, vcc, 0, v17, vcc
	v_add_co_u32_e32 v36, vcc, s37, v16
	s_mov_b32 s46, 0x60000
	s_nop 0
	v_addc_co_u32_e32 v37, vcc, 0, v17, vcc
	global_load_dword v69, v[18:19], off nt
	global_load_dword v27, v[20:21], off nt
	global_load_dword v68, v[22:23], off nt
	global_load_dword v26, v[24:25], off nt
	global_load_dword v67, v[28:29], off nt
	s_nop 0
	global_load_dword v29, v[30:31], off nt
	global_load_dword v66, v[32:33], off nt
	global_load_dword v28, v[36:37], off nt
	v_add_co_u32_e32 v18, vcc, s46, v16
	s_mov_b32 s47, 0x64000
	s_nop 0
	v_addc_co_u32_e32 v19, vcc, 0, v17, vcc
	v_readlane_b32 s60, v249, 51
	v_add_co_u32_e32 v20, vcc, s47, v16
	s_mov_b32 s60, 0x68000
	s_nop 0
	v_addc_co_u32_e32 v21, vcc, 0, v17, vcc
	v_readlane_b32 s61, v249, 52
	v_add_co_u32_e32 v22, vcc, s60, v16
	s_mov_b32 s61, 0x6c000
	s_nop 0
	v_addc_co_u32_e32 v23, vcc, 0, v17, vcc
	v_readlane_b32 s62, v249, 53
	v_add_co_u32_e32 v24, vcc, s61, v16
	s_mov_b32 s62, 0x70000
	s_nop 0
	v_addc_co_u32_e32 v25, vcc, 0, v17, vcc
	v_readlane_b32 s63, v249, 54
	v_add_co_u32_e32 v30, vcc, s62, v16
	s_mov_b32 s63, 0x74000
	s_nop 0
	v_addc_co_u32_e32 v31, vcc, 0, v17, vcc
	v_add_co_u32_e32 v32, vcc, s63, v16
	s_mov_b32 s64, 0x78000
	s_nop 0
	v_addc_co_u32_e32 v33, vcc, 0, v17, vcc
	v_add_co_u32_e32 v36, vcc, s64, v16
	s_mov_b32 s65, 0x7c000
	s_nop 0
	v_addc_co_u32_e32 v37, vcc, 0, v17, vcc
	v_add_co_u32_e32 v16, vcc, s65, v16
	v_readlane_b32 s54, v249, 45
	s_nop 0
	v_addc_co_u32_e32 v17, vcc, 0, v17, vcc
	global_load_dword v73, v[18:19], off nt
	global_load_dword v49, v[20:21], off nt
	global_load_dword v72, v[22:23], off nt
	global_load_dword v48, v[24:25], off nt
	global_load_dword v71, v[30:31], off nt
	global_load_dword v51, v[32:33], off nt
	global_load_dword v70, v[36:37], off nt
	global_load_dword v50, v[16:17], off nt
	v_mbcnt_lo_u32_b32 v16, -1, 0
	v_mbcnt_hi_u32_b32 v16, -1, v16
	v_and_b32_e32 v18, 64, v16
	v_xor_b32_e32 v17, 32, v16
	v_add_u32_e32 v18, 64, v18
	v_cmp_lt_i32_e32 vcc, v17, v18
	v_readlane_b32 s66, v249, 57
	v_readlane_b32 s67, v249, 58
	v_cndmask_b32_e32 v16, v16, v17, vcc
	s_lshl_b32 s5, s1, 5
	v_lshlrev_b32_e32 v98, 2, v16
	v_mov_b32_e32 v35, v34
	s_add_i32 s66, s5, 0x14000
	s_mov_b32 s22, 0x3e000000
	s_movk_i32 s67, 0x5600
	s_mov_b32 s52, s0
	s_mov_b32 s54, s4
	v_readlane_b32 s53, v249, 44
	v_readlane_b32 s55, v249, 46
	v_readlane_b32 s56, v249, 47
	v_readlane_b32 s57, v249, 48
	v_readlane_b32 s58, v249, 49
	v_readlane_b32 s59, v249, 50
	s_branch .LBB0_742

; template <class MapF>
; __device__ __forceinline__ void rot_stream(const float* W, int ld, bf16* WT, int ldk, LAS float* scr, int lane, unsigned* cmax, int it, int nitems, int stride, const MapF map) {
;     ...
;     while (true) {
;         const int itb = it + stride; const bool hb = itb < nitems;
;         if (hb) { rb = map(itb); rot_load(vb, W, ld, rb, lane); }
.LBB0_742:
	s_cmpk_lt_i32 s1, 0x2300
	s_cselect_b64 s[56:57], -1, 0
	s_cmpk_gt_i32 s1, 0x22ff
	s_cbranch_scc1 .LBB0_744
	s_add_i32 s0, s1, 0x500
	s_ashr_i32 s4, s0, 31
	s_lshr_b32 s4, s4, 25
	s_add_i32 s4, s0, s4
	s_ashr_i32 s5, s4, 7
	s_and_b32 s4, s4, 0x7ffff80
	s_sub_i32 s4, s0, s4
	s_lshl_b32 s0, s5, 6
	v_or_b32_e32 v16, s0, v1
	v_ashrrev_i32_e32 v17, 31, v16
	v_readlane_b32 s80, v249, 43
	s_lshl_b32 s4, s4, 5
	v_lshlrev_b64 v[16:17], 14, v[16:17]
	v_readlane_b32 s92, v249, 55
	v_readlane_b32 s93, v249, 56
	s_ashr_i32 s5, s4, 31
	v_readlane_b32 s81, v249, 44
	v_lshl_add_u64 v[16:17], s[92:93], 0, v[16:17]
	v_lshl_add_u64 v[16:17], s[4:5], 2, v[16:17]
	v_lshl_add_u64 v[38:39], v[16:17], 0, v[2:3]
	v_add_co_u32_e32 v16, vcc, s6, v38
	v_readlane_b32 s82, v249, 45
	s_nop 0
	v_addc_co_u32_e32 v17, vcc, 0, v39, vcc
	v_add_co_u32_e32 v18, vcc, s7, v38
	v_readlane_b32 s83, v249, 46
	s_nop 0
	v_addc_co_u32_e32 v19, vcc, 0, v39, vcc
	v_add_co_u32_e32 v22, vcc, s8, v38
	v_readlane_b32 s84, v249, 47
	s_nop 0
	v_addc_co_u32_e32 v23, vcc, 0, v39, vcc
	v_add_co_u32_e32 v24, vcc, s11, v38
	v_readlane_b32 s85, v249, 48
	s_nop 0
	v_addc_co_u32_e32 v25, vcc, 0, v39, vcc
	v_add_co_u32_e32 v30, vcc, s12, v38
	v_readlane_b32 s86, v249, 49
	s_nop 0
	v_addc_co_u32_e32 v31, vcc, 0, v39, vcc
	v_add_co_u32_e32 v32, vcc, s13, v38
	v_readlane_b32 s87, v249, 50
	s_nop 0
	v_addc_co_u32_e32 v33, vcc, 0, v39, vcc
	v_add_co_u32_e32 v36, vcc, s16, v38
	v_readlane_b32 s88, v249, 51
	s_nop 0
	v_addc_co_u32_e32 v37, vcc, 0, v39, vcc
	global_load_dword v21, v[38:39], off nt
	global_load_dword v20, v[16:17], off nt
	global_load_dword v43, v[18:19], off nt
	global_load_dword v42, v[22:23], off nt
	s_nop 0
	global_load_dword v17, v[24:25], off nt
	global_load_dword v16, v[30:31], off nt
	s_nop 0
	global_load_dword v31, v[32:33], off nt
	global_load_dword v30, v[36:37], off nt
	v_add_co_u32_e32 v18, vcc, s17, v38
	v_readlane_b32 s89, v249, 52
	s_nop 0
	v_addc_co_u32_e32 v19, vcc, 0, v39, vcc
	v_add_co_u32_e32 v22, vcc, s18, v38
	v_readlane_b32 s90, v249, 53
	s_nop 0
	v_addc_co_u32_e32 v23, vcc, 0, v39, vcc
	v_add_co_u32_e32 v32, vcc, s19, v38
	v_readlane_b32 s91, v249, 54
	s_nop 0
	v_addc_co_u32_e32 v33, vcc, 0, v39, vcc
	v_add_co_u32_e32 v36, vcc, s20, v38
	v_readlane_b32 s94, v249, 57
	s_nop 0
	v_addc_co_u32_e32 v37, vcc, 0, v39, vcc
	v_add_co_u32_e32 v40, vcc, s21, v38
	v_readlane_b32 s95, v249, 58
	s_nop 0
	v_addc_co_u32_e32 v41, vcc, 0, v39, vcc
	v_add_co_u32_e32 v44, vcc, s23, v38
	s_nop 1
	v_addc_co_u32_e32 v45, vcc, 0, v39, vcc
	v_add_co_u32_e32 v52, vcc, s24, v38
	s_nop 1
	v_addc_co_u32_e32 v53, vcc, 0, v39, vcc
	v_add_co_u32_e32 v56, vcc, s25, v38
	s_nop 1
	v_addc_co_u32_e32 v57, vcc, 0, v39, vcc
	global_load_dword v25, v[18:19], off nt
	global_load_dword v24, v[22:23], off nt
	global_load_dword v47, v[32:33], off nt
	global_load_dword v46, v[36:37], off nt
	s_nop 0
	global_load_dword v19, v[40:41], off nt
	global_load_dword v18, v[44:45], off nt
	global_load_dword v37, v[52:53], off nt
	global_load_dword v36, v[56:57], off nt
	v_add_co_u32_e32 v22, vcc, s26, v38
	s_nop 1
	v_addc_co_u32_e32 v23, vcc, 0, v39, vcc
	v_add_co_u32_e32 v40, vcc, s27, v38
	s_nop 1
	v_addc_co_u32_e32 v41, vcc, 0, v39, vcc
	v_add_co_u32_e32 v44, vcc, s28, v38
	s_nop 1
	v_addc_co_u32_e32 v45, vcc, 0, v39, vcc
	v_add_co_u32_e32 v56, vcc, s29, v38
	s_nop 1
	v_addc_co_u32_e32 v57, vcc, 0, v39, vcc
	v_add_co_u32_e32 v60, vcc, s33, v38
	s_nop 1
	v_addc_co_u32_e32 v61, vcc, 0, v39, vcc
	v_add_co_u32_e32 v74, vcc, s35, v38
	s_nop 1
	v_addc_co_u32_e32 v75, vcc, 0, v39, vcc
	v_add_co_u32_e32 v76, vcc, s36, v38
	s_nop 1
	v_addc_co_u32_e32 v77, vcc, 0, v39, vcc
	v_add_co_u32_e32 v78, vcc, s37, v38
	s_nop 1
	v_addc_co_u32_e32 v79, vcc, 0, v39, vcc
	global_load_dword v33, v[22:23], off nt
	global_load_dword v32, v[40:41], off nt
	global_load_dword v53, v[44:45], off nt
	global_load_dword v52, v[56:57], off nt
	s_nop 0
	global_load_dword v23, v[60:61], off nt
	global_load_dword v22, v[74:75], off nt
	global_load_dword v45, v[76:77], off nt
	global_load_dword v44, v[78:79], off nt
	v_add_co_u32_e32 v40, vcc, s46, v38
	s_nop 1
	v_addc_co_u32_e32 v41, vcc, 0, v39, vcc
	v_add_co_u32_e32 v56, vcc, s47, v38
	s_nop 1
	v_addc_co_u32_e32 v57, vcc, 0, v39, vcc
	v_add_co_u32_e32 v60, vcc, s60, v38
	s_nop 1
	v_addc_co_u32_e32 v61, vcc, 0, v39, vcc
	v_add_co_u32_e32 v74, vcc, s61, v38
	s_nop 1
	v_addc_co_u32_e32 v75, vcc, 0, v39, vcc
	v_add_co_u32_e32 v76, vcc, s62, v38
	s_nop 1
	v_addc_co_u32_e32 v77, vcc, 0, v39, vcc
	v_add_co_u32_e32 v78, vcc, s63, v38
	s_nop 1
	v_addc_co_u32_e32 v79, vcc, 0, v39, vcc
	v_add_co_u32_e32 v80, vcc, s64, v38
	s_nop 1
	v_addc_co_u32_e32 v81, vcc, 0, v39, vcc
	v_add_co_u32_e32 v82, vcc, s65, v38
	s_nop 1
	v_addc_co_u32_e32 v83, vcc, 0, v39, vcc
	global_load_dword v41, v[40:41], off nt
	s_nop 0
	global_load_dword v40, v[56:57], off nt
	s_nop 0
	global_load_dword v61, v[60:61], off nt
	s_nop 0
	global_load_dword v60, v[74:75], off nt
	global_load_dword v39, v[76:77], off nt
	global_load_dword v38, v[78:79], off nt
	global_load_dword v57, v[80:81], off nt
	global_load_dword v56, v[82:83], off nt

; __device__ __forceinline__ unsigned cvt_pk_bf16(float lo, float hi) { unsigned r; asm volatile("v_cvt_pk_bf16_f32 %0, %1, %2" : "=v"(r) : "v"(lo), "v"(hi)); return r; }
; #define LAS __attribute__((address_space(3)))
; #define LDS_WAIT() asm volatile("s_waitcnt lgkmcnt(0)" ::: "memory")
; __device__ __forceinline__ void rot_finish(float (&v)[32], bf16* WT, int ldk, const RotItem r, LAS float* scr, int lane, unsigned* cmax) {
;     ...
;     for (int i = 0; i < 32; ++i) scr[(32 * hf + i) * 33 + nn] = v[i];
;     LDS_WAIT(); asm volatile("" ::: "memory");
;     const int c = lane & 7;
; #pragma unroll
;     for (int j = 0; j < 4; ++j) { const int n = (lane >> 3) + 8 * j; const LAS float* sp = scr + (8 * c) * 33 + n;
;         v4u o; o.x = cvt_pk_bf16(sp[0 * 33], sp[1 * 33]); o.y = cvt_pk_bf16(sp[2 * 33], sp[3 * 33]);
;         o.z = cvt_pk_bf16(sp[4 * 33], sp[5 * 33]); o.w = cvt_pk_bf16(sp[6 * 33], sp[7 * 33]);
;         *(v4u*)(WT + (size_t)(r.drow0 + n) * ldk + r.k0 + 8 * c) = o; }
;     LDS_WAIT(); asm volatile("" ::: "memory");
.LBB0_746:
	s_or_b64 exec, exec, s[58:59]
	v_add_u32_e32 v99, 0x400, v91
	v_add_u32_e32 v100, 0x800, v91
	v_add_u32_e32 v101, 0xc00, v91
	v_add_u32_e32 v102, v90, v92
	ds_write2_b32 v91, v8, v9 offset1:33
	ds_write2_b32 v91, v74, v75 offset0:66 offset1:99
	ds_write2_b32 v91, v10, v11 offset0:132 offset1:165
	ds_write2_b32 v91, v76, v77 offset0:198 offset1:231
	ds_write2_b32 v99, v12, v13 offset0:8 offset1:41
	ds_write2_b32 v99, v78, v79 offset0:74 offset1:107
	ds_write2_b32 v99, v14, v15 offset0:140 offset1:173
	ds_write2_b32 v99, v80, v81 offset0:206 offset1:239
	ds_write2_b32 v100, v26, v27 offset0:16 offset1:49
	ds_write2_b32 v100, v82, v83 offset0:82 offset1:115
	ds_write2_b32 v100, v28, v29 offset0:148 offset1:181
	ds_write2_b32 v100, v84, v85 offset0:214 offset1:247
	ds_write2_b32 v101, v48, v49 offset0:24 offset1:57
	ds_write2_b32 v101, v86, v87 offset0:90 offset1:123
	ds_write2_b32 v101, v50, v51 offset0:156 offset1:189
	ds_write_b32 v91, v88 offset:3960
	ds_write_b32 v102, v89
	s_waitcnt lgkmcnt(0)
	s_waitcnt lgkmcnt(14)
	ds_read2_b32 v[54:55], v94 offset1:33
	s_waitcnt lgkmcnt(0)
	v_cvt_pk_bf16_f32 v62, v54, v55
	ds_read2_b32 v[54:55], v94 offset0:66 offset1:99
	s_waitcnt lgkmcnt(0)
	v_cvt_pk_bf16_f32 v63, v54, v55
	ds_read2_b32 v[54:55], v94 offset0:132 offset1:165
	s_ashr_i32 s53, s52, 31
	s_waitcnt lgkmcnt(0)
	v_cvt_pk_bf16_f32 v64, v54, v55
	ds_read2_b32 v[54:55], v94 offset0:198 offset1:231
	v_lshl_add_u64 v[58:59], s[52:53], 1, v[6:7]
	v_or_b32_e32 v66, s54, v93
	s_waitcnt lgkmcnt(0)
	v_cvt_pk_bf16_f32 v65, v54, v55
	ds_read2_b32 v[54:55], v94 offset0:8 offset1:41
	v_mad_i64_i32 v[66:67], s[58:59], v66, s67, v[58:59]
	global_store_dwordx4 v[66:67], v[62:65], off
	v_or_b32_e32 v66, s54, v95
	v_mad_i64_i32 v[66:67], s[58:59], v66, s67, v[58:59]
	s_waitcnt lgkmcnt(0)
	v_cvt_pk_bf16_f32 v62, v54, v55
	ds_read2_b32 v[54:55], v94 offset0:74 offset1:107
	s_waitcnt lgkmcnt(0)
	v_cvt_pk_bf16_f32 v63, v54, v55
	ds_read2_b32 v[54:55], v94 offset0:140 offset1:173
	s_waitcnt lgkmcnt(0)
	v_cvt_pk_bf16_f32 v64, v54, v55
	ds_read2_b32 v[54:55], v94 offset0:206 offset1:239
	s_waitcnt lgkmcnt(0)
	v_cvt_pk_bf16_f32 v65, v54, v55
	ds_read2_b32 v[54:55], v94 offset0:16 offset1:49
	global_store_dwordx4 v[66:67], v[62:65], off
	v_or_b32_e32 v66, s54, v96
	v_mad_i64_i32 v[66:67], s[58:59], v66, s67, v[58:59]
	s_waitcnt lgkmcnt(0)
	v_cvt_pk_bf16_f32 v62, v54, v55
	ds_read2_b32 v[54:55], v94 offset0:82 offset1:115
	s_waitcnt lgkmcnt(0)
	v_cvt_pk_bf16_f32 v63, v54, v55
	ds_read2_b32 v[54:55], v94 offset0:148 offset1:181
	s_waitcnt lgkmcnt(0)
	v_cvt_pk_bf16_f32 v64, v54, v55
	ds_read2_b32 v[54:55], v94 offset0:214 offset1:247
	s_waitcnt lgkmcnt(0)
	v_cvt_pk_bf16_f32 v65, v54, v55
	ds_read2_b32 v[54:55], v94 offset0:24 offset1:57
	global_store_dwordx4 v[66:67], v[62:65], off
	s_andn2_b64 vcc, exec, s[56:57]
	s_mov_b64 s[56:57], -1
	s_waitcnt lgkmcnt(0)
	v_cvt_pk_bf16_f32 v62, v54, v55
	ds_read2_b32 v[54:55], v94 offset0:90 offset1:123
	v_or_b32_e32 v65, s54, v97
	s_waitcnt lgkmcnt(0)
	v_cvt_pk_bf16_f32 v63, v54, v55
	ds_read2_b32 v[54:55], v94 offset0:156 offset1:189
	v_mad_i64_i32 v[58:59], s[58:59], v65, s67, v[58:59]
	s_waitcnt lgkmcnt(0)
	v_cvt_pk_bf16_f32 v64, v54, v55
	ds_read2_b32 v[54:55], v94 offset0:222 offset1:255
	s_waitcnt lgkmcnt(0)
	v_cvt_pk_bf16_f32 v65, v54, v55
	global_store_dwordx4 v[58:59], v[62:65], off
	s_waitcnt lgkmcnt(0)
	s_cbranch_vccnz .LBB0_741
	s_add_i32 s53, s1, 0xa00
	s_cmpk_gt_i32 s1, 0x1dff
	s_cselect_b64 s[56:57], -1, 0
	s_and_b64 vcc, exec, s[56:57]
	s_cbranch_vccnz .LBB0_749
; template <class MapF>
; __device__ __forceinline__ void rot_stream(const float* W, int ld, bf16* WT, int ldk, LAS float* scr, int lane, unsigned* cmax, int it, int nitems, int stride, const MapF map) {
;     ...
;         it = itb + stride; const bool ha = it < nitems;
;         if (ha) { ra = map(it); rot_load(va, W, ld, ra, lane); }
	s_ashr_i32 s1, s53, 31
	s_lshr_b32 s1, s1, 25
	s_add_i32 s1, s53, s1
	s_ashr_i32 s1, s1, 7
	s_lshl_b32 s52, s1, 6
	v_or_b32_e32 v8, s52, v1
	s_lshl_b32 s1, s1, 12
	v_ashrrev_i32_e32 v9, 31, v8
	v_readlane_b32 s80, v249, 43
	s_sub_i32 s54, s66, s1
	v_lshlrev_b64 v[8:9], 14, v[8:9]
	v_readlane_b32 s92, v249, 55
	v_readlane_b32 s93, v249, 56
	s_ashr_i32 s55, s54, 31
	v_readlane_b32 s81, v249, 44
	v_lshl_add_u64 v[8:9], s[92:93], 0, v[8:9]
	v_lshl_add_u64 v[8:9], s[54:55], 2, v[8:9]
	v_lshl_add_u64 v[48:49], v[8:9], 0, v[2:3]
	v_add_co_u32_e32 v8, vcc, s6, v48
	v_readlane_b32 s82, v249, 45
	s_nop 0
	v_addc_co_u32_e32 v9, vcc, 0, v49, vcc
	v_add_co_u32_e32 v10, vcc, s7, v48
	v_readlane_b32 s83, v249, 46
	s_nop 0
	v_addc_co_u32_e32 v11, vcc, 0, v49, vcc
	v_add_co_u32_e32 v12, vcc, s8, v48
	v_readlane_b32 s84, v249, 47
	s_nop 0
	v_addc_co_u32_e32 v13, vcc, 0, v49, vcc
	v_add_co_u32_e32 v14, vcc, s11, v48
	v_readlane_b32 s85, v249, 48
	s_nop 0
	v_addc_co_u32_e32 v15, vcc, 0, v49, vcc
	v_add_co_u32_e32 v26, vcc, s12, v48
	v_readlane_b32 s86, v249, 49
	s_nop 0
	v_addc_co_u32_e32 v27, vcc, 0, v49, vcc
	v_add_co_u32_e32 v28, vcc, s13, v48
	v_readlane_b32 s87, v249, 50
	s_nop 0
	v_addc_co_u32_e32 v29, vcc, 0, v49, vcc
	v_add_co_u32_e32 v50, vcc, s16, v48
	v_readlane_b32 s88, v249, 51
	s_nop 0
	v_addc_co_u32_e32 v51, vcc, 0, v49, vcc
	global_load_dword v59, v[48:49], off nt
	s_nop 0
	global_load_dword v9, v[8:9], off nt
	s_nop 0
	global_load_dword v58, v[10:11], off nt
	global_load_dword v8, v[12:13], off nt
	global_load_dword v55, v[14:15], off nt
	s_nop 0
	global_load_dword v11, v[26:27], off nt
	global_load_dword v54, v[28:29], off nt
	global_load_dword v10, v[50:51], off nt
	v_add_co_u32_e32 v12, vcc, s17, v48
	v_readlane_b32 s89, v249, 52
	s_nop 0
	v_addc_co_u32_e32 v13, vcc, 0, v49, vcc
	v_add_co_u32_e32 v14, vcc, s18, v48
	v_readlane_b32 s90, v249, 53
	s_nop 0
	v_addc_co_u32_e32 v15, vcc, 0, v49, vcc
	v_add_co_u32_e32 v26, vcc, s19, v48
	v_readlane_b32 s91, v249, 54
	s_nop 0
	v_addc_co_u32_e32 v27, vcc, 0, v49, vcc
	v_add_co_u32_e32 v28, vcc, s20, v48
	v_readlane_b32 s94, v249, 57
	s_nop 0
	v_addc_co_u32_e32 v29, vcc, 0, v49, vcc
	v_add_co_u32_e32 v50, vcc, s21, v48
	v_readlane_b32 s95, v249, 58
	s_nop 0
	v_addc_co_u32_e32 v51, vcc, 0, v49, vcc
	v_add_co_u32_e32 v66, vcc, s23, v48
	s_nop 1
	v_addc_co_u32_e32 v67, vcc, 0, v49, vcc
	v_add_co_u32_e32 v68, vcc, s24, v48
	s_nop 1
	v_addc_co_u32_e32 v69, vcc, 0, v49, vcc
	v_add_co_u32_e32 v70, vcc, s25, v48
	s_nop 1
	v_addc_co_u32_e32 v71, vcc, 0, v49, vcc
	global_load_dword v65, v[12:13], off nt
	s_nop 0
	global_load_dword v13, v[14:15], off nt
	global_load_dword v64, v[26:27], off nt
	global_load_dword v12, v[28:29], off nt
	global_load_dword v63, v[50:51], off nt
	s_nop 0
	global_load_dword v15, v[66:67], off nt
	global_load_dword v62, v[68:69], off nt
	global_load_dword v14, v[70:71], off nt
	v_add_co_u32_e32 v26, vcc, s26, v48
	s_nop 1
	v_addc_co_u32_e32 v27, vcc, 0, v49, vcc
	v_add_co_u32_e32 v28, vcc, s27, v48
	s_nop 1
	v_addc_co_u32_e32 v29, vcc, 0, v49, vcc
	v_add_co_u32_e32 v50, vcc, s28, v48
	s_nop 1
	v_addc_co_u32_e32 v51, vcc, 0, v49, vcc
	v_add_co_u32_e32 v66, vcc, s29, v48
	s_nop 1
	v_addc_co_u32_e32 v67, vcc, 0, v49, vcc
	v_add_co_u32_e32 v70, vcc, s33, v48
	s_nop 1
	v_addc_co_u32_e32 v71, vcc, 0, v49, vcc
	v_add_co_u32_e32 v72, vcc, s35, v48
	s_nop 1
	v_addc_co_u32_e32 v73, vcc, 0, v49, vcc
	v_add_co_u32_e32 v74, vcc, s36, v48
	s_nop 1
	v_addc_co_u32_e32 v75, vcc, 0, v49, vcc
	v_add_co_u32_e32 v76, vcc, s37, v48
	s_nop 1
	v_addc_co_u32_e32 v77, vcc, 0, v49, vcc
	global_load_dword v69, v[26:27], off nt
	s_nop 0
	global_load_dword v27, v[28:29], off nt
	global_load_dword v68, v[50:51], off nt
	global_load_dword v26, v[66:67], off nt
	s_nop 0
	global_load_dword v67, v[70:71], off nt
	global_load_dword v29, v[72:73], off nt
	global_load_dword v66, v[74:75], off nt
	global_load_dword v28, v[76:77], off nt
	v_add_co_u32_e32 v50, vcc, s46, v48
	s_nop 1
	v_addc_co_u32_e32 v51, vcc, 0, v49, vcc
	v_add_co_u32_e32 v70, vcc, s47, v48
	s_nop 1
	v_addc_co_u32_e32 v71, vcc, 0, v49, vcc
	v_add_co_u32_e32 v74, vcc, s60, v48
	s_nop 1
	v_addc_co_u32_e32 v75, vcc, 0, v49, vcc
	v_add_co_u32_e32 v76, vcc, s61, v48
	s_nop 1
	v_addc_co_u32_e32 v77, vcc, 0, v49, vcc
	v_add_co_u32_e32 v78, vcc, s62, v48
	s_nop 1
	v_addc_co_u32_e32 v79, vcc, 0, v49, vcc
	v_add_co_u32_e32 v80, vcc, 0x74000, v48
	s_nop 1
	v_addc_co_u32_e32 v81, vcc, 0, v49, vcc
	v_add_co_u32_e32 v82, vcc, 0x78000, v48
	s_nop 1
	v_addc_co_u32_e32 v83, vcc, 0, v49, vcc
	v_add_co_u32_e32 v84, vcc, 0x7c000, v48
	s_nop 1
	v_addc_co_u32_e32 v85, vcc, 0, v49, vcc
	global_load_dword v73, v[50:51], off nt
	global_load_dword v49, v[70:71], off nt
	global_load_dword v72, v[74:75], off nt
	global_load_dword v48, v[76:77], off nt
	s_nop 0
	global_load_dword v71, v[78:79], off nt
	global_load_dword v51, v[80:81], off nt
	global_load_dword v70, v[82:83], off nt
	global_load_dword v50, v[84:85], off nt
	s_branch .LBB0_750

; #define LAS __attribute__((address_space(3)))
; __device__ __forceinline__ void rot_load(float (&v)[32], const float* W, int ld, const RotItem r, int lane) {
;     const float* wp = W + (size_t)(r.k0 + 32 * (lane >> 5)) * ld + r.n0 + (lane & 31);
; #pragma unroll
;     for (int i = 0; i < 32; ++i) v[i] = wp[(size_t)i * ld];
; }
; template <class MapF>
; __device__ __forceinline__ void rot_stream(const float* W, int ld, bf16* WT, int ldk, LAS float* scr, int lane, unsigned* cmax, int it, int nitems, int stride, const MapF map) {
;     if (it >= nitems) return;
;     float va[32], vb[32]; RotItem ra = map(it), rb = ra;
;     rot_load(va, W, ld, ra, lane);
.LBB0_753:
.LBB0_754:
	v_readlane_b32 s0, v249, 40
	s_cmpk_gt_i32 s0, 0x55ff
	s_cbranch_scc1 .LBB0_768
	v_readlane_b32 s4, v249, 40
	s_ashr_i32 s0, s4, 31
	s_lshr_b32 s0, s0, 25
	s_add_i32 s0, s4, s0
	s_ashr_i32 s1, s0, 7
	s_and_b32 s0, s0, 0x7ffff80
	s_sub_i32 s4, s4, s0
	s_lshl_b32 s0, s1, 6
	s_waitcnt vmcnt(32)
	v_or_b32_e32 v8, s0, v1
	v_ashrrev_i32_e32 v9, 31, v8
	v_readlane_b32 s52, v249, 43
	s_lshl_b32 s4, s4, 5
	v_lshlrev_b64 v[8:9], 14, v[8:9]
	v_readlane_b32 s64, v249, 55
	v_readlane_b32 s65, v249, 56
	s_ashr_i32 s5, s4, 31
	v_mov_b32_e32 v3, 0
	v_lshl_add_u64 v[8:9], s[64:65], 0, v[8:9]
	v_lshl_add_u64 v[8:9], s[4:5], 2, v[8:9]
	v_lshl_add_u64 v[16:17], v[8:9], 0, v[2:3]
	s_movk_i32 s6, 0x4000
	v_add_co_u32_e32 v8, vcc, s6, v16
	s_mov_b32 s7, 0x8000
	s_nop 0
	v_addc_co_u32_e32 v9, vcc, 0, v17, vcc
	s_waitcnt vmcnt(28)
	v_add_co_u32_e32 v10, vcc, s7, v16
	s_mov_b32 s8, 0xc000
	s_nop 0
	v_addc_co_u32_e32 v11, vcc, 0, v17, vcc
	s_waitcnt vmcnt(24)
	v_add_co_u32_e32 v12, vcc, s8, v16
	s_mov_b32 s11, 0x10000
	s_nop 0
	v_addc_co_u32_e32 v13, vcc, 0, v17, vcc
	s_waitcnt vmcnt(20)
	v_add_co_u32_e32 v14, vcc, s11, v16
	s_mov_b32 s12, 0x14000
	s_nop 0
	v_addc_co_u32_e32 v15, vcc, 0, v17, vcc
	v_add_co_u32_e32 v18, vcc, s12, v16
	s_mov_b32 s13, 0x18000
	s_nop 0
	v_addc_co_u32_e32 v19, vcc, 0, v17, vcc
	v_add_co_u32_e32 v20, vcc, s13, v16
	s_mov_b32 s16, 0x1c000
	s_nop 0
	v_addc_co_u32_e32 v21, vcc, 0, v17, vcc
	v_add_co_u32_e32 v22, vcc, s16, v16
	s_mov_b32 s17, 0x20000
	s_nop 0
	v_addc_co_u32_e32 v23, vcc, 0, v17, vcc
	global_load_dword v61, v[16:17], off nt
	s_nop 0
	global_load_dword v9, v[8:9], off nt
	s_nop 0
	global_load_dword v60, v[10:11], off nt
	global_load_dword v8, v[12:13], off nt
	global_load_dword v55, v[14:15], off nt
	s_nop 0
	global_load_dword v11, v[18:19], off nt
	global_load_dword v54, v[20:21], off nt
	global_load_dword v10, v[22:23], off nt
	v_add_co_u32_e32 v12, vcc, s17, v16
	s_mov_b32 s18, 0x24000
	s_nop 0
	v_addc_co_u32_e32 v13, vcc, 0, v17, vcc
	v_add_co_u32_e32 v14, vcc, s18, v16
	s_mov_b32 s19, 0x28000
	s_nop 0
	v_addc_co_u32_e32 v15, vcc, 0, v17, vcc
	v_add_co_u32_e32 v18, vcc, s19, v16
	s_mov_b32 s20, 0x2c000
	s_nop 0
	v_addc_co_u32_e32 v19, vcc, 0, v17, vcc
	v_add_co_u32_e32 v20, vcc, s20, v16
	s_mov_b32 s21, 0x30000
	s_nop 0
	v_addc_co_u32_e32 v21, vcc, 0, v17, vcc
	v_add_co_u32_e32 v22, vcc, s21, v16
	s_mov_b32 s23, 0x34000
	s_nop 0
	v_addc_co_u32_e32 v23, vcc, 0, v17, vcc
	v_add_co_u32_e32 v24, vcc, s23, v16
	s_mov_b32 s24, 0x38000
	s_nop 0
	v_addc_co_u32_e32 v25, vcc, 0, v17, vcc
	s_waitcnt vmcnt(24)
	v_add_co_u32_e32 v26, vcc, s24, v16
	s_mov_b32 s25, 0x3c000
	s_nop 0
	v_addc_co_u32_e32 v27, vcc, 0, v17, vcc
	s_waitcnt vmcnt(20)
	v_add_co_u32_e32 v28, vcc, s25, v16
	s_mov_b32 s26, 0x40000
	s_nop 0
	v_addc_co_u32_e32 v29, vcc, 0, v17, vcc
	global_load_dword v65, v[12:13], off nt
	s_nop 0
	global_load_dword v13, v[14:15], off nt
	global_load_dword v64, v[18:19], off nt
	global_load_dword v12, v[20:21], off nt
	global_load_dword v63, v[22:23], off nt
	s_nop 0
	global_load_dword v15, v[24:25], off nt
	global_load_dword v62, v[26:27], off nt
	global_load_dword v14, v[28:29], off nt
	v_add_co_u32_e32 v18, vcc, s26, v16
	s_mov_b32 s27, 0x44000
	s_nop 0
	v_addc_co_u32_e32 v19, vcc, 0, v17, vcc
	v_add_co_u32_e32 v20, vcc, s27, v16
	s_mov_b32 s28, 0x48000
	s_nop 0
	v_addc_co_u32_e32 v21, vcc, 0, v17, vcc
	v_add_co_u32_e32 v22, vcc, s28, v16
	s_mov_b32 s29, 0x4c000
	s_nop 0
	v_addc_co_u32_e32 v23, vcc, 0, v17, vcc
	v_add_co_u32_e32 v24, vcc, s29, v16
	s_mov_b32 s33, 0x50000
	s_nop 0
	v_addc_co_u32_e32 v25, vcc, 0, v17, vcc
	v_add_co_u32_e32 v28, vcc, s33, v16
	s_mov_b32 s35, 0x54000
	s_nop 0
	v_addc_co_u32_e32 v29, vcc, 0, v17, vcc
	v_add_co_u32_e32 v30, vcc, s35, v16
	s_mov_b32 s36, 0x58000
	s_nop 0
	v_addc_co_u32_e32 v31, vcc, 0, v17, vcc
	v_add_co_u32_e32 v32, vcc, s36, v16
	s_mov_b32 s37, 0x5c000
	s_nop 0
	v_addc_co_u32_e32 v33, vcc, 0, v17, vcc
	v_add_co_u32_e32 v36, vcc, s37, v16
	s_mov_b32 s46, 0x60000
	s_nop 0
	v_addc_co_u32_e32 v37, vcc, 0, v17, vcc
	global_load_dword v69, v[18:19], off nt
	global_load_dword v27, v[20:21], off nt
	global_load_dword v68, v[22:23], off nt
	global_load_dword v26, v[24:25], off nt
	global_load_dword v67, v[28:29], off nt
	s_nop 0
	global_load_dword v29, v[30:31], off nt
	global_load_dword v66, v[32:33], off nt
	global_load_dword v28, v[36:37], off nt
	v_add_co_u32_e32 v18, vcc, s46, v16
	s_mov_b32 s47, 0x64000
	s_nop 0
	v_addc_co_u32_e32 v19, vcc, 0, v17, vcc
	v_readlane_b32 s60, v249, 51
	v_add_co_u32_e32 v20, vcc, s47, v16
	s_mov_b32 s60, 0x68000
	s_nop 0
	v_addc_co_u32_e32 v21, vcc, 0, v17, vcc
	v_readlane_b32 s61, v249, 52
	v_add_co_u32_e32 v22, vcc, s60, v16
	s_mov_b32 s61, 0x6c000
	s_nop 0
	v_addc_co_u32_e32 v23, vcc, 0, v17, vcc
	v_readlane_b32 s62, v249, 53
	v_add_co_u32_e32 v24, vcc, s61, v16
	s_mov_b32 s62, 0x70000
	s_nop 0
	v_addc_co_u32_e32 v25, vcc, 0, v17, vcc
	v_readlane_b32 s63, v249, 54
	v_add_co_u32_e32 v30, vcc, s62, v16
	s_mov_b32 s63, 0x74000
	s_nop 0
	v_addc_co_u32_e32 v31, vcc, 0, v17, vcc
	v_add_co_u32_e32 v32, vcc, s63, v16
	s_mov_b32 s64, 0x78000
	s_nop 0
	v_addc_co_u32_e32 v33, vcc, 0, v17, vcc
	v_add_co_u32_e32 v36, vcc, s64, v16
	s_mov_b32 s65, 0x7c000
	s_nop 0
	v_addc_co_u32_e32 v37, vcc, 0, v17, vcc
	v_add_co_u32_e32 v16, vcc, s65, v16
	v_readlane_b32 s54, v249, 45
	s_nop 0
	v_addc_co_u32_e32 v17, vcc, 0, v17, vcc
	global_load_dword v73, v[18:19], off nt
	global_load_dword v49, v[20:21], off nt
	global_load_dword v72, v[22:23], off nt
	global_load_dword v48, v[24:25], off nt
	global_load_dword v71, v[30:31], off nt
	global_load_dword v51, v[32:33], off nt
	global_load_dword v70, v[36:37], off nt
	global_load_dword v50, v[16:17], off nt
	v_mbcnt_lo_u32_b32 v16, -1, 0
	v_mbcnt_hi_u32_b32 v16, -1, v16
	v_and_b32_e32 v18, 64, v16
	v_xor_b32_e32 v17, 32, v16
	v_add_u32_e32 v18, 64, v18
	v_cmp_lt_i32_e32 vcc, v17, v18
	v_readlane_b32 s66, v249, 57
	v_readlane_b32 s67, v249, 58
	v_cndmask_b32_e32 v16, v16, v17, vcc
	v_lshlrev_b32_e32 v98, 2, v16
	v_mov_b32_e32 v35, v34
	s_lshl_b32 s66, s10, 4
	s_movk_i32 s67, 0x5600
	s_mov_b32 s22, 0x3e000000
	s_mov_b32 s52, s0
	s_mov_b32 s54, s4
	v_readlane_b32 s53, v249, 44
	v_readlane_b32 s55, v249, 46
	v_readlane_b32 s56, v249, 47
	v_readlane_b32 s57, v249, 48
	v_readlane_b32 s58, v249, 49
	v_readlane_b32 s59, v249, 50
	s_branch .LBB0_758

; __device__ __forceinline__ void rot_load(float (&v)[32], const float* W, int ld, const RotItem r, int lane) {
;     const float* wp = W + (size_t)(r.k0 + 32 * (lane >> 5)) * ld + r.n0 + (lane & 31);
; #pragma unroll
;     for (int i = 0; i < 32; ++i) v[i] = wp[(size_t)i * ld];
; }
; template <class MapF>
; __device__ __forceinline__ void rot_stream(const float* W, int ld, bf16* WT, int ldk, LAS float* scr, int lane, unsigned* cmax, int it, int nitems, int stride, const MapF map) {
;     ...
;     while (true) {
;         const int itb = it + stride; const bool hb = itb < nitems;
;         if (hb) { rb = map(itb); rot_load(vb, W, ld, rb, lane); }
.LBB0_758:
	v_readlane_b32 s1, v249, 40
	s_add_i32 s68, s1, s9
	s_cmpk_lt_i32 s68, 0x5600
	s_cselect_b64 s[56:57], -1, 0
	s_cmpk_gt_i32 s68, 0x55ff
	s_cbranch_scc1 .LBB0_760
	s_ashr_i32 s0, s68, 31
	s_lshr_b32 s0, s0, 25
	s_add_i32 s0, s68, s0
	s_ashr_i32 s1, s0, 7
	s_and_b32 s0, s0, 0x7ffff80
	s_sub_i32 s4, s68, s0
	s_lshl_b32 s0, s1, 6
	v_or_b32_e32 v16, s0, v1
	v_ashrrev_i32_e32 v17, 31, v16
	v_readlane_b32 s80, v249, 43
	s_lshl_b32 s4, s4, 5
	v_lshlrev_b64 v[16:17], 14, v[16:17]
	v_readlane_b32 s92, v249, 55
	v_readlane_b32 s93, v249, 56
	s_ashr_i32 s5, s4, 31
	v_readlane_b32 s81, v249, 44
	v_lshl_add_u64 v[16:17], s[92:93], 0, v[16:17]
	v_lshl_add_u64 v[16:17], s[4:5], 2, v[16:17]
	v_lshl_add_u64 v[38:39], v[16:17], 0, v[2:3]
	v_add_co_u32_e32 v16, vcc, s6, v38
	v_readlane_b32 s82, v249, 45
	s_nop 0
	v_addc_co_u32_e32 v17, vcc, 0, v39, vcc
	v_add_co_u32_e32 v18, vcc, s7, v38
	v_readlane_b32 s83, v249, 46
	s_nop 0
	v_addc_co_u32_e32 v19, vcc, 0, v39, vcc
	v_add_co_u32_e32 v22, vcc, s8, v38
	v_readlane_b32 s84, v249, 47
	s_nop 0
	v_addc_co_u32_e32 v23, vcc, 0, v39, vcc
	v_add_co_u32_e32 v24, vcc, s11, v38
	v_readlane_b32 s85, v249, 48
	s_nop 0
	v_addc_co_u32_e32 v25, vcc, 0, v39, vcc
	v_add_co_u32_e32 v30, vcc, s12, v38
	v_readlane_b32 s86, v249, 49
	s_nop 0
	v_addc_co_u32_e32 v31, vcc, 0, v39, vcc
	v_add_co_u32_e32 v32, vcc, s13, v38
	v_readlane_b32 s87, v249, 50
	s_nop 0
	v_addc_co_u32_e32 v33, vcc, 0, v39, vcc
	v_add_co_u32_e32 v36, vcc, s16, v38
	v_readlane_b32 s88, v249, 51
	s_nop 0
	v_addc_co_u32_e32 v37, vcc, 0, v39, vcc
	global_load_dword v21, v[38:39], off nt
	global_load_dword v20, v[16:17], off nt
	global_load_dword v43, v[18:19], off nt
	global_load_dword v42, v[22:23], off nt
	s_nop 0
	global_load_dword v17, v[24:25], off nt
	global_load_dword v16, v[30:31], off nt
	s_nop 0
	global_load_dword v31, v[32:33], off nt
	global_load_dword v30, v[36:37], off nt
	v_add_co_u32_e32 v18, vcc, s17, v38
	v_readlane_b32 s89, v249, 52
	s_nop 0
	v_addc_co_u32_e32 v19, vcc, 0, v39, vcc
	v_add_co_u32_e32 v22, vcc, s18, v38
	v_readlane_b32 s90, v249, 53
	s_nop 0
	v_addc_co_u32_e32 v23, vcc, 0, v39, vcc
	v_add_co_u32_e32 v32, vcc, s19, v38
	v_readlane_b32 s91, v249, 54
	s_nop 0
	v_addc_co_u32_e32 v33, vcc, 0, v39, vcc
	v_add_co_u32_e32 v36, vcc, s20, v38
	v_readlane_b32 s94, v249, 57
	s_nop 0
	v_addc_co_u32_e32 v37, vcc, 0, v39, vcc
	v_add_co_u32_e32 v40, vcc, s21, v38
	v_readlane_b32 s95, v249, 58
	s_nop 0
	v_addc_co_u32_e32 v41, vcc, 0, v39, vcc
	v_add_co_u32_e32 v44, vcc, s23, v38
	s_nop 1
	v_addc_co_u32_e32 v45, vcc, 0, v39, vcc
	v_add_co_u32_e32 v52, vcc, s24, v38
	s_nop 1
	v_addc_co_u32_e32 v53, vcc, 0, v39, vcc
	v_add_co_u32_e32 v56, vcc, s25, v38
	s_nop 1
	v_addc_co_u32_e32 v57, vcc, 0, v39, vcc
	global_load_dword v25, v[18:19], off nt
	global_load_dword v24, v[22:23], off nt
	global_load_dword v47, v[32:33], off nt
	global_load_dword v46, v[36:37], off nt
	s_nop 0
	global_load_dword v19, v[40:41], off nt
	global_load_dword v18, v[44:45], off nt
	global_load_dword v37, v[52:53], off nt
	global_load_dword v36, v[56:57], off nt
	v_add_co_u32_e32 v22, vcc, s26, v38
	s_nop 1
	v_addc_co_u32_e32 v23, vcc, 0, v39, vcc
	v_add_co_u32_e32 v40, vcc, s27, v38
	s_nop 1
	v_addc_co_u32_e32 v41, vcc, 0, v39, vcc
	v_add_co_u32_e32 v44, vcc, s28, v38
	s_nop 1
	v_addc_co_u32_e32 v45, vcc, 0, v39, vcc
	v_add_co_u32_e32 v56, vcc, s29, v38
	s_nop 1
	v_addc_co_u32_e32 v57, vcc, 0, v39, vcc
	v_add_co_u32_e32 v58, vcc, s33, v38
	s_nop 1
	v_addc_co_u32_e32 v59, vcc, 0, v39, vcc
	v_add_co_u32_e32 v74, vcc, s35, v38
	s_nop 1
	v_addc_co_u32_e32 v75, vcc, 0, v39, vcc
	v_add_co_u32_e32 v76, vcc, s36, v38
	s_nop 1
	v_addc_co_u32_e32 v77, vcc, 0, v39, vcc
	v_add_co_u32_e32 v78, vcc, s37, v38
	s_nop 1
	v_addc_co_u32_e32 v79, vcc, 0, v39, vcc
	global_load_dword v33, v[22:23], off nt
	global_load_dword v32, v[40:41], off nt
	global_load_dword v53, v[44:45], off nt
	global_load_dword v52, v[56:57], off nt
	s_nop 0
	global_load_dword v23, v[58:59], off nt
	global_load_dword v22, v[74:75], off nt
	global_load_dword v45, v[76:77], off nt
	global_load_dword v44, v[78:79], off nt
	v_add_co_u32_e32 v40, vcc, s46, v38
	s_nop 1
	v_addc_co_u32_e32 v41, vcc, 0, v39, vcc
	v_add_co_u32_e32 v56, vcc, s47, v38
	s_nop 1
	v_addc_co_u32_e32 v57, vcc, 0, v39, vcc
	v_add_co_u32_e32 v58, vcc, s60, v38
	s_nop 1
	v_addc_co_u32_e32 v59, vcc, 0, v39, vcc
	v_add_co_u32_e32 v74, vcc, s61, v38
	s_nop 1
	v_addc_co_u32_e32 v75, vcc, 0, v39, vcc
	v_add_co_u32_e32 v76, vcc, s62, v38
	s_nop 1
	v_addc_co_u32_e32 v77, vcc, 0, v39, vcc
	v_add_co_u32_e32 v78, vcc, s63, v38
	s_nop 1
	v_addc_co_u32_e32 v79, vcc, 0, v39, vcc
	v_add_co_u32_e32 v80, vcc, s64, v38
	s_nop 1
	v_addc_co_u32_e32 v81, vcc, 0, v39, vcc
	v_add_co_u32_e32 v82, vcc, s65, v38
	s_nop 1
	v_addc_co_u32_e32 v83, vcc, 0, v39, vcc
	global_load_dword v41, v[40:41], off nt
	s_nop 0
	global_load_dword v40, v[56:57], off nt
	s_nop 0
	global_load_dword v59, v[58:59], off nt
	s_nop 0
	global_load_dword v58, v[74:75], off nt
	global_load_dword v39, v[76:77], off nt
	global_load_dword v38, v[78:79], off nt
	global_load_dword v57, v[80:81], off nt
	global_load_dword v56, v[82:83], off nt

; __device__ __forceinline__ unsigned cvt_pk_bf16(float lo, float hi) { unsigned r; asm volatile("v_cvt_pk_bf16_f32 %0, %1, %2" : "=v"(r) : "v"(lo), "v"(hi)); return r; }
; #define LAS __attribute__((address_space(3)))
; #define LDS_WAIT() asm volatile("s_waitcnt lgkmcnt(0)" ::: "memory")
; __device__ __forceinline__ void rot_finish(float (&v)[32], bf16* WT, int ldk, const RotItem r, LAS float* scr, int lane, unsigned* cmax) {
;     ...
;     for (int i = 0; i < 32; ++i) scr[(32 * hf + i) * 33 + nn] = v[i];
;     LDS_WAIT(); asm volatile("" ::: "memory");
;     const int c = lane & 7;
; #pragma unroll
;     for (int j = 0; j < 4; ++j) { const int n = (lane >> 3) + 8 * j; const LAS float* sp = scr + (8 * c) * 33 + n;
;         v4u o; o.x = cvt_pk_bf16(sp[0 * 33], sp[1 * 33]); o.y = cvt_pk_bf16(sp[2 * 33], sp[3 * 33]);
;         o.z = cvt_pk_bf16(sp[4 * 33], sp[5 * 33]); o.w = cvt_pk_bf16(sp[6 * 33], sp[7 * 33]);
;         *(v4u*)(WT + (size_t)(r.drow0 + n) * ldk + r.k0 + 8 * c) = o; }
;     LDS_WAIT(); asm volatile("" ::: "memory");
; }
; template <class MapF>
; __device__ __forceinline__ void rot_stream(const float* W, int ld, bf16* WT, int ldk, LAS float* scr, int lane, unsigned* cmax, int it, int nitems, int stride, const MapF map) {
;     if (it >= nitems) return;
;     float va[32], vb[32]; RotItem ra = map(it), rb = ra;
;     rot_load(va, W, ld, ra, lane);
; #pragma unroll 1
;     while (true) {
;         const int itb = it + stride; const bool hb = itb < nitems;
;         if (hb) { rb = map(itb); rot_load(vb, W, ld, rb, lane); }
;         rot_finish(va, WT, ldk, ra, scr, lane, cmax);
;         if (!hb) break;
;         it = itb + stride; const bool ha = it < nitems;
;         if (ha) { ra = map(it); rot_load(va, W, ld, ra, lane); }
.LBB0_762:
	s_or_b64 exec, exec, s[58:59]
	v_add_u32_e32 v99, 0x400, v91
	v_add_u32_e32 v100, 0x800, v91
	v_add_u32_e32 v101, 0xc00, v91
	v_add_u32_e32 v102, v90, v92
	ds_write2_b32 v91, v8, v9 offset1:33
	ds_write2_b32 v91, v74, v75 offset0:66 offset1:99
	ds_write2_b32 v91, v10, v11 offset0:132 offset1:165
	ds_write2_b32 v91, v76, v77 offset0:198 offset1:231
	ds_write2_b32 v99, v12, v13 offset0:8 offset1:41
	ds_write2_b32 v99, v78, v79 offset0:74 offset1:107
	ds_write2_b32 v99, v14, v15 offset0:140 offset1:173
	ds_write2_b32 v99, v80, v81 offset0:206 offset1:239
	ds_write2_b32 v100, v26, v27 offset0:16 offset1:49
	ds_write2_b32 v100, v82, v83 offset0:82 offset1:115
	ds_write2_b32 v100, v28, v29 offset0:148 offset1:181
	ds_write2_b32 v100, v84, v85 offset0:214 offset1:247
	ds_write2_b32 v101, v48, v49 offset0:24 offset1:57
	ds_write2_b32 v101, v86, v87 offset0:90 offset1:123
	ds_write2_b32 v101, v50, v51 offset0:156 offset1:189
	ds_write_b32 v91, v88 offset:3960
	ds_write_b32 v102, v89
	s_waitcnt lgkmcnt(0)
	s_waitcnt lgkmcnt(14)
	ds_read2_b32 v[54:55], v94 offset1:33
	s_waitcnt lgkmcnt(0)
	v_cvt_pk_bf16_f32 v60, v54, v55
	ds_read2_b32 v[54:55], v94 offset0:66 offset1:99
	s_waitcnt lgkmcnt(0)
	v_cvt_pk_bf16_f32 v61, v54, v55
	ds_read2_b32 v[54:55], v94 offset0:132 offset1:165
	s_ashr_i32 s53, s52, 31
	s_waitcnt lgkmcnt(0)
	v_cvt_pk_bf16_f32 v62, v54, v55
	ds_read2_b32 v[54:55], v94 offset0:198 offset1:231
	v_lshl_add_u64 v[64:65], s[52:53], 1, v[6:7]
	v_or_b32_e32 v66, s54, v93
	s_waitcnt lgkmcnt(0)
	v_cvt_pk_bf16_f32 v63, v54, v55
	ds_read2_b32 v[54:55], v94 offset0:8 offset1:41
	v_mad_i64_i32 v[66:67], s[58:59], v66, s67, v[64:65]
	global_store_dwordx4 v[66:67], v[60:63], off
	v_or_b32_e32 v66, s54, v95
	v_mad_i64_i32 v[66:67], s[58:59], v66, s67, v[64:65]
	s_waitcnt lgkmcnt(0)
	v_cvt_pk_bf16_f32 v60, v54, v55
	ds_read2_b32 v[54:55], v94 offset0:74 offset1:107
	s_waitcnt lgkmcnt(0)
	v_cvt_pk_bf16_f32 v61, v54, v55
	ds_read2_b32 v[54:55], v94 offset0:140 offset1:173
	s_waitcnt lgkmcnt(0)
	v_cvt_pk_bf16_f32 v62, v54, v55
	ds_read2_b32 v[54:55], v94 offset0:206 offset1:239
	s_waitcnt lgkmcnt(0)
	v_cvt_pk_bf16_f32 v63, v54, v55
	ds_read2_b32 v[54:55], v94 offset0:16 offset1:49
	global_store_dwordx4 v[66:67], v[60:63], off
	v_or_b32_e32 v66, s54, v96
	v_mad_i64_i32 v[66:67], s[58:59], v66, s67, v[64:65]
	s_waitcnt lgkmcnt(0)
	v_cvt_pk_bf16_f32 v60, v54, v55
	ds_read2_b32 v[54:55], v94 offset0:82 offset1:115
	s_waitcnt lgkmcnt(0)
	v_cvt_pk_bf16_f32 v61, v54, v55
	ds_read2_b32 v[54:55], v94 offset0:148 offset1:181
	s_waitcnt lgkmcnt(0)
	v_cvt_pk_bf16_f32 v62, v54, v55
	ds_read2_b32 v[54:55], v94 offset0:214 offset1:247
	s_waitcnt lgkmcnt(0)
	v_cvt_pk_bf16_f32 v63, v54, v55
	ds_read2_b32 v[54:55], v94 offset0:24 offset1:57
	global_store_dwordx4 v[66:67], v[60:63], off
	s_andn2_b64 vcc, exec, s[56:57]
	s_mov_b64 s[56:57], -1
	s_waitcnt lgkmcnt(0)
	v_cvt_pk_bf16_f32 v60, v54, v55
	ds_read2_b32 v[54:55], v94 offset0:90 offset1:123
	v_or_b32_e32 v63, s54, v97
	s_waitcnt lgkmcnt(0)
	v_cvt_pk_bf16_f32 v61, v54, v55
	ds_read2_b32 v[54:55], v94 offset0:156 offset1:189
	v_mad_i64_i32 v[64:65], s[58:59], v63, s67, v[64:65]
	s_waitcnt lgkmcnt(0)
	v_cvt_pk_bf16_f32 v62, v54, v55
	ds_read2_b32 v[54:55], v94 offset0:222 offset1:255
	s_waitcnt lgkmcnt(0)
	v_cvt_pk_bf16_f32 v63, v54, v55
	global_store_dwordx4 v[64:65], v[60:63], off
	s_waitcnt lgkmcnt(0)
	s_cbranch_vccnz .LBB0_757
	v_readlane_b32 s1, v249, 40
	s_add_i32 s1, s66, s1
	s_cmpk_gt_i32 s1, 0x55ff
	s_cbranch_scc1 .LBB0_765
; __device__ __forceinline__ void rot_load(float (&v)[32], const float* W, int ld, const RotItem r, int lane) {
;     const float* wp = W + (size_t)(r.k0 + 32 * (lane >> 5)) * ld + r.n0 + (lane & 31);
; #pragma unroll
;     for (int i = 0; i < 32; ++i) v[i] = wp[(size_t)i * ld];
; }
; template <class MapF>
; __device__ __forceinline__ void rot_stream(const float* W, int ld, bf16* WT, int ldk, LAS float* scr, int lane, unsigned* cmax, int it, int nitems, int stride, const MapF map) {
;     ...
;         it = itb + stride; const bool ha = it < nitems;
;         if (ha) { ra = map(it); rot_load(va, W, ld, ra, lane); }
	s_ashr_i32 s5, s1, 31
	s_lshr_b32 s5, s5, 25
	s_add_i32 s5, s1, s5
	s_ashr_i32 s52, s5, 7
	s_lshl_b32 s52, s52, 6
	s_and_b32 s5, s5, 0x7ffff80
	v_or_b32_e32 v8, s52, v1
	s_sub_i32 s1, s1, s5
	v_ashrrev_i32_e32 v9, 31, v8
	v_readlane_b32 s80, v249, 43
	s_lshl_b32 s54, s1, 5
	v_lshlrev_b64 v[8:9], 14, v[8:9]
	v_readlane_b32 s92, v249, 55
	v_readlane_b32 s93, v249, 56
	s_ashr_i32 s55, s54, 31
	v_readlane_b32 s81, v249, 44
	v_lshl_add_u64 v[8:9], s[92:93], 0, v[8:9]
	v_lshl_add_u64 v[8:9], s[54:55], 2, v[8:9]
	v_lshl_add_u64 v[48:49], v[8:9], 0, v[2:3]
	v_add_co_u32_e32 v8, vcc, s6, v48
	v_readlane_b32 s82, v249, 45
	s_nop 0
	v_addc_co_u32_e32 v9, vcc, 0, v49, vcc
	v_add_co_u32_e32 v10, vcc, s7, v48
	v_readlane_b32 s83, v249, 46
	s_nop 0
	v_addc_co_u32_e32 v11, vcc, 0, v49, vcc
	v_add_co_u32_e32 v12, vcc, s8, v48
	v_readlane_b32 s84, v249, 47
	s_nop 0
	v_addc_co_u32_e32 v13, vcc, 0, v49, vcc
	v_add_co_u32_e32 v14, vcc, s11, v48
	v_readlane_b32 s85, v249, 48
	s_nop 0
	v_addc_co_u32_e32 v15, vcc, 0, v49, vcc
	v_add_co_u32_e32 v26, vcc, s12, v48
	v_readlane_b32 s86, v249, 49
	s_nop 0
	v_addc_co_u32_e32 v27, vcc, 0, v49, vcc
	v_add_co_u32_e32 v28, vcc, s13, v48
	v_readlane_b32 s87, v249, 50
	s_nop 0
	v_addc_co_u32_e32 v29, vcc, 0, v49, vcc
	v_add_co_u32_e32 v50, vcc, s16, v48
	v_readlane_b32 s88, v249, 51
	s_nop 0
	v_addc_co_u32_e32 v51, vcc, 0, v49, vcc
	global_load_dword v61, v[48:49], off nt
	s_nop 0
	global_load_dword v9, v[8:9], off nt
	s_nop 0
	global_load_dword v60, v[10:11], off nt
	global_load_dword v8, v[12:13], off nt
	global_load_dword v55, v[14:15], off nt
	s_nop 0
	global_load_dword v11, v[26:27], off nt
	global_load_dword v54, v[28:29], off nt
	global_load_dword v10, v[50:51], off nt
	v_add_co_u32_e32 v12, vcc, s17, v48
	v_readlane_b32 s89, v249, 52
	s_nop 0
	v_addc_co_u32_e32 v13, vcc, 0, v49, vcc
	v_add_co_u32_e32 v14, vcc, s18, v48
	v_readlane_b32 s90, v249, 53
	s_nop 0
	v_addc_co_u32_e32 v15, vcc, 0, v49, vcc
	v_add_co_u32_e32 v26, vcc, s19, v48
	v_readlane_b32 s91, v249, 54
	s_nop 0
	v_addc_co_u32_e32 v27, vcc, 0, v49, vcc
	v_add_co_u32_e32 v28, vcc, s20, v48
	v_readlane_b32 s94, v249, 57
	s_nop 0
	v_addc_co_u32_e32 v29, vcc, 0, v49, vcc
	v_add_co_u32_e32 v50, vcc, s21, v48
	v_readlane_b32 s95, v249, 58
	s_nop 0
	v_addc_co_u32_e32 v51, vcc, 0, v49, vcc
	v_add_co_u32_e32 v66, vcc, s23, v48
	s_nop 1
	v_addc_co_u32_e32 v67, vcc, 0, v49, vcc
	v_add_co_u32_e32 v68, vcc, s24, v48
	s_nop 1
	v_addc_co_u32_e32 v69, vcc, 0, v49, vcc
	v_add_co_u32_e32 v70, vcc, s25, v48
	s_nop 1
	v_addc_co_u32_e32 v71, vcc, 0, v49, vcc
	global_load_dword v65, v[12:13], off nt
	s_nop 0
	global_load_dword v13, v[14:15], off nt
	global_load_dword v64, v[26:27], off nt
	global_load_dword v12, v[28:29], off nt
	global_load_dword v63, v[50:51], off nt
	s_nop 0
	global_load_dword v15, v[66:67], off nt
	global_load_dword v62, v[68:69], off nt
	global_load_dword v14, v[70:71], off nt
	v_add_co_u32_e32 v26, vcc, s26, v48
	s_nop 1
	v_addc_co_u32_e32 v27, vcc, 0, v49, vcc
	v_add_co_u32_e32 v28, vcc, s27, v48
	s_nop 1
	v_addc_co_u32_e32 v29, vcc, 0, v49, vcc
	v_add_co_u32_e32 v50, vcc, s28, v48
	s_nop 1
	v_addc_co_u32_e32 v51, vcc, 0, v49, vcc
	v_add_co_u32_e32 v66, vcc, s29, v48
	s_nop 1
	v_addc_co_u32_e32 v67, vcc, 0, v49, vcc
	v_add_co_u32_e32 v70, vcc, s33, v48
	s_nop 1
	v_addc_co_u32_e32 v71, vcc, 0, v49, vcc
	v_add_co_u32_e32 v72, vcc, s35, v48
	s_nop 1
	v_addc_co_u32_e32 v73, vcc, 0, v49, vcc
	v_add_co_u32_e32 v74, vcc, s36, v48
	s_nop 1
	v_addc_co_u32_e32 v75, vcc, 0, v49, vcc
	v_add_co_u32_e32 v76, vcc, s37, v48
	s_nop 1
	v_addc_co_u32_e32 v77, vcc, 0, v49, vcc
	global_load_dword v69, v[26:27], off nt
	s_nop 0
	global_load_dword v27, v[28:29], off nt
	global_load_dword v68, v[50:51], off nt
	global_load_dword v26, v[66:67], off nt
	s_nop 0
	global_load_dword v67, v[70:71], off nt
	global_load_dword v29, v[72:73], off nt
	global_load_dword v66, v[74:75], off nt
	global_load_dword v28, v[76:77], off nt
	v_add_co_u32_e32 v50, vcc, s46, v48
	s_nop 1
	v_addc_co_u32_e32 v51, vcc, 0, v49, vcc
	v_add_co_u32_e32 v70, vcc, s47, v48
	s_nop 1
	v_addc_co_u32_e32 v71, vcc, 0, v49, vcc
	v_add_co_u32_e32 v74, vcc, s60, v48
	s_nop 1
	v_addc_co_u32_e32 v75, vcc, 0, v49, vcc
	v_add_co_u32_e32 v76, vcc, s61, v48
	s_nop 1
	v_addc_co_u32_e32 v77, vcc, 0, v49, vcc
	v_add_co_u32_e32 v78, vcc, s62, v48
	s_nop 1
	v_addc_co_u32_e32 v79, vcc, 0, v49, vcc
	v_add_co_u32_e32 v80, vcc, 0x74000, v48
	s_nop 1
	v_addc_co_u32_e32 v81, vcc, 0, v49, vcc
	v_add_co_u32_e32 v82, vcc, 0x78000, v48
	s_nop 1
	v_addc_co_u32_e32 v83, vcc, 0, v49, vcc
	v_add_co_u32_e32 v84, vcc, 0x7c000, v48
	s_nop 1
	v_addc_co_u32_e32 v85, vcc, 0, v49, vcc
	global_load_dword v73, v[50:51], off nt
	global_load_dword v49, v[70:71], off nt
	global_load_dword v72, v[74:75], off nt
	global_load_dword v48, v[76:77], off nt
	s_nop 0
	global_load_dword v71, v[78:79], off nt
	global_load_dword v51, v[80:81], off nt
	global_load_dword v70, v[82:83], off nt
	global_load_dword v50, v[84:85], off nt
	s_branch .LBB0_766

; __device__ __forceinline__ float bf_lo(unsigned w) { return __uint_as_float(w << 16); }
; __device__ __forceinline__ float bf_hi(unsigned w) { return __uint_as_float(w & 0xffff0000u); }
; __device__ __forceinline__ float dot4(f32x4 a) { return (a.x * a.x + a.y * a.y) + (a.z * a.z + a.w * a.w); }
; __global__ void __launch_bounds__(NWAVES * 64, 2) fwd_kernel(Args args) {
;     ...
;             for (int slot = vcu; slot < M / 8; slot += G) {
;                 const int b = slot / (SEQ / 8);
;                 if (b != cur_b) { __syncthreads();
;                     for (int i = tid; i < D; i += NWAVES * 64) { cG[i] = mod[b * NMOD + 2 * D + i] * g_mix_post[i]; cA[i] = g_ffn_pre[i] * (1.0f + mod[b * NMOD + 4 * D + i]); cB[i] = mod[b * NMOD + 3 * D + i]; }
;                     __syncthreads(); cur_b = b; }
;                 { const size_t row = (size_t)slot * 8 + wave;
;                     const f32x4* xr = (const f32x4*)(x + row * D) + lane; const v2u* yr = (const v2u*)(Y + row * D) + lane;
;                     f32x4 v[16]; v2u yv[16]; float sy = 0.f;
; #pragma unroll
;                     for (int j = 0; j < 16; ++j) { v[j] = xr[64 * j]; yv[j] = yr[64 * j]; }
; #pragma unroll
;                     for (int j = 0; j < 16; ++j) { const f32x4 y = {bf_lo(yv[j].x), bf_hi(yv[j].x), bf_lo(yv[j].y), bf_hi(yv[j].y)}; sy += dot4(y); }
;                     const float rstdy = 1.0f / sqrtf(wave_sum(sy) * (1.0f / D) + RMS_EPS);
.LBB0_773:
	v_add_u32_e32 v9, s20, v7
	v_add_u32_e32 v8, 0x2200, v9
	v_add_u32_e32 v10, 0x4200, v9
	v_add_u32_e32 v12, 0x3200, v9
	v_ashrrev_i32_e32 v9, 31, v8
	v_ashrrev_i32_e32 v11, 31, v10
	v_ashrrev_i32_e32 v13, 31, v12
	v_lshl_add_u64 v[8:9], v[8:9], 2, s[30:31]
	v_lshl_add_u64 v[10:11], v[10:11], 2, s[30:31]
	global_load_dword v14, v[4:5], off nt
	global_load_dword v15, v[2:3], off nt
	v_lshl_add_u64 v[12:13], v[12:13], 2, s[30:31]
	global_load_dword v8, v[8:9], off nt
	s_nop 0
	global_load_dword v9, v[10:11], off nt
	s_nop 0
	global_load_dword v10, v[12:13], off nt
	v_add_u32_e32 v7, 0x200, v7
	v_cmp_lt_u32_e32 vcc, s6, v7
	v_lshl_add_u64 v[4:5], v[4:5], 0, s[4:5]
	v_lshl_add_u64 v[2:3], v[2:3], 0, s[4:5]
	s_or_b64 s[0:1], vcc, s[0:1]
	s_waitcnt vmcnt(2)
	v_mul_f32_e32 v8, v8, v14
	s_waitcnt vmcnt(1)
	v_add_f32_e32 v9, 1.0, v9
	v_mul_f32_e32 v9, v15, v9
	s_waitcnt vmcnt(0)
	ds_write_b32 v6, v10 offset:32768
	ds_write2st64_b32 v6, v8, v9 offset1:64
	v_add_u32_e32 v6, 0x800, v6
	s_andn2_b64 exec, exec, s[0:1]
	s_cbranch_execnz .LBB0_773
	s_or_b64 exec, exec, s[0:1]
	s_mov_b32 s20, s21
	s_waitcnt lgkmcnt(0)
	s_barrier
.LBB0_775:
	s_lshl_b64 s[0:1], s[22:23], 3
	v_readlane_b32 s24, v249, 38
	s_add_u32 s36, s0, s24
	s_addc_u32 s37, s1, 0
	s_lshl_b64 s[44:45], s[36:37], 13
	v_lshl_add_u64 v[2:3], v[42:43], 0, s[44:45]
	global_load_dwordx2 v[4:5], v[2:3], off nt
	global_load_dwordx2 v[6:7], v[2:3], off offset:512 nt
	global_load_dwordx2 v[8:9], v[2:3], off offset:1024 nt
	global_load_dwordx2 v[10:11], v[2:3], off offset:1536 nt
	global_load_dwordx2 v[12:13], v[2:3], off offset:2048 nt
	global_load_dwordx2 v[14:15], v[2:3], off offset:2560 nt
	global_load_dwordx2 v[16:17], v[2:3], off offset:3072 nt
	global_load_dwordx2 v[18:19], v[2:3], off offset:3584 nt
	v_add_co_u32_e32 v2, vcc, s7, v2
	s_lshl_b64 s[0:1], s[36:37], 14
	s_nop 0
	v_addc_co_u32_e32 v3, vcc, 0, v3, vcc
	global_load_dwordx2 v[20:21], v[2:3], off nt
	global_load_dwordx2 v[22:23], v[2:3], off offset:512 nt
	global_load_dwordx2 v[24:25], v[2:3], off offset:1024 nt
	global_load_dwordx2 v[26:27], v[2:3], off offset:1536 nt
	global_load_dwordx2 v[28:29], v[2:3], off offset:2048 nt
	global_load_dwordx2 v[30:31], v[2:3], off offset:2560 nt
	global_load_dwordx2 v[32:33], v[2:3], off offset:3072 nt
	s_nop 0
	global_load_dwordx2 v[2:3], v[2:3], off offset:3584 nt
	v_lshl_add_u64 v[134:135], v[44:45], 0, s[44:45]
	v_readlane_b32 s25, v249, 39
	s_waitcnt vmcnt(15)
	v_and_b32_e32 v97, 0xffff0000, v4
	v_and_b32_e32 v99, 0xffff0000, v5
	v_lshlrev_b32_e32 v96, 16, v4
	s_waitcnt vmcnt(12)
	v_lshlrev_b32_e32 v133, 16, v10
	v_lshlrev_b32_e32 v98, 16, v5
	v_and_b32_e32 v65, 0xffff0000, v7
	v_and_b32_e32 v64, 0xffff0000, v6
	s_waitcnt vmcnt(8)
	v_lshlrev_b32_e32 v123, 16, v18
	v_lshlrev_b32_e32 v66, 16, v8
	v_and_b32_e32 v67, 0xffff0000, v8
	v_lshlrev_b32_e32 v68, 16, v9
	v_and_b32_e32 v69, 0xffff0000, v9
	v_mul_f32_e32 v4, v99, v99
	v_mul_f32_e32 v8, v97, v97
	v_mov_b32_e32 v5, v133
	v_mov_b32_e32 v9, v123
	v_lshlrev_b32_e32 v63, 16, v7
	v_lshlrev_b32_e32 v62, 16, v6
	v_and_b32_e32 v121, 0xffff0000, v18
	v_lshlrev_b32_e32 v118, 16, v19
	v_and_b32_e32 v119, 0xffff0000, v19
	v_pk_mul_f32 v[6:7], v[64:65], v[64:65]
	v_pk_fma_f32 v[18:19], v[98:99], v[98:99], v[4:5] op_sel_hi:[1,1,0]
	v_pk_fma_f32 v[34:35], v[96:97], v[96:97], v[8:9] op_sel_hi:[1,1,0]
	v_and_b32_e32 v73, 0xffff0000, v10
	v_lshlrev_b32_e32 v70, 16, v11
	v_and_b32_e32 v71, 0xffff0000, v11
	v_lshlrev_b32_e32 v74, 16, v12
	v_and_b32_e32 v76, 0xffff0000, v12
	v_mul_f32_e32 v10, v67, v67
	v_mul_f32_e32 v12, v69, v69
	v_pk_fma_f32 v[6:7], v[62:63], v[62:63], v[6:7]
	v_mov_b32_e32 v132, v34
	v_mov_b32_e32 v4, v18
	v_lshlrev_b32_e32 v75, 16, v13
	v_and_b32_e32 v77, 0xffff0000, v13
	v_mul_f32_e32 v36, v73, v73
	v_mul_f32_e32 v37, v70, v70
	v_mul_f32_e32 v38, v71, v71
	v_pk_fma_f32 v[10:11], v[66:67], v[66:67], v[10:11] op_sel_hi:[1,1,0]
	v_pk_fma_f32 v[12:13], v[68:69], v[68:69], v[12:13] op_sel_hi:[1,1,0]
	v_pk_add_f32 v[18:19], v[34:35], v[18:19]
	v_pk_add_f32 v[6:7], v[6:7], v[6:7] op_sel:[0,1] op_sel_hi:[1,0]
	v_pk_mul_f32 v[4:5], v[132:133], v[4:5]
	v_mov_b32_e32 v11, v37
	v_mov_b32_e32 v13, v38
	v_mov_b32_e32 v7, v36
	v_mov_b32_e32 v19, v5
	v_lshlrev_b32_e32 v81, 16, v15
	v_lshlrev_b32_e32 v80, 16, v14
	v_and_b32_e32 v87, 0xffff0000, v15
	v_and_b32_e32 v86, 0xffff0000, v14
	v_pk_mul_f32 v[14:15], v[76:77], v[76:77]
	v_pk_add_f32 v[10:11], v[10:11], v[12:13]
	v_pk_add_f32 v[4:5], v[18:19], v[6:7]
	v_pk_fma_f32 v[14:15], v[74:75], v[74:75], v[14:15]
	v_pk_add_f32 v[4:5], v[4:5], v[10:11]
	v_pk_add_f32 v[14:15], v[14:15], v[14:15] op_sel:[0,1] op_sel_hi:[1,0]
	v_pk_add_f32 v[4:5], v[4:5], v[4:5] op_sel:[0,1] op_sel_hi:[1,0]
	v_lshlrev_b32_e32 v90, 16, v16
	v_and_b32_e32 v91, 0xffff0000, v16
	v_lshlrev_b32_e32 v94, 16, v17
	v_and_b32_e32 v95, 0xffff0000, v17
	v_pk_mul_f32 v[16:17], v[86:87], v[86:87]
	v_mov_b32_e32 v8, v14
	v_mov_b32_e32 v122, v4
	v_pk_fma_f32 v[16:17], v[80:81], v[80:81], v[16:17]
	v_pk_add_f32 v[4:5], v[4:5], v[14:15]
	v_pk_mul_f32 v[6:7], v[122:123], v[8:9]
	v_mul_f32_e32 v72, v121, v121
	v_mov_b32_e32 v5, v7
	v_pk_add_f32 v[6:7], v[16:17], v[16:17] op_sel:[0,1] op_sel_hi:[1,0]
	v_mul_f32_e32 v8, v95, v95
	v_mov_b32_e32 v7, v72
	v_pk_add_f32 v[4:5], v[4:5], v[6:7]
	v_mul_f32_e32 v6, v91, v91
	v_mul_f32_e32 v78, v118, v118
	v_mul_f32_e32 v79, v119, v119
	v_pk_fma_f32 v[6:7], v[90:91], v[90:91], v[6:7] op_sel_hi:[1,1,0]
	v_pk_fma_f32 v[8:9], v[94:95], v[94:95], v[8:9] op_sel_hi:[1,1,0]
	v_mov_b32_e32 v7, v78
	v_mov_b32_e32 v9, v79
	v_pk_add_f32 v[6:7], v[6:7], v[8:9]
	s_waitcnt vmcnt(7)
; __device__ __forceinline__ unsigned cvt_pk_bf16(float lo, float hi) { unsigned r; asm volatile("v_cvt_pk_bf16_f32 %0, %1, %2" : "=v"(r) : "v"(lo), "v"(hi)); return r; }
; __device__ __forceinline__ float bf_lo(unsigned w) { return __uint_as_float(w << 16); }
; __device__ __forceinline__ float bf_hi(unsigned w) { return __uint_as_float(w & 0xffff0000u); }
; #define LAS __attribute__((address_space(3)))
; __device__ __forceinline__ float dot4(f32x4 a) { return (a.x * a.x + a.y * a.y) + (a.z * a.z + a.w * a.w); }
; __global__ void __launch_bounds__(NWAVES * 64, 2) fwd_kernel(Args args) {
;     ...
;                     f32x4 v[16]; v2u yv[16]; float sy = 0.f;
; #pragma unroll
;                     for (int j = 0; j < 16; ++j) { v[j] = xr[64 * j]; yv[j] = yr[64 * j]; }
; #pragma unroll
;                     for (int j = 0; j < 16; ++j) { const f32x4 y = {bf_lo(yv[j].x), bf_hi(yv[j].x), bf_lo(yv[j].y), bf_hi(yv[j].y)}; sy += dot4(y); }
;                     const float rstdy = 1.0f / sqrtf(wave_sum(sy) * (1.0f / D) + RMS_EPS);
;                     float s1 = 0.f; v2u* orow = (v2u*)(X1B + row * D) + lane;
; #pragma unroll
;                     for (int j = 0; j < 16; ++j) { const f32x4 y = {bf_lo(yv[j].x), bf_hi(yv[j].x), bf_lo(yv[j].y), bf_hi(yv[j].y)}; const f32x4 gq = ((const LAS f32x4*)cG)[lane + 64 * j];
;                         v[j] = v[j] + gq * (y * rstdy); s1 += dot4(v[j]); v2u w; w.x = cvt_pk_bf16(v[j].x, v[j].y); w.y = cvt_pk_bf16(v[j].z, v[j].w); orow[64 * j] = w; }
	v_and_b32_e32 v131, 0xffff0000, v21
	v_and_b32_e32 v130, 0xffff0000, v20
	v_pk_add_f32 v[4:5], v[4:5], v[6:7]
	v_lshlrev_b32_e32 v129, 16, v21
	v_lshlrev_b32_e32 v128, 16, v20
	v_pk_mul_f32 v[6:7], v[130:131], v[130:131]
	s_waitcnt vmcnt(6)
	v_and_b32_e32 v127, 0xffff0000, v23
	v_pk_fma_f32 v[6:7], v[128:129], v[128:129], v[6:7]
	v_and_b32_e32 v126, 0xffff0000, v22
	v_pk_add_f32 v[6:7], v[6:7], v[6:7] op_sel:[0,1] op_sel_hi:[1,0]
	s_waitcnt vmcnt(4)
	v_lshlrev_b32_e32 v109, 16, v26
	v_pk_add_f32 v[4:5], v[4:5], v[4:5] op_sel:[0,1] op_sel_hi:[1,0]
	v_lshlrev_b32_e32 v125, 16, v23
	v_lshlrev_b32_e32 v124, 16, v22
	v_pk_mul_f32 v[8:9], v[126:127], v[126:127]
	v_mov_b32_e32 v108, v4
	v_mov_b32_e32 v10, v6
	v_mov_b32_e32 v11, v109
	v_pk_fma_f32 v[8:9], v[124:125], v[124:125], v[8:9]
	v_and_b32_e32 v107, 0xffff0000, v26
	v_pk_add_f32 v[4:5], v[4:5], v[6:7]
	v_pk_mul_f32 v[6:7], v[108:109], v[10:11]
	v_mul_f32_e32 v12, v107, v107
	v_mov_b32_e32 v5, v7
	v_pk_add_f32 v[6:7], v[8:9], v[8:9] op_sel:[0,1] op_sel_hi:[1,0]
	v_and_b32_e32 v115, 0xffff0000, v24
	v_and_b32_e32 v117, 0xffff0000, v25
	v_mov_b32_e32 v7, v12
	v_lshlrev_b32_e32 v114, 16, v24
	v_lshlrev_b32_e32 v116, 16, v25
	v_lshlrev_b32_e32 v104, 16, v27
	v_and_b32_e32 v105, 0xffff0000, v27
	v_pk_add_f32 v[4:5], v[4:5], v[6:7]
	v_mul_f32_e32 v6, v115, v115
	v_mul_f32_e32 v8, v117, v117
	v_mul_f32_e32 v13, v104, v104
	v_mul_f32_e32 v14, v105, v105
	v_pk_fma_f32 v[6:7], v[114:115], v[114:115], v[6:7] op_sel_hi:[1,1,0]
	v_pk_fma_f32 v[8:9], v[116:117], v[116:117], v[8:9] op_sel_hi:[1,1,0]
	v_mov_b32_e32 v7, v13
	v_mov_b32_e32 v9, v14
	v_pk_add_f32 v[6:7], v[6:7], v[8:9]
	s_waitcnt vmcnt(3)
	v_and_b32_e32 v113, 0xffff0000, v29
	v_and_b32_e32 v112, 0xffff0000, v28
	v_pk_add_f32 v[4:5], v[4:5], v[6:7]
	v_lshlrev_b32_e32 v111, 16, v29
	v_lshlrev_b32_e32 v110, 16, v28
	v_pk_mul_f32 v[6:7], v[112:113], v[112:113]
	s_waitcnt vmcnt(2)
	v_and_b32_e32 v103, 0xffff0000, v31
	v_pk_fma_f32 v[6:7], v[110:111], v[110:111], v[6:7]
	v_and_b32_e32 v102, 0xffff0000, v30
	v_pk_add_f32 v[6:7], v[6:7], v[6:7] op_sel:[0,1] op_sel_hi:[1,0]
	s_waitcnt vmcnt(0)
	v_lshlrev_b32_e32 v85, 16, v2
	v_and_b32_e32 v83, 0xffff0000, v2
	v_lshlrev_b32_e32 v78, 16, v3
	v_and_b32_e32 v79, 0xffff0000, v3
	v_pk_add_f32 v[2:3], v[4:5], v[4:5] op_sel:[0,1] op_sel_hi:[1,0]
	v_lshlrev_b32_e32 v101, 16, v31
	v_lshlrev_b32_e32 v100, 16, v30
	v_pk_mul_f32 v[8:9], v[102:103], v[102:103]
	v_mov_b32_e32 v84, v2
	v_mov_b32_e32 v4, v6
	v_mov_b32_e32 v5, v85
	v_pk_fma_f32 v[8:9], v[100:101], v[100:101], v[8:9]
	v_pk_add_f32 v[2:3], v[2:3], v[6:7]
	v_pk_mul_f32 v[4:5], v[84:85], v[4:5]
	v_mul_f32_e32 v10, v83, v83
	v_mov_b32_e32 v3, v5
	v_pk_add_f32 v[4:5], v[8:9], v[8:9] op_sel:[0,1] op_sel_hi:[1,0]
	v_and_b32_e32 v89, 0xffff0000, v32
	v_and_b32_e32 v93, 0xffff0000, v33
	v_mov_b32_e32 v5, v10
	v_lshlrev_b32_e32 v88, 16, v32
	v_lshlrev_b32_e32 v92, 16, v33
	v_pk_add_f32 v[2:3], v[2:3], v[4:5]
	v_mul_f32_e32 v4, v89, v89
	v_mul_f32_e32 v6, v93, v93
	v_mul_f32_e32 v11, v78, v78
	v_mul_f32_e32 v12, v79, v79
	v_pk_fma_f32 v[4:5], v[88:89], v[88:89], v[4:5] op_sel_hi:[1,1,0]
	v_pk_fma_f32 v[6:7], v[92:93], v[92:93], v[6:7] op_sel_hi:[1,1,0]
	v_mov_b32_e32 v5, v11
	v_mov_b32_e32 v7, v12
	v_pk_add_f32 v[4:5], v[4:5], v[6:7]
	v_mov_b32_e32 v120, v123
	v_pk_add_f32 v[2:3], v[2:3], v[4:5]
	s_nop 0
	v_add_f32_e32 v4, v2, v3
	v_lshl_add_u64 v[2:3], v[40:41], 0, s[0:1]
	global_load_dwordx4 v[148:151], v[2:3], off nt
	global_load_dwordx4 v[152:155], v[2:3], off offset:1024 nt
	global_load_dwordx4 v[156:159], v[2:3], off offset:2048 nt
	global_load_dwordx4 v[160:163], v[2:3], off offset:3072 nt
	ds_bpermute_b32 v5, v136, v4
	s_waitcnt lgkmcnt(0)
	v_add_f32_e32 v4, v4, v5
	ds_bpermute_b32 v5, v137, v4
	s_waitcnt lgkmcnt(0)
	v_add_f32_e32 v4, v4, v5
	ds_bpermute_b32 v5, v138, v4
	s_waitcnt lgkmcnt(0)
	v_add_f32_e32 v6, v4, v5
	ds_bpermute_b32 v7, v139, v6
	v_add_co_u32_e32 v4, vcc, s7, v2
	s_waitcnt lgkmcnt(0)
	v_add_f32_e32 v8, v6, v7
	v_addc_co_u32_e32 v5, vcc, 0, v3, vcc
	v_add_co_u32_e32 v6, vcc, s8, v2
	global_load_dwordx4 v[164:167], v[4:5], off offset:1024 nt
	global_load_dwordx4 v[168:171], v[4:5], off offset:2048 nt
	global_load_dwordx4 v[34:37], v[4:5], off offset:3072 nt
	v_addc_co_u32_e32 v7, vcc, 0, v3, vcc
	global_load_dwordx4 v[172:175], v[6:7], off offset:-4096 nt
	global_load_dwordx4 v[30:33], v[6:7], off nt
	global_load_dwordx4 v[26:29], v[6:7], off offset:1024 nt
	global_load_dwordx4 v[22:25], v[6:7], off offset:2048 nt
	global_load_dwordx4 v[14:17], v[6:7], off offset:3072 nt
	ds_bpermute_b32 v9, v140, v8
	v_add_co_u32_e64 v2, s[0:1], s11, v2
	s_waitcnt lgkmcnt(0)
	v_add_f32_e32 v4, v8, v9
	ds_bpermute_b32 v5, v141, v4
	v_addc_co_u32_e64 v3, s[0:1], 0, v3, s[0:1]
	s_waitcnt lgkmcnt(0)
	v_add_f32_e32 v4, v4, v5
	v_fmamk_f32 v4, v4, 0x39800000, v145
	v_mul_f32_e32 v5, 0x4f800000, v4
	v_cmp_gt_f32_e32 vcc, s12, v4
	s_nop 1
	v_cndmask_b32_e32 v4, v4, v5, vcc
	v_sqrt_f32_e32 v5, v4
	s_nop 0
	v_add_u32_e32 v6, -1, v5
	v_fma_f32 v7, -v6, v5, v4
	v_cmp_ge_f32_e64 s[0:1], 0, v7
	v_add_u32_e32 v7, 1, v5
	s_nop 0
	v_cndmask_b32_e64 v6, v5, v6, s[0:1]
	v_fma_f32 v5, -v7, v5, v4
	v_cmp_lt_f32_e64 s[0:1], 0, v5
	s_nop 1
	v_cndmask_b32_e64 v5, v6, v7, s[0:1]
	v_mul_f32_e32 v6, 0x37800000, v5
	v_cndmask_b32_e32 v5, v5, v6, vcc
	v_cmp_class_f32_e32 vcc, v4, v146
	s_nop 1
	v_cndmask_b32_e32 v38, v5, v4, vcc
	v_div_scale_f32 v72, s[0:1], v38, v38, 1.0
	v_rcp_f32_e32 v82, v72
	global_load_dwordx4 v[18:21], v[2:3], off nt
	global_load_dwordx4 v[10:13], v[2:3], off offset:1024 nt
	global_load_dwordx4 v[6:9], v[2:3], off offset:2048 nt
	s_nop 0
	global_load_dwordx4 v[2:5], v[2:3], off offset:3072 nt
	ds_read_b128 v[182:185], v1
	v_fma_f32 v84, -v72, v82, 1.0
	v_fmac_f32_e32 v82, v84, v82
	v_div_scale_f32 v84, vcc, 1.0, v38, 1.0
	v_mul_f32_e32 v106, v84, v82
	v_fma_f32 v108, -v72, v106, v84
	v_fmac_f32_e32 v106, v108, v82
	v_fma_f32 v72, -v72, v106, v84
	v_div_fmas_f32 v72, v72, v82, v106
	v_div_fixup_f32 v38, v72, v38, 1.0
	v_pk_mul_f32 v[176:177], v[38:39], v[96:97] op_sel_hi:[0,1]
	v_pk_mul_f32 v[96:97], v[38:39], v[98:99] op_sel_hi:[0,1]
	s_waitcnt vmcnt(15) lgkmcnt(0)
; __device__ __forceinline__ unsigned cvt_pk_bf16(float lo, float hi) { unsigned r; asm volatile("v_cvt_pk_bf16_f32 %0, %1, %2" : "=v"(r) : "v"(lo), "v"(hi)); return r; }
; __device__ __forceinline__ float bf_lo(unsigned w) { return __uint_as_float(w << 16); }
; __device__ __forceinline__ float bf_hi(unsigned w) { return __uint_as_float(w & 0xffff0000u); }
; #define LAS __attribute__((address_space(3)))
; __device__ __forceinline__ float dot4(f32x4 a) { return (a.x * a.x + a.y * a.y) + (a.z * a.z + a.w * a.w); }
; __global__ void __launch_bounds__(NWAVES * 64, 2) fwd_kernel(Args args) {
;     ...
;                     float s1 = 0.f; v2u* orow = (v2u*)(X1B + row * D) + lane;
; #pragma unroll
;                     for (int j = 0; j < 16; ++j) { const f32x4 y = {bf_lo(yv[j].x), bf_hi(yv[j].x), bf_lo(yv[j].y), bf_hi(yv[j].y)}; const f32x4 gq = ((const LAS f32x4*)cG)[lane + 64 * j];
;                         v[j] = v[j] + gq * (y * rstdy); s1 += dot4(v[j]); v2u w; w.x = cvt_pk_bf16(v[j].x, v[j].y); w.y = cvt_pk_bf16(v[j].z, v[j].w); orow[64 * j] = w; }
;                     const float rstd1 = 1.0f / sqrtf(wave_sum(s1) * (1.0f / D) + RMS_EPS);
	v_pk_fma_f32 v[96:97], v[184:185], v[96:97], v[150:151]
	v_pk_fma_f32 v[98:99], v[182:183], v[176:177], v[148:149]
	v_pk_mul_f32 v[148:149], v[96:97], v[96:97]
	v_pk_mul_f32 v[150:151], v[98:99], v[98:99]
	v_mov_b32_e32 v182, v62
	v_pk_mov_b32 v[176:177], v[150:151], v[148:149] op_sel:[1,0]
	v_mov_b32_e32 v151, v149
	v_cvt_pk_bf16_f32 v148, v98, v99
	v_cvt_pk_bf16_f32 v149, v96, v97
	v_pk_add_f32 v[176:177], v[176:177], v[150:151]
	global_store_dwordx2 v[134:135], v[148:149], off
	ds_read_b128 v[148:151], v1 offset:1024
	v_mov_b32_e32 v183, v64
	v_mov_b32_e32 v64, v63
	v_pk_mul_f32 v[182:183], v[38:39], v[182:183] op_sel_hi:[0,1]
	v_pk_mul_f32 v[62:63], v[38:39], v[64:65] op_sel_hi:[0,1]
	s_waitcnt vmcnt(15) lgkmcnt(0)
	v_pk_fma_f32 v[62:63], v[150:151], v[62:63], v[154:155]
	v_pk_fma_f32 v[64:65], v[148:149], v[182:183], v[152:153]
	v_pk_mul_f32 v[148:149], v[62:63], v[62:63]
	v_pk_mul_f32 v[152:153], v[64:65], v[64:65]
	v_cvt_pk_bf16_f32 v182, v64, v65
	v_cvt_pk_bf16_f32 v183, v62, v63
	global_store_dwordx2 v[134:135], v[182:183], off offset:512
	v_pk_mov_b32 v[154:155], v[152:153], v[148:149] op_sel:[1,0]
	v_mov_b32_e32 v153, v149
	ds_read_b128 v[148:151], v1 offset:2048
	v_pk_add_f32 v[152:153], v[154:155], v[152:153]
	v_pk_mul_f32 v[154:155], v[38:39], v[66:67] op_sel_hi:[0,1]
	v_pk_mul_f32 v[66:67], v[38:39], v[68:69] op_sel_hi:[0,1]
	v_mov_b32_e32 v72, v133
	s_waitcnt vmcnt(15) lgkmcnt(0)
	v_pk_fma_f32 v[66:67], v[150:151], v[66:67], v[158:159]
	v_pk_fma_f32 v[68:69], v[148:149], v[154:155], v[156:157]
	v_pk_mul_f32 v[72:73], v[38:39], v[72:73] op_sel_hi:[0,1]
	v_cvt_pk_bf16_f32 v154, v68, v69
	v_cvt_pk_bf16_f32 v155, v66, v67
	ds_read_b128 v[148:151], v1 offset:3072
	v_pk_add_f32 v[132:133], v[176:177], v[176:177] op_sel:[0,1] op_sel_hi:[1,0]
	v_pk_mul_f32 v[70:71], v[38:39], v[70:71] op_sel_hi:[0,1]
	global_store_dwordx2 v[134:135], v[154:155], off offset:1024
	v_mov_b32_e32 v156, v80
	s_waitcnt vmcnt(15) lgkmcnt(0)
	v_pk_fma_f32 v[72:73], v[148:149], v[72:73], v[160:161]
	v_pk_add_f32 v[148:149], v[152:153], v[152:153] op_sel:[0,1] op_sel_hi:[1,0]
	v_mul_f32_e32 v82, v72, v72
	v_mul_f32_e32 v84, v73, v73
	v_mov_b32_e32 v133, v82
	v_mov_b32_e32 v149, v84
	v_mul_f32_e32 v82, v69, v69
	v_pk_fma_f32 v[70:71], v[150:151], v[70:71], v[162:163]
	v_pk_add_f32 v[132:133], v[132:133], v[148:149]
	v_pk_fma_f32 v[148:149], v[68:69], v[68:69], v[82:83] op_sel_hi:[1,1,0]
	v_mul_f32_e32 v82, v67, v67
	v_mul_f32_e32 v106, v70, v70
	v_mul_f32_e32 v108, v71, v71
	v_pk_fma_f32 v[150:151], v[66:67], v[66:67], v[82:83] op_sel_hi:[1,1,0]
	v_mov_b32_e32 v149, v106
	v_mov_b32_e32 v151, v108
	v_pk_add_f32 v[148:149], v[148:149], v[150:151]
	v_mov_b32_e32 v152, v74
	v_pk_add_f32 v[132:133], v[132:133], v[148:149]
	v_cvt_pk_bf16_f32 v148, v72, v73
	v_cvt_pk_bf16_f32 v149, v70, v71
	global_store_dwordx2 v[134:135], v[148:149], off offset:1536
	ds_read_b128 v[148:151], v1 offset:4096
	v_mov_b32_e32 v153, v76
	v_mov_b32_e32 v76, v75
	v_pk_mul_f32 v[152:153], v[38:39], v[152:153] op_sel_hi:[0,1]
	v_pk_mul_f32 v[74:75], v[38:39], v[76:77] op_sel_hi:[0,1]
	s_waitcnt vmcnt(12) lgkmcnt(0)
	v_pk_fma_f32 v[74:75], v[150:151], v[74:75], v[174:175]
	v_pk_fma_f32 v[76:77], v[148:149], v[152:153], v[172:173]
	v_pk_mul_f32 v[148:149], v[74:75], v[74:75]
	v_pk_mul_f32 v[152:153], v[76:77], v[76:77]
	v_mov_b32_e32 v157, v86
	v_pk_mov_b32 v[154:155], v[152:153], v[148:149] op_sel:[1,0]
	v_mov_b32_e32 v153, v149
	v_cvt_pk_bf16_f32 v148, v76, v77
	v_cvt_pk_bf16_f32 v149, v74, v75
	global_store_dwordx2 v[134:135], v[148:149], off offset:2048
	ds_read_b128 v[148:151], v1 offset:5120
	v_mov_b32_e32 v86, v81
	v_pk_mul_f32 v[156:157], v[38:39], v[156:157] op_sel_hi:[0,1]
	v_pk_mul_f32 v[80:81], v[38:39], v[86:87] op_sel_hi:[0,1]
	v_pk_add_f32 v[152:153], v[154:155], v[152:153]
	s_waitcnt lgkmcnt(0)
	v_pk_fma_f32 v[80:81], v[150:151], v[80:81], v[166:167]
	v_pk_fma_f32 v[86:87], v[148:149], v[156:157], v[164:165]
	v_pk_mul_f32 v[154:155], v[38:39], v[90:91] op_sel_hi:[0,1]
	v_cvt_pk_bf16_f32 v156, v86, v87
	v_cvt_pk_bf16_f32 v157, v80, v81
	ds_read_b128 v[148:151], v1 offset:6144
	v_pk_mul_f32 v[90:91], v[38:39], v[94:95] op_sel_hi:[0,1]
	v_pk_add_f32 v[132:133], v[132:133], v[132:133] op_sel:[0,1] op_sel_hi:[1,0]
	global_store_dwordx2 v[134:135], v[156:157], off offset:2560
	v_pk_mul_f32 v[120:121], v[38:39], v[120:121] op_sel_hi:[0,1]
	s_waitcnt lgkmcnt(0)
	v_pk_fma_f32 v[94:95], v[148:149], v[154:155], v[168:169]
	v_pk_add_f32 v[148:149], v[152:153], v[152:153] op_sel:[0,1] op_sel_hi:[1,0]
	v_mul_f32_e32 v82, v94, v94
	v_mul_f32_e32 v84, v95, v95
	v_mov_b32_e32 v133, v82
	v_mov_b32_e32 v149, v84
	v_mul_f32_e32 v82, v87, v87
	v_pk_fma_f32 v[90:91], v[150:151], v[90:91], v[170:171]
	v_pk_add_f32 v[132:133], v[132:133], v[148:149]
	v_pk_fma_f32 v[148:149], v[86:87], v[86:87], v[82:83] op_sel_hi:[1,1,0]
	v_mul_f32_e32 v82, v81, v81
	v_mul_f32_e32 v106, v90, v90
	v_mul_f32_e32 v108, v91, v91
	v_pk_fma_f32 v[150:151], v[80:81], v[80:81], v[82:83] op_sel_hi:[1,1,0]
	v_mov_b32_e32 v149, v106
	v_mov_b32_e32 v151, v108
	v_pk_add_f32 v[148:149], v[148:149], v[150:151]
	v_cvt_pk_bf16_f32 v152, v94, v95
	v_cvt_pk_bf16_f32 v153, v90, v91
	v_pk_mul_f32 v[118:119], v[38:39], v[118:119] op_sel_hi:[0,1]
	v_pk_add_f32 v[132:133], v[132:133], v[148:149]
	ds_read_b128 v[148:151], v1 offset:7168
	global_store_dwordx2 v[134:135], v[152:153], off offset:3072
	v_pk_mul_f32 v[114:115], v[38:39], v[114:115] op_sel_hi:[0,1]
	v_pk_mul_f32 v[116:117], v[38:39], v[116:117] op_sel_hi:[0,1]
	v_pk_mul_f32 v[104:105], v[38:39], v[104:105] op_sel_hi:[0,1]
	s_waitcnt lgkmcnt(0)
; __device__ __forceinline__ unsigned cvt_pk_bf16(float lo, float hi) { unsigned r; asm volatile("v_cvt_pk_bf16_f32 %0, %1, %2" : "=v"(r) : "v"(lo), "v"(hi)); return r; }
; __device__ __forceinline__ float bf_lo(unsigned w) { return __uint_as_float(w << 16); }
; __device__ __forceinline__ float bf_hi(unsigned w) { return __uint_as_float(w & 0xffff0000u); }
; #define LAS __attribute__((address_space(3)))
; __device__ __forceinline__ float dot4(f32x4 a) { return (a.x * a.x + a.y * a.y) + (a.z * a.z + a.w * a.w); }
; __global__ void __launch_bounds__(NWAVES * 64, 2) fwd_kernel(Args args) {
;     ...
;                     float s1 = 0.f; v2u* orow = (v2u*)(X1B + row * D) + lane;
; #pragma unroll
;                     for (int j = 0; j < 16; ++j) { const f32x4 y = {bf_lo(yv[j].x), bf_hi(yv[j].x), bf_lo(yv[j].y), bf_hi(yv[j].y)}; const f32x4 gq = ((const LAS f32x4*)cG)[lane + 64 * j];
;                         v[j] = v[j] + gq * (y * rstdy); s1 += dot4(v[j]); v2u w; w.x = cvt_pk_bf16(v[j].x, v[j].y); w.y = cvt_pk_bf16(v[j].z, v[j].w); orow[64 * j] = w; }
;                     const float rstd1 = 1.0f / sqrtf(wave_sum(s1) * (1.0f / D) + RMS_EPS);
	v_pk_fma_f32 v[36:37], v[150:151], v[118:119], v[36:37]
	v_pk_fma_f32 v[34:35], v[148:149], v[120:121], v[34:35]
	v_pk_mul_f32 v[120:121], v[36:37], v[36:37]
	v_pk_mul_f32 v[118:119], v[34:35], v[34:35]
	v_pk_mul_f32 v[88:89], v[38:39], v[88:89] op_sel_hi:[0,1]
	v_pk_mov_b32 v[122:123], v[118:119], v[120:121] op_sel:[1,0]
	v_mov_b32_e32 v119, v121
	v_pk_add_f32 v[148:149], v[122:123], v[118:119]
	v_cvt_pk_bf16_f32 v118, v34, v35
	v_cvt_pk_bf16_f32 v119, v36, v37
	global_store_dwordx2 v[134:135], v[118:119], off offset:3584
	ds_read_b128 v[118:121], v1 offset:8192
	v_mov_b32_e32 v122, v128
	v_mov_b32_e32 v123, v130
	v_pk_mul_f32 v[122:123], v[38:39], v[122:123] op_sel_hi:[0,1]
	v_mov_b32_e32 v130, v129
	v_pk_mul_f32 v[128:129], v[38:39], v[130:131] op_sel_hi:[0,1]
	s_waitcnt vmcnt(15) lgkmcnt(0)
	v_pk_fma_f32 v[118:119], v[118:119], v[122:123], v[30:31]
	v_add_co_u32_e32 v30, vcc, s7, v134
	v_pk_fma_f32 v[32:33], v[120:121], v[128:129], v[32:33]
	v_cvt_pk_bf16_f32 v120, v118, v119
	s_nop 0
	v_addc_co_u32_e32 v31, vcc, 0, v135, vcc
	v_cvt_pk_bf16_f32 v121, v32, v33
	global_store_dwordx2 v[30:31], v[120:121], off
	ds_read_b128 v[120:123], v1 offset:9216
	v_mov_b32_e32 v128, v124
	v_mov_b32_e32 v129, v126
	v_pk_mul_f32 v[128:129], v[38:39], v[128:129] op_sel_hi:[0,1]
	v_mov_b32_e32 v126, v125
	v_pk_mul_f32 v[124:125], v[38:39], v[126:127] op_sel_hi:[0,1]
	s_waitcnt vmcnt(15) lgkmcnt(0)
	v_pk_fma_f32 v[26:27], v[120:121], v[128:129], v[26:27]
	v_pk_fma_f32 v[28:29], v[122:123], v[124:125], v[28:29]
	v_mul_f32_e32 v82, v26, v26
	v_mul_f32_e32 v84, v27, v27
	v_pk_add_f32 v[120:121], v[132:133], v[132:133] op_sel:[0,1] op_sel_hi:[1,0]
	v_pk_add_f32 v[122:123], v[148:149], v[148:149] op_sel:[0,1] op_sel_hi:[1,0]
	v_mov_b32_e32 v121, v82
	v_mov_b32_e32 v123, v84
	v_mul_f32_e32 v82, v119, v119
	v_pk_add_f32 v[124:125], v[120:121], v[122:123]
	v_pk_fma_f32 v[120:121], v[118:119], v[118:119], v[82:83] op_sel_hi:[1,1,0]
	v_mul_f32_e32 v82, v33, v33
	v_mul_f32_e32 v106, v28, v28
	v_mul_f32_e32 v108, v29, v29
	v_pk_fma_f32 v[122:123], v[32:33], v[32:33], v[82:83] op_sel_hi:[1,1,0]
	v_mov_b32_e32 v121, v106
	v_mov_b32_e32 v123, v108
	v_pk_add_f32 v[126:127], v[120:121], v[122:123]
	v_cvt_pk_bf16_f32 v128, v26, v27
	v_cvt_pk_bf16_f32 v129, v28, v29
	ds_read_b128 v[120:123], v1 offset:10240
	global_store_dwordx2 v[30:31], v[128:129], off offset:512
	v_mov_b32_e32 v106, v109
	v_pk_mul_f32 v[106:107], v[38:39], v[106:107] op_sel_hi:[0,1]
	v_mov_b32_e32 v108, v110
	s_waitcnt vmcnt(15) lgkmcnt(0)
	v_pk_fma_f32 v[24:25], v[122:123], v[116:117], v[24:25]
	v_pk_fma_f32 v[22:23], v[120:121], v[114:115], v[22:23]
	v_pk_mul_f32 v[116:117], v[24:25], v[24:25]
	v_pk_mul_f32 v[114:115], v[22:23], v[22:23]
	v_cvt_pk_bf16_f32 v122, v22, v23
	v_cvt_pk_bf16_f32 v123, v24, v25
	global_store_dwordx2 v[30:31], v[122:123], off offset:1024
	v_pk_mov_b32 v[120:121], v[114:115], v[116:117] op_sel:[1,0]
	v_mov_b32_e32 v115, v117
	v_pk_add_f32 v[120:121], v[120:121], v[114:115]
	ds_read_b128 v[114:117], v1 offset:11264
	v_mov_b32_e32 v109, v112
	v_pk_mul_f32 v[108:109], v[38:39], v[108:109] op_sel_hi:[0,1]
	v_mov_b32_e32 v112, v111
	v_pk_add_f32 v[124:125], v[124:125], v[126:127]
	s_waitcnt vmcnt(15) lgkmcnt(0)
	v_pk_fma_f32 v[16:17], v[116:117], v[104:105], v[16:17]
	v_pk_fma_f32 v[14:15], v[114:115], v[106:107], v[14:15]
	v_pk_mul_f32 v[110:111], v[38:39], v[112:113] op_sel_hi:[0,1]
	v_cvt_pk_bf16_f32 v104, v14, v15
	v_cvt_pk_bf16_f32 v105, v16, v17
	global_store_dwordx2 v[30:31], v[104:105], off offset:1536
	ds_read_b128 v[104:107], v1 offset:12288
	v_pk_mul_f32 v[92:93], v[38:39], v[92:93] op_sel_hi:[0,1]
	v_pk_mul_f32 v[78:79], v[38:39], v[78:79] op_sel_hi:[0,1]
	s_waitcnt vmcnt(15) lgkmcnt(0)
	v_pk_fma_f32 v[18:19], v[104:105], v[108:109], v[18:19]
	v_pk_fma_f32 v[20:21], v[106:107], v[110:111], v[20:21]
	v_mul_f32_e32 v82, v18, v18
	v_mul_f32_e32 v84, v19, v19
	v_pk_add_f32 v[104:105], v[124:125], v[124:125] op_sel:[0,1] op_sel_hi:[1,0]
	v_pk_add_f32 v[106:107], v[120:121], v[120:121] op_sel:[0,1] op_sel_hi:[1,0]
	v_mov_b32_e32 v105, v82
	v_mov_b32_e32 v107, v84
	v_mul_f32_e32 v82, v15, v15
	v_mul_f32_e32 v108, v20, v20
	v_pk_add_f32 v[104:105], v[104:105], v[106:107]
	v_pk_fma_f32 v[106:107], v[14:15], v[14:15], v[82:83] op_sel_hi:[1,1,0]
	v_mul_f32_e32 v82, v17, v17
	v_mul_f32_e32 v110, v21, v21
	v_mov_b32_e32 v107, v108
	v_pk_fma_f32 v[108:109], v[16:17], v[16:17], v[82:83] op_sel_hi:[1,1,0]
	v_mov_b32_e32 v111, v102
	v_mov_b32_e32 v109, v110
	v_pk_add_f32 v[106:107], v[106:107], v[108:109]
	v_mov_b32_e32 v110, v100
	v_pk_add_f32 v[108:109], v[104:105], v[106:107]
	v_cvt_pk_bf16_f32 v104, v18, v19
	v_cvt_pk_bf16_f32 v105, v20, v21
	global_store_dwordx2 v[30:31], v[104:105], off offset:2048
	ds_read_b128 v[104:107], v1 offset:13312
	v_mov_b32_e32 v102, v101
	v_pk_mul_f32 v[110:111], v[38:39], v[110:111] op_sel_hi:[0,1]
	v_pk_mul_f32 v[100:101], v[38:39], v[102:103] op_sel_hi:[0,1]
	v_mov_b32_e32 v82, v85
	s_waitcnt vmcnt(15) lgkmcnt(0)
	v_pk_fma_f32 v[12:13], v[106:107], v[100:101], v[12:13]
	v_pk_fma_f32 v[10:11], v[104:105], v[110:111], v[10:11]
	v_pk_mul_f32 v[106:107], v[12:13], v[12:13]
	v_cvt_pk_bf16_f32 v112, v10, v11
	v_cvt_pk_bf16_f32 v113, v12, v13
	ds_read_b128 v[100:103], v1 offset:14336
	global_store_dwordx2 v[30:31], v[112:113], off offset:2560
	v_pk_mul_f32 v[104:105], v[10:11], v[10:11]
	v_pk_mul_f32 v[82:83], v[38:39], v[82:83] op_sel_hi:[0,1]
	v_pk_mov_b32 v[110:111], v[104:105], v[106:107] op_sel:[1,0]
	s_waitcnt vmcnt(15) lgkmcnt(0)
; #define LAS __attribute__((address_space(3)))
; __device__ __forceinline__ float xlane1(float t) { return dpp_mov<0xB1, 0xF, true>(0.f, t); }
; __device__ __forceinline__ float xlane2(float t) { return dpp_mov<0x4E, 0xF, true>(0.f, t); }
; __device__ __forceinline__ float xlane4(float t) { const float r = dpp_mov<0x104, 0x5, false>(t, t); return dpp_mov<0x114, 0xA, false>(r, t); }
; __device__ __forceinline__ float xlane8(float t) { return dpp_mov<0x128, 0xF, true>(0.f, t); }
; __device__ __forceinline__ f32x4 rot64(f32x4 t, const RotSigns sg) {
;     { const float p0 = t.x + t.y, p1 = t.x - t.y, p2 = t.z + t.w, p3 = t.z - t.w; t = (f32x4){p0 + p2, p1 + p3, p0 - p2, p1 - p3}; }
;     t = (f32x4){__builtin_fmaf(sg.s1, t.x, xlane1(t.x)), __builtin_fmaf(sg.s1, t.y, xlane1(t.y)), __builtin_fmaf(sg.s1, t.z, xlane1(t.z)), __builtin_fmaf(sg.s1, t.w, xlane1(t.w))};
;     t = (f32x4){__builtin_fmaf(sg.s2, t.x, xlane2(t.x)), __builtin_fmaf(sg.s2, t.y, xlane2(t.y)), __builtin_fmaf(sg.s2, t.z, xlane2(t.z)), __builtin_fmaf(sg.s2, t.w, xlane2(t.w))};
;     t = (f32x4){__builtin_fmaf(sg.s4, t.x, xlane4(t.x)), __builtin_fmaf(sg.s4, t.y, xlane4(t.y)), __builtin_fmaf(sg.s4, t.z, xlane4(t.z)), __builtin_fmaf(sg.s4, t.w, xlane4(t.w))};
;     t = (f32x4){__builtin_fmaf(sg.s8, t.x, xlane8(t.x)), __builtin_fmaf(sg.s8, t.y, xlane8(t.y)), __builtin_fmaf(sg.s8, t.z, xlane8(t.z)), __builtin_fmaf(sg.s8, t.w, xlane8(t.w))};
;     return t * 0.125f;
; }
; __global__ void __launch_bounds__(NWAVES * 64, 2) fwd_kernel(Args args) {
;     ...
;                     const float rstd1 = 1.0f / sqrtf(wave_sum(s1) * (1.0f / D) + RMS_EPS);
; #pragma unroll
;                     for (int j = 0; j < 16; ++j) { const f32x4 a = ((const LAS f32x4*)cA)[lane + 64 * j], bb = ((const LAS f32x4*)cB)[lane + 64 * j]; v[j] = v[j] * rstd1 * a + bb; }
;                     rotq_row(v, (unsigned*)(U2Q8 + row * D), r2scale + row, lane);
	v_pk_fma_f32 v[8:9], v[102:103], v[92:93], v[8:9]
	v_pk_fma_f32 v[6:7], v[100:101], v[88:89], v[6:7]
	v_mov_b32_e32 v105, v107
	v_cvt_pk_bf16_f32 v88, v6, v7
	v_cvt_pk_bf16_f32 v89, v8, v9
	ds_read_b128 v[100:103], v1 offset:15360
	v_pk_add_f32 v[92:93], v[110:111], v[104:105]
	global_store_dwordx2 v[30:31], v[88:89], off offset:3072
	s_waitcnt vmcnt(15) lgkmcnt(0)
	v_pk_fma_f32 v[100:101], v[100:101], v[82:83], v[2:3]
	v_pk_fma_f32 v[4:5], v[102:103], v[78:79], v[4:5]
	v_mul_f32_e32 v38, v100, v100
	v_mul_f32_e32 v82, v101, v101
	v_pk_add_f32 v[2:3], v[108:109], v[108:109] op_sel:[0,1] op_sel_hi:[1,0]
	v_pk_add_f32 v[78:79], v[92:93], v[92:93] op_sel:[0,1] op_sel_hi:[1,0]
	v_mov_b32_e32 v3, v38
	v_mov_b32_e32 v79, v82
	v_mul_f32_e32 v38, v7, v7
	v_mul_f32_e32 v83, v4, v4
	v_pk_add_f32 v[2:3], v[2:3], v[78:79]
	v_pk_fma_f32 v[78:79], v[6:7], v[6:7], v[38:39] op_sel_hi:[1,1,0]
	v_mul_f32_e32 v38, v9, v9
	v_mul_f32_e32 v84, v5, v5
	v_mov_b32_e32 v79, v83
	v_pk_fma_f32 v[82:83], v[8:9], v[8:9], v[38:39] op_sel_hi:[1,1,0]
	s_nop 0
	v_mov_b32_e32 v83, v84
	v_pk_add_f32 v[78:79], v[78:79], v[82:83]
	s_nop 0
	v_pk_add_f32 v[2:3], v[2:3], v[78:79]
	s_nop 0
	v_add_f32_e32 v2, v2, v3
	ds_bpermute_b32 v3, v136, v2
	s_waitcnt lgkmcnt(0)
	v_add_f32_e32 v2, v2, v3
	ds_bpermute_b32 v3, v137, v2
	s_waitcnt lgkmcnt(0)
	v_add_f32_e32 v2, v2, v3
	ds_bpermute_b32 v3, v138, v2
	s_waitcnt lgkmcnt(0)
	v_add_f32_e32 v2, v2, v3
	ds_bpermute_b32 v3, v139, v2
	s_waitcnt lgkmcnt(0)
	v_add_f32_e32 v2, v2, v3
	ds_bpermute_b32 v3, v140, v2
	s_waitcnt lgkmcnt(0)
	v_add_f32_e32 v2, v2, v3
	ds_bpermute_b32 v3, v141, v2
	s_waitcnt lgkmcnt(0)
	v_add_f32_e32 v2, v2, v3
	v_fmamk_f32 v2, v2, 0x39800000, v145
	v_mul_f32_e32 v3, 0x4f800000, v2
	v_cmp_gt_f32_e32 vcc, s12, v2
	s_nop 1
	v_cndmask_b32_e32 v2, v2, v3, vcc
	v_sqrt_f32_e32 v3, v2
	s_nop 0
	v_add_u32_e32 v38, -1, v3
	v_fma_f32 v78, -v38, v3, v2
	v_cmp_ge_f32_e64 s[0:1], 0, v78
	v_add_u32_e32 v78, 1, v3
	s_nop 0
	v_cndmask_b32_e64 v38, v3, v38, s[0:1]
	v_fma_f32 v3, -v78, v3, v2
	v_cmp_lt_f32_e64 s[0:1], 0, v3
	s_nop 1
	v_cndmask_b32_e64 v3, v38, v78, s[0:1]
	v_mul_f32_e32 v38, 0x37800000, v3
	v_cndmask_b32_e32 v3, v3, v38, vcc
	v_cmp_class_f32_e32 vcc, v2, v146
	s_nop 1
	v_cndmask_b32_e32 v38, v3, v2, vcc
	v_div_scale_f32 v78, s[0:1], v38, v38, 1.0
	v_rcp_f32_e32 v79, v78
	v_cvt_pk_bf16_f32 v2, v100, v101
	v_cvt_pk_bf16_f32 v3, v4, v5
	s_nop 0
	v_fma_f32 v82, -v78, v79, 1.0
	v_fmac_f32_e32 v79, v82, v79
	v_div_scale_f32 v82, vcc, 1.0, v38, 1.0
	v_mul_f32_e32 v83, v82, v79
	v_fma_f32 v84, -v78, v83, v82
	v_fmac_f32_e32 v83, v84, v79
	v_fma_f32 v78, -v78, v83, v82
	v_div_fmas_f32 v78, v78, v79, v83
	v_div_fixup_f32 v38, v78, v38, 1.0
	ds_read_b128 v[82:85], v1 offset:16384
	ds_read_b128 v[102:105], v1 offset:32768
	v_pk_mul_f32 v[78:79], v[38:39], v[98:99] op_sel_hi:[0,1]
	v_pk_mul_f32 v[88:89], v[38:39], v[96:97] op_sel_hi:[0,1]
	ds_read_b128 v[96:99], v1 offset:33792
	ds_read_b128 v[106:109], v1 offset:47104
	ds_read_b128 v[110:113], v1 offset:17408
	s_waitcnt lgkmcnt(3)
	v_pk_fma_f32 v[116:117], v[82:83], v[78:79], v[102:103]
	v_pk_mul_f32 v[82:83], v[38:39], v[62:63] op_sel_hi:[0,1]
	v_pk_fma_f32 v[114:115], v[84:85], v[88:89], v[104:105]
	v_pk_mul_f32 v[78:79], v[38:39], v[64:65] op_sel_hi:[0,1]
	ds_read_b128 v[62:65], v1 offset:18432
	s_waitcnt lgkmcnt(1)
	v_pk_fma_f32 v[120:121], v[112:113], v[82:83], v[98:99]
	ds_read_b128 v[82:85], v1 offset:34816
	v_pk_fma_f32 v[122:123], v[110:111], v[78:79], v[96:97]
	v_pk_mul_f32 v[78:79], v[38:39], v[68:69] op_sel_hi:[0,1]
	v_pk_mul_f32 v[88:89], v[38:39], v[66:67] op_sel_hi:[0,1]
	ds_read_b128 v[66:69], v1 offset:35840
	ds_read_b128 v[110:113], v1 offset:19456
	s_waitcnt lgkmcnt(2)
	v_pk_fma_f32 v[102:103], v[64:65], v[88:89], v[84:85]
	v_pk_fma_f32 v[104:105], v[62:63], v[78:79], v[82:83]
	v_pk_mul_f32 v[62:63], v[38:39], v[72:73] op_sel_hi:[0,1]
	v_pk_mul_f32 v[64:65], v[38:39], v[70:71] op_sel_hi:[0,1]
	ds_read_b128 v[70:73], v1 offset:20480
	ds_read_b128 v[82:85], v1 offset:36864
	s_waitcnt lgkmcnt(2)
	v_pk_fma_f32 v[98:99], v[110:111], v[62:63], v[66:67]
	v_pk_mul_f32 v[62:63], v[38:39], v[74:75] op_sel_hi:[0,1]
	v_pk_fma_f32 v[96:97], v[112:113], v[64:65], v[68:69]
	v_pk_mul_f32 v[64:65], v[38:39], v[76:77] op_sel_hi:[0,1]
	ds_read_b128 v[66:69], v1 offset:37888
	s_waitcnt lgkmcnt(1)
	v_pk_fma_f32 v[62:63], v[72:73], v[62:63], v[84:85]
	ds_read_b128 v[72:75], v1 offset:21504
	ds_read_b128 v[76:79], v1 offset:22528
	v_pk_fma_f32 v[64:65], v[70:71], v[64:65], v[82:83]
	v_pk_mul_f32 v[70:71], v[38:39], v[80:81] op_sel_hi:[0,1]
	ds_read_b128 v[80:83], v1 offset:38912
	v_pk_mul_f32 v[84:85], v[38:39], v[86:87] op_sel_hi:[0,1]
	s_waitcnt lgkmcnt(2)
	v_pk_fma_f32 v[72:73], v[72:73], v[84:85], v[66:67]
	v_pk_mul_f32 v[84:85], v[38:39], v[90:91] op_sel_hi:[0,1]
	v_pk_fma_f32 v[70:71], v[74:75], v[70:71], v[68:69]
	ds_read_b128 v[66:69], v1 offset:39936
	s_waitcnt lgkmcnt(1)
	v_pk_fma_f32 v[78:79], v[78:79], v[84:85], v[82:83]
	ds_read_b128 v[82:85], v1 offset:23552
	v_pk_mul_f32 v[74:75], v[38:39], v[94:95] op_sel_hi:[0,1]
	v_pk_fma_f32 v[80:81], v[76:77], v[74:75], v[80:81]
	v_pk_mul_f32 v[74:75], v[38:39], v[36:37] op_sel_hi:[0,1]
	v_pk_mul_f32 v[88:89], v[38:39], v[34:35] op_sel_hi:[0,1]
	ds_read_b128 v[34:37], v1 offset:24576
	s_waitcnt lgkmcnt(1)
	v_pk_fma_f32 v[86:87], v[84:85], v[74:75], v[68:69]
	ds_read_b128 v[74:77], v1 offset:40960
	v_pk_fma_f32 v[88:89], v[82:83], v[88:89], v[66:67]
	ds_read_b128 v[66:69], v1 offset:41984
	ds_read_b128 v[110:113], v1 offset:25600
	v_pk_mul_f32 v[32:33], v[38:39], v[32:33] op_sel_hi:[0,1]
	v_pk_mul_f32 v[82:83], v[38:39], v[118:119] op_sel_hi:[0,1]
	s_waitcnt lgkmcnt(2)
; __device__ __forceinline__ float xlane1(float t) { return dpp_mov<0xB1, 0xF, true>(0.f, t); }
; __device__ __forceinline__ float xlane2(float t) { return dpp_mov<0x4E, 0xF, true>(0.f, t); }
; __device__ __forceinline__ float xlane4(float t) { const float r = dpp_mov<0x104, 0x5, false>(t, t); return dpp_mov<0x114, 0xA, false>(r, t); }
; __device__ __forceinline__ float xlane8(float t) { return dpp_mov<0x128, 0xF, true>(0.f, t); }
; __device__ __forceinline__ f32x4 rot64(f32x4 t, const RotSigns sg) {
;     { const float p0 = t.x + t.y, p1 = t.x - t.y, p2 = t.z + t.w, p3 = t.z - t.w; t = (f32x4){p0 + p2, p1 + p3, p0 - p2, p1 - p3}; }
;     t = (f32x4){__builtin_fmaf(sg.s1, t.x, xlane1(t.x)), __builtin_fmaf(sg.s1, t.y, xlane1(t.y)), __builtin_fmaf(sg.s1, t.z, xlane1(t.z)), __builtin_fmaf(sg.s1, t.w, xlane1(t.w))};
;     t = (f32x4){__builtin_fmaf(sg.s2, t.x, xlane2(t.x)), __builtin_fmaf(sg.s2, t.y, xlane2(t.y)), __builtin_fmaf(sg.s2, t.z, xlane2(t.z)), __builtin_fmaf(sg.s2, t.w, xlane2(t.w))};
;     t = (f32x4){__builtin_fmaf(sg.s4, t.x, xlane4(t.x)), __builtin_fmaf(sg.s4, t.y, xlane4(t.y)), __builtin_fmaf(sg.s4, t.z, xlane4(t.z)), __builtin_fmaf(sg.s4, t.w, xlane4(t.w))};
;     t = (f32x4){__builtin_fmaf(sg.s8, t.x, xlane8(t.x)), __builtin_fmaf(sg.s8, t.y, xlane8(t.y)), __builtin_fmaf(sg.s8, t.z, xlane8(t.z)), __builtin_fmaf(sg.s8, t.w, xlane8(t.w))};
;     return t * 0.125f;
; }
; __device__ __forceinline__ unsigned pack_q8m(float a, float b, float c, float d, float inv) {
;     const unsigned ua = __float_as_uint(__builtin_fmaf(a, inv, 12582912.0f)), ub = __float_as_uint(__builtin_fmaf(b, inv, 12582912.0f));
;     const unsigned uc = __float_as_uint(__builtin_fmaf(c, inv, 12582912.0f)), ud = __float_as_uint(__builtin_fmaf(d, inv, 12582912.0f));
;     return __builtin_amdgcn_perm(__builtin_amdgcn_perm(ud, uc, 0x0c0c0400u), __builtin_amdgcn_perm(ub, ua, 0x0c0c0400u), 0x05040100u);
; }
; __device__ __forceinline__ void rotq_row(f32x4 (&v)[16], unsigned* q8row, float* rsp, int lane) {
;     float am = 0.f; const RotSigns sg = rot_signs(lane);
; #pragma unroll
;     for (int j = 0; j < 16; ++j) { v[j] = rot64(v[j], sg);
;         am = fmaxf(fmaxf(am, fmaxf(fabsf(v[j].x), fabsf(v[j].y))), fmaxf(fabsf(v[j].z), fabsf(v[j].w))); }
	v_pk_fma_f32 v[90:91], v[36:37], v[32:33], v[76:77]
	v_pk_mul_f32 v[32:33], v[38:39], v[28:29] op_sel_hi:[0,1]
	v_pk_fma_f32 v[92:93], v[34:35], v[82:83], v[74:75]
	v_pk_mul_f32 v[36:37], v[38:39], v[26:27] op_sel_hi:[0,1]
	ds_read_b128 v[26:29], v1 offset:26624
	s_waitcnt lgkmcnt(1)
	v_pk_fma_f32 v[82:83], v[112:113], v[32:33], v[68:69]
	ds_read_b128 v[32:35], v1 offset:43008
	v_pk_fma_f32 v[84:85], v[110:111], v[36:37], v[66:67]
	v_pk_mul_f32 v[36:37], v[38:39], v[24:25] op_sel_hi:[0,1]
	v_pk_mul_f32 v[66:67], v[38:39], v[22:23] op_sel_hi:[0,1]
	ds_read_b128 v[22:25], v1 offset:44032
	s_waitcnt lgkmcnt(1)
	v_pk_fma_f32 v[74:75], v[28:29], v[36:37], v[34:35]
	ds_read_b128 v[34:37], v1 offset:27648
	v_pk_fma_f32 v[76:77], v[26:27], v[66:67], v[32:33]
	v_pk_mul_f32 v[26:27], v[38:39], v[16:17] op_sel_hi:[0,1]
	v_pk_mul_f32 v[28:29], v[38:39], v[14:15] op_sel_hi:[0,1]
	ds_read_b128 v[14:17], v1 offset:28672
	s_waitcnt lgkmcnt(1)
	v_pk_fma_f32 v[66:67], v[36:37], v[26:27], v[24:25]
	ds_read_b128 v[24:27], v1 offset:45056
	v_pk_fma_f32 v[68:69], v[34:35], v[28:29], v[22:23]
	v_pk_mul_f32 v[22:23], v[38:39], v[18:19] op_sel_hi:[0,1]
	v_pk_mul_f32 v[28:29], v[38:39], v[20:21] op_sel_hi:[0,1]
	ds_read_b128 v[18:21], v1 offset:46080
	ds_read_b128 v[110:113], v1 offset:29696
	s_waitcnt lgkmcnt(2)
	v_pk_fma_f32 v[34:35], v[16:17], v[28:29], v[26:27]
	v_pk_fma_f32 v[36:37], v[14:15], v[22:23], v[24:25]
	v_pk_mul_f32 v[14:15], v[38:39], v[10:11] op_sel_hi:[0,1]
	v_pk_mul_f32 v[16:17], v[38:39], v[12:13] op_sel_hi:[0,1]
	ds_read_b128 v[10:13], v1 offset:30720
	s_waitcnt lgkmcnt(1)
	v_pk_fma_f32 v[26:27], v[112:113], v[16:17], v[20:21]
	v_pk_fma_f32 v[24:25], v[110:111], v[14:15], v[18:19]
	v_pk_mul_f32 v[14:15], v[38:39], v[6:7] op_sel_hi:[0,1]
	v_pk_mul_f32 v[16:17], v[38:39], v[8:9] op_sel_hi:[0,1]
	ds_read_b128 v[6:9], v142 offset:16384
	ds_read_b128 v[20:23], v142 offset:32768
	s_waitcnt lgkmcnt(2)
	v_pk_fma_f32 v[18:19], v[12:13], v[16:17], v[108:109]
	v_pk_mul_f32 v[12:13], v[38:39], v[100:101] op_sel_hi:[0,1]
	v_pk_mul_f32 v[4:5], v[38:39], v[4:5] op_sel_hi:[0,1]
	v_pk_fma_f32 v[16:17], v[10:11], v[14:15], v[106:107]
	s_waitcnt lgkmcnt(0)
	v_pk_fma_f32 v[10:11], v[8:9], v[4:5], v[22:23]
	v_pk_fma_f32 v[8:9], v[6:7], v[12:13], v[20:21]
	v_mov_b32_e32 v4, v114
	v_mov_b32_e32 v5, v116
	v_mov_b32_e32 v6, v115
	v_mov_b32_e32 v7, v117
	v_pk_add_f32 v[12:13], v[4:5], v[6:7]
	v_pk_add_f32 v[4:5], v[4:5], v[6:7] neg_lo:[0,1] neg_hi:[0,1]
	v_pk_mov_b32 v[6:7], v[116:117], v[114:115] op_sel:[1,0]
	v_mov_b32_e32 v117, v115
	v_pk_add_f32 v[14:15], v[6:7], v[116:117]
	v_pk_add_f32 v[6:7], v[6:7], v[116:117] neg_lo:[0,1] neg_hi:[0,1]
	v_mov_b32_e32 v13, v5
	v_mov_b32_e32 v15, v7
	v_pk_add_f32 v[20:21], v[14:15], v[12:13]
	v_mov_b32_e32 v15, v5
	v_mov_b32_e32 v13, v7
	v_pk_add_f32 v[4:5], v[14:15], v[12:13] neg_lo:[0,1] neg_hi:[0,1]
	v_mov_b32_dpp v22, v20 quad_perm:[1,0,3,2] row_mask:0xf bank_mask:0xf bound_ctrl:1
	v_mov_b32_dpp v23, v21 quad_perm:[1,0,3,2] row_mask:0xf bank_mask:0xf bound_ctrl:1
	v_mov_b32_dpp v6, v4 quad_perm:[1,0,3,2] row_mask:0xf bank_mask:0xf bound_ctrl:1
	v_mov_b32_dpp v7, v5 quad_perm:[1,0,3,2] row_mask:0xf bank_mask:0xf bound_ctrl:1
	v_pk_fma_f32 v[20:21], v[46:47], v[20:21], v[22:23]
	v_pk_fma_f32 v[4:5], v[46:47], v[4:5], v[6:7]
	v_mov_b32_e32 v14, v121
	v_mov_b32_dpp v22, v20 quad_perm:[2,3,0,1] row_mask:0xf bank_mask:0xf bound_ctrl:1
	v_mov_b32_dpp v23, v21 quad_perm:[2,3,0,1] row_mask:0xf bank_mask:0xf bound_ctrl:1
	v_mov_b32_dpp v6, v4 quad_perm:[2,3,0,1] row_mask:0xf bank_mask:0xf bound_ctrl:1
	v_mov_b32_dpp v7, v5 quad_perm:[2,3,0,1] row_mask:0xf bank_mask:0xf bound_ctrl:1
	v_pk_fma_f32 v[20:21], v[48:49], v[20:21], v[22:23]
	v_pk_fma_f32 v[4:5], v[48:49], v[4:5], v[6:7]
	v_mov_b32_e32 v22, v20
	v_mov_b32_e32 v23, v21
	v_mov_b32_e32 v6, v4
	v_mov_b32_e32 v7, v5
	v_mov_b32_dpp v22, v22 row_shl:4 row_mask:0xf bank_mask:0x5
	v_mov_b32_dpp v23, v23 row_shl:4 row_mask:0xf bank_mask:0x5
	v_mov_b32_dpp v6, v6 row_shl:4 row_mask:0xf bank_mask:0x5
	v_mov_b32_dpp v7, v7 row_shl:4 row_mask:0xf bank_mask:0x5
	v_mov_b32_dpp v22, v20 row_shr:4 row_mask:0xf bank_mask:0xa
	v_mov_b32_dpp v23, v21 row_shr:4 row_mask:0xf bank_mask:0xa
	v_mov_b32_dpp v6, v4 row_shr:4 row_mask:0xf bank_mask:0xa
	v_mov_b32_dpp v7, v5 row_shr:4 row_mask:0xf bank_mask:0xa
	v_pk_fma_f32 v[20:21], v[50:51], v[20:21], v[22:23]
	v_pk_fma_f32 v[4:5], v[50:51], v[4:5], v[6:7]
	v_mov_b32_e32 v15, v123
	v_mov_b32_dpp v22, v20 row_ror:8 row_mask:0xf bank_mask:0xf bound_ctrl:1
	v_mov_b32_dpp v23, v21 row_ror:8 row_mask:0xf bank_mask:0xf bound_ctrl:1
	v_mov_b32_dpp v6, v4 row_ror:8 row_mask:0xf bank_mask:0xf bound_ctrl:1
	v_mov_b32_dpp v7, v5 row_ror:8 row_mask:0xf bank_mask:0xf bound_ctrl:1
	v_pk_fma_f32 v[12:13], v[52:53], v[20:21], v[22:23]
	v_pk_fma_f32 v[4:5], v[56:57], v[4:5], v[6:7]
	v_pk_mul_f32 v[6:7], v[12:13], s[18:19] op_sel_hi:[1,0]
	v_pk_mul_f32 v[4:5], v[4:5], s[18:19] op_sel_hi:[1,0]
	v_max_f32_e64 v12, |v6|, |v7|
	v_max_f32_e64 v13, |v4|, |v5|
	v_max3_f32 v38, v12, 0, v13
	v_mov_b32_e32 v12, v120
	v_mov_b32_e32 v13, v122
	v_pk_add_f32 v[20:21], v[12:13], v[14:15]
	v_pk_add_f32 v[12:13], v[12:13], v[14:15] neg_lo:[0,1] neg_hi:[0,1]
	v_pk_mov_b32 v[14:15], v[122:123], v[120:121] op_sel:[1,0]
	v_mov_b32_e32 v123, v121
	v_pk_add_f32 v[22:23], v[14:15], v[122:123]
	v_pk_add_f32 v[14:15], v[14:15], v[122:123] neg_lo:[0,1] neg_hi:[0,1]
	v_mov_b32_e32 v21, v13
	v_mov_b32_e32 v23, v15
	v_pk_add_f32 v[28:29], v[22:23], v[20:21]
	v_mov_b32_e32 v23, v13
	v_mov_b32_e32 v21, v15
	v_pk_add_f32 v[12:13], v[22:23], v[20:21] neg_lo:[0,1] neg_hi:[0,1]
; __device__ __forceinline__ float xlane1(float t) { return dpp_mov<0xB1, 0xF, true>(0.f, t); }
; __device__ __forceinline__ float xlane2(float t) { return dpp_mov<0x4E, 0xF, true>(0.f, t); }
; __device__ __forceinline__ float xlane4(float t) { const float r = dpp_mov<0x104, 0x5, false>(t, t); return dpp_mov<0x114, 0xA, false>(r, t); }
; __device__ __forceinline__ float xlane8(float t) { return dpp_mov<0x128, 0xF, true>(0.f, t); }
; __device__ __forceinline__ f32x4 rot64(f32x4 t, const RotSigns sg) {
;     { const float p0 = t.x + t.y, p1 = t.x - t.y, p2 = t.z + t.w, p3 = t.z - t.w; t = (f32x4){p0 + p2, p1 + p3, p0 - p2, p1 - p3}; }
;     t = (f32x4){__builtin_fmaf(sg.s1, t.x, xlane1(t.x)), __builtin_fmaf(sg.s1, t.y, xlane1(t.y)), __builtin_fmaf(sg.s1, t.z, xlane1(t.z)), __builtin_fmaf(sg.s1, t.w, xlane1(t.w))};
;     t = (f32x4){__builtin_fmaf(sg.s2, t.x, xlane2(t.x)), __builtin_fmaf(sg.s2, t.y, xlane2(t.y)), __builtin_fmaf(sg.s2, t.z, xlane2(t.z)), __builtin_fmaf(sg.s2, t.w, xlane2(t.w))};
;     t = (f32x4){__builtin_fmaf(sg.s4, t.x, xlane4(t.x)), __builtin_fmaf(sg.s4, t.y, xlane4(t.y)), __builtin_fmaf(sg.s4, t.z, xlane4(t.z)), __builtin_fmaf(sg.s4, t.w, xlane4(t.w))};
;     t = (f32x4){__builtin_fmaf(sg.s8, t.x, xlane8(t.x)), __builtin_fmaf(sg.s8, t.y, xlane8(t.y)), __builtin_fmaf(sg.s8, t.z, xlane8(t.z)), __builtin_fmaf(sg.s8, t.w, xlane8(t.w))};
;     return t * 0.125f;
; }
; __device__ __forceinline__ unsigned pack_q8m(float a, float b, float c, float d, float inv) {
;     const unsigned ua = __float_as_uint(__builtin_fmaf(a, inv, 12582912.0f)), ub = __float_as_uint(__builtin_fmaf(b, inv, 12582912.0f));
;     const unsigned uc = __float_as_uint(__builtin_fmaf(c, inv, 12582912.0f)), ud = __float_as_uint(__builtin_fmaf(d, inv, 12582912.0f));
;     return __builtin_amdgcn_perm(__builtin_amdgcn_perm(ud, uc, 0x0c0c0400u), __builtin_amdgcn_perm(ub, ua, 0x0c0c0400u), 0x05040100u);
; }
; __device__ __forceinline__ void rotq_row(f32x4 (&v)[16], unsigned* q8row, float* rsp, int lane) {
;     float am = 0.f; const RotSigns sg = rot_signs(lane);
; #pragma unroll
;     for (int j = 0; j < 16; ++j) { v[j] = rot64(v[j], sg);
;         am = fmaxf(fmaxf(am, fmaxf(fabsf(v[j].x), fabsf(v[j].y))), fmaxf(fabsf(v[j].z), fabsf(v[j].w))); }
	v_mov_b32_dpp v32, v28 quad_perm:[1,0,3,2] row_mask:0xf bank_mask:0xf bound_ctrl:1
	v_mov_b32_dpp v33, v29 quad_perm:[1,0,3,2] row_mask:0xf bank_mask:0xf bound_ctrl:1
	v_mov_b32_dpp v14, v12 quad_perm:[1,0,3,2] row_mask:0xf bank_mask:0xf bound_ctrl:1
	v_mov_b32_dpp v15, v13 quad_perm:[1,0,3,2] row_mask:0xf bank_mask:0xf bound_ctrl:1
	v_pk_fma_f32 v[28:29], v[46:47], v[28:29], v[32:33]
	v_pk_fma_f32 v[12:13], v[46:47], v[12:13], v[14:15]
	v_mov_b32_e32 v22, v103
	v_mov_b32_dpp v32, v28 quad_perm:[2,3,0,1] row_mask:0xf bank_mask:0xf bound_ctrl:1
	v_mov_b32_dpp v33, v29 quad_perm:[2,3,0,1] row_mask:0xf bank_mask:0xf bound_ctrl:1
	v_mov_b32_dpp v14, v12 quad_perm:[2,3,0,1] row_mask:0xf bank_mask:0xf bound_ctrl:1
	v_mov_b32_dpp v15, v13 quad_perm:[2,3,0,1] row_mask:0xf bank_mask:0xf bound_ctrl:1
	v_pk_fma_f32 v[28:29], v[48:49], v[28:29], v[32:33]
	v_pk_fma_f32 v[12:13], v[48:49], v[12:13], v[14:15]
	v_mov_b32_e32 v32, v28
	v_mov_b32_e32 v33, v29
	v_mov_b32_e32 v14, v12
	v_mov_b32_e32 v15, v13
	v_mov_b32_dpp v32, v32 row_shl:4 row_mask:0xf bank_mask:0x5
	v_mov_b32_dpp v33, v33 row_shl:4 row_mask:0xf bank_mask:0x5
	v_mov_b32_dpp v14, v14 row_shl:4 row_mask:0xf bank_mask:0x5
	v_mov_b32_dpp v15, v15 row_shl:4 row_mask:0xf bank_mask:0x5
	v_mov_b32_dpp v32, v28 row_shr:4 row_mask:0xf bank_mask:0xa
	v_mov_b32_dpp v33, v29 row_shr:4 row_mask:0xf bank_mask:0xa
	v_mov_b32_dpp v14, v12 row_shr:4 row_mask:0xf bank_mask:0xa
	v_mov_b32_dpp v15, v13 row_shr:4 row_mask:0xf bank_mask:0xa
	v_pk_fma_f32 v[28:29], v[50:51], v[28:29], v[32:33]
	v_pk_fma_f32 v[12:13], v[50:51], v[12:13], v[14:15]
	v_mov_b32_e32 v23, v105
	v_mov_b32_dpp v32, v28 row_ror:8 row_mask:0xf bank_mask:0xf bound_ctrl:1
	v_mov_b32_dpp v33, v29 row_ror:8 row_mask:0xf bank_mask:0xf bound_ctrl:1
	v_mov_b32_dpp v14, v12 row_ror:8 row_mask:0xf bank_mask:0xf bound_ctrl:1
	v_mov_b32_dpp v15, v13 row_ror:8 row_mask:0xf bank_mask:0xf bound_ctrl:1
	v_pk_fma_f32 v[20:21], v[52:53], v[28:29], v[32:33]
	v_pk_fma_f32 v[12:13], v[56:57], v[12:13], v[14:15]
	v_pk_mul_f32 v[14:15], v[20:21], s[18:19] op_sel_hi:[1,0]
	v_pk_mul_f32 v[12:13], v[12:13], s[18:19] op_sel_hi:[1,0]
	v_max_f32_e64 v20, |v14|, |v15|
	v_max_f32_e64 v21, |v12|, |v13|
	v_max3_f32 v38, v38, v20, v21
	v_mov_b32_e32 v20, v102
	v_mov_b32_e32 v21, v104
	v_pk_add_f32 v[28:29], v[20:21], v[22:23]
	v_pk_add_f32 v[20:21], v[20:21], v[22:23] neg_lo:[0,1] neg_hi:[0,1]
	v_pk_mov_b32 v[22:23], v[104:105], v[102:103] op_sel:[1,0]
	v_mov_b32_e32 v105, v103
	v_pk_add_f32 v[32:33], v[22:23], v[104:105]
	v_pk_add_f32 v[22:23], v[22:23], v[104:105] neg_lo:[0,1] neg_hi:[0,1]
	v_mov_b32_e32 v29, v21
	v_mov_b32_e32 v33, v23
	v_pk_add_f32 v[94:95], v[32:33], v[28:29]
	v_mov_b32_e32 v33, v21
	v_mov_b32_e32 v29, v23
	v_pk_add_f32 v[20:21], v[32:33], v[28:29] neg_lo:[0,1] neg_hi:[0,1]
	v_mov_b32_dpp v100, v94 quad_perm:[1,0,3,2] row_mask:0xf bank_mask:0xf bound_ctrl:1
	v_mov_b32_dpp v101, v95 quad_perm:[1,0,3,2] row_mask:0xf bank_mask:0xf bound_ctrl:1
	v_mov_b32_dpp v22, v20 quad_perm:[1,0,3,2] row_mask:0xf bank_mask:0xf bound_ctrl:1
	v_mov_b32_dpp v23, v21 quad_perm:[1,0,3,2] row_mask:0xf bank_mask:0xf bound_ctrl:1
	v_pk_fma_f32 v[94:95], v[46:47], v[94:95], v[100:101]
	v_pk_fma_f32 v[20:21], v[46:47], v[20:21], v[22:23]
	v_mov_b32_e32 v32, v97
	v_mov_b32_dpp v100, v94 quad_perm:[2,3,0,1] row_mask:0xf bank_mask:0xf bound_ctrl:1
	v_mov_b32_dpp v101, v95 quad_perm:[2,3,0,1] row_mask:0xf bank_mask:0xf bound_ctrl:1
	v_mov_b32_dpp v22, v20 quad_perm:[2,3,0,1] row_mask:0xf bank_mask:0xf bound_ctrl:1
	v_mov_b32_dpp v23, v21 quad_perm:[2,3,0,1] row_mask:0xf bank_mask:0xf bound_ctrl:1
	v_pk_fma_f32 v[94:95], v[48:49], v[94:95], v[100:101]
	v_pk_fma_f32 v[20:21], v[48:49], v[20:21], v[22:23]
	v_mov_b32_e32 v100, v94
	v_mov_b32_e32 v101, v95
	v_mov_b32_e32 v22, v20
	v_mov_b32_e32 v23, v21
	v_mov_b32_dpp v100, v100 row_shl:4 row_mask:0xf bank_mask:0x5
	v_mov_b32_dpp v101, v101 row_shl:4 row_mask:0xf bank_mask:0x5
	v_mov_b32_dpp v22, v22 row_shl:4 row_mask:0xf bank_mask:0x5
	v_mov_b32_dpp v23, v23 row_shl:4 row_mask:0xf bank_mask:0x5
	v_mov_b32_dpp v100, v94 row_shr:4 row_mask:0xf bank_mask:0xa
	v_mov_b32_dpp v101, v95 row_shr:4 row_mask:0xf bank_mask:0xa
	v_mov_b32_dpp v22, v20 row_shr:4 row_mask:0xf bank_mask:0xa
	v_mov_b32_dpp v23, v21 row_shr:4 row_mask:0xf bank_mask:0xa
	v_pk_fma_f32 v[94:95], v[50:51], v[94:95], v[100:101]
	v_pk_fma_f32 v[20:21], v[50:51], v[20:21], v[22:23]
	v_mov_b32_e32 v33, v99
	v_mov_b32_dpp v100, v94 row_ror:8 row_mask:0xf bank_mask:0xf bound_ctrl:1
	v_mov_b32_dpp v101, v95 row_ror:8 row_mask:0xf bank_mask:0xf bound_ctrl:1
	v_mov_b32_dpp v22, v20 row_ror:8 row_mask:0xf bank_mask:0xf bound_ctrl:1
	v_mov_b32_dpp v23, v21 row_ror:8 row_mask:0xf bank_mask:0xf bound_ctrl:1
	v_pk_fma_f32 v[28:29], v[52:53], v[94:95], v[100:101]
	v_pk_fma_f32 v[20:21], v[56:57], v[20:21], v[22:23]
	v_pk_mul_f32 v[22:23], v[28:29], s[18:19] op_sel_hi:[1,0]
	v_pk_mul_f32 v[20:21], v[20:21], s[18:19] op_sel_hi:[1,0]
	v_max_f32_e64 v28, |v22|, |v23|
	v_max_f32_e64 v29, |v20|, |v21|
	v_max3_f32 v38, v38, v28, v29
	v_mov_b32_e32 v28, v96
	v_mov_b32_e32 v29, v98
	v_pk_add_f32 v[94:95], v[28:29], v[32:33]
	v_pk_add_f32 v[28:29], v[28:29], v[32:33] neg_lo:[0,1] neg_hi:[0,1]
	v_pk_mov_b32 v[32:33], v[98:99], v[96:97] op_sel:[1,0]
	v_mov_b32_e32 v99, v97
	v_pk_add_f32 v[96:97], v[32:33], v[98:99]
	v_pk_add_f32 v[32:33], v[32:33], v[98:99] neg_lo:[0,1] neg_hi:[0,1]
	v_mov_b32_e32 v95, v29
	v_mov_b32_e32 v97, v33
	v_pk_add_f32 v[98:99], v[96:97], v[94:95]
	v_mov_b32_e32 v97, v29
	v_mov_b32_e32 v95, v33
	v_pk_add_f32 v[28:29], v[96:97], v[94:95] neg_lo:[0,1] neg_hi:[0,1]
; __device__ __forceinline__ float xlane1(float t) { return dpp_mov<0xB1, 0xF, true>(0.f, t); }
; __device__ __forceinline__ float xlane2(float t) { return dpp_mov<0x4E, 0xF, true>(0.f, t); }
; __device__ __forceinline__ float xlane4(float t) { const float r = dpp_mov<0x104, 0x5, false>(t, t); return dpp_mov<0x114, 0xA, false>(r, t); }
; __device__ __forceinline__ float xlane8(float t) { return dpp_mov<0x128, 0xF, true>(0.f, t); }
; __device__ __forceinline__ f32x4 rot64(f32x4 t, const RotSigns sg) {
;     { const float p0 = t.x + t.y, p1 = t.x - t.y, p2 = t.z + t.w, p3 = t.z - t.w; t = (f32x4){p0 + p2, p1 + p3, p0 - p2, p1 - p3}; }
;     t = (f32x4){__builtin_fmaf(sg.s1, t.x, xlane1(t.x)), __builtin_fmaf(sg.s1, t.y, xlane1(t.y)), __builtin_fmaf(sg.s1, t.z, xlane1(t.z)), __builtin_fmaf(sg.s1, t.w, xlane1(t.w))};
;     t = (f32x4){__builtin_fmaf(sg.s2, t.x, xlane2(t.x)), __builtin_fmaf(sg.s2, t.y, xlane2(t.y)), __builtin_fmaf(sg.s2, t.z, xlane2(t.z)), __builtin_fmaf(sg.s2, t.w, xlane2(t.w))};
;     t = (f32x4){__builtin_fmaf(sg.s4, t.x, xlane4(t.x)), __builtin_fmaf(sg.s4, t.y, xlane4(t.y)), __builtin_fmaf(sg.s4, t.z, xlane4(t.z)), __builtin_fmaf(sg.s4, t.w, xlane4(t.w))};
;     t = (f32x4){__builtin_fmaf(sg.s8, t.x, xlane8(t.x)), __builtin_fmaf(sg.s8, t.y, xlane8(t.y)), __builtin_fmaf(sg.s8, t.z, xlane8(t.z)), __builtin_fmaf(sg.s8, t.w, xlane8(t.w))};
;     return t * 0.125f;
; }
; __device__ __forceinline__ unsigned pack_q8m(float a, float b, float c, float d, float inv) {
;     const unsigned ua = __float_as_uint(__builtin_fmaf(a, inv, 12582912.0f)), ub = __float_as_uint(__builtin_fmaf(b, inv, 12582912.0f));
;     const unsigned uc = __float_as_uint(__builtin_fmaf(c, inv, 12582912.0f)), ud = __float_as_uint(__builtin_fmaf(d, inv, 12582912.0f));
;     return __builtin_amdgcn_perm(__builtin_amdgcn_perm(ud, uc, 0x0c0c0400u), __builtin_amdgcn_perm(ub, ua, 0x0c0c0400u), 0x05040100u);
; }
; __device__ __forceinline__ void rotq_row(f32x4 (&v)[16], unsigned* q8row, float* rsp, int lane) {
;     float am = 0.f; const RotSigns sg = rot_signs(lane);
; #pragma unroll
;     for (int j = 0; j < 16; ++j) { v[j] = rot64(v[j], sg);
;         am = fmaxf(fmaxf(am, fmaxf(fabsf(v[j].x), fabsf(v[j].y))), fmaxf(fabsf(v[j].z), fabsf(v[j].w))); }
	v_mov_b32_dpp v100, v98 quad_perm:[1,0,3,2] row_mask:0xf bank_mask:0xf bound_ctrl:1
	v_mov_b32_dpp v101, v99 quad_perm:[1,0,3,2] row_mask:0xf bank_mask:0xf bound_ctrl:1
	v_mov_b32_dpp v32, v28 quad_perm:[1,0,3,2] row_mask:0xf bank_mask:0xf bound_ctrl:1
	v_mov_b32_dpp v33, v29 quad_perm:[1,0,3,2] row_mask:0xf bank_mask:0xf bound_ctrl:1
	v_pk_fma_f32 v[98:99], v[46:47], v[98:99], v[100:101]
	v_pk_fma_f32 v[28:29], v[46:47], v[28:29], v[32:33]
	v_mov_b32_e32 v96, v63
	v_mov_b32_dpp v100, v98 quad_perm:[2,3,0,1] row_mask:0xf bank_mask:0xf bound_ctrl:1
	v_mov_b32_dpp v101, v99 quad_perm:[2,3,0,1] row_mask:0xf bank_mask:0xf bound_ctrl:1
	v_mov_b32_dpp v32, v28 quad_perm:[2,3,0,1] row_mask:0xf bank_mask:0xf bound_ctrl:1
	v_mov_b32_dpp v33, v29 quad_perm:[2,3,0,1] row_mask:0xf bank_mask:0xf bound_ctrl:1
	v_pk_fma_f32 v[98:99], v[48:49], v[98:99], v[100:101]
	v_pk_fma_f32 v[28:29], v[48:49], v[28:29], v[32:33]
	v_mov_b32_e32 v100, v98
	v_mov_b32_e32 v101, v99
	v_mov_b32_e32 v32, v28
	v_mov_b32_e32 v33, v29
	v_mov_b32_dpp v100, v100 row_shl:4 row_mask:0xf bank_mask:0x5
	v_mov_b32_dpp v101, v101 row_shl:4 row_mask:0xf bank_mask:0x5
	v_mov_b32_dpp v32, v32 row_shl:4 row_mask:0xf bank_mask:0x5
	v_mov_b32_dpp v33, v33 row_shl:4 row_mask:0xf bank_mask:0x5
	v_mov_b32_dpp v100, v98 row_shr:4 row_mask:0xf bank_mask:0xa
	v_mov_b32_dpp v101, v99 row_shr:4 row_mask:0xf bank_mask:0xa
	v_mov_b32_dpp v32, v28 row_shr:4 row_mask:0xf bank_mask:0xa
	v_mov_b32_dpp v33, v29 row_shr:4 row_mask:0xf bank_mask:0xa
	v_pk_fma_f32 v[98:99], v[50:51], v[98:99], v[100:101]
	v_pk_fma_f32 v[28:29], v[50:51], v[28:29], v[32:33]
	v_mov_b32_e32 v97, v65
	v_mov_b32_dpp v100, v98 row_ror:8 row_mask:0xf bank_mask:0xf bound_ctrl:1
	v_mov_b32_dpp v101, v99 row_ror:8 row_mask:0xf bank_mask:0xf bound_ctrl:1
	v_mov_b32_dpp v32, v28 row_ror:8 row_mask:0xf bank_mask:0xf bound_ctrl:1
	v_mov_b32_dpp v33, v29 row_ror:8 row_mask:0xf bank_mask:0xf bound_ctrl:1
	v_pk_fma_f32 v[94:95], v[52:53], v[98:99], v[100:101]
	v_pk_fma_f32 v[28:29], v[56:57], v[28:29], v[32:33]
	v_pk_mul_f32 v[32:33], v[94:95], s[18:19] op_sel_hi:[1,0]
	v_pk_mul_f32 v[28:29], v[28:29], s[18:19] op_sel_hi:[1,0]
	v_max_f32_e64 v94, |v32|, |v33|
	v_max_f32_e64 v95, |v28|, |v29|
	v_max3_f32 v38, v38, v94, v95
	v_mov_b32_e32 v94, v62
	v_mov_b32_e32 v95, v64
	v_pk_add_f32 v[98:99], v[94:95], v[96:97]
	v_pk_add_f32 v[94:95], v[94:95], v[96:97] neg_lo:[0,1] neg_hi:[0,1]
	v_pk_mov_b32 v[96:97], v[64:65], v[62:63] op_sel:[1,0]
	v_mov_b32_e32 v65, v63
	v_pk_add_f32 v[62:63], v[96:97], v[64:65]
	v_pk_add_f32 v[64:65], v[96:97], v[64:65] neg_lo:[0,1] neg_hi:[0,1]
	v_mov_b32_e32 v99, v95
	v_mov_b32_e32 v63, v65
	v_pk_add_f32 v[96:97], v[62:63], v[98:99]
	v_mov_b32_e32 v63, v95
	v_mov_b32_e32 v99, v65
	v_pk_add_f32 v[62:63], v[62:63], v[98:99] neg_lo:[0,1] neg_hi:[0,1]
	v_mov_b32_dpp v100, v96 quad_perm:[1,0,3,2] row_mask:0xf bank_mask:0xf bound_ctrl:1
	v_mov_b32_dpp v101, v97 quad_perm:[1,0,3,2] row_mask:0xf bank_mask:0xf bound_ctrl:1
	v_mov_b32_dpp v64, v62 quad_perm:[1,0,3,2] row_mask:0xf bank_mask:0xf bound_ctrl:1
	v_mov_b32_dpp v65, v63 quad_perm:[1,0,3,2] row_mask:0xf bank_mask:0xf bound_ctrl:1
	v_pk_fma_f32 v[96:97], v[46:47], v[96:97], v[100:101]
	v_pk_fma_f32 v[62:63], v[46:47], v[62:63], v[64:65]
	global_store_dwordx2 v[30:31], v[2:3], off offset:3584
	v_mov_b32_dpp v100, v96 quad_perm:[2,3,0,1] row_mask:0xf bank_mask:0xf bound_ctrl:1
	v_mov_b32_dpp v101, v97 quad_perm:[2,3,0,1] row_mask:0xf bank_mask:0xf bound_ctrl:1
	v_mov_b32_dpp v64, v62 quad_perm:[2,3,0,1] row_mask:0xf bank_mask:0xf bound_ctrl:1
	v_mov_b32_dpp v65, v63 quad_perm:[2,3,0,1] row_mask:0xf bank_mask:0xf bound_ctrl:1
	v_pk_fma_f32 v[96:97], v[48:49], v[96:97], v[100:101]
	v_pk_fma_f32 v[62:63], v[48:49], v[62:63], v[64:65]
	v_mov_b32_e32 v100, v96
	v_mov_b32_e32 v101, v97
	v_mov_b32_e32 v64, v62
	v_mov_b32_e32 v65, v63
	v_mov_b32_dpp v100, v100 row_shl:4 row_mask:0xf bank_mask:0x5
	v_mov_b32_dpp v101, v101 row_shl:4 row_mask:0xf bank_mask:0x5
	v_mov_b32_dpp v64, v64 row_shl:4 row_mask:0xf bank_mask:0x5
	v_mov_b32_dpp v65, v65 row_shl:4 row_mask:0xf bank_mask:0x5
	v_mov_b32_dpp v100, v96 row_shr:4 row_mask:0xf bank_mask:0xa
	v_mov_b32_dpp v101, v97 row_shr:4 row_mask:0xf bank_mask:0xa
	v_mov_b32_dpp v64, v62 row_shr:4 row_mask:0xf bank_mask:0xa
	v_mov_b32_dpp v65, v63 row_shr:4 row_mask:0xf bank_mask:0xa
	v_pk_fma_f32 v[96:97], v[50:51], v[96:97], v[100:101]
	v_pk_fma_f32 v[62:63], v[50:51], v[62:63], v[64:65]
	s_nop 0
	v_mov_b32_dpp v100, v96 row_ror:8 row_mask:0xf bank_mask:0xf bound_ctrl:1
	v_mov_b32_dpp v101, v97 row_ror:8 row_mask:0xf bank_mask:0xf bound_ctrl:1
	v_mov_b32_dpp v64, v62 row_ror:8 row_mask:0xf bank_mask:0xf bound_ctrl:1
	v_mov_b32_dpp v65, v63 row_ror:8 row_mask:0xf bank_mask:0xf bound_ctrl:1
	v_pk_fma_f32 v[94:95], v[52:53], v[96:97], v[100:101]
	v_pk_fma_f32 v[62:63], v[56:57], v[62:63], v[64:65]
	v_pk_mul_f32 v[64:65], v[94:95], s[18:19] op_sel_hi:[1,0]
	v_pk_mul_f32 v[62:63], v[62:63], s[18:19] op_sel_hi:[1,0]
	v_max_f32_e64 v94, |v64|, |v65|
	v_max_f32_e64 v95, |v62|, |v63|
	v_max3_f32 v38, v38, v94, v95
	v_mov_b32_e32 v94, v70
	v_mov_b32_e32 v95, v72
	v_mov_b32_e32 v96, v71
	v_mov_b32_e32 v97, v73
	v_pk_add_f32 v[98:99], v[94:95], v[96:97]
	v_pk_add_f32 v[94:95], v[94:95], v[96:97] neg_lo:[0,1] neg_hi:[0,1]
	v_pk_mov_b32 v[96:97], v[72:73], v[70:71] op_sel:[1,0]
	v_mov_b32_e32 v73, v71
	v_pk_add_f32 v[70:71], v[96:97], v[72:73]
	v_pk_add_f32 v[72:73], v[96:97], v[72:73] neg_lo:[0,1] neg_hi:[0,1]
	v_mov_b32_e32 v99, v95
	v_mov_b32_e32 v71, v73
	v_pk_add_f32 v[96:97], v[70:71], v[98:99]
	v_mov_b32_e32 v71, v95
	v_mov_b32_e32 v99, v73
; __device__ __forceinline__ float xlane1(float t) { return dpp_mov<0xB1, 0xF, true>(0.f, t); }
; __device__ __forceinline__ float xlane2(float t) { return dpp_mov<0x4E, 0xF, true>(0.f, t); }
; __device__ __forceinline__ float xlane4(float t) { const float r = dpp_mov<0x104, 0x5, false>(t, t); return dpp_mov<0x114, 0xA, false>(r, t); }
; __device__ __forceinline__ float xlane8(float t) { return dpp_mov<0x128, 0xF, true>(0.f, t); }
; __device__ __forceinline__ f32x4 rot64(f32x4 t, const RotSigns sg) {
;     { const float p0 = t.x + t.y, p1 = t.x - t.y, p2 = t.z + t.w, p3 = t.z - t.w; t = (f32x4){p0 + p2, p1 + p3, p0 - p2, p1 - p3}; }
;     t = (f32x4){__builtin_fmaf(sg.s1, t.x, xlane1(t.x)), __builtin_fmaf(sg.s1, t.y, xlane1(t.y)), __builtin_fmaf(sg.s1, t.z, xlane1(t.z)), __builtin_fmaf(sg.s1, t.w, xlane1(t.w))};
;     t = (f32x4){__builtin_fmaf(sg.s2, t.x, xlane2(t.x)), __builtin_fmaf(sg.s2, t.y, xlane2(t.y)), __builtin_fmaf(sg.s2, t.z, xlane2(t.z)), __builtin_fmaf(sg.s2, t.w, xlane2(t.w))};
;     t = (f32x4){__builtin_fmaf(sg.s4, t.x, xlane4(t.x)), __builtin_fmaf(sg.s4, t.y, xlane4(t.y)), __builtin_fmaf(sg.s4, t.z, xlane4(t.z)), __builtin_fmaf(sg.s4, t.w, xlane4(t.w))};
;     t = (f32x4){__builtin_fmaf(sg.s8, t.x, xlane8(t.x)), __builtin_fmaf(sg.s8, t.y, xlane8(t.y)), __builtin_fmaf(sg.s8, t.z, xlane8(t.z)), __builtin_fmaf(sg.s8, t.w, xlane8(t.w))};
;     return t * 0.125f;
; }
; __device__ __forceinline__ unsigned pack_q8m(float a, float b, float c, float d, float inv) {
;     const unsigned ua = __float_as_uint(__builtin_fmaf(a, inv, 12582912.0f)), ub = __float_as_uint(__builtin_fmaf(b, inv, 12582912.0f));
;     const unsigned uc = __float_as_uint(__builtin_fmaf(c, inv, 12582912.0f)), ud = __float_as_uint(__builtin_fmaf(d, inv, 12582912.0f));
;     return __builtin_amdgcn_perm(__builtin_amdgcn_perm(ud, uc, 0x0c0c0400u), __builtin_amdgcn_perm(ub, ua, 0x0c0c0400u), 0x05040100u);
; }
; __device__ __forceinline__ void rotq_row(f32x4 (&v)[16], unsigned* q8row, float* rsp, int lane) {
;     float am = 0.f; const RotSigns sg = rot_signs(lane);
; #pragma unroll
;     for (int j = 0; j < 16; ++j) { v[j] = rot64(v[j], sg);
;         am = fmaxf(fmaxf(am, fmaxf(fabsf(v[j].x), fabsf(v[j].y))), fmaxf(fabsf(v[j].z), fabsf(v[j].w))); }
	v_pk_add_f32 v[70:71], v[70:71], v[98:99] neg_lo:[0,1] neg_hi:[0,1]
	v_mov_b32_dpp v100, v96 quad_perm:[1,0,3,2] row_mask:0xf bank_mask:0xf bound_ctrl:1
	v_mov_b32_dpp v101, v97 quad_perm:[1,0,3,2] row_mask:0xf bank_mask:0xf bound_ctrl:1
	v_mov_b32_dpp v72, v70 quad_perm:[1,0,3,2] row_mask:0xf bank_mask:0xf bound_ctrl:1
	v_mov_b32_dpp v73, v71 quad_perm:[1,0,3,2] row_mask:0xf bank_mask:0xf bound_ctrl:1
	v_pk_fma_f32 v[96:97], v[46:47], v[96:97], v[100:101]
	v_pk_fma_f32 v[70:71], v[46:47], v[70:71], v[72:73]
	s_nop 0
	v_mov_b32_dpp v100, v96 quad_perm:[2,3,0,1] row_mask:0xf bank_mask:0xf bound_ctrl:1
	v_mov_b32_dpp v101, v97 quad_perm:[2,3,0,1] row_mask:0xf bank_mask:0xf bound_ctrl:1
	v_mov_b32_dpp v72, v70 quad_perm:[2,3,0,1] row_mask:0xf bank_mask:0xf bound_ctrl:1
	v_mov_b32_dpp v73, v71 quad_perm:[2,3,0,1] row_mask:0xf bank_mask:0xf bound_ctrl:1
	v_pk_fma_f32 v[96:97], v[48:49], v[96:97], v[100:101]
	v_pk_fma_f32 v[70:71], v[48:49], v[70:71], v[72:73]
	v_mov_b32_e32 v100, v96
	v_mov_b32_e32 v101, v97
	v_mov_b32_e32 v72, v70
	v_mov_b32_e32 v73, v71
	v_mov_b32_dpp v100, v100 row_shl:4 row_mask:0xf bank_mask:0x5
	v_mov_b32_dpp v101, v101 row_shl:4 row_mask:0xf bank_mask:0x5
	v_mov_b32_dpp v72, v72 row_shl:4 row_mask:0xf bank_mask:0x5
	v_mov_b32_dpp v73, v73 row_shl:4 row_mask:0xf bank_mask:0x5
	v_mov_b32_dpp v100, v96 row_shr:4 row_mask:0xf bank_mask:0xa
	v_mov_b32_dpp v101, v97 row_shr:4 row_mask:0xf bank_mask:0xa
	v_mov_b32_dpp v72, v70 row_shr:4 row_mask:0xf bank_mask:0xa
	v_mov_b32_dpp v73, v71 row_shr:4 row_mask:0xf bank_mask:0xa
	v_pk_fma_f32 v[96:97], v[50:51], v[96:97], v[100:101]
	v_pk_fma_f32 v[70:71], v[50:51], v[70:71], v[72:73]
	s_nop 0
	v_mov_b32_dpp v100, v96 row_ror:8 row_mask:0xf bank_mask:0xf bound_ctrl:1
	v_mov_b32_dpp v101, v97 row_ror:8 row_mask:0xf bank_mask:0xf bound_ctrl:1
	v_mov_b32_dpp v72, v70 row_ror:8 row_mask:0xf bank_mask:0xf bound_ctrl:1
	v_mov_b32_dpp v73, v71 row_ror:8 row_mask:0xf bank_mask:0xf bound_ctrl:1
	v_pk_fma_f32 v[94:95], v[52:53], v[96:97], v[100:101]
	v_pk_fma_f32 v[70:71], v[56:57], v[70:71], v[72:73]
	v_pk_mul_f32 v[72:73], v[94:95], s[18:19] op_sel_hi:[1,0]
	v_pk_mul_f32 v[70:71], v[70:71], s[18:19] op_sel_hi:[1,0]
	v_max_f32_e64 v94, |v72|, |v73|
	v_max_f32_e64 v95, |v70|, |v71|
	v_max3_f32 v38, v38, v94, v95
	v_mov_b32_e32 v94, v78
	v_mov_b32_e32 v95, v80
	v_mov_b32_e32 v96, v79
	v_mov_b32_e32 v97, v81
	v_pk_add_f32 v[98:99], v[94:95], v[96:97]
	v_pk_add_f32 v[94:95], v[94:95], v[96:97] neg_lo:[0,1] neg_hi:[0,1]
	v_pk_mov_b32 v[96:97], v[80:81], v[78:79] op_sel:[1,0]
	v_mov_b32_e32 v81, v79
	v_pk_add_f32 v[78:79], v[96:97], v[80:81]
	v_pk_add_f32 v[80:81], v[96:97], v[80:81] neg_lo:[0,1] neg_hi:[0,1]
	v_mov_b32_e32 v99, v95
	v_mov_b32_e32 v79, v81
	v_pk_add_f32 v[96:97], v[78:79], v[98:99]
	v_mov_b32_e32 v79, v95
	v_mov_b32_e32 v99, v81
	v_pk_add_f32 v[78:79], v[78:79], v[98:99] neg_lo:[0,1] neg_hi:[0,1]
	v_mov_b32_dpp v100, v96 quad_perm:[1,0,3,2] row_mask:0xf bank_mask:0xf bound_ctrl:1
	v_mov_b32_dpp v101, v97 quad_perm:[1,0,3,2] row_mask:0xf bank_mask:0xf bound_ctrl:1
	v_mov_b32_dpp v80, v78 quad_perm:[1,0,3,2] row_mask:0xf bank_mask:0xf bound_ctrl:1
	v_mov_b32_dpp v81, v79 quad_perm:[1,0,3,2] row_mask:0xf bank_mask:0xf bound_ctrl:1
	v_pk_fma_f32 v[96:97], v[46:47], v[96:97], v[100:101]
	v_pk_fma_f32 v[78:79], v[46:47], v[78:79], v[80:81]
	s_nop 0
	v_mov_b32_dpp v100, v96 quad_perm:[2,3,0,1] row_mask:0xf bank_mask:0xf bound_ctrl:1
	v_mov_b32_dpp v101, v97 quad_perm:[2,3,0,1] row_mask:0xf bank_mask:0xf bound_ctrl:1
	v_mov_b32_dpp v80, v78 quad_perm:[2,3,0,1] row_mask:0xf bank_mask:0xf bound_ctrl:1
	v_mov_b32_dpp v81, v79 quad_perm:[2,3,0,1] row_mask:0xf bank_mask:0xf bound_ctrl:1
	v_pk_fma_f32 v[96:97], v[48:49], v[96:97], v[100:101]
	v_pk_fma_f32 v[78:79], v[48:49], v[78:79], v[80:81]
	v_mov_b32_e32 v100, v96
	v_mov_b32_e32 v101, v97
	v_mov_b32_e32 v80, v78
	v_mov_b32_e32 v81, v79
	v_mov_b32_dpp v100, v100 row_shl:4 row_mask:0xf bank_mask:0x5
	v_mov_b32_dpp v101, v101 row_shl:4 row_mask:0xf bank_mask:0x5
	v_mov_b32_dpp v80, v80 row_shl:4 row_mask:0xf bank_mask:0x5
	v_mov_b32_dpp v81, v81 row_shl:4 row_mask:0xf bank_mask:0x5
	v_mov_b32_dpp v100, v96 row_shr:4 row_mask:0xf bank_mask:0xa
	v_mov_b32_dpp v101, v97 row_shr:4 row_mask:0xf bank_mask:0xa
	v_mov_b32_dpp v80, v78 row_shr:4 row_mask:0xf bank_mask:0xa
	v_mov_b32_dpp v81, v79 row_shr:4 row_mask:0xf bank_mask:0xa
	v_pk_fma_f32 v[96:97], v[50:51], v[96:97], v[100:101]
	v_pk_fma_f32 v[78:79], v[50:51], v[78:79], v[80:81]
	s_nop 0
	v_mov_b32_dpp v100, v96 row_ror:8 row_mask:0xf bank_mask:0xf bound_ctrl:1
	v_mov_b32_dpp v101, v97 row_ror:8 row_mask:0xf bank_mask:0xf bound_ctrl:1
	v_mov_b32_dpp v80, v78 row_ror:8 row_mask:0xf bank_mask:0xf bound_ctrl:1
	v_mov_b32_dpp v81, v79 row_ror:8 row_mask:0xf bank_mask:0xf bound_ctrl:1
	v_pk_fma_f32 v[94:95], v[52:53], v[96:97], v[100:101]
	v_pk_fma_f32 v[78:79], v[56:57], v[78:79], v[80:81]
	v_pk_mul_f32 v[80:81], v[94:95], s[18:19] op_sel_hi:[1,0]
	v_pk_mul_f32 v[78:79], v[78:79], s[18:19] op_sel_hi:[1,0]
	v_max_f32_e64 v94, |v80|, |v81|
	v_max_f32_e64 v95, |v78|, |v79|
	v_max3_f32 v38, v38, v94, v95
	v_mov_b32_e32 v94, v86
	v_mov_b32_e32 v95, v88
	v_mov_b32_e32 v96, v87
	v_mov_b32_e32 v97, v89
	v_pk_add_f32 v[98:99], v[94:95], v[96:97]
	v_pk_add_f32 v[94:95], v[94:95], v[96:97] neg_lo:[0,1] neg_hi:[0,1]
	v_pk_mov_b32 v[96:97], v[88:89], v[86:87] op_sel:[1,0]
	v_mov_b32_e32 v89, v87
	v_pk_add_f32 v[86:87], v[96:97], v[88:89]
	v_pk_add_f32 v[88:89], v[96:97], v[88:89] neg_lo:[0,1] neg_hi:[0,1]
	v_mov_b32_e32 v99, v95
	v_mov_b32_e32 v87, v89
	v_pk_add_f32 v[96:97], v[86:87], v[98:99]
; __device__ __forceinline__ float xlane1(float t) { return dpp_mov<0xB1, 0xF, true>(0.f, t); }
; __device__ __forceinline__ float xlane2(float t) { return dpp_mov<0x4E, 0xF, true>(0.f, t); }
; __device__ __forceinline__ float xlane4(float t) { const float r = dpp_mov<0x104, 0x5, false>(t, t); return dpp_mov<0x114, 0xA, false>(r, t); }
; __device__ __forceinline__ float xlane8(float t) { return dpp_mov<0x128, 0xF, true>(0.f, t); }
; __device__ __forceinline__ f32x4 rot64(f32x4 t, const RotSigns sg) {
;     { const float p0 = t.x + t.y, p1 = t.x - t.y, p2 = t.z + t.w, p3 = t.z - t.w; t = (f32x4){p0 + p2, p1 + p3, p0 - p2, p1 - p3}; }
;     t = (f32x4){__builtin_fmaf(sg.s1, t.x, xlane1(t.x)), __builtin_fmaf(sg.s1, t.y, xlane1(t.y)), __builtin_fmaf(sg.s1, t.z, xlane1(t.z)), __builtin_fmaf(sg.s1, t.w, xlane1(t.w))};
;     t = (f32x4){__builtin_fmaf(sg.s2, t.x, xlane2(t.x)), __builtin_fmaf(sg.s2, t.y, xlane2(t.y)), __builtin_fmaf(sg.s2, t.z, xlane2(t.z)), __builtin_fmaf(sg.s2, t.w, xlane2(t.w))};
;     t = (f32x4){__builtin_fmaf(sg.s4, t.x, xlane4(t.x)), __builtin_fmaf(sg.s4, t.y, xlane4(t.y)), __builtin_fmaf(sg.s4, t.z, xlane4(t.z)), __builtin_fmaf(sg.s4, t.w, xlane4(t.w))};
;     t = (f32x4){__builtin_fmaf(sg.s8, t.x, xlane8(t.x)), __builtin_fmaf(sg.s8, t.y, xlane8(t.y)), __builtin_fmaf(sg.s8, t.z, xlane8(t.z)), __builtin_fmaf(sg.s8, t.w, xlane8(t.w))};
;     return t * 0.125f;
; }
; __device__ __forceinline__ unsigned pack_q8m(float a, float b, float c, float d, float inv) {
;     const unsigned ua = __float_as_uint(__builtin_fmaf(a, inv, 12582912.0f)), ub = __float_as_uint(__builtin_fmaf(b, inv, 12582912.0f));
;     const unsigned uc = __float_as_uint(__builtin_fmaf(c, inv, 12582912.0f)), ud = __float_as_uint(__builtin_fmaf(d, inv, 12582912.0f));
;     return __builtin_amdgcn_perm(__builtin_amdgcn_perm(ud, uc, 0x0c0c0400u), __builtin_amdgcn_perm(ub, ua, 0x0c0c0400u), 0x05040100u);
; }
; __device__ __forceinline__ void rotq_row(f32x4 (&v)[16], unsigned* q8row, float* rsp, int lane) {
;     float am = 0.f; const RotSigns sg = rot_signs(lane);
; #pragma unroll
;     for (int j = 0; j < 16; ++j) { v[j] = rot64(v[j], sg);
;         am = fmaxf(fmaxf(am, fmaxf(fabsf(v[j].x), fabsf(v[j].y))), fmaxf(fabsf(v[j].z), fabsf(v[j].w))); }
	v_mov_b32_e32 v87, v95
	v_mov_b32_e32 v99, v89
	v_pk_add_f32 v[86:87], v[86:87], v[98:99] neg_lo:[0,1] neg_hi:[0,1]
	v_mov_b32_dpp v100, v96 quad_perm:[1,0,3,2] row_mask:0xf bank_mask:0xf bound_ctrl:1
	v_mov_b32_dpp v101, v97 quad_perm:[1,0,3,2] row_mask:0xf bank_mask:0xf bound_ctrl:1
	v_mov_b32_dpp v88, v86 quad_perm:[1,0,3,2] row_mask:0xf bank_mask:0xf bound_ctrl:1
	v_mov_b32_dpp v89, v87 quad_perm:[1,0,3,2] row_mask:0xf bank_mask:0xf bound_ctrl:1
	v_pk_fma_f32 v[96:97], v[46:47], v[96:97], v[100:101]
	v_pk_fma_f32 v[86:87], v[46:47], v[86:87], v[88:89]
	s_nop 0
	v_mov_b32_dpp v100, v96 quad_perm:[2,3,0,1] row_mask:0xf bank_mask:0xf bound_ctrl:1
	v_mov_b32_dpp v101, v97 quad_perm:[2,3,0,1] row_mask:0xf bank_mask:0xf bound_ctrl:1
	v_mov_b32_dpp v88, v86 quad_perm:[2,3,0,1] row_mask:0xf bank_mask:0xf bound_ctrl:1
	v_mov_b32_dpp v89, v87 quad_perm:[2,3,0,1] row_mask:0xf bank_mask:0xf bound_ctrl:1
	v_pk_fma_f32 v[96:97], v[48:49], v[96:97], v[100:101]
	v_pk_fma_f32 v[86:87], v[48:49], v[86:87], v[88:89]
	v_mov_b32_e32 v100, v96
	v_mov_b32_e32 v101, v97
	v_mov_b32_e32 v88, v86
	v_mov_b32_e32 v89, v87
	v_mov_b32_dpp v100, v100 row_shl:4 row_mask:0xf bank_mask:0x5
	v_mov_b32_dpp v101, v101 row_shl:4 row_mask:0xf bank_mask:0x5
	v_mov_b32_dpp v88, v88 row_shl:4 row_mask:0xf bank_mask:0x5
	v_mov_b32_dpp v89, v89 row_shl:4 row_mask:0xf bank_mask:0x5
	v_mov_b32_dpp v100, v96 row_shr:4 row_mask:0xf bank_mask:0xa
	v_mov_b32_dpp v101, v97 row_shr:4 row_mask:0xf bank_mask:0xa
	v_mov_b32_dpp v88, v86 row_shr:4 row_mask:0xf bank_mask:0xa
	v_mov_b32_dpp v89, v87 row_shr:4 row_mask:0xf bank_mask:0xa
	v_pk_fma_f32 v[96:97], v[50:51], v[96:97], v[100:101]
	v_pk_fma_f32 v[86:87], v[50:51], v[86:87], v[88:89]
	s_nop 0
	v_mov_b32_dpp v100, v96 row_ror:8 row_mask:0xf bank_mask:0xf bound_ctrl:1
	v_mov_b32_dpp v101, v97 row_ror:8 row_mask:0xf bank_mask:0xf bound_ctrl:1
	v_mov_b32_dpp v88, v86 row_ror:8 row_mask:0xf bank_mask:0xf bound_ctrl:1
	v_mov_b32_dpp v89, v87 row_ror:8 row_mask:0xf bank_mask:0xf bound_ctrl:1
	v_pk_fma_f32 v[94:95], v[52:53], v[96:97], v[100:101]
	v_pk_fma_f32 v[86:87], v[56:57], v[86:87], v[88:89]
	v_pk_mul_f32 v[88:89], v[94:95], s[18:19] op_sel_hi:[1,0]
	v_pk_mul_f32 v[86:87], v[86:87], s[18:19] op_sel_hi:[1,0]
	v_max_f32_e64 v94, |v88|, |v89|
	v_max_f32_e64 v95, |v86|, |v87|
	v_max3_f32 v38, v38, v94, v95
	v_mov_b32_e32 v94, v90
	v_mov_b32_e32 v95, v92
	v_mov_b32_e32 v96, v91
	v_mov_b32_e32 v97, v93
	v_pk_add_f32 v[98:99], v[94:95], v[96:97]
	v_pk_add_f32 v[94:95], v[94:95], v[96:97] neg_lo:[0,1] neg_hi:[0,1]
	v_pk_mov_b32 v[96:97], v[92:93], v[90:91] op_sel:[1,0]
	v_mov_b32_e32 v93, v91
	v_pk_add_f32 v[90:91], v[96:97], v[92:93]
	v_pk_add_f32 v[92:93], v[96:97], v[92:93] neg_lo:[0,1] neg_hi:[0,1]
	v_mov_b32_e32 v99, v95
	v_mov_b32_e32 v91, v93
	v_pk_add_f32 v[96:97], v[90:91], v[98:99]
	v_mov_b32_e32 v91, v95
	v_mov_b32_e32 v99, v93
	v_pk_add_f32 v[90:91], v[90:91], v[98:99] neg_lo:[0,1] neg_hi:[0,1]
	v_mov_b32_dpp v100, v96 quad_perm:[1,0,3,2] row_mask:0xf bank_mask:0xf bound_ctrl:1
	v_mov_b32_dpp v101, v97 quad_perm:[1,0,3,2] row_mask:0xf bank_mask:0xf bound_ctrl:1
	v_mov_b32_dpp v92, v90 quad_perm:[1,0,3,2] row_mask:0xf bank_mask:0xf bound_ctrl:1
	v_mov_b32_dpp v93, v91 quad_perm:[1,0,3,2] row_mask:0xf bank_mask:0xf bound_ctrl:1
	v_pk_fma_f32 v[96:97], v[46:47], v[96:97], v[100:101]
	v_pk_fma_f32 v[90:91], v[46:47], v[90:91], v[92:93]
	s_nop 0
	v_mov_b32_dpp v100, v96 quad_perm:[2,3,0,1] row_mask:0xf bank_mask:0xf bound_ctrl:1
	v_mov_b32_dpp v101, v97 quad_perm:[2,3,0,1] row_mask:0xf bank_mask:0xf bound_ctrl:1
	v_mov_b32_dpp v92, v90 quad_perm:[2,3,0,1] row_mask:0xf bank_mask:0xf bound_ctrl:1
	v_mov_b32_dpp v93, v91 quad_perm:[2,3,0,1] row_mask:0xf bank_mask:0xf bound_ctrl:1
	v_pk_fma_f32 v[96:97], v[48:49], v[96:97], v[100:101]
	v_pk_fma_f32 v[90:91], v[48:49], v[90:91], v[92:93]
	v_mov_b32_e32 v100, v96
	v_mov_b32_e32 v101, v97
	v_mov_b32_e32 v92, v90
	v_mov_b32_e32 v93, v91
	v_mov_b32_dpp v100, v100 row_shl:4 row_mask:0xf bank_mask:0x5
	v_mov_b32_dpp v101, v101 row_shl:4 row_mask:0xf bank_mask:0x5
	v_mov_b32_dpp v92, v92 row_shl:4 row_mask:0xf bank_mask:0x5
	v_mov_b32_dpp v93, v93 row_shl:4 row_mask:0xf bank_mask:0x5
	v_mov_b32_dpp v100, v96 row_shr:4 row_mask:0xf bank_mask:0xa
	v_mov_b32_dpp v101, v97 row_shr:4 row_mask:0xf bank_mask:0xa
	v_mov_b32_dpp v92, v90 row_shr:4 row_mask:0xf bank_mask:0xa
	v_mov_b32_dpp v93, v91 row_shr:4 row_mask:0xf bank_mask:0xa
	v_pk_fma_f32 v[96:97], v[50:51], v[96:97], v[100:101]
	v_pk_fma_f32 v[90:91], v[50:51], v[90:91], v[92:93]
	s_nop 0
	v_mov_b32_dpp v100, v96 row_ror:8 row_mask:0xf bank_mask:0xf bound_ctrl:1
	v_mov_b32_dpp v101, v97 row_ror:8 row_mask:0xf bank_mask:0xf bound_ctrl:1
	v_mov_b32_dpp v92, v90 row_ror:8 row_mask:0xf bank_mask:0xf bound_ctrl:1
	v_mov_b32_dpp v93, v91 row_ror:8 row_mask:0xf bank_mask:0xf bound_ctrl:1
	v_pk_fma_f32 v[94:95], v[52:53], v[96:97], v[100:101]
	v_pk_fma_f32 v[90:91], v[56:57], v[90:91], v[92:93]
	v_pk_mul_f32 v[92:93], v[94:95], s[18:19] op_sel_hi:[1,0]
	v_pk_mul_f32 v[90:91], v[90:91], s[18:19] op_sel_hi:[1,0]
	v_max_f32_e64 v94, |v92|, |v93|
	v_max_f32_e64 v95, |v90|, |v91|
	v_max3_f32 v38, v38, v94, v95
	v_mov_b32_e32 v94, v82
	v_mov_b32_e32 v95, v84
	v_mov_b32_e32 v96, v83
	v_mov_b32_e32 v97, v85
	v_pk_add_f32 v[98:99], v[94:95], v[96:97]
	v_pk_add_f32 v[94:95], v[94:95], v[96:97] neg_lo:[0,1] neg_hi:[0,1]
	v_pk_mov_b32 v[96:97], v[84:85], v[82:83] op_sel:[1,0]
	v_mov_b32_e32 v85, v83
	v_pk_add_f32 v[82:83], v[96:97], v[84:85]
	v_pk_add_f32 v[84:85], v[96:97], v[84:85] neg_lo:[0,1] neg_hi:[0,1]
	v_mov_b32_e32 v99, v95
	v_mov_b32_e32 v83, v85
; __device__ __forceinline__ float xlane1(float t) { return dpp_mov<0xB1, 0xF, true>(0.f, t); }
; __device__ __forceinline__ float xlane2(float t) { return dpp_mov<0x4E, 0xF, true>(0.f, t); }
; __device__ __forceinline__ float xlane4(float t) { const float r = dpp_mov<0x104, 0x5, false>(t, t); return dpp_mov<0x114, 0xA, false>(r, t); }
; __device__ __forceinline__ float xlane8(float t) { return dpp_mov<0x128, 0xF, true>(0.f, t); }
; __device__ __forceinline__ f32x4 rot64(f32x4 t, const RotSigns sg) {
;     { const float p0 = t.x + t.y, p1 = t.x - t.y, p2 = t.z + t.w, p3 = t.z - t.w; t = (f32x4){p0 + p2, p1 + p3, p0 - p2, p1 - p3}; }
;     t = (f32x4){__builtin_fmaf(sg.s1, t.x, xlane1(t.x)), __builtin_fmaf(sg.s1, t.y, xlane1(t.y)), __builtin_fmaf(sg.s1, t.z, xlane1(t.z)), __builtin_fmaf(sg.s1, t.w, xlane1(t.w))};
;     t = (f32x4){__builtin_fmaf(sg.s2, t.x, xlane2(t.x)), __builtin_fmaf(sg.s2, t.y, xlane2(t.y)), __builtin_fmaf(sg.s2, t.z, xlane2(t.z)), __builtin_fmaf(sg.s2, t.w, xlane2(t.w))};
;     t = (f32x4){__builtin_fmaf(sg.s4, t.x, xlane4(t.x)), __builtin_fmaf(sg.s4, t.y, xlane4(t.y)), __builtin_fmaf(sg.s4, t.z, xlane4(t.z)), __builtin_fmaf(sg.s4, t.w, xlane4(t.w))};
;     t = (f32x4){__builtin_fmaf(sg.s8, t.x, xlane8(t.x)), __builtin_fmaf(sg.s8, t.y, xlane8(t.y)), __builtin_fmaf(sg.s8, t.z, xlane8(t.z)), __builtin_fmaf(sg.s8, t.w, xlane8(t.w))};
;     return t * 0.125f;
; }
; __device__ __forceinline__ unsigned pack_q8m(float a, float b, float c, float d, float inv) {
;     const unsigned ua = __float_as_uint(__builtin_fmaf(a, inv, 12582912.0f)), ub = __float_as_uint(__builtin_fmaf(b, inv, 12582912.0f));
;     const unsigned uc = __float_as_uint(__builtin_fmaf(c, inv, 12582912.0f)), ud = __float_as_uint(__builtin_fmaf(d, inv, 12582912.0f));
;     return __builtin_amdgcn_perm(__builtin_amdgcn_perm(ud, uc, 0x0c0c0400u), __builtin_amdgcn_perm(ub, ua, 0x0c0c0400u), 0x05040100u);
; }
; __device__ __forceinline__ void rotq_row(f32x4 (&v)[16], unsigned* q8row, float* rsp, int lane) {
;     float am = 0.f; const RotSigns sg = rot_signs(lane);
; #pragma unroll
;     for (int j = 0; j < 16; ++j) { v[j] = rot64(v[j], sg);
;         am = fmaxf(fmaxf(am, fmaxf(fabsf(v[j].x), fabsf(v[j].y))), fmaxf(fabsf(v[j].z), fabsf(v[j].w))); }
	v_pk_add_f32 v[96:97], v[82:83], v[98:99]
	v_mov_b32_e32 v83, v95
	v_mov_b32_e32 v99, v85
	v_pk_add_f32 v[82:83], v[82:83], v[98:99] neg_lo:[0,1] neg_hi:[0,1]
	v_mov_b32_dpp v100, v96 quad_perm:[1,0,3,2] row_mask:0xf bank_mask:0xf bound_ctrl:1
	v_mov_b32_dpp v101, v97 quad_perm:[1,0,3,2] row_mask:0xf bank_mask:0xf bound_ctrl:1
	v_mov_b32_dpp v84, v82 quad_perm:[1,0,3,2] row_mask:0xf bank_mask:0xf bound_ctrl:1
	v_mov_b32_dpp v85, v83 quad_perm:[1,0,3,2] row_mask:0xf bank_mask:0xf bound_ctrl:1
	v_pk_fma_f32 v[96:97], v[46:47], v[96:97], v[100:101]
	v_pk_fma_f32 v[82:83], v[46:47], v[82:83], v[84:85]
	s_nop 0
	v_mov_b32_dpp v100, v96 quad_perm:[2,3,0,1] row_mask:0xf bank_mask:0xf bound_ctrl:1
	v_mov_b32_dpp v101, v97 quad_perm:[2,3,0,1] row_mask:0xf bank_mask:0xf bound_ctrl:1
	v_mov_b32_dpp v84, v82 quad_perm:[2,3,0,1] row_mask:0xf bank_mask:0xf bound_ctrl:1
	v_mov_b32_dpp v85, v83 quad_perm:[2,3,0,1] row_mask:0xf bank_mask:0xf bound_ctrl:1
	v_pk_fma_f32 v[96:97], v[48:49], v[96:97], v[100:101]
	v_pk_fma_f32 v[82:83], v[48:49], v[82:83], v[84:85]
	v_mov_b32_e32 v100, v96
	v_mov_b32_e32 v101, v97
	v_mov_b32_e32 v84, v82
	v_mov_b32_e32 v85, v83
	v_mov_b32_dpp v100, v100 row_shl:4 row_mask:0xf bank_mask:0x5
	v_mov_b32_dpp v101, v101 row_shl:4 row_mask:0xf bank_mask:0x5
	v_mov_b32_dpp v84, v84 row_shl:4 row_mask:0xf bank_mask:0x5
	v_mov_b32_dpp v85, v85 row_shl:4 row_mask:0xf bank_mask:0x5
	v_mov_b32_dpp v100, v96 row_shr:4 row_mask:0xf bank_mask:0xa
	v_mov_b32_dpp v101, v97 row_shr:4 row_mask:0xf bank_mask:0xa
	v_mov_b32_dpp v84, v82 row_shr:4 row_mask:0xf bank_mask:0xa
	v_mov_b32_dpp v85, v83 row_shr:4 row_mask:0xf bank_mask:0xa
	v_pk_fma_f32 v[96:97], v[50:51], v[96:97], v[100:101]
	v_pk_fma_f32 v[82:83], v[50:51], v[82:83], v[84:85]
	s_nop 0
	v_mov_b32_dpp v100, v96 row_ror:8 row_mask:0xf bank_mask:0xf bound_ctrl:1
	v_mov_b32_dpp v101, v97 row_ror:8 row_mask:0xf bank_mask:0xf bound_ctrl:1
	v_mov_b32_dpp v84, v82 row_ror:8 row_mask:0xf bank_mask:0xf bound_ctrl:1
	v_mov_b32_dpp v85, v83 row_ror:8 row_mask:0xf bank_mask:0xf bound_ctrl:1
	v_pk_fma_f32 v[94:95], v[52:53], v[96:97], v[100:101]
	v_pk_fma_f32 v[82:83], v[56:57], v[82:83], v[84:85]
	v_pk_mul_f32 v[84:85], v[94:95], s[18:19] op_sel_hi:[1,0]
	v_pk_mul_f32 v[82:83], v[82:83], s[18:19] op_sel_hi:[1,0]
	v_max_f32_e64 v94, |v84|, |v85|
	v_max_f32_e64 v95, |v82|, |v83|
	v_max3_f32 v38, v38, v94, v95
	v_mov_b32_e32 v94, v74
	v_mov_b32_e32 v95, v76
	v_mov_b32_e32 v96, v75
	v_mov_b32_e32 v97, v77
	v_pk_add_f32 v[98:99], v[94:95], v[96:97]
	v_pk_add_f32 v[94:95], v[94:95], v[96:97] neg_lo:[0,1] neg_hi:[0,1]
	v_pk_mov_b32 v[96:97], v[76:77], v[74:75] op_sel:[1,0]
	v_mov_b32_e32 v77, v75
	v_pk_add_f32 v[74:75], v[96:97], v[76:77]
	v_pk_add_f32 v[76:77], v[96:97], v[76:77] neg_lo:[0,1] neg_hi:[0,1]
	v_mov_b32_e32 v99, v95
	v_mov_b32_e32 v75, v77
	v_pk_add_f32 v[96:97], v[74:75], v[98:99]
	v_mov_b32_e32 v75, v95
	v_mov_b32_e32 v99, v77
	v_pk_add_f32 v[74:75], v[74:75], v[98:99] neg_lo:[0,1] neg_hi:[0,1]
	v_mov_b32_dpp v100, v96 quad_perm:[1,0,3,2] row_mask:0xf bank_mask:0xf bound_ctrl:1
	v_mov_b32_dpp v101, v97 quad_perm:[1,0,3,2] row_mask:0xf bank_mask:0xf bound_ctrl:1
	v_mov_b32_dpp v76, v74 quad_perm:[1,0,3,2] row_mask:0xf bank_mask:0xf bound_ctrl:1
	v_mov_b32_dpp v77, v75 quad_perm:[1,0,3,2] row_mask:0xf bank_mask:0xf bound_ctrl:1
	v_pk_fma_f32 v[96:97], v[46:47], v[96:97], v[100:101]
	v_pk_fma_f32 v[74:75], v[46:47], v[74:75], v[76:77]
	s_nop 0
	v_mov_b32_dpp v100, v96 quad_perm:[2,3,0,1] row_mask:0xf bank_mask:0xf bound_ctrl:1
	v_mov_b32_dpp v101, v97 quad_perm:[2,3,0,1] row_mask:0xf bank_mask:0xf bound_ctrl:1
	v_mov_b32_dpp v76, v74 quad_perm:[2,3,0,1] row_mask:0xf bank_mask:0xf bound_ctrl:1
	v_mov_b32_dpp v77, v75 quad_perm:[2,3,0,1] row_mask:0xf bank_mask:0xf bound_ctrl:1
	v_pk_fma_f32 v[96:97], v[48:49], v[96:97], v[100:101]
	v_pk_fma_f32 v[74:75], v[48:49], v[74:75], v[76:77]
	v_mov_b32_e32 v100, v96
	v_mov_b32_e32 v101, v97
	v_mov_b32_e32 v76, v74
	v_mov_b32_e32 v77, v75
	v_mov_b32_dpp v100, v100 row_shl:4 row_mask:0xf bank_mask:0x5
	v_mov_b32_dpp v101, v101 row_shl:4 row_mask:0xf bank_mask:0x5
	v_mov_b32_dpp v76, v76 row_shl:4 row_mask:0xf bank_mask:0x5
	v_mov_b32_dpp v77, v77 row_shl:4 row_mask:0xf bank_mask:0x5
	v_mov_b32_dpp v100, v96 row_shr:4 row_mask:0xf bank_mask:0xa
	v_mov_b32_dpp v101, v97 row_shr:4 row_mask:0xf bank_mask:0xa
	v_mov_b32_dpp v76, v74 row_shr:4 row_mask:0xf bank_mask:0xa
	v_mov_b32_dpp v77, v75 row_shr:4 row_mask:0xf bank_mask:0xa
	v_pk_fma_f32 v[96:97], v[50:51], v[96:97], v[100:101]
	v_pk_fma_f32 v[74:75], v[50:51], v[74:75], v[76:77]
	s_nop 0
	v_mov_b32_dpp v100, v96 row_ror:8 row_mask:0xf bank_mask:0xf bound_ctrl:1
	v_mov_b32_dpp v101, v97 row_ror:8 row_mask:0xf bank_mask:0xf bound_ctrl:1
	v_mov_b32_dpp v76, v74 row_ror:8 row_mask:0xf bank_mask:0xf bound_ctrl:1
	v_mov_b32_dpp v77, v75 row_ror:8 row_mask:0xf bank_mask:0xf bound_ctrl:1
	v_pk_fma_f32 v[94:95], v[52:53], v[96:97], v[100:101]
	v_pk_fma_f32 v[74:75], v[56:57], v[74:75], v[76:77]
	v_pk_mul_f32 v[76:77], v[94:95], s[18:19] op_sel_hi:[1,0]
	v_pk_mul_f32 v[74:75], v[74:75], s[18:19] op_sel_hi:[1,0]
	v_max_f32_e64 v94, |v76|, |v77|
	v_max_f32_e64 v95, |v74|, |v75|
	v_max3_f32 v38, v38, v94, v95
	v_mov_b32_e32 v94, v66
	v_mov_b32_e32 v95, v68
	v_mov_b32_e32 v96, v67
	v_mov_b32_e32 v97, v69
	v_pk_add_f32 v[98:99], v[94:95], v[96:97]
	v_pk_add_f32 v[94:95], v[94:95], v[96:97] neg_lo:[0,1] neg_hi:[0,1]
	v_pk_mov_b32 v[96:97], v[68:69], v[66:67] op_sel:[1,0]
	v_mov_b32_e32 v69, v67
	v_pk_add_f32 v[66:67], v[96:97], v[68:69]
	v_pk_add_f32 v[68:69], v[96:97], v[68:69] neg_lo:[0,1] neg_hi:[0,1]
; __device__ __forceinline__ float xlane1(float t) { return dpp_mov<0xB1, 0xF, true>(0.f, t); }
; __device__ __forceinline__ float xlane2(float t) { return dpp_mov<0x4E, 0xF, true>(0.f, t); }
; __device__ __forceinline__ float xlane4(float t) { const float r = dpp_mov<0x104, 0x5, false>(t, t); return dpp_mov<0x114, 0xA, false>(r, t); }
; __device__ __forceinline__ float xlane8(float t) { return dpp_mov<0x128, 0xF, true>(0.f, t); }
; __device__ __forceinline__ f32x4 rot64(f32x4 t, const RotSigns sg) {
;     { const float p0 = t.x + t.y, p1 = t.x - t.y, p2 = t.z + t.w, p3 = t.z - t.w; t = (f32x4){p0 + p2, p1 + p3, p0 - p2, p1 - p3}; }
;     t = (f32x4){__builtin_fmaf(sg.s1, t.x, xlane1(t.x)), __builtin_fmaf(sg.s1, t.y, xlane1(t.y)), __builtin_fmaf(sg.s1, t.z, xlane1(t.z)), __builtin_fmaf(sg.s1, t.w, xlane1(t.w))};
;     t = (f32x4){__builtin_fmaf(sg.s2, t.x, xlane2(t.x)), __builtin_fmaf(sg.s2, t.y, xlane2(t.y)), __builtin_fmaf(sg.s2, t.z, xlane2(t.z)), __builtin_fmaf(sg.s2, t.w, xlane2(t.w))};
;     t = (f32x4){__builtin_fmaf(sg.s4, t.x, xlane4(t.x)), __builtin_fmaf(sg.s4, t.y, xlane4(t.y)), __builtin_fmaf(sg.s4, t.z, xlane4(t.z)), __builtin_fmaf(sg.s4, t.w, xlane4(t.w))};
;     t = (f32x4){__builtin_fmaf(sg.s8, t.x, xlane8(t.x)), __builtin_fmaf(sg.s8, t.y, xlane8(t.y)), __builtin_fmaf(sg.s8, t.z, xlane8(t.z)), __builtin_fmaf(sg.s8, t.w, xlane8(t.w))};
;     return t * 0.125f;
; }
; __device__ __forceinline__ unsigned pack_q8m(float a, float b, float c, float d, float inv) {
;     const unsigned ua = __float_as_uint(__builtin_fmaf(a, inv, 12582912.0f)), ub = __float_as_uint(__builtin_fmaf(b, inv, 12582912.0f));
;     const unsigned uc = __float_as_uint(__builtin_fmaf(c, inv, 12582912.0f)), ud = __float_as_uint(__builtin_fmaf(d, inv, 12582912.0f));
;     return __builtin_amdgcn_perm(__builtin_amdgcn_perm(ud, uc, 0x0c0c0400u), __builtin_amdgcn_perm(ub, ua, 0x0c0c0400u), 0x05040100u);
; }
; __device__ __forceinline__ void rotq_row(f32x4 (&v)[16], unsigned* q8row, float* rsp, int lane) {
;     float am = 0.f; const RotSigns sg = rot_signs(lane);
; #pragma unroll
;     for (int j = 0; j < 16; ++j) { v[j] = rot64(v[j], sg);
;         am = fmaxf(fmaxf(am, fmaxf(fabsf(v[j].x), fabsf(v[j].y))), fmaxf(fabsf(v[j].z), fabsf(v[j].w))); }
	v_mov_b32_e32 v99, v95
	v_mov_b32_e32 v67, v69
	v_pk_add_f32 v[96:97], v[66:67], v[98:99]
	v_mov_b32_e32 v67, v95
	v_mov_b32_e32 v99, v69
	v_pk_add_f32 v[66:67], v[66:67], v[98:99] neg_lo:[0,1] neg_hi:[0,1]
	v_mov_b32_dpp v100, v96 quad_perm:[1,0,3,2] row_mask:0xf bank_mask:0xf bound_ctrl:1
	v_mov_b32_dpp v101, v97 quad_perm:[1,0,3,2] row_mask:0xf bank_mask:0xf bound_ctrl:1
	v_mov_b32_dpp v68, v66 quad_perm:[1,0,3,2] row_mask:0xf bank_mask:0xf bound_ctrl:1
	v_mov_b32_dpp v69, v67 quad_perm:[1,0,3,2] row_mask:0xf bank_mask:0xf bound_ctrl:1
	v_pk_fma_f32 v[96:97], v[46:47], v[96:97], v[100:101]
	v_pk_fma_f32 v[66:67], v[46:47], v[66:67], v[68:69]
	s_nop 0
	v_mov_b32_dpp v100, v96 quad_perm:[2,3,0,1] row_mask:0xf bank_mask:0xf bound_ctrl:1
	v_mov_b32_dpp v101, v97 quad_perm:[2,3,0,1] row_mask:0xf bank_mask:0xf bound_ctrl:1
	v_mov_b32_dpp v68, v66 quad_perm:[2,3,0,1] row_mask:0xf bank_mask:0xf bound_ctrl:1
	v_mov_b32_dpp v69, v67 quad_perm:[2,3,0,1] row_mask:0xf bank_mask:0xf bound_ctrl:1
	v_pk_fma_f32 v[96:97], v[48:49], v[96:97], v[100:101]
	v_pk_fma_f32 v[66:67], v[48:49], v[66:67], v[68:69]
	v_mov_b32_e32 v100, v96
	v_mov_b32_e32 v101, v97
	v_mov_b32_e32 v68, v66
	v_mov_b32_e32 v69, v67
	v_mov_b32_dpp v100, v100 row_shl:4 row_mask:0xf bank_mask:0x5
	v_mov_b32_dpp v101, v101 row_shl:4 row_mask:0xf bank_mask:0x5
	v_mov_b32_dpp v68, v68 row_shl:4 row_mask:0xf bank_mask:0x5
	v_mov_b32_dpp v69, v69 row_shl:4 row_mask:0xf bank_mask:0x5
	v_mov_b32_dpp v100, v96 row_shr:4 row_mask:0xf bank_mask:0xa
	v_mov_b32_dpp v101, v97 row_shr:4 row_mask:0xf bank_mask:0xa
	v_mov_b32_dpp v68, v66 row_shr:4 row_mask:0xf bank_mask:0xa
	v_mov_b32_dpp v69, v67 row_shr:4 row_mask:0xf bank_mask:0xa
	v_pk_fma_f32 v[96:97], v[50:51], v[96:97], v[100:101]
	v_pk_fma_f32 v[66:67], v[50:51], v[66:67], v[68:69]
	s_nop 0
	v_mov_b32_dpp v100, v96 row_ror:8 row_mask:0xf bank_mask:0xf bound_ctrl:1
	v_mov_b32_dpp v101, v97 row_ror:8 row_mask:0xf bank_mask:0xf bound_ctrl:1
	v_mov_b32_dpp v68, v66 row_ror:8 row_mask:0xf bank_mask:0xf bound_ctrl:1
	v_mov_b32_dpp v69, v67 row_ror:8 row_mask:0xf bank_mask:0xf bound_ctrl:1
	v_pk_fma_f32 v[94:95], v[52:53], v[96:97], v[100:101]
	v_pk_fma_f32 v[66:67], v[56:57], v[66:67], v[68:69]
	v_pk_mul_f32 v[68:69], v[94:95], s[18:19] op_sel_hi:[1,0]
	v_pk_mul_f32 v[66:67], v[66:67], s[18:19] op_sel_hi:[1,0]
	v_max_f32_e64 v94, |v68|, |v69|
	v_max_f32_e64 v95, |v66|, |v67|
	v_max3_f32 v38, v38, v94, v95
	v_mov_b32_e32 v94, v34
	v_mov_b32_e32 v95, v36
	v_mov_b32_e32 v96, v35
	v_mov_b32_e32 v97, v37
	v_pk_add_f32 v[98:99], v[94:95], v[96:97]
	v_pk_add_f32 v[94:95], v[94:95], v[96:97] neg_lo:[0,1] neg_hi:[0,1]
	v_pk_mov_b32 v[96:97], v[36:37], v[34:35] op_sel:[1,0]
	v_mov_b32_e32 v37, v35
	v_pk_add_f32 v[34:35], v[96:97], v[36:37]
	v_pk_add_f32 v[36:37], v[96:97], v[36:37] neg_lo:[0,1] neg_hi:[0,1]
	v_mov_b32_e32 v99, v95
	v_mov_b32_e32 v35, v37
	v_pk_add_f32 v[96:97], v[34:35], v[98:99]
	v_mov_b32_e32 v35, v95
	v_mov_b32_e32 v99, v37
	v_pk_add_f32 v[34:35], v[34:35], v[98:99] neg_lo:[0,1] neg_hi:[0,1]
	v_mov_b32_dpp v100, v96 quad_perm:[1,0,3,2] row_mask:0xf bank_mask:0xf bound_ctrl:1
	v_mov_b32_dpp v101, v97 quad_perm:[1,0,3,2] row_mask:0xf bank_mask:0xf bound_ctrl:1
	v_mov_b32_dpp v36, v34 quad_perm:[1,0,3,2] row_mask:0xf bank_mask:0xf bound_ctrl:1
	v_mov_b32_dpp v37, v35 quad_perm:[1,0,3,2] row_mask:0xf bank_mask:0xf bound_ctrl:1
	v_pk_fma_f32 v[96:97], v[46:47], v[96:97], v[100:101]
	v_pk_fma_f32 v[34:35], v[46:47], v[34:35], v[36:37]
	s_nop 0
	v_mov_b32_dpp v100, v96 quad_perm:[2,3,0,1] row_mask:0xf bank_mask:0xf bound_ctrl:1
	v_mov_b32_dpp v101, v97 quad_perm:[2,3,0,1] row_mask:0xf bank_mask:0xf bound_ctrl:1
	v_mov_b32_dpp v36, v34 quad_perm:[2,3,0,1] row_mask:0xf bank_mask:0xf bound_ctrl:1
	v_mov_b32_dpp v37, v35 quad_perm:[2,3,0,1] row_mask:0xf bank_mask:0xf bound_ctrl:1
	v_pk_fma_f32 v[96:97], v[48:49], v[96:97], v[100:101]
	v_pk_fma_f32 v[34:35], v[48:49], v[34:35], v[36:37]
	v_mov_b32_e32 v100, v96
	v_mov_b32_e32 v101, v97
	v_mov_b32_e32 v36, v34
	v_mov_b32_e32 v37, v35
	v_mov_b32_dpp v100, v100 row_shl:4 row_mask:0xf bank_mask:0x5
	v_mov_b32_dpp v101, v101 row_shl:4 row_mask:0xf bank_mask:0x5
	v_mov_b32_dpp v36, v36 row_shl:4 row_mask:0xf bank_mask:0x5
	v_mov_b32_dpp v37, v37 row_shl:4 row_mask:0xf bank_mask:0x5
	v_mov_b32_dpp v100, v96 row_shr:4 row_mask:0xf bank_mask:0xa
	v_mov_b32_dpp v101, v97 row_shr:4 row_mask:0xf bank_mask:0xa
	v_mov_b32_dpp v36, v34 row_shr:4 row_mask:0xf bank_mask:0xa
	v_mov_b32_dpp v37, v35 row_shr:4 row_mask:0xf bank_mask:0xa
	v_pk_fma_f32 v[96:97], v[50:51], v[96:97], v[100:101]
	v_pk_fma_f32 v[34:35], v[50:51], v[34:35], v[36:37]
	s_nop 0
	v_mov_b32_dpp v100, v96 row_ror:8 row_mask:0xf bank_mask:0xf bound_ctrl:1
	v_mov_b32_dpp v101, v97 row_ror:8 row_mask:0xf bank_mask:0xf bound_ctrl:1
	v_mov_b32_dpp v36, v34 row_ror:8 row_mask:0xf bank_mask:0xf bound_ctrl:1
	v_mov_b32_dpp v37, v35 row_ror:8 row_mask:0xf bank_mask:0xf bound_ctrl:1
	v_pk_fma_f32 v[94:95], v[52:53], v[96:97], v[100:101]
	v_pk_fma_f32 v[34:35], v[56:57], v[34:35], v[36:37]
	v_pk_mul_f32 v[36:37], v[94:95], s[18:19] op_sel_hi:[1,0]
	v_pk_mul_f32 v[34:35], v[34:35], s[18:19] op_sel_hi:[1,0]
	v_max_f32_e64 v94, |v36|, |v37|
	v_max_f32_e64 v95, |v34|, |v35|
	v_max3_f32 v38, v38, v94, v95
	v_mov_b32_e32 v94, v26
	v_mov_b32_e32 v95, v24
	v_mov_b32_e32 v96, v27
	v_mov_b32_e32 v97, v25
	v_pk_add_f32 v[98:99], v[94:95], v[96:97]
	v_pk_add_f32 v[94:95], v[94:95], v[96:97] neg_lo:[0,1] neg_hi:[0,1]
	v_pk_mov_b32 v[96:97], v[24:25], v[26:27] op_sel:[1,0]
	v_mov_b32_e32 v25, v27
	v_pk_add_f32 v[26:27], v[96:97], v[24:25]
; __device__ __forceinline__ float xlane1(float t) { return dpp_mov<0xB1, 0xF, true>(0.f, t); }
; __device__ __forceinline__ float xlane2(float t) { return dpp_mov<0x4E, 0xF, true>(0.f, t); }
; __device__ __forceinline__ float xlane4(float t) { const float r = dpp_mov<0x104, 0x5, false>(t, t); return dpp_mov<0x114, 0xA, false>(r, t); }
; __device__ __forceinline__ float xlane8(float t) { return dpp_mov<0x128, 0xF, true>(0.f, t); }
; __device__ __forceinline__ f32x4 rot64(f32x4 t, const RotSigns sg) {
;     { const float p0 = t.x + t.y, p1 = t.x - t.y, p2 = t.z + t.w, p3 = t.z - t.w; t = (f32x4){p0 + p2, p1 + p3, p0 - p2, p1 - p3}; }
;     t = (f32x4){__builtin_fmaf(sg.s1, t.x, xlane1(t.x)), __builtin_fmaf(sg.s1, t.y, xlane1(t.y)), __builtin_fmaf(sg.s1, t.z, xlane1(t.z)), __builtin_fmaf(sg.s1, t.w, xlane1(t.w))};
;     t = (f32x4){__builtin_fmaf(sg.s2, t.x, xlane2(t.x)), __builtin_fmaf(sg.s2, t.y, xlane2(t.y)), __builtin_fmaf(sg.s2, t.z, xlane2(t.z)), __builtin_fmaf(sg.s2, t.w, xlane2(t.w))};
;     t = (f32x4){__builtin_fmaf(sg.s4, t.x, xlane4(t.x)), __builtin_fmaf(sg.s4, t.y, xlane4(t.y)), __builtin_fmaf(sg.s4, t.z, xlane4(t.z)), __builtin_fmaf(sg.s4, t.w, xlane4(t.w))};
;     t = (f32x4){__builtin_fmaf(sg.s8, t.x, xlane8(t.x)), __builtin_fmaf(sg.s8, t.y, xlane8(t.y)), __builtin_fmaf(sg.s8, t.z, xlane8(t.z)), __builtin_fmaf(sg.s8, t.w, xlane8(t.w))};
;     return t * 0.125f;
; }
; __device__ __forceinline__ unsigned pack_q8m(float a, float b, float c, float d, float inv) {
;     const unsigned ua = __float_as_uint(__builtin_fmaf(a, inv, 12582912.0f)), ub = __float_as_uint(__builtin_fmaf(b, inv, 12582912.0f));
;     const unsigned uc = __float_as_uint(__builtin_fmaf(c, inv, 12582912.0f)), ud = __float_as_uint(__builtin_fmaf(d, inv, 12582912.0f));
;     return __builtin_amdgcn_perm(__builtin_amdgcn_perm(ud, uc, 0x0c0c0400u), __builtin_amdgcn_perm(ub, ua, 0x0c0c0400u), 0x05040100u);
; }
; __device__ __forceinline__ void rotq_row(f32x4 (&v)[16], unsigned* q8row, float* rsp, int lane) {
;     float am = 0.f; const RotSigns sg = rot_signs(lane);
; #pragma unroll
;     for (int j = 0; j < 16; ++j) { v[j] = rot64(v[j], sg);
;         am = fmaxf(fmaxf(am, fmaxf(fabsf(v[j].x), fabsf(v[j].y))), fmaxf(fabsf(v[j].z), fabsf(v[j].w))); }
	v_pk_add_f32 v[24:25], v[96:97], v[24:25] neg_lo:[0,1] neg_hi:[0,1]
	v_mov_b32_e32 v99, v95
	v_mov_b32_e32 v27, v25
	v_pk_add_f32 v[96:97], v[26:27], v[98:99]
	v_mov_b32_e32 v27, v95
	v_mov_b32_e32 v99, v25
	v_pk_add_f32 v[24:25], v[26:27], v[98:99] neg_lo:[0,1] neg_hi:[0,1]
	v_mov_b32_dpp v100, v96 quad_perm:[1,0,3,2] row_mask:0xf bank_mask:0xf bound_ctrl:1
	v_mov_b32_dpp v101, v97 quad_perm:[1,0,3,2] row_mask:0xf bank_mask:0xf bound_ctrl:1
	v_mov_b32_dpp v26, v24 quad_perm:[1,0,3,2] row_mask:0xf bank_mask:0xf bound_ctrl:1
	v_mov_b32_dpp v27, v25 quad_perm:[1,0,3,2] row_mask:0xf bank_mask:0xf bound_ctrl:1
	v_pk_fma_f32 v[96:97], v[46:47], v[96:97], v[100:101]
	v_pk_fma_f32 v[24:25], v[46:47], v[24:25], v[26:27]
	s_nop 0
	v_mov_b32_dpp v100, v96 quad_perm:[2,3,0,1] row_mask:0xf bank_mask:0xf bound_ctrl:1
	v_mov_b32_dpp v101, v97 quad_perm:[2,3,0,1] row_mask:0xf bank_mask:0xf bound_ctrl:1
	v_mov_b32_dpp v26, v24 quad_perm:[2,3,0,1] row_mask:0xf bank_mask:0xf bound_ctrl:1
	v_mov_b32_dpp v27, v25 quad_perm:[2,3,0,1] row_mask:0xf bank_mask:0xf bound_ctrl:1
	v_pk_fma_f32 v[96:97], v[48:49], v[96:97], v[100:101]
	v_pk_fma_f32 v[24:25], v[48:49], v[24:25], v[26:27]
	v_mov_b32_e32 v100, v96
	v_mov_b32_e32 v101, v97
	v_mov_b32_e32 v26, v24
	v_mov_b32_e32 v27, v25
	v_mov_b32_dpp v100, v100 row_shl:4 row_mask:0xf bank_mask:0x5
	v_mov_b32_dpp v101, v101 row_shl:4 row_mask:0xf bank_mask:0x5
	v_mov_b32_dpp v26, v26 row_shl:4 row_mask:0xf bank_mask:0x5
	v_mov_b32_dpp v27, v27 row_shl:4 row_mask:0xf bank_mask:0x5
	v_mov_b32_dpp v100, v96 row_shr:4 row_mask:0xf bank_mask:0xa
	v_mov_b32_dpp v101, v97 row_shr:4 row_mask:0xf bank_mask:0xa
	v_mov_b32_dpp v26, v24 row_shr:4 row_mask:0xf bank_mask:0xa
	v_mov_b32_dpp v27, v25 row_shr:4 row_mask:0xf bank_mask:0xa
	v_pk_fma_f32 v[96:97], v[50:51], v[96:97], v[100:101]
	v_pk_fma_f32 v[24:25], v[50:51], v[24:25], v[26:27]
	s_nop 0
	v_mov_b32_dpp v100, v96 row_ror:8 row_mask:0xf bank_mask:0xf bound_ctrl:1
	v_mov_b32_dpp v101, v97 row_ror:8 row_mask:0xf bank_mask:0xf bound_ctrl:1
	v_mov_b32_dpp v26, v24 row_ror:8 row_mask:0xf bank_mask:0xf bound_ctrl:1
	v_mov_b32_dpp v27, v25 row_ror:8 row_mask:0xf bank_mask:0xf bound_ctrl:1
	v_pk_fma_f32 v[94:95], v[52:53], v[96:97], v[100:101]
	v_pk_fma_f32 v[24:25], v[56:57], v[24:25], v[26:27]
	v_pk_mul_f32 v[26:27], v[94:95], s[18:19] op_sel_hi:[1,0]
	v_pk_mul_f32 v[24:25], v[24:25], s[18:19] op_sel_hi:[1,0]
	v_max_f32_e64 v94, |v26|, |v27|
	v_max_f32_e64 v95, |v24|, |v25|
	v_max3_f32 v38, v38, v94, v95
	v_mov_b32_e32 v94, v18
	v_mov_b32_e32 v95, v16
	v_mov_b32_e32 v96, v19
	v_mov_b32_e32 v97, v17
	v_pk_add_f32 v[98:99], v[94:95], v[96:97]
	v_pk_add_f32 v[94:95], v[94:95], v[96:97] neg_lo:[0,1] neg_hi:[0,1]
	v_pk_mov_b32 v[96:97], v[16:17], v[18:19] op_sel:[1,0]
	v_mov_b32_e32 v17, v19
	v_pk_add_f32 v[18:19], v[96:97], v[16:17]
	v_pk_add_f32 v[16:17], v[96:97], v[16:17] neg_lo:[0,1] neg_hi:[0,1]
	v_mov_b32_e32 v99, v95
	v_mov_b32_e32 v19, v17
	v_pk_add_f32 v[96:97], v[18:19], v[98:99]
	v_mov_b32_e32 v19, v95
	v_mov_b32_e32 v99, v17
	v_pk_add_f32 v[16:17], v[18:19], v[98:99] neg_lo:[0,1] neg_hi:[0,1]
	v_mov_b32_dpp v100, v96 quad_perm:[1,0,3,2] row_mask:0xf bank_mask:0xf bound_ctrl:1
	v_mov_b32_dpp v101, v97 quad_perm:[1,0,3,2] row_mask:0xf bank_mask:0xf bound_ctrl:1
	v_mov_b32_dpp v18, v16 quad_perm:[1,0,3,2] row_mask:0xf bank_mask:0xf bound_ctrl:1
	v_mov_b32_dpp v19, v17 quad_perm:[1,0,3,2] row_mask:0xf bank_mask:0xf bound_ctrl:1
	v_pk_fma_f32 v[96:97], v[46:47], v[96:97], v[100:101]
	v_pk_fma_f32 v[16:17], v[46:47], v[16:17], v[18:19]
	s_nop 0
	v_mov_b32_dpp v100, v96 quad_perm:[2,3,0,1] row_mask:0xf bank_mask:0xf bound_ctrl:1
	v_mov_b32_dpp v101, v97 quad_perm:[2,3,0,1] row_mask:0xf bank_mask:0xf bound_ctrl:1
	v_mov_b32_dpp v18, v16 quad_perm:[2,3,0,1] row_mask:0xf bank_mask:0xf bound_ctrl:1
	v_mov_b32_dpp v19, v17 quad_perm:[2,3,0,1] row_mask:0xf bank_mask:0xf bound_ctrl:1
	v_pk_fma_f32 v[96:97], v[48:49], v[96:97], v[100:101]
	v_pk_fma_f32 v[16:17], v[48:49], v[16:17], v[18:19]
	v_mov_b32_e32 v100, v96
	v_mov_b32_e32 v101, v97
	v_mov_b32_e32 v18, v16
	v_mov_b32_e32 v19, v17
	v_mov_b32_dpp v100, v100 row_shl:4 row_mask:0xf bank_mask:0x5
	v_mov_b32_dpp v101, v101 row_shl:4 row_mask:0xf bank_mask:0x5
	v_mov_b32_dpp v18, v18 row_shl:4 row_mask:0xf bank_mask:0x5
	v_mov_b32_dpp v19, v19 row_shl:4 row_mask:0xf bank_mask:0x5
	v_mov_b32_dpp v100, v96 row_shr:4 row_mask:0xf bank_mask:0xa
	v_mov_b32_dpp v101, v97 row_shr:4 row_mask:0xf bank_mask:0xa
	v_mov_b32_dpp v18, v16 row_shr:4 row_mask:0xf bank_mask:0xa
	v_mov_b32_dpp v19, v17 row_shr:4 row_mask:0xf bank_mask:0xa
	v_pk_fma_f32 v[96:97], v[50:51], v[96:97], v[100:101]
	v_pk_fma_f32 v[16:17], v[50:51], v[16:17], v[18:19]
	s_nop 0
	v_mov_b32_dpp v100, v96 row_ror:8 row_mask:0xf bank_mask:0xf bound_ctrl:1
	v_mov_b32_dpp v101, v97 row_ror:8 row_mask:0xf bank_mask:0xf bound_ctrl:1
	v_mov_b32_dpp v18, v16 row_ror:8 row_mask:0xf bank_mask:0xf bound_ctrl:1
	v_mov_b32_dpp v19, v17 row_ror:8 row_mask:0xf bank_mask:0xf bound_ctrl:1
	v_pk_fma_f32 v[94:95], v[52:53], v[96:97], v[100:101]
	v_pk_fma_f32 v[16:17], v[56:57], v[16:17], v[18:19]
	v_pk_mul_f32 v[18:19], v[94:95], s[18:19] op_sel_hi:[1,0]
	v_pk_mul_f32 v[16:17], v[16:17], s[18:19] op_sel_hi:[1,0]
	v_max_f32_e64 v94, |v18|, |v19|
	v_max_f32_e64 v95, |v16|, |v17|
	v_max3_f32 v38, v38, v94, v95
	v_mov_b32_e32 v94, v10
	v_mov_b32_e32 v95, v8
	v_mov_b32_e32 v96, v11
	v_mov_b32_e32 v97, v9
	v_pk_add_f32 v[98:99], v[94:95], v[96:97]
	v_pk_add_f32 v[94:95], v[94:95], v[96:97] neg_lo:[0,1] neg_hi:[0,1]
	v_pk_mov_b32 v[96:97], v[8:9], v[10:11] op_sel:[1,0]
	v_mov_b32_e32 v9, v11
; __device__ __forceinline__ float xlane1(float t) { return dpp_mov<0xB1, 0xF, true>(0.f, t); }
; __device__ __forceinline__ float xlane2(float t) { return dpp_mov<0x4E, 0xF, true>(0.f, t); }
; __device__ __forceinline__ float xlane4(float t) { const float r = dpp_mov<0x104, 0x5, false>(t, t); return dpp_mov<0x114, 0xA, false>(r, t); }
; __device__ __forceinline__ f32x4 rot64(f32x4 t, const RotSigns sg) {
;     { const float p0 = t.x + t.y, p1 = t.x - t.y, p2 = t.z + t.w, p3 = t.z - t.w; t = (f32x4){p0 + p2, p1 + p3, p0 - p2, p1 - p3}; }
;     t = (f32x4){__builtin_fmaf(sg.s1, t.x, xlane1(t.x)), __builtin_fmaf(sg.s1, t.y, xlane1(t.y)), __builtin_fmaf(sg.s1, t.z, xlane1(t.z)), __builtin_fmaf(sg.s1, t.w, xlane1(t.w))};
;     t = (f32x4){__builtin_fmaf(sg.s2, t.x, xlane2(t.x)), __builtin_fmaf(sg.s2, t.y, xlane2(t.y)), __builtin_fmaf(sg.s2, t.z, xlane2(t.z)), __builtin_fmaf(sg.s2, t.w, xlane2(t.w))};
;     t = (f32x4){__builtin_fmaf(sg.s4, t.x, xlane4(t.x)), __builtin_fmaf(sg.s4, t.y, xlane4(t.y)), __builtin_fmaf(sg.s4, t.z, xlane4(t.z)), __builtin_fmaf(sg.s4, t.w, xlane4(t.w))};
;     t = (f32x4){__builtin_fmaf(sg.s8, t.x, xlane8(t.x)), __builtin_fmaf(sg.s8, t.y, xlane8(t.y)), __builtin_fmaf(sg.s8, t.z, xlane8(t.z)), __builtin_fmaf(sg.s8, t.w, xlane8(t.w))};
;     return t * 0.125f;
; }
; __device__ __forceinline__ unsigned pack_q8m(float a, float b, float c, float d, float inv) {
;     const unsigned ua = __float_as_uint(__builtin_fmaf(a, inv, 12582912.0f)), ub = __float_as_uint(__builtin_fmaf(b, inv, 12582912.0f));
;     const unsigned uc = __float_as_uint(__builtin_fmaf(c, inv, 12582912.0f)), ud = __float_as_uint(__builtin_fmaf(d, inv, 12582912.0f));
;     return __builtin_amdgcn_perm(__builtin_amdgcn_perm(ud, uc, 0x0c0c0400u), __builtin_amdgcn_perm(ub, ua, 0x0c0c0400u), 0x05040100u);
; }
; __device__ __forceinline__ void rotq_row(f32x4 (&v)[16], unsigned* q8row, float* rsp, int lane) {
;     float am = 0.f; const RotSigns sg = rot_signs(lane);
; #pragma unroll
;     for (int j = 0; j < 16; ++j) { v[j] = rot64(v[j], sg);
;         am = fmaxf(fmaxf(am, fmaxf(fabsf(v[j].x), fabsf(v[j].y))), fmaxf(fabsf(v[j].z), fabsf(v[j].w))); }
; #pragma unroll
;     for (int o = 1; o < 64; o <<= 1) am = fmaxf(am, __shfl_xor(am, o));
;     am = fmaxf(am, 1e-30f); const float qi = 127.0f / am;
	v_pk_add_f32 v[10:11], v[96:97], v[8:9]
	v_pk_add_f32 v[8:9], v[96:97], v[8:9] neg_lo:[0,1] neg_hi:[0,1]
	v_mov_b32_e32 v99, v95
	v_mov_b32_e32 v11, v9
	v_pk_add_f32 v[96:97], v[10:11], v[98:99]
	v_mov_b32_e32 v11, v95
	v_mov_b32_e32 v99, v9
	v_pk_add_f32 v[8:9], v[10:11], v[98:99] neg_lo:[0,1] neg_hi:[0,1]
	v_mov_b32_dpp v100, v96 quad_perm:[1,0,3,2] row_mask:0xf bank_mask:0xf bound_ctrl:1
	v_mov_b32_dpp v101, v97 quad_perm:[1,0,3,2] row_mask:0xf bank_mask:0xf bound_ctrl:1
	v_mov_b32_dpp v10, v8 quad_perm:[1,0,3,2] row_mask:0xf bank_mask:0xf bound_ctrl:1
	v_mov_b32_dpp v11, v9 quad_perm:[1,0,3,2] row_mask:0xf bank_mask:0xf bound_ctrl:1
	v_pk_fma_f32 v[96:97], v[46:47], v[96:97], v[100:101]
	v_pk_fma_f32 v[8:9], v[46:47], v[8:9], v[10:11]
	s_nop 0
	v_mov_b32_dpp v100, v96 quad_perm:[2,3,0,1] row_mask:0xf bank_mask:0xf bound_ctrl:1
	v_mov_b32_dpp v101, v97 quad_perm:[2,3,0,1] row_mask:0xf bank_mask:0xf bound_ctrl:1
	v_mov_b32_dpp v10, v8 quad_perm:[2,3,0,1] row_mask:0xf bank_mask:0xf bound_ctrl:1
	v_mov_b32_dpp v11, v9 quad_perm:[2,3,0,1] row_mask:0xf bank_mask:0xf bound_ctrl:1
	v_pk_fma_f32 v[96:97], v[48:49], v[96:97], v[100:101]
	v_pk_fma_f32 v[8:9], v[48:49], v[8:9], v[10:11]
	v_mov_b32_e32 v100, v96
	v_mov_b32_e32 v101, v97
	v_mov_b32_e32 v10, v8
	v_mov_b32_e32 v11, v9
	v_mov_b32_dpp v100, v100 row_shl:4 row_mask:0xf bank_mask:0x5
	v_mov_b32_dpp v101, v101 row_shl:4 row_mask:0xf bank_mask:0x5
	v_mov_b32_dpp v10, v10 row_shl:4 row_mask:0xf bank_mask:0x5
	v_mov_b32_dpp v11, v11 row_shl:4 row_mask:0xf bank_mask:0x5
	v_mov_b32_dpp v100, v96 row_shr:4 row_mask:0xf bank_mask:0xa
	v_mov_b32_dpp v101, v97 row_shr:4 row_mask:0xf bank_mask:0xa
	v_mov_b32_dpp v10, v8 row_shr:4 row_mask:0xf bank_mask:0xa
	v_mov_b32_dpp v11, v9 row_shr:4 row_mask:0xf bank_mask:0xa
	v_pk_fma_f32 v[96:97], v[50:51], v[96:97], v[100:101]
	v_pk_fma_f32 v[8:9], v[50:51], v[8:9], v[10:11]
	s_nop 0
	v_mov_b32_dpp v100, v96 row_ror:8 row_mask:0xf bank_mask:0xf bound_ctrl:1
	v_mov_b32_dpp v101, v97 row_ror:8 row_mask:0xf bank_mask:0xf bound_ctrl:1
	v_mov_b32_dpp v10, v8 row_ror:8 row_mask:0xf bank_mask:0xf bound_ctrl:1
	v_mov_b32_dpp v11, v9 row_ror:8 row_mask:0xf bank_mask:0xf bound_ctrl:1
	v_pk_fma_f32 v[94:95], v[52:53], v[96:97], v[100:101]
	v_pk_fma_f32 v[8:9], v[56:57], v[8:9], v[10:11]
	v_pk_mul_f32 v[94:95], v[94:95], s[18:19] op_sel_hi:[1,0]
	v_pk_mul_f32 v[10:11], v[8:9], s[18:19] op_sel_hi:[1,0]
	v_max_f32_e64 v8, |v94|, |v95|
	v_max_f32_e64 v9, |v10|, |v11|
	v_max3_f32 v8, v38, v8, v9
	ds_bpermute_b32 v9, v136, v8
	s_waitcnt lgkmcnt(0)
	v_max_f32_e32 v9, v9, v9
	v_max_f32_e32 v8, v8, v9
	ds_bpermute_b32 v9, v137, v8
	s_waitcnt lgkmcnt(0)
	v_max_f32_e32 v9, v9, v9
	v_max_f32_e32 v8, v8, v9
	ds_bpermute_b32 v9, v138, v8
	s_waitcnt lgkmcnt(0)
	v_max_f32_e32 v9, v9, v9
	v_max_f32_e32 v8, v8, v9
	ds_bpermute_b32 v9, v139, v8
	s_waitcnt lgkmcnt(0)
	v_max_f32_e32 v9, v9, v9
	v_max_f32_e32 v8, v8, v9
	ds_bpermute_b32 v9, v140, v8
	s_waitcnt lgkmcnt(0)
	v_max_f32_e32 v9, v9, v9
	v_max_f32_e32 v8, v8, v9
	ds_bpermute_b32 v9, v141, v8
	s_waitcnt lgkmcnt(0)
; __device__ __forceinline__ unsigned pack_q8m(float a, float b, float c, float d, float inv) {
;     const unsigned ua = __float_as_uint(__builtin_fmaf(a, inv, 12582912.0f)), ub = __float_as_uint(__builtin_fmaf(b, inv, 12582912.0f));
;     const unsigned uc = __float_as_uint(__builtin_fmaf(c, inv, 12582912.0f)), ud = __float_as_uint(__builtin_fmaf(d, inv, 12582912.0f));
;     return __builtin_amdgcn_perm(__builtin_amdgcn_perm(ud, uc, 0x0c0c0400u), __builtin_amdgcn_perm(ub, ua, 0x0c0c0400u), 0x05040100u);
; }
; __device__ __forceinline__ void rotq_row(f32x4 (&v)[16], unsigned* q8row, float* rsp, int lane) {
;     float am = 0.f; const RotSigns sg = rot_signs(lane);
; #pragma unroll
;     for (int j = 0; j < 16; ++j) { v[j] = rot64(v[j], sg);
;         am = fmaxf(fmaxf(am, fmaxf(fabsf(v[j].x), fabsf(v[j].y))), fmaxf(fabsf(v[j].z), fabsf(v[j].w))); }
; #pragma unroll
;     for (int o = 1; o < 64; o <<= 1) am = fmaxf(am, __shfl_xor(am, o));
;     am = fmaxf(am, 1e-30f); const float qi = 127.0f / am;
; #pragma unroll
;     for (int j = 0; j < 16; ++j) q8row[lane + 64 * j] = pack_q8m(v[j].x, v[j].y, v[j].z, v[j].w, qi);
;     if (lane == 0) *rsp = am * (1.0f / 127.0f);
	v_max3_f32 v8, v8, v9, s13
	v_div_scale_f32 v9, s[0:1], v8, v8, s16
	v_rcp_f32_e32 v38, v9
	s_lshl_b64 s[0:1], s[36:37], 12
	v_fma_f32 v2, -v9, v38, 1.0
	v_fmac_f32_e32 v38, v2, v38
	v_div_scale_f32 v2, vcc, s16, v8, s16
	v_mul_f32_e32 v3, v2, v38
	v_fma_f32 v30, -v9, v3, v2
	v_fmac_f32_e32 v3, v30, v38
	v_fma_f32 v2, -v9, v3, v2
	v_div_fmas_f32 v2, v2, v38, v3
	v_div_fixup_f32 v9, v2, v8, s16
	v_fmaak_f32 v2, v6, v9, 0x4b400000
	v_fmaak_f32 v3, v7, v9, 0x4b400000
	v_fmaak_f32 v4, v4, v9, 0x4b400000
	v_fmaak_f32 v5, v5, v9, 0x4b400000
	v_perm_b32 v4, v5, v4, s17
	v_perm_b32 v2, v3, v2, s17
	v_perm_b32 v4, v4, v2, s19
	v_lshl_add_u64 v[2:3], v[54:55], 0, s[0:1]
	global_store_dword v[2:3], v4, off
	v_fmaak_f32 v4, v14, v9, 0x4b400000
	v_fmaak_f32 v5, v15, v9, 0x4b400000
	v_fmaak_f32 v6, v12, v9, 0x4b400000
	v_fmaak_f32 v7, v13, v9, 0x4b400000
	v_perm_b32 v6, v7, v6, s17
	v_perm_b32 v4, v5, v4, s17
	v_perm_b32 v4, v6, v4, s19
	global_store_dword v[2:3], v4, off offset:256
	v_fmaak_f32 v4, v22, v9, 0x4b400000
	v_fmaak_f32 v5, v23, v9, 0x4b400000
	v_fmaak_f32 v6, v20, v9, 0x4b400000
	v_fmaak_f32 v7, v21, v9, 0x4b400000
	v_perm_b32 v6, v7, v6, s17
	v_perm_b32 v4, v5, v4, s17
	v_perm_b32 v4, v6, v4, s19
	global_store_dword v[2:3], v4, off offset:512
	v_fmaak_f32 v4, v32, v9, 0x4b400000
	v_fmaak_f32 v5, v33, v9, 0x4b400000
	v_fmaak_f32 v6, v28, v9, 0x4b400000
	v_fmaak_f32 v7, v29, v9, 0x4b400000
	v_perm_b32 v6, v7, v6, s17
	v_perm_b32 v4, v5, v4, s17
	v_perm_b32 v4, v6, v4, s19
	global_store_dword v[2:3], v4, off offset:768
	v_fmaak_f32 v4, v64, v9, 0x4b400000
	v_fmaak_f32 v5, v65, v9, 0x4b400000
	v_fmaak_f32 v6, v62, v9, 0x4b400000
	v_fmaak_f32 v7, v63, v9, 0x4b400000
	v_perm_b32 v6, v7, v6, s17
	v_perm_b32 v4, v5, v4, s17
	v_perm_b32 v4, v6, v4, s19
	global_store_dword v[2:3], v4, off offset:1024
	v_fmaak_f32 v4, v72, v9, 0x4b400000
	v_fmaak_f32 v5, v73, v9, 0x4b400000
	v_fmaak_f32 v6, v70, v9, 0x4b400000
	v_fmaak_f32 v7, v71, v9, 0x4b400000
	v_perm_b32 v6, v7, v6, s17
	v_perm_b32 v4, v5, v4, s17
	v_perm_b32 v4, v6, v4, s19
	global_store_dword v[2:3], v4, off offset:1280
	v_fmaak_f32 v4, v80, v9, 0x4b400000
	v_fmaak_f32 v5, v81, v9, 0x4b400000
	v_fmaak_f32 v6, v78, v9, 0x4b400000
	v_fmaak_f32 v7, v79, v9, 0x4b400000
	v_perm_b32 v6, v7, v6, s17
	v_perm_b32 v4, v5, v4, s17
	v_perm_b32 v4, v6, v4, s19
	global_store_dword v[2:3], v4, off offset:1536
	v_fmaak_f32 v4, v88, v9, 0x4b400000
	v_fmaak_f32 v5, v89, v9, 0x4b400000
	v_fmaak_f32 v6, v86, v9, 0x4b400000
	v_fmaak_f32 v7, v87, v9, 0x4b400000
	v_perm_b32 v6, v7, v6, s17
	v_perm_b32 v4, v5, v4, s17
	v_perm_b32 v4, v6, v4, s19
	global_store_dword v[2:3], v4, off offset:1792
	v_fmaak_f32 v4, v92, v9, 0x4b400000
	v_fmaak_f32 v5, v93, v9, 0x4b400000
	v_fmaak_f32 v6, v90, v9, 0x4b400000
	v_fmaak_f32 v7, v91, v9, 0x4b400000
	v_perm_b32 v6, v7, v6, s17
	v_perm_b32 v4, v5, v4, s17
	v_perm_b32 v4, v6, v4, s19
	global_store_dword v[2:3], v4, off offset:2048
	v_fmaak_f32 v4, v84, v9, 0x4b400000
	v_fmaak_f32 v5, v85, v9, 0x4b400000
	v_fmaak_f32 v6, v82, v9, 0x4b400000
	v_fmaak_f32 v7, v83, v9, 0x4b400000
	v_perm_b32 v6, v7, v6, s17
	v_perm_b32 v4, v5, v4, s17
	v_perm_b32 v4, v6, v4, s19
	global_store_dword v[2:3], v4, off offset:2304
	v_fmaak_f32 v4, v76, v9, 0x4b400000
	v_fmaak_f32 v5, v77, v9, 0x4b400000
	v_fmaak_f32 v6, v74, v9, 0x4b400000
	v_fmaak_f32 v7, v75, v9, 0x4b400000
	v_perm_b32 v6, v7, v6, s17
	v_perm_b32 v4, v5, v4, s17
	v_perm_b32 v4, v6, v4, s19
	global_store_dword v[2:3], v4, off offset:2560
	v_fmaak_f32 v4, v68, v9, 0x4b400000
	v_fmaak_f32 v5, v69, v9, 0x4b400000
	v_fmaak_f32 v6, v66, v9, 0x4b400000
	v_fmaak_f32 v7, v67, v9, 0x4b400000
	v_perm_b32 v6, v7, v6, s17
	v_perm_b32 v4, v5, v4, s17
	v_perm_b32 v4, v6, v4, s19
	global_store_dword v[2:3], v4, off offset:2816
	v_fmaak_f32 v4, v36, v9, 0x4b400000
	v_fmaak_f32 v5, v37, v9, 0x4b400000
	v_fmaak_f32 v6, v34, v9, 0x4b400000
	v_fmaak_f32 v7, v35, v9, 0x4b400000
	v_perm_b32 v6, v7, v6, s17
	v_perm_b32 v4, v5, v4, s17
	v_perm_b32 v4, v6, v4, s19
	global_store_dword v[2:3], v4, off offset:3072
	v_fmaak_f32 v4, v26, v9, 0x4b400000
	v_fmaak_f32 v5, v27, v9, 0x4b400000
	v_fmaak_f32 v6, v24, v9, 0x4b400000
	v_fmaak_f32 v7, v25, v9, 0x4b400000
	v_perm_b32 v6, v7, v6, s17
	v_perm_b32 v4, v5, v4, s17
	v_perm_b32 v4, v6, v4, s19
	global_store_dword v[2:3], v4, off offset:3328
	v_fmaak_f32 v4, v18, v9, 0x4b400000
	v_fmaak_f32 v5, v19, v9, 0x4b400000
	v_fmaak_f32 v6, v16, v9, 0x4b400000
	v_fmaak_f32 v7, v17, v9, 0x4b400000
	v_perm_b32 v6, v7, v6, s17
	v_perm_b32 v4, v5, v4, s17
	v_perm_b32 v4, v6, v4, s19
	global_store_dword v[2:3], v4, off offset:3584
	v_fmaak_f32 v4, v94, v9, 0x4b400000
	v_fmaak_f32 v5, v95, v9, 0x4b400000
	v_fmaak_f32 v6, v10, v9, 0x4b400000
	v_fmaak_f32 v7, v11, v9, 0x4b400000
	v_perm_b32 v6, v7, v6, s17
	v_perm_b32 v4, v5, v4, s17
	v_perm_b32 v4, v6, v4, s19
	global_store_dword v[2:3], v4, off offset:3840
	s_and_saveexec_b64 s[0:1], s[2:3]
	s_cbranch_execz .LBB0_770
	s_lshl_b64 s[24:25], s[36:37], 2
	s_add_u32 s24, s48, s24
	v_mul_f32_e32 v2, 0x3c010204, v8
	s_addc_u32 s25, s49, s25
	global_store_dword v39, v2, s[24:25]
	s_branch .LBB0_770

; __global__ void __launch_bounds__(NWAVES * 64, 2) fwd_kernel(Args args) {
;     ...
;         { const unsigned T = (unsigned)D * (DFF / 8), S = (unsigned)G * NWAVES * 64;
;           for (unsigned it = (unsigned)bx * NWAVES * 64 + tid; it < T; it += 4 * S) {
;               v4u w[4]; unsigned cm[4];
; #pragma unroll
;               for (int j = 0; j < 4; ++j) { const unsigned i2 = it + j * S; if (i2 < T) { w[j] = *(const v4u*)(Wdn_t + (size_t)i2 * 8); cm[j] = cmaxd[i2 / (DFF / 8)]; } }
.LBB0_921:
	v_mul_hi_u32 v16, v19, s20
	v_lshl_add_u64 v[14:15], v[20:21], 1, s[42:43]
	v_lshrrev_b32_e32 v16, 6, v16
	v_and_b32_e32 v22, 0xfffffc, v16
	global_load_dwordx4 v[14:17], v[14:15], off nt
	s_nop 0
	global_load_dword v28, v22, s[40:41] nt
	v_add_u32_e32 v22, s18, v19
	v_cmp_gt_u32_e64 s[0:1], s6, v22
	v_add_u32_e32 v26, s19, v20
	s_and_saveexec_b64 s[2:3], s[0:1]
	s_cbranch_execz .LBB0_923
	v_mov_b32_e32 v27, v21
	v_mul_hi_u32 v12, v22, s20
	v_lshl_add_u64 v[10:11], v[26:27], 1, s[42:43]
	v_lshrrev_b32_e32 v12, 6, v12
	v_and_b32_e32 v22, 0xfffffc, v12
	global_load_dwordx4 v[10:13], v[10:11], off nt
	s_nop 0
	global_load_dword v27, v22, s[40:41] nt
.LBB0_923:
	s_or_b64 exec, exec, s[2:3]
	v_add_u32_e32 v22, s9, v19
	v_cmp_gt_u32_e64 s[4:5], s6, v22
	v_add_u32_e32 v24, s11, v20
	s_and_saveexec_b64 s[2:3], s[4:5]
	s_cbranch_execz .LBB0_925
	v_mov_b32_e32 v25, v21
	v_mul_hi_u32 v8, v22, s20
	v_lshl_add_u64 v[6:7], v[24:25], 1, s[42:43]
	v_lshrrev_b32_e32 v8, 6, v8
	v_and_b32_e32 v22, 0xfffffc, v8
	global_load_dwordx4 v[6:9], v[6:7], off nt
	s_nop 0
	global_load_dword v25, v22, s[40:41] nt
.LBB0_925:
	s_or_b64 exec, exec, s[2:3]
	v_add_u32_e32 v29, s12, v19
	v_cmp_gt_u32_e64 s[2:3], s6, v29
	v_add_u32_e32 v22, s13, v20
	s_and_saveexec_b64 s[24:25], s[2:3]
	s_cbranch_execz .LBB0_927
	v_mul_hi_u32 v4, v29, s20
	v_mov_b32_e32 v23, v21
	v_lshrrev_b32_e32 v4, 6, v4
	v_lshl_add_u64 v[2:3], v[22:23], 1, s[42:43]
	v_and_b32_e32 v23, 0xfffffc, v4
	global_load_dwordx4 v[2:5], v[2:3], off nt
	s_nop 0
	global_load_dword v23, v23, s[40:41] nt

; __global__ void __launch_bounds__(NWAVES * 64, 2) fwd_kernel(Args args) {
;     ...
;         for (int i = bx * NWAVES * 64 + tid; i < D; i += G * NWAVES * 64) cscaled[i] = fmaxf(__uint_as_float(cmaxd[i]), 1e-30f) * (1.0f / 127.0f);
.LBB0_936:
	v_ashrrev_i32_e32 v7, 31, v3
	v_mov_b32_e32 v6, v3
	v_ashrrev_i32_e32 v9, 31, v2
	v_mov_b32_e32 v8, v2
	v_lshlrev_b64 v[6:7], 2, v[6:7]
	v_lshlrev_b64 v[8:9], 2, v[8:9]
	v_lshl_add_u64 v[12:13], s[40:41], 0, v[6:7]
	v_lshl_add_u64 v[10:11], s[40:41], 0, v[8:9]
	global_load_dword v14, v[12:13], off nt
	global_load_dword v15, v[10:11], off nt
	v_add_u32_e32 v5, -2, v5
	v_cmp_eq_u32_e32 vcc, 0, v5
	v_add_u32_e32 v3, s7, v3
	v_add_u32_e32 v2, s6, v2
	v_lshl_add_u64 v[8:9], s[16:17], 0, v[8:9]
	s_or_b64 s[4:5], vcc, s[4:5]
	v_lshl_add_u64 v[6:7], s[16:17], 0, v[6:7]
	s_waitcnt vmcnt(0)
	v_max_f32_e32 v10, v14, v14
	v_max_f32_e32 v12, v15, v15
	v_max_f32_e32 v11, 0xda24260, v10
	v_max_f32_e32 v10, 0xda24260, v12
	v_pk_mul_f32 v[10:11], v[10:11], s[22:23] op_sel_hi:[1,0]
	global_store_dword v[8:9], v10, off
	global_store_dword v[6:7], v11, off
	s_andn2_b64 exec, exec, s[4:5]
	s_cbranch_execnz .LBB0_936
	s_or_b64 exec, exec, s[4:5]
	v_mad_u64_u32 v[18:19], s[4:5], v4, s18, v[18:19]
	v_cmp_ne_u32_e32 vcc, v1, v4
	s_orn2_b64 s[4:5], vcc, exec

; __global__ void __launch_bounds__(NWAVES * 64, 2) fwd_kernel(Args args) {
;     ...
;         for (int i = bx * NWAVES * 64 + tid; i < D; i += G * NWAVES * 64) cscaled[i] = fmaxf(__uint_as_float(cmaxd[i]), 1e-30f) * (1.0f / 127.0f);
.LBB0_940:
	v_add_co_u32_e32 v4, vcc, 0xbb2b0000, v2
	v_add_u32_e32 v18, s18, v18
	s_nop 0
	v_addc_co_u32_e32 v5, vcc, -1, v3, vcc
	global_load_dword v1, v[4:5], off nt
	v_cmp_lt_i32_e32 vcc, s6, v18
	s_or_b64 s[4:5], vcc, s[4:5]
	s_waitcnt vmcnt(0)
	v_max_f32_e32 v1, v1, v1
	v_max_f32_e32 v1, 0xda24260, v1
	v_mul_f32_e32 v1, 0x3c010204, v1
	global_store_dword v[2:3], v1, off
	v_lshl_add_u64 v[2:3], v[2:3], 0, s[0:1]
	s_andn2_b64 exec, exec, s[4:5]
	s_cbranch_execnz .LBB0_940

; __device__ __forceinline__ unsigned cvt_pk_bf16(float lo, float hi) { unsigned r; asm volatile("v_cvt_pk_bf16_f32 %0, %1, %2" : "=v"(r) : "v"(lo), "v"(hi)); return r; }
; __device__ __forceinline__ float bf_lo(unsigned w) { return __uint_as_float(w << 16); }
; __device__ __forceinline__ float bf_hi(unsigned w) { return __uint_as_float(w & 0xffff0000u); }
; __device__ __forceinline__ float xlane1(float t) { return dpp_mov<0xB1, 0xF, true>(0.f, t); }
; __device__ __forceinline__ float xlane2(float t) { return dpp_mov<0x4E, 0xF, true>(0.f, t); }
; __device__ __forceinline__ f32x4 rot64(f32x4 t, const RotSigns sg) {
;     { const float p0 = t.x + t.y, p1 = t.x - t.y, p2 = t.z + t.w, p3 = t.z - t.w; t = (f32x4){p0 + p2, p1 + p3, p0 - p2, p1 - p3}; }
;     t = (f32x4){__builtin_fmaf(sg.s1, t.x, xlane1(t.x)), __builtin_fmaf(sg.s1, t.y, xlane1(t.y)), __builtin_fmaf(sg.s1, t.z, xlane1(t.z)), __builtin_fmaf(sg.s1, t.w, xlane1(t.w))};
;     t = (f32x4){__builtin_fmaf(sg.s2, t.x, xlane2(t.x)), __builtin_fmaf(sg.s2, t.y, xlane2(t.y)), __builtin_fmaf(sg.s2, t.z, xlane2(t.z)), __builtin_fmaf(sg.s2, t.w, xlane2(t.w))};
;     t = (f32x4){__builtin_fmaf(sg.s4, t.x, xlane4(t.x)), __builtin_fmaf(sg.s4, t.y, xlane4(t.y)), __builtin_fmaf(sg.s4, t.z, xlane4(t.z)), __builtin_fmaf(sg.s4, t.w, xlane4(t.w))};
;     t = (f32x4){__builtin_fmaf(sg.s8, t.x, xlane8(t.x)), __builtin_fmaf(sg.s8, t.y, xlane8(t.y)), __builtin_fmaf(sg.s8, t.z, xlane8(t.z)), __builtin_fmaf(sg.s8, t.w, xlane8(t.w))};
;     return t * 0.125f;
; }
; __global__ void __launch_bounds__(NWAVES * 64, 2) fwd_kernel(Args args) {
;     ...
;         for (int slot = vcu; slot < M / 8; slot += G) { const size_t row = (size_t)slot * 8 + wave;
;             const v2u* hp = (const v2u*)(H + row * DFF) + lane; v2u pk[DFF / 256]; float am = 0.f; const RotSigns sg = rot_signs(lane);
; #pragma unroll
;             for (int c = 0; c < DFF / 256; ++c) pk[c] = hp[64 * c];
; #pragma unroll
;             for (int c = 0; c < DFF / 256; ++c) { const f32x4 t = rot64((f32x4){bf_lo(pk[c].x), bf_hi(pk[c].x), bf_lo(pk[c].y), bf_hi(pk[c].y)}, sg);
;                 pk[c].x = cvt_pk_bf16(t.x, t.y); pk[c].y = cvt_pk_bf16(t.z, t.w);
;                 am = fmaxf(fmaxf(am, fmaxf(fabsf(bf_lo(pk[c].x)), fabsf(bf_hi(pk[c].x)))), fmaxf(fabsf(bf_lo(pk[c].y)), fabsf(bf_hi(pk[c].y)))); }
.LBB0_944:
	s_mov_b64 s[26:27], s[78:79]
	v_lshl_add_u64 v[16:17], s[26:27], 0, v[14:15]
	v_add_co_u32_e32 v18, vcc, 0x29000000, v16
	s_nop 1
	v_addc_co_u32_e32 v19, vcc, 0, v17, vcc
	global_load_dwordx2 v[100:101], v[18:19], off nt
	global_load_dwordx2 v[104:105], v[18:19], off offset:512 nt
	global_load_dwordx2 v[96:97], v[18:19], off offset:1024 nt
	global_load_dwordx2 v[94:95], v[18:19], off offset:1536 nt
	global_load_dwordx2 v[92:93], v[18:19], off offset:2048 nt
	global_load_dwordx2 v[90:91], v[18:19], off offset:2560 nt
	global_load_dwordx2 v[88:89], v[18:19], off offset:3072 nt
	global_load_dwordx2 v[86:87], v[18:19], off offset:3584 nt
	v_add_co_u32_e32 v20, vcc, 0x29001000, v16
	s_waitcnt vmcnt(0)
	v_lshlrev_b32_e32 v103, 16, v101
	v_lshlrev_b32_e32 v102, 16, v100
	v_and_b32_e32 v101, 0xffff0000, v101
	v_and_b32_e32 v100, 0xffff0000, v100
	v_pk_add_f32 v[106:107], v[102:103], v[100:101]
	v_pk_add_f32 v[100:101], v[102:103], v[100:101] neg_lo:[0,1] neg_hi:[0,1]
	v_mov_b32_e32 v108, v106
	v_pk_mov_b32 v[102:103], v[106:107], v[100:101] op_sel:[1,0]
	v_mov_b32_e32 v109, v101
	v_mov_b32_e32 v110, v106
	v_mov_b32_e32 v111, v100
	v_mov_b32_e32 v100, v107
	v_pk_add_f32 v[102:103], v[108:109], v[102:103]
	v_pk_add_f32 v[100:101], v[110:111], v[100:101] neg_lo:[0,1] neg_hi:[0,1]
	v_addc_co_u32_e32 v21, vcc, 0, v17, vcc
	v_mov_b32_dpp v108, v102 quad_perm:[1,0,3,2] row_mask:0xf bank_mask:0xf bound_ctrl:1
	v_mov_b32_dpp v109, v103 quad_perm:[1,0,3,2] row_mask:0xf bank_mask:0xf bound_ctrl:1
	v_mov_b32_dpp v106, v100 quad_perm:[1,0,3,2] row_mask:0xf bank_mask:0xf bound_ctrl:1
	v_mov_b32_dpp v107, v101 quad_perm:[1,0,3,2] row_mask:0xf bank_mask:0xf bound_ctrl:1
	v_pk_fma_f32 v[102:103], v[2:3], v[102:103], v[108:109]
	v_pk_fma_f32 v[100:101], v[2:3], v[100:101], v[106:107]
	v_add_co_u32_e32 v18, vcc, 0x29002000, v16
	v_mov_b32_dpp v108, v102 quad_perm:[2,3,0,1] row_mask:0xf bank_mask:0xf bound_ctrl:1
	v_mov_b32_dpp v109, v103 quad_perm:[2,3,0,1] row_mask:0xf bank_mask:0xf bound_ctrl:1
	v_mov_b32_dpp v106, v100 quad_perm:[2,3,0,1] row_mask:0xf bank_mask:0xf bound_ctrl:1
	v_mov_b32_dpp v107, v101 quad_perm:[2,3,0,1] row_mask:0xf bank_mask:0xf bound_ctrl:1
	v_pk_fma_f32 v[102:103], v[4:5], v[102:103], v[108:109]
	v_pk_fma_f32 v[100:101], v[4:5], v[100:101], v[106:107]
	v_addc_co_u32_e32 v19, vcc, 0, v17, vcc
	v_mov_b32_e32 v108, v102
	v_mov_b32_e32 v109, v103
	v_mov_b32_e32 v106, v100
	v_mov_b32_e32 v107, v101
	global_load_dwordx2 v[84:85], v[20:21], off nt
	global_load_dwordx2 v[82:83], v[20:21], off offset:512 nt
	global_load_dwordx2 v[80:81], v[20:21], off offset:1024 nt
	global_load_dwordx2 v[78:79], v[20:21], off offset:1536 nt
	global_load_dwordx2 v[76:77], v[20:21], off offset:2048 nt
	global_load_dwordx2 v[74:75], v[20:21], off offset:2560 nt
	global_load_dwordx2 v[72:73], v[20:21], off offset:3072 nt
	global_load_dwordx2 v[70:71], v[20:21], off offset:3584 nt
	v_add_co_u32_e32 v20, vcc, 0x29003000, v16
	v_mov_b32_dpp v108, v108 row_shl:4 row_mask:0xf bank_mask:0x5
	v_mov_b32_dpp v109, v109 row_shl:4 row_mask:0xf bank_mask:0x5
	v_mov_b32_dpp v106, v106 row_shl:4 row_mask:0xf bank_mask:0x5
	v_mov_b32_dpp v107, v107 row_shl:4 row_mask:0xf bank_mask:0x5
	v_addc_co_u32_e32 v21, vcc, 0, v17, vcc
	v_mov_b32_dpp v108, v102 row_shr:4 row_mask:0xf bank_mask:0xa
	v_mov_b32_dpp v109, v103 row_shr:4 row_mask:0xf bank_mask:0xa
	v_mov_b32_dpp v106, v100 row_shr:4 row_mask:0xf bank_mask:0xa
	v_mov_b32_dpp v107, v101 row_shr:4 row_mask:0xf bank_mask:0xa
	global_load_dwordx2 v[68:69], v[18:19], off nt
	global_load_dwordx2 v[66:67], v[18:19], off offset:512 nt
	global_load_dwordx2 v[64:65], v[18:19], off offset:1024 nt
	global_load_dwordx2 v[62:63], v[18:19], off offset:1536 nt
	global_load_dwordx2 v[60:61], v[18:19], off offset:2048 nt
	global_load_dwordx2 v[58:59], v[18:19], off offset:2560 nt
	global_load_dwordx2 v[56:57], v[18:19], off offset:3072 nt
	global_load_dwordx2 v[54:55], v[18:19], off offset:3584 nt
	v_add_co_u32_e32 v18, vcc, 0x29004000, v16
	v_pk_fma_f32 v[102:103], v[6:7], v[102:103], v[108:109]
	v_pk_fma_f32 v[100:101], v[6:7], v[100:101], v[106:107]
	v_addc_co_u32_e32 v19, vcc, 0, v17, vcc
	v_mov_b32_dpp v108, v102 row_ror:8 row_mask:0xf bank_mask:0xf bound_ctrl:1
	v_mov_b32_dpp v109, v103 row_ror:8 row_mask:0xf bank_mask:0xf bound_ctrl:1
	v_mov_b32_dpp v106, v100 row_ror:8 row_mask:0xf bank_mask:0xf bound_ctrl:1
	v_mov_b32_dpp v107, v101 row_ror:8 row_mask:0xf bank_mask:0xf bound_ctrl:1
	v_add_co_u32_e32 v16, vcc, 0x29005000, v16
	v_pk_fma_f32 v[102:103], v[8:9], v[102:103], v[108:109]
	v_pk_fma_f32 v[100:101], v[10:11], v[100:101], v[106:107]
	v_addc_co_u32_e32 v17, vcc, 0, v17, vcc
	v_pk_mul_f32 v[100:101], v[100:101], s[22:23] op_sel_hi:[1,0]
	v_pk_mul_f32 v[102:103], v[102:103], s[22:23] op_sel_hi:[1,0]
	global_load_dwordx2 v[52:53], v[20:21], off nt
	global_load_dwordx2 v[50:51], v[20:21], off offset:512 nt
	global_load_dwordx2 v[48:49], v[20:21], off offset:1024 nt
	global_load_dwordx2 v[46:47], v[20:21], off offset:1536 nt
	global_load_dwordx2 v[44:45], v[20:21], off offset:2048 nt
	global_load_dwordx2 v[42:43], v[20:21], off offset:2560 nt
	global_load_dwordx2 v[40:41], v[20:21], off offset:3072 nt
	global_load_dwordx2 v[38:39], v[20:21], off offset:3584 nt
	global_load_dwordx2 v[36:37], v[18:19], off nt
	global_load_dwordx2 v[34:35], v[18:19], off offset:512 nt
	global_load_dwordx2 v[32:33], v[18:19], off offset:1024 nt
	global_load_dwordx2 v[30:31], v[18:19], off offset:1536 nt
	global_load_dwordx2 v[28:29], v[18:19], off offset:2048 nt
	global_load_dwordx2 v[26:27], v[18:19], off offset:2560 nt
; __device__ __forceinline__ unsigned cvt_pk_bf16(float lo, float hi) { unsigned r; asm volatile("v_cvt_pk_bf16_f32 %0, %1, %2" : "=v"(r) : "v"(lo), "v"(hi)); return r; }
; __device__ __forceinline__ float bf_lo(unsigned w) { return __uint_as_float(w << 16); }
; __device__ __forceinline__ float bf_hi(unsigned w) { return __uint_as_float(w & 0xffff0000u); }
; __device__ __forceinline__ float xlane1(float t) { return dpp_mov<0xB1, 0xF, true>(0.f, t); }
; __device__ __forceinline__ float xlane2(float t) { return dpp_mov<0x4E, 0xF, true>(0.f, t); }
; __device__ __forceinline__ f32x4 rot64(f32x4 t, const RotSigns sg) {
;     { const float p0 = t.x + t.y, p1 = t.x - t.y, p2 = t.z + t.w, p3 = t.z - t.w; t = (f32x4){p0 + p2, p1 + p3, p0 - p2, p1 - p3}; }
;     t = (f32x4){__builtin_fmaf(sg.s1, t.x, xlane1(t.x)), __builtin_fmaf(sg.s1, t.y, xlane1(t.y)), __builtin_fmaf(sg.s1, t.z, xlane1(t.z)), __builtin_fmaf(sg.s1, t.w, xlane1(t.w))};
;     t = (f32x4){__builtin_fmaf(sg.s2, t.x, xlane2(t.x)), __builtin_fmaf(sg.s2, t.y, xlane2(t.y)), __builtin_fmaf(sg.s2, t.z, xlane2(t.z)), __builtin_fmaf(sg.s2, t.w, xlane2(t.w))};
;     t = (f32x4){__builtin_fmaf(sg.s4, t.x, xlane4(t.x)), __builtin_fmaf(sg.s4, t.y, xlane4(t.y)), __builtin_fmaf(sg.s4, t.z, xlane4(t.z)), __builtin_fmaf(sg.s4, t.w, xlane4(t.w))};
;     t = (f32x4){__builtin_fmaf(sg.s8, t.x, xlane8(t.x)), __builtin_fmaf(sg.s8, t.y, xlane8(t.y)), __builtin_fmaf(sg.s8, t.z, xlane8(t.z)), __builtin_fmaf(sg.s8, t.w, xlane8(t.w))};
;     return t * 0.125f;
; __global__ void __launch_bounds__(NWAVES * 64, 2) fwd_kernel(Args args) {
;     ...
;         for (int slot = vcu; slot < M / 8; slot += G) { const size_t row = (size_t)slot * 8 + wave;
;             const v2u* hp = (const v2u*)(H + row * DFF) + lane; v2u pk[DFF / 256]; float am = 0.f; const RotSigns sg = rot_signs(lane);
; #pragma unroll
;             for (int c = 0; c < DFF / 256; ++c) pk[c] = hp[64 * c];
; #pragma unroll
;             for (int c = 0; c < DFF / 256; ++c) { const f32x4 t = rot64((f32x4){bf_lo(pk[c].x), bf_hi(pk[c].x), bf_lo(pk[c].y), bf_hi(pk[c].y)}, sg);
;                 pk[c].x = cvt_pk_bf16(t.x, t.y); pk[c].y = cvt_pk_bf16(t.z, t.w);
;                 am = fmaxf(fmaxf(am, fmaxf(fabsf(bf_lo(pk[c].x)), fabsf(bf_hi(pk[c].x)))), fmaxf(fabsf(bf_lo(pk[c].y)), fabsf(bf_hi(pk[c].y)))); }
	global_load_dwordx2 v[24:25], v[18:19], off offset:3072 nt
	global_load_dwordx2 v[22:23], v[18:19], off offset:3584 nt
	global_load_dwordx2 v[20:21], v[16:17], off nt
	s_nop 0
	global_load_dwordx2 v[18:19], v[16:17], off offset:512 nt
	s_nop 0
	global_load_dwordx2 v[16:17], v[16:17], off offset:1024 nt
	v_cvt_pk_bf16_f32 v102, v102, v103
	v_cvt_pk_bf16_f32 v103, v100, v101
	s_nop 0
	v_lshlrev_b32_e32 v99, 16, v102
	v_and_b32_e32 v100, 0xffff0000, v102
	v_max_f32_e64 v101, |v100|, |v100|
	v_max_f32_e64 v102, |v99|, |v99|
	v_max_f32_e32 v106, v102, v101
	v_lshlrev_b32_e32 v101, 16, v103
	v_and_b32_e32 v102, 0xffff0000, v103
	v_max_f32_e64 v103, |v102|, |v102|
	v_max_f32_e64 v107, |v101|, |v101|
	v_max_f32_e32 v103, v107, v103
	v_max3_f32 v114, v106, 0, v103
	v_lshlrev_b32_e32 v107, 16, v105
	v_lshlrev_b32_e32 v106, 16, v104
	v_and_b32_e32 v105, 0xffff0000, v105
	v_and_b32_e32 v104, 0xffff0000, v104
	v_pk_add_f32 v[108:109], v[106:107], v[104:105]
	v_pk_add_f32 v[104:105], v[106:107], v[104:105] neg_lo:[0,1] neg_hi:[0,1]
	v_mov_b32_e32 v110, v108
	v_pk_mov_b32 v[106:107], v[108:109], v[104:105] op_sel:[1,0]
	v_mov_b32_e32 v111, v105
	v_mov_b32_e32 v112, v108
	v_mov_b32_e32 v113, v104
	v_mov_b32_e32 v104, v109
	v_pk_add_f32 v[106:107], v[110:111], v[106:107]
	v_pk_add_f32 v[104:105], v[112:113], v[104:105] neg_lo:[0,1] neg_hi:[0,1]
	s_nop 0
	v_mov_b32_dpp v110, v106 quad_perm:[1,0,3,2] row_mask:0xf bank_mask:0xf bound_ctrl:1
	v_mov_b32_dpp v111, v107 quad_perm:[1,0,3,2] row_mask:0xf bank_mask:0xf bound_ctrl:1
	v_mov_b32_dpp v108, v104 quad_perm:[1,0,3,2] row_mask:0xf bank_mask:0xf bound_ctrl:1
	v_mov_b32_dpp v109, v105 quad_perm:[1,0,3,2] row_mask:0xf bank_mask:0xf bound_ctrl:1
	v_pk_fma_f32 v[106:107], v[2:3], v[106:107], v[110:111]
	v_pk_fma_f32 v[104:105], v[2:3], v[104:105], v[108:109]
	s_nop 0
	v_mov_b32_dpp v110, v106 quad_perm:[2,3,0,1] row_mask:0xf bank_mask:0xf bound_ctrl:1
	v_mov_b32_dpp v111, v107 quad_perm:[2,3,0,1] row_mask:0xf bank_mask:0xf bound_ctrl:1
	v_mov_b32_dpp v108, v104 quad_perm:[2,3,0,1] row_mask:0xf bank_mask:0xf bound_ctrl:1
	v_mov_b32_dpp v109, v105 quad_perm:[2,3,0,1] row_mask:0xf bank_mask:0xf bound_ctrl:1
	v_pk_fma_f32 v[106:107], v[4:5], v[106:107], v[110:111]
	v_pk_fma_f32 v[104:105], v[4:5], v[104:105], v[108:109]
	v_mov_b32_e32 v110, v106
	v_mov_b32_e32 v111, v107
	v_mov_b32_e32 v108, v104
	v_mov_b32_e32 v109, v105
	v_mov_b32_dpp v110, v110 row_shl:4 row_mask:0xf bank_mask:0x5
	v_mov_b32_dpp v111, v111 row_shl:4 row_mask:0xf bank_mask:0x5
	v_mov_b32_dpp v108, v108 row_shl:4 row_mask:0xf bank_mask:0x5
	v_mov_b32_dpp v109, v109 row_shl:4 row_mask:0xf bank_mask:0x5
	v_mov_b32_dpp v110, v106 row_shr:4 row_mask:0xf bank_mask:0xa
	v_mov_b32_dpp v111, v107 row_shr:4 row_mask:0xf bank_mask:0xa
	v_mov_b32_dpp v108, v104 row_shr:4 row_mask:0xf bank_mask:0xa
	v_mov_b32_dpp v109, v105 row_shr:4 row_mask:0xf bank_mask:0xa
	v_pk_fma_f32 v[106:107], v[6:7], v[106:107], v[110:111]
	v_pk_fma_f32 v[104:105], v[6:7], v[104:105], v[108:109]
	s_nop 0
	v_mov_b32_dpp v110, v106 row_ror:8 row_mask:0xf bank_mask:0xf bound_ctrl:1
	v_mov_b32_dpp v111, v107 row_ror:8 row_mask:0xf bank_mask:0xf bound_ctrl:1
	v_mov_b32_dpp v108, v104 row_ror:8 row_mask:0xf bank_mask:0xf bound_ctrl:1
	v_mov_b32_dpp v109, v105 row_ror:8 row_mask:0xf bank_mask:0xf bound_ctrl:1
	v_pk_fma_f32 v[106:107], v[8:9], v[106:107], v[110:111]
	v_pk_fma_f32 v[104:105], v[10:11], v[104:105], v[108:109]
	v_pk_mul_f32 v[106:107], v[106:107], s[22:23] op_sel_hi:[1,0]
	v_pk_mul_f32 v[104:105], v[104:105], s[22:23] op_sel_hi:[1,0]
	v_cvt_pk_bf16_f32 v106, v106, v107
	s_nop 0
	v_cvt_pk_bf16_f32 v107, v104, v105
	v_lshlrev_b32_e32 v103, 16, v106
	v_and_b32_e32 v104, 0xffff0000, v106
	v_max_f32_e64 v105, |v104|, |v104|
	v_max_f32_e64 v106, |v103|, |v103|
	v_max_f32_e32 v108, v106, v105
	v_lshlrev_b32_e32 v105, 16, v107
	v_and_b32_e32 v106, 0xffff0000, v107
	v_max_f32_e64 v107, |v106|, |v106|
	v_max_f32_e64 v109, |v105|, |v105|
	v_max_f32_e32 v107, v109, v107
	v_max3_f32 v116, v114, v108, v107
	v_lshlrev_b32_e32 v109, 16, v97
	v_lshlrev_b32_e32 v108, 16, v96
	v_and_b32_e32 v97, 0xffff0000, v97
	v_and_b32_e32 v96, 0xffff0000, v96
	v_pk_add_f32 v[110:111], v[108:109], v[96:97]
	v_pk_add_f32 v[96:97], v[108:109], v[96:97] neg_lo:[0,1] neg_hi:[0,1]
	v_mov_b32_e32 v112, v110
	v_pk_mov_b32 v[108:109], v[110:111], v[96:97] op_sel:[1,0]
	v_mov_b32_e32 v113, v97
	v_mov_b32_e32 v114, v110
	v_mov_b32_e32 v115, v96
	v_mov_b32_e32 v96, v111
	v_pk_add_f32 v[108:109], v[112:113], v[108:109]
	v_pk_add_f32 v[96:97], v[114:115], v[96:97] neg_lo:[0,1] neg_hi:[0,1]
	s_nop 0
	v_mov_b32_dpp v112, v108 quad_perm:[1,0,3,2] row_mask:0xf bank_mask:0xf bound_ctrl:1
	v_mov_b32_dpp v113, v109 quad_perm:[1,0,3,2] row_mask:0xf bank_mask:0xf bound_ctrl:1
	v_mov_b32_dpp v110, v96 quad_perm:[1,0,3,2] row_mask:0xf bank_mask:0xf bound_ctrl:1
	v_mov_b32_dpp v111, v97 quad_perm:[1,0,3,2] row_mask:0xf bank_mask:0xf bound_ctrl:1
	v_pk_fma_f32 v[108:109], v[2:3], v[108:109], v[112:113]
	v_pk_fma_f32 v[96:97], v[2:3], v[96:97], v[110:111]
	s_nop 0
	v_mov_b32_dpp v112, v108 quad_perm:[2,3,0,1] row_mask:0xf bank_mask:0xf bound_ctrl:1
	v_mov_b32_dpp v113, v109 quad_perm:[2,3,0,1] row_mask:0xf bank_mask:0xf bound_ctrl:1
	v_mov_b32_dpp v110, v96 quad_perm:[2,3,0,1] row_mask:0xf bank_mask:0xf bound_ctrl:1
	v_mov_b32_dpp v111, v97 quad_perm:[2,3,0,1] row_mask:0xf bank_mask:0xf bound_ctrl:1
	v_pk_fma_f32 v[108:109], v[4:5], v[108:109], v[112:113]
	v_pk_fma_f32 v[96:97], v[4:5], v[96:97], v[110:111]
	v_mov_b32_e32 v112, v108
	v_mov_b32_e32 v113, v109
	v_mov_b32_e32 v110, v96
	v_mov_b32_e32 v111, v97
; __device__ __forceinline__ unsigned cvt_pk_bf16(float lo, float hi) { unsigned r; asm volatile("v_cvt_pk_bf16_f32 %0, %1, %2" : "=v"(r) : "v"(lo), "v"(hi)); return r; }
; __device__ __forceinline__ float bf_lo(unsigned w) { return __uint_as_float(w << 16); }
; __device__ __forceinline__ float bf_hi(unsigned w) { return __uint_as_float(w & 0xffff0000u); }
; __device__ __forceinline__ float xlane1(float t) { return dpp_mov<0xB1, 0xF, true>(0.f, t); }
; __device__ __forceinline__ float xlane2(float t) { return dpp_mov<0x4E, 0xF, true>(0.f, t); }
; __device__ __forceinline__ float xlane4(float t) { const float r = dpp_mov<0x104, 0x5, false>(t, t); return dpp_mov<0x114, 0xA, false>(r, t); }
; __device__ __forceinline__ float xlane8(float t) { return dpp_mov<0x128, 0xF, true>(0.f, t); }
; __device__ __forceinline__ f32x4 rot64(f32x4 t, const RotSigns sg) {
;     { const float p0 = t.x + t.y, p1 = t.x - t.y, p2 = t.z + t.w, p3 = t.z - t.w; t = (f32x4){p0 + p2, p1 + p3, p0 - p2, p1 - p3}; }
;     t = (f32x4){__builtin_fmaf(sg.s1, t.x, xlane1(t.x)), __builtin_fmaf(sg.s1, t.y, xlane1(t.y)), __builtin_fmaf(sg.s1, t.z, xlane1(t.z)), __builtin_fmaf(sg.s1, t.w, xlane1(t.w))};
;     t = (f32x4){__builtin_fmaf(sg.s2, t.x, xlane2(t.x)), __builtin_fmaf(sg.s2, t.y, xlane2(t.y)), __builtin_fmaf(sg.s2, t.z, xlane2(t.z)), __builtin_fmaf(sg.s2, t.w, xlane2(t.w))};
;     t = (f32x4){__builtin_fmaf(sg.s4, t.x, xlane4(t.x)), __builtin_fmaf(sg.s4, t.y, xlane4(t.y)), __builtin_fmaf(sg.s4, t.z, xlane4(t.z)), __builtin_fmaf(sg.s4, t.w, xlane4(t.w))};
;     t = (f32x4){__builtin_fmaf(sg.s8, t.x, xlane8(t.x)), __builtin_fmaf(sg.s8, t.y, xlane8(t.y)), __builtin_fmaf(sg.s8, t.z, xlane8(t.z)), __builtin_fmaf(sg.s8, t.w, xlane8(t.w))};
;     return t * 0.125f;
; __global__ void __launch_bounds__(NWAVES * 64, 2) fwd_kernel(Args args) {
;     ...
;             for (int c = 0; c < DFF / 256; ++c) { const f32x4 t = rot64((f32x4){bf_lo(pk[c].x), bf_hi(pk[c].x), bf_lo(pk[c].y), bf_hi(pk[c].y)}, sg);
;                 pk[c].x = cvt_pk_bf16(t.x, t.y); pk[c].y = cvt_pk_bf16(t.z, t.w);
;                 am = fmaxf(fmaxf(am, fmaxf(fabsf(bf_lo(pk[c].x)), fabsf(bf_hi(pk[c].x)))), fmaxf(fabsf(bf_lo(pk[c].y)), fabsf(bf_hi(pk[c].y)))); }
	v_mov_b32_dpp v112, v112 row_shl:4 row_mask:0xf bank_mask:0x5
	v_mov_b32_dpp v113, v113 row_shl:4 row_mask:0xf bank_mask:0x5
	v_mov_b32_dpp v110, v110 row_shl:4 row_mask:0xf bank_mask:0x5
	v_mov_b32_dpp v111, v111 row_shl:4 row_mask:0xf bank_mask:0x5
	v_mov_b32_dpp v112, v108 row_shr:4 row_mask:0xf bank_mask:0xa
	v_mov_b32_dpp v113, v109 row_shr:4 row_mask:0xf bank_mask:0xa
	v_mov_b32_dpp v110, v96 row_shr:4 row_mask:0xf bank_mask:0xa
	v_mov_b32_dpp v111, v97 row_shr:4 row_mask:0xf bank_mask:0xa
	v_pk_fma_f32 v[108:109], v[6:7], v[108:109], v[112:113]
	v_pk_fma_f32 v[96:97], v[6:7], v[96:97], v[110:111]
	s_nop 0
	v_mov_b32_dpp v112, v108 row_ror:8 row_mask:0xf bank_mask:0xf bound_ctrl:1
	v_mov_b32_dpp v113, v109 row_ror:8 row_mask:0xf bank_mask:0xf bound_ctrl:1
	v_mov_b32_dpp v110, v96 row_ror:8 row_mask:0xf bank_mask:0xf bound_ctrl:1
	v_mov_b32_dpp v111, v97 row_ror:8 row_mask:0xf bank_mask:0xf bound_ctrl:1
	v_pk_fma_f32 v[108:109], v[8:9], v[108:109], v[112:113]
	v_pk_fma_f32 v[96:97], v[10:11], v[96:97], v[110:111]
	v_pk_mul_f32 v[108:109], v[108:109], s[22:23] op_sel_hi:[1,0]
	v_pk_mul_f32 v[96:97], v[96:97], s[22:23] op_sel_hi:[1,0]
	v_cvt_pk_bf16_f32 v107, v108, v109
	s_nop 0
	v_cvt_pk_bf16_f32 v108, v96, v97
	v_lshlrev_b32_e32 v96, 16, v107
	v_and_b32_e32 v97, 0xffff0000, v107
	v_max_f32_e64 v107, |v97|, |v97|
	v_max_f32_e64 v109, |v96|, |v96|
	v_max_f32_e32 v109, v109, v107
	v_lshlrev_b32_e32 v107, 16, v108
	v_and_b32_e32 v108, 0xffff0000, v108
	v_max_f32_e64 v110, |v108|, |v108|
	v_max_f32_e64 v111, |v107|, |v107|
	v_max_f32_e32 v110, v111, v110
	v_max3_f32 v118, v116, v109, v110
	v_lshlrev_b32_e32 v111, 16, v95
	v_lshlrev_b32_e32 v110, 16, v94
	v_and_b32_e32 v95, 0xffff0000, v95
	v_and_b32_e32 v94, 0xffff0000, v94
	v_pk_add_f32 v[112:113], v[110:111], v[94:95]
	v_pk_add_f32 v[94:95], v[110:111], v[94:95] neg_lo:[0,1] neg_hi:[0,1]
	v_mov_b32_e32 v114, v112
	v_pk_mov_b32 v[110:111], v[112:113], v[94:95] op_sel:[1,0]
	v_mov_b32_e32 v115, v95
	v_mov_b32_e32 v116, v112
	v_mov_b32_e32 v117, v94
	v_mov_b32_e32 v94, v113
	v_pk_add_f32 v[110:111], v[114:115], v[110:111]
	v_pk_add_f32 v[94:95], v[116:117], v[94:95] neg_lo:[0,1] neg_hi:[0,1]
	s_nop 0
	v_mov_b32_dpp v114, v110 quad_perm:[1,0,3,2] row_mask:0xf bank_mask:0xf bound_ctrl:1
	v_mov_b32_dpp v115, v111 quad_perm:[1,0,3,2] row_mask:0xf bank_mask:0xf bound_ctrl:1
	v_mov_b32_dpp v112, v94 quad_perm:[1,0,3,2] row_mask:0xf bank_mask:0xf bound_ctrl:1
	v_mov_b32_dpp v113, v95 quad_perm:[1,0,3,2] row_mask:0xf bank_mask:0xf bound_ctrl:1
	v_pk_fma_f32 v[110:111], v[2:3], v[110:111], v[114:115]
	v_pk_fma_f32 v[94:95], v[2:3], v[94:95], v[112:113]
	s_nop 0
	v_mov_b32_dpp v114, v110 quad_perm:[2,3,0,1] row_mask:0xf bank_mask:0xf bound_ctrl:1
	v_mov_b32_dpp v115, v111 quad_perm:[2,3,0,1] row_mask:0xf bank_mask:0xf bound_ctrl:1
	v_mov_b32_dpp v112, v94 quad_perm:[2,3,0,1] row_mask:0xf bank_mask:0xf bound_ctrl:1
	v_mov_b32_dpp v113, v95 quad_perm:[2,3,0,1] row_mask:0xf bank_mask:0xf bound_ctrl:1
	v_pk_fma_f32 v[110:111], v[4:5], v[110:111], v[114:115]
	v_pk_fma_f32 v[94:95], v[4:5], v[94:95], v[112:113]
	v_mov_b32_e32 v114, v110
	v_mov_b32_e32 v115, v111
	v_mov_b32_e32 v112, v94
	v_mov_b32_e32 v113, v95
	v_mov_b32_dpp v114, v114 row_shl:4 row_mask:0xf bank_mask:0x5
	v_mov_b32_dpp v115, v115 row_shl:4 row_mask:0xf bank_mask:0x5
	v_mov_b32_dpp v112, v112 row_shl:4 row_mask:0xf bank_mask:0x5
	v_mov_b32_dpp v113, v113 row_shl:4 row_mask:0xf bank_mask:0x5
	v_mov_b32_dpp v114, v110 row_shr:4 row_mask:0xf bank_mask:0xa
	v_mov_b32_dpp v115, v111 row_shr:4 row_mask:0xf bank_mask:0xa
	v_mov_b32_dpp v112, v94 row_shr:4 row_mask:0xf bank_mask:0xa
	v_mov_b32_dpp v113, v95 row_shr:4 row_mask:0xf bank_mask:0xa
	v_pk_fma_f32 v[110:111], v[6:7], v[110:111], v[114:115]
	v_pk_fma_f32 v[94:95], v[6:7], v[94:95], v[112:113]
	s_nop 0
	v_mov_b32_dpp v114, v110 row_ror:8 row_mask:0xf bank_mask:0xf bound_ctrl:1
	v_mov_b32_dpp v115, v111 row_ror:8 row_mask:0xf bank_mask:0xf bound_ctrl:1
	v_mov_b32_dpp v112, v94 row_ror:8 row_mask:0xf bank_mask:0xf bound_ctrl:1
	v_mov_b32_dpp v113, v95 row_ror:8 row_mask:0xf bank_mask:0xf bound_ctrl:1
	v_pk_fma_f32 v[110:111], v[8:9], v[110:111], v[114:115]
	v_pk_fma_f32 v[94:95], v[10:11], v[94:95], v[112:113]
	v_pk_mul_f32 v[110:111], v[110:111], s[22:23] op_sel_hi:[1,0]
	v_pk_mul_f32 v[94:95], v[94:95], s[22:23] op_sel_hi:[1,0]
	v_cvt_pk_bf16_f32 v109, v110, v111
	s_nop 0
	v_cvt_pk_bf16_f32 v110, v94, v95
	v_lshlrev_b32_e32 v94, 16, v109
	v_and_b32_e32 v95, 0xffff0000, v109
	v_max_f32_e64 v109, |v95|, |v95|
	v_max_f32_e64 v111, |v94|, |v94|
	v_max_f32_e32 v111, v111, v109
	v_lshlrev_b32_e32 v109, 16, v110
	v_and_b32_e32 v110, 0xffff0000, v110
	v_max_f32_e64 v112, |v110|, |v110|
	v_max_f32_e64 v113, |v109|, |v109|
	v_max_f32_e32 v112, v113, v112
	v_max3_f32 v120, v118, v111, v112
	v_lshlrev_b32_e32 v113, 16, v93
	v_lshlrev_b32_e32 v112, 16, v92
	v_and_b32_e32 v93, 0xffff0000, v93
	v_and_b32_e32 v92, 0xffff0000, v92
	v_pk_add_f32 v[114:115], v[112:113], v[92:93]
	v_pk_add_f32 v[92:93], v[112:113], v[92:93] neg_lo:[0,1] neg_hi:[0,1]
	v_mov_b32_e32 v116, v114
	v_pk_mov_b32 v[112:113], v[114:115], v[92:93] op_sel:[1,0]
	v_mov_b32_e32 v117, v93
	v_mov_b32_e32 v118, v114
	v_mov_b32_e32 v119, v92
	v_mov_b32_e32 v92, v115
	v_pk_add_f32 v[112:113], v[116:117], v[112:113]
	v_pk_add_f32 v[92:93], v[118:119], v[92:93] neg_lo:[0,1] neg_hi:[0,1]
	s_nop 0
	v_mov_b32_dpp v116, v112 quad_perm:[1,0,3,2] row_mask:0xf bank_mask:0xf bound_ctrl:1
	v_mov_b32_dpp v117, v113 quad_perm:[1,0,3,2] row_mask:0xf bank_mask:0xf bound_ctrl:1
	v_mov_b32_dpp v114, v92 quad_perm:[1,0,3,2] row_mask:0xf bank_mask:0xf bound_ctrl:1
; __device__ __forceinline__ unsigned cvt_pk_bf16(float lo, float hi) { unsigned r; asm volatile("v_cvt_pk_bf16_f32 %0, %1, %2" : "=v"(r) : "v"(lo), "v"(hi)); return r; }
; __device__ __forceinline__ float bf_lo(unsigned w) { return __uint_as_float(w << 16); }
; __device__ __forceinline__ float bf_hi(unsigned w) { return __uint_as_float(w & 0xffff0000u); }
; __device__ __forceinline__ float xlane1(float t) { return dpp_mov<0xB1, 0xF, true>(0.f, t); }
; __device__ __forceinline__ float xlane2(float t) { return dpp_mov<0x4E, 0xF, true>(0.f, t); }
; __device__ __forceinline__ float xlane4(float t) { const float r = dpp_mov<0x104, 0x5, false>(t, t); return dpp_mov<0x114, 0xA, false>(r, t); }
; __device__ __forceinline__ float xlane8(float t) { return dpp_mov<0x128, 0xF, true>(0.f, t); }
; __device__ __forceinline__ f32x4 rot64(f32x4 t, const RotSigns sg) {
;     { const float p0 = t.x + t.y, p1 = t.x - t.y, p2 = t.z + t.w, p3 = t.z - t.w; t = (f32x4){p0 + p2, p1 + p3, p0 - p2, p1 - p3}; }
;     t = (f32x4){__builtin_fmaf(sg.s1, t.x, xlane1(t.x)), __builtin_fmaf(sg.s1, t.y, xlane1(t.y)), __builtin_fmaf(sg.s1, t.z, xlane1(t.z)), __builtin_fmaf(sg.s1, t.w, xlane1(t.w))};
;     t = (f32x4){__builtin_fmaf(sg.s2, t.x, xlane2(t.x)), __builtin_fmaf(sg.s2, t.y, xlane2(t.y)), __builtin_fmaf(sg.s2, t.z, xlane2(t.z)), __builtin_fmaf(sg.s2, t.w, xlane2(t.w))};
;     t = (f32x4){__builtin_fmaf(sg.s4, t.x, xlane4(t.x)), __builtin_fmaf(sg.s4, t.y, xlane4(t.y)), __builtin_fmaf(sg.s4, t.z, xlane4(t.z)), __builtin_fmaf(sg.s4, t.w, xlane4(t.w))};
;     t = (f32x4){__builtin_fmaf(sg.s8, t.x, xlane8(t.x)), __builtin_fmaf(sg.s8, t.y, xlane8(t.y)), __builtin_fmaf(sg.s8, t.z, xlane8(t.z)), __builtin_fmaf(sg.s8, t.w, xlane8(t.w))};
;     return t * 0.125f;
; __global__ void __launch_bounds__(NWAVES * 64, 2) fwd_kernel(Args args) {
;     ...
;             for (int c = 0; c < DFF / 256; ++c) { const f32x4 t = rot64((f32x4){bf_lo(pk[c].x), bf_hi(pk[c].x), bf_lo(pk[c].y), bf_hi(pk[c].y)}, sg);
;                 pk[c].x = cvt_pk_bf16(t.x, t.y); pk[c].y = cvt_pk_bf16(t.z, t.w);
;                 am = fmaxf(fmaxf(am, fmaxf(fabsf(bf_lo(pk[c].x)), fabsf(bf_hi(pk[c].x)))), fmaxf(fabsf(bf_lo(pk[c].y)), fabsf(bf_hi(pk[c].y)))); }
	v_mov_b32_dpp v115, v93 quad_perm:[1,0,3,2] row_mask:0xf bank_mask:0xf bound_ctrl:1
	v_pk_fma_f32 v[112:113], v[2:3], v[112:113], v[116:117]
	v_pk_fma_f32 v[92:93], v[2:3], v[92:93], v[114:115]
	s_nop 0
	v_mov_b32_dpp v116, v112 quad_perm:[2,3,0,1] row_mask:0xf bank_mask:0xf bound_ctrl:1
	v_mov_b32_dpp v117, v113 quad_perm:[2,3,0,1] row_mask:0xf bank_mask:0xf bound_ctrl:1
	v_mov_b32_dpp v114, v92 quad_perm:[2,3,0,1] row_mask:0xf bank_mask:0xf bound_ctrl:1
	v_mov_b32_dpp v115, v93 quad_perm:[2,3,0,1] row_mask:0xf bank_mask:0xf bound_ctrl:1
	v_pk_fma_f32 v[112:113], v[4:5], v[112:113], v[116:117]
	v_pk_fma_f32 v[92:93], v[4:5], v[92:93], v[114:115]
	v_mov_b32_e32 v116, v112
	v_mov_b32_e32 v117, v113
	v_mov_b32_e32 v114, v92
	v_mov_b32_e32 v115, v93
	v_mov_b32_dpp v116, v116 row_shl:4 row_mask:0xf bank_mask:0x5
	v_mov_b32_dpp v117, v117 row_shl:4 row_mask:0xf bank_mask:0x5
	v_mov_b32_dpp v114, v114 row_shl:4 row_mask:0xf bank_mask:0x5
	v_mov_b32_dpp v115, v115 row_shl:4 row_mask:0xf bank_mask:0x5
	v_mov_b32_dpp v116, v112 row_shr:4 row_mask:0xf bank_mask:0xa
	v_mov_b32_dpp v117, v113 row_shr:4 row_mask:0xf bank_mask:0xa
	v_mov_b32_dpp v114, v92 row_shr:4 row_mask:0xf bank_mask:0xa
	v_mov_b32_dpp v115, v93 row_shr:4 row_mask:0xf bank_mask:0xa
	v_pk_fma_f32 v[112:113], v[6:7], v[112:113], v[116:117]
	v_pk_fma_f32 v[92:93], v[6:7], v[92:93], v[114:115]
	s_nop 0
	v_mov_b32_dpp v116, v112 row_ror:8 row_mask:0xf bank_mask:0xf bound_ctrl:1
	v_mov_b32_dpp v117, v113 row_ror:8 row_mask:0xf bank_mask:0xf bound_ctrl:1
	v_mov_b32_dpp v114, v92 row_ror:8 row_mask:0xf bank_mask:0xf bound_ctrl:1
	v_mov_b32_dpp v115, v93 row_ror:8 row_mask:0xf bank_mask:0xf bound_ctrl:1
	v_pk_fma_f32 v[112:113], v[8:9], v[112:113], v[116:117]
	v_pk_fma_f32 v[92:93], v[10:11], v[92:93], v[114:115]
	v_pk_mul_f32 v[112:113], v[112:113], s[22:23] op_sel_hi:[1,0]
	v_pk_mul_f32 v[92:93], v[92:93], s[22:23] op_sel_hi:[1,0]
	v_cvt_pk_bf16_f32 v111, v112, v113
	s_nop 0
	v_cvt_pk_bf16_f32 v112, v92, v93
	v_lshlrev_b32_e32 v92, 16, v111
	v_and_b32_e32 v93, 0xffff0000, v111
	v_max_f32_e64 v111, |v93|, |v93|
	v_max_f32_e64 v113, |v92|, |v92|
	v_max_f32_e32 v113, v113, v111
	v_lshlrev_b32_e32 v111, 16, v112
	v_and_b32_e32 v112, 0xffff0000, v112
	v_max_f32_e64 v114, |v112|, |v112|
	v_max_f32_e64 v115, |v111|, |v111|
	v_max_f32_e32 v114, v115, v114
	v_max3_f32 v122, v120, v113, v114
	v_lshlrev_b32_e32 v115, 16, v91
	v_lshlrev_b32_e32 v114, 16, v90
	v_and_b32_e32 v91, 0xffff0000, v91
	v_and_b32_e32 v90, 0xffff0000, v90
	v_pk_add_f32 v[116:117], v[114:115], v[90:91]
	v_pk_add_f32 v[90:91], v[114:115], v[90:91] neg_lo:[0,1] neg_hi:[0,1]
	v_mov_b32_e32 v118, v116
	v_pk_mov_b32 v[114:115], v[116:117], v[90:91] op_sel:[1,0]
	v_mov_b32_e32 v119, v91
	v_mov_b32_e32 v120, v116
	v_mov_b32_e32 v121, v90
	v_mov_b32_e32 v90, v117
	v_pk_add_f32 v[114:115], v[118:119], v[114:115]
	v_pk_add_f32 v[90:91], v[120:121], v[90:91] neg_lo:[0,1] neg_hi:[0,1]
	s_nop 0
	v_mov_b32_dpp v118, v114 quad_perm:[1,0,3,2] row_mask:0xf bank_mask:0xf bound_ctrl:1
	v_mov_b32_dpp v119, v115 quad_perm:[1,0,3,2] row_mask:0xf bank_mask:0xf bound_ctrl:1
	v_mov_b32_dpp v116, v90 quad_perm:[1,0,3,2] row_mask:0xf bank_mask:0xf bound_ctrl:1
	v_mov_b32_dpp v117, v91 quad_perm:[1,0,3,2] row_mask:0xf bank_mask:0xf bound_ctrl:1
	v_pk_fma_f32 v[114:115], v[2:3], v[114:115], v[118:119]
	v_pk_fma_f32 v[90:91], v[2:3], v[90:91], v[116:117]
	s_nop 0
	v_mov_b32_dpp v118, v114 quad_perm:[2,3,0,1] row_mask:0xf bank_mask:0xf bound_ctrl:1
	v_mov_b32_dpp v119, v115 quad_perm:[2,3,0,1] row_mask:0xf bank_mask:0xf bound_ctrl:1
	v_mov_b32_dpp v116, v90 quad_perm:[2,3,0,1] row_mask:0xf bank_mask:0xf bound_ctrl:1
	v_mov_b32_dpp v117, v91 quad_perm:[2,3,0,1] row_mask:0xf bank_mask:0xf bound_ctrl:1
	v_pk_fma_f32 v[114:115], v[4:5], v[114:115], v[118:119]
	v_pk_fma_f32 v[90:91], v[4:5], v[90:91], v[116:117]
	v_mov_b32_e32 v118, v114
	v_mov_b32_e32 v119, v115
	v_mov_b32_e32 v116, v90
	v_mov_b32_e32 v117, v91
	v_mov_b32_dpp v118, v118 row_shl:4 row_mask:0xf bank_mask:0x5
	v_mov_b32_dpp v119, v119 row_shl:4 row_mask:0xf bank_mask:0x5
	v_mov_b32_dpp v116, v116 row_shl:4 row_mask:0xf bank_mask:0x5
	v_mov_b32_dpp v117, v117 row_shl:4 row_mask:0xf bank_mask:0x5
	v_mov_b32_dpp v118, v114 row_shr:4 row_mask:0xf bank_mask:0xa
	v_mov_b32_dpp v119, v115 row_shr:4 row_mask:0xf bank_mask:0xa
	v_mov_b32_dpp v116, v90 row_shr:4 row_mask:0xf bank_mask:0xa
	v_mov_b32_dpp v117, v91 row_shr:4 row_mask:0xf bank_mask:0xa
	v_pk_fma_f32 v[114:115], v[6:7], v[114:115], v[118:119]
	v_pk_fma_f32 v[90:91], v[6:7], v[90:91], v[116:117]
	s_nop 0
	v_mov_b32_dpp v118, v114 row_ror:8 row_mask:0xf bank_mask:0xf bound_ctrl:1
	v_mov_b32_dpp v119, v115 row_ror:8 row_mask:0xf bank_mask:0xf bound_ctrl:1
	v_mov_b32_dpp v116, v90 row_ror:8 row_mask:0xf bank_mask:0xf bound_ctrl:1
	v_mov_b32_dpp v117, v91 row_ror:8 row_mask:0xf bank_mask:0xf bound_ctrl:1
	v_pk_fma_f32 v[114:115], v[8:9], v[114:115], v[118:119]
	v_pk_fma_f32 v[90:91], v[10:11], v[90:91], v[116:117]
	v_pk_mul_f32 v[114:115], v[114:115], s[22:23] op_sel_hi:[1,0]
	v_pk_mul_f32 v[90:91], v[90:91], s[22:23] op_sel_hi:[1,0]
	v_cvt_pk_bf16_f32 v113, v114, v115
	s_nop 0
	v_cvt_pk_bf16_f32 v114, v90, v91
	v_lshlrev_b32_e32 v90, 16, v113
	v_and_b32_e32 v91, 0xffff0000, v113
	v_max_f32_e64 v113, |v91|, |v91|
	v_max_f32_e64 v115, |v90|, |v90|
	v_max_f32_e32 v115, v115, v113
	v_lshlrev_b32_e32 v113, 16, v114
	v_and_b32_e32 v114, 0xffff0000, v114
	v_max_f32_e64 v116, |v114|, |v114|
	v_max_f32_e64 v117, |v113|, |v113|
	v_max_f32_e32 v116, v117, v116
	v_max3_f32 v124, v122, v115, v116
	v_lshlrev_b32_e32 v117, 16, v89
	v_lshlrev_b32_e32 v116, 16, v88
; __device__ __forceinline__ unsigned cvt_pk_bf16(float lo, float hi) { unsigned r; asm volatile("v_cvt_pk_bf16_f32 %0, %1, %2" : "=v"(r) : "v"(lo), "v"(hi)); return r; }
; __device__ __forceinline__ float bf_lo(unsigned w) { return __uint_as_float(w << 16); }
; __device__ __forceinline__ float bf_hi(unsigned w) { return __uint_as_float(w & 0xffff0000u); }
; __device__ __forceinline__ float xlane1(float t) { return dpp_mov<0xB1, 0xF, true>(0.f, t); }
; __device__ __forceinline__ float xlane2(float t) { return dpp_mov<0x4E, 0xF, true>(0.f, t); }
; __device__ __forceinline__ float xlane4(float t) { const float r = dpp_mov<0x104, 0x5, false>(t, t); return dpp_mov<0x114, 0xA, false>(r, t); }
; __device__ __forceinline__ float xlane8(float t) { return dpp_mov<0x128, 0xF, true>(0.f, t); }
; __device__ __forceinline__ f32x4 rot64(f32x4 t, const RotSigns sg) {
;     { const float p0 = t.x + t.y, p1 = t.x - t.y, p2 = t.z + t.w, p3 = t.z - t.w; t = (f32x4){p0 + p2, p1 + p3, p0 - p2, p1 - p3}; }
;     t = (f32x4){__builtin_fmaf(sg.s1, t.x, xlane1(t.x)), __builtin_fmaf(sg.s1, t.y, xlane1(t.y)), __builtin_fmaf(sg.s1, t.z, xlane1(t.z)), __builtin_fmaf(sg.s1, t.w, xlane1(t.w))};
;     t = (f32x4){__builtin_fmaf(sg.s2, t.x, xlane2(t.x)), __builtin_fmaf(sg.s2, t.y, xlane2(t.y)), __builtin_fmaf(sg.s2, t.z, xlane2(t.z)), __builtin_fmaf(sg.s2, t.w, xlane2(t.w))};
;     t = (f32x4){__builtin_fmaf(sg.s4, t.x, xlane4(t.x)), __builtin_fmaf(sg.s4, t.y, xlane4(t.y)), __builtin_fmaf(sg.s4, t.z, xlane4(t.z)), __builtin_fmaf(sg.s4, t.w, xlane4(t.w))};
;     t = (f32x4){__builtin_fmaf(sg.s8, t.x, xlane8(t.x)), __builtin_fmaf(sg.s8, t.y, xlane8(t.y)), __builtin_fmaf(sg.s8, t.z, xlane8(t.z)), __builtin_fmaf(sg.s8, t.w, xlane8(t.w))};
;     return t * 0.125f;
; __global__ void __launch_bounds__(NWAVES * 64, 2) fwd_kernel(Args args) {
;     ...
;             for (int c = 0; c < DFF / 256; ++c) { const f32x4 t = rot64((f32x4){bf_lo(pk[c].x), bf_hi(pk[c].x), bf_lo(pk[c].y), bf_hi(pk[c].y)}, sg);
;                 pk[c].x = cvt_pk_bf16(t.x, t.y); pk[c].y = cvt_pk_bf16(t.z, t.w);
;                 am = fmaxf(fmaxf(am, fmaxf(fabsf(bf_lo(pk[c].x)), fabsf(bf_hi(pk[c].x)))), fmaxf(fabsf(bf_lo(pk[c].y)), fabsf(bf_hi(pk[c].y)))); }
	v_and_b32_e32 v89, 0xffff0000, v89
	v_and_b32_e32 v88, 0xffff0000, v88
	v_pk_add_f32 v[118:119], v[116:117], v[88:89]
	v_pk_add_f32 v[88:89], v[116:117], v[88:89] neg_lo:[0,1] neg_hi:[0,1]
	v_mov_b32_e32 v120, v118
	v_pk_mov_b32 v[116:117], v[118:119], v[88:89] op_sel:[1,0]
	v_mov_b32_e32 v121, v89
	v_mov_b32_e32 v122, v118
	v_mov_b32_e32 v123, v88
	v_mov_b32_e32 v88, v119
	v_pk_add_f32 v[116:117], v[120:121], v[116:117]
	v_pk_add_f32 v[88:89], v[122:123], v[88:89] neg_lo:[0,1] neg_hi:[0,1]
	s_nop 0
	v_mov_b32_dpp v120, v116 quad_perm:[1,0,3,2] row_mask:0xf bank_mask:0xf bound_ctrl:1
	v_mov_b32_dpp v121, v117 quad_perm:[1,0,3,2] row_mask:0xf bank_mask:0xf bound_ctrl:1
	v_mov_b32_dpp v118, v88 quad_perm:[1,0,3,2] row_mask:0xf bank_mask:0xf bound_ctrl:1
	v_mov_b32_dpp v119, v89 quad_perm:[1,0,3,2] row_mask:0xf bank_mask:0xf bound_ctrl:1
	v_pk_fma_f32 v[116:117], v[2:3], v[116:117], v[120:121]
	v_pk_fma_f32 v[88:89], v[2:3], v[88:89], v[118:119]
	s_nop 0
	v_mov_b32_dpp v120, v116 quad_perm:[2,3,0,1] row_mask:0xf bank_mask:0xf bound_ctrl:1
	v_mov_b32_dpp v121, v117 quad_perm:[2,3,0,1] row_mask:0xf bank_mask:0xf bound_ctrl:1
	v_mov_b32_dpp v118, v88 quad_perm:[2,3,0,1] row_mask:0xf bank_mask:0xf bound_ctrl:1
	v_mov_b32_dpp v119, v89 quad_perm:[2,3,0,1] row_mask:0xf bank_mask:0xf bound_ctrl:1
	v_pk_fma_f32 v[116:117], v[4:5], v[116:117], v[120:121]
	v_pk_fma_f32 v[88:89], v[4:5], v[88:89], v[118:119]
	v_mov_b32_e32 v120, v116
	v_mov_b32_e32 v121, v117
	v_mov_b32_e32 v118, v88
	v_mov_b32_e32 v119, v89
	v_mov_b32_dpp v120, v120 row_shl:4 row_mask:0xf bank_mask:0x5
	v_mov_b32_dpp v121, v121 row_shl:4 row_mask:0xf bank_mask:0x5
	v_mov_b32_dpp v118, v118 row_shl:4 row_mask:0xf bank_mask:0x5
	v_mov_b32_dpp v119, v119 row_shl:4 row_mask:0xf bank_mask:0x5
	v_mov_b32_dpp v120, v116 row_shr:4 row_mask:0xf bank_mask:0xa
	v_mov_b32_dpp v121, v117 row_shr:4 row_mask:0xf bank_mask:0xa
	v_mov_b32_dpp v118, v88 row_shr:4 row_mask:0xf bank_mask:0xa
	v_mov_b32_dpp v119, v89 row_shr:4 row_mask:0xf bank_mask:0xa
	v_pk_fma_f32 v[116:117], v[6:7], v[116:117], v[120:121]
	v_pk_fma_f32 v[88:89], v[6:7], v[88:89], v[118:119]
	s_nop 0
	v_mov_b32_dpp v120, v116 row_ror:8 row_mask:0xf bank_mask:0xf bound_ctrl:1
	v_mov_b32_dpp v121, v117 row_ror:8 row_mask:0xf bank_mask:0xf bound_ctrl:1
	v_mov_b32_dpp v118, v88 row_ror:8 row_mask:0xf bank_mask:0xf bound_ctrl:1
	v_mov_b32_dpp v119, v89 row_ror:8 row_mask:0xf bank_mask:0xf bound_ctrl:1
	v_pk_fma_f32 v[116:117], v[8:9], v[116:117], v[120:121]
	v_pk_fma_f32 v[88:89], v[10:11], v[88:89], v[118:119]
	v_pk_mul_f32 v[116:117], v[116:117], s[22:23] op_sel_hi:[1,0]
	v_pk_mul_f32 v[88:89], v[88:89], s[22:23] op_sel_hi:[1,0]
	v_cvt_pk_bf16_f32 v115, v116, v117
	s_nop 0
	v_cvt_pk_bf16_f32 v116, v88, v89
	v_lshlrev_b32_e32 v88, 16, v115
	v_and_b32_e32 v89, 0xffff0000, v115
	v_max_f32_e64 v115, |v89|, |v89|
	v_max_f32_e64 v117, |v88|, |v88|
	v_max_f32_e32 v117, v117, v115
	v_lshlrev_b32_e32 v115, 16, v116
	v_and_b32_e32 v116, 0xffff0000, v116
	v_max_f32_e64 v118, |v116|, |v116|
	v_max_f32_e64 v119, |v115|, |v115|
	v_max_f32_e32 v118, v119, v118
	v_max3_f32 v126, v124, v117, v118
	v_lshlrev_b32_e32 v119, 16, v87
	v_lshlrev_b32_e32 v118, 16, v86
	v_and_b32_e32 v87, 0xffff0000, v87
	v_and_b32_e32 v86, 0xffff0000, v86
	v_pk_add_f32 v[120:121], v[118:119], v[86:87]
	v_pk_add_f32 v[86:87], v[118:119], v[86:87] neg_lo:[0,1] neg_hi:[0,1]
	v_mov_b32_e32 v122, v120
	v_pk_mov_b32 v[118:119], v[120:121], v[86:87] op_sel:[1,0]
	v_mov_b32_e32 v123, v87
	v_mov_b32_e32 v124, v120
	v_mov_b32_e32 v125, v86
	v_mov_b32_e32 v86, v121
	v_pk_add_f32 v[118:119], v[122:123], v[118:119]
	v_pk_add_f32 v[86:87], v[124:125], v[86:87] neg_lo:[0,1] neg_hi:[0,1]
	s_nop 0
	v_mov_b32_dpp v122, v118 quad_perm:[1,0,3,2] row_mask:0xf bank_mask:0xf bound_ctrl:1
	v_mov_b32_dpp v123, v119 quad_perm:[1,0,3,2] row_mask:0xf bank_mask:0xf bound_ctrl:1
	v_mov_b32_dpp v120, v86 quad_perm:[1,0,3,2] row_mask:0xf bank_mask:0xf bound_ctrl:1
	v_mov_b32_dpp v121, v87 quad_perm:[1,0,3,2] row_mask:0xf bank_mask:0xf bound_ctrl:1
	v_pk_fma_f32 v[118:119], v[2:3], v[118:119], v[122:123]
	v_pk_fma_f32 v[86:87], v[2:3], v[86:87], v[120:121]
	s_nop 0
	v_mov_b32_dpp v122, v118 quad_perm:[2,3,0,1] row_mask:0xf bank_mask:0xf bound_ctrl:1
	v_mov_b32_dpp v123, v119 quad_perm:[2,3,0,1] row_mask:0xf bank_mask:0xf bound_ctrl:1
	v_mov_b32_dpp v120, v86 quad_perm:[2,3,0,1] row_mask:0xf bank_mask:0xf bound_ctrl:1
	v_mov_b32_dpp v121, v87 quad_perm:[2,3,0,1] row_mask:0xf bank_mask:0xf bound_ctrl:1
	v_pk_fma_f32 v[118:119], v[4:5], v[118:119], v[122:123]
	v_pk_fma_f32 v[86:87], v[4:5], v[86:87], v[120:121]
	v_mov_b32_e32 v122, v118
	v_mov_b32_e32 v123, v119
	v_mov_b32_e32 v120, v86
	v_mov_b32_e32 v121, v87
	v_mov_b32_dpp v122, v122 row_shl:4 row_mask:0xf bank_mask:0x5
	v_mov_b32_dpp v123, v123 row_shl:4 row_mask:0xf bank_mask:0x5
	v_mov_b32_dpp v120, v120 row_shl:4 row_mask:0xf bank_mask:0x5
	v_mov_b32_dpp v121, v121 row_shl:4 row_mask:0xf bank_mask:0x5
	v_mov_b32_dpp v122, v118 row_shr:4 row_mask:0xf bank_mask:0xa
	v_mov_b32_dpp v123, v119 row_shr:4 row_mask:0xf bank_mask:0xa
	v_mov_b32_dpp v120, v86 row_shr:4 row_mask:0xf bank_mask:0xa
	v_mov_b32_dpp v121, v87 row_shr:4 row_mask:0xf bank_mask:0xa
	v_pk_fma_f32 v[118:119], v[6:7], v[118:119], v[122:123]
	v_pk_fma_f32 v[86:87], v[6:7], v[86:87], v[120:121]
	s_nop 0
	v_mov_b32_dpp v122, v118 row_ror:8 row_mask:0xf bank_mask:0xf bound_ctrl:1
	v_mov_b32_dpp v123, v119 row_ror:8 row_mask:0xf bank_mask:0xf bound_ctrl:1
	v_mov_b32_dpp v120, v86 row_ror:8 row_mask:0xf bank_mask:0xf bound_ctrl:1
	v_mov_b32_dpp v121, v87 row_ror:8 row_mask:0xf bank_mask:0xf bound_ctrl:1
	v_pk_fma_f32 v[118:119], v[8:9], v[118:119], v[122:123]
	v_pk_fma_f32 v[86:87], v[10:11], v[86:87], v[120:121]
	v_pk_mul_f32 v[118:119], v[118:119], s[22:23] op_sel_hi:[1,0]
	v_pk_mul_f32 v[86:87], v[86:87], s[22:23] op_sel_hi:[1,0]
	v_cvt_pk_bf16_f32 v117, v118, v119
	s_nop 0
	v_cvt_pk_bf16_f32 v118, v86, v87
	v_lshlrev_b32_e32 v86, 16, v117
	v_and_b32_e32 v87, 0xffff0000, v117
	v_max_f32_e64 v117, |v87|, |v87|
	v_max_f32_e64 v119, |v86|, |v86|
	v_max_f32_e32 v119, v119, v117
	v_lshlrev_b32_e32 v117, 16, v118
	v_and_b32_e32 v118, 0xffff0000, v118
	v_max_f32_e64 v120, |v118|, |v118|
	v_max_f32_e64 v121, |v117|, |v117|
	v_max_f32_e32 v120, v121, v120
	v_max3_f32 v128, v126, v119, v120
	s_waitcnt vmcnt(0)
; __device__ __forceinline__ unsigned cvt_pk_bf16(float lo, float hi) { unsigned r; asm volatile("v_cvt_pk_bf16_f32 %0, %1, %2" : "=v"(r) : "v"(lo), "v"(hi)); return r; }
; __device__ __forceinline__ float bf_lo(unsigned w) { return __uint_as_float(w << 16); }
; __device__ __forceinline__ float bf_hi(unsigned w) { return __uint_as_float(w & 0xffff0000u); }
; __device__ __forceinline__ float xlane1(float t) { return dpp_mov<0xB1, 0xF, true>(0.f, t); }
; __device__ __forceinline__ float xlane2(float t) { return dpp_mov<0x4E, 0xF, true>(0.f, t); }
; __device__ __forceinline__ float xlane4(float t) { const float r = dpp_mov<0x104, 0x5, false>(t, t); return dpp_mov<0x114, 0xA, false>(r, t); }
; __device__ __forceinline__ float xlane8(float t) { return dpp_mov<0x128, 0xF, true>(0.f, t); }
; __device__ __forceinline__ f32x4 rot64(f32x4 t, const RotSigns sg) {
;     { const float p0 = t.x + t.y, p1 = t.x - t.y, p2 = t.z + t.w, p3 = t.z - t.w; t = (f32x4){p0 + p2, p1 + p3, p0 - p2, p1 - p3}; }
;     t = (f32x4){__builtin_fmaf(sg.s1, t.x, xlane1(t.x)), __builtin_fmaf(sg.s1, t.y, xlane1(t.y)), __builtin_fmaf(sg.s1, t.z, xlane1(t.z)), __builtin_fmaf(sg.s1, t.w, xlane1(t.w))};
;     t = (f32x4){__builtin_fmaf(sg.s2, t.x, xlane2(t.x)), __builtin_fmaf(sg.s2, t.y, xlane2(t.y)), __builtin_fmaf(sg.s2, t.z, xlane2(t.z)), __builtin_fmaf(sg.s2, t.w, xlane2(t.w))};
;     t = (f32x4){__builtin_fmaf(sg.s4, t.x, xlane4(t.x)), __builtin_fmaf(sg.s4, t.y, xlane4(t.y)), __builtin_fmaf(sg.s4, t.z, xlane4(t.z)), __builtin_fmaf(sg.s4, t.w, xlane4(t.w))};
;     t = (f32x4){__builtin_fmaf(sg.s8, t.x, xlane8(t.x)), __builtin_fmaf(sg.s8, t.y, xlane8(t.y)), __builtin_fmaf(sg.s8, t.z, xlane8(t.z)), __builtin_fmaf(sg.s8, t.w, xlane8(t.w))};
;     return t * 0.125f;
; __global__ void __launch_bounds__(NWAVES * 64, 2) fwd_kernel(Args args) {
;     ...
;             for (int c = 0; c < DFF / 256; ++c) { const f32x4 t = rot64((f32x4){bf_lo(pk[c].x), bf_hi(pk[c].x), bf_lo(pk[c].y), bf_hi(pk[c].y)}, sg);
;                 pk[c].x = cvt_pk_bf16(t.x, t.y); pk[c].y = cvt_pk_bf16(t.z, t.w);
;                 am = fmaxf(fmaxf(am, fmaxf(fabsf(bf_lo(pk[c].x)), fabsf(bf_hi(pk[c].x)))), fmaxf(fabsf(bf_lo(pk[c].y)), fabsf(bf_hi(pk[c].y)))); }
	v_lshlrev_b32_e32 v121, 16, v85
	v_lshlrev_b32_e32 v120, 16, v84
	v_and_b32_e32 v85, 0xffff0000, v85
	v_and_b32_e32 v84, 0xffff0000, v84
	v_pk_add_f32 v[122:123], v[120:121], v[84:85]
	v_pk_add_f32 v[84:85], v[120:121], v[84:85] neg_lo:[0,1] neg_hi:[0,1]
	v_mov_b32_e32 v124, v122
	v_pk_mov_b32 v[120:121], v[122:123], v[84:85] op_sel:[1,0]
	v_mov_b32_e32 v125, v85
	v_mov_b32_e32 v126, v122
	v_mov_b32_e32 v127, v84
	v_mov_b32_e32 v84, v123
	v_pk_add_f32 v[120:121], v[124:125], v[120:121]
	v_pk_add_f32 v[84:85], v[126:127], v[84:85] neg_lo:[0,1] neg_hi:[0,1]
	s_nop 0
	v_mov_b32_dpp v124, v120 quad_perm:[1,0,3,2] row_mask:0xf bank_mask:0xf bound_ctrl:1
	v_mov_b32_dpp v125, v121 quad_perm:[1,0,3,2] row_mask:0xf bank_mask:0xf bound_ctrl:1
	v_mov_b32_dpp v122, v84 quad_perm:[1,0,3,2] row_mask:0xf bank_mask:0xf bound_ctrl:1
	v_mov_b32_dpp v123, v85 quad_perm:[1,0,3,2] row_mask:0xf bank_mask:0xf bound_ctrl:1
	v_pk_fma_f32 v[120:121], v[2:3], v[120:121], v[124:125]
	v_pk_fma_f32 v[84:85], v[2:3], v[84:85], v[122:123]
	s_nop 0
	v_mov_b32_dpp v124, v120 quad_perm:[2,3,0,1] row_mask:0xf bank_mask:0xf bound_ctrl:1
	v_mov_b32_dpp v125, v121 quad_perm:[2,3,0,1] row_mask:0xf bank_mask:0xf bound_ctrl:1
	v_mov_b32_dpp v122, v84 quad_perm:[2,3,0,1] row_mask:0xf bank_mask:0xf bound_ctrl:1
	v_mov_b32_dpp v123, v85 quad_perm:[2,3,0,1] row_mask:0xf bank_mask:0xf bound_ctrl:1
	v_pk_fma_f32 v[120:121], v[4:5], v[120:121], v[124:125]
	v_pk_fma_f32 v[84:85], v[4:5], v[84:85], v[122:123]
	v_mov_b32_e32 v124, v120
	v_mov_b32_e32 v125, v121
	v_mov_b32_e32 v122, v84
	v_mov_b32_e32 v123, v85
	v_mov_b32_dpp v124, v124 row_shl:4 row_mask:0xf bank_mask:0x5
	v_mov_b32_dpp v125, v125 row_shl:4 row_mask:0xf bank_mask:0x5
	v_mov_b32_dpp v122, v122 row_shl:4 row_mask:0xf bank_mask:0x5
	v_mov_b32_dpp v123, v123 row_shl:4 row_mask:0xf bank_mask:0x5
	v_mov_b32_dpp v124, v120 row_shr:4 row_mask:0xf bank_mask:0xa
	v_mov_b32_dpp v125, v121 row_shr:4 row_mask:0xf bank_mask:0xa
	v_mov_b32_dpp v122, v84 row_shr:4 row_mask:0xf bank_mask:0xa
	v_mov_b32_dpp v123, v85 row_shr:4 row_mask:0xf bank_mask:0xa
	v_pk_fma_f32 v[120:121], v[6:7], v[120:121], v[124:125]
	v_pk_fma_f32 v[84:85], v[6:7], v[84:85], v[122:123]
	s_nop 0
	v_mov_b32_dpp v124, v120 row_ror:8 row_mask:0xf bank_mask:0xf bound_ctrl:1
	v_mov_b32_dpp v125, v121 row_ror:8 row_mask:0xf bank_mask:0xf bound_ctrl:1
	v_mov_b32_dpp v122, v84 row_ror:8 row_mask:0xf bank_mask:0xf bound_ctrl:1
	v_mov_b32_dpp v123, v85 row_ror:8 row_mask:0xf bank_mask:0xf bound_ctrl:1
	v_pk_fma_f32 v[120:121], v[8:9], v[120:121], v[124:125]
	v_pk_fma_f32 v[84:85], v[10:11], v[84:85], v[122:123]
	v_pk_mul_f32 v[120:121], v[120:121], s[22:23] op_sel_hi:[1,0]
	v_pk_mul_f32 v[84:85], v[84:85], s[22:23] op_sel_hi:[1,0]
	v_cvt_pk_bf16_f32 v119, v120, v121
	s_nop 0
	v_cvt_pk_bf16_f32 v120, v84, v85
	v_lshlrev_b32_e32 v84, 16, v119
	v_and_b32_e32 v85, 0xffff0000, v119
	v_max_f32_e64 v119, |v85|, |v85|
	v_max_f32_e64 v121, |v84|, |v84|
	v_max_f32_e32 v121, v121, v119
	v_lshlrev_b32_e32 v119, 16, v120
	v_and_b32_e32 v120, 0xffff0000, v120
	v_max_f32_e64 v122, |v120|, |v120|
	v_max_f32_e64 v123, |v119|, |v119|
	v_max_f32_e32 v122, v123, v122
	v_max3_f32 v130, v128, v121, v122
	v_lshlrev_b32_e32 v123, 16, v83
	v_lshlrev_b32_e32 v122, 16, v82
	v_and_b32_e32 v83, 0xffff0000, v83
	v_and_b32_e32 v82, 0xffff0000, v82
	v_pk_add_f32 v[124:125], v[122:123], v[82:83]
	v_pk_add_f32 v[82:83], v[122:123], v[82:83] neg_lo:[0,1] neg_hi:[0,1]
	v_mov_b32_e32 v126, v124
	v_pk_mov_b32 v[122:123], v[124:125], v[82:83] op_sel:[1,0]
	v_mov_b32_e32 v127, v83
	v_mov_b32_e32 v128, v124
	v_mov_b32_e32 v129, v82
	v_mov_b32_e32 v82, v125
	v_pk_add_f32 v[122:123], v[126:127], v[122:123]
	v_pk_add_f32 v[82:83], v[128:129], v[82:83] neg_lo:[0,1] neg_hi:[0,1]
	s_nop 0
	v_mov_b32_dpp v126, v122 quad_perm:[1,0,3,2] row_mask:0xf bank_mask:0xf bound_ctrl:1
	v_mov_b32_dpp v127, v123 quad_perm:[1,0,3,2] row_mask:0xf bank_mask:0xf bound_ctrl:1
	v_mov_b32_dpp v124, v82 quad_perm:[1,0,3,2] row_mask:0xf bank_mask:0xf bound_ctrl:1
	v_mov_b32_dpp v125, v83 quad_perm:[1,0,3,2] row_mask:0xf bank_mask:0xf bound_ctrl:1
	v_pk_fma_f32 v[122:123], v[2:3], v[122:123], v[126:127]
	v_pk_fma_f32 v[82:83], v[2:3], v[82:83], v[124:125]
	s_nop 0
	v_mov_b32_dpp v126, v122 quad_perm:[2,3,0,1] row_mask:0xf bank_mask:0xf bound_ctrl:1
	v_mov_b32_dpp v127, v123 quad_perm:[2,3,0,1] row_mask:0xf bank_mask:0xf bound_ctrl:1
	v_mov_b32_dpp v124, v82 quad_perm:[2,3,0,1] row_mask:0xf bank_mask:0xf bound_ctrl:1
	v_mov_b32_dpp v125, v83 quad_perm:[2,3,0,1] row_mask:0xf bank_mask:0xf bound_ctrl:1
	v_pk_fma_f32 v[122:123], v[4:5], v[122:123], v[126:127]
	v_pk_fma_f32 v[82:83], v[4:5], v[82:83], v[124:125]
	v_mov_b32_e32 v126, v122
	v_mov_b32_e32 v127, v123
	v_mov_b32_e32 v124, v82
	v_mov_b32_e32 v125, v83
	v_mov_b32_dpp v126, v126 row_shl:4 row_mask:0xf bank_mask:0x5
	v_mov_b32_dpp v127, v127 row_shl:4 row_mask:0xf bank_mask:0x5
	v_mov_b32_dpp v124, v124 row_shl:4 row_mask:0xf bank_mask:0x5
	v_mov_b32_dpp v125, v125 row_shl:4 row_mask:0xf bank_mask:0x5
	v_mov_b32_dpp v126, v122 row_shr:4 row_mask:0xf bank_mask:0xa
	v_mov_b32_dpp v127, v123 row_shr:4 row_mask:0xf bank_mask:0xa
	v_mov_b32_dpp v124, v82 row_shr:4 row_mask:0xf bank_mask:0xa
	v_mov_b32_dpp v125, v83 row_shr:4 row_mask:0xf bank_mask:0xa
	v_pk_fma_f32 v[122:123], v[6:7], v[122:123], v[126:127]
	v_pk_fma_f32 v[82:83], v[6:7], v[82:83], v[124:125]
	s_nop 0
	v_mov_b32_dpp v126, v122 row_ror:8 row_mask:0xf bank_mask:0xf bound_ctrl:1
	v_mov_b32_dpp v127, v123 row_ror:8 row_mask:0xf bank_mask:0xf bound_ctrl:1
	v_mov_b32_dpp v124, v82 row_ror:8 row_mask:0xf bank_mask:0xf bound_ctrl:1
; __device__ __forceinline__ unsigned cvt_pk_bf16(float lo, float hi) { unsigned r; asm volatile("v_cvt_pk_bf16_f32 %0, %1, %2" : "=v"(r) : "v"(lo), "v"(hi)); return r; }
; __device__ __forceinline__ float bf_lo(unsigned w) { return __uint_as_float(w << 16); }
; __device__ __forceinline__ float bf_hi(unsigned w) { return __uint_as_float(w & 0xffff0000u); }
; __device__ __forceinline__ float xlane1(float t) { return dpp_mov<0xB1, 0xF, true>(0.f, t); }
; __device__ __forceinline__ float xlane2(float t) { return dpp_mov<0x4E, 0xF, true>(0.f, t); }
; __device__ __forceinline__ float xlane4(float t) { const float r = dpp_mov<0x104, 0x5, false>(t, t); return dpp_mov<0x114, 0xA, false>(r, t); }
; __device__ __forceinline__ float xlane8(float t) { return dpp_mov<0x128, 0xF, true>(0.f, t); }
; __device__ __forceinline__ f32x4 rot64(f32x4 t, const RotSigns sg) {
;     { const float p0 = t.x + t.y, p1 = t.x - t.y, p2 = t.z + t.w, p3 = t.z - t.w; t = (f32x4){p0 + p2, p1 + p3, p0 - p2, p1 - p3}; }
;     t = (f32x4){__builtin_fmaf(sg.s1, t.x, xlane1(t.x)), __builtin_fmaf(sg.s1, t.y, xlane1(t.y)), __builtin_fmaf(sg.s1, t.z, xlane1(t.z)), __builtin_fmaf(sg.s1, t.w, xlane1(t.w))};
;     t = (f32x4){__builtin_fmaf(sg.s2, t.x, xlane2(t.x)), __builtin_fmaf(sg.s2, t.y, xlane2(t.y)), __builtin_fmaf(sg.s2, t.z, xlane2(t.z)), __builtin_fmaf(sg.s2, t.w, xlane2(t.w))};
;     t = (f32x4){__builtin_fmaf(sg.s4, t.x, xlane4(t.x)), __builtin_fmaf(sg.s4, t.y, xlane4(t.y)), __builtin_fmaf(sg.s4, t.z, xlane4(t.z)), __builtin_fmaf(sg.s4, t.w, xlane4(t.w))};
;     t = (f32x4){__builtin_fmaf(sg.s8, t.x, xlane8(t.x)), __builtin_fmaf(sg.s8, t.y, xlane8(t.y)), __builtin_fmaf(sg.s8, t.z, xlane8(t.z)), __builtin_fmaf(sg.s8, t.w, xlane8(t.w))};
;     return t * 0.125f;
; __global__ void __launch_bounds__(NWAVES * 64, 2) fwd_kernel(Args args) {
;     ...
;             for (int c = 0; c < DFF / 256; ++c) { const f32x4 t = rot64((f32x4){bf_lo(pk[c].x), bf_hi(pk[c].x), bf_lo(pk[c].y), bf_hi(pk[c].y)}, sg);
;                 pk[c].x = cvt_pk_bf16(t.x, t.y); pk[c].y = cvt_pk_bf16(t.z, t.w);
;                 am = fmaxf(fmaxf(am, fmaxf(fabsf(bf_lo(pk[c].x)), fabsf(bf_hi(pk[c].x)))), fmaxf(fabsf(bf_lo(pk[c].y)), fabsf(bf_hi(pk[c].y)))); }
	v_mov_b32_dpp v125, v83 row_ror:8 row_mask:0xf bank_mask:0xf bound_ctrl:1
	v_pk_fma_f32 v[122:123], v[8:9], v[122:123], v[126:127]
	v_pk_fma_f32 v[82:83], v[10:11], v[82:83], v[124:125]
	v_pk_mul_f32 v[122:123], v[122:123], s[22:23] op_sel_hi:[1,0]
	v_pk_mul_f32 v[82:83], v[82:83], s[22:23] op_sel_hi:[1,0]
	v_cvt_pk_bf16_f32 v121, v122, v123
	s_nop 0
	v_cvt_pk_bf16_f32 v122, v82, v83
	v_lshlrev_b32_e32 v82, 16, v121
	v_and_b32_e32 v83, 0xffff0000, v121
	v_max_f32_e64 v121, |v83|, |v83|
	v_max_f32_e64 v123, |v82|, |v82|
	v_max_f32_e32 v123, v123, v121
	v_lshlrev_b32_e32 v121, 16, v122
	v_and_b32_e32 v122, 0xffff0000, v122
	v_max_f32_e64 v124, |v122|, |v122|
	v_max_f32_e64 v125, |v121|, |v121|
	v_max_f32_e32 v124, v125, v124
	v_max3_f32 v132, v130, v123, v124
	v_lshlrev_b32_e32 v125, 16, v81
	v_lshlrev_b32_e32 v124, 16, v80
	v_and_b32_e32 v81, 0xffff0000, v81
	v_and_b32_e32 v80, 0xffff0000, v80
	v_pk_add_f32 v[126:127], v[124:125], v[80:81]
	v_pk_add_f32 v[80:81], v[124:125], v[80:81] neg_lo:[0,1] neg_hi:[0,1]
	v_mov_b32_e32 v128, v126
	v_pk_mov_b32 v[124:125], v[126:127], v[80:81] op_sel:[1,0]
	v_mov_b32_e32 v129, v81
	v_mov_b32_e32 v130, v126
	v_mov_b32_e32 v131, v80
	v_mov_b32_e32 v80, v127
	v_pk_add_f32 v[124:125], v[128:129], v[124:125]
	v_pk_add_f32 v[80:81], v[130:131], v[80:81] neg_lo:[0,1] neg_hi:[0,1]
	s_nop 0
	v_mov_b32_dpp v128, v124 quad_perm:[1,0,3,2] row_mask:0xf bank_mask:0xf bound_ctrl:1
	v_mov_b32_dpp v129, v125 quad_perm:[1,0,3,2] row_mask:0xf bank_mask:0xf bound_ctrl:1
	v_mov_b32_dpp v126, v80 quad_perm:[1,0,3,2] row_mask:0xf bank_mask:0xf bound_ctrl:1
	v_mov_b32_dpp v127, v81 quad_perm:[1,0,3,2] row_mask:0xf bank_mask:0xf bound_ctrl:1
	v_pk_fma_f32 v[124:125], v[2:3], v[124:125], v[128:129]
	v_pk_fma_f32 v[80:81], v[2:3], v[80:81], v[126:127]
	s_nop 0
	v_mov_b32_dpp v128, v124 quad_perm:[2,3,0,1] row_mask:0xf bank_mask:0xf bound_ctrl:1
	v_mov_b32_dpp v129, v125 quad_perm:[2,3,0,1] row_mask:0xf bank_mask:0xf bound_ctrl:1
	v_mov_b32_dpp v126, v80 quad_perm:[2,3,0,1] row_mask:0xf bank_mask:0xf bound_ctrl:1
	v_mov_b32_dpp v127, v81 quad_perm:[2,3,0,1] row_mask:0xf bank_mask:0xf bound_ctrl:1
	v_pk_fma_f32 v[124:125], v[4:5], v[124:125], v[128:129]
	v_pk_fma_f32 v[80:81], v[4:5], v[80:81], v[126:127]
	v_mov_b32_e32 v128, v124
	v_mov_b32_e32 v129, v125
	v_mov_b32_e32 v126, v80
	v_mov_b32_e32 v127, v81
	v_mov_b32_dpp v128, v128 row_shl:4 row_mask:0xf bank_mask:0x5
	v_mov_b32_dpp v129, v129 row_shl:4 row_mask:0xf bank_mask:0x5
	v_mov_b32_dpp v126, v126 row_shl:4 row_mask:0xf bank_mask:0x5
	v_mov_b32_dpp v127, v127 row_shl:4 row_mask:0xf bank_mask:0x5
	v_mov_b32_dpp v128, v124 row_shr:4 row_mask:0xf bank_mask:0xa
	v_mov_b32_dpp v129, v125 row_shr:4 row_mask:0xf bank_mask:0xa
	v_mov_b32_dpp v126, v80 row_shr:4 row_mask:0xf bank_mask:0xa
	v_mov_b32_dpp v127, v81 row_shr:4 row_mask:0xf bank_mask:0xa
	v_pk_fma_f32 v[124:125], v[6:7], v[124:125], v[128:129]
	v_pk_fma_f32 v[80:81], v[6:7], v[80:81], v[126:127]
	s_nop 0
	v_mov_b32_dpp v128, v124 row_ror:8 row_mask:0xf bank_mask:0xf bound_ctrl:1
	v_mov_b32_dpp v129, v125 row_ror:8 row_mask:0xf bank_mask:0xf bound_ctrl:1
	v_mov_b32_dpp v126, v80 row_ror:8 row_mask:0xf bank_mask:0xf bound_ctrl:1
	v_mov_b32_dpp v127, v81 row_ror:8 row_mask:0xf bank_mask:0xf bound_ctrl:1
	v_pk_fma_f32 v[124:125], v[8:9], v[124:125], v[128:129]
	v_pk_fma_f32 v[80:81], v[10:11], v[80:81], v[126:127]
	v_pk_mul_f32 v[124:125], v[124:125], s[22:23] op_sel_hi:[1,0]
	v_pk_mul_f32 v[80:81], v[80:81], s[22:23] op_sel_hi:[1,0]
	v_cvt_pk_bf16_f32 v123, v124, v125
	s_nop 0
	v_cvt_pk_bf16_f32 v124, v80, v81
	v_lshlrev_b32_e32 v80, 16, v123
	v_and_b32_e32 v81, 0xffff0000, v123
	v_max_f32_e64 v123, |v81|, |v81|
	v_max_f32_e64 v125, |v80|, |v80|
	v_max_f32_e32 v125, v125, v123
	v_lshlrev_b32_e32 v123, 16, v124
	v_and_b32_e32 v124, 0xffff0000, v124
	v_max_f32_e64 v126, |v124|, |v124|
	v_max_f32_e64 v127, |v123|, |v123|
	v_max_f32_e32 v126, v127, v126
	v_max3_f32 v134, v132, v125, v126
	v_lshlrev_b32_e32 v127, 16, v79
	v_lshlrev_b32_e32 v126, 16, v78
	v_and_b32_e32 v79, 0xffff0000, v79
	v_and_b32_e32 v78, 0xffff0000, v78
	v_pk_add_f32 v[128:129], v[126:127], v[78:79]
	v_pk_add_f32 v[78:79], v[126:127], v[78:79] neg_lo:[0,1] neg_hi:[0,1]
	v_mov_b32_e32 v130, v128
	v_pk_mov_b32 v[126:127], v[128:129], v[78:79] op_sel:[1,0]
	v_mov_b32_e32 v131, v79
	v_mov_b32_e32 v132, v128
	v_mov_b32_e32 v133, v78
	v_mov_b32_e32 v78, v129
	v_pk_add_f32 v[126:127], v[130:131], v[126:127]
	v_pk_add_f32 v[78:79], v[132:133], v[78:79] neg_lo:[0,1] neg_hi:[0,1]
	s_nop 0
	v_mov_b32_dpp v130, v126 quad_perm:[1,0,3,2] row_mask:0xf bank_mask:0xf bound_ctrl:1
	v_mov_b32_dpp v131, v127 quad_perm:[1,0,3,2] row_mask:0xf bank_mask:0xf bound_ctrl:1
	v_mov_b32_dpp v128, v78 quad_perm:[1,0,3,2] row_mask:0xf bank_mask:0xf bound_ctrl:1
	v_mov_b32_dpp v129, v79 quad_perm:[1,0,3,2] row_mask:0xf bank_mask:0xf bound_ctrl:1
	v_pk_fma_f32 v[126:127], v[2:3], v[126:127], v[130:131]
	v_pk_fma_f32 v[78:79], v[2:3], v[78:79], v[128:129]
	s_nop 0
	v_mov_b32_dpp v130, v126 quad_perm:[2,3,0,1] row_mask:0xf bank_mask:0xf bound_ctrl:1
	v_mov_b32_dpp v131, v127 quad_perm:[2,3,0,1] row_mask:0xf bank_mask:0xf bound_ctrl:1
	v_mov_b32_dpp v128, v78 quad_perm:[2,3,0,1] row_mask:0xf bank_mask:0xf bound_ctrl:1
	v_mov_b32_dpp v129, v79 quad_perm:[2,3,0,1] row_mask:0xf bank_mask:0xf bound_ctrl:1
	v_pk_fma_f32 v[126:127], v[4:5], v[126:127], v[130:131]
	v_pk_fma_f32 v[78:79], v[4:5], v[78:79], v[128:129]
	v_mov_b32_e32 v130, v126
	v_mov_b32_e32 v131, v127
	v_mov_b32_e32 v128, v78
	v_mov_b32_e32 v129, v79
	v_mov_b32_dpp v130, v130 row_shl:4 row_mask:0xf bank_mask:0x5
; __device__ __forceinline__ unsigned cvt_pk_bf16(float lo, float hi) { unsigned r; asm volatile("v_cvt_pk_bf16_f32 %0, %1, %2" : "=v"(r) : "v"(lo), "v"(hi)); return r; }
; __device__ __forceinline__ float bf_lo(unsigned w) { return __uint_as_float(w << 16); }
; __device__ __forceinline__ float bf_hi(unsigned w) { return __uint_as_float(w & 0xffff0000u); }
; __device__ __forceinline__ float xlane1(float t) { return dpp_mov<0xB1, 0xF, true>(0.f, t); }
; __device__ __forceinline__ float xlane2(float t) { return dpp_mov<0x4E, 0xF, true>(0.f, t); }
; __device__ __forceinline__ float xlane4(float t) { const float r = dpp_mov<0x104, 0x5, false>(t, t); return dpp_mov<0x114, 0xA, false>(r, t); }
; __device__ __forceinline__ float xlane8(float t) { return dpp_mov<0x128, 0xF, true>(0.f, t); }
; __device__ __forceinline__ f32x4 rot64(f32x4 t, const RotSigns sg) {
;     { const float p0 = t.x + t.y, p1 = t.x - t.y, p2 = t.z + t.w, p3 = t.z - t.w; t = (f32x4){p0 + p2, p1 + p3, p0 - p2, p1 - p3}; }
;     t = (f32x4){__builtin_fmaf(sg.s1, t.x, xlane1(t.x)), __builtin_fmaf(sg.s1, t.y, xlane1(t.y)), __builtin_fmaf(sg.s1, t.z, xlane1(t.z)), __builtin_fmaf(sg.s1, t.w, xlane1(t.w))};
;     t = (f32x4){__builtin_fmaf(sg.s2, t.x, xlane2(t.x)), __builtin_fmaf(sg.s2, t.y, xlane2(t.y)), __builtin_fmaf(sg.s2, t.z, xlane2(t.z)), __builtin_fmaf(sg.s2, t.w, xlane2(t.w))};
;     t = (f32x4){__builtin_fmaf(sg.s4, t.x, xlane4(t.x)), __builtin_fmaf(sg.s4, t.y, xlane4(t.y)), __builtin_fmaf(sg.s4, t.z, xlane4(t.z)), __builtin_fmaf(sg.s4, t.w, xlane4(t.w))};
;     t = (f32x4){__builtin_fmaf(sg.s8, t.x, xlane8(t.x)), __builtin_fmaf(sg.s8, t.y, xlane8(t.y)), __builtin_fmaf(sg.s8, t.z, xlane8(t.z)), __builtin_fmaf(sg.s8, t.w, xlane8(t.w))};
;     return t * 0.125f;
; __global__ void __launch_bounds__(NWAVES * 64, 2) fwd_kernel(Args args) {
;     ...
;             for (int c = 0; c < DFF / 256; ++c) { const f32x4 t = rot64((f32x4){bf_lo(pk[c].x), bf_hi(pk[c].x), bf_lo(pk[c].y), bf_hi(pk[c].y)}, sg);
;                 pk[c].x = cvt_pk_bf16(t.x, t.y); pk[c].y = cvt_pk_bf16(t.z, t.w);
;                 am = fmaxf(fmaxf(am, fmaxf(fabsf(bf_lo(pk[c].x)), fabsf(bf_hi(pk[c].x)))), fmaxf(fabsf(bf_lo(pk[c].y)), fabsf(bf_hi(pk[c].y)))); }
	v_mov_b32_dpp v131, v131 row_shl:4 row_mask:0xf bank_mask:0x5
	v_mov_b32_dpp v128, v128 row_shl:4 row_mask:0xf bank_mask:0x5
	v_mov_b32_dpp v129, v129 row_shl:4 row_mask:0xf bank_mask:0x5
	v_mov_b32_dpp v130, v126 row_shr:4 row_mask:0xf bank_mask:0xa
	v_mov_b32_dpp v131, v127 row_shr:4 row_mask:0xf bank_mask:0xa
	v_mov_b32_dpp v128, v78 row_shr:4 row_mask:0xf bank_mask:0xa
	v_mov_b32_dpp v129, v79 row_shr:4 row_mask:0xf bank_mask:0xa
	v_pk_fma_f32 v[126:127], v[6:7], v[126:127], v[130:131]
	v_pk_fma_f32 v[78:79], v[6:7], v[78:79], v[128:129]
	s_nop 0
	v_mov_b32_dpp v130, v126 row_ror:8 row_mask:0xf bank_mask:0xf bound_ctrl:1
	v_mov_b32_dpp v131, v127 row_ror:8 row_mask:0xf bank_mask:0xf bound_ctrl:1
	v_mov_b32_dpp v128, v78 row_ror:8 row_mask:0xf bank_mask:0xf bound_ctrl:1
	v_mov_b32_dpp v129, v79 row_ror:8 row_mask:0xf bank_mask:0xf bound_ctrl:1
	v_pk_fma_f32 v[126:127], v[8:9], v[126:127], v[130:131]
	v_pk_fma_f32 v[78:79], v[10:11], v[78:79], v[128:129]
	v_pk_mul_f32 v[126:127], v[126:127], s[22:23] op_sel_hi:[1,0]
	v_pk_mul_f32 v[78:79], v[78:79], s[22:23] op_sel_hi:[1,0]
	v_cvt_pk_bf16_f32 v125, v126, v127
	s_nop 0
	v_cvt_pk_bf16_f32 v126, v78, v79
	v_lshlrev_b32_e32 v78, 16, v125
	v_and_b32_e32 v79, 0xffff0000, v125
	v_max_f32_e64 v125, |v79|, |v79|
	v_max_f32_e64 v127, |v78|, |v78|
	v_max_f32_e32 v127, v127, v125
	v_lshlrev_b32_e32 v125, 16, v126
	v_and_b32_e32 v126, 0xffff0000, v126
	v_max_f32_e64 v128, |v126|, |v126|
	v_max_f32_e64 v129, |v125|, |v125|
	v_max_f32_e32 v128, v129, v128
	v_max3_f32 v136, v134, v127, v128
	v_lshlrev_b32_e32 v129, 16, v77
	v_lshlrev_b32_e32 v128, 16, v76
	v_and_b32_e32 v77, 0xffff0000, v77
	v_and_b32_e32 v76, 0xffff0000, v76
	v_pk_add_f32 v[130:131], v[128:129], v[76:77]
	v_pk_add_f32 v[76:77], v[128:129], v[76:77] neg_lo:[0,1] neg_hi:[0,1]
	v_mov_b32_e32 v132, v130
	v_pk_mov_b32 v[128:129], v[130:131], v[76:77] op_sel:[1,0]
	v_mov_b32_e32 v133, v77
	v_mov_b32_e32 v134, v130
	v_mov_b32_e32 v135, v76
	v_mov_b32_e32 v76, v131
	v_pk_add_f32 v[128:129], v[132:133], v[128:129]
	v_pk_add_f32 v[76:77], v[134:135], v[76:77] neg_lo:[0,1] neg_hi:[0,1]
	s_nop 0
	v_mov_b32_dpp v132, v128 quad_perm:[1,0,3,2] row_mask:0xf bank_mask:0xf bound_ctrl:1
	v_mov_b32_dpp v133, v129 quad_perm:[1,0,3,2] row_mask:0xf bank_mask:0xf bound_ctrl:1
	v_mov_b32_dpp v130, v76 quad_perm:[1,0,3,2] row_mask:0xf bank_mask:0xf bound_ctrl:1
	v_mov_b32_dpp v131, v77 quad_perm:[1,0,3,2] row_mask:0xf bank_mask:0xf bound_ctrl:1
	v_pk_fma_f32 v[128:129], v[2:3], v[128:129], v[132:133]
	v_pk_fma_f32 v[76:77], v[2:3], v[76:77], v[130:131]
	s_nop 0
	v_mov_b32_dpp v132, v128 quad_perm:[2,3,0,1] row_mask:0xf bank_mask:0xf bound_ctrl:1
	v_mov_b32_dpp v133, v129 quad_perm:[2,3,0,1] row_mask:0xf bank_mask:0xf bound_ctrl:1
	v_mov_b32_dpp v130, v76 quad_perm:[2,3,0,1] row_mask:0xf bank_mask:0xf bound_ctrl:1
	v_mov_b32_dpp v131, v77 quad_perm:[2,3,0,1] row_mask:0xf bank_mask:0xf bound_ctrl:1
	v_pk_fma_f32 v[128:129], v[4:5], v[128:129], v[132:133]
	v_pk_fma_f32 v[76:77], v[4:5], v[76:77], v[130:131]
	v_mov_b32_e32 v132, v128
	v_mov_b32_e32 v133, v129
	v_mov_b32_e32 v130, v76
	v_mov_b32_e32 v131, v77
	v_mov_b32_dpp v132, v132 row_shl:4 row_mask:0xf bank_mask:0x5
	v_mov_b32_dpp v133, v133 row_shl:4 row_mask:0xf bank_mask:0x5
	v_mov_b32_dpp v130, v130 row_shl:4 row_mask:0xf bank_mask:0x5
	v_mov_b32_dpp v131, v131 row_shl:4 row_mask:0xf bank_mask:0x5
	v_mov_b32_dpp v132, v128 row_shr:4 row_mask:0xf bank_mask:0xa
	v_mov_b32_dpp v133, v129 row_shr:4 row_mask:0xf bank_mask:0xa
	v_mov_b32_dpp v130, v76 row_shr:4 row_mask:0xf bank_mask:0xa
	v_mov_b32_dpp v131, v77 row_shr:4 row_mask:0xf bank_mask:0xa
	v_pk_fma_f32 v[128:129], v[6:7], v[128:129], v[132:133]
	v_pk_fma_f32 v[76:77], v[6:7], v[76:77], v[130:131]
	s_nop 0
	v_mov_b32_dpp v132, v128 row_ror:8 row_mask:0xf bank_mask:0xf bound_ctrl:1
	v_mov_b32_dpp v133, v129 row_ror:8 row_mask:0xf bank_mask:0xf bound_ctrl:1
	v_mov_b32_dpp v130, v76 row_ror:8 row_mask:0xf bank_mask:0xf bound_ctrl:1
	v_mov_b32_dpp v131, v77 row_ror:8 row_mask:0xf bank_mask:0xf bound_ctrl:1
	v_pk_fma_f32 v[128:129], v[8:9], v[128:129], v[132:133]
	v_pk_fma_f32 v[76:77], v[10:11], v[76:77], v[130:131]
	v_pk_mul_f32 v[128:129], v[128:129], s[22:23] op_sel_hi:[1,0]
	v_pk_mul_f32 v[76:77], v[76:77], s[22:23] op_sel_hi:[1,0]
	v_cvt_pk_bf16_f32 v127, v128, v129
	s_nop 0
	v_cvt_pk_bf16_f32 v128, v76, v77
	v_lshlrev_b32_e32 v76, 16, v127
	v_and_b32_e32 v77, 0xffff0000, v127
	v_max_f32_e64 v127, |v77|, |v77|
	v_max_f32_e64 v129, |v76|, |v76|
	v_max_f32_e32 v129, v129, v127
	v_lshlrev_b32_e32 v127, 16, v128
	v_and_b32_e32 v128, 0xffff0000, v128
	v_max_f32_e64 v130, |v128|, |v128|
	v_max_f32_e64 v131, |v127|, |v127|
	v_max_f32_e32 v130, v131, v130
	v_max3_f32 v138, v136, v129, v130
	v_lshlrev_b32_e32 v131, 16, v75
	v_lshlrev_b32_e32 v130, 16, v74
	v_and_b32_e32 v75, 0xffff0000, v75
	v_and_b32_e32 v74, 0xffff0000, v74
	v_pk_add_f32 v[132:133], v[130:131], v[74:75]
	v_pk_add_f32 v[74:75], v[130:131], v[74:75] neg_lo:[0,1] neg_hi:[0,1]
	v_mov_b32_e32 v134, v132
	v_pk_mov_b32 v[130:131], v[132:133], v[74:75] op_sel:[1,0]
	v_mov_b32_e32 v135, v75
	v_mov_b32_e32 v136, v132
	v_mov_b32_e32 v137, v74
	v_mov_b32_e32 v74, v133
	v_pk_add_f32 v[130:131], v[134:135], v[130:131]
	v_pk_add_f32 v[74:75], v[136:137], v[74:75] neg_lo:[0,1] neg_hi:[0,1]
	s_nop 0
	v_mov_b32_dpp v134, v130 quad_perm:[1,0,3,2] row_mask:0xf bank_mask:0xf bound_ctrl:1
	v_mov_b32_dpp v135, v131 quad_perm:[1,0,3,2] row_mask:0xf bank_mask:0xf bound_ctrl:1
	v_mov_b32_dpp v132, v74 quad_perm:[1,0,3,2] row_mask:0xf bank_mask:0xf bound_ctrl:1
	v_mov_b32_dpp v133, v75 quad_perm:[1,0,3,2] row_mask:0xf bank_mask:0xf bound_ctrl:1
; __device__ __forceinline__ unsigned cvt_pk_bf16(float lo, float hi) { unsigned r; asm volatile("v_cvt_pk_bf16_f32 %0, %1, %2" : "=v"(r) : "v"(lo), "v"(hi)); return r; }
; __device__ __forceinline__ float bf_lo(unsigned w) { return __uint_as_float(w << 16); }
; __device__ __forceinline__ float bf_hi(unsigned w) { return __uint_as_float(w & 0xffff0000u); }
; __device__ __forceinline__ float xlane1(float t) { return dpp_mov<0xB1, 0xF, true>(0.f, t); }
; __device__ __forceinline__ float xlane2(float t) { return dpp_mov<0x4E, 0xF, true>(0.f, t); }
; __device__ __forceinline__ float xlane4(float t) { const float r = dpp_mov<0x104, 0x5, false>(t, t); return dpp_mov<0x114, 0xA, false>(r, t); }
; __device__ __forceinline__ float xlane8(float t) { return dpp_mov<0x128, 0xF, true>(0.f, t); }
; __device__ __forceinline__ f32x4 rot64(f32x4 t, const RotSigns sg) {
;     { const float p0 = t.x + t.y, p1 = t.x - t.y, p2 = t.z + t.w, p3 = t.z - t.w; t = (f32x4){p0 + p2, p1 + p3, p0 - p2, p1 - p3}; }
;     t = (f32x4){__builtin_fmaf(sg.s1, t.x, xlane1(t.x)), __builtin_fmaf(sg.s1, t.y, xlane1(t.y)), __builtin_fmaf(sg.s1, t.z, xlane1(t.z)), __builtin_fmaf(sg.s1, t.w, xlane1(t.w))};
;     t = (f32x4){__builtin_fmaf(sg.s2, t.x, xlane2(t.x)), __builtin_fmaf(sg.s2, t.y, xlane2(t.y)), __builtin_fmaf(sg.s2, t.z, xlane2(t.z)), __builtin_fmaf(sg.s2, t.w, xlane2(t.w))};
;     t = (f32x4){__builtin_fmaf(sg.s4, t.x, xlane4(t.x)), __builtin_fmaf(sg.s4, t.y, xlane4(t.y)), __builtin_fmaf(sg.s4, t.z, xlane4(t.z)), __builtin_fmaf(sg.s4, t.w, xlane4(t.w))};
;     t = (f32x4){__builtin_fmaf(sg.s8, t.x, xlane8(t.x)), __builtin_fmaf(sg.s8, t.y, xlane8(t.y)), __builtin_fmaf(sg.s8, t.z, xlane8(t.z)), __builtin_fmaf(sg.s8, t.w, xlane8(t.w))};
;     return t * 0.125f;
; __global__ void __launch_bounds__(NWAVES * 64, 2) fwd_kernel(Args args) {
;     ...
;             for (int c = 0; c < DFF / 256; ++c) { const f32x4 t = rot64((f32x4){bf_lo(pk[c].x), bf_hi(pk[c].x), bf_lo(pk[c].y), bf_hi(pk[c].y)}, sg);
;                 pk[c].x = cvt_pk_bf16(t.x, t.y); pk[c].y = cvt_pk_bf16(t.z, t.w);
;                 am = fmaxf(fmaxf(am, fmaxf(fabsf(bf_lo(pk[c].x)), fabsf(bf_hi(pk[c].x)))), fmaxf(fabsf(bf_lo(pk[c].y)), fabsf(bf_hi(pk[c].y)))); }
	v_pk_fma_f32 v[130:131], v[2:3], v[130:131], v[134:135]
	v_pk_fma_f32 v[74:75], v[2:3], v[74:75], v[132:133]
	s_nop 0
	v_mov_b32_dpp v134, v130 quad_perm:[2,3,0,1] row_mask:0xf bank_mask:0xf bound_ctrl:1
	v_mov_b32_dpp v135, v131 quad_perm:[2,3,0,1] row_mask:0xf bank_mask:0xf bound_ctrl:1
	v_mov_b32_dpp v132, v74 quad_perm:[2,3,0,1] row_mask:0xf bank_mask:0xf bound_ctrl:1
	v_mov_b32_dpp v133, v75 quad_perm:[2,3,0,1] row_mask:0xf bank_mask:0xf bound_ctrl:1
	v_pk_fma_f32 v[130:131], v[4:5], v[130:131], v[134:135]
	v_pk_fma_f32 v[74:75], v[4:5], v[74:75], v[132:133]
	v_mov_b32_e32 v134, v130
	v_mov_b32_e32 v135, v131
	v_mov_b32_e32 v132, v74
	v_mov_b32_e32 v133, v75
	v_mov_b32_dpp v134, v134 row_shl:4 row_mask:0xf bank_mask:0x5
	v_mov_b32_dpp v135, v135 row_shl:4 row_mask:0xf bank_mask:0x5
	v_mov_b32_dpp v132, v132 row_shl:4 row_mask:0xf bank_mask:0x5
	v_mov_b32_dpp v133, v133 row_shl:4 row_mask:0xf bank_mask:0x5
	v_mov_b32_dpp v134, v130 row_shr:4 row_mask:0xf bank_mask:0xa
	v_mov_b32_dpp v135, v131 row_shr:4 row_mask:0xf bank_mask:0xa
	v_mov_b32_dpp v132, v74 row_shr:4 row_mask:0xf bank_mask:0xa
	v_mov_b32_dpp v133, v75 row_shr:4 row_mask:0xf bank_mask:0xa
	v_pk_fma_f32 v[130:131], v[6:7], v[130:131], v[134:135]
	v_pk_fma_f32 v[74:75], v[6:7], v[74:75], v[132:133]
	s_nop 0
	v_mov_b32_dpp v134, v130 row_ror:8 row_mask:0xf bank_mask:0xf bound_ctrl:1
	v_mov_b32_dpp v135, v131 row_ror:8 row_mask:0xf bank_mask:0xf bound_ctrl:1
	v_mov_b32_dpp v132, v74 row_ror:8 row_mask:0xf bank_mask:0xf bound_ctrl:1
	v_mov_b32_dpp v133, v75 row_ror:8 row_mask:0xf bank_mask:0xf bound_ctrl:1
	v_pk_fma_f32 v[130:131], v[8:9], v[130:131], v[134:135]
	v_pk_fma_f32 v[74:75], v[10:11], v[74:75], v[132:133]
	v_pk_mul_f32 v[130:131], v[130:131], s[22:23] op_sel_hi:[1,0]
	v_pk_mul_f32 v[74:75], v[74:75], s[22:23] op_sel_hi:[1,0]
	v_cvt_pk_bf16_f32 v129, v130, v131
	s_nop 0
	v_cvt_pk_bf16_f32 v130, v74, v75
	v_lshlrev_b32_e32 v74, 16, v129
	v_and_b32_e32 v75, 0xffff0000, v129
	v_max_f32_e64 v129, |v75|, |v75|
	v_max_f32_e64 v131, |v74|, |v74|
	v_max_f32_e32 v131, v131, v129
	v_lshlrev_b32_e32 v129, 16, v130
	v_and_b32_e32 v130, 0xffff0000, v130
	v_max_f32_e64 v132, |v130|, |v130|
	v_max_f32_e64 v133, |v129|, |v129|
	v_max_f32_e32 v132, v133, v132
	v_max3_f32 v140, v138, v131, v132
	v_lshlrev_b32_e32 v133, 16, v73
	v_lshlrev_b32_e32 v132, 16, v72
	v_and_b32_e32 v73, 0xffff0000, v73
	v_and_b32_e32 v72, 0xffff0000, v72
	v_pk_add_f32 v[134:135], v[132:133], v[72:73]
	v_pk_add_f32 v[72:73], v[132:133], v[72:73] neg_lo:[0,1] neg_hi:[0,1]
	v_mov_b32_e32 v136, v134
	v_pk_mov_b32 v[132:133], v[134:135], v[72:73] op_sel:[1,0]
	v_mov_b32_e32 v137, v73
	v_mov_b32_e32 v138, v134
	v_mov_b32_e32 v139, v72
	v_mov_b32_e32 v72, v135
	v_pk_add_f32 v[132:133], v[136:137], v[132:133]
	v_pk_add_f32 v[72:73], v[138:139], v[72:73] neg_lo:[0,1] neg_hi:[0,1]
	s_nop 0
	v_mov_b32_dpp v136, v132 quad_perm:[1,0,3,2] row_mask:0xf bank_mask:0xf bound_ctrl:1
	v_mov_b32_dpp v137, v133 quad_perm:[1,0,3,2] row_mask:0xf bank_mask:0xf bound_ctrl:1
	v_mov_b32_dpp v134, v72 quad_perm:[1,0,3,2] row_mask:0xf bank_mask:0xf bound_ctrl:1
	v_mov_b32_dpp v135, v73 quad_perm:[1,0,3,2] row_mask:0xf bank_mask:0xf bound_ctrl:1
	v_pk_fma_f32 v[132:133], v[2:3], v[132:133], v[136:137]
	v_pk_fma_f32 v[72:73], v[2:3], v[72:73], v[134:135]
	s_nop 0
	v_mov_b32_dpp v136, v132 quad_perm:[2,3,0,1] row_mask:0xf bank_mask:0xf bound_ctrl:1
	v_mov_b32_dpp v137, v133 quad_perm:[2,3,0,1] row_mask:0xf bank_mask:0xf bound_ctrl:1
	v_mov_b32_dpp v134, v72 quad_perm:[2,3,0,1] row_mask:0xf bank_mask:0xf bound_ctrl:1
	v_mov_b32_dpp v135, v73 quad_perm:[2,3,0,1] row_mask:0xf bank_mask:0xf bound_ctrl:1
	v_pk_fma_f32 v[132:133], v[4:5], v[132:133], v[136:137]
	v_pk_fma_f32 v[72:73], v[4:5], v[72:73], v[134:135]
	v_mov_b32_e32 v136, v132
	v_mov_b32_e32 v137, v133
	v_mov_b32_e32 v134, v72
	v_mov_b32_e32 v135, v73
	v_mov_b32_dpp v136, v136 row_shl:4 row_mask:0xf bank_mask:0x5
	v_mov_b32_dpp v137, v137 row_shl:4 row_mask:0xf bank_mask:0x5
	v_mov_b32_dpp v134, v134 row_shl:4 row_mask:0xf bank_mask:0x5
	v_mov_b32_dpp v135, v135 row_shl:4 row_mask:0xf bank_mask:0x5
	v_mov_b32_dpp v136, v132 row_shr:4 row_mask:0xf bank_mask:0xa
	v_mov_b32_dpp v137, v133 row_shr:4 row_mask:0xf bank_mask:0xa
	v_mov_b32_dpp v134, v72 row_shr:4 row_mask:0xf bank_mask:0xa
	v_mov_b32_dpp v135, v73 row_shr:4 row_mask:0xf bank_mask:0xa
	v_pk_fma_f32 v[132:133], v[6:7], v[132:133], v[136:137]
	v_pk_fma_f32 v[72:73], v[6:7], v[72:73], v[134:135]
	s_nop 0
	v_mov_b32_dpp v136, v132 row_ror:8 row_mask:0xf bank_mask:0xf bound_ctrl:1
	v_mov_b32_dpp v137, v133 row_ror:8 row_mask:0xf bank_mask:0xf bound_ctrl:1
	v_mov_b32_dpp v134, v72 row_ror:8 row_mask:0xf bank_mask:0xf bound_ctrl:1
	v_mov_b32_dpp v135, v73 row_ror:8 row_mask:0xf bank_mask:0xf bound_ctrl:1
	v_pk_fma_f32 v[132:133], v[8:9], v[132:133], v[136:137]
	v_pk_fma_f32 v[72:73], v[10:11], v[72:73], v[134:135]
	v_pk_mul_f32 v[132:133], v[132:133], s[22:23] op_sel_hi:[1,0]
	v_pk_mul_f32 v[72:73], v[72:73], s[22:23] op_sel_hi:[1,0]
	v_cvt_pk_bf16_f32 v131, v132, v133
	s_nop 0
	v_cvt_pk_bf16_f32 v132, v72, v73
	v_lshlrev_b32_e32 v72, 16, v131
	v_and_b32_e32 v73, 0xffff0000, v131
	v_max_f32_e64 v131, |v73|, |v73|
	v_max_f32_e64 v133, |v72|, |v72|
	v_max_f32_e32 v133, v133, v131
	v_lshlrev_b32_e32 v131, 16, v132
	v_and_b32_e32 v132, 0xffff0000, v132
	v_max_f32_e64 v134, |v132|, |v132|
	v_max_f32_e64 v135, |v131|, |v131|
	v_max_f32_e32 v134, v135, v134
	v_max3_f32 v142, v140, v133, v134
	v_lshlrev_b32_e32 v135, 16, v71
	v_lshlrev_b32_e32 v134, 16, v70
	v_and_b32_e32 v71, 0xffff0000, v71
	v_and_b32_e32 v70, 0xffff0000, v70
; __device__ __forceinline__ unsigned cvt_pk_bf16(float lo, float hi) { unsigned r; asm volatile("v_cvt_pk_bf16_f32 %0, %1, %2" : "=v"(r) : "v"(lo), "v"(hi)); return r; }
; __device__ __forceinline__ float bf_lo(unsigned w) { return __uint_as_float(w << 16); }
; __device__ __forceinline__ float bf_hi(unsigned w) { return __uint_as_float(w & 0xffff0000u); }
; __device__ __forceinline__ float xlane1(float t) { return dpp_mov<0xB1, 0xF, true>(0.f, t); }
; __device__ __forceinline__ float xlane2(float t) { return dpp_mov<0x4E, 0xF, true>(0.f, t); }
; __device__ __forceinline__ float xlane4(float t) { const float r = dpp_mov<0x104, 0x5, false>(t, t); return dpp_mov<0x114, 0xA, false>(r, t); }
; __device__ __forceinline__ float xlane8(float t) { return dpp_mov<0x128, 0xF, true>(0.f, t); }
; __device__ __forceinline__ f32x4 rot64(f32x4 t, const RotSigns sg) {
;     { const float p0 = t.x + t.y, p1 = t.x - t.y, p2 = t.z + t.w, p3 = t.z - t.w; t = (f32x4){p0 + p2, p1 + p3, p0 - p2, p1 - p3}; }
;     t = (f32x4){__builtin_fmaf(sg.s1, t.x, xlane1(t.x)), __builtin_fmaf(sg.s1, t.y, xlane1(t.y)), __builtin_fmaf(sg.s1, t.z, xlane1(t.z)), __builtin_fmaf(sg.s1, t.w, xlane1(t.w))};
;     t = (f32x4){__builtin_fmaf(sg.s2, t.x, xlane2(t.x)), __builtin_fmaf(sg.s2, t.y, xlane2(t.y)), __builtin_fmaf(sg.s2, t.z, xlane2(t.z)), __builtin_fmaf(sg.s2, t.w, xlane2(t.w))};
;     t = (f32x4){__builtin_fmaf(sg.s4, t.x, xlane4(t.x)), __builtin_fmaf(sg.s4, t.y, xlane4(t.y)), __builtin_fmaf(sg.s4, t.z, xlane4(t.z)), __builtin_fmaf(sg.s4, t.w, xlane4(t.w))};
;     t = (f32x4){__builtin_fmaf(sg.s8, t.x, xlane8(t.x)), __builtin_fmaf(sg.s8, t.y, xlane8(t.y)), __builtin_fmaf(sg.s8, t.z, xlane8(t.z)), __builtin_fmaf(sg.s8, t.w, xlane8(t.w))};
;     return t * 0.125f;
; __global__ void __launch_bounds__(NWAVES * 64, 2) fwd_kernel(Args args) {
;     ...
;             for (int c = 0; c < DFF / 256; ++c) { const f32x4 t = rot64((f32x4){bf_lo(pk[c].x), bf_hi(pk[c].x), bf_lo(pk[c].y), bf_hi(pk[c].y)}, sg);
;                 pk[c].x = cvt_pk_bf16(t.x, t.y); pk[c].y = cvt_pk_bf16(t.z, t.w);
;                 am = fmaxf(fmaxf(am, fmaxf(fabsf(bf_lo(pk[c].x)), fabsf(bf_hi(pk[c].x)))), fmaxf(fabsf(bf_lo(pk[c].y)), fabsf(bf_hi(pk[c].y)))); }
	v_pk_add_f32 v[136:137], v[134:135], v[70:71]
	v_pk_add_f32 v[70:71], v[134:135], v[70:71] neg_lo:[0,1] neg_hi:[0,1]
	v_mov_b32_e32 v138, v136
	v_pk_mov_b32 v[134:135], v[136:137], v[70:71] op_sel:[1,0]
	v_mov_b32_e32 v139, v71
	v_mov_b32_e32 v140, v136
	v_mov_b32_e32 v141, v70
	v_mov_b32_e32 v70, v137
	v_pk_add_f32 v[134:135], v[138:139], v[134:135]
	v_pk_add_f32 v[70:71], v[140:141], v[70:71] neg_lo:[0,1] neg_hi:[0,1]
	s_nop 0
	v_mov_b32_dpp v138, v134 quad_perm:[1,0,3,2] row_mask:0xf bank_mask:0xf bound_ctrl:1
	v_mov_b32_dpp v139, v135 quad_perm:[1,0,3,2] row_mask:0xf bank_mask:0xf bound_ctrl:1
	v_mov_b32_dpp v136, v70 quad_perm:[1,0,3,2] row_mask:0xf bank_mask:0xf bound_ctrl:1
	v_mov_b32_dpp v137, v71 quad_perm:[1,0,3,2] row_mask:0xf bank_mask:0xf bound_ctrl:1
	v_pk_fma_f32 v[134:135], v[2:3], v[134:135], v[138:139]
	v_pk_fma_f32 v[70:71], v[2:3], v[70:71], v[136:137]
	s_nop 0
	v_mov_b32_dpp v138, v134 quad_perm:[2,3,0,1] row_mask:0xf bank_mask:0xf bound_ctrl:1
	v_mov_b32_dpp v139, v135 quad_perm:[2,3,0,1] row_mask:0xf bank_mask:0xf bound_ctrl:1
	v_mov_b32_dpp v136, v70 quad_perm:[2,3,0,1] row_mask:0xf bank_mask:0xf bound_ctrl:1
	v_mov_b32_dpp v137, v71 quad_perm:[2,3,0,1] row_mask:0xf bank_mask:0xf bound_ctrl:1
	v_pk_fma_f32 v[134:135], v[4:5], v[134:135], v[138:139]
	v_pk_fma_f32 v[70:71], v[4:5], v[70:71], v[136:137]
	v_mov_b32_e32 v138, v134
	v_mov_b32_e32 v139, v135
	v_mov_b32_e32 v136, v70
	v_mov_b32_e32 v137, v71
	v_mov_b32_dpp v138, v138 row_shl:4 row_mask:0xf bank_mask:0x5
	v_mov_b32_dpp v139, v139 row_shl:4 row_mask:0xf bank_mask:0x5
	v_mov_b32_dpp v136, v136 row_shl:4 row_mask:0xf bank_mask:0x5
	v_mov_b32_dpp v137, v137 row_shl:4 row_mask:0xf bank_mask:0x5
	v_mov_b32_dpp v138, v134 row_shr:4 row_mask:0xf bank_mask:0xa
	v_mov_b32_dpp v139, v135 row_shr:4 row_mask:0xf bank_mask:0xa
	v_mov_b32_dpp v136, v70 row_shr:4 row_mask:0xf bank_mask:0xa
	v_mov_b32_dpp v137, v71 row_shr:4 row_mask:0xf bank_mask:0xa
	v_pk_fma_f32 v[134:135], v[6:7], v[134:135], v[138:139]
	v_pk_fma_f32 v[70:71], v[6:7], v[70:71], v[136:137]
	s_nop 0
	v_mov_b32_dpp v138, v134 row_ror:8 row_mask:0xf bank_mask:0xf bound_ctrl:1
	v_mov_b32_dpp v139, v135 row_ror:8 row_mask:0xf bank_mask:0xf bound_ctrl:1
	v_mov_b32_dpp v136, v70 row_ror:8 row_mask:0xf bank_mask:0xf bound_ctrl:1
	v_mov_b32_dpp v137, v71 row_ror:8 row_mask:0xf bank_mask:0xf bound_ctrl:1
	v_pk_fma_f32 v[134:135], v[8:9], v[134:135], v[138:139]
	v_pk_fma_f32 v[70:71], v[10:11], v[70:71], v[136:137]
	v_pk_mul_f32 v[134:135], v[134:135], s[22:23] op_sel_hi:[1,0]
	v_pk_mul_f32 v[70:71], v[70:71], s[22:23] op_sel_hi:[1,0]
	v_cvt_pk_bf16_f32 v133, v134, v135
	s_nop 0
	v_cvt_pk_bf16_f32 v134, v70, v71
	v_lshlrev_b32_e32 v70, 16, v133
	v_and_b32_e32 v71, 0xffff0000, v133
	v_max_f32_e64 v133, |v71|, |v71|
	v_max_f32_e64 v135, |v70|, |v70|
	v_max_f32_e32 v135, v135, v133
	v_lshlrev_b32_e32 v133, 16, v134
	v_and_b32_e32 v134, 0xffff0000, v134
	v_max_f32_e64 v136, |v134|, |v134|
	v_max_f32_e64 v137, |v133|, |v133|
	v_max_f32_e32 v136, v137, v136
	v_max3_f32 v144, v142, v135, v136
	v_lshlrev_b32_e32 v137, 16, v69
	v_lshlrev_b32_e32 v136, 16, v68
	v_and_b32_e32 v69, 0xffff0000, v69
	v_and_b32_e32 v68, 0xffff0000, v68
	v_pk_add_f32 v[138:139], v[136:137], v[68:69]
	v_pk_add_f32 v[68:69], v[136:137], v[68:69] neg_lo:[0,1] neg_hi:[0,1]
	v_mov_b32_e32 v140, v138
	v_pk_mov_b32 v[136:137], v[138:139], v[68:69] op_sel:[1,0]
	v_mov_b32_e32 v141, v69
	v_mov_b32_e32 v142, v138
	v_mov_b32_e32 v143, v68
	v_mov_b32_e32 v68, v139
	v_pk_add_f32 v[136:137], v[140:141], v[136:137]
	v_pk_add_f32 v[68:69], v[142:143], v[68:69] neg_lo:[0,1] neg_hi:[0,1]
	s_nop 0
	v_mov_b32_dpp v140, v136 quad_perm:[1,0,3,2] row_mask:0xf bank_mask:0xf bound_ctrl:1
	v_mov_b32_dpp v141, v137 quad_perm:[1,0,3,2] row_mask:0xf bank_mask:0xf bound_ctrl:1
	v_mov_b32_dpp v138, v68 quad_perm:[1,0,3,2] row_mask:0xf bank_mask:0xf bound_ctrl:1
	v_mov_b32_dpp v139, v69 quad_perm:[1,0,3,2] row_mask:0xf bank_mask:0xf bound_ctrl:1
	v_pk_fma_f32 v[136:137], v[2:3], v[136:137], v[140:141]
	v_pk_fma_f32 v[68:69], v[2:3], v[68:69], v[138:139]
	s_nop 0
	v_mov_b32_dpp v140, v136 quad_perm:[2,3,0,1] row_mask:0xf bank_mask:0xf bound_ctrl:1
	v_mov_b32_dpp v141, v137 quad_perm:[2,3,0,1] row_mask:0xf bank_mask:0xf bound_ctrl:1
	v_mov_b32_dpp v138, v68 quad_perm:[2,3,0,1] row_mask:0xf bank_mask:0xf bound_ctrl:1
	v_mov_b32_dpp v139, v69 quad_perm:[2,3,0,1] row_mask:0xf bank_mask:0xf bound_ctrl:1
	v_pk_fma_f32 v[136:137], v[4:5], v[136:137], v[140:141]
	v_pk_fma_f32 v[68:69], v[4:5], v[68:69], v[138:139]
	v_mov_b32_e32 v140, v136
	v_mov_b32_e32 v141, v137
	v_mov_b32_e32 v138, v68
	v_mov_b32_e32 v139, v69
	v_mov_b32_dpp v140, v140 row_shl:4 row_mask:0xf bank_mask:0x5
	v_mov_b32_dpp v141, v141 row_shl:4 row_mask:0xf bank_mask:0x5
	v_mov_b32_dpp v138, v138 row_shl:4 row_mask:0xf bank_mask:0x5
	v_mov_b32_dpp v139, v139 row_shl:4 row_mask:0xf bank_mask:0x5
	v_mov_b32_dpp v140, v136 row_shr:4 row_mask:0xf bank_mask:0xa
	v_mov_b32_dpp v141, v137 row_shr:4 row_mask:0xf bank_mask:0xa
	v_mov_b32_dpp v138, v68 row_shr:4 row_mask:0xf bank_mask:0xa
	v_mov_b32_dpp v139, v69 row_shr:4 row_mask:0xf bank_mask:0xa
	v_pk_fma_f32 v[136:137], v[6:7], v[136:137], v[140:141]
	v_pk_fma_f32 v[68:69], v[6:7], v[68:69], v[138:139]
	s_nop 0
	v_mov_b32_dpp v140, v136 row_ror:8 row_mask:0xf bank_mask:0xf bound_ctrl:1
	v_mov_b32_dpp v141, v137 row_ror:8 row_mask:0xf bank_mask:0xf bound_ctrl:1
	v_mov_b32_dpp v138, v68 row_ror:8 row_mask:0xf bank_mask:0xf bound_ctrl:1
	v_mov_b32_dpp v139, v69 row_ror:8 row_mask:0xf bank_mask:0xf bound_ctrl:1
	v_pk_fma_f32 v[136:137], v[8:9], v[136:137], v[140:141]
; __device__ __forceinline__ unsigned cvt_pk_bf16(float lo, float hi) { unsigned r; asm volatile("v_cvt_pk_bf16_f32 %0, %1, %2" : "=v"(r) : "v"(lo), "v"(hi)); return r; }
; __device__ __forceinline__ float bf_lo(unsigned w) { return __uint_as_float(w << 16); }
; __device__ __forceinline__ float bf_hi(unsigned w) { return __uint_as_float(w & 0xffff0000u); }
; __device__ __forceinline__ float xlane1(float t) { return dpp_mov<0xB1, 0xF, true>(0.f, t); }
; __device__ __forceinline__ float xlane2(float t) { return dpp_mov<0x4E, 0xF, true>(0.f, t); }
; __device__ __forceinline__ float xlane4(float t) { const float r = dpp_mov<0x104, 0x5, false>(t, t); return dpp_mov<0x114, 0xA, false>(r, t); }
; __device__ __forceinline__ float xlane8(float t) { return dpp_mov<0x128, 0xF, true>(0.f, t); }
; __device__ __forceinline__ f32x4 rot64(f32x4 t, const RotSigns sg) {
;     { const float p0 = t.x + t.y, p1 = t.x - t.y, p2 = t.z + t.w, p3 = t.z - t.w; t = (f32x4){p0 + p2, p1 + p3, p0 - p2, p1 - p3}; }
;     t = (f32x4){__builtin_fmaf(sg.s1, t.x, xlane1(t.x)), __builtin_fmaf(sg.s1, t.y, xlane1(t.y)), __builtin_fmaf(sg.s1, t.z, xlane1(t.z)), __builtin_fmaf(sg.s1, t.w, xlane1(t.w))};
;     t = (f32x4){__builtin_fmaf(sg.s2, t.x, xlane2(t.x)), __builtin_fmaf(sg.s2, t.y, xlane2(t.y)), __builtin_fmaf(sg.s2, t.z, xlane2(t.z)), __builtin_fmaf(sg.s2, t.w, xlane2(t.w))};
;     t = (f32x4){__builtin_fmaf(sg.s4, t.x, xlane4(t.x)), __builtin_fmaf(sg.s4, t.y, xlane4(t.y)), __builtin_fmaf(sg.s4, t.z, xlane4(t.z)), __builtin_fmaf(sg.s4, t.w, xlane4(t.w))};
;     t = (f32x4){__builtin_fmaf(sg.s8, t.x, xlane8(t.x)), __builtin_fmaf(sg.s8, t.y, xlane8(t.y)), __builtin_fmaf(sg.s8, t.z, xlane8(t.z)), __builtin_fmaf(sg.s8, t.w, xlane8(t.w))};
;     return t * 0.125f;
; __global__ void __launch_bounds__(NWAVES * 64, 2) fwd_kernel(Args args) {
;     ...
;             for (int c = 0; c < DFF / 256; ++c) { const f32x4 t = rot64((f32x4){bf_lo(pk[c].x), bf_hi(pk[c].x), bf_lo(pk[c].y), bf_hi(pk[c].y)}, sg);
;                 pk[c].x = cvt_pk_bf16(t.x, t.y); pk[c].y = cvt_pk_bf16(t.z, t.w);
;                 am = fmaxf(fmaxf(am, fmaxf(fabsf(bf_lo(pk[c].x)), fabsf(bf_hi(pk[c].x)))), fmaxf(fabsf(bf_lo(pk[c].y)), fabsf(bf_hi(pk[c].y)))); }
	v_pk_fma_f32 v[68:69], v[10:11], v[68:69], v[138:139]
	v_pk_mul_f32 v[136:137], v[136:137], s[22:23] op_sel_hi:[1,0]
	v_pk_mul_f32 v[68:69], v[68:69], s[22:23] op_sel_hi:[1,0]
	v_cvt_pk_bf16_f32 v135, v136, v137
	s_nop 0
	v_cvt_pk_bf16_f32 v136, v68, v69
	v_lshlrev_b32_e32 v68, 16, v135
	v_and_b32_e32 v69, 0xffff0000, v135
	v_max_f32_e64 v135, |v69|, |v69|
	v_max_f32_e64 v137, |v68|, |v68|
	v_max_f32_e32 v137, v137, v135
	v_lshlrev_b32_e32 v135, 16, v136
	v_and_b32_e32 v136, 0xffff0000, v136
	v_max_f32_e64 v138, |v136|, |v136|
	v_max_f32_e64 v139, |v135|, |v135|
	v_max_f32_e32 v138, v139, v138
	v_max3_f32 v146, v144, v137, v138
	v_lshlrev_b32_e32 v139, 16, v67
	v_lshlrev_b32_e32 v138, 16, v66
	v_and_b32_e32 v67, 0xffff0000, v67
	v_and_b32_e32 v66, 0xffff0000, v66
	v_pk_add_f32 v[140:141], v[138:139], v[66:67]
	v_pk_add_f32 v[66:67], v[138:139], v[66:67] neg_lo:[0,1] neg_hi:[0,1]
	v_mov_b32_e32 v142, v140
	v_pk_mov_b32 v[138:139], v[140:141], v[66:67] op_sel:[1,0]
	v_mov_b32_e32 v143, v67
	v_mov_b32_e32 v144, v140
	v_mov_b32_e32 v145, v66
	v_mov_b32_e32 v66, v141
	v_pk_add_f32 v[138:139], v[142:143], v[138:139]
	v_pk_add_f32 v[66:67], v[144:145], v[66:67] neg_lo:[0,1] neg_hi:[0,1]
	s_nop 0
	v_mov_b32_dpp v142, v138 quad_perm:[1,0,3,2] row_mask:0xf bank_mask:0xf bound_ctrl:1
	v_mov_b32_dpp v143, v139 quad_perm:[1,0,3,2] row_mask:0xf bank_mask:0xf bound_ctrl:1
	v_mov_b32_dpp v140, v66 quad_perm:[1,0,3,2] row_mask:0xf bank_mask:0xf bound_ctrl:1
	v_mov_b32_dpp v141, v67 quad_perm:[1,0,3,2] row_mask:0xf bank_mask:0xf bound_ctrl:1
	v_pk_fma_f32 v[138:139], v[2:3], v[138:139], v[142:143]
	v_pk_fma_f32 v[66:67], v[2:3], v[66:67], v[140:141]
	s_nop 0
	v_mov_b32_dpp v142, v138 quad_perm:[2,3,0,1] row_mask:0xf bank_mask:0xf bound_ctrl:1
	v_mov_b32_dpp v143, v139 quad_perm:[2,3,0,1] row_mask:0xf bank_mask:0xf bound_ctrl:1
	v_mov_b32_dpp v140, v66 quad_perm:[2,3,0,1] row_mask:0xf bank_mask:0xf bound_ctrl:1
	v_mov_b32_dpp v141, v67 quad_perm:[2,3,0,1] row_mask:0xf bank_mask:0xf bound_ctrl:1
	v_pk_fma_f32 v[138:139], v[4:5], v[138:139], v[142:143]
	v_pk_fma_f32 v[66:67], v[4:5], v[66:67], v[140:141]
	v_mov_b32_e32 v142, v138
	v_mov_b32_e32 v143, v139
	v_mov_b32_e32 v140, v66
	v_mov_b32_e32 v141, v67
	v_mov_b32_dpp v142, v142 row_shl:4 row_mask:0xf bank_mask:0x5
	v_mov_b32_dpp v143, v143 row_shl:4 row_mask:0xf bank_mask:0x5
	v_mov_b32_dpp v140, v140 row_shl:4 row_mask:0xf bank_mask:0x5
	v_mov_b32_dpp v141, v141 row_shl:4 row_mask:0xf bank_mask:0x5
	v_mov_b32_dpp v142, v138 row_shr:4 row_mask:0xf bank_mask:0xa
	v_mov_b32_dpp v143, v139 row_shr:4 row_mask:0xf bank_mask:0xa
	v_mov_b32_dpp v140, v66 row_shr:4 row_mask:0xf bank_mask:0xa
	v_mov_b32_dpp v141, v67 row_shr:4 row_mask:0xf bank_mask:0xa
	v_pk_fma_f32 v[138:139], v[6:7], v[138:139], v[142:143]
	v_pk_fma_f32 v[66:67], v[6:7], v[66:67], v[140:141]
	s_nop 0
	v_mov_b32_dpp v142, v138 row_ror:8 row_mask:0xf bank_mask:0xf bound_ctrl:1
	v_mov_b32_dpp v143, v139 row_ror:8 row_mask:0xf bank_mask:0xf bound_ctrl:1
	v_mov_b32_dpp v140, v66 row_ror:8 row_mask:0xf bank_mask:0xf bound_ctrl:1
	v_mov_b32_dpp v141, v67 row_ror:8 row_mask:0xf bank_mask:0xf bound_ctrl:1
	v_pk_fma_f32 v[138:139], v[8:9], v[138:139], v[142:143]
	v_pk_fma_f32 v[66:67], v[10:11], v[66:67], v[140:141]
	v_pk_mul_f32 v[138:139], v[138:139], s[22:23] op_sel_hi:[1,0]
	v_pk_mul_f32 v[66:67], v[66:67], s[22:23] op_sel_hi:[1,0]
	v_cvt_pk_bf16_f32 v137, v138, v139
	s_nop 0
	v_cvt_pk_bf16_f32 v138, v66, v67
	v_lshlrev_b32_e32 v66, 16, v137
	v_and_b32_e32 v67, 0xffff0000, v137
	v_max_f32_e64 v137, |v67|, |v67|
	v_max_f32_e64 v139, |v66|, |v66|
	v_max_f32_e32 v139, v139, v137
	v_lshlrev_b32_e32 v137, 16, v138
	v_and_b32_e32 v138, 0xffff0000, v138
	v_max_f32_e64 v140, |v138|, |v138|
	v_max_f32_e64 v141, |v137|, |v137|
	v_max_f32_e32 v140, v141, v140
	v_max3_f32 v148, v146, v139, v140
	v_lshlrev_b32_e32 v141, 16, v65
	v_lshlrev_b32_e32 v140, 16, v64
	v_and_b32_e32 v65, 0xffff0000, v65
	v_and_b32_e32 v64, 0xffff0000, v64
	v_pk_add_f32 v[142:143], v[140:141], v[64:65]
	v_pk_add_f32 v[64:65], v[140:141], v[64:65] neg_lo:[0,1] neg_hi:[0,1]
	v_mov_b32_e32 v144, v142
	v_pk_mov_b32 v[140:141], v[142:143], v[64:65] op_sel:[1,0]
	v_mov_b32_e32 v145, v65
	v_mov_b32_e32 v146, v142
	v_mov_b32_e32 v147, v64
	v_mov_b32_e32 v64, v143
	v_pk_add_f32 v[140:141], v[144:145], v[140:141]
	v_pk_add_f32 v[64:65], v[146:147], v[64:65] neg_lo:[0,1] neg_hi:[0,1]
	s_nop 0
	v_mov_b32_dpp v144, v140 quad_perm:[1,0,3,2] row_mask:0xf bank_mask:0xf bound_ctrl:1
	v_mov_b32_dpp v145, v141 quad_perm:[1,0,3,2] row_mask:0xf bank_mask:0xf bound_ctrl:1
	v_mov_b32_dpp v142, v64 quad_perm:[1,0,3,2] row_mask:0xf bank_mask:0xf bound_ctrl:1
	v_mov_b32_dpp v143, v65 quad_perm:[1,0,3,2] row_mask:0xf bank_mask:0xf bound_ctrl:1
	v_pk_fma_f32 v[140:141], v[2:3], v[140:141], v[144:145]
	v_pk_fma_f32 v[64:65], v[2:3], v[64:65], v[142:143]
	s_nop 0
	v_mov_b32_dpp v144, v140 quad_perm:[2,3,0,1] row_mask:0xf bank_mask:0xf bound_ctrl:1
	v_mov_b32_dpp v145, v141 quad_perm:[2,3,0,1] row_mask:0xf bank_mask:0xf bound_ctrl:1
	v_mov_b32_dpp v142, v64 quad_perm:[2,3,0,1] row_mask:0xf bank_mask:0xf bound_ctrl:1
	v_mov_b32_dpp v143, v65 quad_perm:[2,3,0,1] row_mask:0xf bank_mask:0xf bound_ctrl:1
	v_pk_fma_f32 v[140:141], v[4:5], v[140:141], v[144:145]
	v_pk_fma_f32 v[64:65], v[4:5], v[64:65], v[142:143]
	v_mov_b32_e32 v144, v140
	v_mov_b32_e32 v145, v141
	v_mov_b32_e32 v142, v64
	v_mov_b32_e32 v143, v65
	v_mov_b32_dpp v144, v144 row_shl:4 row_mask:0xf bank_mask:0x5
	v_mov_b32_dpp v145, v145 row_shl:4 row_mask:0xf bank_mask:0x5
	v_mov_b32_dpp v142, v142 row_shl:4 row_mask:0xf bank_mask:0x5
; __device__ __forceinline__ unsigned cvt_pk_bf16(float lo, float hi) { unsigned r; asm volatile("v_cvt_pk_bf16_f32 %0, %1, %2" : "=v"(r) : "v"(lo), "v"(hi)); return r; }
; __device__ __forceinline__ float bf_lo(unsigned w) { return __uint_as_float(w << 16); }
; __device__ __forceinline__ float bf_hi(unsigned w) { return __uint_as_float(w & 0xffff0000u); }
; __device__ __forceinline__ float xlane1(float t) { return dpp_mov<0xB1, 0xF, true>(0.f, t); }
; __device__ __forceinline__ float xlane2(float t) { return dpp_mov<0x4E, 0xF, true>(0.f, t); }
; __device__ __forceinline__ float xlane4(float t) { const float r = dpp_mov<0x104, 0x5, false>(t, t); return dpp_mov<0x114, 0xA, false>(r, t); }
; __device__ __forceinline__ float xlane8(float t) { return dpp_mov<0x128, 0xF, true>(0.f, t); }
; __device__ __forceinline__ f32x4 rot64(f32x4 t, const RotSigns sg) {
;     { const float p0 = t.x + t.y, p1 = t.x - t.y, p2 = t.z + t.w, p3 = t.z - t.w; t = (f32x4){p0 + p2, p1 + p3, p0 - p2, p1 - p3}; }
;     t = (f32x4){__builtin_fmaf(sg.s1, t.x, xlane1(t.x)), __builtin_fmaf(sg.s1, t.y, xlane1(t.y)), __builtin_fmaf(sg.s1, t.z, xlane1(t.z)), __builtin_fmaf(sg.s1, t.w, xlane1(t.w))};
;     t = (f32x4){__builtin_fmaf(sg.s2, t.x, xlane2(t.x)), __builtin_fmaf(sg.s2, t.y, xlane2(t.y)), __builtin_fmaf(sg.s2, t.z, xlane2(t.z)), __builtin_fmaf(sg.s2, t.w, xlane2(t.w))};
;     t = (f32x4){__builtin_fmaf(sg.s4, t.x, xlane4(t.x)), __builtin_fmaf(sg.s4, t.y, xlane4(t.y)), __builtin_fmaf(sg.s4, t.z, xlane4(t.z)), __builtin_fmaf(sg.s4, t.w, xlane4(t.w))};
;     t = (f32x4){__builtin_fmaf(sg.s8, t.x, xlane8(t.x)), __builtin_fmaf(sg.s8, t.y, xlane8(t.y)), __builtin_fmaf(sg.s8, t.z, xlane8(t.z)), __builtin_fmaf(sg.s8, t.w, xlane8(t.w))};
;     return t * 0.125f;
; __global__ void __launch_bounds__(NWAVES * 64, 2) fwd_kernel(Args args) {
;     ...
;             for (int c = 0; c < DFF / 256; ++c) { const f32x4 t = rot64((f32x4){bf_lo(pk[c].x), bf_hi(pk[c].x), bf_lo(pk[c].y), bf_hi(pk[c].y)}, sg);
;                 pk[c].x = cvt_pk_bf16(t.x, t.y); pk[c].y = cvt_pk_bf16(t.z, t.w);
;                 am = fmaxf(fmaxf(am, fmaxf(fabsf(bf_lo(pk[c].x)), fabsf(bf_hi(pk[c].x)))), fmaxf(fabsf(bf_lo(pk[c].y)), fabsf(bf_hi(pk[c].y)))); }
	v_mov_b32_dpp v143, v143 row_shl:4 row_mask:0xf bank_mask:0x5
	v_mov_b32_dpp v144, v140 row_shr:4 row_mask:0xf bank_mask:0xa
	v_mov_b32_dpp v145, v141 row_shr:4 row_mask:0xf bank_mask:0xa
	v_mov_b32_dpp v142, v64 row_shr:4 row_mask:0xf bank_mask:0xa
	v_mov_b32_dpp v143, v65 row_shr:4 row_mask:0xf bank_mask:0xa
	v_pk_fma_f32 v[140:141], v[6:7], v[140:141], v[144:145]
	v_pk_fma_f32 v[64:65], v[6:7], v[64:65], v[142:143]
	s_nop 0
	v_mov_b32_dpp v144, v140 row_ror:8 row_mask:0xf bank_mask:0xf bound_ctrl:1
	v_mov_b32_dpp v145, v141 row_ror:8 row_mask:0xf bank_mask:0xf bound_ctrl:1
	v_mov_b32_dpp v142, v64 row_ror:8 row_mask:0xf bank_mask:0xf bound_ctrl:1
	v_mov_b32_dpp v143, v65 row_ror:8 row_mask:0xf bank_mask:0xf bound_ctrl:1
	v_pk_fma_f32 v[140:141], v[8:9], v[140:141], v[144:145]
	v_pk_fma_f32 v[64:65], v[10:11], v[64:65], v[142:143]
	v_pk_mul_f32 v[140:141], v[140:141], s[22:23] op_sel_hi:[1,0]
	v_pk_mul_f32 v[64:65], v[64:65], s[22:23] op_sel_hi:[1,0]
	v_cvt_pk_bf16_f32 v139, v140, v141
	s_nop 0
	v_cvt_pk_bf16_f32 v140, v64, v65
	v_lshlrev_b32_e32 v64, 16, v139
	v_and_b32_e32 v65, 0xffff0000, v139
	v_max_f32_e64 v139, |v65|, |v65|
	v_max_f32_e64 v141, |v64|, |v64|
	v_max_f32_e32 v141, v141, v139
	v_lshlrev_b32_e32 v139, 16, v140
	v_and_b32_e32 v140, 0xffff0000, v140
	v_max_f32_e64 v142, |v140|, |v140|
	v_max_f32_e64 v143, |v139|, |v139|
	v_max_f32_e32 v142, v143, v142
	v_max3_f32 v150, v148, v141, v142
	v_lshlrev_b32_e32 v143, 16, v63
	v_lshlrev_b32_e32 v142, 16, v62
	v_and_b32_e32 v63, 0xffff0000, v63
	v_and_b32_e32 v62, 0xffff0000, v62
	v_pk_add_f32 v[144:145], v[142:143], v[62:63]
	v_pk_add_f32 v[62:63], v[142:143], v[62:63] neg_lo:[0,1] neg_hi:[0,1]
	v_mov_b32_e32 v146, v144
	v_pk_mov_b32 v[142:143], v[144:145], v[62:63] op_sel:[1,0]
	v_mov_b32_e32 v147, v63
	v_mov_b32_e32 v148, v144
	v_mov_b32_e32 v149, v62
	v_mov_b32_e32 v62, v145
	v_pk_add_f32 v[142:143], v[146:147], v[142:143]
	v_pk_add_f32 v[62:63], v[148:149], v[62:63] neg_lo:[0,1] neg_hi:[0,1]
	s_nop 0
	v_mov_b32_dpp v146, v142 quad_perm:[1,0,3,2] row_mask:0xf bank_mask:0xf bound_ctrl:1
	v_mov_b32_dpp v147, v143 quad_perm:[1,0,3,2] row_mask:0xf bank_mask:0xf bound_ctrl:1
	v_mov_b32_dpp v144, v62 quad_perm:[1,0,3,2] row_mask:0xf bank_mask:0xf bound_ctrl:1
	v_mov_b32_dpp v145, v63 quad_perm:[1,0,3,2] row_mask:0xf bank_mask:0xf bound_ctrl:1
	v_pk_fma_f32 v[142:143], v[2:3], v[142:143], v[146:147]
	v_pk_fma_f32 v[62:63], v[2:3], v[62:63], v[144:145]
	s_nop 0
	v_mov_b32_dpp v146, v142 quad_perm:[2,3,0,1] row_mask:0xf bank_mask:0xf bound_ctrl:1
	v_mov_b32_dpp v147, v143 quad_perm:[2,3,0,1] row_mask:0xf bank_mask:0xf bound_ctrl:1
	v_mov_b32_dpp v144, v62 quad_perm:[2,3,0,1] row_mask:0xf bank_mask:0xf bound_ctrl:1
	v_mov_b32_dpp v145, v63 quad_perm:[2,3,0,1] row_mask:0xf bank_mask:0xf bound_ctrl:1
	v_pk_fma_f32 v[142:143], v[4:5], v[142:143], v[146:147]
	v_pk_fma_f32 v[62:63], v[4:5], v[62:63], v[144:145]
	v_mov_b32_e32 v146, v142
	v_mov_b32_e32 v147, v143
	v_mov_b32_e32 v144, v62
	v_mov_b32_e32 v145, v63
	v_mov_b32_dpp v146, v146 row_shl:4 row_mask:0xf bank_mask:0x5
	v_mov_b32_dpp v147, v147 row_shl:4 row_mask:0xf bank_mask:0x5
	v_mov_b32_dpp v144, v144 row_shl:4 row_mask:0xf bank_mask:0x5
	v_mov_b32_dpp v145, v145 row_shl:4 row_mask:0xf bank_mask:0x5
	v_mov_b32_dpp v146, v142 row_shr:4 row_mask:0xf bank_mask:0xa
	v_mov_b32_dpp v147, v143 row_shr:4 row_mask:0xf bank_mask:0xa
	v_mov_b32_dpp v144, v62 row_shr:4 row_mask:0xf bank_mask:0xa
	v_mov_b32_dpp v145, v63 row_shr:4 row_mask:0xf bank_mask:0xa
	v_pk_fma_f32 v[142:143], v[6:7], v[142:143], v[146:147]
	v_pk_fma_f32 v[62:63], v[6:7], v[62:63], v[144:145]
	s_nop 0
	v_mov_b32_dpp v146, v142 row_ror:8 row_mask:0xf bank_mask:0xf bound_ctrl:1
	v_mov_b32_dpp v147, v143 row_ror:8 row_mask:0xf bank_mask:0xf bound_ctrl:1
	v_mov_b32_dpp v144, v62 row_ror:8 row_mask:0xf bank_mask:0xf bound_ctrl:1
	v_mov_b32_dpp v145, v63 row_ror:8 row_mask:0xf bank_mask:0xf bound_ctrl:1
	v_pk_fma_f32 v[142:143], v[8:9], v[142:143], v[146:147]
	v_pk_fma_f32 v[62:63], v[10:11], v[62:63], v[144:145]
	v_pk_mul_f32 v[142:143], v[142:143], s[22:23] op_sel_hi:[1,0]
	v_pk_mul_f32 v[62:63], v[62:63], s[22:23] op_sel_hi:[1,0]
	v_cvt_pk_bf16_f32 v141, v142, v143
	s_nop 0
	v_cvt_pk_bf16_f32 v142, v62, v63
	v_lshlrev_b32_e32 v62, 16, v141
	v_and_b32_e32 v63, 0xffff0000, v141
	v_max_f32_e64 v141, |v63|, |v63|
	v_max_f32_e64 v143, |v62|, |v62|
	v_max_f32_e32 v143, v143, v141
	v_lshlrev_b32_e32 v141, 16, v142
	v_and_b32_e32 v142, 0xffff0000, v142
	v_max_f32_e64 v144, |v142|, |v142|
	v_max_f32_e64 v145, |v141|, |v141|
	v_max_f32_e32 v144, v145, v144
	v_max3_f32 v152, v150, v143, v144
	v_lshlrev_b32_e32 v145, 16, v61
	v_lshlrev_b32_e32 v144, 16, v60
	v_and_b32_e32 v61, 0xffff0000, v61
	v_and_b32_e32 v60, 0xffff0000, v60
	v_pk_add_f32 v[146:147], v[144:145], v[60:61]
	v_pk_add_f32 v[60:61], v[144:145], v[60:61] neg_lo:[0,1] neg_hi:[0,1]
	v_mov_b32_e32 v148, v146
	v_pk_mov_b32 v[144:145], v[146:147], v[60:61] op_sel:[1,0]
	v_mov_b32_e32 v149, v61
	v_mov_b32_e32 v150, v146
	v_mov_b32_e32 v151, v60
	v_mov_b32_e32 v60, v147
	v_pk_add_f32 v[144:145], v[148:149], v[144:145]
	v_pk_add_f32 v[60:61], v[150:151], v[60:61] neg_lo:[0,1] neg_hi:[0,1]
	s_nop 0
	v_mov_b32_dpp v148, v144 quad_perm:[1,0,3,2] row_mask:0xf bank_mask:0xf bound_ctrl:1
	v_mov_b32_dpp v149, v145 quad_perm:[1,0,3,2] row_mask:0xf bank_mask:0xf bound_ctrl:1
	v_mov_b32_dpp v146, v60 quad_perm:[1,0,3,2] row_mask:0xf bank_mask:0xf bound_ctrl:1
	v_mov_b32_dpp v147, v61 quad_perm:[1,0,3,2] row_mask:0xf bank_mask:0xf bound_ctrl:1
	v_pk_fma_f32 v[144:145], v[2:3], v[144:145], v[148:149]
	v_pk_fma_f32 v[60:61], v[2:3], v[60:61], v[146:147]
; __device__ __forceinline__ unsigned cvt_pk_bf16(float lo, float hi) { unsigned r; asm volatile("v_cvt_pk_bf16_f32 %0, %1, %2" : "=v"(r) : "v"(lo), "v"(hi)); return r; }
; __device__ __forceinline__ float bf_lo(unsigned w) { return __uint_as_float(w << 16); }
; __device__ __forceinline__ float bf_hi(unsigned w) { return __uint_as_float(w & 0xffff0000u); }
; __device__ __forceinline__ float xlane1(float t) { return dpp_mov<0xB1, 0xF, true>(0.f, t); }
; __device__ __forceinline__ float xlane2(float t) { return dpp_mov<0x4E, 0xF, true>(0.f, t); }
; __device__ __forceinline__ float xlane4(float t) { const float r = dpp_mov<0x104, 0x5, false>(t, t); return dpp_mov<0x114, 0xA, false>(r, t); }
; __device__ __forceinline__ float xlane8(float t) { return dpp_mov<0x128, 0xF, true>(0.f, t); }
; __device__ __forceinline__ f32x4 rot64(f32x4 t, const RotSigns sg) {
;     { const float p0 = t.x + t.y, p1 = t.x - t.y, p2 = t.z + t.w, p3 = t.z - t.w; t = (f32x4){p0 + p2, p1 + p3, p0 - p2, p1 - p3}; }
;     t = (f32x4){__builtin_fmaf(sg.s1, t.x, xlane1(t.x)), __builtin_fmaf(sg.s1, t.y, xlane1(t.y)), __builtin_fmaf(sg.s1, t.z, xlane1(t.z)), __builtin_fmaf(sg.s1, t.w, xlane1(t.w))};
;     t = (f32x4){__builtin_fmaf(sg.s2, t.x, xlane2(t.x)), __builtin_fmaf(sg.s2, t.y, xlane2(t.y)), __builtin_fmaf(sg.s2, t.z, xlane2(t.z)), __builtin_fmaf(sg.s2, t.w, xlane2(t.w))};
;     t = (f32x4){__builtin_fmaf(sg.s4, t.x, xlane4(t.x)), __builtin_fmaf(sg.s4, t.y, xlane4(t.y)), __builtin_fmaf(sg.s4, t.z, xlane4(t.z)), __builtin_fmaf(sg.s4, t.w, xlane4(t.w))};
;     t = (f32x4){__builtin_fmaf(sg.s8, t.x, xlane8(t.x)), __builtin_fmaf(sg.s8, t.y, xlane8(t.y)), __builtin_fmaf(sg.s8, t.z, xlane8(t.z)), __builtin_fmaf(sg.s8, t.w, xlane8(t.w))};
;     return t * 0.125f;
; __global__ void __launch_bounds__(NWAVES * 64, 2) fwd_kernel(Args args) {
;     ...
;             for (int c = 0; c < DFF / 256; ++c) { const f32x4 t = rot64((f32x4){bf_lo(pk[c].x), bf_hi(pk[c].x), bf_lo(pk[c].y), bf_hi(pk[c].y)}, sg);
;                 pk[c].x = cvt_pk_bf16(t.x, t.y); pk[c].y = cvt_pk_bf16(t.z, t.w);
;                 am = fmaxf(fmaxf(am, fmaxf(fabsf(bf_lo(pk[c].x)), fabsf(bf_hi(pk[c].x)))), fmaxf(fabsf(bf_lo(pk[c].y)), fabsf(bf_hi(pk[c].y)))); }
	s_nop 0
	v_mov_b32_dpp v148, v144 quad_perm:[2,3,0,1] row_mask:0xf bank_mask:0xf bound_ctrl:1
	v_mov_b32_dpp v149, v145 quad_perm:[2,3,0,1] row_mask:0xf bank_mask:0xf bound_ctrl:1
	v_mov_b32_dpp v146, v60 quad_perm:[2,3,0,1] row_mask:0xf bank_mask:0xf bound_ctrl:1
	v_mov_b32_dpp v147, v61 quad_perm:[2,3,0,1] row_mask:0xf bank_mask:0xf bound_ctrl:1
	v_pk_fma_f32 v[144:145], v[4:5], v[144:145], v[148:149]
	v_pk_fma_f32 v[60:61], v[4:5], v[60:61], v[146:147]
	v_mov_b32_e32 v148, v144
	v_mov_b32_e32 v149, v145
	v_mov_b32_e32 v146, v60
	v_mov_b32_e32 v147, v61
	v_mov_b32_dpp v148, v148 row_shl:4 row_mask:0xf bank_mask:0x5
	v_mov_b32_dpp v149, v149 row_shl:4 row_mask:0xf bank_mask:0x5
	v_mov_b32_dpp v146, v146 row_shl:4 row_mask:0xf bank_mask:0x5
	v_mov_b32_dpp v147, v147 row_shl:4 row_mask:0xf bank_mask:0x5
	v_mov_b32_dpp v148, v144 row_shr:4 row_mask:0xf bank_mask:0xa
	v_mov_b32_dpp v149, v145 row_shr:4 row_mask:0xf bank_mask:0xa
	v_mov_b32_dpp v146, v60 row_shr:4 row_mask:0xf bank_mask:0xa
	v_mov_b32_dpp v147, v61 row_shr:4 row_mask:0xf bank_mask:0xa
	v_pk_fma_f32 v[144:145], v[6:7], v[144:145], v[148:149]
	v_pk_fma_f32 v[60:61], v[6:7], v[60:61], v[146:147]
	s_nop 0
	v_mov_b32_dpp v148, v144 row_ror:8 row_mask:0xf bank_mask:0xf bound_ctrl:1
	v_mov_b32_dpp v149, v145 row_ror:8 row_mask:0xf bank_mask:0xf bound_ctrl:1
	v_mov_b32_dpp v146, v60 row_ror:8 row_mask:0xf bank_mask:0xf bound_ctrl:1
	v_mov_b32_dpp v147, v61 row_ror:8 row_mask:0xf bank_mask:0xf bound_ctrl:1
	v_pk_fma_f32 v[144:145], v[8:9], v[144:145], v[148:149]
	v_pk_fma_f32 v[60:61], v[10:11], v[60:61], v[146:147]
	v_pk_mul_f32 v[144:145], v[144:145], s[22:23] op_sel_hi:[1,0]
	v_pk_mul_f32 v[60:61], v[60:61], s[22:23] op_sel_hi:[1,0]
	v_cvt_pk_bf16_f32 v143, v144, v145
	s_nop 0
	v_cvt_pk_bf16_f32 v144, v60, v61
	v_lshlrev_b32_e32 v60, 16, v143
	v_and_b32_e32 v61, 0xffff0000, v143
	v_max_f32_e64 v143, |v61|, |v61|
	v_max_f32_e64 v145, |v60|, |v60|
	v_max_f32_e32 v145, v145, v143
	v_lshlrev_b32_e32 v143, 16, v144
	v_and_b32_e32 v144, 0xffff0000, v144
	v_max_f32_e64 v146, |v144|, |v144|
	v_max_f32_e64 v147, |v143|, |v143|
	v_max_f32_e32 v146, v147, v146
	v_max3_f32 v154, v152, v145, v146
	v_lshlrev_b32_e32 v147, 16, v59
	v_lshlrev_b32_e32 v146, 16, v58
	v_and_b32_e32 v59, 0xffff0000, v59
	v_and_b32_e32 v58, 0xffff0000, v58
	v_pk_add_f32 v[148:149], v[146:147], v[58:59]
	v_pk_add_f32 v[58:59], v[146:147], v[58:59] neg_lo:[0,1] neg_hi:[0,1]
	v_mov_b32_e32 v150, v148
	v_pk_mov_b32 v[146:147], v[148:149], v[58:59] op_sel:[1,0]
	v_mov_b32_e32 v151, v59
	v_mov_b32_e32 v152, v148
	v_mov_b32_e32 v153, v58
	v_mov_b32_e32 v58, v149
	v_pk_add_f32 v[146:147], v[150:151], v[146:147]
	v_pk_add_f32 v[58:59], v[152:153], v[58:59] neg_lo:[0,1] neg_hi:[0,1]
	s_nop 0
	v_mov_b32_dpp v150, v146 quad_perm:[1,0,3,2] row_mask:0xf bank_mask:0xf bound_ctrl:1
	v_mov_b32_dpp v151, v147 quad_perm:[1,0,3,2] row_mask:0xf bank_mask:0xf bound_ctrl:1
	v_mov_b32_dpp v148, v58 quad_perm:[1,0,3,2] row_mask:0xf bank_mask:0xf bound_ctrl:1
	v_mov_b32_dpp v149, v59 quad_perm:[1,0,3,2] row_mask:0xf bank_mask:0xf bound_ctrl:1
	v_pk_fma_f32 v[146:147], v[2:3], v[146:147], v[150:151]
	v_pk_fma_f32 v[58:59], v[2:3], v[58:59], v[148:149]
	s_nop 0
	v_mov_b32_dpp v150, v146 quad_perm:[2,3,0,1] row_mask:0xf bank_mask:0xf bound_ctrl:1
	v_mov_b32_dpp v151, v147 quad_perm:[2,3,0,1] row_mask:0xf bank_mask:0xf bound_ctrl:1
	v_mov_b32_dpp v148, v58 quad_perm:[2,3,0,1] row_mask:0xf bank_mask:0xf bound_ctrl:1
	v_mov_b32_dpp v149, v59 quad_perm:[2,3,0,1] row_mask:0xf bank_mask:0xf bound_ctrl:1
	v_pk_fma_f32 v[146:147], v[4:5], v[146:147], v[150:151]
	v_pk_fma_f32 v[58:59], v[4:5], v[58:59], v[148:149]
	v_mov_b32_e32 v150, v146
	v_mov_b32_e32 v151, v147
	v_mov_b32_e32 v148, v58
	v_mov_b32_e32 v149, v59
	v_mov_b32_dpp v150, v150 row_shl:4 row_mask:0xf bank_mask:0x5
	v_mov_b32_dpp v151, v151 row_shl:4 row_mask:0xf bank_mask:0x5
	v_mov_b32_dpp v148, v148 row_shl:4 row_mask:0xf bank_mask:0x5
	v_mov_b32_dpp v149, v149 row_shl:4 row_mask:0xf bank_mask:0x5
	v_mov_b32_dpp v150, v146 row_shr:4 row_mask:0xf bank_mask:0xa
	v_mov_b32_dpp v151, v147 row_shr:4 row_mask:0xf bank_mask:0xa
	v_mov_b32_dpp v148, v58 row_shr:4 row_mask:0xf bank_mask:0xa
	v_mov_b32_dpp v149, v59 row_shr:4 row_mask:0xf bank_mask:0xa
	v_pk_fma_f32 v[146:147], v[6:7], v[146:147], v[150:151]
	v_pk_fma_f32 v[58:59], v[6:7], v[58:59], v[148:149]
	s_nop 0
	v_mov_b32_dpp v150, v146 row_ror:8 row_mask:0xf bank_mask:0xf bound_ctrl:1
	v_mov_b32_dpp v151, v147 row_ror:8 row_mask:0xf bank_mask:0xf bound_ctrl:1
	v_mov_b32_dpp v148, v58 row_ror:8 row_mask:0xf bank_mask:0xf bound_ctrl:1
	v_mov_b32_dpp v149, v59 row_ror:8 row_mask:0xf bank_mask:0xf bound_ctrl:1
	v_pk_fma_f32 v[146:147], v[8:9], v[146:147], v[150:151]
	v_pk_fma_f32 v[58:59], v[10:11], v[58:59], v[148:149]
	v_pk_mul_f32 v[146:147], v[146:147], s[22:23] op_sel_hi:[1,0]
	v_pk_mul_f32 v[58:59], v[58:59], s[22:23] op_sel_hi:[1,0]
	v_cvt_pk_bf16_f32 v145, v146, v147
	s_nop 0
	v_cvt_pk_bf16_f32 v146, v58, v59
	v_lshlrev_b32_e32 v58, 16, v145
	v_and_b32_e32 v59, 0xffff0000, v145
	v_max_f32_e64 v145, |v59|, |v59|
	v_max_f32_e64 v147, |v58|, |v58|
	v_max_f32_e32 v147, v147, v145
	v_lshlrev_b32_e32 v145, 16, v146
	v_and_b32_e32 v146, 0xffff0000, v146
	v_max_f32_e64 v148, |v146|, |v146|
	v_max_f32_e64 v149, |v145|, |v145|
	v_max_f32_e32 v148, v149, v148
	v_max3_f32 v156, v154, v147, v148
	v_lshlrev_b32_e32 v149, 16, v57
	v_lshlrev_b32_e32 v148, 16, v56
	v_and_b32_e32 v57, 0xffff0000, v57
	v_and_b32_e32 v56, 0xffff0000, v56
	v_pk_add_f32 v[150:151], v[148:149], v[56:57]
	v_pk_add_f32 v[56:57], v[148:149], v[56:57] neg_lo:[0,1] neg_hi:[0,1]
; __device__ __forceinline__ unsigned cvt_pk_bf16(float lo, float hi) { unsigned r; asm volatile("v_cvt_pk_bf16_f32 %0, %1, %2" : "=v"(r) : "v"(lo), "v"(hi)); return r; }
; __device__ __forceinline__ float bf_lo(unsigned w) { return __uint_as_float(w << 16); }
; __device__ __forceinline__ float bf_hi(unsigned w) { return __uint_as_float(w & 0xffff0000u); }
; __device__ __forceinline__ float xlane1(float t) { return dpp_mov<0xB1, 0xF, true>(0.f, t); }
; __device__ __forceinline__ float xlane2(float t) { return dpp_mov<0x4E, 0xF, true>(0.f, t); }
; __device__ __forceinline__ float xlane4(float t) { const float r = dpp_mov<0x104, 0x5, false>(t, t); return dpp_mov<0x114, 0xA, false>(r, t); }
; __device__ __forceinline__ float xlane8(float t) { return dpp_mov<0x128, 0xF, true>(0.f, t); }
; __device__ __forceinline__ f32x4 rot64(f32x4 t, const RotSigns sg) {
;     { const float p0 = t.x + t.y, p1 = t.x - t.y, p2 = t.z + t.w, p3 = t.z - t.w; t = (f32x4){p0 + p2, p1 + p3, p0 - p2, p1 - p3}; }
;     t = (f32x4){__builtin_fmaf(sg.s1, t.x, xlane1(t.x)), __builtin_fmaf(sg.s1, t.y, xlane1(t.y)), __builtin_fmaf(sg.s1, t.z, xlane1(t.z)), __builtin_fmaf(sg.s1, t.w, xlane1(t.w))};
;     t = (f32x4){__builtin_fmaf(sg.s2, t.x, xlane2(t.x)), __builtin_fmaf(sg.s2, t.y, xlane2(t.y)), __builtin_fmaf(sg.s2, t.z, xlane2(t.z)), __builtin_fmaf(sg.s2, t.w, xlane2(t.w))};
;     t = (f32x4){__builtin_fmaf(sg.s4, t.x, xlane4(t.x)), __builtin_fmaf(sg.s4, t.y, xlane4(t.y)), __builtin_fmaf(sg.s4, t.z, xlane4(t.z)), __builtin_fmaf(sg.s4, t.w, xlane4(t.w))};
;     t = (f32x4){__builtin_fmaf(sg.s8, t.x, xlane8(t.x)), __builtin_fmaf(sg.s8, t.y, xlane8(t.y)), __builtin_fmaf(sg.s8, t.z, xlane8(t.z)), __builtin_fmaf(sg.s8, t.w, xlane8(t.w))};
;     return t * 0.125f;
; __global__ void __launch_bounds__(NWAVES * 64, 2) fwd_kernel(Args args) {
;     ...
;             for (int c = 0; c < DFF / 256; ++c) { const f32x4 t = rot64((f32x4){bf_lo(pk[c].x), bf_hi(pk[c].x), bf_lo(pk[c].y), bf_hi(pk[c].y)}, sg);
;                 pk[c].x = cvt_pk_bf16(t.x, t.y); pk[c].y = cvt_pk_bf16(t.z, t.w);
;                 am = fmaxf(fmaxf(am, fmaxf(fabsf(bf_lo(pk[c].x)), fabsf(bf_hi(pk[c].x)))), fmaxf(fabsf(bf_lo(pk[c].y)), fabsf(bf_hi(pk[c].y)))); }
	v_mov_b32_e32 v152, v150
	v_pk_mov_b32 v[148:149], v[150:151], v[56:57] op_sel:[1,0]
	v_mov_b32_e32 v153, v57
	v_mov_b32_e32 v154, v150
	v_mov_b32_e32 v155, v56
	v_mov_b32_e32 v56, v151
	v_pk_add_f32 v[148:149], v[152:153], v[148:149]
	v_pk_add_f32 v[56:57], v[154:155], v[56:57] neg_lo:[0,1] neg_hi:[0,1]
	s_nop 0
	v_mov_b32_dpp v152, v148 quad_perm:[1,0,3,2] row_mask:0xf bank_mask:0xf bound_ctrl:1
	v_mov_b32_dpp v153, v149 quad_perm:[1,0,3,2] row_mask:0xf bank_mask:0xf bound_ctrl:1
	v_mov_b32_dpp v150, v56 quad_perm:[1,0,3,2] row_mask:0xf bank_mask:0xf bound_ctrl:1
	v_mov_b32_dpp v151, v57 quad_perm:[1,0,3,2] row_mask:0xf bank_mask:0xf bound_ctrl:1
	v_pk_fma_f32 v[148:149], v[2:3], v[148:149], v[152:153]
	v_pk_fma_f32 v[56:57], v[2:3], v[56:57], v[150:151]
	s_nop 0
	v_mov_b32_dpp v152, v148 quad_perm:[2,3,0,1] row_mask:0xf bank_mask:0xf bound_ctrl:1
	v_mov_b32_dpp v153, v149 quad_perm:[2,3,0,1] row_mask:0xf bank_mask:0xf bound_ctrl:1
	v_mov_b32_dpp v150, v56 quad_perm:[2,3,0,1] row_mask:0xf bank_mask:0xf bound_ctrl:1
	v_mov_b32_dpp v151, v57 quad_perm:[2,3,0,1] row_mask:0xf bank_mask:0xf bound_ctrl:1
	v_pk_fma_f32 v[148:149], v[4:5], v[148:149], v[152:153]
	v_pk_fma_f32 v[56:57], v[4:5], v[56:57], v[150:151]
	v_mov_b32_e32 v152, v148
	v_mov_b32_e32 v153, v149
	v_mov_b32_e32 v150, v56
	v_mov_b32_e32 v151, v57
	v_mov_b32_dpp v152, v152 row_shl:4 row_mask:0xf bank_mask:0x5
	v_mov_b32_dpp v153, v153 row_shl:4 row_mask:0xf bank_mask:0x5
	v_mov_b32_dpp v150, v150 row_shl:4 row_mask:0xf bank_mask:0x5
	v_mov_b32_dpp v151, v151 row_shl:4 row_mask:0xf bank_mask:0x5
	v_mov_b32_dpp v152, v148 row_shr:4 row_mask:0xf bank_mask:0xa
	v_mov_b32_dpp v153, v149 row_shr:4 row_mask:0xf bank_mask:0xa
	v_mov_b32_dpp v150, v56 row_shr:4 row_mask:0xf bank_mask:0xa
	v_mov_b32_dpp v151, v57 row_shr:4 row_mask:0xf bank_mask:0xa
	v_pk_fma_f32 v[148:149], v[6:7], v[148:149], v[152:153]
	v_pk_fma_f32 v[56:57], v[6:7], v[56:57], v[150:151]
	s_nop 0
	v_mov_b32_dpp v152, v148 row_ror:8 row_mask:0xf bank_mask:0xf bound_ctrl:1
	v_mov_b32_dpp v153, v149 row_ror:8 row_mask:0xf bank_mask:0xf bound_ctrl:1
	v_mov_b32_dpp v150, v56 row_ror:8 row_mask:0xf bank_mask:0xf bound_ctrl:1
	v_mov_b32_dpp v151, v57 row_ror:8 row_mask:0xf bank_mask:0xf bound_ctrl:1
	v_pk_fma_f32 v[148:149], v[8:9], v[148:149], v[152:153]
	v_pk_fma_f32 v[56:57], v[10:11], v[56:57], v[150:151]
	v_pk_mul_f32 v[148:149], v[148:149], s[22:23] op_sel_hi:[1,0]
	v_pk_mul_f32 v[56:57], v[56:57], s[22:23] op_sel_hi:[1,0]
	v_cvt_pk_bf16_f32 v147, v148, v149
	s_nop 0
	v_cvt_pk_bf16_f32 v148, v56, v57
	v_lshlrev_b32_e32 v56, 16, v147
	v_and_b32_e32 v57, 0xffff0000, v147
	v_max_f32_e64 v147, |v57|, |v57|
	v_max_f32_e64 v149, |v56|, |v56|
	v_max_f32_e32 v149, v149, v147
	v_lshlrev_b32_e32 v147, 16, v148
	v_and_b32_e32 v148, 0xffff0000, v148
	v_max_f32_e64 v150, |v148|, |v148|
	v_max_f32_e64 v151, |v147|, |v147|
	v_max_f32_e32 v150, v151, v150
	v_max3_f32 v158, v156, v149, v150
	v_lshlrev_b32_e32 v151, 16, v55
	v_lshlrev_b32_e32 v150, 16, v54
	v_and_b32_e32 v55, 0xffff0000, v55
	v_and_b32_e32 v54, 0xffff0000, v54
	v_pk_add_f32 v[152:153], v[150:151], v[54:55]
	v_pk_add_f32 v[54:55], v[150:151], v[54:55] neg_lo:[0,1] neg_hi:[0,1]
	v_mov_b32_e32 v154, v152
	v_pk_mov_b32 v[150:151], v[152:153], v[54:55] op_sel:[1,0]
	v_mov_b32_e32 v155, v55
	v_mov_b32_e32 v156, v152
	v_mov_b32_e32 v157, v54
	v_mov_b32_e32 v54, v153
	v_pk_add_f32 v[150:151], v[154:155], v[150:151]
	v_pk_add_f32 v[54:55], v[156:157], v[54:55] neg_lo:[0,1] neg_hi:[0,1]
	s_nop 0
	v_mov_b32_dpp v154, v150 quad_perm:[1,0,3,2] row_mask:0xf bank_mask:0xf bound_ctrl:1
	v_mov_b32_dpp v155, v151 quad_perm:[1,0,3,2] row_mask:0xf bank_mask:0xf bound_ctrl:1
	v_mov_b32_dpp v152, v54 quad_perm:[1,0,3,2] row_mask:0xf bank_mask:0xf bound_ctrl:1
	v_mov_b32_dpp v153, v55 quad_perm:[1,0,3,2] row_mask:0xf bank_mask:0xf bound_ctrl:1
	v_pk_fma_f32 v[150:151], v[2:3], v[150:151], v[154:155]
	v_pk_fma_f32 v[54:55], v[2:3], v[54:55], v[152:153]
	s_nop 0
	v_mov_b32_dpp v154, v150 quad_perm:[2,3,0,1] row_mask:0xf bank_mask:0xf bound_ctrl:1
	v_mov_b32_dpp v155, v151 quad_perm:[2,3,0,1] row_mask:0xf bank_mask:0xf bound_ctrl:1
	v_mov_b32_dpp v152, v54 quad_perm:[2,3,0,1] row_mask:0xf bank_mask:0xf bound_ctrl:1
	v_mov_b32_dpp v153, v55 quad_perm:[2,3,0,1] row_mask:0xf bank_mask:0xf bound_ctrl:1
	v_pk_fma_f32 v[150:151], v[4:5], v[150:151], v[154:155]
	v_pk_fma_f32 v[54:55], v[4:5], v[54:55], v[152:153]
	v_mov_b32_e32 v154, v150
	v_mov_b32_e32 v155, v151
	v_mov_b32_e32 v152, v54
	v_mov_b32_e32 v153, v55
	v_mov_b32_dpp v154, v154 row_shl:4 row_mask:0xf bank_mask:0x5
	v_mov_b32_dpp v155, v155 row_shl:4 row_mask:0xf bank_mask:0x5
	v_mov_b32_dpp v152, v152 row_shl:4 row_mask:0xf bank_mask:0x5
	v_mov_b32_dpp v153, v153 row_shl:4 row_mask:0xf bank_mask:0x5
	v_mov_b32_dpp v154, v150 row_shr:4 row_mask:0xf bank_mask:0xa
	v_mov_b32_dpp v155, v151 row_shr:4 row_mask:0xf bank_mask:0xa
	v_mov_b32_dpp v152, v54 row_shr:4 row_mask:0xf bank_mask:0xa
	v_mov_b32_dpp v153, v55 row_shr:4 row_mask:0xf bank_mask:0xa
	v_pk_fma_f32 v[150:151], v[6:7], v[150:151], v[154:155]
	v_pk_fma_f32 v[54:55], v[6:7], v[54:55], v[152:153]
	s_nop 0
	v_mov_b32_dpp v154, v150 row_ror:8 row_mask:0xf bank_mask:0xf bound_ctrl:1
	v_mov_b32_dpp v155, v151 row_ror:8 row_mask:0xf bank_mask:0xf bound_ctrl:1
	v_mov_b32_dpp v152, v54 row_ror:8 row_mask:0xf bank_mask:0xf bound_ctrl:1
	v_mov_b32_dpp v153, v55 row_ror:8 row_mask:0xf bank_mask:0xf bound_ctrl:1
	v_pk_fma_f32 v[150:151], v[8:9], v[150:151], v[154:155]
	v_pk_fma_f32 v[54:55], v[10:11], v[54:55], v[152:153]
	v_pk_mul_f32 v[150:151], v[150:151], s[22:23] op_sel_hi:[1,0]
; __device__ __forceinline__ unsigned cvt_pk_bf16(float lo, float hi) { unsigned r; asm volatile("v_cvt_pk_bf16_f32 %0, %1, %2" : "=v"(r) : "v"(lo), "v"(hi)); return r; }
; __device__ __forceinline__ float bf_lo(unsigned w) { return __uint_as_float(w << 16); }
; __device__ __forceinline__ float bf_hi(unsigned w) { return __uint_as_float(w & 0xffff0000u); }
; __device__ __forceinline__ float xlane1(float t) { return dpp_mov<0xB1, 0xF, true>(0.f, t); }
; __device__ __forceinline__ float xlane2(float t) { return dpp_mov<0x4E, 0xF, true>(0.f, t); }
; __device__ __forceinline__ float xlane4(float t) { const float r = dpp_mov<0x104, 0x5, false>(t, t); return dpp_mov<0x114, 0xA, false>(r, t); }
; __device__ __forceinline__ float xlane8(float t) { return dpp_mov<0x128, 0xF, true>(0.f, t); }
; __device__ __forceinline__ f32x4 rot64(f32x4 t, const RotSigns sg) {
;     { const float p0 = t.x + t.y, p1 = t.x - t.y, p2 = t.z + t.w, p3 = t.z - t.w; t = (f32x4){p0 + p2, p1 + p3, p0 - p2, p1 - p3}; }
;     t = (f32x4){__builtin_fmaf(sg.s1, t.x, xlane1(t.x)), __builtin_fmaf(sg.s1, t.y, xlane1(t.y)), __builtin_fmaf(sg.s1, t.z, xlane1(t.z)), __builtin_fmaf(sg.s1, t.w, xlane1(t.w))};
;     t = (f32x4){__builtin_fmaf(sg.s2, t.x, xlane2(t.x)), __builtin_fmaf(sg.s2, t.y, xlane2(t.y)), __builtin_fmaf(sg.s2, t.z, xlane2(t.z)), __builtin_fmaf(sg.s2, t.w, xlane2(t.w))};
;     t = (f32x4){__builtin_fmaf(sg.s4, t.x, xlane4(t.x)), __builtin_fmaf(sg.s4, t.y, xlane4(t.y)), __builtin_fmaf(sg.s4, t.z, xlane4(t.z)), __builtin_fmaf(sg.s4, t.w, xlane4(t.w))};
;     t = (f32x4){__builtin_fmaf(sg.s8, t.x, xlane8(t.x)), __builtin_fmaf(sg.s8, t.y, xlane8(t.y)), __builtin_fmaf(sg.s8, t.z, xlane8(t.z)), __builtin_fmaf(sg.s8, t.w, xlane8(t.w))};
;     return t * 0.125f;
; __global__ void __launch_bounds__(NWAVES * 64, 2) fwd_kernel(Args args) {
;     ...
;             for (int c = 0; c < DFF / 256; ++c) { const f32x4 t = rot64((f32x4){bf_lo(pk[c].x), bf_hi(pk[c].x), bf_lo(pk[c].y), bf_hi(pk[c].y)}, sg);
;                 pk[c].x = cvt_pk_bf16(t.x, t.y); pk[c].y = cvt_pk_bf16(t.z, t.w);
;                 am = fmaxf(fmaxf(am, fmaxf(fabsf(bf_lo(pk[c].x)), fabsf(bf_hi(pk[c].x)))), fmaxf(fabsf(bf_lo(pk[c].y)), fabsf(bf_hi(pk[c].y)))); }
	v_pk_mul_f32 v[54:55], v[54:55], s[22:23] op_sel_hi:[1,0]
	v_cvt_pk_bf16_f32 v149, v150, v151
	s_nop 0
	v_cvt_pk_bf16_f32 v150, v54, v55
	v_lshlrev_b32_e32 v54, 16, v149
	v_and_b32_e32 v55, 0xffff0000, v149
	v_max_f32_e64 v149, |v55|, |v55|
	v_max_f32_e64 v151, |v54|, |v54|
	v_max_f32_e32 v151, v151, v149
	v_lshlrev_b32_e32 v149, 16, v150
	v_and_b32_e32 v150, 0xffff0000, v150
	v_max_f32_e64 v152, |v150|, |v150|
	v_max_f32_e64 v153, |v149|, |v149|
	v_max_f32_e32 v152, v153, v152
	v_max3_f32 v160, v158, v151, v152
	v_lshlrev_b32_e32 v153, 16, v53
	v_lshlrev_b32_e32 v152, 16, v52
	v_and_b32_e32 v53, 0xffff0000, v53
	v_and_b32_e32 v52, 0xffff0000, v52
	v_pk_add_f32 v[154:155], v[152:153], v[52:53]
	v_pk_add_f32 v[52:53], v[152:153], v[52:53] neg_lo:[0,1] neg_hi:[0,1]
	v_mov_b32_e32 v156, v154
	v_pk_mov_b32 v[152:153], v[154:155], v[52:53] op_sel:[1,0]
	v_mov_b32_e32 v157, v53
	v_mov_b32_e32 v158, v154
	v_mov_b32_e32 v159, v52
	v_mov_b32_e32 v52, v155
	v_pk_add_f32 v[152:153], v[156:157], v[152:153]
	v_pk_add_f32 v[52:53], v[158:159], v[52:53] neg_lo:[0,1] neg_hi:[0,1]
	s_nop 0
	v_mov_b32_dpp v156, v152 quad_perm:[1,0,3,2] row_mask:0xf bank_mask:0xf bound_ctrl:1
	v_mov_b32_dpp v157, v153 quad_perm:[1,0,3,2] row_mask:0xf bank_mask:0xf bound_ctrl:1
	v_mov_b32_dpp v154, v52 quad_perm:[1,0,3,2] row_mask:0xf bank_mask:0xf bound_ctrl:1
	v_mov_b32_dpp v155, v53 quad_perm:[1,0,3,2] row_mask:0xf bank_mask:0xf bound_ctrl:1
	v_pk_fma_f32 v[152:153], v[2:3], v[152:153], v[156:157]
	v_pk_fma_f32 v[52:53], v[2:3], v[52:53], v[154:155]
	s_nop 0
	v_mov_b32_dpp v156, v152 quad_perm:[2,3,0,1] row_mask:0xf bank_mask:0xf bound_ctrl:1
	v_mov_b32_dpp v157, v153 quad_perm:[2,3,0,1] row_mask:0xf bank_mask:0xf bound_ctrl:1
	v_mov_b32_dpp v154, v52 quad_perm:[2,3,0,1] row_mask:0xf bank_mask:0xf bound_ctrl:1
	v_mov_b32_dpp v155, v53 quad_perm:[2,3,0,1] row_mask:0xf bank_mask:0xf bound_ctrl:1
	v_pk_fma_f32 v[152:153], v[4:5], v[152:153], v[156:157]
	v_pk_fma_f32 v[52:53], v[4:5], v[52:53], v[154:155]
	v_mov_b32_e32 v156, v152
	v_mov_b32_e32 v157, v153
	v_mov_b32_e32 v154, v52
	v_mov_b32_e32 v155, v53
	v_mov_b32_dpp v156, v156 row_shl:4 row_mask:0xf bank_mask:0x5
	v_mov_b32_dpp v157, v157 row_shl:4 row_mask:0xf bank_mask:0x5
	v_mov_b32_dpp v154, v154 row_shl:4 row_mask:0xf bank_mask:0x5
	v_mov_b32_dpp v155, v155 row_shl:4 row_mask:0xf bank_mask:0x5
	v_mov_b32_dpp v156, v152 row_shr:4 row_mask:0xf bank_mask:0xa
	v_mov_b32_dpp v157, v153 row_shr:4 row_mask:0xf bank_mask:0xa
	v_mov_b32_dpp v154, v52 row_shr:4 row_mask:0xf bank_mask:0xa
	v_mov_b32_dpp v155, v53 row_shr:4 row_mask:0xf bank_mask:0xa
	v_pk_fma_f32 v[152:153], v[6:7], v[152:153], v[156:157]
	v_pk_fma_f32 v[52:53], v[6:7], v[52:53], v[154:155]
	s_nop 0
	v_mov_b32_dpp v156, v152 row_ror:8 row_mask:0xf bank_mask:0xf bound_ctrl:1
	v_mov_b32_dpp v157, v153 row_ror:8 row_mask:0xf bank_mask:0xf bound_ctrl:1
	v_mov_b32_dpp v154, v52 row_ror:8 row_mask:0xf bank_mask:0xf bound_ctrl:1
	v_mov_b32_dpp v155, v53 row_ror:8 row_mask:0xf bank_mask:0xf bound_ctrl:1
	v_pk_fma_f32 v[152:153], v[8:9], v[152:153], v[156:157]
	v_pk_fma_f32 v[52:53], v[10:11], v[52:53], v[154:155]
	v_pk_mul_f32 v[152:153], v[152:153], s[22:23] op_sel_hi:[1,0]
	v_pk_mul_f32 v[52:53], v[52:53], s[22:23] op_sel_hi:[1,0]
	v_cvt_pk_bf16_f32 v151, v152, v153
	s_nop 0
	v_cvt_pk_bf16_f32 v152, v52, v53
	v_lshlrev_b32_e32 v52, 16, v151
	v_and_b32_e32 v53, 0xffff0000, v151
	v_max_f32_e64 v151, |v53|, |v53|
	v_max_f32_e64 v153, |v52|, |v52|
	v_max_f32_e32 v153, v153, v151
	v_lshlrev_b32_e32 v151, 16, v152
	v_and_b32_e32 v152, 0xffff0000, v152
	v_max_f32_e64 v154, |v152|, |v152|
	v_max_f32_e64 v155, |v151|, |v151|
	v_max_f32_e32 v154, v155, v154
	v_max3_f32 v162, v160, v153, v154
	v_lshlrev_b32_e32 v155, 16, v51
	v_lshlrev_b32_e32 v154, 16, v50
	v_and_b32_e32 v51, 0xffff0000, v51
	v_and_b32_e32 v50, 0xffff0000, v50
	v_pk_add_f32 v[156:157], v[154:155], v[50:51]
	v_pk_add_f32 v[50:51], v[154:155], v[50:51] neg_lo:[0,1] neg_hi:[0,1]
	v_mov_b32_e32 v158, v156
	v_pk_mov_b32 v[154:155], v[156:157], v[50:51] op_sel:[1,0]
	v_mov_b32_e32 v159, v51
	v_mov_b32_e32 v160, v156
	v_mov_b32_e32 v161, v50
	v_mov_b32_e32 v50, v157
	v_pk_add_f32 v[154:155], v[158:159], v[154:155]
	v_pk_add_f32 v[50:51], v[160:161], v[50:51] neg_lo:[0,1] neg_hi:[0,1]
	s_nop 0
	v_mov_b32_dpp v158, v154 quad_perm:[1,0,3,2] row_mask:0xf bank_mask:0xf bound_ctrl:1
	v_mov_b32_dpp v159, v155 quad_perm:[1,0,3,2] row_mask:0xf bank_mask:0xf bound_ctrl:1
	v_mov_b32_dpp v156, v50 quad_perm:[1,0,3,2] row_mask:0xf bank_mask:0xf bound_ctrl:1
	v_mov_b32_dpp v157, v51 quad_perm:[1,0,3,2] row_mask:0xf bank_mask:0xf bound_ctrl:1
	v_pk_fma_f32 v[154:155], v[2:3], v[154:155], v[158:159]
	v_pk_fma_f32 v[50:51], v[2:3], v[50:51], v[156:157]
	s_nop 0
	v_mov_b32_dpp v158, v154 quad_perm:[2,3,0,1] row_mask:0xf bank_mask:0xf bound_ctrl:1
	v_mov_b32_dpp v159, v155 quad_perm:[2,3,0,1] row_mask:0xf bank_mask:0xf bound_ctrl:1
	v_mov_b32_dpp v156, v50 quad_perm:[2,3,0,1] row_mask:0xf bank_mask:0xf bound_ctrl:1
	v_mov_b32_dpp v157, v51 quad_perm:[2,3,0,1] row_mask:0xf bank_mask:0xf bound_ctrl:1
	v_pk_fma_f32 v[154:155], v[4:5], v[154:155], v[158:159]
	v_pk_fma_f32 v[50:51], v[4:5], v[50:51], v[156:157]
	v_mov_b32_e32 v158, v154
	v_mov_b32_e32 v159, v155
	v_mov_b32_e32 v156, v50
	v_mov_b32_e32 v157, v51
	v_mov_b32_dpp v158, v158 row_shl:4 row_mask:0xf bank_mask:0x5
	v_mov_b32_dpp v159, v159 row_shl:4 row_mask:0xf bank_mask:0x5
	v_mov_b32_dpp v156, v156 row_shl:4 row_mask:0xf bank_mask:0x5
	v_mov_b32_dpp v157, v157 row_shl:4 row_mask:0xf bank_mask:0x5
	v_mov_b32_dpp v158, v154 row_shr:4 row_mask:0xf bank_mask:0xa
; __device__ __forceinline__ unsigned cvt_pk_bf16(float lo, float hi) { unsigned r; asm volatile("v_cvt_pk_bf16_f32 %0, %1, %2" : "=v"(r) : "v"(lo), "v"(hi)); return r; }
; __device__ __forceinline__ float bf_lo(unsigned w) { return __uint_as_float(w << 16); }
; __device__ __forceinline__ float bf_hi(unsigned w) { return __uint_as_float(w & 0xffff0000u); }
; __device__ __forceinline__ float xlane1(float t) { return dpp_mov<0xB1, 0xF, true>(0.f, t); }
; __device__ __forceinline__ float xlane2(float t) { return dpp_mov<0x4E, 0xF, true>(0.f, t); }
; __device__ __forceinline__ float xlane4(float t) { const float r = dpp_mov<0x104, 0x5, false>(t, t); return dpp_mov<0x114, 0xA, false>(r, t); }
; __device__ __forceinline__ float xlane8(float t) { return dpp_mov<0x128, 0xF, true>(0.f, t); }
; __device__ __forceinline__ f32x4 rot64(f32x4 t, const RotSigns sg) {
;     { const float p0 = t.x + t.y, p1 = t.x - t.y, p2 = t.z + t.w, p3 = t.z - t.w; t = (f32x4){p0 + p2, p1 + p3, p0 - p2, p1 - p3}; }
;     t = (f32x4){__builtin_fmaf(sg.s1, t.x, xlane1(t.x)), __builtin_fmaf(sg.s1, t.y, xlane1(t.y)), __builtin_fmaf(sg.s1, t.z, xlane1(t.z)), __builtin_fmaf(sg.s1, t.w, xlane1(t.w))};
;     t = (f32x4){__builtin_fmaf(sg.s2, t.x, xlane2(t.x)), __builtin_fmaf(sg.s2, t.y, xlane2(t.y)), __builtin_fmaf(sg.s2, t.z, xlane2(t.z)), __builtin_fmaf(sg.s2, t.w, xlane2(t.w))};
;     t = (f32x4){__builtin_fmaf(sg.s4, t.x, xlane4(t.x)), __builtin_fmaf(sg.s4, t.y, xlane4(t.y)), __builtin_fmaf(sg.s4, t.z, xlane4(t.z)), __builtin_fmaf(sg.s4, t.w, xlane4(t.w))};
;     t = (f32x4){__builtin_fmaf(sg.s8, t.x, xlane8(t.x)), __builtin_fmaf(sg.s8, t.y, xlane8(t.y)), __builtin_fmaf(sg.s8, t.z, xlane8(t.z)), __builtin_fmaf(sg.s8, t.w, xlane8(t.w))};
;     return t * 0.125f;
; __global__ void __launch_bounds__(NWAVES * 64, 2) fwd_kernel(Args args) {
;     ...
;             for (int c = 0; c < DFF / 256; ++c) { const f32x4 t = rot64((f32x4){bf_lo(pk[c].x), bf_hi(pk[c].x), bf_lo(pk[c].y), bf_hi(pk[c].y)}, sg);
;                 pk[c].x = cvt_pk_bf16(t.x, t.y); pk[c].y = cvt_pk_bf16(t.z, t.w);
;                 am = fmaxf(fmaxf(am, fmaxf(fabsf(bf_lo(pk[c].x)), fabsf(bf_hi(pk[c].x)))), fmaxf(fabsf(bf_lo(pk[c].y)), fabsf(bf_hi(pk[c].y)))); }
	v_mov_b32_dpp v159, v155 row_shr:4 row_mask:0xf bank_mask:0xa
	v_mov_b32_dpp v156, v50 row_shr:4 row_mask:0xf bank_mask:0xa
	v_mov_b32_dpp v157, v51 row_shr:4 row_mask:0xf bank_mask:0xa
	v_pk_fma_f32 v[154:155], v[6:7], v[154:155], v[158:159]
	v_pk_fma_f32 v[50:51], v[6:7], v[50:51], v[156:157]
	s_nop 0
	v_mov_b32_dpp v158, v154 row_ror:8 row_mask:0xf bank_mask:0xf bound_ctrl:1
	v_mov_b32_dpp v159, v155 row_ror:8 row_mask:0xf bank_mask:0xf bound_ctrl:1
	v_mov_b32_dpp v156, v50 row_ror:8 row_mask:0xf bank_mask:0xf bound_ctrl:1
	v_mov_b32_dpp v157, v51 row_ror:8 row_mask:0xf bank_mask:0xf bound_ctrl:1
	v_pk_fma_f32 v[154:155], v[8:9], v[154:155], v[158:159]
	v_pk_fma_f32 v[50:51], v[10:11], v[50:51], v[156:157]
	v_pk_mul_f32 v[154:155], v[154:155], s[22:23] op_sel_hi:[1,0]
	v_pk_mul_f32 v[50:51], v[50:51], s[22:23] op_sel_hi:[1,0]
	v_cvt_pk_bf16_f32 v153, v154, v155
	s_nop 0
	v_cvt_pk_bf16_f32 v154, v50, v51
	v_lshlrev_b32_e32 v50, 16, v153
	v_and_b32_e32 v51, 0xffff0000, v153
	v_max_f32_e64 v153, |v51|, |v51|
	v_max_f32_e64 v155, |v50|, |v50|
	v_max_f32_e32 v155, v155, v153
	v_lshlrev_b32_e32 v153, 16, v154
	v_and_b32_e32 v154, 0xffff0000, v154
	v_max_f32_e64 v156, |v154|, |v154|
	v_max_f32_e64 v157, |v153|, |v153|
	v_max_f32_e32 v156, v157, v156
	v_max3_f32 v164, v162, v155, v156
	v_lshlrev_b32_e32 v157, 16, v49
	v_lshlrev_b32_e32 v156, 16, v48
	v_and_b32_e32 v49, 0xffff0000, v49
	v_and_b32_e32 v48, 0xffff0000, v48
	v_pk_add_f32 v[158:159], v[156:157], v[48:49]
	v_pk_add_f32 v[48:49], v[156:157], v[48:49] neg_lo:[0,1] neg_hi:[0,1]
	v_mov_b32_e32 v160, v158
	v_pk_mov_b32 v[156:157], v[158:159], v[48:49] op_sel:[1,0]
	v_mov_b32_e32 v161, v49
	v_mov_b32_e32 v162, v158
	v_mov_b32_e32 v163, v48
	v_mov_b32_e32 v48, v159
	v_pk_add_f32 v[156:157], v[160:161], v[156:157]
	v_pk_add_f32 v[48:49], v[162:163], v[48:49] neg_lo:[0,1] neg_hi:[0,1]
	s_nop 0
	v_mov_b32_dpp v160, v156 quad_perm:[1,0,3,2] row_mask:0xf bank_mask:0xf bound_ctrl:1
	v_mov_b32_dpp v161, v157 quad_perm:[1,0,3,2] row_mask:0xf bank_mask:0xf bound_ctrl:1
	v_mov_b32_dpp v158, v48 quad_perm:[1,0,3,2] row_mask:0xf bank_mask:0xf bound_ctrl:1
	v_mov_b32_dpp v159, v49 quad_perm:[1,0,3,2] row_mask:0xf bank_mask:0xf bound_ctrl:1
	v_pk_fma_f32 v[156:157], v[2:3], v[156:157], v[160:161]
	v_pk_fma_f32 v[48:49], v[2:3], v[48:49], v[158:159]
	s_nop 0
	v_mov_b32_dpp v160, v156 quad_perm:[2,3,0,1] row_mask:0xf bank_mask:0xf bound_ctrl:1
	v_mov_b32_dpp v161, v157 quad_perm:[2,3,0,1] row_mask:0xf bank_mask:0xf bound_ctrl:1
	v_mov_b32_dpp v158, v48 quad_perm:[2,3,0,1] row_mask:0xf bank_mask:0xf bound_ctrl:1
	v_mov_b32_dpp v159, v49 quad_perm:[2,3,0,1] row_mask:0xf bank_mask:0xf bound_ctrl:1
	v_pk_fma_f32 v[156:157], v[4:5], v[156:157], v[160:161]
	v_pk_fma_f32 v[48:49], v[4:5], v[48:49], v[158:159]
	v_mov_b32_e32 v160, v156
	v_mov_b32_e32 v161, v157
	v_mov_b32_e32 v158, v48
	v_mov_b32_e32 v159, v49
	v_mov_b32_dpp v160, v160 row_shl:4 row_mask:0xf bank_mask:0x5
	v_mov_b32_dpp v161, v161 row_shl:4 row_mask:0xf bank_mask:0x5
	v_mov_b32_dpp v158, v158 row_shl:4 row_mask:0xf bank_mask:0x5
	v_mov_b32_dpp v159, v159 row_shl:4 row_mask:0xf bank_mask:0x5
	v_mov_b32_dpp v160, v156 row_shr:4 row_mask:0xf bank_mask:0xa
	v_mov_b32_dpp v161, v157 row_shr:4 row_mask:0xf bank_mask:0xa
	v_mov_b32_dpp v158, v48 row_shr:4 row_mask:0xf bank_mask:0xa
	v_mov_b32_dpp v159, v49 row_shr:4 row_mask:0xf bank_mask:0xa
	v_pk_fma_f32 v[156:157], v[6:7], v[156:157], v[160:161]
	v_pk_fma_f32 v[48:49], v[6:7], v[48:49], v[158:159]
	s_nop 0
	v_mov_b32_dpp v160, v156 row_ror:8 row_mask:0xf bank_mask:0xf bound_ctrl:1
	v_mov_b32_dpp v161, v157 row_ror:8 row_mask:0xf bank_mask:0xf bound_ctrl:1
	v_mov_b32_dpp v158, v48 row_ror:8 row_mask:0xf bank_mask:0xf bound_ctrl:1
	v_mov_b32_dpp v159, v49 row_ror:8 row_mask:0xf bank_mask:0xf bound_ctrl:1
	v_pk_fma_f32 v[156:157], v[8:9], v[156:157], v[160:161]
	v_pk_fma_f32 v[48:49], v[10:11], v[48:49], v[158:159]
	v_pk_mul_f32 v[156:157], v[156:157], s[22:23] op_sel_hi:[1,0]
	v_pk_mul_f32 v[48:49], v[48:49], s[22:23] op_sel_hi:[1,0]
	v_cvt_pk_bf16_f32 v155, v156, v157
	s_nop 0
	v_cvt_pk_bf16_f32 v156, v48, v49
	v_lshlrev_b32_e32 v48, 16, v155
	v_and_b32_e32 v49, 0xffff0000, v155
	v_max_f32_e64 v155, |v49|, |v49|
	v_max_f32_e64 v157, |v48|, |v48|
	v_max_f32_e32 v157, v157, v155
	v_lshlrev_b32_e32 v155, 16, v156
	v_and_b32_e32 v156, 0xffff0000, v156
	v_max_f32_e64 v158, |v156|, |v156|
	v_max_f32_e64 v159, |v155|, |v155|
	v_max_f32_e32 v158, v159, v158
	v_max3_f32 v166, v164, v157, v158
	v_lshlrev_b32_e32 v159, 16, v47
	v_lshlrev_b32_e32 v158, 16, v46
	v_and_b32_e32 v47, 0xffff0000, v47
	v_and_b32_e32 v46, 0xffff0000, v46
	v_pk_add_f32 v[160:161], v[158:159], v[46:47]
	v_pk_add_f32 v[46:47], v[158:159], v[46:47] neg_lo:[0,1] neg_hi:[0,1]
	v_mov_b32_e32 v162, v160
	v_pk_mov_b32 v[158:159], v[160:161], v[46:47] op_sel:[1,0]
	v_mov_b32_e32 v163, v47
	v_mov_b32_e32 v164, v160
	v_mov_b32_e32 v165, v46
	v_mov_b32_e32 v46, v161
	v_pk_add_f32 v[158:159], v[162:163], v[158:159]
	v_pk_add_f32 v[46:47], v[164:165], v[46:47] neg_lo:[0,1] neg_hi:[0,1]
	s_nop 0
	v_mov_b32_dpp v162, v158 quad_perm:[1,0,3,2] row_mask:0xf bank_mask:0xf bound_ctrl:1
	v_mov_b32_dpp v163, v159 quad_perm:[1,0,3,2] row_mask:0xf bank_mask:0xf bound_ctrl:1
	v_mov_b32_dpp v160, v46 quad_perm:[1,0,3,2] row_mask:0xf bank_mask:0xf bound_ctrl:1
	v_mov_b32_dpp v161, v47 quad_perm:[1,0,3,2] row_mask:0xf bank_mask:0xf bound_ctrl:1
	v_pk_fma_f32 v[158:159], v[2:3], v[158:159], v[162:163]
	v_pk_fma_f32 v[46:47], v[2:3], v[46:47], v[160:161]
	s_nop 0
	v_mov_b32_dpp v162, v158 quad_perm:[2,3,0,1] row_mask:0xf bank_mask:0xf bound_ctrl:1
; __device__ __forceinline__ unsigned cvt_pk_bf16(float lo, float hi) { unsigned r; asm volatile("v_cvt_pk_bf16_f32 %0, %1, %2" : "=v"(r) : "v"(lo), "v"(hi)); return r; }
; __device__ __forceinline__ float bf_lo(unsigned w) { return __uint_as_float(w << 16); }
; __device__ __forceinline__ float bf_hi(unsigned w) { return __uint_as_float(w & 0xffff0000u); }
; __device__ __forceinline__ float xlane1(float t) { return dpp_mov<0xB1, 0xF, true>(0.f, t); }
; __device__ __forceinline__ float xlane2(float t) { return dpp_mov<0x4E, 0xF, true>(0.f, t); }
; __device__ __forceinline__ float xlane4(float t) { const float r = dpp_mov<0x104, 0x5, false>(t, t); return dpp_mov<0x114, 0xA, false>(r, t); }
; __device__ __forceinline__ float xlane8(float t) { return dpp_mov<0x128, 0xF, true>(0.f, t); }
; __device__ __forceinline__ f32x4 rot64(f32x4 t, const RotSigns sg) {
;     { const float p0 = t.x + t.y, p1 = t.x - t.y, p2 = t.z + t.w, p3 = t.z - t.w; t = (f32x4){p0 + p2, p1 + p3, p0 - p2, p1 - p3}; }
;     t = (f32x4){__builtin_fmaf(sg.s1, t.x, xlane1(t.x)), __builtin_fmaf(sg.s1, t.y, xlane1(t.y)), __builtin_fmaf(sg.s1, t.z, xlane1(t.z)), __builtin_fmaf(sg.s1, t.w, xlane1(t.w))};
;     t = (f32x4){__builtin_fmaf(sg.s2, t.x, xlane2(t.x)), __builtin_fmaf(sg.s2, t.y, xlane2(t.y)), __builtin_fmaf(sg.s2, t.z, xlane2(t.z)), __builtin_fmaf(sg.s2, t.w, xlane2(t.w))};
;     t = (f32x4){__builtin_fmaf(sg.s4, t.x, xlane4(t.x)), __builtin_fmaf(sg.s4, t.y, xlane4(t.y)), __builtin_fmaf(sg.s4, t.z, xlane4(t.z)), __builtin_fmaf(sg.s4, t.w, xlane4(t.w))};
;     t = (f32x4){__builtin_fmaf(sg.s8, t.x, xlane8(t.x)), __builtin_fmaf(sg.s8, t.y, xlane8(t.y)), __builtin_fmaf(sg.s8, t.z, xlane8(t.z)), __builtin_fmaf(sg.s8, t.w, xlane8(t.w))};
;     return t * 0.125f;
; __global__ void __launch_bounds__(NWAVES * 64, 2) fwd_kernel(Args args) {
;     ...
;             for (int c = 0; c < DFF / 256; ++c) { const f32x4 t = rot64((f32x4){bf_lo(pk[c].x), bf_hi(pk[c].x), bf_lo(pk[c].y), bf_hi(pk[c].y)}, sg);
;                 pk[c].x = cvt_pk_bf16(t.x, t.y); pk[c].y = cvt_pk_bf16(t.z, t.w);
;                 am = fmaxf(fmaxf(am, fmaxf(fabsf(bf_lo(pk[c].x)), fabsf(bf_hi(pk[c].x)))), fmaxf(fabsf(bf_lo(pk[c].y)), fabsf(bf_hi(pk[c].y)))); }
	v_mov_b32_dpp v163, v159 quad_perm:[2,3,0,1] row_mask:0xf bank_mask:0xf bound_ctrl:1
	v_mov_b32_dpp v160, v46 quad_perm:[2,3,0,1] row_mask:0xf bank_mask:0xf bound_ctrl:1
	v_mov_b32_dpp v161, v47 quad_perm:[2,3,0,1] row_mask:0xf bank_mask:0xf bound_ctrl:1
	v_pk_fma_f32 v[158:159], v[4:5], v[158:159], v[162:163]
	v_pk_fma_f32 v[46:47], v[4:5], v[46:47], v[160:161]
	v_mov_b32_e32 v162, v158
	v_mov_b32_e32 v163, v159
	v_mov_b32_e32 v160, v46
	v_mov_b32_e32 v161, v47
	v_mov_b32_dpp v162, v162 row_shl:4 row_mask:0xf bank_mask:0x5
	v_mov_b32_dpp v163, v163 row_shl:4 row_mask:0xf bank_mask:0x5
	v_mov_b32_dpp v160, v160 row_shl:4 row_mask:0xf bank_mask:0x5
	v_mov_b32_dpp v161, v161 row_shl:4 row_mask:0xf bank_mask:0x5
	v_mov_b32_dpp v162, v158 row_shr:4 row_mask:0xf bank_mask:0xa
	v_mov_b32_dpp v163, v159 row_shr:4 row_mask:0xf bank_mask:0xa
	v_mov_b32_dpp v160, v46 row_shr:4 row_mask:0xf bank_mask:0xa
	v_mov_b32_dpp v161, v47 row_shr:4 row_mask:0xf bank_mask:0xa
	v_pk_fma_f32 v[158:159], v[6:7], v[158:159], v[162:163]
	v_pk_fma_f32 v[46:47], v[6:7], v[46:47], v[160:161]
	s_nop 0
	v_mov_b32_dpp v162, v158 row_ror:8 row_mask:0xf bank_mask:0xf bound_ctrl:1
	v_mov_b32_dpp v163, v159 row_ror:8 row_mask:0xf bank_mask:0xf bound_ctrl:1
	v_mov_b32_dpp v160, v46 row_ror:8 row_mask:0xf bank_mask:0xf bound_ctrl:1
	v_mov_b32_dpp v161, v47 row_ror:8 row_mask:0xf bank_mask:0xf bound_ctrl:1
	v_pk_fma_f32 v[158:159], v[8:9], v[158:159], v[162:163]
	v_pk_fma_f32 v[46:47], v[10:11], v[46:47], v[160:161]
	v_pk_mul_f32 v[158:159], v[158:159], s[22:23] op_sel_hi:[1,0]
	v_pk_mul_f32 v[46:47], v[46:47], s[22:23] op_sel_hi:[1,0]
	v_cvt_pk_bf16_f32 v157, v158, v159
	s_nop 0
	v_cvt_pk_bf16_f32 v158, v46, v47
	v_lshlrev_b32_e32 v46, 16, v157
	v_and_b32_e32 v47, 0xffff0000, v157
	v_max_f32_e64 v157, |v47|, |v47|
	v_max_f32_e64 v159, |v46|, |v46|
	v_max_f32_e32 v159, v159, v157
	v_lshlrev_b32_e32 v157, 16, v158
	v_and_b32_e32 v158, 0xffff0000, v158
	v_max_f32_e64 v160, |v158|, |v158|
	v_max_f32_e64 v161, |v157|, |v157|
	v_max_f32_e32 v160, v161, v160
	v_max3_f32 v168, v166, v159, v160
	v_lshlrev_b32_e32 v161, 16, v45
	v_lshlrev_b32_e32 v160, 16, v44
	v_and_b32_e32 v45, 0xffff0000, v45
	v_and_b32_e32 v44, 0xffff0000, v44
	v_pk_add_f32 v[162:163], v[160:161], v[44:45]
	v_pk_add_f32 v[44:45], v[160:161], v[44:45] neg_lo:[0,1] neg_hi:[0,1]
	v_mov_b32_e32 v164, v162
	v_pk_mov_b32 v[160:161], v[162:163], v[44:45] op_sel:[1,0]
	v_mov_b32_e32 v165, v45
	v_mov_b32_e32 v166, v162
	v_mov_b32_e32 v167, v44
	v_mov_b32_e32 v44, v163
	v_pk_add_f32 v[160:161], v[164:165], v[160:161]
	v_pk_add_f32 v[44:45], v[166:167], v[44:45] neg_lo:[0,1] neg_hi:[0,1]
	s_nop 0
	v_mov_b32_dpp v164, v160 quad_perm:[1,0,3,2] row_mask:0xf bank_mask:0xf bound_ctrl:1
	v_mov_b32_dpp v165, v161 quad_perm:[1,0,3,2] row_mask:0xf bank_mask:0xf bound_ctrl:1
	v_mov_b32_dpp v162, v44 quad_perm:[1,0,3,2] row_mask:0xf bank_mask:0xf bound_ctrl:1
	v_mov_b32_dpp v163, v45 quad_perm:[1,0,3,2] row_mask:0xf bank_mask:0xf bound_ctrl:1
	v_pk_fma_f32 v[160:161], v[2:3], v[160:161], v[164:165]
	v_pk_fma_f32 v[44:45], v[2:3], v[44:45], v[162:163]
	s_nop 0
	v_mov_b32_dpp v164, v160 quad_perm:[2,3,0,1] row_mask:0xf bank_mask:0xf bound_ctrl:1
	v_mov_b32_dpp v165, v161 quad_perm:[2,3,0,1] row_mask:0xf bank_mask:0xf bound_ctrl:1
	v_mov_b32_dpp v162, v44 quad_perm:[2,3,0,1] row_mask:0xf bank_mask:0xf bound_ctrl:1
	v_mov_b32_dpp v163, v45 quad_perm:[2,3,0,1] row_mask:0xf bank_mask:0xf bound_ctrl:1
	v_pk_fma_f32 v[160:161], v[4:5], v[160:161], v[164:165]
	v_pk_fma_f32 v[44:45], v[4:5], v[44:45], v[162:163]
	v_mov_b32_e32 v164, v160
	v_mov_b32_e32 v165, v161
	v_mov_b32_e32 v162, v44
	v_mov_b32_e32 v163, v45
	v_mov_b32_dpp v164, v164 row_shl:4 row_mask:0xf bank_mask:0x5
	v_mov_b32_dpp v165, v165 row_shl:4 row_mask:0xf bank_mask:0x5
	v_mov_b32_dpp v162, v162 row_shl:4 row_mask:0xf bank_mask:0x5
	v_mov_b32_dpp v163, v163 row_shl:4 row_mask:0xf bank_mask:0x5
	v_mov_b32_dpp v164, v160 row_shr:4 row_mask:0xf bank_mask:0xa
	v_mov_b32_dpp v165, v161 row_shr:4 row_mask:0xf bank_mask:0xa
	v_mov_b32_dpp v162, v44 row_shr:4 row_mask:0xf bank_mask:0xa
	v_mov_b32_dpp v163, v45 row_shr:4 row_mask:0xf bank_mask:0xa
	v_pk_fma_f32 v[160:161], v[6:7], v[160:161], v[164:165]
	v_pk_fma_f32 v[44:45], v[6:7], v[44:45], v[162:163]
	s_nop 0
	v_mov_b32_dpp v164, v160 row_ror:8 row_mask:0xf bank_mask:0xf bound_ctrl:1
	v_mov_b32_dpp v165, v161 row_ror:8 row_mask:0xf bank_mask:0xf bound_ctrl:1
	v_mov_b32_dpp v162, v44 row_ror:8 row_mask:0xf bank_mask:0xf bound_ctrl:1
	v_mov_b32_dpp v163, v45 row_ror:8 row_mask:0xf bank_mask:0xf bound_ctrl:1
	v_pk_fma_f32 v[160:161], v[8:9], v[160:161], v[164:165]
	v_pk_fma_f32 v[44:45], v[10:11], v[44:45], v[162:163]
	v_pk_mul_f32 v[160:161], v[160:161], s[22:23] op_sel_hi:[1,0]
	v_pk_mul_f32 v[44:45], v[44:45], s[22:23] op_sel_hi:[1,0]
	v_cvt_pk_bf16_f32 v159, v160, v161
	s_nop 0
	v_cvt_pk_bf16_f32 v160, v44, v45
	v_lshlrev_b32_e32 v44, 16, v159
	v_and_b32_e32 v45, 0xffff0000, v159
	v_max_f32_e64 v159, |v45|, |v45|
	v_max_f32_e64 v161, |v44|, |v44|
	v_max_f32_e32 v161, v161, v159
	v_lshlrev_b32_e32 v159, 16, v160
	v_and_b32_e32 v160, 0xffff0000, v160
	v_max_f32_e64 v162, |v160|, |v160|
	v_max_f32_e64 v163, |v159|, |v159|
	v_max_f32_e32 v162, v163, v162
	v_max3_f32 v170, v168, v161, v162
	v_lshlrev_b32_e32 v163, 16, v43
	v_lshlrev_b32_e32 v162, 16, v42
	v_and_b32_e32 v43, 0xffff0000, v43
	v_and_b32_e32 v42, 0xffff0000, v42
	v_pk_add_f32 v[164:165], v[162:163], v[42:43]
	v_pk_add_f32 v[42:43], v[162:163], v[42:43] neg_lo:[0,1] neg_hi:[0,1]
	v_mov_b32_e32 v166, v164
	v_pk_mov_b32 v[162:163], v[164:165], v[42:43] op_sel:[1,0]
; __device__ __forceinline__ unsigned cvt_pk_bf16(float lo, float hi) { unsigned r; asm volatile("v_cvt_pk_bf16_f32 %0, %1, %2" : "=v"(r) : "v"(lo), "v"(hi)); return r; }
; __device__ __forceinline__ float bf_lo(unsigned w) { return __uint_as_float(w << 16); }
; __device__ __forceinline__ float bf_hi(unsigned w) { return __uint_as_float(w & 0xffff0000u); }
; __device__ __forceinline__ float xlane1(float t) { return dpp_mov<0xB1, 0xF, true>(0.f, t); }
; __device__ __forceinline__ float xlane2(float t) { return dpp_mov<0x4E, 0xF, true>(0.f, t); }
; __device__ __forceinline__ float xlane4(float t) { const float r = dpp_mov<0x104, 0x5, false>(t, t); return dpp_mov<0x114, 0xA, false>(r, t); }
; __device__ __forceinline__ float xlane8(float t) { return dpp_mov<0x128, 0xF, true>(0.f, t); }
; __device__ __forceinline__ f32x4 rot64(f32x4 t, const RotSigns sg) {
;     { const float p0 = t.x + t.y, p1 = t.x - t.y, p2 = t.z + t.w, p3 = t.z - t.w; t = (f32x4){p0 + p2, p1 + p3, p0 - p2, p1 - p3}; }
;     t = (f32x4){__builtin_fmaf(sg.s1, t.x, xlane1(t.x)), __builtin_fmaf(sg.s1, t.y, xlane1(t.y)), __builtin_fmaf(sg.s1, t.z, xlane1(t.z)), __builtin_fmaf(sg.s1, t.w, xlane1(t.w))};
;     t = (f32x4){__builtin_fmaf(sg.s2, t.x, xlane2(t.x)), __builtin_fmaf(sg.s2, t.y, xlane2(t.y)), __builtin_fmaf(sg.s2, t.z, xlane2(t.z)), __builtin_fmaf(sg.s2, t.w, xlane2(t.w))};
;     t = (f32x4){__builtin_fmaf(sg.s4, t.x, xlane4(t.x)), __builtin_fmaf(sg.s4, t.y, xlane4(t.y)), __builtin_fmaf(sg.s4, t.z, xlane4(t.z)), __builtin_fmaf(sg.s4, t.w, xlane4(t.w))};
;     t = (f32x4){__builtin_fmaf(sg.s8, t.x, xlane8(t.x)), __builtin_fmaf(sg.s8, t.y, xlane8(t.y)), __builtin_fmaf(sg.s8, t.z, xlane8(t.z)), __builtin_fmaf(sg.s8, t.w, xlane8(t.w))};
;     return t * 0.125f;
; __global__ void __launch_bounds__(NWAVES * 64, 2) fwd_kernel(Args args) {
;     ...
;             for (int c = 0; c < DFF / 256; ++c) { const f32x4 t = rot64((f32x4){bf_lo(pk[c].x), bf_hi(pk[c].x), bf_lo(pk[c].y), bf_hi(pk[c].y)}, sg);
;                 pk[c].x = cvt_pk_bf16(t.x, t.y); pk[c].y = cvt_pk_bf16(t.z, t.w);
;                 am = fmaxf(fmaxf(am, fmaxf(fabsf(bf_lo(pk[c].x)), fabsf(bf_hi(pk[c].x)))), fmaxf(fabsf(bf_lo(pk[c].y)), fabsf(bf_hi(pk[c].y)))); }
	v_mov_b32_e32 v167, v43
	v_mov_b32_e32 v168, v164
	v_mov_b32_e32 v169, v42
	v_mov_b32_e32 v42, v165
	v_pk_add_f32 v[162:163], v[166:167], v[162:163]
	v_pk_add_f32 v[42:43], v[168:169], v[42:43] neg_lo:[0,1] neg_hi:[0,1]
	s_nop 0
	v_mov_b32_dpp v166, v162 quad_perm:[1,0,3,2] row_mask:0xf bank_mask:0xf bound_ctrl:1
	v_mov_b32_dpp v167, v163 quad_perm:[1,0,3,2] row_mask:0xf bank_mask:0xf bound_ctrl:1
	v_mov_b32_dpp v164, v42 quad_perm:[1,0,3,2] row_mask:0xf bank_mask:0xf bound_ctrl:1
	v_mov_b32_dpp v165, v43 quad_perm:[1,0,3,2] row_mask:0xf bank_mask:0xf bound_ctrl:1
	v_pk_fma_f32 v[162:163], v[2:3], v[162:163], v[166:167]
	v_pk_fma_f32 v[42:43], v[2:3], v[42:43], v[164:165]
	s_nop 0
	v_mov_b32_dpp v166, v162 quad_perm:[2,3,0,1] row_mask:0xf bank_mask:0xf bound_ctrl:1
	v_mov_b32_dpp v167, v163 quad_perm:[2,3,0,1] row_mask:0xf bank_mask:0xf bound_ctrl:1
	v_mov_b32_dpp v164, v42 quad_perm:[2,3,0,1] row_mask:0xf bank_mask:0xf bound_ctrl:1
	v_mov_b32_dpp v165, v43 quad_perm:[2,3,0,1] row_mask:0xf bank_mask:0xf bound_ctrl:1
	v_pk_fma_f32 v[162:163], v[4:5], v[162:163], v[166:167]
	v_pk_fma_f32 v[42:43], v[4:5], v[42:43], v[164:165]
	v_mov_b32_e32 v166, v162
	v_mov_b32_e32 v167, v163
	v_mov_b32_e32 v164, v42
	v_mov_b32_e32 v165, v43
	v_mov_b32_dpp v166, v166 row_shl:4 row_mask:0xf bank_mask:0x5
	v_mov_b32_dpp v167, v167 row_shl:4 row_mask:0xf bank_mask:0x5
	v_mov_b32_dpp v164, v164 row_shl:4 row_mask:0xf bank_mask:0x5
	v_mov_b32_dpp v165, v165 row_shl:4 row_mask:0xf bank_mask:0x5
	v_mov_b32_dpp v166, v162 row_shr:4 row_mask:0xf bank_mask:0xa
	v_mov_b32_dpp v167, v163 row_shr:4 row_mask:0xf bank_mask:0xa
	v_mov_b32_dpp v164, v42 row_shr:4 row_mask:0xf bank_mask:0xa
	v_mov_b32_dpp v165, v43 row_shr:4 row_mask:0xf bank_mask:0xa
	v_pk_fma_f32 v[162:163], v[6:7], v[162:163], v[166:167]
	v_pk_fma_f32 v[42:43], v[6:7], v[42:43], v[164:165]
	s_nop 0
	v_mov_b32_dpp v166, v162 row_ror:8 row_mask:0xf bank_mask:0xf bound_ctrl:1
	v_mov_b32_dpp v167, v163 row_ror:8 row_mask:0xf bank_mask:0xf bound_ctrl:1
	v_mov_b32_dpp v164, v42 row_ror:8 row_mask:0xf bank_mask:0xf bound_ctrl:1
	v_mov_b32_dpp v165, v43 row_ror:8 row_mask:0xf bank_mask:0xf bound_ctrl:1
	v_pk_fma_f32 v[162:163], v[8:9], v[162:163], v[166:167]
	v_pk_fma_f32 v[42:43], v[10:11], v[42:43], v[164:165]
	v_pk_mul_f32 v[162:163], v[162:163], s[22:23] op_sel_hi:[1,0]
	v_pk_mul_f32 v[42:43], v[42:43], s[22:23] op_sel_hi:[1,0]
	v_cvt_pk_bf16_f32 v161, v162, v163
	s_nop 0
	v_cvt_pk_bf16_f32 v162, v42, v43
	v_lshlrev_b32_e32 v42, 16, v161
	v_and_b32_e32 v43, 0xffff0000, v161
	v_max_f32_e64 v161, |v43|, |v43|
	v_max_f32_e64 v163, |v42|, |v42|
	v_max_f32_e32 v163, v163, v161
	v_lshlrev_b32_e32 v161, 16, v162
	v_and_b32_e32 v162, 0xffff0000, v162
	v_max_f32_e64 v164, |v162|, |v162|
	v_max_f32_e64 v165, |v161|, |v161|
	v_max_f32_e32 v164, v165, v164
	v_max3_f32 v172, v170, v163, v164
	v_lshlrev_b32_e32 v165, 16, v41
	v_lshlrev_b32_e32 v164, 16, v40
	v_and_b32_e32 v41, 0xffff0000, v41
	v_and_b32_e32 v40, 0xffff0000, v40
	v_pk_add_f32 v[166:167], v[164:165], v[40:41]
	v_pk_add_f32 v[40:41], v[164:165], v[40:41] neg_lo:[0,1] neg_hi:[0,1]
	v_mov_b32_e32 v168, v166
	v_pk_mov_b32 v[164:165], v[166:167], v[40:41] op_sel:[1,0]
	v_mov_b32_e32 v169, v41
	v_mov_b32_e32 v170, v166
	v_mov_b32_e32 v171, v40
	v_mov_b32_e32 v40, v167
	v_pk_add_f32 v[164:165], v[168:169], v[164:165]
	v_pk_add_f32 v[40:41], v[170:171], v[40:41] neg_lo:[0,1] neg_hi:[0,1]
	s_nop 0
	v_mov_b32_dpp v168, v164 quad_perm:[1,0,3,2] row_mask:0xf bank_mask:0xf bound_ctrl:1
	v_mov_b32_dpp v169, v165 quad_perm:[1,0,3,2] row_mask:0xf bank_mask:0xf bound_ctrl:1
	v_mov_b32_dpp v166, v40 quad_perm:[1,0,3,2] row_mask:0xf bank_mask:0xf bound_ctrl:1
	v_mov_b32_dpp v167, v41 quad_perm:[1,0,3,2] row_mask:0xf bank_mask:0xf bound_ctrl:1
	v_pk_fma_f32 v[164:165], v[2:3], v[164:165], v[168:169]
	v_pk_fma_f32 v[40:41], v[2:3], v[40:41], v[166:167]
	s_nop 0
	v_mov_b32_dpp v168, v164 quad_perm:[2,3,0,1] row_mask:0xf bank_mask:0xf bound_ctrl:1
	v_mov_b32_dpp v169, v165 quad_perm:[2,3,0,1] row_mask:0xf bank_mask:0xf bound_ctrl:1
	v_mov_b32_dpp v166, v40 quad_perm:[2,3,0,1] row_mask:0xf bank_mask:0xf bound_ctrl:1
	v_mov_b32_dpp v167, v41 quad_perm:[2,3,0,1] row_mask:0xf bank_mask:0xf bound_ctrl:1
	v_pk_fma_f32 v[164:165], v[4:5], v[164:165], v[168:169]
	v_pk_fma_f32 v[40:41], v[4:5], v[40:41], v[166:167]
	v_mov_b32_e32 v168, v164
	v_mov_b32_e32 v169, v165
	v_mov_b32_e32 v166, v40
	v_mov_b32_e32 v167, v41
	v_mov_b32_dpp v168, v168 row_shl:4 row_mask:0xf bank_mask:0x5
	v_mov_b32_dpp v169, v169 row_shl:4 row_mask:0xf bank_mask:0x5
	v_mov_b32_dpp v166, v166 row_shl:4 row_mask:0xf bank_mask:0x5
	v_mov_b32_dpp v167, v167 row_shl:4 row_mask:0xf bank_mask:0x5
	v_mov_b32_dpp v168, v164 row_shr:4 row_mask:0xf bank_mask:0xa
	v_mov_b32_dpp v169, v165 row_shr:4 row_mask:0xf bank_mask:0xa
	v_mov_b32_dpp v166, v40 row_shr:4 row_mask:0xf bank_mask:0xa
	v_mov_b32_dpp v167, v41 row_shr:4 row_mask:0xf bank_mask:0xa
	v_pk_fma_f32 v[164:165], v[6:7], v[164:165], v[168:169]
	v_pk_fma_f32 v[40:41], v[6:7], v[40:41], v[166:167]
	s_nop 0
	v_mov_b32_dpp v168, v164 row_ror:8 row_mask:0xf bank_mask:0xf bound_ctrl:1
	v_mov_b32_dpp v169, v165 row_ror:8 row_mask:0xf bank_mask:0xf bound_ctrl:1
	v_mov_b32_dpp v166, v40 row_ror:8 row_mask:0xf bank_mask:0xf bound_ctrl:1
	v_mov_b32_dpp v167, v41 row_ror:8 row_mask:0xf bank_mask:0xf bound_ctrl:1
	v_pk_fma_f32 v[164:165], v[8:9], v[164:165], v[168:169]
	v_pk_fma_f32 v[40:41], v[10:11], v[40:41], v[166:167]
	v_pk_mul_f32 v[164:165], v[164:165], s[22:23] op_sel_hi:[1,0]
	v_pk_mul_f32 v[40:41], v[40:41], s[22:23] op_sel_hi:[1,0]
	v_cvt_pk_bf16_f32 v163, v164, v165
; __device__ __forceinline__ unsigned cvt_pk_bf16(float lo, float hi) { unsigned r; asm volatile("v_cvt_pk_bf16_f32 %0, %1, %2" : "=v"(r) : "v"(lo), "v"(hi)); return r; }
; __device__ __forceinline__ float bf_lo(unsigned w) { return __uint_as_float(w << 16); }
; __device__ __forceinline__ float bf_hi(unsigned w) { return __uint_as_float(w & 0xffff0000u); }
; __device__ __forceinline__ float xlane1(float t) { return dpp_mov<0xB1, 0xF, true>(0.f, t); }
; __device__ __forceinline__ float xlane2(float t) { return dpp_mov<0x4E, 0xF, true>(0.f, t); }
; __device__ __forceinline__ float xlane4(float t) { const float r = dpp_mov<0x104, 0x5, false>(t, t); return dpp_mov<0x114, 0xA, false>(r, t); }
; __device__ __forceinline__ float xlane8(float t) { return dpp_mov<0x128, 0xF, true>(0.f, t); }
; __device__ __forceinline__ f32x4 rot64(f32x4 t, const RotSigns sg) {
;     { const float p0 = t.x + t.y, p1 = t.x - t.y, p2 = t.z + t.w, p3 = t.z - t.w; t = (f32x4){p0 + p2, p1 + p3, p0 - p2, p1 - p3}; }
;     t = (f32x4){__builtin_fmaf(sg.s1, t.x, xlane1(t.x)), __builtin_fmaf(sg.s1, t.y, xlane1(t.y)), __builtin_fmaf(sg.s1, t.z, xlane1(t.z)), __builtin_fmaf(sg.s1, t.w, xlane1(t.w))};
;     t = (f32x4){__builtin_fmaf(sg.s2, t.x, xlane2(t.x)), __builtin_fmaf(sg.s2, t.y, xlane2(t.y)), __builtin_fmaf(sg.s2, t.z, xlane2(t.z)), __builtin_fmaf(sg.s2, t.w, xlane2(t.w))};
;     t = (f32x4){__builtin_fmaf(sg.s4, t.x, xlane4(t.x)), __builtin_fmaf(sg.s4, t.y, xlane4(t.y)), __builtin_fmaf(sg.s4, t.z, xlane4(t.z)), __builtin_fmaf(sg.s4, t.w, xlane4(t.w))};
;     t = (f32x4){__builtin_fmaf(sg.s8, t.x, xlane8(t.x)), __builtin_fmaf(sg.s8, t.y, xlane8(t.y)), __builtin_fmaf(sg.s8, t.z, xlane8(t.z)), __builtin_fmaf(sg.s8, t.w, xlane8(t.w))};
;     return t * 0.125f;
; __global__ void __launch_bounds__(NWAVES * 64, 2) fwd_kernel(Args args) {
;     ...
;             for (int c = 0; c < DFF / 256; ++c) { const f32x4 t = rot64((f32x4){bf_lo(pk[c].x), bf_hi(pk[c].x), bf_lo(pk[c].y), bf_hi(pk[c].y)}, sg);
;                 pk[c].x = cvt_pk_bf16(t.x, t.y); pk[c].y = cvt_pk_bf16(t.z, t.w);
;                 am = fmaxf(fmaxf(am, fmaxf(fabsf(bf_lo(pk[c].x)), fabsf(bf_hi(pk[c].x)))), fmaxf(fabsf(bf_lo(pk[c].y)), fabsf(bf_hi(pk[c].y)))); }
	s_nop 0
	v_cvt_pk_bf16_f32 v164, v40, v41
	v_lshlrev_b32_e32 v40, 16, v163
	v_and_b32_e32 v41, 0xffff0000, v163
	v_max_f32_e64 v163, |v41|, |v41|
	v_max_f32_e64 v165, |v40|, |v40|
	v_max_f32_e32 v165, v165, v163
	v_lshlrev_b32_e32 v163, 16, v164
	v_and_b32_e32 v164, 0xffff0000, v164
	v_max_f32_e64 v166, |v164|, |v164|
	v_max_f32_e64 v167, |v163|, |v163|
	v_max_f32_e32 v166, v167, v166
	v_max3_f32 v174, v172, v165, v166
	v_lshlrev_b32_e32 v167, 16, v39
	v_lshlrev_b32_e32 v166, 16, v38
	v_and_b32_e32 v39, 0xffff0000, v39
	v_and_b32_e32 v38, 0xffff0000, v38
	v_pk_add_f32 v[168:169], v[166:167], v[38:39]
	v_pk_add_f32 v[38:39], v[166:167], v[38:39] neg_lo:[0,1] neg_hi:[0,1]
	v_mov_b32_e32 v170, v168
	v_pk_mov_b32 v[166:167], v[168:169], v[38:39] op_sel:[1,0]
	v_mov_b32_e32 v171, v39
	v_mov_b32_e32 v172, v168
	v_mov_b32_e32 v173, v38
	v_mov_b32_e32 v38, v169
	v_pk_add_f32 v[166:167], v[170:171], v[166:167]
	v_pk_add_f32 v[38:39], v[172:173], v[38:39] neg_lo:[0,1] neg_hi:[0,1]
	s_nop 0
	v_mov_b32_dpp v170, v166 quad_perm:[1,0,3,2] row_mask:0xf bank_mask:0xf bound_ctrl:1
	v_mov_b32_dpp v171, v167 quad_perm:[1,0,3,2] row_mask:0xf bank_mask:0xf bound_ctrl:1
	v_mov_b32_dpp v168, v38 quad_perm:[1,0,3,2] row_mask:0xf bank_mask:0xf bound_ctrl:1
	v_mov_b32_dpp v169, v39 quad_perm:[1,0,3,2] row_mask:0xf bank_mask:0xf bound_ctrl:1
	v_pk_fma_f32 v[166:167], v[2:3], v[166:167], v[170:171]
	v_pk_fma_f32 v[38:39], v[2:3], v[38:39], v[168:169]
	s_nop 0
	v_mov_b32_dpp v170, v166 quad_perm:[2,3,0,1] row_mask:0xf bank_mask:0xf bound_ctrl:1
	v_mov_b32_dpp v171, v167 quad_perm:[2,3,0,1] row_mask:0xf bank_mask:0xf bound_ctrl:1
	v_mov_b32_dpp v168, v38 quad_perm:[2,3,0,1] row_mask:0xf bank_mask:0xf bound_ctrl:1
	v_mov_b32_dpp v169, v39 quad_perm:[2,3,0,1] row_mask:0xf bank_mask:0xf bound_ctrl:1
	v_pk_fma_f32 v[166:167], v[4:5], v[166:167], v[170:171]
	v_pk_fma_f32 v[38:39], v[4:5], v[38:39], v[168:169]
	v_mov_b32_e32 v170, v166
	v_mov_b32_e32 v171, v167
	v_mov_b32_e32 v168, v38
	v_mov_b32_e32 v169, v39
	v_mov_b32_dpp v170, v170 row_shl:4 row_mask:0xf bank_mask:0x5
	v_mov_b32_dpp v171, v171 row_shl:4 row_mask:0xf bank_mask:0x5
	v_mov_b32_dpp v168, v168 row_shl:4 row_mask:0xf bank_mask:0x5
	v_mov_b32_dpp v169, v169 row_shl:4 row_mask:0xf bank_mask:0x5
	v_mov_b32_dpp v170, v166 row_shr:4 row_mask:0xf bank_mask:0xa
	v_mov_b32_dpp v171, v167 row_shr:4 row_mask:0xf bank_mask:0xa
	v_mov_b32_dpp v168, v38 row_shr:4 row_mask:0xf bank_mask:0xa
	v_mov_b32_dpp v169, v39 row_shr:4 row_mask:0xf bank_mask:0xa
	v_pk_fma_f32 v[166:167], v[6:7], v[166:167], v[170:171]
	v_pk_fma_f32 v[38:39], v[6:7], v[38:39], v[168:169]
	s_nop 0
	v_mov_b32_dpp v170, v166 row_ror:8 row_mask:0xf bank_mask:0xf bound_ctrl:1
	v_mov_b32_dpp v171, v167 row_ror:8 row_mask:0xf bank_mask:0xf bound_ctrl:1
	v_mov_b32_dpp v168, v38 row_ror:8 row_mask:0xf bank_mask:0xf bound_ctrl:1
	v_mov_b32_dpp v169, v39 row_ror:8 row_mask:0xf bank_mask:0xf bound_ctrl:1
	v_pk_fma_f32 v[166:167], v[8:9], v[166:167], v[170:171]
	v_pk_fma_f32 v[38:39], v[10:11], v[38:39], v[168:169]
	v_pk_mul_f32 v[166:167], v[166:167], s[22:23] op_sel_hi:[1,0]
	v_pk_mul_f32 v[38:39], v[38:39], s[22:23] op_sel_hi:[1,0]
	v_cvt_pk_bf16_f32 v165, v166, v167
	s_nop 0
	v_cvt_pk_bf16_f32 v166, v38, v39
	v_lshlrev_b32_e32 v38, 16, v165
	v_and_b32_e32 v39, 0xffff0000, v165
	v_max_f32_e64 v165, |v39|, |v39|
	v_max_f32_e64 v167, |v38|, |v38|
	v_max_f32_e32 v167, v167, v165
	v_lshlrev_b32_e32 v165, 16, v166
	v_and_b32_e32 v166, 0xffff0000, v166
	v_max_f32_e64 v168, |v166|, |v166|
	v_max_f32_e64 v169, |v165|, |v165|
	v_max_f32_e32 v168, v169, v168
	v_max3_f32 v176, v174, v167, v168
	v_lshlrev_b32_e32 v169, 16, v37
	v_lshlrev_b32_e32 v168, 16, v36
	v_and_b32_e32 v37, 0xffff0000, v37
	v_and_b32_e32 v36, 0xffff0000, v36
	v_pk_add_f32 v[170:171], v[168:169], v[36:37]
	v_pk_add_f32 v[36:37], v[168:169], v[36:37] neg_lo:[0,1] neg_hi:[0,1]
	v_mov_b32_e32 v172, v170
	v_pk_mov_b32 v[168:169], v[170:171], v[36:37] op_sel:[1,0]
	v_mov_b32_e32 v173, v37
	v_mov_b32_e32 v174, v170
	v_mov_b32_e32 v175, v36
	v_mov_b32_e32 v36, v171
	v_pk_add_f32 v[168:169], v[172:173], v[168:169]
	v_pk_add_f32 v[36:37], v[174:175], v[36:37] neg_lo:[0,1] neg_hi:[0,1]
	s_nop 0
	v_mov_b32_dpp v172, v168 quad_perm:[1,0,3,2] row_mask:0xf bank_mask:0xf bound_ctrl:1
	v_mov_b32_dpp v173, v169 quad_perm:[1,0,3,2] row_mask:0xf bank_mask:0xf bound_ctrl:1
	v_mov_b32_dpp v170, v36 quad_perm:[1,0,3,2] row_mask:0xf bank_mask:0xf bound_ctrl:1
	v_mov_b32_dpp v171, v37 quad_perm:[1,0,3,2] row_mask:0xf bank_mask:0xf bound_ctrl:1
	v_pk_fma_f32 v[168:169], v[2:3], v[168:169], v[172:173]
	v_pk_fma_f32 v[36:37], v[2:3], v[36:37], v[170:171]
	s_nop 0
	v_mov_b32_dpp v172, v168 quad_perm:[2,3,0,1] row_mask:0xf bank_mask:0xf bound_ctrl:1
	v_mov_b32_dpp v173, v169 quad_perm:[2,3,0,1] row_mask:0xf bank_mask:0xf bound_ctrl:1
	v_mov_b32_dpp v170, v36 quad_perm:[2,3,0,1] row_mask:0xf bank_mask:0xf bound_ctrl:1
	v_mov_b32_dpp v171, v37 quad_perm:[2,3,0,1] row_mask:0xf bank_mask:0xf bound_ctrl:1
	v_pk_fma_f32 v[168:169], v[4:5], v[168:169], v[172:173]
	v_pk_fma_f32 v[36:37], v[4:5], v[36:37], v[170:171]
	v_mov_b32_e32 v172, v168
	v_mov_b32_e32 v173, v169
	v_mov_b32_e32 v170, v36
	v_mov_b32_e32 v171, v37
	v_mov_b32_dpp v172, v172 row_shl:4 row_mask:0xf bank_mask:0x5
	v_mov_b32_dpp v173, v173 row_shl:4 row_mask:0xf bank_mask:0x5
	v_mov_b32_dpp v170, v170 row_shl:4 row_mask:0xf bank_mask:0x5
	v_mov_b32_dpp v171, v171 row_shl:4 row_mask:0xf bank_mask:0x5
	v_mov_b32_dpp v172, v168 row_shr:4 row_mask:0xf bank_mask:0xa
	v_mov_b32_dpp v173, v169 row_shr:4 row_mask:0xf bank_mask:0xa
	v_mov_b32_dpp v170, v36 row_shr:4 row_mask:0xf bank_mask:0xa
; __device__ __forceinline__ unsigned cvt_pk_bf16(float lo, float hi) { unsigned r; asm volatile("v_cvt_pk_bf16_f32 %0, %1, %2" : "=v"(r) : "v"(lo), "v"(hi)); return r; }
; __device__ __forceinline__ float bf_lo(unsigned w) { return __uint_as_float(w << 16); }
; __device__ __forceinline__ float bf_hi(unsigned w) { return __uint_as_float(w & 0xffff0000u); }
; __device__ __forceinline__ float xlane1(float t) { return dpp_mov<0xB1, 0xF, true>(0.f, t); }
; __device__ __forceinline__ float xlane2(float t) { return dpp_mov<0x4E, 0xF, true>(0.f, t); }
; __device__ __forceinline__ float xlane4(float t) { const float r = dpp_mov<0x104, 0x5, false>(t, t); return dpp_mov<0x114, 0xA, false>(r, t); }
; __device__ __forceinline__ float xlane8(float t) { return dpp_mov<0x128, 0xF, true>(0.f, t); }
; __device__ __forceinline__ f32x4 rot64(f32x4 t, const RotSigns sg) {
;     { const float p0 = t.x + t.y, p1 = t.x - t.y, p2 = t.z + t.w, p3 = t.z - t.w; t = (f32x4){p0 + p2, p1 + p3, p0 - p2, p1 - p3}; }
;     t = (f32x4){__builtin_fmaf(sg.s1, t.x, xlane1(t.x)), __builtin_fmaf(sg.s1, t.y, xlane1(t.y)), __builtin_fmaf(sg.s1, t.z, xlane1(t.z)), __builtin_fmaf(sg.s1, t.w, xlane1(t.w))};
;     t = (f32x4){__builtin_fmaf(sg.s2, t.x, xlane2(t.x)), __builtin_fmaf(sg.s2, t.y, xlane2(t.y)), __builtin_fmaf(sg.s2, t.z, xlane2(t.z)), __builtin_fmaf(sg.s2, t.w, xlane2(t.w))};
;     t = (f32x4){__builtin_fmaf(sg.s4, t.x, xlane4(t.x)), __builtin_fmaf(sg.s4, t.y, xlane4(t.y)), __builtin_fmaf(sg.s4, t.z, xlane4(t.z)), __builtin_fmaf(sg.s4, t.w, xlane4(t.w))};
;     t = (f32x4){__builtin_fmaf(sg.s8, t.x, xlane8(t.x)), __builtin_fmaf(sg.s8, t.y, xlane8(t.y)), __builtin_fmaf(sg.s8, t.z, xlane8(t.z)), __builtin_fmaf(sg.s8, t.w, xlane8(t.w))};
;     return t * 0.125f;
; __global__ void __launch_bounds__(NWAVES * 64, 2) fwd_kernel(Args args) {
;     ...
;             for (int c = 0; c < DFF / 256; ++c) { const f32x4 t = rot64((f32x4){bf_lo(pk[c].x), bf_hi(pk[c].x), bf_lo(pk[c].y), bf_hi(pk[c].y)}, sg);
;                 pk[c].x = cvt_pk_bf16(t.x, t.y); pk[c].y = cvt_pk_bf16(t.z, t.w);
;                 am = fmaxf(fmaxf(am, fmaxf(fabsf(bf_lo(pk[c].x)), fabsf(bf_hi(pk[c].x)))), fmaxf(fabsf(bf_lo(pk[c].y)), fabsf(bf_hi(pk[c].y)))); }
	v_mov_b32_dpp v171, v37 row_shr:4 row_mask:0xf bank_mask:0xa
	v_pk_fma_f32 v[168:169], v[6:7], v[168:169], v[172:173]
	v_pk_fma_f32 v[36:37], v[6:7], v[36:37], v[170:171]
	s_nop 0
	v_mov_b32_dpp v172, v168 row_ror:8 row_mask:0xf bank_mask:0xf bound_ctrl:1
	v_mov_b32_dpp v173, v169 row_ror:8 row_mask:0xf bank_mask:0xf bound_ctrl:1
	v_mov_b32_dpp v170, v36 row_ror:8 row_mask:0xf bank_mask:0xf bound_ctrl:1
	v_mov_b32_dpp v171, v37 row_ror:8 row_mask:0xf bank_mask:0xf bound_ctrl:1
	v_pk_fma_f32 v[168:169], v[8:9], v[168:169], v[172:173]
	v_pk_fma_f32 v[36:37], v[10:11], v[36:37], v[170:171]
	v_pk_mul_f32 v[168:169], v[168:169], s[22:23] op_sel_hi:[1,0]
	v_pk_mul_f32 v[36:37], v[36:37], s[22:23] op_sel_hi:[1,0]
	v_cvt_pk_bf16_f32 v167, v168, v169
	s_nop 0
	v_cvt_pk_bf16_f32 v168, v36, v37
	v_lshlrev_b32_e32 v36, 16, v167
	v_and_b32_e32 v37, 0xffff0000, v167
	v_max_f32_e64 v167, |v37|, |v37|
	v_max_f32_e64 v169, |v36|, |v36|
	v_max_f32_e32 v169, v169, v167
	v_lshlrev_b32_e32 v167, 16, v168
	v_and_b32_e32 v168, 0xffff0000, v168
	v_max_f32_e64 v170, |v168|, |v168|
	v_max_f32_e64 v171, |v167|, |v167|
	v_max_f32_e32 v170, v171, v170
	v_max3_f32 v181, v176, v169, v170
	v_lshlrev_b32_e32 v171, 16, v35
	v_lshlrev_b32_e32 v170, 16, v34
	v_and_b32_e32 v35, 0xffff0000, v35
	v_and_b32_e32 v34, 0xffff0000, v34
	v_pk_add_f32 v[172:173], v[170:171], v[34:35]
	v_pk_add_f32 v[34:35], v[170:171], v[34:35] neg_lo:[0,1] neg_hi:[0,1]
	v_mov_b32_e32 v174, v172
	v_pk_mov_b32 v[170:171], v[172:173], v[34:35] op_sel:[1,0]
	v_mov_b32_e32 v175, v35
	v_mov_b32_e32 v176, v172
	v_mov_b32_e32 v177, v34
	v_mov_b32_e32 v34, v173
	v_pk_add_f32 v[170:171], v[174:175], v[170:171]
	v_pk_add_f32 v[34:35], v[176:177], v[34:35] neg_lo:[0,1] neg_hi:[0,1]
	s_nop 0
	v_mov_b32_dpp v174, v170 quad_perm:[1,0,3,2] row_mask:0xf bank_mask:0xf bound_ctrl:1
	v_mov_b32_dpp v175, v171 quad_perm:[1,0,3,2] row_mask:0xf bank_mask:0xf bound_ctrl:1
	v_mov_b32_dpp v172, v34 quad_perm:[1,0,3,2] row_mask:0xf bank_mask:0xf bound_ctrl:1
	v_mov_b32_dpp v173, v35 quad_perm:[1,0,3,2] row_mask:0xf bank_mask:0xf bound_ctrl:1
	v_pk_fma_f32 v[170:171], v[2:3], v[170:171], v[174:175]
	v_pk_fma_f32 v[34:35], v[2:3], v[34:35], v[172:173]
	s_nop 0
	v_mov_b32_dpp v174, v170 quad_perm:[2,3,0,1] row_mask:0xf bank_mask:0xf bound_ctrl:1
	v_mov_b32_dpp v175, v171 quad_perm:[2,3,0,1] row_mask:0xf bank_mask:0xf bound_ctrl:1
	v_mov_b32_dpp v172, v34 quad_perm:[2,3,0,1] row_mask:0xf bank_mask:0xf bound_ctrl:1
	v_mov_b32_dpp v173, v35 quad_perm:[2,3,0,1] row_mask:0xf bank_mask:0xf bound_ctrl:1
	v_pk_fma_f32 v[170:171], v[4:5], v[170:171], v[174:175]
	v_pk_fma_f32 v[34:35], v[4:5], v[34:35], v[172:173]
	v_mov_b32_e32 v174, v170
	v_mov_b32_e32 v175, v171
	v_mov_b32_e32 v172, v34
	v_mov_b32_e32 v173, v35
	v_mov_b32_dpp v174, v174 row_shl:4 row_mask:0xf bank_mask:0x5
	v_mov_b32_dpp v175, v175 row_shl:4 row_mask:0xf bank_mask:0x5
	v_mov_b32_dpp v172, v172 row_shl:4 row_mask:0xf bank_mask:0x5
	v_mov_b32_dpp v173, v173 row_shl:4 row_mask:0xf bank_mask:0x5
	v_mov_b32_dpp v174, v170 row_shr:4 row_mask:0xf bank_mask:0xa
	v_mov_b32_dpp v175, v171 row_shr:4 row_mask:0xf bank_mask:0xa
	v_mov_b32_dpp v172, v34 row_shr:4 row_mask:0xf bank_mask:0xa
	v_mov_b32_dpp v173, v35 row_shr:4 row_mask:0xf bank_mask:0xa
	v_pk_fma_f32 v[170:171], v[6:7], v[170:171], v[174:175]
	v_pk_fma_f32 v[34:35], v[6:7], v[34:35], v[172:173]
	s_nop 0
	v_mov_b32_dpp v174, v170 row_ror:8 row_mask:0xf bank_mask:0xf bound_ctrl:1
	v_mov_b32_dpp v175, v171 row_ror:8 row_mask:0xf bank_mask:0xf bound_ctrl:1
	v_mov_b32_dpp v172, v34 row_ror:8 row_mask:0xf bank_mask:0xf bound_ctrl:1
	v_mov_b32_dpp v173, v35 row_ror:8 row_mask:0xf bank_mask:0xf bound_ctrl:1
	v_pk_fma_f32 v[170:171], v[8:9], v[170:171], v[174:175]
	v_pk_fma_f32 v[34:35], v[10:11], v[34:35], v[172:173]
	v_pk_mul_f32 v[170:171], v[170:171], s[22:23] op_sel_hi:[1,0]
	v_pk_mul_f32 v[34:35], v[34:35], s[22:23] op_sel_hi:[1,0]
	v_cvt_pk_bf16_f32 v169, v170, v171
	s_nop 0
	v_cvt_pk_bf16_f32 v170, v34, v35
	v_lshlrev_b32_e32 v34, 16, v169
	v_and_b32_e32 v35, 0xffff0000, v169
	v_max_f32_e64 v169, |v35|, |v35|
	v_max_f32_e64 v171, |v34|, |v34|
	v_max_f32_e32 v171, v171, v169
	v_lshlrev_b32_e32 v169, 16, v170
	v_and_b32_e32 v170, 0xffff0000, v170
	v_max_f32_e64 v172, |v170|, |v170|
	v_max_f32_e64 v173, |v169|, |v169|
	v_max_f32_e32 v172, v173, v172
	v_max3_f32 v181, v181, v171, v172
	v_lshlrev_b32_e32 v173, 16, v33
	v_lshlrev_b32_e32 v172, 16, v32
	v_and_b32_e32 v33, 0xffff0000, v33
	v_and_b32_e32 v32, 0xffff0000, v32
	v_pk_add_f32 v[174:175], v[172:173], v[32:33]
	v_pk_add_f32 v[32:33], v[172:173], v[32:33] neg_lo:[0,1] neg_hi:[0,1]
	v_mov_b32_e32 v176, v174
	v_pk_mov_b32 v[172:173], v[174:175], v[32:33] op_sel:[1,0]
	v_mov_b32_e32 v177, v33
	v_mov_b32_e32 v182, v174
	v_mov_b32_e32 v183, v32
	v_mov_b32_e32 v32, v175
	v_pk_add_f32 v[172:173], v[176:177], v[172:173]
	v_pk_add_f32 v[32:33], v[182:183], v[32:33] neg_lo:[0,1] neg_hi:[0,1]
	s_nop 0
	v_mov_b32_dpp v176, v172 quad_perm:[1,0,3,2] row_mask:0xf bank_mask:0xf bound_ctrl:1
	v_mov_b32_dpp v177, v173 quad_perm:[1,0,3,2] row_mask:0xf bank_mask:0xf bound_ctrl:1
	v_mov_b32_dpp v174, v32 quad_perm:[1,0,3,2] row_mask:0xf bank_mask:0xf bound_ctrl:1
	v_mov_b32_dpp v175, v33 quad_perm:[1,0,3,2] row_mask:0xf bank_mask:0xf bound_ctrl:1
	v_pk_fma_f32 v[172:173], v[2:3], v[172:173], v[176:177]
	v_pk_fma_f32 v[32:33], v[2:3], v[32:33], v[174:175]
	s_nop 0
	v_mov_b32_dpp v176, v172 quad_perm:[2,3,0,1] row_mask:0xf bank_mask:0xf bound_ctrl:1
	v_mov_b32_dpp v177, v173 quad_perm:[2,3,0,1] row_mask:0xf bank_mask:0xf bound_ctrl:1
	v_mov_b32_dpp v174, v32 quad_perm:[2,3,0,1] row_mask:0xf bank_mask:0xf bound_ctrl:1
; __device__ __forceinline__ unsigned cvt_pk_bf16(float lo, float hi) { unsigned r; asm volatile("v_cvt_pk_bf16_f32 %0, %1, %2" : "=v"(r) : "v"(lo), "v"(hi)); return r; }
; __device__ __forceinline__ float bf_lo(unsigned w) { return __uint_as_float(w << 16); }
; __device__ __forceinline__ float bf_hi(unsigned w) { return __uint_as_float(w & 0xffff0000u); }
; __device__ __forceinline__ float xlane1(float t) { return dpp_mov<0xB1, 0xF, true>(0.f, t); }
; __device__ __forceinline__ float xlane2(float t) { return dpp_mov<0x4E, 0xF, true>(0.f, t); }
; __device__ __forceinline__ float xlane4(float t) { const float r = dpp_mov<0x104, 0x5, false>(t, t); return dpp_mov<0x114, 0xA, false>(r, t); }
; __device__ __forceinline__ float xlane8(float t) { return dpp_mov<0x128, 0xF, true>(0.f, t); }
; __device__ __forceinline__ f32x4 rot64(f32x4 t, const RotSigns sg) {
;     { const float p0 = t.x + t.y, p1 = t.x - t.y, p2 = t.z + t.w, p3 = t.z - t.w; t = (f32x4){p0 + p2, p1 + p3, p0 - p2, p1 - p3}; }
;     t = (f32x4){__builtin_fmaf(sg.s1, t.x, xlane1(t.x)), __builtin_fmaf(sg.s1, t.y, xlane1(t.y)), __builtin_fmaf(sg.s1, t.z, xlane1(t.z)), __builtin_fmaf(sg.s1, t.w, xlane1(t.w))};
;     t = (f32x4){__builtin_fmaf(sg.s2, t.x, xlane2(t.x)), __builtin_fmaf(sg.s2, t.y, xlane2(t.y)), __builtin_fmaf(sg.s2, t.z, xlane2(t.z)), __builtin_fmaf(sg.s2, t.w, xlane2(t.w))};
;     t = (f32x4){__builtin_fmaf(sg.s4, t.x, xlane4(t.x)), __builtin_fmaf(sg.s4, t.y, xlane4(t.y)), __builtin_fmaf(sg.s4, t.z, xlane4(t.z)), __builtin_fmaf(sg.s4, t.w, xlane4(t.w))};
;     t = (f32x4){__builtin_fmaf(sg.s8, t.x, xlane8(t.x)), __builtin_fmaf(sg.s8, t.y, xlane8(t.y)), __builtin_fmaf(sg.s8, t.z, xlane8(t.z)), __builtin_fmaf(sg.s8, t.w, xlane8(t.w))};
;     return t * 0.125f;
; __global__ void __launch_bounds__(NWAVES * 64, 2) fwd_kernel(Args args) {
;     ...
;             for (int c = 0; c < DFF / 256; ++c) { const f32x4 t = rot64((f32x4){bf_lo(pk[c].x), bf_hi(pk[c].x), bf_lo(pk[c].y), bf_hi(pk[c].y)}, sg);
;                 pk[c].x = cvt_pk_bf16(t.x, t.y); pk[c].y = cvt_pk_bf16(t.z, t.w);
;                 am = fmaxf(fmaxf(am, fmaxf(fabsf(bf_lo(pk[c].x)), fabsf(bf_hi(pk[c].x)))), fmaxf(fabsf(bf_lo(pk[c].y)), fabsf(bf_hi(pk[c].y)))); }
	v_mov_b32_dpp v175, v33 quad_perm:[2,3,0,1] row_mask:0xf bank_mask:0xf bound_ctrl:1
	v_pk_fma_f32 v[172:173], v[4:5], v[172:173], v[176:177]
	v_pk_fma_f32 v[32:33], v[4:5], v[32:33], v[174:175]
	v_mov_b32_e32 v176, v172
	v_mov_b32_e32 v177, v173
	v_mov_b32_e32 v174, v32
	v_mov_b32_e32 v175, v33
	v_mov_b32_dpp v176, v176 row_shl:4 row_mask:0xf bank_mask:0x5
	v_mov_b32_dpp v177, v177 row_shl:4 row_mask:0xf bank_mask:0x5
	v_mov_b32_dpp v174, v174 row_shl:4 row_mask:0xf bank_mask:0x5
	v_mov_b32_dpp v175, v175 row_shl:4 row_mask:0xf bank_mask:0x5
	v_mov_b32_dpp v176, v172 row_shr:4 row_mask:0xf bank_mask:0xa
	v_mov_b32_dpp v177, v173 row_shr:4 row_mask:0xf bank_mask:0xa
	v_mov_b32_dpp v174, v32 row_shr:4 row_mask:0xf bank_mask:0xa
	v_mov_b32_dpp v175, v33 row_shr:4 row_mask:0xf bank_mask:0xa
	v_pk_fma_f32 v[172:173], v[6:7], v[172:173], v[176:177]
	v_pk_fma_f32 v[32:33], v[6:7], v[32:33], v[174:175]
	s_nop 0
	v_mov_b32_dpp v176, v172 row_ror:8 row_mask:0xf bank_mask:0xf bound_ctrl:1
	v_mov_b32_dpp v177, v173 row_ror:8 row_mask:0xf bank_mask:0xf bound_ctrl:1
	v_mov_b32_dpp v174, v32 row_ror:8 row_mask:0xf bank_mask:0xf bound_ctrl:1
	v_mov_b32_dpp v175, v33 row_ror:8 row_mask:0xf bank_mask:0xf bound_ctrl:1
	v_pk_fma_f32 v[172:173], v[8:9], v[172:173], v[176:177]
	v_pk_fma_f32 v[32:33], v[10:11], v[32:33], v[174:175]
	v_pk_mul_f32 v[172:173], v[172:173], s[22:23] op_sel_hi:[1,0]
	v_pk_mul_f32 v[32:33], v[32:33], s[22:23] op_sel_hi:[1,0]
	v_cvt_pk_bf16_f32 v171, v172, v173
	s_nop 0
	v_cvt_pk_bf16_f32 v172, v32, v33
	v_lshlrev_b32_e32 v32, 16, v171
	v_and_b32_e32 v33, 0xffff0000, v171
	v_max_f32_e64 v171, |v33|, |v33|
	v_max_f32_e64 v173, |v32|, |v32|
	v_max_f32_e32 v173, v173, v171
	v_lshlrev_b32_e32 v171, 16, v172
	v_and_b32_e32 v172, 0xffff0000, v172
	v_max_f32_e64 v174, |v172|, |v172|
	v_max_f32_e64 v175, |v171|, |v171|
	v_max_f32_e32 v174, v175, v174
	v_max3_f32 v181, v181, v173, v174
	v_lshlrev_b32_e32 v175, 16, v31
	v_lshlrev_b32_e32 v174, 16, v30
	v_and_b32_e32 v31, 0xffff0000, v31
	v_and_b32_e32 v30, 0xffff0000, v30
	v_pk_add_f32 v[176:177], v[174:175], v[30:31]
	v_pk_add_f32 v[30:31], v[174:175], v[30:31] neg_lo:[0,1] neg_hi:[0,1]
	v_mov_b32_e32 v182, v176
	v_pk_mov_b32 v[174:175], v[176:177], v[30:31] op_sel:[1,0]
	v_mov_b32_e32 v183, v31
	v_mov_b32_e32 v184, v176
	v_mov_b32_e32 v185, v30
	v_mov_b32_e32 v30, v177
	v_pk_add_f32 v[174:175], v[182:183], v[174:175]
	v_pk_add_f32 v[30:31], v[184:185], v[30:31] neg_lo:[0,1] neg_hi:[0,1]
	s_nop 0
	v_mov_b32_dpp v182, v174 quad_perm:[1,0,3,2] row_mask:0xf bank_mask:0xf bound_ctrl:1
	v_mov_b32_dpp v183, v175 quad_perm:[1,0,3,2] row_mask:0xf bank_mask:0xf bound_ctrl:1
	v_mov_b32_dpp v176, v30 quad_perm:[1,0,3,2] row_mask:0xf bank_mask:0xf bound_ctrl:1
	v_mov_b32_dpp v177, v31 quad_perm:[1,0,3,2] row_mask:0xf bank_mask:0xf bound_ctrl:1
	v_pk_fma_f32 v[174:175], v[2:3], v[174:175], v[182:183]
	v_pk_fma_f32 v[30:31], v[2:3], v[30:31], v[176:177]
	s_nop 0
	v_mov_b32_dpp v182, v174 quad_perm:[2,3,0,1] row_mask:0xf bank_mask:0xf bound_ctrl:1
	v_mov_b32_dpp v183, v175 quad_perm:[2,3,0,1] row_mask:0xf bank_mask:0xf bound_ctrl:1
	v_mov_b32_dpp v176, v30 quad_perm:[2,3,0,1] row_mask:0xf bank_mask:0xf bound_ctrl:1
	v_mov_b32_dpp v177, v31 quad_perm:[2,3,0,1] row_mask:0xf bank_mask:0xf bound_ctrl:1
	v_pk_fma_f32 v[174:175], v[4:5], v[174:175], v[182:183]
	v_pk_fma_f32 v[30:31], v[4:5], v[30:31], v[176:177]
	v_mov_b32_e32 v182, v174
	v_mov_b32_e32 v183, v175
	v_mov_b32_e32 v176, v30
	v_mov_b32_e32 v177, v31
	v_mov_b32_dpp v182, v182 row_shl:4 row_mask:0xf bank_mask:0x5
	v_mov_b32_dpp v183, v183 row_shl:4 row_mask:0xf bank_mask:0x5
	v_mov_b32_dpp v176, v176 row_shl:4 row_mask:0xf bank_mask:0x5
	v_mov_b32_dpp v177, v177 row_shl:4 row_mask:0xf bank_mask:0x5
	v_mov_b32_dpp v182, v174 row_shr:4 row_mask:0xf bank_mask:0xa
	v_mov_b32_dpp v183, v175 row_shr:4 row_mask:0xf bank_mask:0xa
	v_mov_b32_dpp v176, v30 row_shr:4 row_mask:0xf bank_mask:0xa
	v_mov_b32_dpp v177, v31 row_shr:4 row_mask:0xf bank_mask:0xa
	v_pk_fma_f32 v[174:175], v[6:7], v[174:175], v[182:183]
	v_pk_fma_f32 v[30:31], v[6:7], v[30:31], v[176:177]
	s_nop 0
	v_mov_b32_dpp v182, v174 row_ror:8 row_mask:0xf bank_mask:0xf bound_ctrl:1
	v_mov_b32_dpp v183, v175 row_ror:8 row_mask:0xf bank_mask:0xf bound_ctrl:1
	v_mov_b32_dpp v176, v30 row_ror:8 row_mask:0xf bank_mask:0xf bound_ctrl:1
	v_mov_b32_dpp v177, v31 row_ror:8 row_mask:0xf bank_mask:0xf bound_ctrl:1
	v_pk_fma_f32 v[174:175], v[8:9], v[174:175], v[182:183]
	v_pk_fma_f32 v[30:31], v[10:11], v[30:31], v[176:177]
	v_pk_mul_f32 v[174:175], v[174:175], s[22:23] op_sel_hi:[1,0]
	v_pk_mul_f32 v[30:31], v[30:31], s[22:23] op_sel_hi:[1,0]
	v_cvt_pk_bf16_f32 v173, v174, v175
	s_nop 0
	v_cvt_pk_bf16_f32 v174, v30, v31
	v_lshlrev_b32_e32 v30, 16, v173
	v_and_b32_e32 v31, 0xffff0000, v173
	v_max_f32_e64 v173, |v31|, |v31|
	v_max_f32_e64 v175, |v30|, |v30|
	v_max_f32_e32 v175, v175, v173
	v_lshlrev_b32_e32 v173, 16, v174
	v_and_b32_e32 v174, 0xffff0000, v174
	v_max_f32_e64 v176, |v174|, |v174|
	v_max_f32_e64 v177, |v173|, |v173|
	v_max_f32_e32 v176, v177, v176
	v_max3_f32 v181, v181, v175, v176
	v_lshlrev_b32_e32 v177, 16, v29
	v_lshlrev_b32_e32 v176, 16, v28
	v_and_b32_e32 v29, 0xffff0000, v29
	v_and_b32_e32 v28, 0xffff0000, v28
	v_pk_add_f32 v[182:183], v[176:177], v[28:29]
	v_pk_add_f32 v[28:29], v[176:177], v[28:29] neg_lo:[0,1] neg_hi:[0,1]
	v_mov_b32_e32 v184, v182
	v_pk_mov_b32 v[176:177], v[182:183], v[28:29] op_sel:[1,0]
	v_mov_b32_e32 v185, v29
	v_mov_b32_e32 v186, v182
	v_mov_b32_e32 v187, v28
	v_mov_b32_e32 v28, v183
	v_pk_add_f32 v[176:177], v[184:185], v[176:177]
; __device__ __forceinline__ unsigned cvt_pk_bf16(float lo, float hi) { unsigned r; asm volatile("v_cvt_pk_bf16_f32 %0, %1, %2" : "=v"(r) : "v"(lo), "v"(hi)); return r; }
; __device__ __forceinline__ float bf_lo(unsigned w) { return __uint_as_float(w << 16); }
; __device__ __forceinline__ float bf_hi(unsigned w) { return __uint_as_float(w & 0xffff0000u); }
; __device__ __forceinline__ float xlane1(float t) { return dpp_mov<0xB1, 0xF, true>(0.f, t); }
; __device__ __forceinline__ float xlane2(float t) { return dpp_mov<0x4E, 0xF, true>(0.f, t); }
; __device__ __forceinline__ float xlane4(float t) { const float r = dpp_mov<0x104, 0x5, false>(t, t); return dpp_mov<0x114, 0xA, false>(r, t); }
; __device__ __forceinline__ float xlane8(float t) { return dpp_mov<0x128, 0xF, true>(0.f, t); }
; __device__ __forceinline__ f32x4 rot64(f32x4 t, const RotSigns sg) {
;     { const float p0 = t.x + t.y, p1 = t.x - t.y, p2 = t.z + t.w, p3 = t.z - t.w; t = (f32x4){p0 + p2, p1 + p3, p0 - p2, p1 - p3}; }
;     t = (f32x4){__builtin_fmaf(sg.s1, t.x, xlane1(t.x)), __builtin_fmaf(sg.s1, t.y, xlane1(t.y)), __builtin_fmaf(sg.s1, t.z, xlane1(t.z)), __builtin_fmaf(sg.s1, t.w, xlane1(t.w))};
;     t = (f32x4){__builtin_fmaf(sg.s2, t.x, xlane2(t.x)), __builtin_fmaf(sg.s2, t.y, xlane2(t.y)), __builtin_fmaf(sg.s2, t.z, xlane2(t.z)), __builtin_fmaf(sg.s2, t.w, xlane2(t.w))};
;     t = (f32x4){__builtin_fmaf(sg.s4, t.x, xlane4(t.x)), __builtin_fmaf(sg.s4, t.y, xlane4(t.y)), __builtin_fmaf(sg.s4, t.z, xlane4(t.z)), __builtin_fmaf(sg.s4, t.w, xlane4(t.w))};
;     t = (f32x4){__builtin_fmaf(sg.s8, t.x, xlane8(t.x)), __builtin_fmaf(sg.s8, t.y, xlane8(t.y)), __builtin_fmaf(sg.s8, t.z, xlane8(t.z)), __builtin_fmaf(sg.s8, t.w, xlane8(t.w))};
;     return t * 0.125f;
; __global__ void __launch_bounds__(NWAVES * 64, 2) fwd_kernel(Args args) {
;     ...
;             for (int c = 0; c < DFF / 256; ++c) { const f32x4 t = rot64((f32x4){bf_lo(pk[c].x), bf_hi(pk[c].x), bf_lo(pk[c].y), bf_hi(pk[c].y)}, sg);
;                 pk[c].x = cvt_pk_bf16(t.x, t.y); pk[c].y = cvt_pk_bf16(t.z, t.w);
;                 am = fmaxf(fmaxf(am, fmaxf(fabsf(bf_lo(pk[c].x)), fabsf(bf_hi(pk[c].x)))), fmaxf(fabsf(bf_lo(pk[c].y)), fabsf(bf_hi(pk[c].y)))); }
	v_pk_add_f32 v[28:29], v[186:187], v[28:29] neg_lo:[0,1] neg_hi:[0,1]
	s_nop 0
	v_mov_b32_dpp v184, v176 quad_perm:[1,0,3,2] row_mask:0xf bank_mask:0xf bound_ctrl:1
	v_mov_b32_dpp v185, v177 quad_perm:[1,0,3,2] row_mask:0xf bank_mask:0xf bound_ctrl:1
	v_mov_b32_dpp v182, v28 quad_perm:[1,0,3,2] row_mask:0xf bank_mask:0xf bound_ctrl:1
	v_mov_b32_dpp v183, v29 quad_perm:[1,0,3,2] row_mask:0xf bank_mask:0xf bound_ctrl:1
	v_pk_fma_f32 v[176:177], v[2:3], v[176:177], v[184:185]
	v_pk_fma_f32 v[28:29], v[2:3], v[28:29], v[182:183]
	s_nop 0
	v_mov_b32_dpp v184, v176 quad_perm:[2,3,0,1] row_mask:0xf bank_mask:0xf bound_ctrl:1
	v_mov_b32_dpp v185, v177 quad_perm:[2,3,0,1] row_mask:0xf bank_mask:0xf bound_ctrl:1
	v_mov_b32_dpp v182, v28 quad_perm:[2,3,0,1] row_mask:0xf bank_mask:0xf bound_ctrl:1
	v_mov_b32_dpp v183, v29 quad_perm:[2,3,0,1] row_mask:0xf bank_mask:0xf bound_ctrl:1
	v_pk_fma_f32 v[176:177], v[4:5], v[176:177], v[184:185]
	v_pk_fma_f32 v[28:29], v[4:5], v[28:29], v[182:183]
	v_mov_b32_e32 v184, v176
	v_mov_b32_e32 v185, v177
	v_mov_b32_e32 v182, v28
	v_mov_b32_e32 v183, v29
	v_mov_b32_dpp v184, v184 row_shl:4 row_mask:0xf bank_mask:0x5
	v_mov_b32_dpp v185, v185 row_shl:4 row_mask:0xf bank_mask:0x5
	v_mov_b32_dpp v182, v182 row_shl:4 row_mask:0xf bank_mask:0x5
	v_mov_b32_dpp v183, v183 row_shl:4 row_mask:0xf bank_mask:0x5
	v_mov_b32_dpp v184, v176 row_shr:4 row_mask:0xf bank_mask:0xa
	v_mov_b32_dpp v185, v177 row_shr:4 row_mask:0xf bank_mask:0xa
	v_mov_b32_dpp v182, v28 row_shr:4 row_mask:0xf bank_mask:0xa
	v_mov_b32_dpp v183, v29 row_shr:4 row_mask:0xf bank_mask:0xa
	v_pk_fma_f32 v[176:177], v[6:7], v[176:177], v[184:185]
	v_pk_fma_f32 v[28:29], v[6:7], v[28:29], v[182:183]
	s_nop 0
	v_mov_b32_dpp v184, v176 row_ror:8 row_mask:0xf bank_mask:0xf bound_ctrl:1
	v_mov_b32_dpp v185, v177 row_ror:8 row_mask:0xf bank_mask:0xf bound_ctrl:1
	v_mov_b32_dpp v182, v28 row_ror:8 row_mask:0xf bank_mask:0xf bound_ctrl:1
	v_mov_b32_dpp v183, v29 row_ror:8 row_mask:0xf bank_mask:0xf bound_ctrl:1
	v_pk_fma_f32 v[176:177], v[8:9], v[176:177], v[184:185]
	v_pk_fma_f32 v[28:29], v[10:11], v[28:29], v[182:183]
	v_pk_mul_f32 v[176:177], v[176:177], s[22:23] op_sel_hi:[1,0]
	v_pk_mul_f32 v[28:29], v[28:29], s[22:23] op_sel_hi:[1,0]
	v_cvt_pk_bf16_f32 v175, v176, v177
	s_nop 0
	v_cvt_pk_bf16_f32 v176, v28, v29
	v_lshlrev_b32_e32 v28, 16, v175
	v_and_b32_e32 v29, 0xffff0000, v175
	v_max_f32_e64 v175, |v29|, |v29|
	v_max_f32_e64 v177, |v28|, |v28|
	v_max_f32_e32 v177, v177, v175
	v_lshlrev_b32_e32 v175, 16, v176
	v_and_b32_e32 v176, 0xffff0000, v176
	v_max_f32_e64 v182, |v176|, |v176|
	v_max_f32_e64 v183, |v175|, |v175|
	v_max_f32_e32 v182, v183, v182
	v_max3_f32 v190, v181, v177, v182
	v_lshlrev_b32_e32 v183, 16, v27
	v_lshlrev_b32_e32 v182, 16, v26
	v_and_b32_e32 v27, 0xffff0000, v27
	v_and_b32_e32 v26, 0xffff0000, v26
	v_pk_add_f32 v[184:185], v[182:183], v[26:27]
	v_pk_add_f32 v[26:27], v[182:183], v[26:27] neg_lo:[0,1] neg_hi:[0,1]
	v_mov_b32_e32 v188, v184
	v_pk_mov_b32 v[182:183], v[184:185], v[26:27] op_sel:[1,0]
	v_mov_b32_e32 v189, v26
	v_mov_b32_e32 v26, v185
	v_mov_b32_e32 v186, v184
	v_mov_b32_e32 v187, v27
	v_pk_add_f32 v[26:27], v[188:189], v[26:27] neg_lo:[0,1] neg_hi:[0,1]
	v_pk_add_f32 v[182:183], v[186:187], v[182:183]
	s_nop 0
	v_mov_b32_dpp v184, v26 quad_perm:[1,0,3,2] row_mask:0xf bank_mask:0xf bound_ctrl:1
	v_mov_b32_dpp v185, v27 quad_perm:[1,0,3,2] row_mask:0xf bank_mask:0xf bound_ctrl:1
	v_mov_b32_dpp v186, v182 quad_perm:[1,0,3,2] row_mask:0xf bank_mask:0xf bound_ctrl:1
	v_mov_b32_dpp v187, v183 quad_perm:[1,0,3,2] row_mask:0xf bank_mask:0xf bound_ctrl:1
	v_pk_fma_f32 v[26:27], v[2:3], v[26:27], v[184:185]
	v_pk_fma_f32 v[182:183], v[2:3], v[182:183], v[186:187]
	s_nop 0
	v_mov_b32_dpp v184, v26 quad_perm:[2,3,0,1] row_mask:0xf bank_mask:0xf bound_ctrl:1
	v_mov_b32_dpp v185, v27 quad_perm:[2,3,0,1] row_mask:0xf bank_mask:0xf bound_ctrl:1
	v_mov_b32_dpp v186, v182 quad_perm:[2,3,0,1] row_mask:0xf bank_mask:0xf bound_ctrl:1
	v_mov_b32_dpp v187, v183 quad_perm:[2,3,0,1] row_mask:0xf bank_mask:0xf bound_ctrl:1
	v_pk_fma_f32 v[26:27], v[4:5], v[26:27], v[184:185]
	v_pk_fma_f32 v[182:183], v[4:5], v[182:183], v[186:187]
	v_mov_b32_e32 v184, v26
	v_mov_b32_e32 v185, v27
	v_mov_b32_e32 v186, v182
	v_mov_b32_e32 v187, v183
	v_mov_b32_dpp v184, v184 row_shl:4 row_mask:0xf bank_mask:0x5
	v_mov_b32_dpp v185, v185 row_shl:4 row_mask:0xf bank_mask:0x5
	v_mov_b32_dpp v186, v186 row_shl:4 row_mask:0xf bank_mask:0x5
	v_mov_b32_dpp v187, v187 row_shl:4 row_mask:0xf bank_mask:0x5
	v_mov_b32_dpp v184, v26 row_shr:4 row_mask:0xf bank_mask:0xa
	v_mov_b32_dpp v185, v27 row_shr:4 row_mask:0xf bank_mask:0xa
	v_mov_b32_dpp v186, v182 row_shr:4 row_mask:0xf bank_mask:0xa
	v_mov_b32_dpp v187, v183 row_shr:4 row_mask:0xf bank_mask:0xa
	v_pk_fma_f32 v[26:27], v[6:7], v[26:27], v[184:185]
	v_pk_fma_f32 v[182:183], v[6:7], v[182:183], v[186:187]
	s_nop 0
	v_mov_b32_dpp v184, v26 row_ror:8 row_mask:0xf bank_mask:0xf bound_ctrl:1
	v_mov_b32_dpp v185, v27 row_ror:8 row_mask:0xf bank_mask:0xf bound_ctrl:1
	v_mov_b32_dpp v186, v182 row_ror:8 row_mask:0xf bank_mask:0xf bound_ctrl:1
	v_mov_b32_dpp v187, v183 row_ror:8 row_mask:0xf bank_mask:0xf bound_ctrl:1
	v_pk_fma_f32 v[26:27], v[10:11], v[26:27], v[184:185]
	v_pk_fma_f32 v[182:183], v[8:9], v[182:183], v[186:187]
	v_pk_mul_f32 v[26:27], v[26:27], s[22:23] op_sel_hi:[1,0]
	v_pk_mul_f32 v[182:183], v[182:183], s[22:23] op_sel_hi:[1,0]
	s_nop 0
	v_cvt_pk_bf16_f32 v177, v182, v183
	v_cvt_pk_bf16_f32 v181, v26, v27
	s_nop 0
	v_lshlrev_b32_e32 v26, 16, v177
	v_and_b32_e32 v27, 0xffff0000, v177
	v_max_f32_e64 v177, |v27|, |v27|
; __device__ __forceinline__ unsigned cvt_pk_bf16(float lo, float hi) { unsigned r; asm volatile("v_cvt_pk_bf16_f32 %0, %1, %2" : "=v"(r) : "v"(lo), "v"(hi)); return r; }
; __device__ __forceinline__ float bf_lo(unsigned w) { return __uint_as_float(w << 16); }
; __device__ __forceinline__ float bf_hi(unsigned w) { return __uint_as_float(w & 0xffff0000u); }
; __device__ __forceinline__ float xlane1(float t) { return dpp_mov<0xB1, 0xF, true>(0.f, t); }
; __device__ __forceinline__ float xlane2(float t) { return dpp_mov<0x4E, 0xF, true>(0.f, t); }
; __device__ __forceinline__ float xlane4(float t) { const float r = dpp_mov<0x104, 0x5, false>(t, t); return dpp_mov<0x114, 0xA, false>(r, t); }
; __device__ __forceinline__ float xlane8(float t) { return dpp_mov<0x128, 0xF, true>(0.f, t); }
; __device__ __forceinline__ f32x4 rot64(f32x4 t, const RotSigns sg) {
;     { const float p0 = t.x + t.y, p1 = t.x - t.y, p2 = t.z + t.w, p3 = t.z - t.w; t = (f32x4){p0 + p2, p1 + p3, p0 - p2, p1 - p3}; }
;     t = (f32x4){__builtin_fmaf(sg.s1, t.x, xlane1(t.x)), __builtin_fmaf(sg.s1, t.y, xlane1(t.y)), __builtin_fmaf(sg.s1, t.z, xlane1(t.z)), __builtin_fmaf(sg.s1, t.w, xlane1(t.w))};
;     t = (f32x4){__builtin_fmaf(sg.s2, t.x, xlane2(t.x)), __builtin_fmaf(sg.s2, t.y, xlane2(t.y)), __builtin_fmaf(sg.s2, t.z, xlane2(t.z)), __builtin_fmaf(sg.s2, t.w, xlane2(t.w))};
;     t = (f32x4){__builtin_fmaf(sg.s4, t.x, xlane4(t.x)), __builtin_fmaf(sg.s4, t.y, xlane4(t.y)), __builtin_fmaf(sg.s4, t.z, xlane4(t.z)), __builtin_fmaf(sg.s4, t.w, xlane4(t.w))};
;     t = (f32x4){__builtin_fmaf(sg.s8, t.x, xlane8(t.x)), __builtin_fmaf(sg.s8, t.y, xlane8(t.y)), __builtin_fmaf(sg.s8, t.z, xlane8(t.z)), __builtin_fmaf(sg.s8, t.w, xlane8(t.w))};
;     return t * 0.125f;
; }
; __global__ void __launch_bounds__(NWAVES * 64, 2) fwd_kernel(Args args) {
;     ...
;             for (int c = 0; c < DFF / 256; ++c) { const f32x4 t = rot64((f32x4){bf_lo(pk[c].x), bf_hi(pk[c].x), bf_lo(pk[c].y), bf_hi(pk[c].y)}, sg);
;                 pk[c].x = cvt_pk_bf16(t.x, t.y); pk[c].y = cvt_pk_bf16(t.z, t.w);
;                 am = fmaxf(fmaxf(am, fmaxf(fabsf(bf_lo(pk[c].x)), fabsf(bf_hi(pk[c].x)))), fmaxf(fabsf(bf_lo(pk[c].y)), fabsf(bf_hi(pk[c].y)))); }
	v_max_f32_e64 v182, |v26|, |v26|
	v_max_f32_e32 v182, v182, v177
	v_lshlrev_b32_e32 v177, 16, v181
	v_and_b32_e32 v181, 0xffff0000, v181
	v_max_f32_e64 v183, |v181|, |v181|
	v_max_f32_e64 v184, |v177|, |v177|
	v_max_f32_e32 v183, v184, v183
	v_max3_f32 v190, v190, v182, v183
	v_lshlrev_b32_e32 v183, 16, v25
	v_lshlrev_b32_e32 v182, 16, v24
	v_and_b32_e32 v25, 0xffff0000, v25
	v_and_b32_e32 v24, 0xffff0000, v24
	v_pk_add_f32 v[184:185], v[182:183], v[24:25]
	v_pk_add_f32 v[24:25], v[182:183], v[24:25] neg_lo:[0,1] neg_hi:[0,1]
	v_mov_b32_e32 v186, v184
	v_pk_mov_b32 v[182:183], v[184:185], v[24:25] op_sel:[1,0]
	v_mov_b32_e32 v187, v25
	v_mov_b32_e32 v188, v184
	v_mov_b32_e32 v189, v24
	v_mov_b32_e32 v24, v185
	v_pk_add_f32 v[182:183], v[186:187], v[182:183]
	v_pk_add_f32 v[24:25], v[188:189], v[24:25] neg_lo:[0,1] neg_hi:[0,1]
	s_nop 0
	v_mov_b32_dpp v186, v182 quad_perm:[1,0,3,2] row_mask:0xf bank_mask:0xf bound_ctrl:1
	v_mov_b32_dpp v187, v183 quad_perm:[1,0,3,2] row_mask:0xf bank_mask:0xf bound_ctrl:1
	v_mov_b32_dpp v184, v24 quad_perm:[1,0,3,2] row_mask:0xf bank_mask:0xf bound_ctrl:1
	v_mov_b32_dpp v185, v25 quad_perm:[1,0,3,2] row_mask:0xf bank_mask:0xf bound_ctrl:1
	v_pk_fma_f32 v[182:183], v[2:3], v[182:183], v[186:187]
	v_pk_fma_f32 v[24:25], v[2:3], v[24:25], v[184:185]
	s_nop 0
	v_mov_b32_dpp v186, v182 quad_perm:[2,3,0,1] row_mask:0xf bank_mask:0xf bound_ctrl:1
	v_mov_b32_dpp v187, v183 quad_perm:[2,3,0,1] row_mask:0xf bank_mask:0xf bound_ctrl:1
	v_mov_b32_dpp v184, v24 quad_perm:[2,3,0,1] row_mask:0xf bank_mask:0xf bound_ctrl:1
	v_mov_b32_dpp v185, v25 quad_perm:[2,3,0,1] row_mask:0xf bank_mask:0xf bound_ctrl:1
	v_pk_fma_f32 v[182:183], v[4:5], v[182:183], v[186:187]
	v_pk_fma_f32 v[24:25], v[4:5], v[24:25], v[184:185]
	v_mov_b32_e32 v186, v182
	v_mov_b32_e32 v187, v183
	v_mov_b32_e32 v184, v24
	v_mov_b32_e32 v185, v25
	v_mov_b32_dpp v186, v186 row_shl:4 row_mask:0xf bank_mask:0x5
	v_mov_b32_dpp v187, v187 row_shl:4 row_mask:0xf bank_mask:0x5
	v_mov_b32_dpp v184, v184 row_shl:4 row_mask:0xf bank_mask:0x5
	v_mov_b32_dpp v185, v185 row_shl:4 row_mask:0xf bank_mask:0x5
	v_mov_b32_dpp v186, v182 row_shr:4 row_mask:0xf bank_mask:0xa
	v_mov_b32_dpp v187, v183 row_shr:4 row_mask:0xf bank_mask:0xa
	v_mov_b32_dpp v184, v24 row_shr:4 row_mask:0xf bank_mask:0xa
	v_mov_b32_dpp v185, v25 row_shr:4 row_mask:0xf bank_mask:0xa
	v_pk_fma_f32 v[182:183], v[6:7], v[182:183], v[186:187]
	v_pk_fma_f32 v[24:25], v[6:7], v[24:25], v[184:185]
	s_nop 0
	v_mov_b32_dpp v186, v182 row_ror:8 row_mask:0xf bank_mask:0xf bound_ctrl:1
	v_mov_b32_dpp v187, v183 row_ror:8 row_mask:0xf bank_mask:0xf bound_ctrl:1
	v_mov_b32_dpp v184, v24 row_ror:8 row_mask:0xf bank_mask:0xf bound_ctrl:1
	v_mov_b32_dpp v185, v25 row_ror:8 row_mask:0xf bank_mask:0xf bound_ctrl:1
	v_pk_fma_f32 v[182:183], v[8:9], v[182:183], v[186:187]
	v_pk_fma_f32 v[24:25], v[10:11], v[24:25], v[184:185]
	v_pk_mul_f32 v[182:183], v[182:183], s[22:23] op_sel_hi:[1,0]
	v_pk_mul_f32 v[24:25], v[24:25], s[22:23] op_sel_hi:[1,0]
	v_cvt_pk_bf16_f32 v182, v182, v183
	s_nop 0
	v_cvt_pk_bf16_f32 v183, v24, v25
	v_lshlrev_b32_e32 v24, 16, v182
	v_and_b32_e32 v25, 0xffff0000, v182
	v_max_f32_e64 v182, |v25|, |v25|
	v_max_f32_e64 v184, |v24|, |v24|
	v_max_f32_e32 v184, v184, v182
	v_lshlrev_b32_e32 v182, 16, v183
	v_and_b32_e32 v183, 0xffff0000, v183
	v_max_f32_e64 v185, |v183|, |v183|
	v_max_f32_e64 v186, |v182|, |v182|
	v_max_f32_e32 v185, v186, v185
	v_max3_f32 v192, v190, v184, v185
	v_lshlrev_b32_e32 v185, 16, v23
	v_lshlrev_b32_e32 v184, 16, v22
	v_and_b32_e32 v23, 0xffff0000, v23
	v_and_b32_e32 v22, 0xffff0000, v22
	v_pk_add_f32 v[186:187], v[184:185], v[22:23]
	v_pk_add_f32 v[22:23], v[184:185], v[22:23] neg_lo:[0,1] neg_hi:[0,1]
	v_mov_b32_e32 v188, v186
	v_pk_mov_b32 v[184:185], v[186:187], v[22:23] op_sel:[1,0]
	v_mov_b32_e32 v189, v23
	v_mov_b32_e32 v190, v186
	v_mov_b32_e32 v191, v22
	v_mov_b32_e32 v22, v187
	v_pk_add_f32 v[184:185], v[188:189], v[184:185]
	v_pk_add_f32 v[22:23], v[190:191], v[22:23] neg_lo:[0,1] neg_hi:[0,1]
	s_nop 0
	v_mov_b32_dpp v188, v184 quad_perm:[1,0,3,2] row_mask:0xf bank_mask:0xf bound_ctrl:1
	v_mov_b32_dpp v189, v185 quad_perm:[1,0,3,2] row_mask:0xf bank_mask:0xf bound_ctrl:1
	v_mov_b32_dpp v186, v22 quad_perm:[1,0,3,2] row_mask:0xf bank_mask:0xf bound_ctrl:1
	v_mov_b32_dpp v187, v23 quad_perm:[1,0,3,2] row_mask:0xf bank_mask:0xf bound_ctrl:1
	v_pk_fma_f32 v[184:185], v[2:3], v[184:185], v[188:189]
	v_pk_fma_f32 v[22:23], v[2:3], v[22:23], v[186:187]
	s_nop 0
	v_mov_b32_dpp v188, v184 quad_perm:[2,3,0,1] row_mask:0xf bank_mask:0xf bound_ctrl:1
	v_mov_b32_dpp v189, v185 quad_perm:[2,3,0,1] row_mask:0xf bank_mask:0xf bound_ctrl:1
	v_mov_b32_dpp v186, v22 quad_perm:[2,3,0,1] row_mask:0xf bank_mask:0xf bound_ctrl:1
	v_mov_b32_dpp v187, v23 quad_perm:[2,3,0,1] row_mask:0xf bank_mask:0xf bound_ctrl:1
	v_pk_fma_f32 v[184:185], v[4:5], v[184:185], v[188:189]
	v_pk_fma_f32 v[22:23], v[4:5], v[22:23], v[186:187]
	v_mov_b32_e32 v188, v184
	v_mov_b32_e32 v189, v185
	v_mov_b32_e32 v186, v22
	v_mov_b32_e32 v187, v23
	v_mov_b32_dpp v188, v188 row_shl:4 row_mask:0xf bank_mask:0x5
	v_mov_b32_dpp v189, v189 row_shl:4 row_mask:0xf bank_mask:0x5
	v_mov_b32_dpp v186, v186 row_shl:4 row_mask:0xf bank_mask:0x5
	v_mov_b32_dpp v187, v187 row_shl:4 row_mask:0xf bank_mask:0x5
	v_mov_b32_dpp v188, v184 row_shr:4 row_mask:0xf bank_mask:0xa
	v_mov_b32_dpp v189, v185 row_shr:4 row_mask:0xf bank_mask:0xa
	v_mov_b32_dpp v186, v22 row_shr:4 row_mask:0xf bank_mask:0xa
	v_mov_b32_dpp v187, v23 row_shr:4 row_mask:0xf bank_mask:0xa
	v_pk_fma_f32 v[184:185], v[6:7], v[184:185], v[188:189]
; __device__ __forceinline__ unsigned cvt_pk_bf16(float lo, float hi) { unsigned r; asm volatile("v_cvt_pk_bf16_f32 %0, %1, %2" : "=v"(r) : "v"(lo), "v"(hi)); return r; }
; __device__ __forceinline__ float bf_lo(unsigned w) { return __uint_as_float(w << 16); }
; __device__ __forceinline__ float bf_hi(unsigned w) { return __uint_as_float(w & 0xffff0000u); }
; __device__ __forceinline__ float xlane1(float t) { return dpp_mov<0xB1, 0xF, true>(0.f, t); }
; __device__ __forceinline__ float xlane2(float t) { return dpp_mov<0x4E, 0xF, true>(0.f, t); }
; __device__ __forceinline__ float xlane4(float t) { const float r = dpp_mov<0x104, 0x5, false>(t, t); return dpp_mov<0x114, 0xA, false>(r, t); }
; __device__ __forceinline__ float xlane8(float t) { return dpp_mov<0x128, 0xF, true>(0.f, t); }
; __device__ __forceinline__ f32x4 rot64(f32x4 t, const RotSigns sg) {
;     { const float p0 = t.x + t.y, p1 = t.x - t.y, p2 = t.z + t.w, p3 = t.z - t.w; t = (f32x4){p0 + p2, p1 + p3, p0 - p2, p1 - p3}; }
;     t = (f32x4){__builtin_fmaf(sg.s1, t.x, xlane1(t.x)), __builtin_fmaf(sg.s1, t.y, xlane1(t.y)), __builtin_fmaf(sg.s1, t.z, xlane1(t.z)), __builtin_fmaf(sg.s1, t.w, xlane1(t.w))};
;     t = (f32x4){__builtin_fmaf(sg.s2, t.x, xlane2(t.x)), __builtin_fmaf(sg.s2, t.y, xlane2(t.y)), __builtin_fmaf(sg.s2, t.z, xlane2(t.z)), __builtin_fmaf(sg.s2, t.w, xlane2(t.w))};
;     t = (f32x4){__builtin_fmaf(sg.s4, t.x, xlane4(t.x)), __builtin_fmaf(sg.s4, t.y, xlane4(t.y)), __builtin_fmaf(sg.s4, t.z, xlane4(t.z)), __builtin_fmaf(sg.s4, t.w, xlane4(t.w))};
;     t = (f32x4){__builtin_fmaf(sg.s8, t.x, xlane8(t.x)), __builtin_fmaf(sg.s8, t.y, xlane8(t.y)), __builtin_fmaf(sg.s8, t.z, xlane8(t.z)), __builtin_fmaf(sg.s8, t.w, xlane8(t.w))};
;     return t * 0.125f;
; }
; __global__ void __launch_bounds__(NWAVES * 64, 2) fwd_kernel(Args args) {
;     ...
;             for (int c = 0; c < DFF / 256; ++c) { const f32x4 t = rot64((f32x4){bf_lo(pk[c].x), bf_hi(pk[c].x), bf_lo(pk[c].y), bf_hi(pk[c].y)}, sg);
;                 pk[c].x = cvt_pk_bf16(t.x, t.y); pk[c].y = cvt_pk_bf16(t.z, t.w);
;                 am = fmaxf(fmaxf(am, fmaxf(fabsf(bf_lo(pk[c].x)), fabsf(bf_hi(pk[c].x)))), fmaxf(fabsf(bf_lo(pk[c].y)), fabsf(bf_hi(pk[c].y)))); }
	v_pk_fma_f32 v[22:23], v[6:7], v[22:23], v[186:187]
	s_nop 0
	v_mov_b32_dpp v188, v184 row_ror:8 row_mask:0xf bank_mask:0xf bound_ctrl:1
	v_mov_b32_dpp v189, v185 row_ror:8 row_mask:0xf bank_mask:0xf bound_ctrl:1
	v_mov_b32_dpp v186, v22 row_ror:8 row_mask:0xf bank_mask:0xf bound_ctrl:1
	v_mov_b32_dpp v187, v23 row_ror:8 row_mask:0xf bank_mask:0xf bound_ctrl:1
	v_pk_fma_f32 v[184:185], v[8:9], v[184:185], v[188:189]
	v_pk_fma_f32 v[22:23], v[10:11], v[22:23], v[186:187]
	v_pk_mul_f32 v[184:185], v[184:185], s[22:23] op_sel_hi:[1,0]
	v_pk_mul_f32 v[22:23], v[22:23], s[22:23] op_sel_hi:[1,0]
	v_cvt_pk_bf16_f32 v184, v184, v185
	s_nop 0
	v_cvt_pk_bf16_f32 v185, v22, v23
	v_lshlrev_b32_e32 v22, 16, v184
	v_and_b32_e32 v23, 0xffff0000, v184
	v_max_f32_e64 v184, |v23|, |v23|
	v_max_f32_e64 v186, |v22|, |v22|
	v_max_f32_e32 v186, v186, v184
	v_lshlrev_b32_e32 v184, 16, v185
	v_and_b32_e32 v185, 0xffff0000, v185
	v_max_f32_e64 v187, |v185|, |v185|
	v_max_f32_e64 v188, |v184|, |v184|
	v_max_f32_e32 v187, v188, v187
	v_max3_f32 v194, v192, v186, v187
	v_lshlrev_b32_e32 v187, 16, v21
	v_lshlrev_b32_e32 v186, 16, v20
	v_and_b32_e32 v21, 0xffff0000, v21
	v_and_b32_e32 v20, 0xffff0000, v20
	v_pk_add_f32 v[188:189], v[186:187], v[20:21]
	v_pk_add_f32 v[20:21], v[186:187], v[20:21] neg_lo:[0,1] neg_hi:[0,1]
	v_mov_b32_e32 v190, v188
	v_pk_mov_b32 v[186:187], v[188:189], v[20:21] op_sel:[1,0]
	v_mov_b32_e32 v191, v21
	v_mov_b32_e32 v192, v188
	v_mov_b32_e32 v193, v20
	v_mov_b32_e32 v20, v189
	v_pk_add_f32 v[186:187], v[190:191], v[186:187]
	v_pk_add_f32 v[20:21], v[192:193], v[20:21] neg_lo:[0,1] neg_hi:[0,1]
	s_nop 0
	v_mov_b32_dpp v190, v186 quad_perm:[1,0,3,2] row_mask:0xf bank_mask:0xf bound_ctrl:1
	v_mov_b32_dpp v191, v187 quad_perm:[1,0,3,2] row_mask:0xf bank_mask:0xf bound_ctrl:1
	v_mov_b32_dpp v188, v20 quad_perm:[1,0,3,2] row_mask:0xf bank_mask:0xf bound_ctrl:1
	v_mov_b32_dpp v189, v21 quad_perm:[1,0,3,2] row_mask:0xf bank_mask:0xf bound_ctrl:1
	v_pk_fma_f32 v[186:187], v[2:3], v[186:187], v[190:191]
	v_pk_fma_f32 v[20:21], v[2:3], v[20:21], v[188:189]
	s_nop 0
	v_mov_b32_dpp v190, v186 quad_perm:[2,3,0,1] row_mask:0xf bank_mask:0xf bound_ctrl:1
	v_mov_b32_dpp v191, v187 quad_perm:[2,3,0,1] row_mask:0xf bank_mask:0xf bound_ctrl:1
	v_mov_b32_dpp v188, v20 quad_perm:[2,3,0,1] row_mask:0xf bank_mask:0xf bound_ctrl:1
	v_mov_b32_dpp v189, v21 quad_perm:[2,3,0,1] row_mask:0xf bank_mask:0xf bound_ctrl:1
	v_pk_fma_f32 v[186:187], v[4:5], v[186:187], v[190:191]
	v_pk_fma_f32 v[20:21], v[4:5], v[20:21], v[188:189]
	v_mov_b32_e32 v190, v186
	v_mov_b32_e32 v191, v187
	v_mov_b32_e32 v188, v20
	v_mov_b32_e32 v189, v21
	v_mov_b32_dpp v190, v190 row_shl:4 row_mask:0xf bank_mask:0x5
	v_mov_b32_dpp v191, v191 row_shl:4 row_mask:0xf bank_mask:0x5
	v_mov_b32_dpp v188, v188 row_shl:4 row_mask:0xf bank_mask:0x5
	v_mov_b32_dpp v189, v189 row_shl:4 row_mask:0xf bank_mask:0x5
	v_mov_b32_dpp v190, v186 row_shr:4 row_mask:0xf bank_mask:0xa
	v_mov_b32_dpp v191, v187 row_shr:4 row_mask:0xf bank_mask:0xa
	v_mov_b32_dpp v188, v20 row_shr:4 row_mask:0xf bank_mask:0xa
	v_mov_b32_dpp v189, v21 row_shr:4 row_mask:0xf bank_mask:0xa
	v_pk_fma_f32 v[186:187], v[6:7], v[186:187], v[190:191]
	v_pk_fma_f32 v[20:21], v[6:7], v[20:21], v[188:189]
	s_nop 0
	v_mov_b32_dpp v190, v186 row_ror:8 row_mask:0xf bank_mask:0xf bound_ctrl:1
	v_mov_b32_dpp v191, v187 row_ror:8 row_mask:0xf bank_mask:0xf bound_ctrl:1
	v_mov_b32_dpp v188, v20 row_ror:8 row_mask:0xf bank_mask:0xf bound_ctrl:1
	v_mov_b32_dpp v189, v21 row_ror:8 row_mask:0xf bank_mask:0xf bound_ctrl:1
	v_pk_fma_f32 v[186:187], v[8:9], v[186:187], v[190:191]
	v_pk_fma_f32 v[20:21], v[10:11], v[20:21], v[188:189]
	v_pk_mul_f32 v[186:187], v[186:187], s[22:23] op_sel_hi:[1,0]
	v_pk_mul_f32 v[20:21], v[20:21], s[22:23] op_sel_hi:[1,0]
	v_cvt_pk_bf16_f32 v186, v186, v187
	s_nop 0
	v_cvt_pk_bf16_f32 v187, v20, v21
	v_lshlrev_b32_e32 v20, 16, v186
	v_and_b32_e32 v21, 0xffff0000, v186
	v_max_f32_e64 v186, |v21|, |v21|
	v_max_f32_e64 v188, |v20|, |v20|
	v_max_f32_e32 v188, v188, v186
	v_lshlrev_b32_e32 v186, 16, v187
	v_and_b32_e32 v187, 0xffff0000, v187
	v_max_f32_e64 v189, |v187|, |v187|
	v_max_f32_e64 v190, |v186|, |v186|
	v_max_f32_e32 v189, v190, v189
	v_max3_f32 v196, v194, v188, v189
	v_lshlrev_b32_e32 v189, 16, v19
	v_lshlrev_b32_e32 v188, 16, v18
	v_and_b32_e32 v19, 0xffff0000, v19
	v_and_b32_e32 v18, 0xffff0000, v18
	v_pk_add_f32 v[190:191], v[188:189], v[18:19]
	v_pk_add_f32 v[18:19], v[188:189], v[18:19] neg_lo:[0,1] neg_hi:[0,1]
	v_mov_b32_e32 v192, v190
	v_pk_mov_b32 v[188:189], v[190:191], v[18:19] op_sel:[1,0]
	v_mov_b32_e32 v193, v19
	v_pk_add_f32 v[188:189], v[192:193], v[188:189]
	v_mov_b32_e32 v194, v190
	v_mov_b32_e32 v195, v18
	v_mov_b32_e32 v18, v191
	v_mov_b32_dpp v192, v188 quad_perm:[1,0,3,2] row_mask:0xf bank_mask:0xf bound_ctrl:1
	v_mov_b32_dpp v193, v189 quad_perm:[1,0,3,2] row_mask:0xf bank_mask:0xf bound_ctrl:1
	v_pk_add_f32 v[18:19], v[194:195], v[18:19] neg_lo:[0,1] neg_hi:[0,1]
	v_pk_fma_f32 v[188:189], v[2:3], v[188:189], v[192:193]
	s_nop 0
	v_mov_b32_dpp v190, v18 quad_perm:[1,0,3,2] row_mask:0xf bank_mask:0xf bound_ctrl:1
	v_mov_b32_dpp v191, v19 quad_perm:[1,0,3,2] row_mask:0xf bank_mask:0xf bound_ctrl:1
	v_mov_b32_dpp v192, v188 quad_perm:[2,3,0,1] row_mask:0xf bank_mask:0xf bound_ctrl:1
	v_mov_b32_dpp v193, v189 quad_perm:[2,3,0,1] row_mask:0xf bank_mask:0xf bound_ctrl:1
	v_pk_fma_f32 v[18:19], v[2:3], v[18:19], v[190:191]
	v_pk_fma_f32 v[188:189], v[4:5], v[188:189], v[192:193]
	s_nop 0
	v_mov_b32_dpp v190, v18 quad_perm:[2,3,0,1] row_mask:0xf bank_mask:0xf bound_ctrl:1
; __device__ __forceinline__ unsigned cvt_pk_bf16(float lo, float hi) { unsigned r; asm volatile("v_cvt_pk_bf16_f32 %0, %1, %2" : "=v"(r) : "v"(lo), "v"(hi)); return r; }
; __device__ __forceinline__ float bf_lo(unsigned w) { return __uint_as_float(w << 16); }
; __device__ __forceinline__ float bf_hi(unsigned w) { return __uint_as_float(w & 0xffff0000u); }
; __device__ __forceinline__ float xlane1(float t) { return dpp_mov<0xB1, 0xF, true>(0.f, t); }
; __device__ __forceinline__ float xlane2(float t) { return dpp_mov<0x4E, 0xF, true>(0.f, t); }
; __device__ __forceinline__ float xlane4(float t) { const float r = dpp_mov<0x104, 0x5, false>(t, t); return dpp_mov<0x114, 0xA, false>(r, t); }
; __device__ __forceinline__ float xlane8(float t) { return dpp_mov<0x128, 0xF, true>(0.f, t); }
; __device__ __forceinline__ f32x4 rot64(f32x4 t, const RotSigns sg) {
;     { const float p0 = t.x + t.y, p1 = t.x - t.y, p2 = t.z + t.w, p3 = t.z - t.w; t = (f32x4){p0 + p2, p1 + p3, p0 - p2, p1 - p3}; }
;     t = (f32x4){__builtin_fmaf(sg.s1, t.x, xlane1(t.x)), __builtin_fmaf(sg.s1, t.y, xlane1(t.y)), __builtin_fmaf(sg.s1, t.z, xlane1(t.z)), __builtin_fmaf(sg.s1, t.w, xlane1(t.w))};
;     t = (f32x4){__builtin_fmaf(sg.s2, t.x, xlane2(t.x)), __builtin_fmaf(sg.s2, t.y, xlane2(t.y)), __builtin_fmaf(sg.s2, t.z, xlane2(t.z)), __builtin_fmaf(sg.s2, t.w, xlane2(t.w))};
;     t = (f32x4){__builtin_fmaf(sg.s4, t.x, xlane4(t.x)), __builtin_fmaf(sg.s4, t.y, xlane4(t.y)), __builtin_fmaf(sg.s4, t.z, xlane4(t.z)), __builtin_fmaf(sg.s4, t.w, xlane4(t.w))};
;     t = (f32x4){__builtin_fmaf(sg.s8, t.x, xlane8(t.x)), __builtin_fmaf(sg.s8, t.y, xlane8(t.y)), __builtin_fmaf(sg.s8, t.z, xlane8(t.z)), __builtin_fmaf(sg.s8, t.w, xlane8(t.w))};
;     return t * 0.125f;
; }
; __global__ void __launch_bounds__(NWAVES * 64, 2) fwd_kernel(Args args) {
;     ...
;             for (int c = 0; c < DFF / 256; ++c) { const f32x4 t = rot64((f32x4){bf_lo(pk[c].x), bf_hi(pk[c].x), bf_lo(pk[c].y), bf_hi(pk[c].y)}, sg);
;                 pk[c].x = cvt_pk_bf16(t.x, t.y); pk[c].y = cvt_pk_bf16(t.z, t.w);
;                 am = fmaxf(fmaxf(am, fmaxf(fabsf(bf_lo(pk[c].x)), fabsf(bf_hi(pk[c].x)))), fmaxf(fabsf(bf_lo(pk[c].y)), fabsf(bf_hi(pk[c].y)))); }
; #pragma unroll
;             for (int o = 1; o < 64; o <<= 1) am = fmaxf(am, __shfl_xor(am, o));
	v_mov_b32_dpp v191, v19 quad_perm:[2,3,0,1] row_mask:0xf bank_mask:0xf bound_ctrl:1
	v_mov_b32_e32 v192, v188
	v_mov_b32_e32 v193, v189
	v_pk_fma_f32 v[18:19], v[4:5], v[18:19], v[190:191]
	v_mov_b32_dpp v192, v192 row_shl:4 row_mask:0xf bank_mask:0x5
	v_mov_b32_dpp v193, v193 row_shl:4 row_mask:0xf bank_mask:0x5
	v_mov_b32_e32 v190, v18
	v_mov_b32_e32 v191, v19
	v_mov_b32_dpp v192, v188 row_shr:4 row_mask:0xf bank_mask:0xa
	v_mov_b32_dpp v193, v189 row_shr:4 row_mask:0xf bank_mask:0xa
	v_mov_b32_dpp v190, v190 row_shl:4 row_mask:0xf bank_mask:0x5
	v_mov_b32_dpp v191, v191 row_shl:4 row_mask:0xf bank_mask:0x5
	v_pk_fma_f32 v[188:189], v[6:7], v[188:189], v[192:193]
	v_mov_b32_dpp v190, v18 row_shr:4 row_mask:0xf bank_mask:0xa
	v_mov_b32_dpp v191, v19 row_shr:4 row_mask:0xf bank_mask:0xa
	v_mov_b32_dpp v192, v188 row_ror:8 row_mask:0xf bank_mask:0xf bound_ctrl:1
	v_mov_b32_dpp v193, v189 row_ror:8 row_mask:0xf bank_mask:0xf bound_ctrl:1
	v_pk_fma_f32 v[18:19], v[6:7], v[18:19], v[190:191]
	v_pk_fma_f32 v[188:189], v[8:9], v[188:189], v[192:193]
	s_nop 0
	v_mov_b32_dpp v190, v18 row_ror:8 row_mask:0xf bank_mask:0xf bound_ctrl:1
	v_mov_b32_dpp v191, v19 row_ror:8 row_mask:0xf bank_mask:0xf bound_ctrl:1
	v_pk_fma_f32 v[18:19], v[10:11], v[18:19], v[190:191]
	v_pk_mul_f32 v[188:189], v[188:189], s[22:23] op_sel_hi:[1,0]
	v_pk_mul_f32 v[18:19], v[18:19], s[22:23] op_sel_hi:[1,0]
	v_cvt_pk_bf16_f32 v188, v188, v189
	s_nop 0
	v_lshlrev_b32_e32 v194, 16, v188
	v_and_b32_e32 v195, 0xffff0000, v188
	v_cvt_pk_bf16_f32 v18, v18, v19
	v_max_f32_e64 v19, |v195|, |v195|
	v_max_f32_e64 v188, |v194|, |v194|
	v_lshlrev_b32_e32 v197, 16, v18
	v_and_b32_e32 v198, 0xffff0000, v18
	v_max_f32_e32 v19, v188, v19
	v_max_f32_e64 v18, |v198|, |v198|
	v_max_f32_e64 v188, |v197|, |v197|
	v_max_f32_e32 v18, v188, v18
	v_max3_f32 v196, v196, v19, v18
	v_lshlrev_b32_e32 v19, 16, v17
	v_lshlrev_b32_e32 v18, 16, v16
	v_and_b32_e32 v17, 0xffff0000, v17
	v_and_b32_e32 v16, 0xffff0000, v16
	v_pk_add_f32 v[188:189], v[18:19], v[16:17]
	v_pk_add_f32 v[16:17], v[18:19], v[16:17] neg_lo:[0,1] neg_hi:[0,1]
	v_mov_b32_e32 v190, v188
	v_pk_mov_b32 v[18:19], v[188:189], v[16:17] op_sel:[1,0]
	v_mov_b32_e32 v191, v17
	v_pk_add_f32 v[18:19], v[190:191], v[18:19]
	v_mov_b32_e32 v192, v188
	v_mov_b32_e32 v193, v16
	v_mov_b32_e32 v16, v189
	v_mov_b32_dpp v190, v18 quad_perm:[1,0,3,2] row_mask:0xf bank_mask:0xf bound_ctrl:1
	v_mov_b32_dpp v191, v19 quad_perm:[1,0,3,2] row_mask:0xf bank_mask:0xf bound_ctrl:1
	v_pk_add_f32 v[16:17], v[192:193], v[16:17] neg_lo:[0,1] neg_hi:[0,1]
	v_pk_fma_f32 v[18:19], v[2:3], v[18:19], v[190:191]
	s_nop 0
	v_mov_b32_dpp v188, v16 quad_perm:[1,0,3,2] row_mask:0xf bank_mask:0xf bound_ctrl:1
	v_mov_b32_dpp v189, v17 quad_perm:[1,0,3,2] row_mask:0xf bank_mask:0xf bound_ctrl:1
	v_mov_b32_dpp v190, v18 quad_perm:[2,3,0,1] row_mask:0xf bank_mask:0xf bound_ctrl:1
	v_mov_b32_dpp v191, v19 quad_perm:[2,3,0,1] row_mask:0xf bank_mask:0xf bound_ctrl:1
	v_pk_fma_f32 v[16:17], v[2:3], v[16:17], v[188:189]
	v_pk_fma_f32 v[18:19], v[4:5], v[18:19], v[190:191]
	s_nop 0
	v_mov_b32_dpp v188, v16 quad_perm:[2,3,0,1] row_mask:0xf bank_mask:0xf bound_ctrl:1
	v_mov_b32_dpp v189, v17 quad_perm:[2,3,0,1] row_mask:0xf bank_mask:0xf bound_ctrl:1
	v_mov_b32_e32 v190, v18
	v_mov_b32_e32 v191, v19
	v_pk_fma_f32 v[16:17], v[4:5], v[16:17], v[188:189]
	v_mov_b32_dpp v190, v190 row_shl:4 row_mask:0xf bank_mask:0x5
	v_mov_b32_dpp v191, v191 row_shl:4 row_mask:0xf bank_mask:0x5
	v_mov_b32_e32 v188, v16
	v_mov_b32_e32 v189, v17
	v_mov_b32_dpp v190, v18 row_shr:4 row_mask:0xf bank_mask:0xa
	v_mov_b32_dpp v191, v19 row_shr:4 row_mask:0xf bank_mask:0xa
	v_mov_b32_dpp v188, v188 row_shl:4 row_mask:0xf bank_mask:0x5
	v_mov_b32_dpp v189, v189 row_shl:4 row_mask:0xf bank_mask:0x5
	v_pk_fma_f32 v[18:19], v[6:7], v[18:19], v[190:191]
	v_mov_b32_dpp v188, v16 row_shr:4 row_mask:0xf bank_mask:0xa
	v_mov_b32_dpp v189, v17 row_shr:4 row_mask:0xf bank_mask:0xa
	v_mov_b32_dpp v190, v18 row_ror:8 row_mask:0xf bank_mask:0xf bound_ctrl:1
	v_mov_b32_dpp v191, v19 row_ror:8 row_mask:0xf bank_mask:0xf bound_ctrl:1
	v_pk_fma_f32 v[16:17], v[6:7], v[16:17], v[188:189]
	v_pk_fma_f32 v[18:19], v[8:9], v[18:19], v[190:191]
	s_nop 0
	v_mov_b32_dpp v188, v16 row_ror:8 row_mask:0xf bank_mask:0xf bound_ctrl:1
	v_mov_b32_dpp v189, v17 row_ror:8 row_mask:0xf bank_mask:0xf bound_ctrl:1
	v_pk_fma_f32 v[16:17], v[10:11], v[16:17], v[188:189]
	v_pk_mul_f32 v[18:19], v[18:19], s[22:23] op_sel_hi:[1,0]
	v_pk_mul_f32 v[16:17], v[16:17], s[22:23] op_sel_hi:[1,0]
	v_cvt_pk_bf16_f32 v18, v18, v19
	s_nop 0
	v_lshlrev_b32_e32 v19, 16, v18
	v_and_b32_e32 v190, 0xffff0000, v18
	v_cvt_pk_bf16_f32 v16, v16, v17
	v_max_f32_e64 v17, |v190|, |v190|
	v_max_f32_e64 v18, |v19|, |v19|
	v_lshlrev_b32_e32 v191, 16, v16
	v_and_b32_e32 v192, 0xffff0000, v16
	v_max_f32_e32 v17, v18, v17
	v_max_f32_e64 v16, |v192|, |v192|
	v_max_f32_e64 v18, |v191|, |v191|
	v_max_f32_e32 v16, v18, v16
	v_max3_f32 v16, v196, v17, v16
	v_and_b32_e32 v17, 64, v98
	v_add_u32_e32 v17, 64, v17
	v_xor_b32_e32 v18, 1, v98
	v_cmp_lt_i32_e32 vcc, v18, v17
	s_nop 1
	v_cndmask_b32_e32 v18, v98, v18, vcc
	v_lshlrev_b32_e32 v18, 2, v18
	ds_bpermute_b32 v18, v18, v16
	s_waitcnt lgkmcnt(0)
	v_max_f32_e32 v18, v18, v18
	v_max_f32_e32 v16, v16, v18
	v_xor_b32_e32 v18, 2, v98
	v_cmp_lt_i32_e32 vcc, v18, v17
	s_nop 1
	v_cndmask_b32_e32 v18, v98, v18, vcc
	v_lshlrev_b32_e32 v18, 2, v18
	ds_bpermute_b32 v18, v18, v16
	s_waitcnt lgkmcnt(0)
	v_max_f32_e32 v18, v18, v18
	v_max_f32_e32 v16, v16, v18
	v_xor_b32_e32 v18, 4, v98
	v_cmp_lt_i32_e32 vcc, v18, v17
	s_nop 1
	v_cndmask_b32_e32 v18, v98, v18, vcc
	v_lshlrev_b32_e32 v18, 2, v18
	ds_bpermute_b32 v18, v18, v16
	s_waitcnt lgkmcnt(0)
; __device__ __forceinline__ float bf_lo(unsigned w) { return __uint_as_float(w << 16); }
; __device__ __forceinline__ float bf_hi(unsigned w) { return __uint_as_float(w & 0xffff0000u); }
; __device__ __forceinline__ unsigned pack_q8m(float a, float b, float c, float d, float inv) {
;     const unsigned ua = __float_as_uint(__builtin_fmaf(a, inv, 12582912.0f)), ub = __float_as_uint(__builtin_fmaf(b, inv, 12582912.0f));
;     const unsigned uc = __float_as_uint(__builtin_fmaf(c, inv, 12582912.0f)), ud = __float_as_uint(__builtin_fmaf(d, inv, 12582912.0f));
;     return __builtin_amdgcn_perm(__builtin_amdgcn_perm(ud, uc, 0x0c0c0400u), __builtin_amdgcn_perm(ub, ua, 0x0c0c0400u), 0x05040100u);
; __global__ void __launch_bounds__(NWAVES * 64, 2) fwd_kernel(Args args) {
;     ...
;             for (int o = 1; o < 64; o <<= 1) am = fmaxf(am, __shfl_xor(am, o));
;             am = fmaxf(am, 1e-30f); const float qi = 127.0f / am; unsigned* qrow = (unsigned*)(HQ8 + row * DFF) + lane;
; #pragma unroll
;             for (int c = 0; c < DFF / 256; ++c) qrow[64 * c] = pack_q8m(bf_lo(pk[c].x), bf_hi(pk[c].x), bf_lo(pk[c].y), bf_hi(pk[c].y), qi);
	v_max_f32_e32 v18, v18, v18
	v_max_f32_e32 v16, v16, v18
	v_xor_b32_e32 v18, 8, v98
	v_cmp_lt_i32_e32 vcc, v18, v17
	s_nop 1
	v_cndmask_b32_e32 v18, v98, v18, vcc
	v_lshlrev_b32_e32 v18, 2, v18
	ds_bpermute_b32 v18, v18, v16
	s_waitcnt lgkmcnt(0)
	v_max_f32_e32 v18, v18, v18
	v_max_f32_e32 v16, v16, v18
	v_xor_b32_e32 v18, 16, v98
	v_cmp_lt_i32_e32 vcc, v18, v17
	s_nop 1
	v_cndmask_b32_e32 v18, v98, v18, vcc
	v_lshlrev_b32_e32 v18, 2, v18
	ds_bpermute_b32 v18, v18, v16
	s_waitcnt lgkmcnt(0)
	v_max_f32_e32 v18, v18, v18
	v_max_f32_e32 v16, v16, v18
	v_xor_b32_e32 v18, 32, v98
	v_cmp_lt_i32_e32 vcc, v18, v17
	s_nop 1
	v_cndmask_b32_e32 v17, v98, v18, vcc
	v_lshlrev_b32_e32 v17, 2, v17
	ds_bpermute_b32 v17, v17, v16
	s_waitcnt lgkmcnt(0)
	v_max3_f32 v18, v16, v17, s8
	v_div_scale_f32 v16, s[24:25], v18, v18, s9
	v_rcp_f32_e32 v17, v16
	s_nop 0
	v_fma_f32 v188, -v16, v17, 1.0
	v_fmac_f32_e32 v17, v188, v17
	v_div_scale_f32 v188, vcc, s9, v18, s9
	v_mul_f32_e32 v189, v188, v17
	v_fma_f32 v193, -v16, v189, v188
	v_fmac_f32_e32 v189, v193, v17
	v_fma_f32 v16, -v16, v189, v188
	v_div_fmas_f32 v16, v16, v17, v189
	v_div_fixup_f32 v193, v16, v18, s9
	v_lshl_add_u64 v[16:17], s[26:27], 0, v[12:13]
	v_fmaak_f32 v99, v99, v193, 0x4b400000
	v_fmaak_f32 v100, v100, v193, 0x4b400000
	v_fmaak_f32 v101, v101, v193, 0x4b400000
	v_fmaak_f32 v102, v102, v193, 0x4b400000
	v_perm_b32 v101, v102, v101, s11
	v_perm_b32 v99, v100, v99, s11
	v_add_co_u32_e32 v100, vcc, s13, v16
	v_perm_b32 v99, v101, v99, s12
	s_nop 0
	v_addc_co_u32_e32 v101, vcc, 0, v17, vcc
	v_add_co_u32_e32 v188, vcc, s20, v16
	v_fmaak_f32 v102, v104, v193, 0x4b400000
	s_nop 0
	v_addc_co_u32_e32 v189, vcc, 0, v17, vcc
	global_store_dword v[188:189], v99, off offset:-4096
	v_fmaak_f32 v99, v103, v193, 0x4b400000
	v_fmaak_f32 v103, v105, v193, 0x4b400000
	v_fmaak_f32 v104, v106, v193, 0x4b400000
	v_perm_b32 v103, v104, v103, s11
	v_perm_b32 v99, v102, v99, s11
	v_perm_b32 v99, v103, v99, s12
	global_store_dword v[100:101], v99, off offset:256
	v_fmaak_f32 v96, v96, v193, 0x4b400000
	v_fmaak_f32 v97, v97, v193, 0x4b400000
	v_fmaak_f32 v99, v107, v193, 0x4b400000
	v_fmaak_f32 v102, v108, v193, 0x4b400000
	v_perm_b32 v99, v102, v99, s11
	v_perm_b32 v96, v97, v96, s11
	v_perm_b32 v96, v99, v96, s12
	global_store_dword v[100:101], v96, off offset:512
	v_fmaak_f32 v94, v94, v193, 0x4b400000
	v_fmaak_f32 v95, v95, v193, 0x4b400000
	v_fmaak_f32 v96, v109, v193, 0x4b400000
	v_fmaak_f32 v97, v110, v193, 0x4b400000
	v_perm_b32 v96, v97, v96, s11
	v_perm_b32 v94, v95, v94, s11
	v_perm_b32 v94, v96, v94, s12
	global_store_dword v[100:101], v94, off offset:768
	v_fmaak_f32 v92, v92, v193, 0x4b400000
	v_fmaak_f32 v93, v93, v193, 0x4b400000
	v_fmaak_f32 v94, v111, v193, 0x4b400000
	v_fmaak_f32 v95, v112, v193, 0x4b400000
	v_perm_b32 v94, v95, v94, s11
	v_perm_b32 v92, v93, v92, s11
	v_perm_b32 v92, v94, v92, s12
	global_store_dword v[100:101], v92, off offset:1024
	v_fmaak_f32 v90, v90, v193, 0x4b400000
	v_fmaak_f32 v91, v91, v193, 0x4b400000
	v_fmaak_f32 v92, v113, v193, 0x4b400000
	v_fmaak_f32 v93, v114, v193, 0x4b400000
	v_perm_b32 v92, v93, v92, s11
	v_perm_b32 v90, v91, v90, s11
	v_perm_b32 v90, v92, v90, s12
	global_store_dword v[100:101], v90, off offset:1280
	v_fmaak_f32 v88, v88, v193, 0x4b400000
	v_fmaak_f32 v89, v89, v193, 0x4b400000
	v_fmaak_f32 v90, v115, v193, 0x4b400000
	v_fmaak_f32 v91, v116, v193, 0x4b400000
	v_perm_b32 v90, v91, v90, s11
	v_perm_b32 v88, v89, v88, s11
	v_perm_b32 v88, v90, v88, s12
	global_store_dword v[100:101], v88, off offset:1536
	v_fmaak_f32 v86, v86, v193, 0x4b400000
	v_fmaak_f32 v87, v87, v193, 0x4b400000
	v_fmaak_f32 v88, v117, v193, 0x4b400000
	v_fmaak_f32 v89, v118, v193, 0x4b400000
	v_perm_b32 v88, v89, v88, s11
	v_perm_b32 v86, v87, v86, s11
	v_perm_b32 v86, v88, v86, s12
	global_store_dword v[100:101], v86, off offset:1792
	v_fmaak_f32 v84, v84, v193, 0x4b400000
	v_fmaak_f32 v85, v85, v193, 0x4b400000
	v_fmaak_f32 v86, v119, v193, 0x4b400000
	v_fmaak_f32 v87, v120, v193, 0x4b400000
	v_perm_b32 v86, v87, v86, s11
	v_perm_b32 v84, v85, v84, s11
	v_perm_b32 v84, v86, v84, s12
	global_store_dword v[100:101], v84, off offset:2048
	v_fmaak_f32 v82, v82, v193, 0x4b400000
	v_fmaak_f32 v83, v83, v193, 0x4b400000
	v_fmaak_f32 v84, v121, v193, 0x4b400000
	v_fmaak_f32 v85, v122, v193, 0x4b400000
	v_perm_b32 v84, v85, v84, s11
	v_perm_b32 v82, v83, v82, s11
	v_perm_b32 v82, v84, v82, s12
	global_store_dword v[100:101], v82, off offset:2304
	v_fmaak_f32 v80, v80, v193, 0x4b400000
	v_fmaak_f32 v81, v81, v193, 0x4b400000
	v_fmaak_f32 v82, v123, v193, 0x4b400000
	v_fmaak_f32 v83, v124, v193, 0x4b400000
	v_perm_b32 v82, v83, v82, s11
	v_perm_b32 v80, v81, v80, s11
	v_perm_b32 v80, v82, v80, s12
	global_store_dword v[100:101], v80, off offset:2560
	v_fmaak_f32 v78, v78, v193, 0x4b400000
	v_fmaak_f32 v79, v79, v193, 0x4b400000
	v_fmaak_f32 v80, v125, v193, 0x4b400000
	v_fmaak_f32 v81, v126, v193, 0x4b400000
	v_perm_b32 v80, v81, v80, s11
	v_perm_b32 v78, v79, v78, s11
	v_perm_b32 v78, v80, v78, s12
	global_store_dword v[100:101], v78, off offset:2816
	v_fmaak_f32 v76, v76, v193, 0x4b400000
	v_fmaak_f32 v77, v77, v193, 0x4b400000
	v_fmaak_f32 v78, v127, v193, 0x4b400000
	v_fmaak_f32 v79, v128, v193, 0x4b400000
	v_perm_b32 v78, v79, v78, s11
	v_perm_b32 v76, v77, v76, s11
	v_perm_b32 v76, v78, v76, s12
	global_store_dword v[100:101], v76, off offset:3072
	v_fmaak_f32 v74, v74, v193, 0x4b400000
	v_fmaak_f32 v75, v75, v193, 0x4b400000
	v_fmaak_f32 v76, v129, v193, 0x4b400000
	v_fmaak_f32 v77, v130, v193, 0x4b400000
	v_perm_b32 v76, v77, v76, s11
	v_perm_b32 v74, v75, v74, s11
; __device__ __forceinline__ float bf_lo(unsigned w) { return __uint_as_float(w << 16); }
; __device__ __forceinline__ float bf_hi(unsigned w) { return __uint_as_float(w & 0xffff0000u); }
; __device__ __forceinline__ unsigned pack_q8m(float a, float b, float c, float d, float inv) {
;     const unsigned ua = __float_as_uint(__builtin_fmaf(a, inv, 12582912.0f)), ub = __float_as_uint(__builtin_fmaf(b, inv, 12582912.0f));
;     const unsigned uc = __float_as_uint(__builtin_fmaf(c, inv, 12582912.0f)), ud = __float_as_uint(__builtin_fmaf(d, inv, 12582912.0f));
;     return __builtin_amdgcn_perm(__builtin_amdgcn_perm(ud, uc, 0x0c0c0400u), __builtin_amdgcn_perm(ub, ua, 0x0c0c0400u), 0x05040100u);
; __global__ void __launch_bounds__(NWAVES * 64, 2) fwd_kernel(Args args) {
;     ...
; #pragma unroll
;             for (int c = 0; c < DFF / 256; ++c) qrow[64 * c] = pack_q8m(bf_lo(pk[c].x), bf_hi(pk[c].x), bf_lo(pk[c].y), bf_hi(pk[c].y), qi);
	v_perm_b32 v74, v76, v74, s12
	global_store_dword v[100:101], v74, off offset:3328
	v_fmaak_f32 v72, v72, v193, 0x4b400000
	v_fmaak_f32 v73, v73, v193, 0x4b400000
	v_fmaak_f32 v74, v131, v193, 0x4b400000
	v_fmaak_f32 v75, v132, v193, 0x4b400000
	v_perm_b32 v74, v75, v74, s11
	v_perm_b32 v72, v73, v72, s11
	v_perm_b32 v72, v74, v72, s12
	global_store_dword v[100:101], v72, off offset:3584
	v_fmaak_f32 v70, v70, v193, 0x4b400000
	v_fmaak_f32 v71, v71, v193, 0x4b400000
	v_fmaak_f32 v72, v133, v193, 0x4b400000
	v_fmaak_f32 v73, v134, v193, 0x4b400000
	v_perm_b32 v72, v73, v72, s11
	v_perm_b32 v70, v71, v70, s11
	v_perm_b32 v70, v72, v70, s12
	global_store_dword v[100:101], v70, off offset:3840
	v_fmaak_f32 v68, v68, v193, 0x4b400000
	v_fmaak_f32 v69, v69, v193, 0x4b400000
	v_fmaak_f32 v70, v135, v193, 0x4b400000
	v_fmaak_f32 v71, v136, v193, 0x4b400000
	v_perm_b32 v70, v71, v70, s11
	v_perm_b32 v68, v69, v68, s11
	v_perm_b32 v68, v70, v68, s12
	global_store_dword v[188:189], v68, off
	v_fmaak_f32 v66, v66, v193, 0x4b400000
	v_fmaak_f32 v67, v67, v193, 0x4b400000
	v_fmaak_f32 v68, v137, v193, 0x4b400000
	v_fmaak_f32 v69, v138, v193, 0x4b400000
	v_perm_b32 v68, v69, v68, s11
	v_perm_b32 v66, v67, v66, s11
	v_perm_b32 v66, v68, v66, s12
	global_store_dword v[188:189], v66, off offset:256
	v_fmaak_f32 v64, v64, v193, 0x4b400000
	v_fmaak_f32 v65, v65, v193, 0x4b400000
	v_fmaak_f32 v66, v139, v193, 0x4b400000
	v_fmaak_f32 v67, v140, v193, 0x4b400000
	v_perm_b32 v66, v67, v66, s11
	v_perm_b32 v64, v65, v64, s11
	v_perm_b32 v64, v66, v64, s12
	global_store_dword v[188:189], v64, off offset:512
	v_fmaak_f32 v62, v62, v193, 0x4b400000
	v_fmaak_f32 v63, v63, v193, 0x4b400000
	v_fmaak_f32 v64, v141, v193, 0x4b400000
	v_fmaak_f32 v65, v142, v193, 0x4b400000
	v_perm_b32 v64, v65, v64, s11
	v_perm_b32 v62, v63, v62, s11
	v_perm_b32 v62, v64, v62, s12
	global_store_dword v[188:189], v62, off offset:768
	v_fmaak_f32 v60, v60, v193, 0x4b400000
	v_fmaak_f32 v61, v61, v193, 0x4b400000
	v_fmaak_f32 v62, v143, v193, 0x4b400000
	v_fmaak_f32 v63, v144, v193, 0x4b400000
	v_perm_b32 v62, v63, v62, s11
	v_perm_b32 v60, v61, v60, s11
	v_perm_b32 v60, v62, v60, s12
	global_store_dword v[188:189], v60, off offset:1024
	v_fmaak_f32 v58, v58, v193, 0x4b400000
	v_fmaak_f32 v59, v59, v193, 0x4b400000
	v_fmaak_f32 v60, v145, v193, 0x4b400000
	v_fmaak_f32 v61, v146, v193, 0x4b400000
	v_perm_b32 v60, v61, v60, s11
	v_perm_b32 v58, v59, v58, s11
	v_perm_b32 v58, v60, v58, s12
	global_store_dword v[188:189], v58, off offset:1280
	v_fmaak_f32 v56, v56, v193, 0x4b400000
	v_fmaak_f32 v57, v57, v193, 0x4b400000
	v_fmaak_f32 v58, v147, v193, 0x4b400000
	v_fmaak_f32 v59, v148, v193, 0x4b400000
	v_perm_b32 v58, v59, v58, s11
	v_perm_b32 v56, v57, v56, s11
	v_perm_b32 v56, v58, v56, s12
	global_store_dword v[188:189], v56, off offset:1536
	v_fmaak_f32 v54, v54, v193, 0x4b400000
	v_fmaak_f32 v55, v55, v193, 0x4b400000
	v_fmaak_f32 v56, v149, v193, 0x4b400000
	v_fmaak_f32 v57, v150, v193, 0x4b400000
	v_perm_b32 v56, v57, v56, s11
	v_perm_b32 v54, v55, v54, s11
	v_perm_b32 v54, v56, v54, s12
	global_store_dword v[188:189], v54, off offset:1792
	v_fmaak_f32 v52, v52, v193, 0x4b400000
	v_fmaak_f32 v53, v53, v193, 0x4b400000
	v_fmaak_f32 v54, v151, v193, 0x4b400000
	v_fmaak_f32 v55, v152, v193, 0x4b400000
	v_perm_b32 v54, v55, v54, s11
	v_perm_b32 v52, v53, v52, s11
	v_perm_b32 v52, v54, v52, s12
	global_store_dword v[188:189], v52, off offset:2048
	v_fmaak_f32 v50, v50, v193, 0x4b400000
	v_fmaak_f32 v51, v51, v193, 0x4b400000
	v_fmaak_f32 v52, v153, v193, 0x4b400000
	v_fmaak_f32 v53, v154, v193, 0x4b400000
	v_perm_b32 v52, v53, v52, s11
	v_perm_b32 v50, v51, v50, s11
	v_perm_b32 v50, v52, v50, s12
	global_store_dword v[188:189], v50, off offset:2304
	v_fmaak_f32 v48, v48, v193, 0x4b400000
	v_fmaak_f32 v49, v49, v193, 0x4b400000
	v_fmaak_f32 v50, v155, v193, 0x4b400000
	v_fmaak_f32 v51, v156, v193, 0x4b400000
	v_perm_b32 v50, v51, v50, s11
	v_perm_b32 v48, v49, v48, s11
	v_perm_b32 v48, v50, v48, s12
	global_store_dword v[188:189], v48, off offset:2560
	v_fmaak_f32 v46, v46, v193, 0x4b400000
	v_fmaak_f32 v47, v47, v193, 0x4b400000
	v_fmaak_f32 v48, v157, v193, 0x4b400000
	v_fmaak_f32 v49, v158, v193, 0x4b400000
	v_perm_b32 v48, v49, v48, s11
	v_perm_b32 v46, v47, v46, s11
	v_perm_b32 v46, v48, v46, s12
	global_store_dword v[188:189], v46, off offset:2816
	v_fmaak_f32 v44, v44, v193, 0x4b400000
	v_fmaak_f32 v45, v45, v193, 0x4b400000
	v_fmaak_f32 v46, v159, v193, 0x4b400000
	v_fmaak_f32 v47, v160, v193, 0x4b400000
	v_perm_b32 v46, v47, v46, s11
	v_perm_b32 v44, v45, v44, s11
	v_perm_b32 v44, v46, v44, s12
; __device__ __forceinline__ float bf_lo(unsigned w) { return __uint_as_float(w << 16); }
; __device__ __forceinline__ float bf_hi(unsigned w) { return __uint_as_float(w & 0xffff0000u); }
; __device__ __forceinline__ unsigned pack_q8m(float a, float b, float c, float d, float inv) {
;     const unsigned ua = __float_as_uint(__builtin_fmaf(a, inv, 12582912.0f)), ub = __float_as_uint(__builtin_fmaf(b, inv, 12582912.0f));
;     const unsigned uc = __float_as_uint(__builtin_fmaf(c, inv, 12582912.0f)), ud = __float_as_uint(__builtin_fmaf(d, inv, 12582912.0f));
;     return __builtin_amdgcn_perm(__builtin_amdgcn_perm(ud, uc, 0x0c0c0400u), __builtin_amdgcn_perm(ub, ua, 0x0c0c0400u), 0x05040100u);
; __global__ void __launch_bounds__(NWAVES * 64, 2) fwd_kernel(Args args) {
;     ...
; #pragma unroll
;             for (int c = 0; c < DFF / 256; ++c) qrow[64 * c] = pack_q8m(bf_lo(pk[c].x), bf_hi(pk[c].x), bf_lo(pk[c].y), bf_hi(pk[c].y), qi);
;             if (lane == 0) rhscale[row] = am * (1.0f / 127.0f); }
	global_store_dword v[188:189], v44, off offset:3072
	v_fmaak_f32 v42, v42, v193, 0x4b400000
	v_fmaak_f32 v43, v43, v193, 0x4b400000
	v_fmaak_f32 v44, v161, v193, 0x4b400000
	v_fmaak_f32 v45, v162, v193, 0x4b400000
	v_perm_b32 v44, v45, v44, s11
	v_perm_b32 v42, v43, v42, s11
	v_perm_b32 v42, v44, v42, s12
	global_store_dword v[188:189], v42, off offset:3328
	v_fmaak_f32 v40, v40, v193, 0x4b400000
	v_fmaak_f32 v41, v41, v193, 0x4b400000
	v_fmaak_f32 v42, v163, v193, 0x4b400000
	v_fmaak_f32 v43, v164, v193, 0x4b400000
	v_perm_b32 v42, v43, v42, s11
	v_perm_b32 v40, v41, v40, s11
	v_perm_b32 v40, v42, v40, s12
	global_store_dword v[188:189], v40, off offset:3584
	v_fmaak_f32 v38, v38, v193, 0x4b400000
	v_fmaak_f32 v39, v39, v193, 0x4b400000
	v_fmaak_f32 v40, v165, v193, 0x4b400000
	v_fmaak_f32 v41, v166, v193, 0x4b400000
	v_perm_b32 v40, v41, v40, s11
	v_perm_b32 v38, v39, v38, s11
	v_perm_b32 v38, v40, v38, s12
	global_store_dword v[188:189], v38, off offset:3840
	v_fmaak_f32 v36, v36, v193, 0x4b400000
	v_fmaak_f32 v37, v37, v193, 0x4b400000
	v_fmaak_f32 v38, v167, v193, 0x4b400000
	v_fmaak_f32 v39, v168, v193, 0x4b400000
	v_perm_b32 v38, v39, v38, s11
	v_perm_b32 v36, v37, v36, s11
	v_add_co_u32_e32 v16, vcc, s21, v16
	v_perm_b32 v36, v38, v36, s12
	s_nop 0
	v_addc_co_u32_e32 v17, vcc, 0, v17, vcc
	global_store_dword v[16:17], v36, off
	v_fmaak_f32 v34, v34, v193, 0x4b400000
	v_fmaak_f32 v35, v35, v193, 0x4b400000
	v_fmaak_f32 v36, v169, v193, 0x4b400000
	v_fmaak_f32 v37, v170, v193, 0x4b400000
	v_perm_b32 v36, v37, v36, s11
	v_perm_b32 v34, v35, v34, s11
	v_perm_b32 v34, v36, v34, s12
	global_store_dword v[16:17], v34, off offset:256
	v_fmaak_f32 v32, v32, v193, 0x4b400000
	v_fmaak_f32 v33, v33, v193, 0x4b400000
	v_fmaak_f32 v34, v171, v193, 0x4b400000
	v_fmaak_f32 v35, v172, v193, 0x4b400000
	v_perm_b32 v34, v35, v34, s11
	v_perm_b32 v32, v33, v32, s11
	v_perm_b32 v32, v34, v32, s12
	global_store_dword v[16:17], v32, off offset:512
	v_fmaak_f32 v30, v30, v193, 0x4b400000
	v_fmaak_f32 v31, v31, v193, 0x4b400000
	v_fmaak_f32 v32, v173, v193, 0x4b400000
	v_fmaak_f32 v33, v174, v193, 0x4b400000
	v_perm_b32 v32, v33, v32, s11
	v_perm_b32 v30, v31, v30, s11
	v_perm_b32 v30, v32, v30, s12
	global_store_dword v[16:17], v30, off offset:768
	v_fmaak_f32 v28, v28, v193, 0x4b400000
	v_fmaak_f32 v29, v29, v193, 0x4b400000
	v_fmaak_f32 v30, v175, v193, 0x4b400000
	v_fmaak_f32 v31, v176, v193, 0x4b400000
	v_perm_b32 v30, v31, v30, s11
	v_perm_b32 v28, v29, v28, s11
	v_perm_b32 v28, v30, v28, s12
	global_store_dword v[16:17], v28, off offset:1024
	v_fmaak_f32 v26, v26, v193, 0x4b400000
	v_fmaak_f32 v27, v27, v193, 0x4b400000
	v_fmaak_f32 v28, v177, v193, 0x4b400000
	v_fmaak_f32 v29, v181, v193, 0x4b400000
	v_perm_b32 v28, v29, v28, s11
	v_perm_b32 v26, v27, v26, s11
	v_perm_b32 v26, v28, v26, s12
	global_store_dword v[16:17], v26, off offset:1280
	v_fmaak_f32 v24, v24, v193, 0x4b400000
	v_fmaak_f32 v25, v25, v193, 0x4b400000
	v_fmaak_f32 v26, v182, v193, 0x4b400000
	v_fmaak_f32 v27, v183, v193, 0x4b400000
	v_perm_b32 v26, v27, v26, s11
	v_perm_b32 v24, v25, v24, s11
	v_perm_b32 v24, v26, v24, s12
	global_store_dword v[16:17], v24, off offset:1536
	v_fmaak_f32 v22, v22, v193, 0x4b400000
	v_fmaak_f32 v23, v23, v193, 0x4b400000
	v_fmaak_f32 v24, v184, v193, 0x4b400000
	v_fmaak_f32 v25, v185, v193, 0x4b400000
	v_perm_b32 v24, v25, v24, s11
	v_perm_b32 v22, v23, v22, s11
	v_perm_b32 v22, v24, v22, s12
	global_store_dword v[16:17], v22, off offset:1792
	v_fmaak_f32 v20, v20, v193, 0x4b400000
	v_fmaak_f32 v21, v21, v193, 0x4b400000
	v_fmaak_f32 v22, v186, v193, 0x4b400000
	v_fmaak_f32 v23, v187, v193, 0x4b400000
	v_perm_b32 v22, v23, v22, s11
	v_perm_b32 v20, v21, v20, s11
	v_perm_b32 v20, v22, v20, s12
	global_store_dword v[16:17], v20, off offset:2048
	v_fmaak_f32 v20, v194, v193, 0x4b400000
	v_fmaak_f32 v21, v195, v193, 0x4b400000
	v_fmaak_f32 v22, v197, v193, 0x4b400000
	v_fmaak_f32 v23, v198, v193, 0x4b400000
	v_perm_b32 v22, v23, v22, s11
	v_perm_b32 v20, v21, v20, s11
	v_perm_b32 v20, v22, v20, s12
	global_store_dword v[16:17], v20, off offset:2304
	v_fmaak_f32 v19, v19, v193, 0x4b400000
	v_fmaak_f32 v20, v190, v193, 0x4b400000
	v_fmaak_f32 v21, v191, v193, 0x4b400000
	v_fmaak_f32 v22, v192, v193, 0x4b400000
	v_perm_b32 v21, v22, v21, s11
	v_perm_b32 v19, v20, v19, s11
	v_perm_b32 v19, v21, v19, s12
	global_store_dword v[16:17], v19, off offset:2560
	s_and_saveexec_b64 s[24:25], s[2:3]
	s_cbranch_execz .LBB0_943
	s_mov_b64 s[26:27], s[78:79]
	s_add_u32 s26, s26, s6
	s_addc_u32 s27, s27, s7
	v_mul_f32_e32 v16, 0x3c010204, v18
	global_store_dword v1, v16, s[26:27]
	s_branch .LBB0_943

; __device__ __forceinline__ float bf_lo(unsigned w) { return __uint_as_float(w << 16); }
; __device__ __forceinline__ float bf_hi(unsigned w) { return __uint_as_float(w & 0xffff0000u); }
; __device__ __forceinline__ float dot4(f32x4 a) { return (a.x * a.x + a.y * a.y) + (a.z * a.z + a.w * a.w); }
; __global__ void __launch_bounds__(NWAVES * 64, 2) fwd_kernel(Args args) {
;     ...
;             { const size_t row = (size_t)slot * 8 + wave;
;                 f32x4* xr = (f32x4*)(out + row * D) + lane; const v2u* yr = (const v2u*)(Y2 + row * D) + lane; const v2u* x1r = (const v2u*)(X1B + row * D) + lane;
;                 f32x4 v[16]; v2u yv[16]; float sy = 0.f;
; #pragma unroll
;                 for (int j = 0; j < 16; ++j) { const v2u q = x1r[64 * j]; v[j] = (f32x4){bf_lo(q.x), bf_hi(q.x), bf_lo(q.y), bf_hi(q.y)}; yv[j] = yr[64 * j]; }
; #pragma unroll
;                 for (int j = 0; j < 16; ++j) { const f32x4 y = {bf_lo(yv[j].x), bf_hi(yv[j].x), bf_lo(yv[j].y), bf_hi(yv[j].y)}; sy += dot4(y); }
;                 const float rstdy = 1.0f / sqrtf(wave_sum(sy) * (1.0f / D) + RMS_EPS);
.LBB0_1101:
	v_add_co_u32_e32 v22, vcc, 0xfffff000, v16
	global_load_dwordx2 v[20:21], v[16:17], off offset:-4096 nt
	global_load_dwordx2 v[100:101], v[16:17], off offset:-3584 nt
	v_addc_co_u32_e32 v23, vcc, -1, v17, vcc
	v_add_co_u32_e32 v24, vcc, 0xf7fff000, v16
	global_load_dwordx2 v[26:27], v[22:23], off offset:-3584 nt
	global_load_dwordx2 v[28:29], v[22:23], off offset:-3072 nt
	global_load_dwordx2 v[30:31], v[22:23], off offset:-2560 nt
	global_load_dwordx2 v[32:33], v[22:23], off offset:-2048 nt
	global_load_dwordx2 v[36:37], v[22:23], off offset:-1536 nt
	global_load_dwordx2 v[40:41], v[22:23], off offset:-1024 nt
	v_addc_co_u32_e32 v25, vcc, -1, v17, vcc
	global_load_dwordx2 v[44:45], v[22:23], off offset:-512 nt
	global_load_dwordx2 v[46:47], v[24:25], off offset:-3584 nt
	global_load_dwordx2 v[50:51], v[24:25], off offset:-3072 nt
	global_load_dwordx2 v[52:53], v[24:25], off offset:-2560 nt
	global_load_dwordx2 v[54:55], v[24:25], off offset:-2048 nt
	v_add_co_u32_e32 v22, vcc, s9, v16
	s_add_i32 s34, s34, s10
	s_nop 0
	v_addc_co_u32_e32 v23, vcc, -1, v17, vcc
	global_load_dwordx2 v[102:103], v[16:17], off offset:-3072 nt
	global_load_dwordx2 v[126:127], v[16:17], off offset:-2560 nt
	global_load_dwordx2 v[128:129], v[16:17], off offset:-2048 nt
	global_load_dwordx2 v[130:131], v[16:17], off offset:-1536 nt
	global_load_dwordx2 v[132:133], v[16:17], off offset:-1024 nt
	global_load_dwordx2 v[116:117], v[16:17], off offset:-512 nt
	global_load_dwordx2 v[110:111], v[16:17], off nt
	global_load_dwordx2 v[58:59], v[22:23], off offset:-3072 nt
	global_load_dwordx2 v[60:61], v[22:23], off offset:-2560 nt
	global_load_dwordx2 v[64:65], v[22:23], off offset:-2048 nt
	global_load_dwordx2 v[70:71], v[22:23], off offset:-1536 nt
	global_load_dwordx2 v[138:139], v[22:23], off offset:-1024 nt
	global_load_dwordx2 v[38:39], v[22:23], off offset:-512 nt
	global_load_dwordx2 v[42:43], v[22:23], off nt
	global_load_dwordx2 v[68:69], v[24:25], off offset:-1536 nt
	global_load_dwordx2 v[72:73], v[24:25], off offset:-1024 nt
	global_load_dwordx2 v[74:75], v[24:25], off offset:-512 nt
	global_load_dwordx2 v[76:77], v[24:25], off nt
	global_load_dwordx2 v[90:91], v[22:23], off offset:-3584 nt
	ds_read_b128 v[172:175], v163
	v_lshl_add_u64 v[16:17], v[16:17], 0, s[4:5]
	s_cmpk_lt_i32 s34, 0x800
	s_waitcnt vmcnt(0)
	v_lshlrev_b32_e32 v154, 16, v102
	v_lshlrev_b32_e32 v150, 16, v127
	v_and_b32_e32 v151, 0xffff0000, v127
	v_lshlrev_b32_e32 v92, 16, v26
	v_and_b32_e32 v93, 0xffff0000, v26
	v_lshlrev_b32_e32 v62, 16, v30
	v_and_b32_e32 v63, 0xffff0000, v30
	v_lshlrev_b32_e32 v66, 16, v31
	v_and_b32_e32 v67, 0xffff0000, v31
	v_and_b32_e32 v141, 0xffff0000, v46
	v_and_b32_e32 v143, 0xffff0000, v47
	v_lshlrev_b32_e32 v30, 16, v40
	v_and_b32_e32 v31, 0xffff0000, v40
	v_lshlrev_b32_e32 v140, 16, v46
	v_lshlrev_b32_e32 v142, 16, v47
	v_mul_f32_e32 v40, v143, v143
	v_and_b32_e32 v137, 0xffff0000, v51
	v_and_b32_e32 v136, 0xffff0000, v50
	v_mul_f32_e32 v46, v141, v141
	v_lshlrev_b32_e32 v96, 16, v27
	v_and_b32_e32 v97, 0xffff0000, v27
	v_lshlrev_b32_e32 v80, 16, v28
	v_and_b32_e32 v81, 0xffff0000, v28
	v_lshlrev_b32_e32 v86, 16, v29
	v_and_b32_e32 v87, 0xffff0000, v29
	v_lshlrev_b32_e32 v48, 16, v32
	v_and_b32_e32 v49, 0xffff0000, v32
	v_lshlrev_b32_e32 v56, 16, v33
	v_and_b32_e32 v57, 0xffff0000, v33
	v_lshlrev_b32_e32 v32, 16, v41
	v_and_b32_e32 v33, 0xffff0000, v41
	v_lshlrev_b32_e32 v26, 16, v44
	v_and_b32_e32 v27, 0xffff0000, v44
	v_lshlrev_b32_e32 v28, 16, v45
	v_and_b32_e32 v29, 0xffff0000, v45
	v_pk_fma_f32 v[40:41], v[142:143], v[142:143], v[40:41] op_sel_hi:[1,1,0]
	v_lshlrev_b32_e32 v135, 16, v51
	v_lshlrev_b32_e32 v134, 16, v50
	v_pk_mul_f32 v[44:45], v[136:137], v[136:137]
	v_lshlrev_b32_e32 v115, 16, v54
	v_pk_fma_f32 v[46:47], v[140:141], v[140:141], v[46:47] op_sel_hi:[1,1,0]
	v_pk_fma_f32 v[44:45], v[134:135], v[134:135], v[44:45]
	v_and_b32_e32 v113, 0xffff0000, v54
	v_mov_b32_e32 v114, v46
	v_mov_b32_e32 v50, v40
	v_mov_b32_e32 v51, v115
	v_lshlrev_b32_e32 v122, 16, v52
	v_and_b32_e32 v123, 0xffff0000, v52
	v_mul_f32_e32 v52, v113, v113
	v_pk_add_f32 v[40:41], v[46:47], v[40:41]
	v_pk_mul_f32 v[46:47], v[114:115], v[50:51]
	v_pk_add_f32 v[44:45], v[44:45], v[44:45] op_sel:[0,1] op_sel_hi:[1,0]
	v_and_b32_e32 v125, 0xffff0000, v53
	v_mov_b32_e32 v41, v47
	v_mov_b32_e32 v45, v52
	v_lshlrev_b32_e32 v124, 16, v53
	v_lshlrev_b32_e32 v108, 16, v55
	v_and_b32_e32 v109, 0xffff0000, v55
	v_pk_add_f32 v[40:41], v[40:41], v[44:45]
	v_mul_f32_e32 v44, v123, v123
	v_mul_f32_e32 v46, v125, v125
	v_mul_f32_e32 v53, v108, v108
	v_mul_f32_e32 v54, v109, v109
	v_pk_fma_f32 v[44:45], v[122:123], v[122:123], v[44:45] op_sel_hi:[1,1,0]
	v_pk_fma_f32 v[46:47], v[124:125], v[124:125], v[46:47] op_sel_hi:[1,1,0]
	v_mov_b32_e32 v45, v53
	v_mov_b32_e32 v47, v54
	v_pk_add_f32 v[44:45], v[44:45], v[46:47]
	v_and_b32_e32 v121, 0xffff0000, v69
	v_and_b32_e32 v120, 0xffff0000, v68
	v_pk_add_f32 v[40:41], v[40:41], v[44:45]
	v_lshlrev_b32_e32 v119, 16, v69
	v_lshlrev_b32_e32 v118, 16, v68
	v_pk_mul_f32 v[44:45], v[120:121], v[120:121]
	v_and_b32_e32 v107, 0xffff0000, v73
	v_pk_fma_f32 v[44:45], v[118:119], v[118:119], v[44:45]
	v_and_b32_e32 v106, 0xffff0000, v72
	v_pk_add_f32 v[44:45], v[44:45], v[44:45] op_sel:[0,1] op_sel_hi:[1,0]
	v_lshlrev_b32_e32 v85, 16, v76
	v_pk_add_f32 v[40:41], v[40:41], v[40:41] op_sel:[0,1] op_sel_hi:[1,0]
	v_lshlrev_b32_e32 v105, 16, v73
	v_lshlrev_b32_e32 v104, 16, v72
	v_pk_mul_f32 v[46:47], v[106:107], v[106:107]
	v_mov_b32_e32 v84, v40
	v_mov_b32_e32 v50, v44
	v_mov_b32_e32 v51, v85
	v_pk_fma_f32 v[46:47], v[104:105], v[104:105], v[46:47]
; __device__ __forceinline__ float bf_lo(unsigned w) { return __uint_as_float(w << 16); }
; __device__ __forceinline__ float bf_hi(unsigned w) { return __uint_as_float(w & 0xffff0000u); }
; __device__ __forceinline__ float dot4(f32x4 a) { return (a.x * a.x + a.y * a.y) + (a.z * a.z + a.w * a.w); }
; __device__ __forceinline__ float wave_sum(float v) {
; #pragma unroll
;     for (int o = 1; o < 64; o <<= 1) v += __shfl_xor(v, o);
;     return v;
; }
; __global__ void __launch_bounds__(NWAVES * 64, 2) fwd_kernel(Args args) {
;     ...
;                 for (int j = 0; j < 16; ++j) { const f32x4 y = {bf_lo(yv[j].x), bf_hi(yv[j].x), bf_lo(yv[j].y), bf_hi(yv[j].y)}; sy += dot4(y); }
;                 const float rstdy = 1.0f / sqrtf(wave_sum(sy) * (1.0f / D) + RMS_EPS);
	v_and_b32_e32 v83, 0xffff0000, v76
	v_pk_add_f32 v[40:41], v[40:41], v[44:45]
	v_pk_mul_f32 v[44:45], v[84:85], v[50:51]
	v_mul_f32_e32 v52, v83, v83
	v_mov_b32_e32 v41, v45
	v_pk_add_f32 v[44:45], v[46:47], v[46:47] op_sel:[0,1] op_sel_hi:[1,0]
	v_and_b32_e32 v95, 0xffff0000, v74
	v_and_b32_e32 v99, 0xffff0000, v75
	v_mov_b32_e32 v45, v52
	v_lshlrev_b32_e32 v94, 16, v74
	v_lshlrev_b32_e32 v98, 16, v75
	v_lshlrev_b32_e32 v78, 16, v77
	v_and_b32_e32 v79, 0xffff0000, v77
	v_pk_add_f32 v[40:41], v[40:41], v[44:45]
	v_mul_f32_e32 v44, v95, v95
	v_mul_f32_e32 v46, v99, v99
	v_mul_f32_e32 v53, v78, v78
	v_mul_f32_e32 v54, v79, v79
	v_pk_fma_f32 v[44:45], v[94:95], v[94:95], v[44:45] op_sel_hi:[1,1,0]
	v_pk_fma_f32 v[46:47], v[98:99], v[98:99], v[46:47] op_sel_hi:[1,1,0]
	v_mov_b32_e32 v45, v53
	v_mov_b32_e32 v47, v54
	v_pk_add_f32 v[44:45], v[44:45], v[46:47]
	v_lshlrev_b32_e32 v89, 16, v91
	v_lshlrev_b32_e32 v88, 16, v90
	v_and_b32_e32 v91, 0xffff0000, v91
	v_and_b32_e32 v90, 0xffff0000, v90
	v_pk_add_f32 v[40:41], v[40:41], v[44:45]
	v_pk_mul_f32 v[44:45], v[90:91], v[90:91]
	v_and_b32_e32 v77, 0xffff0000, v59
	v_pk_fma_f32 v[44:45], v[88:89], v[88:89], v[44:45]
	v_and_b32_e32 v76, 0xffff0000, v58
	v_pk_add_f32 v[44:45], v[44:45], v[44:45] op_sel:[0,1] op_sel_hi:[1,0]
	v_lshlrev_b32_e32 v55, 16, v64
	v_pk_add_f32 v[40:41], v[40:41], v[40:41] op_sel:[0,1] op_sel_hi:[1,0]
	v_lshlrev_b32_e32 v75, 16, v59
	v_lshlrev_b32_e32 v74, 16, v58
	v_pk_mul_f32 v[46:47], v[76:77], v[76:77]
	v_mov_b32_e32 v54, v40
	v_mov_b32_e32 v50, v44
	v_mov_b32_e32 v51, v55
	v_pk_fma_f32 v[46:47], v[74:75], v[74:75], v[46:47]
	v_and_b32_e32 v53, 0xffff0000, v64
	v_pk_add_f32 v[40:41], v[40:41], v[44:45]
	v_pk_mul_f32 v[44:45], v[54:55], v[50:51]
	v_mul_f32_e32 v52, v53, v53
	v_mov_b32_e32 v41, v45
	v_pk_add_f32 v[44:45], v[46:47], v[46:47] op_sel:[0,1] op_sel_hi:[1,0]
	v_and_b32_e32 v69, 0xffff0000, v60
	v_and_b32_e32 v73, 0xffff0000, v61
	v_mov_b32_e32 v45, v52
	v_lshlrev_b32_e32 v68, 16, v60
	v_lshlrev_b32_e32 v72, 16, v61
	v_lshlrev_b32_e32 v60, 16, v65
	v_and_b32_e32 v61, 0xffff0000, v65
	v_pk_add_f32 v[40:41], v[40:41], v[44:45]
	v_mul_f32_e32 v44, v69, v69
	v_mul_f32_e32 v46, v73, v73
	v_mul_f32_e32 v58, v60, v60
	v_mul_f32_e32 v59, v61, v61
	v_pk_fma_f32 v[44:45], v[68:69], v[68:69], v[44:45] op_sel_hi:[1,1,0]
	v_pk_fma_f32 v[46:47], v[72:73], v[72:73], v[46:47] op_sel_hi:[1,1,0]
	v_mov_b32_e32 v45, v58
	v_mov_b32_e32 v47, v59
	v_pk_add_f32 v[44:45], v[44:45], v[46:47]
	v_lshlrev_b32_e32 v65, 16, v71
	v_lshlrev_b32_e32 v64, 16, v70
	v_and_b32_e32 v71, 0xffff0000, v71
	v_and_b32_e32 v70, 0xffff0000, v70
	v_pk_add_f32 v[144:145], v[40:41], v[44:45]
	v_pk_mul_f32 v[40:41], v[70:71], v[70:71]
	v_and_b32_e32 v59, 0xffff0000, v139
	v_pk_fma_f32 v[40:41], v[64:65], v[64:65], v[40:41]
	v_and_b32_e32 v58, 0xffff0000, v138
	v_pk_add_f32 v[146:147], v[40:41], v[40:41] op_sel:[0,1] op_sel_hi:[1,0]
	v_lshlrev_b32_e32 v51, 16, v139
	v_lshlrev_b32_e32 v50, 16, v138
	v_pk_mul_f32 v[40:41], v[58:59], v[58:59]
	v_pk_add_f32 v[144:145], v[144:145], v[144:145] op_sel:[0,1] op_sel_hi:[1,0]
	v_pk_fma_f32 v[138:139], v[50:51], v[50:51], v[40:41]
	v_lshlrev_b32_e32 v41, 16, v42
	v_lshlrev_b32_e32 v46, 16, v39
	v_and_b32_e32 v47, 0xffff0000, v39
	v_and_b32_e32 v39, 0xffff0000, v42
	v_mov_b32_e32 v40, v144
	v_mov_b32_e32 v148, v146
	v_mov_b32_e32 v149, v41
	v_lshlrev_b32_e32 v44, 16, v38
	v_and_b32_e32 v45, 0xffff0000, v38
	v_mul_f32_e32 v38, v39, v39
	v_pk_add_f32 v[144:145], v[144:145], v[146:147]
	v_pk_mul_f32 v[146:147], v[40:41], v[148:149]
	v_pk_add_f32 v[138:139], v[138:139], v[138:139] op_sel:[0,1] op_sel_hi:[1,0]
	v_mov_b32_e32 v145, v147
	v_mov_b32_e32 v139, v38
	v_mul_f32_e32 v38, v45, v45
	v_lshlrev_b32_e32 v42, 16, v43
	v_and_b32_e32 v43, 0xffff0000, v43
	v_pk_add_f32 v[138:139], v[144:145], v[138:139]
	v_pk_fma_f32 v[144:145], v[44:45], v[44:45], v[38:39] op_sel_hi:[1,1,0]
	v_mul_f32_e32 v38, v47, v47
	v_mul_f32_e32 v52, v42, v42
	v_mul_f32_e32 v54, v43, v43
	v_pk_fma_f32 v[146:147], v[46:47], v[46:47], v[38:39] op_sel_hi:[1,1,0]
	v_mov_b32_e32 v145, v52
	v_mov_b32_e32 v147, v54
	v_pk_add_f32 v[144:145], v[144:145], v[146:147]
	v_lshlrev_b32_e32 v148, 16, v126
	v_pk_add_f32 v[138:139], v[138:139], v[144:145]
	v_and_b32_e32 v149, 0xffff0000, v126
	v_add_f32_e32 v38, v138, v139
	ds_bpermute_b32 v40, v1, v38
	v_lshlrev_b32_e32 v146, 16, v128
	v_and_b32_e32 v147, 0xffff0000, v128
	v_lshlrev_b32_e32 v144, 16, v129
	v_and_b32_e32 v145, 0xffff0000, v129
	s_waitcnt lgkmcnt(0)
	v_add_f32_e32 v38, v38, v40
	ds_bpermute_b32 v40, v158, v38
	v_lshlrev_b32_e32 v128, 16, v132
	v_and_b32_e32 v129, 0xffff0000, v132
	v_lshlrev_b32_e32 v126, 16, v133
	v_and_b32_e32 v127, 0xffff0000, v133
	s_waitcnt lgkmcnt(0)
	v_add_f32_e32 v38, v38, v40
	ds_bpermute_b32 v40, v159, v38
	v_mov_b32_e32 v112, v115
	v_lshlrev_b32_e32 v34, 16, v36
	v_and_b32_e32 v35, 0xffff0000, v36
	v_lshlrev_b32_e32 v36, 16, v37
	s_waitcnt lgkmcnt(0)
	v_add_f32_e32 v38, v38, v40
	ds_bpermute_b32 v40, v160, v38
	v_and_b32_e32 v37, 0xffff0000, v37
	v_lshlrev_b32_e32 v22, 16, v20
	v_and_b32_e32 v23, 0xffff0000, v20
	v_lshlrev_b32_e32 v24, 16, v21
	s_waitcnt lgkmcnt(0)
	v_add_f32_e32 v38, v38, v40
	ds_bpermute_b32 v40, v161, v38
	v_and_b32_e32 v25, 0xffff0000, v21
	v_lshlrev_b32_e32 v20, 16, v100
	v_and_b32_e32 v21, 0xffff0000, v100
	v_lshlrev_b32_e32 v156, 16, v101
	s_waitcnt lgkmcnt(0)
	v_add_f32_e32 v38, v38, v40
	ds_bpermute_b32 v40, v162, v38
	v_and_b32_e32 v157, 0xffff0000, v101
	v_and_b32_e32 v155, 0xffff0000, v102
	v_lshlrev_b32_e32 v152, 16, v103
	v_and_b32_e32 v153, 0xffff0000, v103
	s_waitcnt lgkmcnt(0)
; __device__ __forceinline__ float bf_lo(unsigned w) { return __uint_as_float(w << 16); }
; __device__ __forceinline__ float bf_hi(unsigned w) { return __uint_as_float(w & 0xffff0000u); }
; #define LAS __attribute__((address_space(3)))
; __global__ void __launch_bounds__(NWAVES * 64, 2) fwd_kernel(Args args) {
;     ...
;                 const float rstdy = 1.0f / sqrtf(wave_sum(sy) * (1.0f / D) + RMS_EPS);
; #pragma unroll
;                 for (int j = 0; j < 16; ++j) { const f32x4 y = {bf_lo(yv[j].x), bf_hi(yv[j].x), bf_lo(yv[j].y), bf_hi(yv[j].y)}; const f32x4 gq = ((const LAS f32x4*)cG)[lane + 64 * j];
;                     xr[64 * j] = v[j] + gq * (y * rstdy); }
	v_add_f32_e32 v38, v38, v40
	v_fmamk_f32 v38, v38, 0x39800000, v169
	v_mul_f32_e32 v40, 0x4f800000, v38
	v_cmp_gt_f32_e32 vcc, s11, v38
	v_lshlrev_b32_e32 v138, 16, v130
	v_and_b32_e32 v139, 0xffff0000, v130
	v_cndmask_b32_e32 v38, v38, v40, vcc
	v_sqrt_f32_e32 v40, v38
	v_lshlrev_b32_e32 v130, 16, v131
	v_and_b32_e32 v131, 0xffff0000, v131
	v_lshlrev_b32_e32 v102, 16, v116
	v_add_u32_e32 v52, -1, v40
	v_fma_f32 v54, -v52, v40, v38
	v_cmp_ge_f32_e64 s[2:3], 0, v54
	v_add_u32_e32 v54, 1, v40
	v_and_b32_e32 v103, 0xffff0000, v116
	v_cndmask_b32_e64 v52, v40, v52, s[2:3]
	v_fma_f32 v40, -v54, v40, v38
	v_cmp_lt_f32_e64 s[2:3], 0, v40
	v_lshlrev_b32_e32 v116, 16, v117
	v_and_b32_e32 v117, 0xffff0000, v117
	v_cndmask_b32_e64 v40, v52, v54, s[2:3]
	v_mul_f32_e32 v52, 0x37800000, v40
	v_cndmask_b32_e32 v40, v40, v52, vcc
	v_cmp_class_f32_e32 vcc, v38, v170
	v_lshlrev_b32_e32 v100, 16, v110
	v_and_b32_e32 v101, 0xffff0000, v110
	v_cndmask_b32_e32 v38, v40, v38, vcc
	v_div_scale_f32 v40, s[2:3], v38, v38, 1.0
	v_rcp_f32_e32 v52, v40
	v_lshlrev_b32_e32 v110, 16, v111
	v_and_b32_e32 v111, 0xffff0000, v111
	v_fma_f32 v54, -v40, v52, 1.0
	v_fmac_f32_e32 v52, v54, v52
	v_div_scale_f32 v54, vcc, 1.0, v38, 1.0
	v_mul_f32_e32 v82, v54, v52
	v_fma_f32 v84, -v40, v82, v54
	v_fmac_f32_e32 v82, v84, v52
	v_fma_f32 v40, -v40, v82, v54
	v_div_fmas_f32 v40, v40, v52, v82
	v_div_fixup_f32 v40, v40, v38, 1.0
	v_pk_mul_f32 v[132:133], v[40:41], v[140:141] op_sel_hi:[0,1]
	v_pk_mul_f32 v[176:177], v[40:41], v[142:143] op_sel_hi:[0,1]
	ds_read_b128 v[140:143], v163 offset:1024
	v_pk_fma_f32 v[174:175], v[174:175], v[176:177], v[96:97]
	v_mov_b32_e32 v96, v134
	v_mov_b32_e32 v97, v136
	v_mov_b32_e32 v136, v135
	v_pk_fma_f32 v[172:173], v[172:173], v[132:133], v[92:93]
	v_pk_mul_f32 v[96:97], v[40:41], v[96:97] op_sel_hi:[0,1]
	v_pk_mul_f32 v[132:133], v[40:41], v[136:137] op_sel_hi:[0,1]
	s_waitcnt lgkmcnt(0)
	v_pk_fma_f32 v[134:135], v[142:143], v[132:133], v[86:87]
	v_pk_fma_f32 v[132:133], v[140:141], v[96:97], v[80:81]
	ds_read_b128 v[140:143], v163 offset:2048
	v_pk_mul_f32 v[80:81], v[40:41], v[122:123] op_sel_hi:[0,1]
	v_pk_mul_f32 v[86:87], v[40:41], v[124:125] op_sel_hi:[0,1]
	ds_read_b128 v[122:125], v163 offset:3072
	v_add_co_u32_e32 v92, vcc, s12, v18
	v_mov_b32_e32 v82, v85
	s_nop 0
	v_addc_co_u32_e32 v93, vcc, -1, v19, vcc
	global_store_dwordx4 v[92:93], v[132:135], off offset:-2048 nt
	v_mov_b32_e32 v52, v55
	v_mov_b32_e32 v38, v41
	s_waitcnt lgkmcnt(1)
	v_pk_fma_f32 v[132:133], v[140:141], v[80:81], v[62:63]
	v_pk_mul_f32 v[62:63], v[40:41], v[112:113] op_sel_hi:[0,1]
	v_pk_fma_f32 v[134:135], v[142:143], v[86:87], v[66:67]
	v_pk_mul_f32 v[66:67], v[40:41], v[108:109] op_sel_hi:[0,1]
	s_waitcnt lgkmcnt(0)
	v_pk_fma_f32 v[112:113], v[122:123], v[62:63], v[48:49]
	v_add_co_u32_e32 v48, vcc, s13, v18
	v_pk_fma_f32 v[114:115], v[124:125], v[66:67], v[56:57]
	s_nop 0
	v_addc_co_u32_e32 v49, vcc, -1, v19, vcc
	global_store_dwordx4 v[48:49], v[112:115], off offset:-4096 nt
	ds_read_b128 v[112:115], v163 offset:4096
	v_mov_b32_e32 v57, v120
	v_mov_b32_e32 v120, v119
	v_mov_b32_e32 v56, v118
	v_pk_mul_f32 v[62:63], v[40:41], v[120:121] op_sel_hi:[0,1]
	ds_read_b128 v[118:121], v163 offset:5120
	v_pk_mul_f32 v[56:57], v[40:41], v[56:57] op_sel_hi:[0,1]
	s_waitcnt lgkmcnt(1)
	v_pk_fma_f32 v[36:37], v[114:115], v[62:63], v[36:37]
	v_pk_fma_f32 v[34:35], v[112:113], v[56:57], v[34:35]
	global_store_dwordx4 v[48:49], v[34:37], off offset:-3072 nt
	v_pk_mul_f32 v[56:57], v[40:41], v[94:95] op_sel_hi:[0,1]
	v_pk_mul_f32 v[62:63], v[40:41], v[98:99] op_sel_hi:[0,1]
	v_mov_b32_e32 v34, v104
	v_mov_b32_e32 v35, v106
	v_mov_b32_e32 v106, v105
	v_pk_mul_f32 v[34:35], v[40:41], v[34:35] op_sel_hi:[0,1]
	v_pk_mul_f32 v[36:37], v[40:41], v[106:107] op_sel_hi:[0,1]
	s_waitcnt lgkmcnt(0)
	v_pk_fma_f32 v[32:33], v[120:121], v[36:37], v[32:33]
	v_pk_fma_f32 v[30:31], v[118:119], v[34:35], v[30:31]
	ds_read_b128 v[34:37], v163 offset:6144
	global_store_dwordx4 v[48:49], v[30:33], off offset:-2048 nt
	ds_read_b128 v[30:33], v163 offset:7168
	global_store_dwordx4 v[92:93], v[172:175], off offset:-3072 nt
	global_store_dwordx4 v[92:93], v[132:135], off offset:-1024 nt
	s_waitcnt lgkmcnt(1)
	v_pk_fma_f32 v[28:29], v[36:37], v[62:63], v[28:29]
	v_pk_fma_f32 v[26:27], v[34:35], v[56:57], v[26:27]
	global_store_dwordx4 v[48:49], v[26:29], off offset:-1024 nt
	s_nop 1
	v_pk_mul_f32 v[26:27], v[40:41], v[82:83] op_sel_hi:[0,1]
	v_pk_mul_f32 v[28:29], v[40:41], v[78:79] op_sel_hi:[0,1]
	s_waitcnt lgkmcnt(0)
	v_pk_fma_f32 v[24:25], v[32:33], v[28:29], v[24:25]
	v_pk_fma_f32 v[22:23], v[30:31], v[26:27], v[22:23]
	global_store_dwordx4 v[48:49], v[22:25], off nt
	ds_read_b128 v[22:25], v163 offset:8192
	v_mov_b32_e32 v26, v88
	v_mov_b32_e32 v27, v90
	v_pk_mul_f32 v[30:31], v[40:41], v[26:27] op_sel_hi:[0,1]
	ds_read_b128 v[26:29], v163 offset:9216
	v_mov_b32_e32 v90, v89
	v_pk_mul_f32 v[32:33], v[40:41], v[90:91] op_sel_hi:[0,1]
	s_waitcnt lgkmcnt(1)
; __device__ __forceinline__ float bf_lo(unsigned w) { return __uint_as_float(w << 16); }
; __device__ __forceinline__ float bf_hi(unsigned w) { return __uint_as_float(w & 0xffff0000u); }
; #define LAS __attribute__((address_space(3)))
; __global__ void __launch_bounds__(NWAVES * 64, 2) fwd_kernel(Args args) {
;     ...
;         for (int slot = vcu; slot < M / 8; slot += G) {
;             const int b = slot / (SEQ / 8);
;             if (b != cur_b) { __syncthreads();
;                 for (int i = tid; i < D; i += NWAVES * 64) cG[i] = mod[b * NMOD + 5 * D + i] * g_ffn_post[i];
;                 __syncthreads(); cur_b = b; }
;     ...
;                 for (int j = 0; j < 16; ++j) { const f32x4 y = {bf_lo(yv[j].x), bf_hi(yv[j].x), bf_lo(yv[j].y), bf_hi(yv[j].y)}; const f32x4 gq = ((const LAS f32x4*)cG)[lane + 64 * j];
;                     xr[64 * j] = v[j] + gq * (y * rstdy); }
	v_pk_fma_f32 v[22:23], v[22:23], v[30:31], v[20:21]
	v_add_co_u32_e32 v30, vcc, s8, v18
	v_pk_fma_f32 v[24:25], v[24:25], v[32:33], v[156:157]
	s_nop 0
	v_addc_co_u32_e32 v31, vcc, -1, v19, vcc
	v_mov_b32_e32 v20, v75
	v_mov_b32_e32 v21, v77
	v_mov_b32_e32 v75, v76
	global_store_dwordx4 v[30:31], v[22:25], off offset:-3072 nt
	v_pk_mul_f32 v[32:33], v[40:41], v[68:69] op_sel_hi:[0,1]
	s_nop 0
	v_pk_mul_f32 v[22:23], v[40:41], v[20:21] op_sel_hi:[0,1]
	v_pk_mul_f32 v[20:21], v[40:41], v[74:75] op_sel_hi:[0,1]
	s_waitcnt lgkmcnt(0)
	v_pk_fma_f32 v[20:21], v[26:27], v[20:21], v[154:155]
	ds_read_b128 v[24:27], v163 offset:10240
	v_pk_fma_f32 v[22:23], v[28:29], v[22:23], v[152:153]
	global_store_dwordx4 v[30:31], v[20:23], off offset:-2048 nt
	ds_read_b128 v[20:23], v163 offset:11264
	v_pk_mul_f32 v[28:29], v[40:41], v[72:73] op_sel_hi:[0,1]
	s_waitcnt lgkmcnt(1)
	v_pk_fma_f32 v[24:25], v[24:25], v[32:33], v[148:149]
	v_pk_fma_f32 v[26:27], v[26:27], v[28:29], v[150:151]
	global_store_dwordx4 v[30:31], v[24:27], off offset:-1024 nt
	s_nop 1
	v_pk_mul_f32 v[24:25], v[40:41], v[60:61] op_sel_hi:[0,1]
	v_pk_mul_f32 v[26:27], v[40:41], v[52:53] op_sel_hi:[0,1]
	s_waitcnt lgkmcnt(0)
	v_pk_fma_f32 v[20:21], v[20:21], v[26:27], v[146:147]
	v_pk_fma_f32 v[22:23], v[22:23], v[24:25], v[144:145]
	global_store_dwordx4 v[18:19], v[20:23], off offset:-4096 nt
	ds_read_b128 v[20:23], v163 offset:12288
	v_mov_b32_e32 v24, v65
	v_mov_b32_e32 v25, v71
	v_pk_mul_f32 v[28:29], v[40:41], v[24:25] op_sel_hi:[0,1]
	v_mov_b32_e32 v65, v70
	ds_read_b128 v[24:27], v163 offset:13312
	v_pk_mul_f32 v[30:31], v[40:41], v[64:65] op_sel_hi:[0,1]
	s_waitcnt lgkmcnt(1)
	v_pk_fma_f32 v[20:21], v[20:21], v[30:31], v[138:139]
	v_pk_fma_f32 v[22:23], v[22:23], v[28:29], v[130:131]
	global_store_dwordx4 v[18:19], v[20:23], off offset:-3072 nt
	v_pk_mul_f32 v[28:29], v[40:41], v[46:47] op_sel_hi:[0,1]
	v_pk_mul_f32 v[30:31], v[40:41], v[44:45] op_sel_hi:[0,1]
	v_mov_b32_e32 v20, v51
	v_mov_b32_e32 v21, v59
	v_mov_b32_e32 v51, v58
	v_pk_mul_f32 v[22:23], v[40:41], v[20:21] op_sel_hi:[0,1]
	v_pk_mul_f32 v[20:21], v[40:41], v[50:51] op_sel_hi:[0,1]
	s_waitcnt lgkmcnt(0)
	v_pk_fma_f32 v[20:21], v[24:25], v[20:21], v[128:129]
	v_pk_fma_f32 v[22:23], v[26:27], v[22:23], v[126:127]
	ds_read_b128 v[24:27], v163 offset:14336
	global_store_dwordx4 v[18:19], v[20:23], off offset:-2048 nt
	ds_read_b128 v[20:23], v163 offset:15360
	s_waitcnt lgkmcnt(1)
	v_pk_fma_f32 v[24:25], v[24:25], v[30:31], v[102:103]
	v_pk_fma_f32 v[26:27], v[26:27], v[28:29], v[116:117]
	global_store_dwordx4 v[18:19], v[24:27], off offset:-1024 nt
	s_nop 1
	v_pk_mul_f32 v[24:25], v[40:41], v[42:43] op_sel_hi:[0,1]
	v_pk_mul_f32 v[26:27], v[40:41], v[38:39] op_sel_hi:[0,1]
	s_waitcnt lgkmcnt(0)
	v_pk_fma_f32 v[20:21], v[20:21], v[26:27], v[100:101]
	v_pk_fma_f32 v[22:23], v[22:23], v[24:25], v[110:111]
	global_store_dwordx4 v[18:19], v[20:23], off nt
	v_lshl_add_u64 v[18:19], v[18:19], 0, s[6:7]
	s_cbranch_scc0 .LBB0_1105
.LBB0_1102:
	s_ashr_i32 s2, s34, 31
	s_lshr_b32 s2, s2, 22
	s_add_i32 s2, s34, s2
	s_ashr_i32 s15, s2, 10
	s_cmp_eq_u32 s15, s14
	s_cbranch_scc1 .LBB0_1101
	s_mul_i32 s14, s15, 0x6000
	s_addk_i32 s14, 0x5000
	v_or_b32_e32 v20, s14, v0
	v_or_b32_e32 v22, s14, v165
	v_or_b32_e32 v24, s14, v179
	v_or_b32_e32 v26, s14, v166
	v_or_b32_e32 v28, s14, v210
	v_or_b32_e32 v30, s14, v167
	v_or_b32_e32 v32, s14, v211
	v_ashrrev_i32_e32 v21, 31, v20
	v_ashrrev_i32_e32 v23, 31, v22
	v_ashrrev_i32_e32 v25, 31, v24
	v_ashrrev_i32_e32 v27, 31, v26
	v_ashrrev_i32_e32 v29, 31, v28
	v_ashrrev_i32_e32 v31, 31, v30
	v_ashrrev_i32_e32 v33, 31, v32
	s_waitcnt lgkmcnt(0)
	s_barrier
	v_lshl_add_u64 v[20:21], v[20:21], 2, s[30:31]
	v_lshl_add_u64 v[22:23], v[22:23], 2, s[30:31]
	v_lshl_add_u64 v[24:25], v[24:25], 2, s[30:31]
	v_lshl_add_u64 v[26:27], v[26:27], 2, s[30:31]
	v_lshl_add_u64 v[28:29], v[28:29], 2, s[30:31]
	v_lshl_add_u64 v[30:31], v[30:31], 2, s[30:31]
	v_lshl_add_u64 v[32:33], v[32:33], 2, s[30:31]
	global_load_dword v34, v[2:3], off nt
	global_load_dword v35, v[2:3], off offset:2048 nt
	global_load_dword v36, v[4:5], off nt
	global_load_dword v37, v[6:7], off nt
	global_load_dword v38, v[8:9], off nt
	global_load_dword v39, v[10:11], off nt
	global_load_dword v40, v[12:13], off nt
	global_load_dword v41, v[20:21], off nt
	global_load_dword v42, v[22:23], off nt
	global_load_dword v43, v[24:25], off nt
	global_load_dword v44, v[26:27], off nt
	global_load_dword v45, v[28:29], off nt
	global_load_dword v46, v[30:31], off nt
	global_load_dword v47, v[32:33], off nt
	s_waitcnt vmcnt(6)
	v_mul_f32_e32 v20, v41, v34
	s_waitcnt vmcnt(5)
	v_mul_f32_e32 v21, v42, v35
	s_waitcnt vmcnt(4)
	v_mul_f32_e32 v22, v43, v36
	s_waitcnt vmcnt(3)
	v_mul_f32_e32 v23, v44, v37
	s_waitcnt vmcnt(2)
	v_mul_f32_e32 v24, v45, v38
	s_waitcnt vmcnt(1)
	v_mul_f32_e32 v25, v46, v39
	s_waitcnt vmcnt(0)
	v_mul_f32_e32 v26, v47, v40
	ds_write2st64_b32 v164, v20, v21 offset1:8
	ds_write2st64_b32 v164, v22, v23 offset0:16 offset1:24
	ds_write2st64_b32 v164, v24, v25 offset0:32 offset1:40
	ds_write_b32 v164, v26 offset:12288
	s_and_saveexec_b64 s[2:3], s[0:1]
	s_cbranch_execz .LBB0_1100
	v_add_u32_e32 v20, s14, v168
	v_ashrrev_i32_e32 v21, 31, v20
	v_lshl_add_u64 v[20:21], v[20:21], 2, s[30:31]
	global_load_dword v22, v[20:21], off nt
	global_load_dword v23, v[14:15], off nt
	s_waitcnt vmcnt(0)
	v_mul_f32_e32 v20, v22, v23
	ds_write_b32 v164, v20 offset:14336
	s_branch .LBB0_1100
